# HNAQP2S + all s_setprio removed from the GEMM K-loop phases
# speedup vs baseline: 1.0057x; 1.0057x over previous
; __device__ __forceinline__ float row_rstd(const float* ss, int row) { return 1.0f / sqrtf(ss[row] * (1.0f / DM) + 1e-6f); }
; #define PG8_STAGE(bufoff, gbase, voff) do { _Pragma("unroll") for (int _i = 0; _i < 2; ++_i) \
;         __builtin_amdgcn_global_load_lds((const unsigned*)((const char*)(gbase) + (voff)[_i]), (LAS unsigned*)(lds + (bufoff) + ldsw + _i * 8192), 16, 0, 0); } while (0)
; #define PG8_LDA(dst, b, h) do { _Pragma("unroll") for (int m = 0; m < 4; ++m) _Pragma("unroll") for (int k = 0; k < 2; ++k) dst[m][k] = *(const LAS bf16x8*)(lds + PG8_SA(b, h) + aoff + m * 2048 + k * 1024); } while (0)
; #define PG8_LDB(dst, b, h) do { _Pragma("unroll") for (int n = 0; n < 2; ++n) _Pragma("unroll") for (int k = 0; k < 2; ++k) dst[n][k] = *(const LAS bf16x8*)(lds + PG8_SB(b, h) + boff + n * 2048 + k * 1024); } while (0)
; #define PG8_WAIT_V(n) asm volatile("s_waitcnt vmcnt(" #n ")" ::: "memory")
; #define PG8_WAIT_L(n) asm volatile("s_waitcnt lgkmcnt(" #n ")" ::: "memory")
; #define PG8_BAR __builtin_amdgcn_s_barrier()
; #define PG8_SCHED __builtin_amdgcn_sched_barrier(0)
;     __device__ __forceinline__ void operator()(const f32x4 (&acc)[2][2][4][2], const Unit& u, int wr, int wc, int fr, int fq) const {
;     ...
;         const float* bp = bias + (size_t)s * BIAS_N + u.pn * BM + wc * 32 + 8 * fq;
;         const f32x4 ba0 = *(const f32x4*)bp, ba1 = *(const f32x4*)(bp + 4), bb0 = *(const f32x4*)(bp + HALF), bb1 = *(const f32x4*)(bp + HALF + 4);
;         const int lane = fq * 16 + fr;
;         const float rsl0 = row_rstd(ss, u.pm * BM + wr * 64 + lane), rsl1 = row_rstd(ss, u.pm * BM + HALF + wr * 64 + lane);
; template <class Epi, class Sched, bool ALIGN_EPI = false, bool SP2 = false>
; __device__ __forceinline__ void gemm_phase(LAS unsigned char* lds, const Gemm g, const Sched& S, const Epi& E) {
;     ...
;             PG8_LDB(B0, 0, 0); PG8_LDB(B1, 0, 1); PG8_SCHED; PG8_LDA(At, 0, 0); PG8_STAGE(PG8_SA(1, 1), a1 + hstep, voffA);
;             PG8_WAIT_V(8); PG8_WAIT_L(0); PG8_BAR; PG8_MMA(0, 0, At, B0); PG8_MMA(0, 1, At, B1); PG8_BAR; PG8_SCHED;
;             PG8_LDA(At, 0, 1); PG8_STAGE(PG8_SB(0, 0), b2, voffB); PG8_STAGE(PG8_SB(0, 1), b2 + hstepB, voffB); PG8_STAGE(PG8_SA(0, 0), a2, voffA);
;             PG8_WAIT_V(8); PG8_WAIT_L(0); PG8_BAR; PG8_MMA(1, 0, At, B0); PG8_MMA(1, 1, At, B1); PG8_BAR; PG8_SCHED;
.Lpre_up1l0:
	s_lshl_b64 s[98:99], s[98:99], 2
	s_add_u32 s98, s68, s98
	s_addc_u32 s99, s69, s99
	s_lshl_b32 s100, s0, 8
	s_ashr_i32 s101, s100, 31
	s_lshl_b64 s[100:101], s[100:101], 2
	s_add_u32 s98, s98, s100
	s_addc_u32 s99, s99, s101
	s_add_u32 s98, s98, s60
	s_addc_u32 s99, s99, 0
	s_lshl_b32 s100, s2, 8
	s_add_i32 s100, s100, s54
	v_or_b32_e32 v162, s100, v171
	v_ashrrev_i32_e32 v163, 31, v162
	v_lshl_add_u64 v[162:163], v[162:163], 2, s[8:9]
	v_add_u32_e32 v164, s100, v172
	v_ashrrev_i32_e32 v165, 31, v164
	v_lshl_add_u64 v[164:165], v[164:165], 2, s[8:9]
	global_load_dwordx4 v[234:237], v177, s[98:99] offset:16
	global_load_dwordx4 v[238:241], v177, s[98:99]
	global_load_dwordx4 v[242:245], v177, s[98:99] offset:528
	global_load_dwordx4 v[246:249], v177, s[98:99] offset:512
	global_load_dword v250, v[162:163], off
	global_load_dword v251, v[164:165], off
	ds_read_b128 v[66:69], v174
	ds_read_b128 v[70:73], v174 offset:1024
	ds_read_b128 v[74:77], v174 offset:2048
	ds_read_b128 v[78:81], v174 offset:3072
	ds_read_b128 v[162:165], v175
	ds_read_b128 v[182:185], v175 offset:1024
	ds_read_b128 v[186:189], v175 offset:2048
	ds_read_b128 v[190:193], v175 offset:3072
	s_add_u32 s20, s16, 0xfff80080
	s_addc_u32 s21, s17, -1
	s_cmp_eq_u32 s19, 28
	s_cselect_b32 s53, s3, s21
	s_cselect_b32 s52, s12, s20
	s_cselect_b32 s51, s13, s18
	s_cselect_b32 s50, s14, s15
	v_lshl_add_u64 v[166:167], s[16:17], 0, v[154:155]
	s_add_i32 m0, s33, 0xc000
	ds_read_b128 v[194:197], v176
	ds_read_b128 v[198:201], v176 offset:1024
	ds_read_b128 v[202:205], v176 offset:2048
	ds_read_b128 v[206:209], v176 offset:3072
	ds_read_b128 v[210:213], v176 offset:4096
	ds_read_b128 v[214:217], v176 offset:5120
	ds_read_b128 v[218:221], v176 offset:6144
	ds_read_b128 v[222:225], v176 offset:7168
	global_load_lds_dwordx4 v[166:167], off
	v_lshl_add_u64 v[166:167], s[16:17], 0, v[156:157]
	s_add_i32 m0, s33, 0xe000
	s_nop 0
	global_load_lds_dwordx4 v[166:167], off
	s_waitcnt lgkmcnt(0)
	s_barrier
	s_waitcnt lgkmcnt(0)
	v_mfma_f32_16x16x32_bf16 v[142:145], v[66:69], v[194:197], 0
	v_mfma_f32_16x16x32_bf16 v[138:141], v[74:77], v[194:197], 0
	v_mfma_f32_16x16x32_bf16 v[126:129], v[66:69], v[202:205], 0
	v_mfma_f32_16x16x32_bf16 v[122:125], v[74:77], v[202:205], 0
	v_mfma_f32_16x16x32_bf16 v[110:113], v[66:69], v[210:213], 0
	v_mfma_f32_16x16x32_bf16 v[106:109], v[74:77], v[210:213], 0
	v_mfma_f32_16x16x32_bf16 v[94:97], v[66:69], v[218:221], 0
	v_mfma_f32_16x16x32_bf16 v[90:93], v[74:77], v[218:221], 0
	v_mfma_f32_16x16x32_bf16 v[142:145], v[70:73], v[198:201], v[142:145]
	v_mfma_f32_16x16x32_bf16 v[138:141], v[78:81], v[198:201], v[138:141]
	v_mfma_f32_16x16x32_bf16 v[126:129], v[70:73], v[206:209], v[126:129]
	v_mfma_f32_16x16x32_bf16 v[122:125], v[78:81], v[206:209], v[122:125]
	v_mfma_f32_16x16x32_bf16 v[110:113], v[70:73], v[214:217], v[110:113]
	v_mfma_f32_16x16x32_bf16 v[106:109], v[78:81], v[214:217], v[106:109]
	v_mfma_f32_16x16x32_bf16 v[94:97], v[70:73], v[222:225], v[94:97]
	v_mfma_f32_16x16x32_bf16 v[90:93], v[78:81], v[222:225], v[90:93]
	v_mfma_f32_16x16x32_bf16 v[134:137], v[162:165], v[194:197], 0
	v_mfma_f32_16x16x32_bf16 v[130:133], v[186:189], v[194:197], 0
	v_mfma_f32_16x16x32_bf16 v[118:121], v[162:165], v[202:205], 0
	v_mfma_f32_16x16x32_bf16 v[114:117], v[186:189], v[202:205], 0
	v_mfma_f32_16x16x32_bf16 v[102:105], v[162:165], v[210:213], 0
	v_mfma_f32_16x16x32_bf16 v[98:101], v[186:189], v[210:213], 0
	v_mfma_f32_16x16x32_bf16 v[86:89], v[162:165], v[218:221], 0
	v_mfma_f32_16x16x32_bf16 v[82:85], v[186:189], v[218:221], 0
	v_mfma_f32_16x16x32_bf16 v[134:137], v[182:185], v[198:201], v[134:137]
	v_mfma_f32_16x16x32_bf16 v[130:133], v[190:193], v[198:201], v[130:133]
	v_mfma_f32_16x16x32_bf16 v[118:121], v[182:185], v[206:209], v[118:121]
	v_mfma_f32_16x16x32_bf16 v[114:117], v[190:193], v[206:209], v[114:117]
	v_mfma_f32_16x16x32_bf16 v[102:105], v[182:185], v[214:217], v[102:105]
	v_mfma_f32_16x16x32_bf16 v[98:101], v[190:193], v[214:217], v[98:101]
	v_mfma_f32_16x16x32_bf16 v[86:89], v[182:185], v[222:225], v[86:89]
	v_mfma_f32_16x16x32_bf16 v[82:85], v[190:193], v[222:225], v[82:85]
	s_barrier
	s_add_i32 s20, s57, s27
	v_lshl_add_u64 v[166:167], s[50:51], 0, v[150:151]
	s_mov_b32 m0, s20
	ds_read_b128 v[194:197], v176 offset:16384
	ds_read_b128 v[198:201], v176 offset:17408
	ds_read_b128 v[202:205], v176 offset:18432
	ds_read_b128 v[206:209], v176 offset:19456
	ds_read_b128 v[210:213], v176 offset:20480
	ds_read_b128 v[214:217], v176 offset:21504
	ds_read_b128 v[218:221], v176 offset:22528
	ds_read_b128 v[222:225], v176 offset:23552
	global_load_lds_dwordx4 v[166:167], off
	s_add_i32 m0, s20, 0x2000
	s_add_u32 s20, s50, 0x80000
	v_lshl_add_u64 v[226:227], s[50:51], 0, v[146:147]
	s_addc_u32 s21, s51, 0
	s_add_i32 s22, s58, s27
	global_load_lds_dwordx4 v[226:227], off
	v_lshl_add_u64 v[228:229], s[20:21], 0, v[150:151]
	s_mov_b32 m0, s22
	v_lshl_add_u64 v[230:231], s[52:53], 0, v[148:149]
	global_load_lds_dwordx4 v[228:229], off
	v_lshl_add_u64 v[228:229], s[20:21], 0, v[146:147]
	s_add_i32 m0, s22, 0x2000
	s_nop 0
	global_load_lds_dwordx4 v[228:229], off
	v_lshl_add_u64 v[228:229], s[52:53], 0, v[152:153]
	s_mov_b32 m0, s33
	s_nop 0
	global_load_lds_dwordx4 v[228:229], off
	s_mov_b32 m0, s34
	s_nop 0
	global_load_lds_dwordx4 v[230:231], off
	s_waitcnt lgkmcnt(0)
	s_barrier
; #define PG8_STAGE(bufoff, gbase, voff) do { _Pragma("unroll") for (int _i = 0; _i < 2; ++_i) \
;         __builtin_amdgcn_global_load_lds((const unsigned*)((const char*)(gbase) + (voff)[_i]), (LAS unsigned*)(lds + (bufoff) + ldsw + _i * 8192), 16, 0, 0); } while (0)
; #define PG8_LDA(dst, b, h) do { _Pragma("unroll") for (int m = 0; m < 4; ++m) _Pragma("unroll") for (int k = 0; k < 2; ++k) dst[m][k] = *(const LAS bf16x8*)(lds + PG8_SA(b, h) + aoff + m * 2048 + k * 1024); } while (0)
; #define PG8_LDB(dst, b, h) do { _Pragma("unroll") for (int n = 0; n < 2; ++n) _Pragma("unroll") for (int k = 0; k < 2; ++k) dst[n][k] = *(const LAS bf16x8*)(lds + PG8_SB(b, h) + boff + n * 2048 + k * 1024); } while (0)
; #define PG8_MMA(ai, bj, At, Bt) do { __builtin_amdgcn_s_setprio(1); _Pragma("unroll") for (int m = 0; m < 4; ++m) _Pragma("unroll") for (int n = 0; n < 2; ++n) _Pragma("unroll") for (int k = 0; k < 2; ++k) \
;         acc[ai][bj][m][n] = __builtin_amdgcn_mfma_f32_16x16x32_bf16(Bt[n][k], At[m][k], acc[ai][bj][m][n], 0, 0, 0); __builtin_amdgcn_s_setprio(0); } while (0)
; #define PG8_WAIT_V(n) asm volatile("s_waitcnt vmcnt(" #n ")" ::: "memory")
; #define PG8_WAIT_L(n) asm volatile("s_waitcnt lgkmcnt(" #n ")" ::: "memory")
; #define PG8_BAR __builtin_amdgcn_s_barrier()
; #define PG8_SCHED __builtin_amdgcn_sched_barrier(0)
; template <class Epi, class Sched, bool ALIGN_EPI = false, bool SP2 = false>
; __device__ __forceinline__ void gemm_phase(LAS unsigned char* lds, const Gemm g, const Sched& S, const Epi& E) {
;     ...
;             PG8_WAIT_V(8); PG8_WAIT_L(0); PG8_BAR; PG8_MMA(1, 0, At, B0); PG8_MMA(1, 1, At, B1); PG8_BAR; PG8_SCHED;
;             PG8_LDB(B0, 1, 0); PG8_LDB(B1, 1, 1); PG8_SCHED; PG8_LDA(At, 1, 0); PG8_STAGE(PG8_SA(0, 1), a2 + hstep, voffA);
;             PG8_WAIT_V(8); PG8_WAIT_L(0); PG8_BAR; PG8_MMA(0, 0, At, B0); PG8_MMA(0, 1, At, B1); PG8_BAR; PG8_SCHED;
	s_waitcnt lgkmcnt(0)
	v_mfma_f32_16x16x32_bf16 v[62:65], v[66:69], v[194:197], 0
	v_mfma_f32_16x16x32_bf16 v[58:61], v[74:77], v[194:197], 0
	v_mfma_f32_16x16x32_bf16 v[46:49], v[66:69], v[202:205], 0
	v_mfma_f32_16x16x32_bf16 v[42:45], v[74:77], v[202:205], 0
	v_mfma_f32_16x16x32_bf16 v[30:33], v[66:69], v[210:213], 0
	v_mfma_f32_16x16x32_bf16 v[26:29], v[74:77], v[210:213], 0
	v_mfma_f32_16x16x32_bf16 v[14:17], v[66:69], v[218:221], 0
	v_mfma_f32_16x16x32_bf16 v[10:13], v[74:77], v[218:221], 0
	v_mfma_f32_16x16x32_bf16 v[62:65], v[70:73], v[198:201], v[62:65]
	v_mfma_f32_16x16x32_bf16 v[58:61], v[78:81], v[198:201], v[58:61]
	v_mfma_f32_16x16x32_bf16 v[46:49], v[70:73], v[206:209], v[46:49]
	v_mfma_f32_16x16x32_bf16 v[42:45], v[78:81], v[206:209], v[42:45]
	v_mfma_f32_16x16x32_bf16 v[30:33], v[70:73], v[214:217], v[30:33]
	v_mfma_f32_16x16x32_bf16 v[26:29], v[78:81], v[214:217], v[26:29]
	v_mfma_f32_16x16x32_bf16 v[14:17], v[70:73], v[222:225], v[14:17]
	v_mfma_f32_16x16x32_bf16 v[10:13], v[78:81], v[222:225], v[10:13]
	v_mfma_f32_16x16x32_bf16 v[54:57], v[162:165], v[194:197], 0
	v_mfma_f32_16x16x32_bf16 v[50:53], v[186:189], v[194:197], 0
	v_mfma_f32_16x16x32_bf16 v[38:41], v[162:165], v[202:205], 0
	v_mfma_f32_16x16x32_bf16 v[34:37], v[186:189], v[202:205], 0
	v_mfma_f32_16x16x32_bf16 v[22:25], v[162:165], v[210:213], 0
	v_mfma_f32_16x16x32_bf16 v[18:21], v[186:189], v[210:213], 0
	v_mfma_f32_16x16x32_bf16 v[6:9], v[162:165], v[218:221], 0
	v_mfma_f32_16x16x32_bf16 v[2:5], v[186:189], v[218:221], 0
	v_mfma_f32_16x16x32_bf16 v[54:57], v[182:185], v[198:201], v[54:57]
	v_mfma_f32_16x16x32_bf16 v[50:53], v[190:193], v[198:201], v[50:53]
	v_mfma_f32_16x16x32_bf16 v[38:41], v[182:185], v[206:209], v[38:41]
	v_mfma_f32_16x16x32_bf16 v[34:37], v[190:193], v[206:209], v[34:37]
	v_mfma_f32_16x16x32_bf16 v[22:25], v[182:185], v[214:217], v[22:25]
	v_mfma_f32_16x16x32_bf16 v[18:21], v[190:193], v[214:217], v[18:21]
	v_mfma_f32_16x16x32_bf16 v[6:9], v[182:185], v[222:225], v[6:9]
	v_mfma_f32_16x16x32_bf16 v[2:5], v[190:193], v[222:225], v[2:5]
	s_barrier
	s_add_i32 s22, 0, 0x18000
	s_add_i32 s23, 0, 0x1c000
	v_add_u32_e32 v78, s22, v170
	v_add_u32_e32 v168, s23, v170
	ds_read_b128 v[66:69], v78
	ds_read_b128 v[70:73], v78 offset:1024
	ds_read_b128 v[74:77], v78 offset:2048
	ds_read_b128 v[78:81], v78 offset:3072
	ds_read_b128 v[162:165], v168
	ds_read_b128 v[182:185], v168 offset:1024
	ds_read_b128 v[186:189], v168 offset:2048
	ds_read_b128 v[190:193], v168 offset:3072
	s_add_u32 s20, s52, 0x80000
	s_addc_u32 s21, s53, 0
	s_mov_b32 m0, s35
	v_lshl_add_u64 v[232:233], s[20:21], 0, v[152:153]
	ds_read_b128 v[194:197], v176 offset:32768
	ds_read_b128 v[198:201], v176 offset:33792
	ds_read_b128 v[202:205], v176 offset:34816
	ds_read_b128 v[206:209], v176 offset:35840
	ds_read_b128 v[210:213], v176 offset:36864
	ds_read_b128 v[214:217], v176 offset:37888
	ds_read_b128 v[218:221], v176 offset:38912
	ds_read_b128 v[222:225], v176 offset:39936
	global_load_lds_dwordx4 v[232:233], off
	v_lshl_add_u64 v[232:233], s[20:21], 0, v[148:149]
	s_mov_b32 m0, s36
	s_nop 0
	global_load_lds_dwordx4 v[232:233], off
	s_waitcnt vmcnt(8)
	s_waitcnt lgkmcnt(0)
	s_barrier
	s_waitcnt lgkmcnt(0)
	v_mfma_f32_16x16x32_bf16 v[142:145], v[66:69], v[194:197], v[142:145]
	v_mfma_f32_16x16x32_bf16 v[138:141], v[74:77], v[194:197], v[138:141]
	v_mfma_f32_16x16x32_bf16 v[126:129], v[66:69], v[202:205], v[126:129]
	v_mfma_f32_16x16x32_bf16 v[122:125], v[74:77], v[202:205], v[122:125]
	v_mfma_f32_16x16x32_bf16 v[110:113], v[66:69], v[210:213], v[110:113]
	v_mfma_f32_16x16x32_bf16 v[106:109], v[74:77], v[210:213], v[106:109]
	v_mfma_f32_16x16x32_bf16 v[94:97], v[66:69], v[218:221], v[94:97]
	v_mfma_f32_16x16x32_bf16 v[90:93], v[74:77], v[218:221], v[90:93]
	v_mfma_f32_16x16x32_bf16 v[142:145], v[70:73], v[198:201], v[142:145]
	v_mfma_f32_16x16x32_bf16 v[138:141], v[78:81], v[198:201], v[138:141]
	v_mfma_f32_16x16x32_bf16 v[126:129], v[70:73], v[206:209], v[126:129]
	v_mfma_f32_16x16x32_bf16 v[122:125], v[78:81], v[206:209], v[122:125]
	v_mfma_f32_16x16x32_bf16 v[110:113], v[70:73], v[214:217], v[110:113]
	v_mfma_f32_16x16x32_bf16 v[106:109], v[78:81], v[214:217], v[106:109]
	v_mfma_f32_16x16x32_bf16 v[94:97], v[70:73], v[222:225], v[94:97]
	v_mfma_f32_16x16x32_bf16 v[90:93], v[78:81], v[222:225], v[90:93]
	v_mfma_f32_16x16x32_bf16 v[134:137], v[162:165], v[194:197], v[134:137]
	v_mfma_f32_16x16x32_bf16 v[130:133], v[186:189], v[194:197], v[130:133]
	v_mfma_f32_16x16x32_bf16 v[118:121], v[162:165], v[202:205], v[118:121]
	v_mfma_f32_16x16x32_bf16 v[114:117], v[186:189], v[202:205], v[114:117]
	v_mfma_f32_16x16x32_bf16 v[102:105], v[162:165], v[210:213], v[102:105]
	v_mfma_f32_16x16x32_bf16 v[98:101], v[186:189], v[210:213], v[98:101]
	v_mfma_f32_16x16x32_bf16 v[86:89], v[162:165], v[218:221], v[86:89]
	v_mfma_f32_16x16x32_bf16 v[82:85], v[186:189], v[218:221], v[82:85]
	v_mfma_f32_16x16x32_bf16 v[134:137], v[182:185], v[198:201], v[134:137]
	v_mfma_f32_16x16x32_bf16 v[130:133], v[190:193], v[198:201], v[130:133]
	v_mfma_f32_16x16x32_bf16 v[118:121], v[182:185], v[206:209], v[118:121]
	v_mfma_f32_16x16x32_bf16 v[114:117], v[190:193], v[206:209], v[114:117]
	v_mfma_f32_16x16x32_bf16 v[102:105], v[182:185], v[214:217], v[102:105]
	v_mfma_f32_16x16x32_bf16 v[98:101], v[190:193], v[214:217], v[98:101]
	v_mfma_f32_16x16x32_bf16 v[86:89], v[182:185], v[222:225], v[86:89]
	v_mfma_f32_16x16x32_bf16 v[82:85], v[190:193], v[222:225], v[82:85]
	s_barrier
; #define PG8_STAGE(bufoff, gbase, voff) do { _Pragma("unroll") for (int _i = 0; _i < 2; ++_i) \
;         __builtin_amdgcn_global_load_lds((const unsigned*)((const char*)(gbase) + (voff)[_i]), (LAS unsigned*)(lds + (bufoff) + ldsw + _i * 8192), 16, 0, 0); } while (0)
; #define PG8_LDA(dst, b, h) do { _Pragma("unroll") for (int m = 0; m < 4; ++m) _Pragma("unroll") for (int k = 0; k < 2; ++k) dst[m][k] = *(const LAS bf16x8*)(lds + PG8_SA(b, h) + aoff + m * 2048 + k * 1024); } while (0)
; #define PG8_LDB(dst, b, h) do { _Pragma("unroll") for (int n = 0; n < 2; ++n) _Pragma("unroll") for (int k = 0; k < 2; ++k) dst[n][k] = *(const LAS bf16x8*)(lds + PG8_SB(b, h) + boff + n * 2048 + k * 1024); } while (0)
; #define PG8_MMA(ai, bj, At, Bt) do { __builtin_amdgcn_s_setprio(1); _Pragma("unroll") for (int m = 0; m < 4; ++m) _Pragma("unroll") for (int n = 0; n < 2; ++n) _Pragma("unroll") for (int k = 0; k < 2; ++k) \
;         acc[ai][bj][m][n] = __builtin_amdgcn_mfma_f32_16x16x32_bf16(Bt[n][k], At[m][k], acc[ai][bj][m][n], 0, 0, 0); __builtin_amdgcn_s_setprio(0); } while (0)
; #define PG8_WAIT_V(n) asm volatile("s_waitcnt vmcnt(" #n ")" ::: "memory")
; #define PG8_WAIT_L(n) asm volatile("s_waitcnt lgkmcnt(" #n ")" ::: "memory")
; #define PG8_BAR __builtin_amdgcn_s_barrier()
; #define PG8_SCHED __builtin_amdgcn_sched_barrier(0)
; template <class Epi, class Sched, bool ALIGN_EPI = false, bool SP2 = false>
; __device__ __forceinline__ void gemm_phase(LAS unsigned char* lds, const Gemm g, const Sched& S, const Epi& E) {
;     ...
;             PG8_LDB(B0, 0, 0); PG8_LDB(B1, 0, 1); PG8_SCHED; PG8_LDA(At, 0, 0); PG8_STAGE(PG8_SA(1, 1), a1 + hstep, voffA);
;             PG8_WAIT_V(8); PG8_WAIT_L(0); PG8_BAR; PG8_MMA(0, 0, At, B0); PG8_MMA(0, 1, At, B1); PG8_BAR; PG8_SCHED;
;     ...
;             PG8_LDA(At, 1, 1); PG8_STAGE(PG8_SB(1, 0), b3, voffB); PG8_STAGE(PG8_SB(1, 1), b3 + hstepB, voffB); PG8_STAGE(PG8_SA(1, 0), a3, voffA);
;             PG8_WAIT_V(8); PG8_WAIT_L(0); PG8_BAR; PG8_MMA(1, 0, At, B0); PG8_MMA(1, 1, At, B1); PG8_BAR; PG8_SCHED;
	s_add_i32 s20, s22, s27
	v_lshl_add_u64 v[166:167], v[166:167], 0, s[10:11]
	s_mov_b32 m0, s20
	ds_read_b128 v[194:197], v176 offset:49152
	ds_read_b128 v[198:201], v176 offset:50176
	ds_read_b128 v[202:205], v176 offset:51200
	ds_read_b128 v[206:209], v176 offset:52224
	ds_read_b128 v[210:213], v176 offset:53248
	ds_read_b128 v[214:217], v176 offset:54272
	ds_read_b128 v[218:221], v176 offset:55296
	ds_read_b128 v[222:225], v176 offset:56320
	global_load_lds_dwordx4 v[166:167], off
	s_add_i32 m0, s20, 0x2000
	s_add_u32 s20, s50, 0x80080
	v_lshl_add_u64 v[166:167], v[226:227], 0, s[10:11]
	s_addc_u32 s21, s51, 0
	s_add_i32 s22, s23, s27
	global_load_lds_dwordx4 v[166:167], off
	v_lshl_add_u64 v[166:167], s[20:21], 0, v[150:151]
	s_mov_b32 m0, s22
	s_nop 0
	global_load_lds_dwordx4 v[166:167], off
	v_lshl_add_u64 v[166:167], s[20:21], 0, v[146:147]
	s_add_i32 m0, s22, 0x2000
	s_nop 0
	global_load_lds_dwordx4 v[166:167], off
	v_lshl_add_u64 v[166:167], v[228:229], 0, s[10:11]
	s_mov_b32 m0, s55
	s_nop 0
	global_load_lds_dwordx4 v[166:167], off
	v_lshl_add_u64 v[166:167], v[230:231], 0, s[10:11]
	s_mov_b32 m0, s56
	s_nop 0
	global_load_lds_dwordx4 v[166:167], off
	s_waitcnt vmcnt(8)
	s_waitcnt lgkmcnt(0)
	s_barrier
	s_waitcnt lgkmcnt(0)
	v_mfma_f32_16x16x32_bf16 v[62:65], v[66:69], v[194:197], v[62:65]
	v_mfma_f32_16x16x32_bf16 v[58:61], v[74:77], v[194:197], v[58:61]
	v_mfma_f32_16x16x32_bf16 v[46:49], v[66:69], v[202:205], v[46:49]
	v_mfma_f32_16x16x32_bf16 v[42:45], v[74:77], v[202:205], v[42:45]
	v_mfma_f32_16x16x32_bf16 v[30:33], v[66:69], v[210:213], v[30:33]
	v_mfma_f32_16x16x32_bf16 v[26:29], v[74:77], v[210:213], v[26:29]
	v_mfma_f32_16x16x32_bf16 v[14:17], v[66:69], v[218:221], v[14:17]
	v_mfma_f32_16x16x32_bf16 v[10:13], v[74:77], v[218:221], v[10:13]
	v_mfma_f32_16x16x32_bf16 v[62:65], v[70:73], v[198:201], v[62:65]
	v_mfma_f32_16x16x32_bf16 v[58:61], v[78:81], v[198:201], v[58:61]
	v_mfma_f32_16x16x32_bf16 v[46:49], v[70:73], v[206:209], v[46:49]
	v_mfma_f32_16x16x32_bf16 v[42:45], v[78:81], v[206:209], v[42:45]
	v_mfma_f32_16x16x32_bf16 v[30:33], v[70:73], v[214:217], v[30:33]
	v_mfma_f32_16x16x32_bf16 v[26:29], v[78:81], v[214:217], v[26:29]
	v_mfma_f32_16x16x32_bf16 v[14:17], v[70:73], v[222:225], v[14:17]
	v_mfma_f32_16x16x32_bf16 v[10:13], v[78:81], v[222:225], v[10:13]
	v_mfma_f32_16x16x32_bf16 v[54:57], v[162:165], v[194:197], v[54:57]
	v_mfma_f32_16x16x32_bf16 v[50:53], v[186:189], v[194:197], v[50:53]
	v_mfma_f32_16x16x32_bf16 v[38:41], v[162:165], v[202:205], v[38:41]
	v_mfma_f32_16x16x32_bf16 v[34:37], v[186:189], v[202:205], v[34:37]
	v_mfma_f32_16x16x32_bf16 v[22:25], v[162:165], v[210:213], v[22:25]
	v_mfma_f32_16x16x32_bf16 v[18:21], v[186:189], v[210:213], v[18:21]
	v_mfma_f32_16x16x32_bf16 v[6:9], v[162:165], v[218:221], v[6:9]
	v_mfma_f32_16x16x32_bf16 v[2:5], v[186:189], v[218:221], v[2:5]
	v_mfma_f32_16x16x32_bf16 v[54:57], v[182:185], v[198:201], v[54:57]
	v_mfma_f32_16x16x32_bf16 v[50:53], v[190:193], v[198:201], v[50:53]
	v_mfma_f32_16x16x32_bf16 v[38:41], v[182:185], v[206:209], v[38:41]
	v_mfma_f32_16x16x32_bf16 v[34:37], v[190:193], v[206:209], v[34:37]
	v_mfma_f32_16x16x32_bf16 v[22:25], v[182:185], v[214:217], v[22:25]
	v_mfma_f32_16x16x32_bf16 v[18:21], v[190:193], v[214:217], v[18:21]
	v_mfma_f32_16x16x32_bf16 v[6:9], v[182:185], v[222:225], v[6:9]
	v_mfma_f32_16x16x32_bf16 v[2:5], v[190:193], v[222:225], v[2:5]
	s_barrier
	s_add_i32 s19, s19, 2
	s_add_u32 s16, s16, 0x100
	s_addc_u32 s17, s17, 0
	s_add_u32 s15, s15, 0x100
	s_addc_u32 s18, s18, 0
	s_cmp_gt_u32 s19, 29
.LBB0_188:
	ds_read_b128 v[66:69], v174
	ds_read_b128 v[70:73], v174 offset:1024
	ds_read_b128 v[74:77], v174 offset:2048
	ds_read_b128 v[78:81], v174 offset:3072
	ds_read_b128 v[162:165], v175
	ds_read_b128 v[182:185], v175 offset:1024
	ds_read_b128 v[186:189], v175 offset:2048
	ds_read_b128 v[190:193], v175 offset:3072
	s_add_u32 s20, s16, 0xfff80080
	s_addc_u32 s21, s17, -1
	s_cmp_eq_u32 s19, 28
	s_cselect_b32 s53, s3, s21
	s_cselect_b32 s52, s12, s20
	s_cselect_b32 s51, s13, s18
	s_cselect_b32 s50, s14, s15
	v_lshl_add_u64 v[166:167], s[16:17], 0, v[154:155]
	s_add_i32 m0, s33, 0xc000
	ds_read_b128 v[194:197], v176
	ds_read_b128 v[198:201], v176 offset:1024
	ds_read_b128 v[202:205], v176 offset:2048
	ds_read_b128 v[206:209], v176 offset:3072
	ds_read_b128 v[210:213], v176 offset:4096
	ds_read_b128 v[214:217], v176 offset:5120
	ds_read_b128 v[218:221], v176 offset:6144
	ds_read_b128 v[222:225], v176 offset:7168
	global_load_lds_dwordx4 v[166:167], off
	v_lshl_add_u64 v[166:167], s[16:17], 0, v[156:157]
	s_add_i32 m0, s33, 0xe000
	s_nop 0
	global_load_lds_dwordx4 v[166:167], off
	s_waitcnt vmcnt(8)
	s_waitcnt lgkmcnt(0)
	s_barrier
; #define PG8_STAGE(bufoff, gbase, voff) do { _Pragma("unroll") for (int _i = 0; _i < 2; ++_i) \
;         __builtin_amdgcn_global_load_lds((const unsigned*)((const char*)(gbase) + (voff)[_i]), (LAS unsigned*)(lds + (bufoff) + ldsw + _i * 8192), 16, 0, 0); } while (0)
; #define PG8_LDA(dst, b, h) do { _Pragma("unroll") for (int m = 0; m < 4; ++m) _Pragma("unroll") for (int k = 0; k < 2; ++k) dst[m][k] = *(const LAS bf16x8*)(lds + PG8_SA(b, h) + aoff + m * 2048 + k * 1024); } while (0)
; #define PG8_MMA(ai, bj, At, Bt) do { __builtin_amdgcn_s_setprio(1); _Pragma("unroll") for (int m = 0; m < 4; ++m) _Pragma("unroll") for (int n = 0; n < 2; ++n) _Pragma("unroll") for (int k = 0; k < 2; ++k) \
;         acc[ai][bj][m][n] = __builtin_amdgcn_mfma_f32_16x16x32_bf16(Bt[n][k], At[m][k], acc[ai][bj][m][n], 0, 0, 0); __builtin_amdgcn_s_setprio(0); } while (0)
; #define PG8_WAIT_V(n) asm volatile("s_waitcnt vmcnt(" #n ")" ::: "memory")
; #define PG8_WAIT_L(n) asm volatile("s_waitcnt lgkmcnt(" #n ")" ::: "memory")
; #define PG8_BAR __builtin_amdgcn_s_barrier()
; #define PG8_SCHED __builtin_amdgcn_sched_barrier(0)
; template <class Epi, class Sched, bool ALIGN_EPI = false, bool SP2 = false>
; __device__ __forceinline__ void gemm_phase(LAS unsigned char* lds, const Gemm g, const Sched& S, const Epi& E) {
;     ...
;             PG8_WAIT_V(8); PG8_WAIT_L(0); PG8_BAR; PG8_MMA(0, 0, At, B0); PG8_MMA(0, 1, At, B1); PG8_BAR; PG8_SCHED;
;             PG8_LDA(At, 0, 1); PG8_STAGE(PG8_SB(0, 0), b2, voffB); PG8_STAGE(PG8_SB(0, 1), b2 + hstepB, voffB); PG8_STAGE(PG8_SA(0, 0), a2, voffA);
;             PG8_WAIT_V(8); PG8_WAIT_L(0); PG8_BAR; PG8_MMA(1, 0, At, B0); PG8_MMA(1, 1, At, B1); PG8_BAR; PG8_SCHED;
	s_waitcnt lgkmcnt(0)
	v_mfma_f32_16x16x32_bf16 v[142:145], v[66:69], v[194:197], v[142:145]
	v_mfma_f32_16x16x32_bf16 v[138:141], v[74:77], v[194:197], v[138:141]
	v_mfma_f32_16x16x32_bf16 v[126:129], v[66:69], v[202:205], v[126:129]
	v_mfma_f32_16x16x32_bf16 v[122:125], v[74:77], v[202:205], v[122:125]
	v_mfma_f32_16x16x32_bf16 v[110:113], v[66:69], v[210:213], v[110:113]
	v_mfma_f32_16x16x32_bf16 v[106:109], v[74:77], v[210:213], v[106:109]
	v_mfma_f32_16x16x32_bf16 v[94:97], v[66:69], v[218:221], v[94:97]
	v_mfma_f32_16x16x32_bf16 v[90:93], v[74:77], v[218:221], v[90:93]
	v_mfma_f32_16x16x32_bf16 v[142:145], v[70:73], v[198:201], v[142:145]
	v_mfma_f32_16x16x32_bf16 v[138:141], v[78:81], v[198:201], v[138:141]
	v_mfma_f32_16x16x32_bf16 v[126:129], v[70:73], v[206:209], v[126:129]
	v_mfma_f32_16x16x32_bf16 v[122:125], v[78:81], v[206:209], v[122:125]
	v_mfma_f32_16x16x32_bf16 v[110:113], v[70:73], v[214:217], v[110:113]
	v_mfma_f32_16x16x32_bf16 v[106:109], v[78:81], v[214:217], v[106:109]
	v_mfma_f32_16x16x32_bf16 v[94:97], v[70:73], v[222:225], v[94:97]
	v_mfma_f32_16x16x32_bf16 v[90:93], v[78:81], v[222:225], v[90:93]
	v_mfma_f32_16x16x32_bf16 v[134:137], v[162:165], v[194:197], v[134:137]
	v_mfma_f32_16x16x32_bf16 v[130:133], v[186:189], v[194:197], v[130:133]
	v_mfma_f32_16x16x32_bf16 v[118:121], v[162:165], v[202:205], v[118:121]
	v_mfma_f32_16x16x32_bf16 v[114:117], v[186:189], v[202:205], v[114:117]
	v_mfma_f32_16x16x32_bf16 v[102:105], v[162:165], v[210:213], v[102:105]
	v_mfma_f32_16x16x32_bf16 v[98:101], v[186:189], v[210:213], v[98:101]
	v_mfma_f32_16x16x32_bf16 v[86:89], v[162:165], v[218:221], v[86:89]
	v_mfma_f32_16x16x32_bf16 v[82:85], v[186:189], v[218:221], v[82:85]
	v_mfma_f32_16x16x32_bf16 v[134:137], v[182:185], v[198:201], v[134:137]
	v_mfma_f32_16x16x32_bf16 v[130:133], v[190:193], v[198:201], v[130:133]
	v_mfma_f32_16x16x32_bf16 v[118:121], v[182:185], v[206:209], v[118:121]
	v_mfma_f32_16x16x32_bf16 v[114:117], v[190:193], v[206:209], v[114:117]
	v_mfma_f32_16x16x32_bf16 v[102:105], v[182:185], v[214:217], v[102:105]
	v_mfma_f32_16x16x32_bf16 v[98:101], v[190:193], v[214:217], v[98:101]
	v_mfma_f32_16x16x32_bf16 v[86:89], v[182:185], v[222:225], v[86:89]
	v_mfma_f32_16x16x32_bf16 v[82:85], v[190:193], v[222:225], v[82:85]
	s_barrier
	s_add_i32 s20, s57, s27
	v_lshl_add_u64 v[166:167], s[50:51], 0, v[150:151]
	s_mov_b32 m0, s20
	ds_read_b128 v[194:197], v176 offset:16384
	ds_read_b128 v[198:201], v176 offset:17408
	ds_read_b128 v[202:205], v176 offset:18432
	ds_read_b128 v[206:209], v176 offset:19456
	ds_read_b128 v[210:213], v176 offset:20480
	ds_read_b128 v[214:217], v176 offset:21504
	ds_read_b128 v[218:221], v176 offset:22528
	ds_read_b128 v[222:225], v176 offset:23552
	global_load_lds_dwordx4 v[166:167], off
	s_add_i32 m0, s20, 0x2000
	s_add_u32 s20, s50, 0x80000
	v_lshl_add_u64 v[226:227], s[50:51], 0, v[146:147]
	s_addc_u32 s21, s51, 0
	s_add_i32 s22, s58, s27
	global_load_lds_dwordx4 v[226:227], off
	v_lshl_add_u64 v[228:229], s[20:21], 0, v[150:151]
	s_mov_b32 m0, s22
	v_lshl_add_u64 v[230:231], s[52:53], 0, v[148:149]
	global_load_lds_dwordx4 v[228:229], off
	v_lshl_add_u64 v[228:229], s[20:21], 0, v[146:147]
	s_add_i32 m0, s22, 0x2000
	s_nop 0
	global_load_lds_dwordx4 v[228:229], off
	v_lshl_add_u64 v[228:229], s[52:53], 0, v[152:153]
	s_mov_b32 m0, s33
	s_nop 0
	global_load_lds_dwordx4 v[228:229], off
	s_mov_b32 m0, s34
	s_nop 0
	global_load_lds_dwordx4 v[230:231], off
	s_waitcnt vmcnt(8)
	s_waitcnt lgkmcnt(0)
	s_barrier
	s_waitcnt lgkmcnt(0)
	v_mfma_f32_16x16x32_bf16 v[62:65], v[66:69], v[194:197], v[62:65]
	v_mfma_f32_16x16x32_bf16 v[58:61], v[74:77], v[194:197], v[58:61]
	v_mfma_f32_16x16x32_bf16 v[46:49], v[66:69], v[202:205], v[46:49]
	v_mfma_f32_16x16x32_bf16 v[42:45], v[74:77], v[202:205], v[42:45]
	v_mfma_f32_16x16x32_bf16 v[30:33], v[66:69], v[210:213], v[30:33]
	v_mfma_f32_16x16x32_bf16 v[26:29], v[74:77], v[210:213], v[26:29]
	v_mfma_f32_16x16x32_bf16 v[14:17], v[66:69], v[218:221], v[14:17]
	v_mfma_f32_16x16x32_bf16 v[10:13], v[74:77], v[218:221], v[10:13]
	v_mfma_f32_16x16x32_bf16 v[62:65], v[70:73], v[198:201], v[62:65]
	v_mfma_f32_16x16x32_bf16 v[58:61], v[78:81], v[198:201], v[58:61]
	v_mfma_f32_16x16x32_bf16 v[46:49], v[70:73], v[206:209], v[46:49]
	v_mfma_f32_16x16x32_bf16 v[42:45], v[78:81], v[206:209], v[42:45]
	v_mfma_f32_16x16x32_bf16 v[30:33], v[70:73], v[214:217], v[30:33]
	v_mfma_f32_16x16x32_bf16 v[26:29], v[78:81], v[214:217], v[26:29]
	v_mfma_f32_16x16x32_bf16 v[14:17], v[70:73], v[222:225], v[14:17]
	v_mfma_f32_16x16x32_bf16 v[10:13], v[78:81], v[222:225], v[10:13]
	v_mfma_f32_16x16x32_bf16 v[54:57], v[162:165], v[194:197], v[54:57]
	v_mfma_f32_16x16x32_bf16 v[50:53], v[186:189], v[194:197], v[50:53]
	v_mfma_f32_16x16x32_bf16 v[38:41], v[162:165], v[202:205], v[38:41]
	v_mfma_f32_16x16x32_bf16 v[34:37], v[186:189], v[202:205], v[34:37]
	v_mfma_f32_16x16x32_bf16 v[22:25], v[162:165], v[210:213], v[22:25]
	v_mfma_f32_16x16x32_bf16 v[18:21], v[186:189], v[210:213], v[18:21]
	v_mfma_f32_16x16x32_bf16 v[6:9], v[162:165], v[218:221], v[6:9]
	v_mfma_f32_16x16x32_bf16 v[2:5], v[186:189], v[218:221], v[2:5]
	v_mfma_f32_16x16x32_bf16 v[54:57], v[182:185], v[198:201], v[54:57]
	v_mfma_f32_16x16x32_bf16 v[50:53], v[190:193], v[198:201], v[50:53]
	v_mfma_f32_16x16x32_bf16 v[38:41], v[182:185], v[206:209], v[38:41]
	v_mfma_f32_16x16x32_bf16 v[34:37], v[190:193], v[206:209], v[34:37]
	v_mfma_f32_16x16x32_bf16 v[22:25], v[182:185], v[214:217], v[22:25]
	v_mfma_f32_16x16x32_bf16 v[18:21], v[190:193], v[214:217], v[18:21]
	v_mfma_f32_16x16x32_bf16 v[6:9], v[182:185], v[222:225], v[6:9]
	v_mfma_f32_16x16x32_bf16 v[2:5], v[190:193], v[222:225], v[2:5]
	s_barrier
; #define PG8_STAGE(bufoff, gbase, voff) do { _Pragma("unroll") for (int _i = 0; _i < 2; ++_i) \
;         __builtin_amdgcn_global_load_lds((const unsigned*)((const char*)(gbase) + (voff)[_i]), (LAS unsigned*)(lds + (bufoff) + ldsw + _i * 8192), 16, 0, 0); } while (0)
; #define PG8_LDA(dst, b, h) do { _Pragma("unroll") for (int m = 0; m < 4; ++m) _Pragma("unroll") for (int k = 0; k < 2; ++k) dst[m][k] = *(const LAS bf16x8*)(lds + PG8_SA(b, h) + aoff + m * 2048 + k * 1024); } while (0)
; #define PG8_LDB(dst, b, h) do { _Pragma("unroll") for (int n = 0; n < 2; ++n) _Pragma("unroll") for (int k = 0; k < 2; ++k) dst[n][k] = *(const LAS bf16x8*)(lds + PG8_SB(b, h) + boff + n * 2048 + k * 1024); } while (0)
; #define PG8_MMA(ai, bj, At, Bt) do { __builtin_amdgcn_s_setprio(1); _Pragma("unroll") for (int m = 0; m < 4; ++m) _Pragma("unroll") for (int n = 0; n < 2; ++n) _Pragma("unroll") for (int k = 0; k < 2; ++k) \
;         acc[ai][bj][m][n] = __builtin_amdgcn_mfma_f32_16x16x32_bf16(Bt[n][k], At[m][k], acc[ai][bj][m][n], 0, 0, 0); __builtin_amdgcn_s_setprio(0); } while (0)
; #define PG8_WAIT_V(n) asm volatile("s_waitcnt vmcnt(" #n ")" ::: "memory")
; #define PG8_WAIT_L(n) asm volatile("s_waitcnt lgkmcnt(" #n ")" ::: "memory")
; #define PG8_BAR __builtin_amdgcn_s_barrier()
; #define PG8_SCHED __builtin_amdgcn_sched_barrier(0)
; template <class Epi, class Sched, bool ALIGN_EPI = false, bool SP2 = false>
; __device__ __forceinline__ void gemm_phase(LAS unsigned char* lds, const Gemm g, const Sched& S, const Epi& E) {
;     ...
;             PG8_LDB(B0, 1, 0); PG8_LDB(B1, 1, 1); PG8_SCHED; PG8_LDA(At, 1, 0); PG8_STAGE(PG8_SA(0, 1), a2 + hstep, voffA);
;             PG8_WAIT_V(8); PG8_WAIT_L(0); PG8_BAR; PG8_MMA(0, 0, At, B0); PG8_MMA(0, 1, At, B1); PG8_BAR; PG8_SCHED;
	s_add_i32 s22, 0, 0x18000
	s_add_i32 s23, 0, 0x1c000
	v_add_u32_e32 v78, s22, v170
	v_add_u32_e32 v168, s23, v170
	ds_read_b128 v[66:69], v78
	ds_read_b128 v[70:73], v78 offset:1024
	ds_read_b128 v[74:77], v78 offset:2048
	ds_read_b128 v[78:81], v78 offset:3072
	ds_read_b128 v[162:165], v168
	ds_read_b128 v[182:185], v168 offset:1024
	ds_read_b128 v[186:189], v168 offset:2048
	ds_read_b128 v[190:193], v168 offset:3072
	s_add_u32 s20, s52, 0x80000
	s_addc_u32 s21, s53, 0
	s_mov_b32 m0, s35
	v_lshl_add_u64 v[232:233], s[20:21], 0, v[152:153]
	ds_read_b128 v[194:197], v176 offset:32768
	ds_read_b128 v[198:201], v176 offset:33792
	ds_read_b128 v[202:205], v176 offset:34816
	ds_read_b128 v[206:209], v176 offset:35840
	ds_read_b128 v[210:213], v176 offset:36864
	ds_read_b128 v[214:217], v176 offset:37888
	ds_read_b128 v[218:221], v176 offset:38912
	ds_read_b128 v[222:225], v176 offset:39936
	global_load_lds_dwordx4 v[232:233], off
	v_lshl_add_u64 v[232:233], s[20:21], 0, v[148:149]
	s_mov_b32 m0, s36
	s_nop 0
	global_load_lds_dwordx4 v[232:233], off
	s_waitcnt vmcnt(8)
	s_waitcnt lgkmcnt(0)
	s_barrier
	s_waitcnt lgkmcnt(0)
	v_mfma_f32_16x16x32_bf16 v[142:145], v[66:69], v[194:197], v[142:145]
	v_mfma_f32_16x16x32_bf16 v[138:141], v[74:77], v[194:197], v[138:141]
	v_mfma_f32_16x16x32_bf16 v[126:129], v[66:69], v[202:205], v[126:129]
	v_mfma_f32_16x16x32_bf16 v[122:125], v[74:77], v[202:205], v[122:125]
	v_mfma_f32_16x16x32_bf16 v[110:113], v[66:69], v[210:213], v[110:113]
	v_mfma_f32_16x16x32_bf16 v[106:109], v[74:77], v[210:213], v[106:109]
	v_mfma_f32_16x16x32_bf16 v[94:97], v[66:69], v[218:221], v[94:97]
	v_mfma_f32_16x16x32_bf16 v[90:93], v[74:77], v[218:221], v[90:93]
	v_mfma_f32_16x16x32_bf16 v[142:145], v[70:73], v[198:201], v[142:145]
	v_mfma_f32_16x16x32_bf16 v[138:141], v[78:81], v[198:201], v[138:141]
	v_mfma_f32_16x16x32_bf16 v[126:129], v[70:73], v[206:209], v[126:129]
	v_mfma_f32_16x16x32_bf16 v[122:125], v[78:81], v[206:209], v[122:125]
	v_mfma_f32_16x16x32_bf16 v[110:113], v[70:73], v[214:217], v[110:113]
	v_mfma_f32_16x16x32_bf16 v[106:109], v[78:81], v[214:217], v[106:109]
	v_mfma_f32_16x16x32_bf16 v[94:97], v[70:73], v[222:225], v[94:97]
	v_mfma_f32_16x16x32_bf16 v[90:93], v[78:81], v[222:225], v[90:93]
	v_mfma_f32_16x16x32_bf16 v[134:137], v[162:165], v[194:197], v[134:137]
	v_mfma_f32_16x16x32_bf16 v[130:133], v[186:189], v[194:197], v[130:133]
	v_mfma_f32_16x16x32_bf16 v[118:121], v[162:165], v[202:205], v[118:121]
	v_mfma_f32_16x16x32_bf16 v[114:117], v[186:189], v[202:205], v[114:117]
	v_mfma_f32_16x16x32_bf16 v[102:105], v[162:165], v[210:213], v[102:105]
	v_mfma_f32_16x16x32_bf16 v[98:101], v[186:189], v[210:213], v[98:101]
	v_mfma_f32_16x16x32_bf16 v[86:89], v[162:165], v[218:221], v[86:89]
	v_mfma_f32_16x16x32_bf16 v[82:85], v[186:189], v[218:221], v[82:85]
	v_mfma_f32_16x16x32_bf16 v[134:137], v[182:185], v[198:201], v[134:137]
	v_mfma_f32_16x16x32_bf16 v[130:133], v[190:193], v[198:201], v[130:133]
	v_mfma_f32_16x16x32_bf16 v[118:121], v[182:185], v[206:209], v[118:121]
	v_mfma_f32_16x16x32_bf16 v[114:117], v[190:193], v[206:209], v[114:117]
	v_mfma_f32_16x16x32_bf16 v[102:105], v[182:185], v[214:217], v[102:105]
	v_mfma_f32_16x16x32_bf16 v[98:101], v[190:193], v[214:217], v[98:101]
	v_mfma_f32_16x16x32_bf16 v[86:89], v[182:185], v[222:225], v[86:89]
	v_mfma_f32_16x16x32_bf16 v[82:85], v[190:193], v[222:225], v[82:85]
	s_barrier
; #define PG8_STAGE(bufoff, gbase, voff) do { _Pragma("unroll") for (int _i = 0; _i < 2; ++_i) \
;         __builtin_amdgcn_global_load_lds((const unsigned*)((const char*)(gbase) + (voff)[_i]), (LAS unsigned*)(lds + (bufoff) + ldsw + _i * 8192), 16, 0, 0); } while (0)
; #define PG8_LDA(dst, b, h) do { _Pragma("unroll") for (int m = 0; m < 4; ++m) _Pragma("unroll") for (int k = 0; k < 2; ++k) dst[m][k] = *(const LAS bf16x8*)(lds + PG8_SA(b, h) + aoff + m * 2048 + k * 1024); } while (0)
; #define PG8_MMA(ai, bj, At, Bt) do { __builtin_amdgcn_s_setprio(1); _Pragma("unroll") for (int m = 0; m < 4; ++m) _Pragma("unroll") for (int n = 0; n < 2; ++n) _Pragma("unroll") for (int k = 0; k < 2; ++k) \
;         acc[ai][bj][m][n] = __builtin_amdgcn_mfma_f32_16x16x32_bf16(Bt[n][k], At[m][k], acc[ai][bj][m][n], 0, 0, 0); __builtin_amdgcn_s_setprio(0); } while (0)
; #define PG8_WAIT_V(n) asm volatile("s_waitcnt vmcnt(" #n ")" ::: "memory")
; #define PG8_WAIT_L(n) asm volatile("s_waitcnt lgkmcnt(" #n ")" ::: "memory")
; #define PG8_BAR __builtin_amdgcn_s_barrier()
; #define PG8_SCHED __builtin_amdgcn_sched_barrier(0)
; template <class Epi, class Sched, bool ALIGN_EPI = false, bool SP2 = false>
; __device__ __forceinline__ void gemm_phase(LAS unsigned char* lds, const Gemm g, const Sched& S, const Epi& E) {
;     ...
;             PG8_LDA(At, 1, 1); PG8_STAGE(PG8_SB(1, 0), b3, voffB); PG8_STAGE(PG8_SB(1, 1), b3 + hstepB, voffB); PG8_STAGE(PG8_SA(1, 0), a3, voffA);
;             PG8_WAIT_V(8); PG8_WAIT_L(0); PG8_BAR; PG8_MMA(1, 0, At, B0); PG8_MMA(1, 1, At, B1); PG8_BAR; PG8_SCHED;
	s_add_i32 s20, s22, s27
	v_lshl_add_u64 v[166:167], v[166:167], 0, s[10:11]
	s_mov_b32 m0, s20
	ds_read_b128 v[194:197], v176 offset:49152
	ds_read_b128 v[198:201], v176 offset:50176
	ds_read_b128 v[202:205], v176 offset:51200
	ds_read_b128 v[206:209], v176 offset:52224
	ds_read_b128 v[210:213], v176 offset:53248
	ds_read_b128 v[214:217], v176 offset:54272
	ds_read_b128 v[218:221], v176 offset:55296
	ds_read_b128 v[222:225], v176 offset:56320
	global_load_lds_dwordx4 v[166:167], off
	s_add_i32 m0, s20, 0x2000
	s_add_u32 s20, s50, 0x80080
	v_lshl_add_u64 v[166:167], v[226:227], 0, s[10:11]
	s_addc_u32 s21, s51, 0
	s_add_i32 s22, s23, s27
	global_load_lds_dwordx4 v[166:167], off
	v_lshl_add_u64 v[166:167], s[20:21], 0, v[150:151]
	s_mov_b32 m0, s22
	s_nop 0
	global_load_lds_dwordx4 v[166:167], off
	v_lshl_add_u64 v[166:167], s[20:21], 0, v[146:147]
	s_add_i32 m0, s22, 0x2000
	s_nop 0
	global_load_lds_dwordx4 v[166:167], off
	v_lshl_add_u64 v[166:167], v[228:229], 0, s[10:11]
	s_mov_b32 m0, s55
	s_nop 0
	global_load_lds_dwordx4 v[166:167], off
	v_lshl_add_u64 v[166:167], v[230:231], 0, s[10:11]
	s_mov_b32 m0, s56
	s_nop 0
	global_load_lds_dwordx4 v[166:167], off
	s_waitcnt vmcnt(8)
	s_waitcnt lgkmcnt(0)
	s_barrier
	s_waitcnt lgkmcnt(0)
	v_mfma_f32_16x16x32_bf16 v[62:65], v[66:69], v[194:197], v[62:65]
	v_mfma_f32_16x16x32_bf16 v[58:61], v[74:77], v[194:197], v[58:61]
	v_mfma_f32_16x16x32_bf16 v[46:49], v[66:69], v[202:205], v[46:49]
	v_mfma_f32_16x16x32_bf16 v[42:45], v[74:77], v[202:205], v[42:45]
	v_mfma_f32_16x16x32_bf16 v[30:33], v[66:69], v[210:213], v[30:33]
	v_mfma_f32_16x16x32_bf16 v[26:29], v[74:77], v[210:213], v[26:29]
	v_mfma_f32_16x16x32_bf16 v[14:17], v[66:69], v[218:221], v[14:17]
	v_mfma_f32_16x16x32_bf16 v[10:13], v[74:77], v[218:221], v[10:13]
	v_mfma_f32_16x16x32_bf16 v[62:65], v[70:73], v[198:201], v[62:65]
	v_mfma_f32_16x16x32_bf16 v[58:61], v[78:81], v[198:201], v[58:61]
	v_mfma_f32_16x16x32_bf16 v[46:49], v[70:73], v[206:209], v[46:49]
	v_mfma_f32_16x16x32_bf16 v[42:45], v[78:81], v[206:209], v[42:45]
	v_mfma_f32_16x16x32_bf16 v[30:33], v[70:73], v[214:217], v[30:33]
	v_mfma_f32_16x16x32_bf16 v[26:29], v[78:81], v[214:217], v[26:29]
	v_mfma_f32_16x16x32_bf16 v[14:17], v[70:73], v[222:225], v[14:17]
	v_mfma_f32_16x16x32_bf16 v[10:13], v[78:81], v[222:225], v[10:13]
	v_mfma_f32_16x16x32_bf16 v[54:57], v[162:165], v[194:197], v[54:57]
	v_mfma_f32_16x16x32_bf16 v[50:53], v[186:189], v[194:197], v[50:53]
	v_mfma_f32_16x16x32_bf16 v[38:41], v[162:165], v[202:205], v[38:41]
	v_mfma_f32_16x16x32_bf16 v[34:37], v[186:189], v[202:205], v[34:37]
	v_mfma_f32_16x16x32_bf16 v[22:25], v[162:165], v[210:213], v[22:25]
	v_mfma_f32_16x16x32_bf16 v[18:21], v[186:189], v[210:213], v[18:21]
	v_mfma_f32_16x16x32_bf16 v[6:9], v[162:165], v[218:221], v[6:9]
	v_mfma_f32_16x16x32_bf16 v[2:5], v[186:189], v[218:221], v[2:5]
	v_mfma_f32_16x16x32_bf16 v[54:57], v[182:185], v[198:201], v[54:57]
	v_mfma_f32_16x16x32_bf16 v[50:53], v[190:193], v[198:201], v[50:53]
	v_mfma_f32_16x16x32_bf16 v[38:41], v[182:185], v[206:209], v[38:41]
	v_mfma_f32_16x16x32_bf16 v[34:37], v[190:193], v[206:209], v[34:37]
	v_mfma_f32_16x16x32_bf16 v[22:25], v[182:185], v[214:217], v[22:25]
	v_mfma_f32_16x16x32_bf16 v[18:21], v[190:193], v[214:217], v[18:21]
	v_mfma_f32_16x16x32_bf16 v[6:9], v[182:185], v[222:225], v[6:9]
	v_mfma_f32_16x16x32_bf16 v[2:5], v[190:193], v[222:225], v[2:5]
	s_barrier
	s_add_i32 s19, s19, 2
	s_add_u32 s16, s16, 0x100
	s_addc_u32 s17, s17, 0
	s_add_u32 s15, s15, 0x100
	s_addc_u32 s18, s18, 0
	s_cmp_gt_u32 s19, 29
	s_cbranch_scc0 .LBB0_188
	s_and_b64 vcc, exec, s[40:41]
	s_cbranch_vccz .LBB0_191
	s_barrier

; #define PG8_STAGE(bufoff, gbase, voff) do { _Pragma("unroll") for (int _i = 0; _i < 2; ++_i) \
;         __builtin_amdgcn_global_load_lds((const unsigned*)((const char*)(gbase) + (voff)[_i]), (LAS unsigned*)(lds + (bufoff) + ldsw + _i * 8192), 16, 0, 0); } while (0)
; #define PG8_LDA(dst, b, h) do { _Pragma("unroll") for (int m = 0; m < 4; ++m) _Pragma("unroll") for (int k = 0; k < 2; ++k) dst[m][k] = *(const LAS bf16x8*)(lds + PG8_SA(b, h) + aoff + m * 2048 + k * 1024); } while (0)
; #define PG8_LDB(dst, b, h) do { _Pragma("unroll") for (int n = 0; n < 2; ++n) _Pragma("unroll") for (int k = 0; k < 2; ++k) dst[n][k] = *(const LAS bf16x8*)(lds + PG8_SB(b, h) + boff + n * 2048 + k * 1024); } while (0)
; #define PG8_MMA(ai, bj, At, Bt) do { __builtin_amdgcn_s_setprio(1); _Pragma("unroll") for (int m = 0; m < 4; ++m) _Pragma("unroll") for (int n = 0; n < 2; ++n) _Pragma("unroll") for (int k = 0; k < 2; ++k) \
;         acc[ai][bj][m][n] = __builtin_amdgcn_mfma_f32_16x16x32_bf16(Bt[n][k], At[m][k], acc[ai][bj][m][n], 0, 0, 0); __builtin_amdgcn_s_setprio(0); } while (0)
; #define PG8_WAIT_V(n) asm volatile("s_waitcnt vmcnt(" #n ")" ::: "memory")
; #define PG8_WAIT_L(n) asm volatile("s_waitcnt lgkmcnt(" #n ")" ::: "memory")
; #define PG8_BAR __builtin_amdgcn_s_barrier()
; #define PG8_SCHED __builtin_amdgcn_sched_barrier(0)
; template <class Epi, class Sched, bool ALIGN_EPI = false, bool SP2 = false>
; __device__ __forceinline__ void gemm_phase(LAS unsigned char* lds, const Gemm g, const Sched& S, const Epi& E) {
;     ...
;             PG8_LDB(B0, 0, 0); PG8_LDB(B1, 0, 1); PG8_SCHED; PG8_LDA(At, 0, 0); PG8_STAGE(PG8_SA(1, 1), a1 + hstep, voffA);
;             PG8_WAIT_V(8); PG8_WAIT_L(0); PG8_BAR; PG8_MMA(0, 0, At, B0); PG8_MMA(0, 1, At, B1); PG8_BAR; PG8_SCHED;
;             PG8_LDA(At, 0, 1); PG8_STAGE(PG8_SB(0, 0), b2, voffB); PG8_STAGE(PG8_SB(0, 1), b2 + hstepB, voffB); PG8_STAGE(PG8_SA(0, 0), a2, voffA);
;             PG8_WAIT_V(8); PG8_WAIT_L(0); PG8_BAR; PG8_MMA(1, 0, At, B0); PG8_MMA(1, 1, At, B1); PG8_BAR; PG8_SCHED;
.LBB0_288:
	ds_read_b128 v[144:147], v135
	ds_read_b128 v[148:151], v135 offset:1024
	ds_read_b128 v[152:155], v135 offset:2048
	ds_read_b128 v[156:159], v135 offset:3072
	ds_read_b128 v[160:163], v140
	ds_read_b128 v[164:167], v140 offset:1024
	ds_read_b128 v[168:171], v140 offset:2048
	ds_read_b128 v[172:175], v140 offset:3072
	s_add_i32 s44, s40, 2
	s_cmp_lg_u32 s24, s40
	s_cselect_b32 s40, s16, 0
	s_cselect_b32 s41, s17, 0
	s_add_u32 s42, s4, s40
	s_addc_u32 s43, s5, s41
	s_add_u32 s40, s2, s40
	s_addc_u32 s41, s3, s41
	v_lshl_add_u64 v[208:209], v[136:137], 0, s[16:17]
	s_mov_b32 m0, s25
	v_lshl_add_u64 v[208:209], v[208:209], 0, s[38:39]
	ds_read_b128 v[176:179], v141
	ds_read_b128 v[180:183], v141 offset:1024
	ds_read_b128 v[184:187], v141 offset:2048
	ds_read_b128 v[188:191], v141 offset:3072
	ds_read_b128 v[192:195], v141 offset:4096
	ds_read_b128 v[196:199], v141 offset:5120
	ds_read_b128 v[200:203], v141 offset:6144
	ds_read_b128 v[204:207], v141 offset:7168
	global_load_lds_dwordx4 v[208:209], off
	v_lshl_add_u64 v[208:209], v[138:139], 0, s[16:17]
	v_lshl_add_u64 v[208:209], v[208:209], 0, s[38:39]
	s_mov_b32 m0, s28
	s_nop 0
	global_load_lds_dwordx4 v[208:209], off
	s_waitcnt vmcnt(8)
	s_waitcnt lgkmcnt(0)
	s_barrier
	s_waitcnt lgkmcnt(0)
	v_mfma_f32_16x16x32_bf16 v[126:129], v[144:147], v[176:179], v[126:129]
	v_mfma_f32_16x16x32_bf16 v[94:97], v[152:155], v[176:179], v[94:97]
	v_mfma_f32_16x16x32_bf16 v[122:125], v[144:147], v[184:187], v[122:125]
	v_mfma_f32_16x16x32_bf16 v[90:93], v[152:155], v[184:187], v[90:93]
	v_mfma_f32_16x16x32_bf16 v[118:121], v[144:147], v[192:195], v[118:121]
	v_mfma_f32_16x16x32_bf16 v[86:89], v[152:155], v[192:195], v[86:89]
	v_mfma_f32_16x16x32_bf16 v[114:117], v[144:147], v[200:203], v[114:117]
	v_mfma_f32_16x16x32_bf16 v[82:85], v[152:155], v[200:203], v[82:85]
	v_mfma_f32_16x16x32_bf16 v[126:129], v[148:151], v[180:183], v[126:129]
	v_mfma_f32_16x16x32_bf16 v[94:97], v[156:159], v[180:183], v[94:97]
	v_mfma_f32_16x16x32_bf16 v[122:125], v[148:151], v[188:191], v[122:125]
	v_mfma_f32_16x16x32_bf16 v[90:93], v[156:159], v[188:191], v[90:93]
	v_mfma_f32_16x16x32_bf16 v[118:121], v[148:151], v[196:199], v[118:121]
	v_mfma_f32_16x16x32_bf16 v[86:89], v[156:159], v[196:199], v[86:89]
	v_mfma_f32_16x16x32_bf16 v[114:117], v[148:151], v[204:207], v[114:117]
	v_mfma_f32_16x16x32_bf16 v[82:85], v[156:159], v[204:207], v[82:85]
	v_mfma_f32_16x16x32_bf16 v[70:73], v[160:163], v[176:179], v[70:73]
	v_mfma_f32_16x16x32_bf16 v[42:45], v[168:171], v[176:179], v[42:45]
	v_mfma_f32_16x16x32_bf16 v[62:65], v[160:163], v[184:187], v[62:65]
	v_mfma_f32_16x16x32_bf16 v[34:37], v[168:171], v[184:187], v[34:37]
	v_mfma_f32_16x16x32_bf16 v[54:57], v[160:163], v[192:195], v[54:57]
	v_mfma_f32_16x16x32_bf16 v[26:29], v[168:171], v[192:195], v[26:29]
	v_mfma_f32_16x16x32_bf16 v[50:53], v[160:163], v[200:203], v[50:53]
	v_mfma_f32_16x16x32_bf16 v[18:21], v[168:171], v[200:203], v[18:21]
	v_mfma_f32_16x16x32_bf16 v[70:73], v[164:167], v[180:183], v[70:73]
	v_mfma_f32_16x16x32_bf16 v[42:45], v[172:175], v[180:183], v[42:45]
	v_mfma_f32_16x16x32_bf16 v[62:65], v[164:167], v[188:191], v[62:65]
	v_mfma_f32_16x16x32_bf16 v[34:37], v[172:175], v[188:191], v[34:37]
	v_mfma_f32_16x16x32_bf16 v[54:57], v[164:167], v[196:199], v[54:57]
	v_mfma_f32_16x16x32_bf16 v[26:29], v[172:175], v[196:199], v[26:29]
	v_mfma_f32_16x16x32_bf16 v[50:53], v[164:167], v[204:207], v[50:53]
	v_mfma_f32_16x16x32_bf16 v[18:21], v[172:175], v[204:207], v[18:21]
	s_barrier
	s_mov_b32 m0, s29
	v_lshl_add_u64 v[208:209], s[40:41], 0, v[132:133]
	s_add_u32 s46, s40, 0x160000
	ds_read_b128 v[176:179], v141 offset:16384
	ds_read_b128 v[180:183], v141 offset:17408
	ds_read_b128 v[184:187], v141 offset:18432
	ds_read_b128 v[188:191], v141 offset:19456
	ds_read_b128 v[192:195], v141 offset:20480
	ds_read_b128 v[196:199], v141 offset:21504
	ds_read_b128 v[200:203], v141 offset:22528
	ds_read_b128 v[204:207], v141 offset:23552
	global_load_lds_dwordx4 v[208:209], off
	v_lshl_add_u64 v[210:211], s[40:41], 0, v[130:131]
	s_mov_b32 m0, s30
	s_addc_u32 s47, s41, 0
	global_load_lds_dwordx4 v[210:211], off
	v_lshl_add_u64 v[212:213], s[46:47], 0, v[132:133]
	s_mov_b32 m0, s31
	v_lshl_add_u64 v[214:215], s[42:43], 0, v[130:131]
	global_load_lds_dwordx4 v[212:213], off
	v_lshl_add_u64 v[212:213], s[46:47], 0, v[130:131]
	s_mov_b32 m0, s33
	s_nop 0
	global_load_lds_dwordx4 v[212:213], off
	v_lshl_add_u64 v[212:213], s[42:43], 0, v[132:133]
	s_mov_b32 m0, s14
	s_nop 0
	global_load_lds_dwordx4 v[212:213], off
	s_mov_b32 m0, s18
	s_nop 0
	global_load_lds_dwordx4 v[214:215], off
	s_waitcnt vmcnt(8)
	s_waitcnt lgkmcnt(0)
	s_barrier
; #define PG8_STAGE(bufoff, gbase, voff) do { _Pragma("unroll") for (int _i = 0; _i < 2; ++_i) \
;         __builtin_amdgcn_global_load_lds((const unsigned*)((const char*)(gbase) + (voff)[_i]), (LAS unsigned*)(lds + (bufoff) + ldsw + _i * 8192), 16, 0, 0); } while (0)
; #define PG8_LDA(dst, b, h) do { _Pragma("unroll") for (int m = 0; m < 4; ++m) _Pragma("unroll") for (int k = 0; k < 2; ++k) dst[m][k] = *(const LAS bf16x8*)(lds + PG8_SA(b, h) + aoff + m * 2048 + k * 1024); } while (0)
; #define PG8_LDB(dst, b, h) do { _Pragma("unroll") for (int n = 0; n < 2; ++n) _Pragma("unroll") for (int k = 0; k < 2; ++k) dst[n][k] = *(const LAS bf16x8*)(lds + PG8_SB(b, h) + boff + n * 2048 + k * 1024); } while (0)
; #define PG8_MMA(ai, bj, At, Bt) do { __builtin_amdgcn_s_setprio(1); _Pragma("unroll") for (int m = 0; m < 4; ++m) _Pragma("unroll") for (int n = 0; n < 2; ++n) _Pragma("unroll") for (int k = 0; k < 2; ++k) \
;         acc[ai][bj][m][n] = __builtin_amdgcn_mfma_f32_16x16x32_bf16(Bt[n][k], At[m][k], acc[ai][bj][m][n], 0, 0, 0); __builtin_amdgcn_s_setprio(0); } while (0)
; #define PG8_WAIT_V(n) asm volatile("s_waitcnt vmcnt(" #n ")" ::: "memory")
; #define PG8_WAIT_L(n) asm volatile("s_waitcnt lgkmcnt(" #n ")" ::: "memory")
; #define PG8_BAR __builtin_amdgcn_s_barrier()
; #define PG8_SCHED __builtin_amdgcn_sched_barrier(0)
; template <class Epi, class Sched, bool ALIGN_EPI = false, bool SP2 = false>
; __device__ __forceinline__ void gemm_phase(LAS unsigned char* lds, const Gemm g, const Sched& S, const Epi& E) {
;     ...
;             PG8_WAIT_V(8); PG8_WAIT_L(0); PG8_BAR; PG8_MMA(1, 0, At, B0); PG8_MMA(1, 1, At, B1); PG8_BAR; PG8_SCHED;
;             PG8_LDB(B0, 1, 0); PG8_LDB(B1, 1, 1); PG8_SCHED; PG8_LDA(At, 1, 0); PG8_STAGE(PG8_SA(0, 1), a2 + hstep, voffA);
;             PG8_WAIT_V(8); PG8_WAIT_L(0); PG8_BAR; PG8_MMA(0, 0, At, B0); PG8_MMA(0, 1, At, B1); PG8_BAR; PG8_SCHED;
	s_waitcnt lgkmcnt(0)
	v_mfma_f32_16x16x32_bf16 v[110:113], v[144:147], v[176:179], v[110:113]
	v_mfma_f32_16x16x32_bf16 v[78:81], v[152:155], v[176:179], v[78:81]
	v_mfma_f32_16x16x32_bf16 v[106:109], v[144:147], v[184:187], v[106:109]
	v_mfma_f32_16x16x32_bf16 v[74:77], v[152:155], v[184:187], v[74:77]
	v_mfma_f32_16x16x32_bf16 v[102:105], v[144:147], v[192:195], v[102:105]
	v_mfma_f32_16x16x32_bf16 v[66:69], v[152:155], v[192:195], v[66:69]
	v_mfma_f32_16x16x32_bf16 v[98:101], v[144:147], v[200:203], v[98:101]
	v_mfma_f32_16x16x32_bf16 v[58:61], v[152:155], v[200:203], v[58:61]
	v_mfma_f32_16x16x32_bf16 v[110:113], v[148:151], v[180:183], v[110:113]
	v_mfma_f32_16x16x32_bf16 v[78:81], v[156:159], v[180:183], v[78:81]
	v_mfma_f32_16x16x32_bf16 v[106:109], v[148:151], v[188:191], v[106:109]
	v_mfma_f32_16x16x32_bf16 v[74:77], v[156:159], v[188:191], v[74:77]
	v_mfma_f32_16x16x32_bf16 v[102:105], v[148:151], v[196:199], v[102:105]
	v_mfma_f32_16x16x32_bf16 v[66:69], v[156:159], v[196:199], v[66:69]
	v_mfma_f32_16x16x32_bf16 v[98:101], v[148:151], v[204:207], v[98:101]
	v_mfma_f32_16x16x32_bf16 v[58:61], v[156:159], v[204:207], v[58:61]
	v_mfma_f32_16x16x32_bf16 v[46:49], v[160:163], v[176:179], v[46:49]
	v_mfma_f32_16x16x32_bf16 v[14:17], v[168:171], v[176:179], v[14:17]
	v_mfma_f32_16x16x32_bf16 v[38:41], v[160:163], v[184:187], v[38:41]
	v_mfma_f32_16x16x32_bf16 v[10:13], v[168:171], v[184:187], v[10:13]
	v_mfma_f32_16x16x32_bf16 v[30:33], v[160:163], v[192:195], v[30:33]
	v_mfma_f32_16x16x32_bf16 v[6:9], v[168:171], v[192:195], v[6:9]
	v_mfma_f32_16x16x32_bf16 v[22:25], v[160:163], v[200:203], v[22:25]
	v_mfma_f32_16x16x32_bf16 v[2:5], v[168:171], v[200:203], v[2:5]
	v_mfma_f32_16x16x32_bf16 v[46:49], v[164:167], v[180:183], v[46:49]
	v_mfma_f32_16x16x32_bf16 v[14:17], v[172:175], v[180:183], v[14:17]
	v_mfma_f32_16x16x32_bf16 v[38:41], v[164:167], v[188:191], v[38:41]
	v_mfma_f32_16x16x32_bf16 v[10:13], v[172:175], v[188:191], v[10:13]
	v_mfma_f32_16x16x32_bf16 v[30:33], v[164:167], v[196:199], v[30:33]
	v_mfma_f32_16x16x32_bf16 v[6:9], v[172:175], v[196:199], v[6:9]
	v_mfma_f32_16x16x32_bf16 v[22:25], v[164:167], v[204:207], v[22:25]
	v_mfma_f32_16x16x32_bf16 v[2:5], v[172:175], v[204:207], v[2:5]
	s_barrier
	ds_read_b128 v[144:147], v142
	ds_read_b128 v[148:151], v142 offset:1024
	ds_read_b128 v[152:155], v142 offset:2048
	ds_read_b128 v[156:159], v142 offset:3072
	ds_read_b128 v[160:163], v143
	ds_read_b128 v[164:167], v143 offset:1024
	ds_read_b128 v[168:171], v143 offset:2048
	ds_read_b128 v[172:175], v143 offset:3072
	s_add_u32 s42, s42, 0x160000
	s_addc_u32 s43, s43, 0
	s_mov_b32 m0, s19
	v_lshl_add_u64 v[216:217], s[42:43], 0, v[132:133]
	ds_read_b128 v[176:179], v141 offset:32768
	ds_read_b128 v[180:183], v141 offset:33792
	ds_read_b128 v[184:187], v141 offset:34816
	ds_read_b128 v[188:191], v141 offset:35840
	ds_read_b128 v[192:195], v141 offset:36864
	ds_read_b128 v[196:199], v141 offset:37888
	ds_read_b128 v[200:203], v141 offset:38912
	ds_read_b128 v[204:207], v141 offset:39936
	global_load_lds_dwordx4 v[216:217], off
	v_lshl_add_u64 v[216:217], s[42:43], 0, v[130:131]
	s_mov_b32 m0, s20
	s_nop 0
	global_load_lds_dwordx4 v[216:217], off
	s_waitcnt vmcnt(8)
	s_waitcnt lgkmcnt(0)
	s_barrier
	s_waitcnt lgkmcnt(0)
	v_mfma_f32_16x16x32_bf16 v[126:129], v[144:147], v[176:179], v[126:129]
	v_mfma_f32_16x16x32_bf16 v[94:97], v[152:155], v[176:179], v[94:97]
	v_mfma_f32_16x16x32_bf16 v[122:125], v[144:147], v[184:187], v[122:125]
	v_mfma_f32_16x16x32_bf16 v[90:93], v[152:155], v[184:187], v[90:93]
	v_mfma_f32_16x16x32_bf16 v[118:121], v[144:147], v[192:195], v[118:121]
	v_mfma_f32_16x16x32_bf16 v[86:89], v[152:155], v[192:195], v[86:89]
	v_mfma_f32_16x16x32_bf16 v[114:117], v[144:147], v[200:203], v[114:117]
	v_mfma_f32_16x16x32_bf16 v[82:85], v[152:155], v[200:203], v[82:85]
	v_mfma_f32_16x16x32_bf16 v[126:129], v[148:151], v[180:183], v[126:129]
	v_mfma_f32_16x16x32_bf16 v[94:97], v[156:159], v[180:183], v[94:97]
	v_mfma_f32_16x16x32_bf16 v[122:125], v[148:151], v[188:191], v[122:125]
	v_mfma_f32_16x16x32_bf16 v[90:93], v[156:159], v[188:191], v[90:93]
	v_mfma_f32_16x16x32_bf16 v[118:121], v[148:151], v[196:199], v[118:121]
	v_mfma_f32_16x16x32_bf16 v[86:89], v[156:159], v[196:199], v[86:89]
	v_mfma_f32_16x16x32_bf16 v[114:117], v[148:151], v[204:207], v[114:117]
	v_mfma_f32_16x16x32_bf16 v[82:85], v[156:159], v[204:207], v[82:85]
	v_mfma_f32_16x16x32_bf16 v[70:73], v[160:163], v[176:179], v[70:73]
	v_mfma_f32_16x16x32_bf16 v[42:45], v[168:171], v[176:179], v[42:45]
	v_mfma_f32_16x16x32_bf16 v[62:65], v[160:163], v[184:187], v[62:65]
	v_mfma_f32_16x16x32_bf16 v[34:37], v[168:171], v[184:187], v[34:37]
	v_mfma_f32_16x16x32_bf16 v[54:57], v[160:163], v[192:195], v[54:57]
	v_mfma_f32_16x16x32_bf16 v[26:29], v[168:171], v[192:195], v[26:29]
	v_mfma_f32_16x16x32_bf16 v[50:53], v[160:163], v[200:203], v[50:53]
	v_mfma_f32_16x16x32_bf16 v[18:21], v[168:171], v[200:203], v[18:21]
	v_mfma_f32_16x16x32_bf16 v[70:73], v[164:167], v[180:183], v[70:73]
	v_mfma_f32_16x16x32_bf16 v[42:45], v[172:175], v[180:183], v[42:45]
	v_mfma_f32_16x16x32_bf16 v[62:65], v[164:167], v[188:191], v[62:65]
	v_mfma_f32_16x16x32_bf16 v[34:37], v[172:175], v[188:191], v[34:37]
	v_mfma_f32_16x16x32_bf16 v[54:57], v[164:167], v[196:199], v[54:57]
	v_mfma_f32_16x16x32_bf16 v[26:29], v[172:175], v[196:199], v[26:29]
	v_mfma_f32_16x16x32_bf16 v[50:53], v[164:167], v[204:207], v[50:53]
	v_mfma_f32_16x16x32_bf16 v[18:21], v[172:175], v[204:207], v[18:21]
	s_barrier
; #define PG8_STAGE(bufoff, gbase, voff) do { _Pragma("unroll") for (int _i = 0; _i < 2; ++_i) \
;         __builtin_amdgcn_global_load_lds((const unsigned*)((const char*)(gbase) + (voff)[_i]), (LAS unsigned*)(lds + (bufoff) + ldsw + _i * 8192), 16, 0, 0); } while (0)
; #define PG8_LDA(dst, b, h) do { _Pragma("unroll") for (int m = 0; m < 4; ++m) _Pragma("unroll") for (int k = 0; k < 2; ++k) dst[m][k] = *(const LAS bf16x8*)(lds + PG8_SA(b, h) + aoff + m * 2048 + k * 1024); } while (0)
; #define PG8_MMA(ai, bj, At, Bt) do { __builtin_amdgcn_s_setprio(1); _Pragma("unroll") for (int m = 0; m < 4; ++m) _Pragma("unroll") for (int n = 0; n < 2; ++n) _Pragma("unroll") for (int k = 0; k < 2; ++k) \
;         acc[ai][bj][m][n] = __builtin_amdgcn_mfma_f32_16x16x32_bf16(Bt[n][k], At[m][k], acc[ai][bj][m][n], 0, 0, 0); __builtin_amdgcn_s_setprio(0); } while (0)
; #define PG8_WAIT_V(n) asm volatile("s_waitcnt vmcnt(" #n ")" ::: "memory")
; #define PG8_WAIT_L(n) asm volatile("s_waitcnt lgkmcnt(" #n ")" ::: "memory")
; #define PG8_BAR __builtin_amdgcn_s_barrier()
; #define PG8_SCHED __builtin_amdgcn_sched_barrier(0)
; template <class Epi, class Sched, bool ALIGN_EPI = false, bool SP2 = false>
; __device__ __forceinline__ void gemm_phase(LAS unsigned char* lds, const Gemm g, const Sched& S, const Epi& E) {
;     ...
;             PG8_LDA(At, 1, 1); PG8_STAGE(PG8_SB(1, 0), b3, voffB); PG8_STAGE(PG8_SB(1, 1), b3 + hstepB, voffB); PG8_STAGE(PG8_SA(1, 0), a3, voffA);
;             PG8_WAIT_V(8); PG8_WAIT_L(0); PG8_BAR; PG8_MMA(1, 0, At, B0); PG8_MMA(1, 1, At, B1); PG8_BAR; PG8_SCHED;
	s_mov_b32 m0, s34
	v_lshl_add_u64 v[208:209], v[208:209], 0, s[10:11]
	s_add_u32 s40, s40, 0x160080
	ds_read_b128 v[176:179], v141 offset:49152
	ds_read_b128 v[180:183], v141 offset:50176
	ds_read_b128 v[184:187], v141 offset:51200
	ds_read_b128 v[188:191], v141 offset:52224
	ds_read_b128 v[192:195], v141 offset:53248
	ds_read_b128 v[196:199], v141 offset:54272
	ds_read_b128 v[200:203], v141 offset:55296
	ds_read_b128 v[204:207], v141 offset:56320
	global_load_lds_dwordx4 v[208:209], off
	v_lshl_add_u64 v[208:209], v[210:211], 0, s[10:11]
	s_mov_b32 m0, s35
	s_addc_u32 s41, s41, 0
	global_load_lds_dwordx4 v[208:209], off
	v_lshl_add_u64 v[208:209], s[40:41], 0, v[132:133]
	s_mov_b32 m0, s36
	s_nop 0
	global_load_lds_dwordx4 v[208:209], off
	v_lshl_add_u64 v[208:209], s[40:41], 0, v[130:131]
	s_mov_b32 m0, s37
	s_nop 0
	global_load_lds_dwordx4 v[208:209], off
	v_lshl_add_u64 v[208:209], v[212:213], 0, s[10:11]
	s_mov_b32 m0, s22
	s_nop 0
	global_load_lds_dwordx4 v[208:209], off
	v_lshl_add_u64 v[208:209], v[214:215], 0, s[10:11]
	s_mov_b32 m0, s23
	s_nop 0
	global_load_lds_dwordx4 v[208:209], off
	s_waitcnt vmcnt(8)
	s_waitcnt lgkmcnt(0)
	s_barrier
	s_waitcnt lgkmcnt(0)
	v_mfma_f32_16x16x32_bf16 v[110:113], v[144:147], v[176:179], v[110:113]
	v_mfma_f32_16x16x32_bf16 v[78:81], v[152:155], v[176:179], v[78:81]
	v_mfma_f32_16x16x32_bf16 v[106:109], v[144:147], v[184:187], v[106:109]
	v_mfma_f32_16x16x32_bf16 v[74:77], v[152:155], v[184:187], v[74:77]
	v_mfma_f32_16x16x32_bf16 v[102:105], v[144:147], v[192:195], v[102:105]
	v_mfma_f32_16x16x32_bf16 v[66:69], v[152:155], v[192:195], v[66:69]
	v_mfma_f32_16x16x32_bf16 v[98:101], v[144:147], v[200:203], v[98:101]
	v_mfma_f32_16x16x32_bf16 v[58:61], v[152:155], v[200:203], v[58:61]
	v_mfma_f32_16x16x32_bf16 v[110:113], v[148:151], v[180:183], v[110:113]
	v_mfma_f32_16x16x32_bf16 v[78:81], v[156:159], v[180:183], v[78:81]
	v_mfma_f32_16x16x32_bf16 v[106:109], v[148:151], v[188:191], v[106:109]
	v_mfma_f32_16x16x32_bf16 v[74:77], v[156:159], v[188:191], v[74:77]
	v_mfma_f32_16x16x32_bf16 v[102:105], v[148:151], v[196:199], v[102:105]
	v_mfma_f32_16x16x32_bf16 v[66:69], v[156:159], v[196:199], v[66:69]
	v_mfma_f32_16x16x32_bf16 v[98:101], v[148:151], v[204:207], v[98:101]
	v_mfma_f32_16x16x32_bf16 v[58:61], v[156:159], v[204:207], v[58:61]
	v_mfma_f32_16x16x32_bf16 v[46:49], v[160:163], v[176:179], v[46:49]
	v_mfma_f32_16x16x32_bf16 v[14:17], v[168:171], v[176:179], v[14:17]
	v_mfma_f32_16x16x32_bf16 v[38:41], v[160:163], v[184:187], v[38:41]
	v_mfma_f32_16x16x32_bf16 v[10:13], v[168:171], v[184:187], v[10:13]
	v_mfma_f32_16x16x32_bf16 v[30:33], v[160:163], v[192:195], v[30:33]
	v_mfma_f32_16x16x32_bf16 v[6:9], v[168:171], v[192:195], v[6:9]
	v_mfma_f32_16x16x32_bf16 v[22:25], v[160:163], v[200:203], v[22:25]
	v_mfma_f32_16x16x32_bf16 v[2:5], v[168:171], v[200:203], v[2:5]
	v_mfma_f32_16x16x32_bf16 v[46:49], v[164:167], v[180:183], v[46:49]
	v_mfma_f32_16x16x32_bf16 v[14:17], v[172:175], v[180:183], v[14:17]
	v_mfma_f32_16x16x32_bf16 v[38:41], v[164:167], v[188:191], v[38:41]
	v_mfma_f32_16x16x32_bf16 v[10:13], v[172:175], v[188:191], v[10:13]
	v_mfma_f32_16x16x32_bf16 v[30:33], v[164:167], v[196:199], v[30:33]
	v_mfma_f32_16x16x32_bf16 v[6:9], v[172:175], v[196:199], v[6:9]
	v_mfma_f32_16x16x32_bf16 v[22:25], v[164:167], v[204:207], v[22:25]
	v_mfma_f32_16x16x32_bf16 v[2:5], v[172:175], v[204:207], v[2:5]
	s_barrier
	s_add_u32 s16, s16, 0x100
	s_addc_u32 s17, s17, 0
	s_cmp_ge_u32 s44, s21
	s_mov_b32 s40, s44
	s_cbranch_scc0 .LBB0_288
	v_readlane_b32 s30, v252, 2
	s_cmpk_lt_u32 s13, 0x100
	v_readlane_b32 s31, v252, 3
	s_mov_b64 s[34:35], s[78:79]
	s_cbranch_scc0 .LBB0_291
	s_barrier

; #define PG8_STAGE(bufoff, gbase, voff) do { _Pragma("unroll") for (int _i = 0; _i < 2; ++_i) \
;         __builtin_amdgcn_global_load_lds((const unsigned*)((const char*)(gbase) + (voff)[_i]), (LAS unsigned*)(lds + (bufoff) + ldsw + _i * 8192), 16, 0, 0); } while (0)
; #define PG8_LDA(dst, b, h) do { _Pragma("unroll") for (int m = 0; m < 4; ++m) _Pragma("unroll") for (int k = 0; k < 2; ++k) dst[m][k] = *(const LAS bf16x8*)(lds + PG8_SA(b, h) + aoff + m * 2048 + k * 1024); } while (0)
; #define PG8_LDB(dst, b, h) do { _Pragma("unroll") for (int n = 0; n < 2; ++n) _Pragma("unroll") for (int k = 0; k < 2; ++k) dst[n][k] = *(const LAS bf16x8*)(lds + PG8_SB(b, h) + boff + n * 2048 + k * 1024); } while (0)
; #define PG8_MMA(ai, bj, At, Bt) do { __builtin_amdgcn_s_setprio(1); _Pragma("unroll") for (int m = 0; m < 4; ++m) _Pragma("unroll") for (int n = 0; n < 2; ++n) _Pragma("unroll") for (int k = 0; k < 2; ++k) \
;         acc[ai][bj][m][n] = __builtin_amdgcn_mfma_f32_16x16x32_bf16(Bt[n][k], At[m][k], acc[ai][bj][m][n], 0, 0, 0); __builtin_amdgcn_s_setprio(0); } while (0)
; #define PG8_WAIT_V(n) asm volatile("s_waitcnt vmcnt(" #n ")" ::: "memory")
; #define PG8_WAIT_L(n) asm volatile("s_waitcnt lgkmcnt(" #n ")" ::: "memory")
; #define PG8_BAR __builtin_amdgcn_s_barrier()
; #define PG8_SCHED __builtin_amdgcn_sched_barrier(0)
; template <class Epi, class Sched, bool ALIGN_EPI = false, bool SP2 = false>
; __device__ __forceinline__ void gemm_phase(LAS unsigned char* lds, const Gemm g, const Sched& S, const Epi& E) {
;     ...
;             PG8_LDB(B0, 0, 0); PG8_LDB(B1, 0, 1); PG8_SCHED; PG8_LDA(At, 0, 0); PG8_STAGE(PG8_SA(1, 1), a1 + hstep, voffA);
;             PG8_WAIT_V(8); PG8_WAIT_L(0); PG8_BAR; PG8_MMA(0, 0, At, B0); PG8_MMA(0, 1, At, B1); PG8_BAR; PG8_SCHED;
;             PG8_LDA(At, 0, 1); PG8_STAGE(PG8_SB(0, 0), b2, voffB); PG8_STAGE(PG8_SB(0, 1), b2 + hstepB, voffB); PG8_STAGE(PG8_SA(0, 0), a2, voffA);
;             PG8_WAIT_V(8); PG8_WAIT_L(0); PG8_BAR; PG8_MMA(1, 0, At, B0); PG8_MMA(1, 1, At, B1); PG8_BAR; PG8_SCHED;
.LBB0_316:
	s_add_u32 s5, s22, 0x100
	s_addc_u32 s12, s23, 0
	s_mov_b32 s13, -2
	ds_read_b128 v[130:133], v196
	ds_read_b128 v[134:137], v196 offset:1024
	ds_read_b128 v[138:141], v196 offset:2048
	ds_read_b128 v[142:145], v196 offset:3072
	ds_read_b128 v[166:169], v197
	ds_read_b128 v[170:173], v197 offset:1024
	ds_read_b128 v[174:177], v197 offset:2048
	ds_read_b128 v[178:181], v197 offset:3072
	s_add_u32 s54, s16, 0x100
	s_addc_u32 s55, s17, 0
	s_cmpk_eq_i32 s13, 0x54
	s_cselect_b32 s59, s3, s55
	s_cselect_b32 s58, s2, s54
	s_cselect_b32 s57, s53, s12
	s_cselect_b32 s56, s52, s5
	v_lshl_add_u64 v[190:191], s[16:17], 0, v[158:159]
	s_add_i32 m0, s29, 0xc000
	ds_read_b128 v[182:185], v198
	ds_read_b128 v[186:189], v198 offset:1024
	ds_read_b128 v[202:205], v198 offset:2048
	ds_read_b128 v[206:209], v198 offset:3072
	ds_read_b128 v[210:213], v198 offset:4096
	ds_read_b128 v[214:217], v198 offset:5120
	ds_read_b128 v[218:221], v198 offset:6144
	ds_read_b128 v[222:225], v198 offset:7168
	global_load_lds_dwordx4 v[190:191], off
	v_lshl_add_u64 v[190:191], s[16:17], 0, v[160:161]
	s_add_i32 m0, s29, 0xe000
	s_nop 0
	global_load_lds_dwordx4 v[190:191], off
	s_waitcnt lgkmcnt(0)
	s_barrier
	s_waitcnt lgkmcnt(0)
	v_mfma_f32_16x16x32_bf16 v[126:129], v[130:133], v[182:185], 0
	v_mfma_f32_16x16x32_bf16 v[122:125], v[138:141], v[182:185], 0
	v_mfma_f32_16x16x32_bf16 v[110:113], v[130:133], v[202:205], 0
	v_mfma_f32_16x16x32_bf16 v[106:109], v[138:141], v[202:205], 0
	v_mfma_f32_16x16x32_bf16 v[94:97], v[130:133], v[210:213], 0
	v_mfma_f32_16x16x32_bf16 v[90:93], v[138:141], v[210:213], 0
	v_mfma_f32_16x16x32_bf16 v[78:81], v[130:133], v[218:221], 0
	v_mfma_f32_16x16x32_bf16 v[74:77], v[138:141], v[218:221], 0
	v_mfma_f32_16x16x32_bf16 v[126:129], v[134:137], v[186:189], v[126:129]
	v_mfma_f32_16x16x32_bf16 v[122:125], v[142:145], v[186:189], v[122:125]
	v_mfma_f32_16x16x32_bf16 v[110:113], v[134:137], v[206:209], v[110:113]
	v_mfma_f32_16x16x32_bf16 v[106:109], v[142:145], v[206:209], v[106:109]
	v_mfma_f32_16x16x32_bf16 v[94:97], v[134:137], v[214:217], v[94:97]
	v_mfma_f32_16x16x32_bf16 v[90:93], v[142:145], v[214:217], v[90:93]
	v_mfma_f32_16x16x32_bf16 v[78:81], v[134:137], v[222:225], v[78:81]
	v_mfma_f32_16x16x32_bf16 v[74:77], v[142:145], v[222:225], v[74:77]
	v_mfma_f32_16x16x32_bf16 v[118:121], v[166:169], v[182:185], 0
	v_mfma_f32_16x16x32_bf16 v[114:117], v[174:177], v[182:185], 0
	v_mfma_f32_16x16x32_bf16 v[102:105], v[166:169], v[202:205], 0
	v_mfma_f32_16x16x32_bf16 v[98:101], v[174:177], v[202:205], 0
	v_mfma_f32_16x16x32_bf16 v[86:89], v[166:169], v[210:213], 0
	v_mfma_f32_16x16x32_bf16 v[82:85], v[174:177], v[210:213], 0
	v_mfma_f32_16x16x32_bf16 v[70:73], v[166:169], v[218:221], 0
	v_mfma_f32_16x16x32_bf16 v[66:69], v[174:177], v[218:221], 0
	v_mfma_f32_16x16x32_bf16 v[118:121], v[170:173], v[186:189], v[118:121]
	v_mfma_f32_16x16x32_bf16 v[114:117], v[178:181], v[186:189], v[114:117]
	v_mfma_f32_16x16x32_bf16 v[102:105], v[170:173], v[206:209], v[102:105]
	v_mfma_f32_16x16x32_bf16 v[98:101], v[178:181], v[206:209], v[98:101]
	v_mfma_f32_16x16x32_bf16 v[86:89], v[170:173], v[214:217], v[86:89]
	v_mfma_f32_16x16x32_bf16 v[82:85], v[178:181], v[214:217], v[82:85]
	v_mfma_f32_16x16x32_bf16 v[70:73], v[170:173], v[222:225], v[70:73]
	v_mfma_f32_16x16x32_bf16 v[66:69], v[178:181], v[222:225], v[66:69]
	s_barrier
	s_add_i32 s14, s64, s28
	v_lshl_add_u64 v[190:191], s[56:57], 0, v[148:149]
	s_mov_b32 m0, s14
	ds_read_b128 v[182:185], v198 offset:16384
	ds_read_b128 v[186:189], v198 offset:17408
	ds_read_b128 v[202:205], v198 offset:18432
	ds_read_b128 v[206:209], v198 offset:19456
	ds_read_b128 v[210:213], v198 offset:20480
	ds_read_b128 v[214:217], v198 offset:21504
	ds_read_b128 v[218:221], v198 offset:22528
	ds_read_b128 v[222:225], v198 offset:23552
	global_load_lds_dwordx4 v[190:191], off
	s_add_i32 m0, s14, 0x2000
	s_add_u32 s14, s56, 0x58000
	v_lshl_add_u64 v[226:227], s[56:57], 0, v[152:153]
	s_addc_u32 s15, s57, 0
	s_add_i32 s16, s65, s28
	global_load_lds_dwordx4 v[226:227], off
	v_lshl_add_u64 v[228:229], s[14:15], 0, v[148:149]
	s_mov_b32 m0, s16
	v_lshl_add_u64 v[230:231], s[58:59], 0, v[150:151]
	global_load_lds_dwordx4 v[228:229], off
	v_lshl_add_u64 v[228:229], s[14:15], 0, v[152:153]
	s_add_i32 m0, s16, 0x2000
	s_nop 0
	global_load_lds_dwordx4 v[228:229], off
	v_lshl_add_u64 v[228:229], s[58:59], 0, v[146:147]
	s_mov_b32 m0, s29
	s_nop 0
	global_load_lds_dwordx4 v[228:229], off
	s_mov_b32 m0, s30
	s_nop 0
	global_load_lds_dwordx4 v[230:231], off
	s_waitcnt lgkmcnt(0)
	s_barrier
	s_waitcnt lgkmcnt(0)
	v_mfma_f32_16x16x32_bf16 v[62:65], v[130:133], v[182:185], 0
	v_mfma_f32_16x16x32_bf16 v[58:61], v[138:141], v[182:185], 0
	v_mfma_f32_16x16x32_bf16 v[46:49], v[130:133], v[202:205], 0
	v_mfma_f32_16x16x32_bf16 v[42:45], v[138:141], v[202:205], 0
	v_mfma_f32_16x16x32_bf16 v[30:33], v[130:133], v[210:213], 0
	v_mfma_f32_16x16x32_bf16 v[26:29], v[138:141], v[210:213], 0
	v_mfma_f32_16x16x32_bf16 v[14:17], v[130:133], v[218:221], 0
	v_mfma_f32_16x16x32_bf16 v[10:13], v[138:141], v[218:221], 0
	v_mfma_f32_16x16x32_bf16 v[62:65], v[134:137], v[186:189], v[62:65]
	v_mfma_f32_16x16x32_bf16 v[58:61], v[142:145], v[186:189], v[58:61]
	v_mfma_f32_16x16x32_bf16 v[46:49], v[134:137], v[206:209], v[46:49]
	v_mfma_f32_16x16x32_bf16 v[42:45], v[142:145], v[206:209], v[42:45]
	v_mfma_f32_16x16x32_bf16 v[30:33], v[134:137], v[214:217], v[30:33]
	v_mfma_f32_16x16x32_bf16 v[26:29], v[142:145], v[214:217], v[26:29]
	v_mfma_f32_16x16x32_bf16 v[14:17], v[134:137], v[222:225], v[14:17]
	v_mfma_f32_16x16x32_bf16 v[10:13], v[142:145], v[222:225], v[10:13]
	v_mfma_f32_16x16x32_bf16 v[54:57], v[166:169], v[182:185], 0
	v_mfma_f32_16x16x32_bf16 v[50:53], v[174:177], v[182:185], 0
	v_mfma_f32_16x16x32_bf16 v[38:41], v[166:169], v[202:205], 0
	v_mfma_f32_16x16x32_bf16 v[34:37], v[174:177], v[202:205], 0
	v_mfma_f32_16x16x32_bf16 v[22:25], v[166:169], v[210:213], 0
	v_mfma_f32_16x16x32_bf16 v[18:21], v[174:177], v[210:213], 0
	v_mfma_f32_16x16x32_bf16 v[6:9], v[166:169], v[218:221], 0
	v_mfma_f32_16x16x32_bf16 v[2:5], v[174:177], v[218:221], 0
	v_mfma_f32_16x16x32_bf16 v[54:57], v[170:173], v[186:189], v[54:57]
	v_mfma_f32_16x16x32_bf16 v[50:53], v[178:181], v[186:189], v[50:53]
	v_mfma_f32_16x16x32_bf16 v[38:41], v[170:173], v[206:209], v[38:41]
	v_mfma_f32_16x16x32_bf16 v[34:37], v[178:181], v[206:209], v[34:37]
	v_mfma_f32_16x16x32_bf16 v[22:25], v[170:173], v[214:217], v[22:25]
	v_mfma_f32_16x16x32_bf16 v[18:21], v[178:181], v[214:217], v[18:21]
	v_mfma_f32_16x16x32_bf16 v[6:9], v[170:173], v[222:225], v[6:9]
	v_mfma_f32_16x16x32_bf16 v[2:5], v[178:181], v[222:225], v[2:5]
	s_barrier
; #define PG8_STAGE(bufoff, gbase, voff) do { _Pragma("unroll") for (int _i = 0; _i < 2; ++_i) \
;         __builtin_amdgcn_global_load_lds((const unsigned*)((const char*)(gbase) + (voff)[_i]), (LAS unsigned*)(lds + (bufoff) + ldsw + _i * 8192), 16, 0, 0); } while (0)
; #define PG8_LDA(dst, b, h) do { _Pragma("unroll") for (int m = 0; m < 4; ++m) _Pragma("unroll") for (int k = 0; k < 2; ++k) dst[m][k] = *(const LAS bf16x8*)(lds + PG8_SA(b, h) + aoff + m * 2048 + k * 1024); } while (0)
; #define PG8_LDB(dst, b, h) do { _Pragma("unroll") for (int n = 0; n < 2; ++n) _Pragma("unroll") for (int k = 0; k < 2; ++k) dst[n][k] = *(const LAS bf16x8*)(lds + PG8_SB(b, h) + boff + n * 2048 + k * 1024); } while (0)
; #define PG8_MMA(ai, bj, At, Bt) do { __builtin_amdgcn_s_setprio(1); _Pragma("unroll") for (int m = 0; m < 4; ++m) _Pragma("unroll") for (int n = 0; n < 2; ++n) _Pragma("unroll") for (int k = 0; k < 2; ++k) \
;         acc[ai][bj][m][n] = __builtin_amdgcn_mfma_f32_16x16x32_bf16(Bt[n][k], At[m][k], acc[ai][bj][m][n], 0, 0, 0); __builtin_amdgcn_s_setprio(0); } while (0)
; #define PG8_WAIT_V(n) asm volatile("s_waitcnt vmcnt(" #n ")" ::: "memory")
; #define PG8_WAIT_L(n) asm volatile("s_waitcnt lgkmcnt(" #n ")" ::: "memory")
; #define PG8_BAR __builtin_amdgcn_s_barrier()
; #define PG8_SCHED __builtin_amdgcn_sched_barrier(0)
; template <class Epi, class Sched, bool ALIGN_EPI = false, bool SP2 = false>
; __device__ __forceinline__ void gemm_phase(LAS unsigned char* lds, const Gemm g, const Sched& S, const Epi& E) {
;     ...
;             PG8_LDB(B0, 1, 0); PG8_LDB(B1, 1, 1); PG8_SCHED; PG8_LDA(At, 1, 0); PG8_STAGE(PG8_SA(0, 1), a2 + hstep, voffA);
;             PG8_WAIT_V(8); PG8_WAIT_L(0); PG8_BAR; PG8_MMA(0, 0, At, B0); PG8_MMA(0, 1, At, B1); PG8_BAR; PG8_SCHED;
;             PG8_LDA(At, 1, 1); PG8_STAGE(PG8_SB(1, 0), b3, voffB); PG8_STAGE(PG8_SB(1, 1), b3 + hstepB, voffB); PG8_STAGE(PG8_SA(1, 0), a3, voffA);
;             PG8_WAIT_V(8); PG8_WAIT_L(0); PG8_BAR; PG8_MMA(1, 0, At, B0); PG8_MMA(1, 1, At, B1); PG8_BAR; PG8_SCHED;
	s_add_i32 s16, 0, 0x18000
	s_add_i32 s17, 0, 0x1c000
	v_add_u32_e32 v142, s16, v1
	v_add_u32_e32 v154, s17, v1
	ds_read_b128 v[130:133], v142
	ds_read_b128 v[134:137], v142 offset:1024
	ds_read_b128 v[138:141], v142 offset:2048
	ds_read_b128 v[142:145], v142 offset:3072
	ds_read_b128 v[166:169], v154
	ds_read_b128 v[170:173], v154 offset:1024
	ds_read_b128 v[174:177], v154 offset:2048
	ds_read_b128 v[178:181], v154 offset:3072
	s_add_u32 s14, s58, 0x160000
	s_addc_u32 s15, s59, 0
	s_mov_b32 m0, s31
	v_lshl_add_u64 v[232:233], s[14:15], 0, v[146:147]
	ds_read_b128 v[182:185], v198 offset:32768
	ds_read_b128 v[186:189], v198 offset:33792
	ds_read_b128 v[202:205], v198 offset:34816
	ds_read_b128 v[206:209], v198 offset:35840
	ds_read_b128 v[210:213], v198 offset:36864
	ds_read_b128 v[214:217], v198 offset:37888
	ds_read_b128 v[218:221], v198 offset:38912
	ds_read_b128 v[222:225], v198 offset:39936
	global_load_lds_dwordx4 v[232:233], off
	v_lshl_add_u64 v[232:233], s[14:15], 0, v[150:151]
	s_mov_b32 m0, s33
	s_nop 0
	global_load_lds_dwordx4 v[232:233], off
	s_waitcnt vmcnt(8)
	s_waitcnt lgkmcnt(0)
	s_barrier
	s_waitcnt lgkmcnt(0)
	v_mfma_f32_16x16x32_bf16 v[126:129], v[130:133], v[182:185], v[126:129]
	v_mfma_f32_16x16x32_bf16 v[122:125], v[138:141], v[182:185], v[122:125]
	v_mfma_f32_16x16x32_bf16 v[110:113], v[130:133], v[202:205], v[110:113]
	v_mfma_f32_16x16x32_bf16 v[106:109], v[138:141], v[202:205], v[106:109]
	v_mfma_f32_16x16x32_bf16 v[94:97], v[130:133], v[210:213], v[94:97]
	v_mfma_f32_16x16x32_bf16 v[90:93], v[138:141], v[210:213], v[90:93]
	v_mfma_f32_16x16x32_bf16 v[78:81], v[130:133], v[218:221], v[78:81]
	v_mfma_f32_16x16x32_bf16 v[74:77], v[138:141], v[218:221], v[74:77]
	v_mfma_f32_16x16x32_bf16 v[126:129], v[134:137], v[186:189], v[126:129]
	v_mfma_f32_16x16x32_bf16 v[122:125], v[142:145], v[186:189], v[122:125]
	v_mfma_f32_16x16x32_bf16 v[110:113], v[134:137], v[206:209], v[110:113]
	v_mfma_f32_16x16x32_bf16 v[106:109], v[142:145], v[206:209], v[106:109]
	v_mfma_f32_16x16x32_bf16 v[94:97], v[134:137], v[214:217], v[94:97]
	v_mfma_f32_16x16x32_bf16 v[90:93], v[142:145], v[214:217], v[90:93]
	v_mfma_f32_16x16x32_bf16 v[78:81], v[134:137], v[222:225], v[78:81]
	v_mfma_f32_16x16x32_bf16 v[74:77], v[142:145], v[222:225], v[74:77]
	v_mfma_f32_16x16x32_bf16 v[118:121], v[166:169], v[182:185], v[118:121]
	v_mfma_f32_16x16x32_bf16 v[114:117], v[174:177], v[182:185], v[114:117]
	v_mfma_f32_16x16x32_bf16 v[102:105], v[166:169], v[202:205], v[102:105]
	v_mfma_f32_16x16x32_bf16 v[98:101], v[174:177], v[202:205], v[98:101]
	v_mfma_f32_16x16x32_bf16 v[86:89], v[166:169], v[210:213], v[86:89]
	v_mfma_f32_16x16x32_bf16 v[82:85], v[174:177], v[210:213], v[82:85]
	v_mfma_f32_16x16x32_bf16 v[70:73], v[166:169], v[218:221], v[70:73]
	v_mfma_f32_16x16x32_bf16 v[66:69], v[174:177], v[218:221], v[66:69]
	v_mfma_f32_16x16x32_bf16 v[118:121], v[170:173], v[186:189], v[118:121]
	v_mfma_f32_16x16x32_bf16 v[114:117], v[178:181], v[186:189], v[114:117]
	v_mfma_f32_16x16x32_bf16 v[102:105], v[170:173], v[206:209], v[102:105]
	v_mfma_f32_16x16x32_bf16 v[98:101], v[178:181], v[206:209], v[98:101]
	v_mfma_f32_16x16x32_bf16 v[86:89], v[170:173], v[214:217], v[86:89]
	v_mfma_f32_16x16x32_bf16 v[82:85], v[178:181], v[214:217], v[82:85]
	v_mfma_f32_16x16x32_bf16 v[70:73], v[170:173], v[222:225], v[70:73]
	v_mfma_f32_16x16x32_bf16 v[66:69], v[178:181], v[222:225], v[66:69]
	s_barrier
	s_add_i32 s14, s16, s28
	v_lshl_add_u64 v[190:191], v[190:191], 0, s[48:49]
	s_mov_b32 m0, s14
	ds_read_b128 v[182:185], v198 offset:49152
	ds_read_b128 v[186:189], v198 offset:50176
	ds_read_b128 v[202:205], v198 offset:51200
	ds_read_b128 v[206:209], v198 offset:52224
	ds_read_b128 v[210:213], v198 offset:53248
	ds_read_b128 v[214:217], v198 offset:54272
	ds_read_b128 v[218:221], v198 offset:55296
	ds_read_b128 v[222:225], v198 offset:56320
	global_load_lds_dwordx4 v[190:191], off
	s_add_i32 m0, s14, 0x2000
	s_add_u32 s14, s56, 0x58080
	v_lshl_add_u64 v[190:191], v[226:227], 0, s[48:49]
	s_addc_u32 s15, s57, 0
	s_add_i32 s16, s17, s28
	global_load_lds_dwordx4 v[190:191], off
	v_lshl_add_u64 v[190:191], s[14:15], 0, v[148:149]
	s_mov_b32 m0, s16
	s_nop 0
	global_load_lds_dwordx4 v[190:191], off
	v_lshl_add_u64 v[190:191], s[14:15], 0, v[152:153]
	s_add_i32 m0, s16, 0x2000
	s_nop 0
	global_load_lds_dwordx4 v[190:191], off
	v_lshl_add_u64 v[190:191], v[228:229], 0, s[48:49]
	s_mov_b32 m0, s61
	s_nop 0
	global_load_lds_dwordx4 v[190:191], off
	v_lshl_add_u64 v[190:191], v[230:231], 0, s[48:49]
	s_mov_b32 m0, s62
	s_nop 0
	global_load_lds_dwordx4 v[190:191], off
	s_waitcnt vmcnt(8)
	s_waitcnt lgkmcnt(0)
	s_barrier
	s_waitcnt lgkmcnt(0)
	v_mfma_f32_16x16x32_bf16 v[62:65], v[130:133], v[182:185], v[62:65]
	v_mfma_f32_16x16x32_bf16 v[58:61], v[138:141], v[182:185], v[58:61]
	v_mfma_f32_16x16x32_bf16 v[46:49], v[130:133], v[202:205], v[46:49]
	v_mfma_f32_16x16x32_bf16 v[42:45], v[138:141], v[202:205], v[42:45]
	v_mfma_f32_16x16x32_bf16 v[30:33], v[130:133], v[210:213], v[30:33]
	v_mfma_f32_16x16x32_bf16 v[26:29], v[138:141], v[210:213], v[26:29]
	v_mfma_f32_16x16x32_bf16 v[14:17], v[130:133], v[218:221], v[14:17]
	v_mfma_f32_16x16x32_bf16 v[10:13], v[138:141], v[218:221], v[10:13]
	v_mfma_f32_16x16x32_bf16 v[62:65], v[134:137], v[186:189], v[62:65]
	v_mfma_f32_16x16x32_bf16 v[58:61], v[142:145], v[186:189], v[58:61]
	v_mfma_f32_16x16x32_bf16 v[46:49], v[134:137], v[206:209], v[46:49]
	v_mfma_f32_16x16x32_bf16 v[42:45], v[142:145], v[206:209], v[42:45]
	v_mfma_f32_16x16x32_bf16 v[30:33], v[134:137], v[214:217], v[30:33]
	v_mfma_f32_16x16x32_bf16 v[26:29], v[142:145], v[214:217], v[26:29]
	v_mfma_f32_16x16x32_bf16 v[14:17], v[134:137], v[222:225], v[14:17]
	v_mfma_f32_16x16x32_bf16 v[10:13], v[142:145], v[222:225], v[10:13]
	v_mfma_f32_16x16x32_bf16 v[54:57], v[166:169], v[182:185], v[54:57]
	v_mfma_f32_16x16x32_bf16 v[50:53], v[174:177], v[182:185], v[50:53]
	v_mfma_f32_16x16x32_bf16 v[38:41], v[166:169], v[202:205], v[38:41]
	v_mfma_f32_16x16x32_bf16 v[34:37], v[174:177], v[202:205], v[34:37]
	v_mfma_f32_16x16x32_bf16 v[22:25], v[166:169], v[210:213], v[22:25]
	v_mfma_f32_16x16x32_bf16 v[18:21], v[174:177], v[210:213], v[18:21]
	v_mfma_f32_16x16x32_bf16 v[6:9], v[166:169], v[218:221], v[6:9]
	v_mfma_f32_16x16x32_bf16 v[2:5], v[174:177], v[218:221], v[2:5]
	v_mfma_f32_16x16x32_bf16 v[54:57], v[170:173], v[186:189], v[54:57]
	v_mfma_f32_16x16x32_bf16 v[50:53], v[178:181], v[186:189], v[50:53]
	v_mfma_f32_16x16x32_bf16 v[38:41], v[170:173], v[206:209], v[38:41]
	v_mfma_f32_16x16x32_bf16 v[34:37], v[178:181], v[206:209], v[34:37]
	v_mfma_f32_16x16x32_bf16 v[22:25], v[170:173], v[214:217], v[22:25]
	v_mfma_f32_16x16x32_bf16 v[18:21], v[178:181], v[214:217], v[18:21]
	v_mfma_f32_16x16x32_bf16 v[6:9], v[170:173], v[222:225], v[6:9]
	v_mfma_f32_16x16x32_bf16 v[2:5], v[178:181], v[222:225], v[2:5]
	s_barrier
	s_add_i32 s13, s13, 2
	s_add_u32 s5, s5, 0x100
	s_addc_u32 s12, s12, 0
	s_cmpk_gt_u32 s13, 0x55
	s_mov_b64 s[16:17], s[54:55]
; #define PG8_STAGE(bufoff, gbase, voff) do { _Pragma("unroll") for (int _i = 0; _i < 2; ++_i) \
;         __builtin_amdgcn_global_load_lds((const unsigned*)((const char*)(gbase) + (voff)[_i]), (LAS unsigned*)(lds + (bufoff) + ldsw + _i * 8192), 16, 0, 0); } while (0)
; #define PG8_LDA(dst, b, h) do { _Pragma("unroll") for (int m = 0; m < 4; ++m) _Pragma("unroll") for (int k = 0; k < 2; ++k) dst[m][k] = *(const LAS bf16x8*)(lds + PG8_SA(b, h) + aoff + m * 2048 + k * 1024); } while (0)
; #define PG8_LDB(dst, b, h) do { _Pragma("unroll") for (int n = 0; n < 2; ++n) _Pragma("unroll") for (int k = 0; k < 2; ++k) dst[n][k] = *(const LAS bf16x8*)(lds + PG8_SB(b, h) + boff + n * 2048 + k * 1024); } while (0)
; #define PG8_MMA(ai, bj, At, Bt) do { __builtin_amdgcn_s_setprio(1); _Pragma("unroll") for (int m = 0; m < 4; ++m) _Pragma("unroll") for (int n = 0; n < 2; ++n) _Pragma("unroll") for (int k = 0; k < 2; ++k) \
;         acc[ai][bj][m][n] = __builtin_amdgcn_mfma_f32_16x16x32_bf16(Bt[n][k], At[m][k], acc[ai][bj][m][n], 0, 0, 0); __builtin_amdgcn_s_setprio(0); } while (0)
; #define PG8_WAIT_V(n) asm volatile("s_waitcnt vmcnt(" #n ")" ::: "memory")
; #define PG8_WAIT_L(n) asm volatile("s_waitcnt lgkmcnt(" #n ")" ::: "memory")
; #define PG8_BAR __builtin_amdgcn_s_barrier()
; #define PG8_SCHED __builtin_amdgcn_sched_barrier(0)
; template <class Epi, class Sched, bool ALIGN_EPI = false, bool SP2 = false>
; __device__ __forceinline__ void gemm_phase(LAS unsigned char* lds, const Gemm g, const Sched& S, const Epi& E) {
;     ...
;         for (int t = 0; t < nt; t += 2) {
;             const bool last = (t == nt - 2);
;             const char* a1 = cA + (size_t)(t + 1) * kstep;
;             const char* a2 = last ? nA : cA + (size_t)(t + 2) * kstep; const char* b2 = last ? nB : cB + (size_t)(t + 2) * kstep;
;             const char* a3 = a2 + kstep; const char* b3 = b2 + kstep;
;             if (last && has_next) S.a_ready(nxt);
;             if constexpr (SP2) {
;             PG8_LDB(B0, 0, 0); PG8_LDB(B1, 0, 1); PG8_SCHED; PG8_LDA(At, 0, 0); PG8_STAGE(PG8_SA(1, 1), a1 + hstep, voffA);
;             PG8_WAIT_V(8); PG8_WAIT_L(0); PG8_BAR; PG8_MMA(0, 0, At, B0); PG8_MMA(0, 1, At, B1); PG8_BAR; PG8_SCHED;
;             PG8_LDA(At, 0, 1); PG8_STAGE(PG8_SB(0, 0), b2, voffB); PG8_STAGE(PG8_SB(0, 1), b2 + hstepB, voffB); PG8_STAGE(PG8_SA(0, 0), a2, voffA);
.LBB0_317:
	ds_read_b128 v[130:133], v196
	ds_read_b128 v[134:137], v196 offset:1024
	ds_read_b128 v[138:141], v196 offset:2048
	ds_read_b128 v[142:145], v196 offset:3072
	ds_read_b128 v[166:169], v197
	ds_read_b128 v[170:173], v197 offset:1024
	ds_read_b128 v[174:177], v197 offset:2048
	ds_read_b128 v[178:181], v197 offset:3072
	s_add_u32 s54, s16, 0x100
	s_addc_u32 s55, s17, 0
	s_cmpk_eq_i32 s13, 0x54
	s_cselect_b32 s59, s3, s55
	s_cselect_b32 s58, s2, s54
	s_cselect_b32 s57, s53, s12
	s_cselect_b32 s56, s52, s5
	v_lshl_add_u64 v[190:191], s[16:17], 0, v[158:159]
	s_add_i32 m0, s29, 0xc000
	ds_read_b128 v[182:185], v198
	ds_read_b128 v[186:189], v198 offset:1024
	ds_read_b128 v[202:205], v198 offset:2048
	ds_read_b128 v[206:209], v198 offset:3072
	ds_read_b128 v[210:213], v198 offset:4096
	ds_read_b128 v[214:217], v198 offset:5120
	ds_read_b128 v[218:221], v198 offset:6144
	ds_read_b128 v[222:225], v198 offset:7168
	global_load_lds_dwordx4 v[190:191], off
	v_lshl_add_u64 v[190:191], s[16:17], 0, v[160:161]
	s_add_i32 m0, s29, 0xe000
	s_nop 0
	global_load_lds_dwordx4 v[190:191], off
	s_waitcnt vmcnt(8)
	s_waitcnt lgkmcnt(0)
	s_barrier
	s_waitcnt lgkmcnt(0)
	v_mfma_f32_16x16x32_bf16 v[126:129], v[130:133], v[182:185], v[126:129]
	v_mfma_f32_16x16x32_bf16 v[122:125], v[138:141], v[182:185], v[122:125]
	v_mfma_f32_16x16x32_bf16 v[110:113], v[130:133], v[202:205], v[110:113]
	v_mfma_f32_16x16x32_bf16 v[106:109], v[138:141], v[202:205], v[106:109]
	v_mfma_f32_16x16x32_bf16 v[94:97], v[130:133], v[210:213], v[94:97]
	v_mfma_f32_16x16x32_bf16 v[90:93], v[138:141], v[210:213], v[90:93]
	v_mfma_f32_16x16x32_bf16 v[78:81], v[130:133], v[218:221], v[78:81]
	v_mfma_f32_16x16x32_bf16 v[74:77], v[138:141], v[218:221], v[74:77]
	v_mfma_f32_16x16x32_bf16 v[126:129], v[134:137], v[186:189], v[126:129]
	v_mfma_f32_16x16x32_bf16 v[122:125], v[142:145], v[186:189], v[122:125]
	v_mfma_f32_16x16x32_bf16 v[110:113], v[134:137], v[206:209], v[110:113]
	v_mfma_f32_16x16x32_bf16 v[106:109], v[142:145], v[206:209], v[106:109]
	v_mfma_f32_16x16x32_bf16 v[94:97], v[134:137], v[214:217], v[94:97]
	v_mfma_f32_16x16x32_bf16 v[90:93], v[142:145], v[214:217], v[90:93]
	v_mfma_f32_16x16x32_bf16 v[78:81], v[134:137], v[222:225], v[78:81]
	v_mfma_f32_16x16x32_bf16 v[74:77], v[142:145], v[222:225], v[74:77]
	v_mfma_f32_16x16x32_bf16 v[118:121], v[166:169], v[182:185], v[118:121]
	v_mfma_f32_16x16x32_bf16 v[114:117], v[174:177], v[182:185], v[114:117]
	v_mfma_f32_16x16x32_bf16 v[102:105], v[166:169], v[202:205], v[102:105]
	v_mfma_f32_16x16x32_bf16 v[98:101], v[174:177], v[202:205], v[98:101]
	v_mfma_f32_16x16x32_bf16 v[86:89], v[166:169], v[210:213], v[86:89]
	v_mfma_f32_16x16x32_bf16 v[82:85], v[174:177], v[210:213], v[82:85]
	v_mfma_f32_16x16x32_bf16 v[70:73], v[166:169], v[218:221], v[70:73]
	v_mfma_f32_16x16x32_bf16 v[66:69], v[174:177], v[218:221], v[66:69]
	v_mfma_f32_16x16x32_bf16 v[118:121], v[170:173], v[186:189], v[118:121]
	v_mfma_f32_16x16x32_bf16 v[114:117], v[178:181], v[186:189], v[114:117]
	v_mfma_f32_16x16x32_bf16 v[102:105], v[170:173], v[206:209], v[102:105]
	v_mfma_f32_16x16x32_bf16 v[98:101], v[178:181], v[206:209], v[98:101]
	v_mfma_f32_16x16x32_bf16 v[86:89], v[170:173], v[214:217], v[86:89]
	v_mfma_f32_16x16x32_bf16 v[82:85], v[178:181], v[214:217], v[82:85]
	v_mfma_f32_16x16x32_bf16 v[70:73], v[170:173], v[222:225], v[70:73]
	v_mfma_f32_16x16x32_bf16 v[66:69], v[178:181], v[222:225], v[66:69]
	s_barrier
	s_add_i32 s14, s64, s28
	v_lshl_add_u64 v[190:191], s[56:57], 0, v[148:149]
	s_mov_b32 m0, s14
	ds_read_b128 v[182:185], v198 offset:16384
	ds_read_b128 v[186:189], v198 offset:17408
	ds_read_b128 v[202:205], v198 offset:18432
	ds_read_b128 v[206:209], v198 offset:19456
	ds_read_b128 v[210:213], v198 offset:20480
	ds_read_b128 v[214:217], v198 offset:21504
	ds_read_b128 v[218:221], v198 offset:22528
	ds_read_b128 v[222:225], v198 offset:23552
	global_load_lds_dwordx4 v[190:191], off
	s_add_i32 m0, s14, 0x2000
	s_add_u32 s14, s56, 0x58000
	v_lshl_add_u64 v[226:227], s[56:57], 0, v[152:153]
	s_addc_u32 s15, s57, 0
	s_add_i32 s16, s65, s28
	global_load_lds_dwordx4 v[226:227], off
	v_lshl_add_u64 v[228:229], s[14:15], 0, v[148:149]
	s_mov_b32 m0, s16
	v_lshl_add_u64 v[230:231], s[58:59], 0, v[150:151]
	global_load_lds_dwordx4 v[228:229], off
	v_lshl_add_u64 v[228:229], s[14:15], 0, v[152:153]
	s_add_i32 m0, s16, 0x2000
	s_nop 0
	global_load_lds_dwordx4 v[228:229], off
	v_lshl_add_u64 v[228:229], s[58:59], 0, v[146:147]
	s_mov_b32 m0, s29
	s_nop 0
	global_load_lds_dwordx4 v[228:229], off
	s_mov_b32 m0, s30
	s_nop 0
	global_load_lds_dwordx4 v[230:231], off
	s_waitcnt vmcnt(8)
	s_waitcnt lgkmcnt(0)
	s_barrier
; #define PG8_STAGE(bufoff, gbase, voff) do { _Pragma("unroll") for (int _i = 0; _i < 2; ++_i) \
;         __builtin_amdgcn_global_load_lds((const unsigned*)((const char*)(gbase) + (voff)[_i]), (LAS unsigned*)(lds + (bufoff) + ldsw + _i * 8192), 16, 0, 0); } while (0)
; #define PG8_LDA(dst, b, h) do { _Pragma("unroll") for (int m = 0; m < 4; ++m) _Pragma("unroll") for (int k = 0; k < 2; ++k) dst[m][k] = *(const LAS bf16x8*)(lds + PG8_SA(b, h) + aoff + m * 2048 + k * 1024); } while (0)
; #define PG8_LDB(dst, b, h) do { _Pragma("unroll") for (int n = 0; n < 2; ++n) _Pragma("unroll") for (int k = 0; k < 2; ++k) dst[n][k] = *(const LAS bf16x8*)(lds + PG8_SB(b, h) + boff + n * 2048 + k * 1024); } while (0)
; #define PG8_MMA(ai, bj, At, Bt) do { __builtin_amdgcn_s_setprio(1); _Pragma("unroll") for (int m = 0; m < 4; ++m) _Pragma("unroll") for (int n = 0; n < 2; ++n) _Pragma("unroll") for (int k = 0; k < 2; ++k) \
;         acc[ai][bj][m][n] = __builtin_amdgcn_mfma_f32_16x16x32_bf16(Bt[n][k], At[m][k], acc[ai][bj][m][n], 0, 0, 0); __builtin_amdgcn_s_setprio(0); } while (0)
; #define PG8_WAIT_V(n) asm volatile("s_waitcnt vmcnt(" #n ")" ::: "memory")
; #define PG8_WAIT_L(n) asm volatile("s_waitcnt lgkmcnt(" #n ")" ::: "memory")
; #define PG8_BAR __builtin_amdgcn_s_barrier()
; #define PG8_SCHED __builtin_amdgcn_sched_barrier(0)
; template <class Epi, class Sched, bool ALIGN_EPI = false, bool SP2 = false>
; __device__ __forceinline__ void gemm_phase(LAS unsigned char* lds, const Gemm g, const Sched& S, const Epi& E) {
;     ...
;             PG8_WAIT_V(8); PG8_WAIT_L(0); PG8_BAR; PG8_MMA(1, 0, At, B0); PG8_MMA(1, 1, At, B1); PG8_BAR; PG8_SCHED;
;             PG8_LDB(B0, 1, 0); PG8_LDB(B1, 1, 1); PG8_SCHED; PG8_LDA(At, 1, 0); PG8_STAGE(PG8_SA(0, 1), a2 + hstep, voffA);
;             PG8_WAIT_V(8); PG8_WAIT_L(0); PG8_BAR; PG8_MMA(0, 0, At, B0); PG8_MMA(0, 1, At, B1); PG8_BAR; PG8_SCHED;
;             PG8_LDA(At, 1, 1); PG8_STAGE(PG8_SB(1, 0), b3, voffB); PG8_STAGE(PG8_SB(1, 1), b3 + hstepB, voffB); PG8_STAGE(PG8_SA(1, 0), a3, voffA);
	s_waitcnt lgkmcnt(0)
	v_mfma_f32_16x16x32_bf16 v[62:65], v[130:133], v[182:185], v[62:65]
	v_mfma_f32_16x16x32_bf16 v[58:61], v[138:141], v[182:185], v[58:61]
	v_mfma_f32_16x16x32_bf16 v[46:49], v[130:133], v[202:205], v[46:49]
	v_mfma_f32_16x16x32_bf16 v[42:45], v[138:141], v[202:205], v[42:45]
	v_mfma_f32_16x16x32_bf16 v[30:33], v[130:133], v[210:213], v[30:33]
	v_mfma_f32_16x16x32_bf16 v[26:29], v[138:141], v[210:213], v[26:29]
	v_mfma_f32_16x16x32_bf16 v[14:17], v[130:133], v[218:221], v[14:17]
	v_mfma_f32_16x16x32_bf16 v[10:13], v[138:141], v[218:221], v[10:13]
	v_mfma_f32_16x16x32_bf16 v[62:65], v[134:137], v[186:189], v[62:65]
	v_mfma_f32_16x16x32_bf16 v[58:61], v[142:145], v[186:189], v[58:61]
	v_mfma_f32_16x16x32_bf16 v[46:49], v[134:137], v[206:209], v[46:49]
	v_mfma_f32_16x16x32_bf16 v[42:45], v[142:145], v[206:209], v[42:45]
	v_mfma_f32_16x16x32_bf16 v[30:33], v[134:137], v[214:217], v[30:33]
	v_mfma_f32_16x16x32_bf16 v[26:29], v[142:145], v[214:217], v[26:29]
	v_mfma_f32_16x16x32_bf16 v[14:17], v[134:137], v[222:225], v[14:17]
	v_mfma_f32_16x16x32_bf16 v[10:13], v[142:145], v[222:225], v[10:13]
	v_mfma_f32_16x16x32_bf16 v[54:57], v[166:169], v[182:185], v[54:57]
	v_mfma_f32_16x16x32_bf16 v[50:53], v[174:177], v[182:185], v[50:53]
	v_mfma_f32_16x16x32_bf16 v[38:41], v[166:169], v[202:205], v[38:41]
	v_mfma_f32_16x16x32_bf16 v[34:37], v[174:177], v[202:205], v[34:37]
	v_mfma_f32_16x16x32_bf16 v[22:25], v[166:169], v[210:213], v[22:25]
	v_mfma_f32_16x16x32_bf16 v[18:21], v[174:177], v[210:213], v[18:21]
	v_mfma_f32_16x16x32_bf16 v[6:9], v[166:169], v[218:221], v[6:9]
	v_mfma_f32_16x16x32_bf16 v[2:5], v[174:177], v[218:221], v[2:5]
	v_mfma_f32_16x16x32_bf16 v[54:57], v[170:173], v[186:189], v[54:57]
	v_mfma_f32_16x16x32_bf16 v[50:53], v[178:181], v[186:189], v[50:53]
	v_mfma_f32_16x16x32_bf16 v[38:41], v[170:173], v[206:209], v[38:41]
	v_mfma_f32_16x16x32_bf16 v[34:37], v[178:181], v[206:209], v[34:37]
	v_mfma_f32_16x16x32_bf16 v[22:25], v[170:173], v[214:217], v[22:25]
	v_mfma_f32_16x16x32_bf16 v[18:21], v[178:181], v[214:217], v[18:21]
	v_mfma_f32_16x16x32_bf16 v[6:9], v[170:173], v[222:225], v[6:9]
	v_mfma_f32_16x16x32_bf16 v[2:5], v[178:181], v[222:225], v[2:5]
	s_barrier
	s_add_i32 s16, 0, 0x18000
	s_add_i32 s17, 0, 0x1c000
	v_add_u32_e32 v142, s16, v1
	v_add_u32_e32 v154, s17, v1
	ds_read_b128 v[130:133], v142
	ds_read_b128 v[134:137], v142 offset:1024
	ds_read_b128 v[138:141], v142 offset:2048
	ds_read_b128 v[142:145], v142 offset:3072
	ds_read_b128 v[166:169], v154
	ds_read_b128 v[170:173], v154 offset:1024
	ds_read_b128 v[174:177], v154 offset:2048
	ds_read_b128 v[178:181], v154 offset:3072
	s_add_u32 s14, s58, 0x160000
	s_addc_u32 s15, s59, 0
	s_mov_b32 m0, s31
	v_lshl_add_u64 v[232:233], s[14:15], 0, v[146:147]
	ds_read_b128 v[182:185], v198 offset:32768
	ds_read_b128 v[186:189], v198 offset:33792
	ds_read_b128 v[202:205], v198 offset:34816
	ds_read_b128 v[206:209], v198 offset:35840
	ds_read_b128 v[210:213], v198 offset:36864
	ds_read_b128 v[214:217], v198 offset:37888
	ds_read_b128 v[218:221], v198 offset:38912
	ds_read_b128 v[222:225], v198 offset:39936
	global_load_lds_dwordx4 v[232:233], off
	v_lshl_add_u64 v[232:233], s[14:15], 0, v[150:151]
	s_mov_b32 m0, s33
	s_nop 0
	global_load_lds_dwordx4 v[232:233], off
	s_waitcnt vmcnt(8)
	s_waitcnt lgkmcnt(0)
	s_barrier
	s_waitcnt lgkmcnt(0)
	v_mfma_f32_16x16x32_bf16 v[126:129], v[130:133], v[182:185], v[126:129]
	v_mfma_f32_16x16x32_bf16 v[122:125], v[138:141], v[182:185], v[122:125]
	v_mfma_f32_16x16x32_bf16 v[110:113], v[130:133], v[202:205], v[110:113]
	v_mfma_f32_16x16x32_bf16 v[106:109], v[138:141], v[202:205], v[106:109]
	v_mfma_f32_16x16x32_bf16 v[94:97], v[130:133], v[210:213], v[94:97]
	v_mfma_f32_16x16x32_bf16 v[90:93], v[138:141], v[210:213], v[90:93]
	v_mfma_f32_16x16x32_bf16 v[78:81], v[130:133], v[218:221], v[78:81]
	v_mfma_f32_16x16x32_bf16 v[74:77], v[138:141], v[218:221], v[74:77]
	v_mfma_f32_16x16x32_bf16 v[126:129], v[134:137], v[186:189], v[126:129]
	v_mfma_f32_16x16x32_bf16 v[122:125], v[142:145], v[186:189], v[122:125]
	v_mfma_f32_16x16x32_bf16 v[110:113], v[134:137], v[206:209], v[110:113]
	v_mfma_f32_16x16x32_bf16 v[106:109], v[142:145], v[206:209], v[106:109]
	v_mfma_f32_16x16x32_bf16 v[94:97], v[134:137], v[214:217], v[94:97]
	v_mfma_f32_16x16x32_bf16 v[90:93], v[142:145], v[214:217], v[90:93]
	v_mfma_f32_16x16x32_bf16 v[78:81], v[134:137], v[222:225], v[78:81]
	v_mfma_f32_16x16x32_bf16 v[74:77], v[142:145], v[222:225], v[74:77]
	v_mfma_f32_16x16x32_bf16 v[118:121], v[166:169], v[182:185], v[118:121]
	v_mfma_f32_16x16x32_bf16 v[114:117], v[174:177], v[182:185], v[114:117]
	v_mfma_f32_16x16x32_bf16 v[102:105], v[166:169], v[202:205], v[102:105]
	v_mfma_f32_16x16x32_bf16 v[98:101], v[174:177], v[202:205], v[98:101]
	v_mfma_f32_16x16x32_bf16 v[86:89], v[166:169], v[210:213], v[86:89]
	v_mfma_f32_16x16x32_bf16 v[82:85], v[174:177], v[210:213], v[82:85]
	v_mfma_f32_16x16x32_bf16 v[70:73], v[166:169], v[218:221], v[70:73]
	v_mfma_f32_16x16x32_bf16 v[66:69], v[174:177], v[218:221], v[66:69]
	v_mfma_f32_16x16x32_bf16 v[118:121], v[170:173], v[186:189], v[118:121]
	v_mfma_f32_16x16x32_bf16 v[114:117], v[178:181], v[186:189], v[114:117]
	v_mfma_f32_16x16x32_bf16 v[102:105], v[170:173], v[206:209], v[102:105]
	v_mfma_f32_16x16x32_bf16 v[98:101], v[178:181], v[206:209], v[98:101]
	v_mfma_f32_16x16x32_bf16 v[86:89], v[170:173], v[214:217], v[86:89]
	v_mfma_f32_16x16x32_bf16 v[82:85], v[178:181], v[214:217], v[82:85]
	v_mfma_f32_16x16x32_bf16 v[70:73], v[170:173], v[222:225], v[70:73]
	v_mfma_f32_16x16x32_bf16 v[66:69], v[178:181], v[222:225], v[66:69]
	s_barrier
; #define PG8_STAGE(bufoff, gbase, voff) do { _Pragma("unroll") for (int _i = 0; _i < 2; ++_i) \
;         __builtin_amdgcn_global_load_lds((const unsigned*)((const char*)(gbase) + (voff)[_i]), (LAS unsigned*)(lds + (bufoff) + ldsw + _i * 8192), 16, 0, 0); } while (0)
; #define PG8_LDA(dst, b, h) do { _Pragma("unroll") for (int m = 0; m < 4; ++m) _Pragma("unroll") for (int k = 0; k < 2; ++k) dst[m][k] = *(const LAS bf16x8*)(lds + PG8_SA(b, h) + aoff + m * 2048 + k * 1024); } while (0)
; #define PG8_MMA(ai, bj, At, Bt) do { __builtin_amdgcn_s_setprio(1); _Pragma("unroll") for (int m = 0; m < 4; ++m) _Pragma("unroll") for (int n = 0; n < 2; ++n) _Pragma("unroll") for (int k = 0; k < 2; ++k) \
;         acc[ai][bj][m][n] = __builtin_amdgcn_mfma_f32_16x16x32_bf16(Bt[n][k], At[m][k], acc[ai][bj][m][n], 0, 0, 0); __builtin_amdgcn_s_setprio(0); } while (0)
; #define PG8_WAIT_V(n) asm volatile("s_waitcnt vmcnt(" #n ")" ::: "memory")
; #define PG8_WAIT_L(n) asm volatile("s_waitcnt lgkmcnt(" #n ")" ::: "memory")
; #define PG8_BAR __builtin_amdgcn_s_barrier()
; #define PG8_SCHED __builtin_amdgcn_sched_barrier(0)
; template <class Epi, class Sched, bool ALIGN_EPI = false, bool SP2 = false>
; __device__ __forceinline__ void gemm_phase(LAS unsigned char* lds, const Gemm g, const Sched& S, const Epi& E) {
;     ...
;             PG8_LDA(At, 1, 1); PG8_STAGE(PG8_SB(1, 0), b3, voffB); PG8_STAGE(PG8_SB(1, 1), b3 + hstepB, voffB); PG8_STAGE(PG8_SA(1, 0), a3, voffA);
;             PG8_WAIT_V(8); PG8_WAIT_L(0); PG8_BAR; PG8_MMA(1, 0, At, B0); PG8_MMA(1, 1, At, B1); PG8_BAR; PG8_SCHED;
;     ...
;         if constexpr (ALIGN_EPI) { if (wr == 0) PG8_BAR; }
	s_add_i32 s14, s16, s28
	v_lshl_add_u64 v[190:191], v[190:191], 0, s[48:49]
	s_mov_b32 m0, s14
	ds_read_b128 v[182:185], v198 offset:49152
	ds_read_b128 v[186:189], v198 offset:50176
	ds_read_b128 v[202:205], v198 offset:51200
	ds_read_b128 v[206:209], v198 offset:52224
	ds_read_b128 v[210:213], v198 offset:53248
	ds_read_b128 v[214:217], v198 offset:54272
	ds_read_b128 v[218:221], v198 offset:55296
	ds_read_b128 v[222:225], v198 offset:56320
	global_load_lds_dwordx4 v[190:191], off
	s_add_i32 m0, s14, 0x2000
	s_add_u32 s14, s56, 0x58080
	v_lshl_add_u64 v[190:191], v[226:227], 0, s[48:49]
	s_addc_u32 s15, s57, 0
	s_add_i32 s16, s17, s28
	global_load_lds_dwordx4 v[190:191], off
	v_lshl_add_u64 v[190:191], s[14:15], 0, v[148:149]
	s_mov_b32 m0, s16
	s_nop 0
	global_load_lds_dwordx4 v[190:191], off
	v_lshl_add_u64 v[190:191], s[14:15], 0, v[152:153]
	s_add_i32 m0, s16, 0x2000
	s_nop 0
	global_load_lds_dwordx4 v[190:191], off
	v_lshl_add_u64 v[190:191], v[228:229], 0, s[48:49]
	s_mov_b32 m0, s61
	s_nop 0
	global_load_lds_dwordx4 v[190:191], off
	v_lshl_add_u64 v[190:191], v[230:231], 0, s[48:49]
	s_mov_b32 m0, s62
	s_nop 0
	global_load_lds_dwordx4 v[190:191], off
	s_waitcnt vmcnt(8)
	s_waitcnt lgkmcnt(0)
	s_barrier
	s_waitcnt lgkmcnt(0)
	v_mfma_f32_16x16x32_bf16 v[62:65], v[130:133], v[182:185], v[62:65]
	v_mfma_f32_16x16x32_bf16 v[58:61], v[138:141], v[182:185], v[58:61]
	v_mfma_f32_16x16x32_bf16 v[46:49], v[130:133], v[202:205], v[46:49]
	v_mfma_f32_16x16x32_bf16 v[42:45], v[138:141], v[202:205], v[42:45]
	v_mfma_f32_16x16x32_bf16 v[30:33], v[130:133], v[210:213], v[30:33]
	v_mfma_f32_16x16x32_bf16 v[26:29], v[138:141], v[210:213], v[26:29]
	v_mfma_f32_16x16x32_bf16 v[14:17], v[130:133], v[218:221], v[14:17]
	v_mfma_f32_16x16x32_bf16 v[10:13], v[138:141], v[218:221], v[10:13]
	v_mfma_f32_16x16x32_bf16 v[62:65], v[134:137], v[186:189], v[62:65]
	v_mfma_f32_16x16x32_bf16 v[58:61], v[142:145], v[186:189], v[58:61]
	v_mfma_f32_16x16x32_bf16 v[46:49], v[134:137], v[206:209], v[46:49]
	v_mfma_f32_16x16x32_bf16 v[42:45], v[142:145], v[206:209], v[42:45]
	v_mfma_f32_16x16x32_bf16 v[30:33], v[134:137], v[214:217], v[30:33]
	v_mfma_f32_16x16x32_bf16 v[26:29], v[142:145], v[214:217], v[26:29]
	v_mfma_f32_16x16x32_bf16 v[14:17], v[134:137], v[222:225], v[14:17]
	v_mfma_f32_16x16x32_bf16 v[10:13], v[142:145], v[222:225], v[10:13]
	v_mfma_f32_16x16x32_bf16 v[54:57], v[166:169], v[182:185], v[54:57]
	v_mfma_f32_16x16x32_bf16 v[50:53], v[174:177], v[182:185], v[50:53]
	v_mfma_f32_16x16x32_bf16 v[38:41], v[166:169], v[202:205], v[38:41]
	v_mfma_f32_16x16x32_bf16 v[34:37], v[174:177], v[202:205], v[34:37]
	v_mfma_f32_16x16x32_bf16 v[22:25], v[166:169], v[210:213], v[22:25]
	v_mfma_f32_16x16x32_bf16 v[18:21], v[174:177], v[210:213], v[18:21]
	v_mfma_f32_16x16x32_bf16 v[6:9], v[166:169], v[218:221], v[6:9]
	v_mfma_f32_16x16x32_bf16 v[2:5], v[174:177], v[218:221], v[2:5]
	v_mfma_f32_16x16x32_bf16 v[54:57], v[170:173], v[186:189], v[54:57]
	v_mfma_f32_16x16x32_bf16 v[50:53], v[178:181], v[186:189], v[50:53]
	v_mfma_f32_16x16x32_bf16 v[38:41], v[170:173], v[206:209], v[38:41]
	v_mfma_f32_16x16x32_bf16 v[34:37], v[178:181], v[206:209], v[34:37]
	v_mfma_f32_16x16x32_bf16 v[22:25], v[170:173], v[214:217], v[22:25]
	v_mfma_f32_16x16x32_bf16 v[18:21], v[178:181], v[214:217], v[18:21]
	v_mfma_f32_16x16x32_bf16 v[6:9], v[170:173], v[222:225], v[6:9]
	v_mfma_f32_16x16x32_bf16 v[2:5], v[178:181], v[222:225], v[2:5]
	s_barrier
	s_add_i32 s13, s13, 2
	s_add_u32 s5, s5, 0x100
	s_addc_u32 s12, s12, 0
	s_cmpk_gt_u32 s13, 0x55
	s_mov_b64 s[16:17], s[54:55]
	s_cbranch_scc0 .LBB0_317
	s_and_b64 vcc, exec, s[50:51]
	s_cbranch_vccz .LBB0_320
	s_barrier

;     __device__ bool next(int i, Unit& u) const { if (i != 0 || c >= 128) return false; const int t = c >> 2; u.pm = t & 3; u.pn = t >> 2; u.koff = koff_bytes; u.q = c & 3; return true; }
; #define PG8_STAGE(bufoff, gbase, voff) do { _Pragma("unroll") for (int _i = 0; _i < 2; ++_i) \
;         __builtin_amdgcn_global_load_lds((const unsigned*)((const char*)(gbase) + (voff)[_i]), (LAS unsigned*)(lds + (bufoff) + ldsw + _i * 8192), 16, 0, 0); } while (0)
; #define PG8_LDA(dst, b, h) do { _Pragma("unroll") for (int m = 0; m < 4; ++m) _Pragma("unroll") for (int k = 0; k < 2; ++k) dst[m][k] = *(const LAS bf16x8*)(lds + PG8_SA(b, h) + aoff + m * 2048 + k * 1024); } while (0)
; #define PG8_LDB(dst, b, h) do { _Pragma("unroll") for (int n = 0; n < 2; ++n) _Pragma("unroll") for (int k = 0; k < 2; ++k) dst[n][k] = *(const LAS bf16x8*)(lds + PG8_SB(b, h) + boff + n * 2048 + k * 1024); } while (0)
; #define PG8_WAIT_V(n) asm volatile("s_waitcnt vmcnt(" #n ")" ::: "memory")
; #define PG8_WAIT_L(n) asm volatile("s_waitcnt lgkmcnt(" #n ")" ::: "memory")
; #define PG8_BAR __builtin_amdgcn_s_barrier()
; template <class Epi, class Sched, bool ALIGN_EPI = false, bool SP2 = false>
; __device__ __forceinline__ void gemm_phase(LAS unsigned char* lds, const Gemm g, const Sched& S, const Epi& E) {
;     ...
;         const bool has_next = S.next(ui + 1, nxt);
;         const char* nA = has_next ? (const char*)g.A + (size_t)nxt.pm * tstep + nxt.koff : cA; const char* nB = has_next ? (const char*)g.Bt + (size_t)nxt.pn * tstep + nxt.koff : cB;
;         for (int t = 0; t < nt; t += 2) {
;             const bool last = (t == nt - 2);
;             const char* a1 = cA + (size_t)(t + 1) * kstep;
;             const char* a2 = last ? nA : cA + (size_t)(t + 2) * kstep; const char* b2 = last ? nB : cB + (size_t)(t + 2) * kstep;
;             const char* a3 = a2 + kstep; const char* b3 = b2 + kstep;
;             if (last && has_next) S.a_ready(nxt);
;             if constexpr (SP2) {
;             PG8_LDB(B0, 0, 0); PG8_LDB(B1, 0, 1); PG8_SCHED; PG8_LDA(At, 0, 0); PG8_STAGE(PG8_SA(1, 1), a1 + hstep, voffA);
;             PG8_WAIT_V(8); PG8_WAIT_L(0); PG8_BAR; PG8_MMA(0, 0, At, B0); PG8_MMA(0, 1, At, B1); PG8_BAR; PG8_SCHED;
;             PG8_LDA(At, 0, 1); PG8_STAGE(PG8_SB(0, 0), b2, voffB); PG8_STAGE(PG8_SB(0, 1), b2 + hstepB, voffB); PG8_STAGE(PG8_SA(0, 0), a2, voffA);
.LBB0_534:
	s_ashr_i32 s53, s52, 31
	s_lshl_b64 s[14:15], s[52:53], 20
	s_add_u32 s54, s93, s14
	s_addc_u32 s55, s92, s15
	s_and_b64 s[14:15], s[44:45], exec
	s_cselect_b32 s0, s55, s17
	s_cselect_b32 s3, s54, s16
	s_ashr_i32 s51, s50, 31
	s_lshl_b64 s[14:15], s[50:51], 20
	s_add_u32 s56, s27, s14
	s_addc_u32 s57, s28, s15
	s_and_b64 s[14:15], s[44:45], exec
	s_cselect_b32 s14, s57, s49
	s_cselect_b32 s15, s56, s48
	s_add_u32 s16, s16, 0x80080
	s_addc_u32 s17, s17, 0
	s_add_u32 s18, s48, 0x100
	s_addc_u32 s19, s49, 0
	s_mov_b32 s20, -2
	ds_read_b128 v[34:37], v203
	ds_read_b128 v[38:41], v203 offset:1024
	ds_read_b128 v[42:45], v203 offset:2048
	ds_read_b128 v[46:49], v203 offset:3072
	s_waitcnt vmcnt(0)
	ds_read_b128 v[98:101], v204
	ds_read_b128 v[102:105], v204 offset:1024
	ds_read_b128 v[106:109], v204 offset:2048
	ds_read_b128 v[110:113], v204 offset:3072
	s_add_u32 s21, s16, 0xfff80080
	s_addc_u32 s22, s17, -1
	s_cmp_eq_u32 s20, 28
	s_cselect_b32 s59, s0, s22
	s_cselect_b32 s58, s3, s21
	s_cselect_b32 s49, s14, s19
	s_cselect_b32 s48, s15, s18
	v_lshl_add_u64 v[182:183], s[16:17], 0, v[172:173]
	s_add_i32 m0, s30, 0xc000
	ds_read_b128 v[212:215], v205
	ds_read_b128 v[216:219], v205 offset:1024
	ds_read_b128 v[220:223], v205 offset:2048
	ds_read_b128 v[224:227], v205 offset:3072
	ds_read_b128 v[228:231], v205 offset:4096
	ds_read_b128 v[232:235], v205 offset:5120
	ds_read_b128 v[236:239], v205 offset:6144
	ds_read_b128 v[240:243], v205 offset:7168
	global_load_lds_dwordx4 v[182:183], off
	v_lshl_add_u64 v[182:183], s[16:17], 0, v[174:175]
	s_add_i32 m0, s30, 0xe000
	s_nop 0
	global_load_lds_dwordx4 v[182:183], off
	s_waitcnt lgkmcnt(0)
	s_barrier
	s_waitcnt lgkmcnt(0)
	v_mfma_f32_16x16x32_bf16 v[158:161], v[34:37], v[212:215], 0
	v_mfma_f32_16x16x32_bf16 v[154:157], v[42:45], v[212:215], 0
	v_mfma_f32_16x16x32_bf16 v[142:145], v[34:37], v[220:223], 0
	v_mfma_f32_16x16x32_bf16 v[138:141], v[42:45], v[220:223], 0
	v_mfma_f32_16x16x32_bf16 v[126:129], v[34:37], v[228:231], 0
	v_mfma_f32_16x16x32_bf16 v[122:125], v[42:45], v[228:231], 0
	v_mfma_f32_16x16x32_bf16 v[94:97], v[34:37], v[236:239], 0
	v_mfma_f32_16x16x32_bf16 v[90:93], v[42:45], v[236:239], 0
	v_mfma_f32_16x16x32_bf16 v[158:161], v[38:41], v[216:219], v[158:161]
	v_mfma_f32_16x16x32_bf16 v[154:157], v[46:49], v[216:219], v[154:157]
	v_mfma_f32_16x16x32_bf16 v[142:145], v[38:41], v[224:227], v[142:145]
	v_mfma_f32_16x16x32_bf16 v[138:141], v[46:49], v[224:227], v[138:141]
	v_mfma_f32_16x16x32_bf16 v[126:129], v[38:41], v[232:235], v[126:129]
	v_mfma_f32_16x16x32_bf16 v[122:125], v[46:49], v[232:235], v[122:125]
	v_mfma_f32_16x16x32_bf16 v[94:97], v[38:41], v[240:243], v[94:97]
	v_mfma_f32_16x16x32_bf16 v[90:93], v[46:49], v[240:243], v[90:93]
	v_mfma_f32_16x16x32_bf16 v[150:153], v[98:101], v[212:215], 0
	v_mfma_f32_16x16x32_bf16 v[146:149], v[106:109], v[212:215], 0
	v_mfma_f32_16x16x32_bf16 v[134:137], v[98:101], v[220:223], 0
	v_mfma_f32_16x16x32_bf16 v[130:133], v[106:109], v[220:223], 0
	v_mfma_f32_16x16x32_bf16 v[118:121], v[98:101], v[228:231], 0
	v_mfma_f32_16x16x32_bf16 v[114:117], v[106:109], v[228:231], 0
	v_mfma_f32_16x16x32_bf16 v[86:89], v[98:101], v[236:239], 0
	v_mfma_f32_16x16x32_bf16 v[82:85], v[106:109], v[236:239], 0
	v_mfma_f32_16x16x32_bf16 v[150:153], v[102:105], v[216:219], v[150:153]
	v_mfma_f32_16x16x32_bf16 v[146:149], v[110:113], v[216:219], v[146:149]
	v_mfma_f32_16x16x32_bf16 v[134:137], v[102:105], v[224:227], v[134:137]
	v_mfma_f32_16x16x32_bf16 v[130:133], v[110:113], v[224:227], v[130:133]
	v_mfma_f32_16x16x32_bf16 v[118:121], v[102:105], v[232:235], v[118:121]
	v_mfma_f32_16x16x32_bf16 v[114:117], v[110:113], v[232:235], v[114:117]
	v_mfma_f32_16x16x32_bf16 v[86:89], v[102:105], v[240:243], v[86:89]
	v_mfma_f32_16x16x32_bf16 v[82:85], v[110:113], v[240:243], v[82:85]
	s_barrier
	s_add_i32 s21, s68, s29
	v_lshl_add_u64 v[182:183], s[48:49], 0, v[164:165]
	s_mov_b32 m0, s21
	ds_read_b128 v[212:215], v205 offset:16384
	ds_read_b128 v[216:219], v205 offset:17408
	ds_read_b128 v[220:223], v205 offset:18432
	ds_read_b128 v[224:227], v205 offset:19456
	ds_read_b128 v[228:231], v205 offset:20480
	ds_read_b128 v[232:235], v205 offset:21504
	ds_read_b128 v[236:239], v205 offset:22528
	ds_read_b128 v[240:243], v205 offset:23552
	global_load_lds_dwordx4 v[182:183], off
	s_add_i32 m0, s21, 0x2000
	s_add_u32 s22, s48, 0x20000
	v_lshl_add_u64 v[244:245], s[48:49], 0, v[168:169]
	s_addc_u32 s23, s49, 0
	s_add_i32 s21, s69, s29
	global_load_lds_dwordx4 v[244:245], off
	v_lshl_add_u64 v[246:247], s[22:23], 0, v[164:165]
	s_mov_b32 m0, s21
	v_lshl_add_u64 v[248:249], s[58:59], 0, v[166:167]
	global_load_lds_dwordx4 v[246:247], off
	v_lshl_add_u64 v[246:247], s[22:23], 0, v[168:169]
	s_add_i32 m0, s21, 0x2000
	s_nop 0
	global_load_lds_dwordx4 v[246:247], off
	v_lshl_add_u64 v[246:247], s[58:59], 0, v[162:163]
	s_mov_b32 m0, s30
	s_nop 0
	global_load_lds_dwordx4 v[246:247], off
	s_mov_b32 m0, s31
	s_nop 0
	global_load_lds_dwordx4 v[248:249], off
	s_waitcnt lgkmcnt(0)
	s_barrier
; #define PG8_STAGE(bufoff, gbase, voff) do { _Pragma("unroll") for (int _i = 0; _i < 2; ++_i) \
;         __builtin_amdgcn_global_load_lds((const unsigned*)((const char*)(gbase) + (voff)[_i]), (LAS unsigned*)(lds + (bufoff) + ldsw + _i * 8192), 16, 0, 0); } while (0)
; #define PG8_LDA(dst, b, h) do { _Pragma("unroll") for (int m = 0; m < 4; ++m) _Pragma("unroll") for (int k = 0; k < 2; ++k) dst[m][k] = *(const LAS bf16x8*)(lds + PG8_SA(b, h) + aoff + m * 2048 + k * 1024); } while (0)
; #define PG8_LDB(dst, b, h) do { _Pragma("unroll") for (int n = 0; n < 2; ++n) _Pragma("unroll") for (int k = 0; k < 2; ++k) dst[n][k] = *(const LAS bf16x8*)(lds + PG8_SB(b, h) + boff + n * 2048 + k * 1024); } while (0)
; #define PG8_MMA(ai, bj, At, Bt) do { __builtin_amdgcn_s_setprio(1); _Pragma("unroll") for (int m = 0; m < 4; ++m) _Pragma("unroll") for (int n = 0; n < 2; ++n) _Pragma("unroll") for (int k = 0; k < 2; ++k) \
;         acc[ai][bj][m][n] = __builtin_amdgcn_mfma_f32_16x16x32_bf16(Bt[n][k], At[m][k], acc[ai][bj][m][n], 0, 0, 0); __builtin_amdgcn_s_setprio(0); } while (0)
; #define PG8_WAIT_V(n) asm volatile("s_waitcnt vmcnt(" #n ")" ::: "memory")
; #define PG8_WAIT_L(n) asm volatile("s_waitcnt lgkmcnt(" #n ")" ::: "memory")
; #define PG8_BAR __builtin_amdgcn_s_barrier()
; #define PG8_SCHED __builtin_amdgcn_sched_barrier(0)
; template <class Epi, class Sched, bool ALIGN_EPI = false, bool SP2 = false>
; __device__ __forceinline__ void gemm_phase(LAS unsigned char* lds, const Gemm g, const Sched& S, const Epi& E) {
;     ...
;             PG8_WAIT_V(8); PG8_WAIT_L(0); PG8_BAR; PG8_MMA(1, 0, At, B0); PG8_MMA(1, 1, At, B1); PG8_BAR; PG8_SCHED;
;             PG8_LDB(B0, 1, 0); PG8_LDB(B1, 1, 1); PG8_SCHED; PG8_LDA(At, 1, 0); PG8_STAGE(PG8_SA(0, 1), a2 + hstep, voffA);
;             PG8_WAIT_V(8); PG8_WAIT_L(0); PG8_BAR; PG8_MMA(0, 0, At, B0); PG8_MMA(0, 1, At, B1); PG8_BAR; PG8_SCHED;
	s_waitcnt lgkmcnt(0)
	v_mfma_f32_16x16x32_bf16 v[78:81], v[34:37], v[212:215], 0
	v_mfma_f32_16x16x32_bf16 v[74:77], v[42:45], v[212:215], 0
	v_mfma_f32_16x16x32_bf16 v[62:65], v[34:37], v[220:223], 0
	v_mfma_f32_16x16x32_bf16 v[58:61], v[42:45], v[220:223], 0
	v_mfma_f32_16x16x32_bf16 v[30:33], v[34:37], v[228:231], 0
	v_mfma_f32_16x16x32_bf16 v[26:29], v[42:45], v[228:231], 0
	v_mfma_f32_16x16x32_bf16 v[14:17], v[34:37], v[236:239], 0
	v_mfma_f32_16x16x32_bf16 v[10:13], v[42:45], v[236:239], 0
	v_mfma_f32_16x16x32_bf16 v[78:81], v[38:41], v[216:219], v[78:81]
	v_mfma_f32_16x16x32_bf16 v[74:77], v[46:49], v[216:219], v[74:77]
	v_mfma_f32_16x16x32_bf16 v[62:65], v[38:41], v[224:227], v[62:65]
	v_mfma_f32_16x16x32_bf16 v[58:61], v[46:49], v[224:227], v[58:61]
	v_mfma_f32_16x16x32_bf16 v[30:33], v[38:41], v[232:235], v[30:33]
	v_mfma_f32_16x16x32_bf16 v[26:29], v[46:49], v[232:235], v[26:29]
	v_mfma_f32_16x16x32_bf16 v[14:17], v[38:41], v[240:243], v[14:17]
	v_mfma_f32_16x16x32_bf16 v[10:13], v[46:49], v[240:243], v[10:13]
	v_mfma_f32_16x16x32_bf16 v[22:25], v[98:101], v[228:231], 0
	v_mfma_f32_16x16x32_bf16 v[18:21], v[106:109], v[228:231], 0
	v_mfma_f32_16x16x32_bf16 v[6:9], v[98:101], v[236:239], 0
	v_mfma_f32_16x16x32_bf16 v[2:5], v[106:109], v[236:239], 0
	v_mfma_f32_16x16x32_bf16 v[34:37], v[98:101], v[212:215], 0
	v_mfma_f32_16x16x32_bf16 v[38:41], v[106:109], v[212:215], 0
	v_mfma_f32_16x16x32_bf16 v[42:45], v[98:101], v[220:223], 0
	v_mfma_f32_16x16x32_bf16 v[46:49], v[106:109], v[220:223], 0
	v_mfma_f32_16x16x32_bf16 v[22:25], v[102:105], v[232:235], v[22:25]
	v_mfma_f32_16x16x32_bf16 v[18:21], v[110:113], v[232:235], v[18:21]
	v_mfma_f32_16x16x32_bf16 v[6:9], v[102:105], v[240:243], v[6:9]
	v_mfma_f32_16x16x32_bf16 v[2:5], v[110:113], v[240:243], v[2:5]
	v_mfma_f32_16x16x32_bf16 v[34:37], v[102:105], v[216:219], v[34:37]
	v_mfma_f32_16x16x32_bf16 v[38:41], v[110:113], v[216:219], v[38:41]
	v_mfma_f32_16x16x32_bf16 v[42:45], v[102:105], v[224:227], v[42:45]
	v_mfma_f32_16x16x32_bf16 v[46:49], v[110:113], v[224:227], v[46:49]
	s_barrier
	s_add_i32 s21, 0, 0x18000
	s_add_i32 s24, 0, 0x1c000
	v_add_u32_e32 v70, s21, v186
	v_add_u32_e32 v110, s24, v186
	ds_read_b128 v[50:53], v70
	ds_read_b128 v[54:57], v70 offset:1024
	ds_read_b128 v[66:69], v70 offset:2048
	ds_read_b128 v[70:73], v70 offset:3072
	ds_read_b128 v[98:101], v110
	ds_read_b128 v[102:105], v110 offset:1024
	ds_read_b128 v[106:109], v110 offset:2048
	ds_read_b128 v[110:113], v110 offset:3072
	s_add_u32 s22, s58, 0x80000
	s_addc_u32 s23, s59, 0
	s_mov_b32 m0, s33
	v_lshl_add_u64 v[250:251], s[22:23], 0, v[162:163]
	ds_read_b128 v[212:215], v205 offset:32768
	ds_read_b128 v[216:219], v205 offset:33792
	ds_read_b128 v[220:223], v205 offset:34816
	ds_read_b128 v[224:227], v205 offset:35840
	ds_read_b128 v[228:231], v205 offset:36864
	ds_read_b128 v[232:235], v205 offset:37888
	ds_read_b128 v[236:239], v205 offset:38912
	ds_read_b128 v[240:243], v205 offset:39936
	global_load_lds_dwordx4 v[250:251], off
	v_lshl_add_u64 v[250:251], s[22:23], 0, v[166:167]
	s_mov_b32 m0, s60
	s_nop 0
	global_load_lds_dwordx4 v[250:251], off
	s_waitcnt vmcnt(8)
	s_waitcnt lgkmcnt(0)
	s_barrier
	s_waitcnt lgkmcnt(0)
	v_mfma_f32_16x16x32_bf16 v[158:161], v[50:53], v[212:215], v[158:161]
	v_mfma_f32_16x16x32_bf16 v[154:157], v[66:69], v[212:215], v[154:157]
	v_mfma_f32_16x16x32_bf16 v[142:145], v[50:53], v[220:223], v[142:145]
	v_mfma_f32_16x16x32_bf16 v[138:141], v[66:69], v[220:223], v[138:141]
	v_mfma_f32_16x16x32_bf16 v[126:129], v[50:53], v[228:231], v[126:129]
	v_mfma_f32_16x16x32_bf16 v[122:125], v[66:69], v[228:231], v[122:125]
	v_mfma_f32_16x16x32_bf16 v[94:97], v[50:53], v[236:239], v[94:97]
	v_mfma_f32_16x16x32_bf16 v[90:93], v[66:69], v[236:239], v[90:93]
	v_mfma_f32_16x16x32_bf16 v[158:161], v[54:57], v[216:219], v[158:161]
	v_mfma_f32_16x16x32_bf16 v[154:157], v[70:73], v[216:219], v[154:157]
	v_mfma_f32_16x16x32_bf16 v[142:145], v[54:57], v[224:227], v[142:145]
	v_mfma_f32_16x16x32_bf16 v[138:141], v[70:73], v[224:227], v[138:141]
	v_mfma_f32_16x16x32_bf16 v[126:129], v[54:57], v[232:235], v[126:129]
	v_mfma_f32_16x16x32_bf16 v[122:125], v[70:73], v[232:235], v[122:125]
	v_mfma_f32_16x16x32_bf16 v[94:97], v[54:57], v[240:243], v[94:97]
	v_mfma_f32_16x16x32_bf16 v[90:93], v[70:73], v[240:243], v[90:93]
	v_mfma_f32_16x16x32_bf16 v[150:153], v[98:101], v[212:215], v[150:153]
	v_mfma_f32_16x16x32_bf16 v[146:149], v[106:109], v[212:215], v[146:149]
	v_mfma_f32_16x16x32_bf16 v[134:137], v[98:101], v[220:223], v[134:137]
	v_mfma_f32_16x16x32_bf16 v[130:133], v[106:109], v[220:223], v[130:133]
	v_mfma_f32_16x16x32_bf16 v[118:121], v[98:101], v[228:231], v[118:121]
	v_mfma_f32_16x16x32_bf16 v[114:117], v[106:109], v[228:231], v[114:117]
	v_mfma_f32_16x16x32_bf16 v[86:89], v[98:101], v[236:239], v[86:89]
	v_mfma_f32_16x16x32_bf16 v[82:85], v[106:109], v[236:239], v[82:85]
	v_mfma_f32_16x16x32_bf16 v[150:153], v[102:105], v[216:219], v[150:153]
	v_mfma_f32_16x16x32_bf16 v[146:149], v[110:113], v[216:219], v[146:149]
	v_mfma_f32_16x16x32_bf16 v[134:137], v[102:105], v[224:227], v[134:137]
	v_mfma_f32_16x16x32_bf16 v[130:133], v[110:113], v[224:227], v[130:133]
	v_mfma_f32_16x16x32_bf16 v[118:121], v[102:105], v[232:235], v[118:121]
	v_mfma_f32_16x16x32_bf16 v[114:117], v[110:113], v[232:235], v[114:117]
	v_mfma_f32_16x16x32_bf16 v[86:89], v[102:105], v[240:243], v[86:89]
	v_mfma_f32_16x16x32_bf16 v[82:85], v[110:113], v[240:243], v[82:85]
	s_barrier
; #define PG8_STAGE(bufoff, gbase, voff) do { _Pragma("unroll") for (int _i = 0; _i < 2; ++_i) \
;         __builtin_amdgcn_global_load_lds((const unsigned*)((const char*)(gbase) + (voff)[_i]), (LAS unsigned*)(lds + (bufoff) + ldsw + _i * 8192), 16, 0, 0); } while (0)
; #define PG8_LDA(dst, b, h) do { _Pragma("unroll") for (int m = 0; m < 4; ++m) _Pragma("unroll") for (int k = 0; k < 2; ++k) dst[m][k] = *(const LAS bf16x8*)(lds + PG8_SA(b, h) + aoff + m * 2048 + k * 1024); } while (0)
; #define PG8_LDB(dst, b, h) do { _Pragma("unroll") for (int n = 0; n < 2; ++n) _Pragma("unroll") for (int k = 0; k < 2; ++k) dst[n][k] = *(const LAS bf16x8*)(lds + PG8_SB(b, h) + boff + n * 2048 + k * 1024); } while (0)
; #define PG8_MMA(ai, bj, At, Bt) do { __builtin_amdgcn_s_setprio(1); _Pragma("unroll") for (int m = 0; m < 4; ++m) _Pragma("unroll") for (int n = 0; n < 2; ++n) _Pragma("unroll") for (int k = 0; k < 2; ++k) \
;         acc[ai][bj][m][n] = __builtin_amdgcn_mfma_f32_16x16x32_bf16(Bt[n][k], At[m][k], acc[ai][bj][m][n], 0, 0, 0); __builtin_amdgcn_s_setprio(0); } while (0)
; #define PG8_WAIT_V(n) asm volatile("s_waitcnt vmcnt(" #n ")" ::: "memory")
; #define PG8_WAIT_L(n) asm volatile("s_waitcnt lgkmcnt(" #n ")" ::: "memory")
; #define PG8_BAR __builtin_amdgcn_s_barrier()
; #define PG8_SCHED __builtin_amdgcn_sched_barrier(0)
; template <class Epi, class Sched, bool ALIGN_EPI = false, bool SP2 = false>
; __device__ __forceinline__ void gemm_phase(LAS unsigned char* lds, const Gemm g, const Sched& S, const Epi& E) {
;     ...
;             PG8_LDB(B0, 0, 0); PG8_LDB(B1, 0, 1); PG8_SCHED; PG8_LDA(At, 0, 0); PG8_STAGE(PG8_SA(1, 1), a1 + hstep, voffA);
;             PG8_WAIT_V(8); PG8_WAIT_L(0); PG8_BAR; PG8_MMA(0, 0, At, B0); PG8_MMA(0, 1, At, B1); PG8_BAR; PG8_SCHED;
;     ...
;             PG8_LDA(At, 1, 1); PG8_STAGE(PG8_SB(1, 0), b3, voffB); PG8_STAGE(PG8_SB(1, 1), b3 + hstepB, voffB); PG8_STAGE(PG8_SA(1, 0), a3, voffA);
;             PG8_WAIT_V(8); PG8_WAIT_L(0); PG8_BAR; PG8_MMA(1, 0, At, B0); PG8_MMA(1, 1, At, B1); PG8_BAR; PG8_SCHED;
	s_add_i32 s21, s21, s29
	v_lshl_add_u64 v[182:183], v[182:183], 0, s[34:35]
	s_mov_b32 m0, s21
	ds_read_b128 v[212:215], v205 offset:49152
	ds_read_b128 v[216:219], v205 offset:50176
	ds_read_b128 v[220:223], v205 offset:51200
	ds_read_b128 v[224:227], v205 offset:52224
	ds_read_b128 v[228:231], v205 offset:53248
	ds_read_b128 v[232:235], v205 offset:54272
	ds_read_b128 v[236:239], v205 offset:55296
	ds_read_b128 v[240:243], v205 offset:56320
	global_load_lds_dwordx4 v[182:183], off
	s_add_i32 m0, s21, 0x2000
	s_add_u32 s22, s48, 0x20080
	v_lshl_add_u64 v[182:183], v[244:245], 0, s[34:35]
	s_addc_u32 s23, s49, 0
	s_add_i32 s21, s24, s29
	global_load_lds_dwordx4 v[182:183], off
	v_lshl_add_u64 v[182:183], s[22:23], 0, v[164:165]
	s_mov_b32 m0, s21
	s_nop 0
	global_load_lds_dwordx4 v[182:183], off
	v_lshl_add_u64 v[182:183], s[22:23], 0, v[168:169]
	s_add_i32 m0, s21, 0x2000
	s_nop 0
	global_load_lds_dwordx4 v[182:183], off
	v_lshl_add_u64 v[182:183], v[246:247], 0, s[34:35]
	s_mov_b32 m0, s65
	s_nop 0
	global_load_lds_dwordx4 v[182:183], off
	v_lshl_add_u64 v[182:183], v[248:249], 0, s[34:35]
	s_mov_b32 m0, s66
	s_nop 0
	global_load_lds_dwordx4 v[182:183], off
	s_waitcnt vmcnt(8)
	s_waitcnt lgkmcnt(0)
	s_barrier
	s_waitcnt lgkmcnt(0)
	v_mfma_f32_16x16x32_bf16 v[78:81], v[50:53], v[212:215], v[78:81]
	v_mfma_f32_16x16x32_bf16 v[74:77], v[66:69], v[212:215], v[74:77]
	v_mfma_f32_16x16x32_bf16 v[62:65], v[50:53], v[220:223], v[62:65]
	v_mfma_f32_16x16x32_bf16 v[58:61], v[66:69], v[220:223], v[58:61]
	v_mfma_f32_16x16x32_bf16 v[30:33], v[50:53], v[228:231], v[30:33]
	v_mfma_f32_16x16x32_bf16 v[26:29], v[66:69], v[228:231], v[26:29]
	v_mfma_f32_16x16x32_bf16 v[14:17], v[50:53], v[236:239], v[14:17]
	v_mfma_f32_16x16x32_bf16 v[10:13], v[66:69], v[236:239], v[10:13]
	v_mfma_f32_16x16x32_bf16 v[78:81], v[54:57], v[216:219], v[78:81]
	v_mfma_f32_16x16x32_bf16 v[74:77], v[70:73], v[216:219], v[74:77]
	v_mfma_f32_16x16x32_bf16 v[62:65], v[54:57], v[224:227], v[62:65]
	v_mfma_f32_16x16x32_bf16 v[58:61], v[70:73], v[224:227], v[58:61]
	v_mfma_f32_16x16x32_bf16 v[30:33], v[54:57], v[232:235], v[30:33]
	v_mfma_f32_16x16x32_bf16 v[26:29], v[70:73], v[232:235], v[26:29]
	v_mfma_f32_16x16x32_bf16 v[14:17], v[54:57], v[240:243], v[14:17]
	v_mfma_f32_16x16x32_bf16 v[10:13], v[70:73], v[240:243], v[10:13]
	v_mfma_f32_16x16x32_bf16 v[34:37], v[98:101], v[212:215], v[34:37]
	v_mfma_f32_16x16x32_bf16 v[70:73], v[102:105], v[216:219], v[34:37]
	v_mfma_f32_16x16x32_bf16 v[34:37], v[106:109], v[212:215], v[38:41]
	v_mfma_f32_16x16x32_bf16 v[66:69], v[110:113], v[216:219], v[34:37]
	v_mfma_f32_16x16x32_bf16 v[34:37], v[98:101], v[220:223], v[42:45]
	v_mfma_f32_16x16x32_bf16 v[54:57], v[102:105], v[224:227], v[34:37]
	v_mfma_f32_16x16x32_bf16 v[34:37], v[106:109], v[220:223], v[46:49]
	v_mfma_f32_16x16x32_bf16 v[22:25], v[98:101], v[228:231], v[22:25]
	v_mfma_f32_16x16x32_bf16 v[18:21], v[106:109], v[228:231], v[18:21]
	v_mfma_f32_16x16x32_bf16 v[6:9], v[98:101], v[236:239], v[6:9]
	v_mfma_f32_16x16x32_bf16 v[2:5], v[106:109], v[236:239], v[2:5]
	v_mfma_f32_16x16x32_bf16 v[50:53], v[110:113], v[224:227], v[34:37]
	v_mfma_f32_16x16x32_bf16 v[22:25], v[102:105], v[232:235], v[22:25]
	v_mfma_f32_16x16x32_bf16 v[18:21], v[110:113], v[232:235], v[18:21]
	v_mfma_f32_16x16x32_bf16 v[6:9], v[102:105], v[240:243], v[6:9]
	v_mfma_f32_16x16x32_bf16 v[2:5], v[110:113], v[240:243], v[2:5]
	s_barrier
	s_add_i32 s20, s20, 2
	s_add_u32 s16, s16, 0x100
	s_addc_u32 s17, s17, 0
	s_add_u32 s18, s18, 0x100
	s_addc_u32 s19, s19, 0
	s_cmp_gt_u32 s20, 29
.LBB0_535:
	ds_read_b128 v[34:37], v203
	ds_read_b128 v[38:41], v203 offset:1024
	ds_read_b128 v[42:45], v203 offset:2048
	ds_read_b128 v[46:49], v203 offset:3072
	s_waitcnt vmcnt(0)
	ds_read_b128 v[98:101], v204
	ds_read_b128 v[102:105], v204 offset:1024
	ds_read_b128 v[106:109], v204 offset:2048
	ds_read_b128 v[110:113], v204 offset:3072
	s_add_u32 s21, s16, 0xfff80080
	s_addc_u32 s22, s17, -1
	s_cmp_eq_u32 s20, 28
	s_cselect_b32 s59, s0, s22
	s_cselect_b32 s58, s3, s21
	s_cselect_b32 s49, s14, s19
	s_cselect_b32 s48, s15, s18
	v_lshl_add_u64 v[182:183], s[16:17], 0, v[172:173]
	s_add_i32 m0, s30, 0xc000
	ds_read_b128 v[212:215], v205
	ds_read_b128 v[216:219], v205 offset:1024
	ds_read_b128 v[220:223], v205 offset:2048
	ds_read_b128 v[224:227], v205 offset:3072
	ds_read_b128 v[228:231], v205 offset:4096
	ds_read_b128 v[232:235], v205 offset:5120
	ds_read_b128 v[236:239], v205 offset:6144
	ds_read_b128 v[240:243], v205 offset:7168
	global_load_lds_dwordx4 v[182:183], off
	v_lshl_add_u64 v[182:183], s[16:17], 0, v[174:175]
	s_add_i32 m0, s30, 0xe000
	s_nop 0
	global_load_lds_dwordx4 v[182:183], off
	s_waitcnt vmcnt(8)
	s_waitcnt lgkmcnt(0)
	s_barrier
; #define PG8_STAGE(bufoff, gbase, voff) do { _Pragma("unroll") for (int _i = 0; _i < 2; ++_i) \
;         __builtin_amdgcn_global_load_lds((const unsigned*)((const char*)(gbase) + (voff)[_i]), (LAS unsigned*)(lds + (bufoff) + ldsw + _i * 8192), 16, 0, 0); } while (0)
; #define PG8_LDA(dst, b, h) do { _Pragma("unroll") for (int m = 0; m < 4; ++m) _Pragma("unroll") for (int k = 0; k < 2; ++k) dst[m][k] = *(const LAS bf16x8*)(lds + PG8_SA(b, h) + aoff + m * 2048 + k * 1024); } while (0)
; #define PG8_LDB(dst, b, h) do { _Pragma("unroll") for (int n = 0; n < 2; ++n) _Pragma("unroll") for (int k = 0; k < 2; ++k) dst[n][k] = *(const LAS bf16x8*)(lds + PG8_SB(b, h) + boff + n * 2048 + k * 1024); } while (0)
; #define PG8_MMA(ai, bj, At, Bt) do { __builtin_amdgcn_s_setprio(1); _Pragma("unroll") for (int m = 0; m < 4; ++m) _Pragma("unroll") for (int n = 0; n < 2; ++n) _Pragma("unroll") for (int k = 0; k < 2; ++k) \
;         acc[ai][bj][m][n] = __builtin_amdgcn_mfma_f32_16x16x32_bf16(Bt[n][k], At[m][k], acc[ai][bj][m][n], 0, 0, 0); __builtin_amdgcn_s_setprio(0); } while (0)
; #define PG8_WAIT_V(n) asm volatile("s_waitcnt vmcnt(" #n ")" ::: "memory")
; #define PG8_WAIT_L(n) asm volatile("s_waitcnt lgkmcnt(" #n ")" ::: "memory")
; #define PG8_BAR __builtin_amdgcn_s_barrier()
; #define PG8_SCHED __builtin_amdgcn_sched_barrier(0)
; template <class Epi, class Sched, bool ALIGN_EPI = false, bool SP2 = false>
; __device__ __forceinline__ void gemm_phase(LAS unsigned char* lds, const Gemm g, const Sched& S, const Epi& E) {
;     ...
;             PG8_WAIT_V(8); PG8_WAIT_L(0); PG8_BAR; PG8_MMA(0, 0, At, B0); PG8_MMA(0, 1, At, B1); PG8_BAR; PG8_SCHED;
;             PG8_LDA(At, 0, 1); PG8_STAGE(PG8_SB(0, 0), b2, voffB); PG8_STAGE(PG8_SB(0, 1), b2 + hstepB, voffB); PG8_STAGE(PG8_SA(0, 0), a2, voffA);
;             PG8_WAIT_V(8); PG8_WAIT_L(0); PG8_BAR; PG8_MMA(1, 0, At, B0); PG8_MMA(1, 1, At, B1); PG8_BAR; PG8_SCHED;
;             PG8_LDB(B0, 1, 0); PG8_LDB(B1, 1, 1); PG8_SCHED; PG8_LDA(At, 1, 0); PG8_STAGE(PG8_SA(0, 1), a2 + hstep, voffA);
;             PG8_WAIT_V(8); PG8_WAIT_L(0); PG8_BAR; PG8_MMA(0, 0, At, B0); PG8_MMA(0, 1, At, B1); PG8_BAR; PG8_SCHED;
	s_waitcnt lgkmcnt(0)
	v_mfma_f32_16x16x32_bf16 v[158:161], v[34:37], v[212:215], v[158:161]
	v_mfma_f32_16x16x32_bf16 v[154:157], v[42:45], v[212:215], v[154:157]
	v_mfma_f32_16x16x32_bf16 v[142:145], v[34:37], v[220:223], v[142:145]
	v_mfma_f32_16x16x32_bf16 v[138:141], v[42:45], v[220:223], v[138:141]
	v_mfma_f32_16x16x32_bf16 v[126:129], v[34:37], v[228:231], v[126:129]
	v_mfma_f32_16x16x32_bf16 v[122:125], v[42:45], v[228:231], v[122:125]
	v_mfma_f32_16x16x32_bf16 v[94:97], v[34:37], v[236:239], v[94:97]
	v_mfma_f32_16x16x32_bf16 v[90:93], v[42:45], v[236:239], v[90:93]
	v_mfma_f32_16x16x32_bf16 v[158:161], v[38:41], v[216:219], v[158:161]
	v_mfma_f32_16x16x32_bf16 v[154:157], v[46:49], v[216:219], v[154:157]
	v_mfma_f32_16x16x32_bf16 v[142:145], v[38:41], v[224:227], v[142:145]
	v_mfma_f32_16x16x32_bf16 v[138:141], v[46:49], v[224:227], v[138:141]
	v_mfma_f32_16x16x32_bf16 v[126:129], v[38:41], v[232:235], v[126:129]
	v_mfma_f32_16x16x32_bf16 v[122:125], v[46:49], v[232:235], v[122:125]
	v_mfma_f32_16x16x32_bf16 v[94:97], v[38:41], v[240:243], v[94:97]
	v_mfma_f32_16x16x32_bf16 v[90:93], v[46:49], v[240:243], v[90:93]
	v_mfma_f32_16x16x32_bf16 v[150:153], v[98:101], v[212:215], v[150:153]
	v_mfma_f32_16x16x32_bf16 v[146:149], v[106:109], v[212:215], v[146:149]
	v_mfma_f32_16x16x32_bf16 v[134:137], v[98:101], v[220:223], v[134:137]
	v_mfma_f32_16x16x32_bf16 v[130:133], v[106:109], v[220:223], v[130:133]
	v_mfma_f32_16x16x32_bf16 v[118:121], v[98:101], v[228:231], v[118:121]
	v_mfma_f32_16x16x32_bf16 v[114:117], v[106:109], v[228:231], v[114:117]
	v_mfma_f32_16x16x32_bf16 v[86:89], v[98:101], v[236:239], v[86:89]
	v_mfma_f32_16x16x32_bf16 v[82:85], v[106:109], v[236:239], v[82:85]
	v_mfma_f32_16x16x32_bf16 v[150:153], v[102:105], v[216:219], v[150:153]
	v_mfma_f32_16x16x32_bf16 v[146:149], v[110:113], v[216:219], v[146:149]
	v_mfma_f32_16x16x32_bf16 v[134:137], v[102:105], v[224:227], v[134:137]
	v_mfma_f32_16x16x32_bf16 v[130:133], v[110:113], v[224:227], v[130:133]
	v_mfma_f32_16x16x32_bf16 v[118:121], v[102:105], v[232:235], v[118:121]
	v_mfma_f32_16x16x32_bf16 v[114:117], v[110:113], v[232:235], v[114:117]
	v_mfma_f32_16x16x32_bf16 v[86:89], v[102:105], v[240:243], v[86:89]
	v_mfma_f32_16x16x32_bf16 v[82:85], v[110:113], v[240:243], v[82:85]
	s_barrier
	s_add_i32 s21, s68, s29
	v_lshl_add_u64 v[182:183], s[48:49], 0, v[164:165]
	s_mov_b32 m0, s21
	ds_read_b128 v[212:215], v205 offset:16384
	ds_read_b128 v[216:219], v205 offset:17408
	ds_read_b128 v[220:223], v205 offset:18432
	ds_read_b128 v[224:227], v205 offset:19456
	ds_read_b128 v[228:231], v205 offset:20480
	ds_read_b128 v[232:235], v205 offset:21504
	ds_read_b128 v[236:239], v205 offset:22528
	ds_read_b128 v[240:243], v205 offset:23552
	global_load_lds_dwordx4 v[182:183], off
	s_add_i32 m0, s21, 0x2000
	s_add_u32 s22, s48, 0x20000
	v_lshl_add_u64 v[244:245], s[48:49], 0, v[168:169]
	s_addc_u32 s23, s49, 0
	s_add_i32 s21, s69, s29
	global_load_lds_dwordx4 v[244:245], off
	v_lshl_add_u64 v[246:247], s[22:23], 0, v[164:165]
	s_mov_b32 m0, s21
	v_lshl_add_u64 v[248:249], s[58:59], 0, v[166:167]
	global_load_lds_dwordx4 v[246:247], off
	v_lshl_add_u64 v[246:247], s[22:23], 0, v[168:169]
	s_add_i32 m0, s21, 0x2000
	s_nop 0
	global_load_lds_dwordx4 v[246:247], off
	v_lshl_add_u64 v[246:247], s[58:59], 0, v[162:163]
	s_mov_b32 m0, s30
	s_nop 0
	global_load_lds_dwordx4 v[246:247], off
	s_mov_b32 m0, s31
	s_nop 0
	global_load_lds_dwordx4 v[248:249], off
	s_waitcnt vmcnt(8)
	s_waitcnt lgkmcnt(0)
	s_barrier
	s_waitcnt lgkmcnt(0)
	v_mfma_f32_16x16x32_bf16 v[78:81], v[34:37], v[212:215], v[78:81]
	v_mfma_f32_16x16x32_bf16 v[74:77], v[42:45], v[212:215], v[74:77]
	v_mfma_f32_16x16x32_bf16 v[62:65], v[34:37], v[220:223], v[62:65]
	v_mfma_f32_16x16x32_bf16 v[58:61], v[42:45], v[220:223], v[58:61]
	v_mfma_f32_16x16x32_bf16 v[30:33], v[34:37], v[228:231], v[30:33]
	v_mfma_f32_16x16x32_bf16 v[26:29], v[42:45], v[228:231], v[26:29]
	v_mfma_f32_16x16x32_bf16 v[14:17], v[34:37], v[236:239], v[14:17]
	v_mfma_f32_16x16x32_bf16 v[10:13], v[42:45], v[236:239], v[10:13]
	v_mfma_f32_16x16x32_bf16 v[78:81], v[38:41], v[216:219], v[78:81]
	v_mfma_f32_16x16x32_bf16 v[74:77], v[46:49], v[216:219], v[74:77]
	v_mfma_f32_16x16x32_bf16 v[62:65], v[38:41], v[224:227], v[62:65]
	v_mfma_f32_16x16x32_bf16 v[58:61], v[46:49], v[224:227], v[58:61]
	v_mfma_f32_16x16x32_bf16 v[30:33], v[38:41], v[232:235], v[30:33]
	v_mfma_f32_16x16x32_bf16 v[26:29], v[46:49], v[232:235], v[26:29]
	v_mfma_f32_16x16x32_bf16 v[14:17], v[38:41], v[240:243], v[14:17]
	v_mfma_f32_16x16x32_bf16 v[10:13], v[46:49], v[240:243], v[10:13]
	v_mfma_f32_16x16x32_bf16 v[22:25], v[98:101], v[228:231], v[22:25]
	v_mfma_f32_16x16x32_bf16 v[18:21], v[106:109], v[228:231], v[18:21]
	v_mfma_f32_16x16x32_bf16 v[6:9], v[98:101], v[236:239], v[6:9]
	v_mfma_f32_16x16x32_bf16 v[2:5], v[106:109], v[236:239], v[2:5]
	v_mfma_f32_16x16x32_bf16 v[34:37], v[98:101], v[212:215], v[70:73]
	v_mfma_f32_16x16x32_bf16 v[38:41], v[106:109], v[212:215], v[66:69]
	v_mfma_f32_16x16x32_bf16 v[42:45], v[98:101], v[220:223], v[54:57]
	v_mfma_f32_16x16x32_bf16 v[46:49], v[106:109], v[220:223], v[50:53]
	v_mfma_f32_16x16x32_bf16 v[22:25], v[102:105], v[232:235], v[22:25]
	v_mfma_f32_16x16x32_bf16 v[18:21], v[110:113], v[232:235], v[18:21]
	v_mfma_f32_16x16x32_bf16 v[6:9], v[102:105], v[240:243], v[6:9]
	v_mfma_f32_16x16x32_bf16 v[2:5], v[110:113], v[240:243], v[2:5]
	v_mfma_f32_16x16x32_bf16 v[34:37], v[102:105], v[216:219], v[34:37]
	v_mfma_f32_16x16x32_bf16 v[38:41], v[110:113], v[216:219], v[38:41]
	v_mfma_f32_16x16x32_bf16 v[42:45], v[102:105], v[224:227], v[42:45]
	v_mfma_f32_16x16x32_bf16 v[46:49], v[110:113], v[224:227], v[46:49]
	s_barrier
; #define PG8_STAGE(bufoff, gbase, voff) do { _Pragma("unroll") for (int _i = 0; _i < 2; ++_i) \
;         __builtin_amdgcn_global_load_lds((const unsigned*)((const char*)(gbase) + (voff)[_i]), (LAS unsigned*)(lds + (bufoff) + ldsw + _i * 8192), 16, 0, 0); } while (0)
; #define PG8_LDA(dst, b, h) do { _Pragma("unroll") for (int m = 0; m < 4; ++m) _Pragma("unroll") for (int k = 0; k < 2; ++k) dst[m][k] = *(const LAS bf16x8*)(lds + PG8_SA(b, h) + aoff + m * 2048 + k * 1024); } while (0)
; #define PG8_LDB(dst, b, h) do { _Pragma("unroll") for (int n = 0; n < 2; ++n) _Pragma("unroll") for (int k = 0; k < 2; ++k) dst[n][k] = *(const LAS bf16x8*)(lds + PG8_SB(b, h) + boff + n * 2048 + k * 1024); } while (0)
; #define PG8_MMA(ai, bj, At, Bt) do { __builtin_amdgcn_s_setprio(1); _Pragma("unroll") for (int m = 0; m < 4; ++m) _Pragma("unroll") for (int n = 0; n < 2; ++n) _Pragma("unroll") for (int k = 0; k < 2; ++k) \
;         acc[ai][bj][m][n] = __builtin_amdgcn_mfma_f32_16x16x32_bf16(Bt[n][k], At[m][k], acc[ai][bj][m][n], 0, 0, 0); __builtin_amdgcn_s_setprio(0); } while (0)
; #define PG8_WAIT_V(n) asm volatile("s_waitcnt vmcnt(" #n ")" ::: "memory")
; #define PG8_WAIT_L(n) asm volatile("s_waitcnt lgkmcnt(" #n ")" ::: "memory")
; #define PG8_BAR __builtin_amdgcn_s_barrier()
; #define PG8_SCHED __builtin_amdgcn_sched_barrier(0)
; template <class Epi, class Sched, bool ALIGN_EPI = false, bool SP2 = false>
; __device__ __forceinline__ void gemm_phase(LAS unsigned char* lds, const Gemm g, const Sched& S, const Epi& E) {
;     ...
;             PG8_LDB(B0, 1, 0); PG8_LDB(B1, 1, 1); PG8_SCHED; PG8_LDA(At, 1, 0); PG8_STAGE(PG8_SA(0, 1), a2 + hstep, voffA);
;             PG8_WAIT_V(8); PG8_WAIT_L(0); PG8_BAR; PG8_MMA(0, 0, At, B0); PG8_MMA(0, 1, At, B1); PG8_BAR; PG8_SCHED;
	s_add_i32 s21, 0, 0x18000
	s_add_i32 s24, 0, 0x1c000
	v_add_u32_e32 v70, s21, v186
	v_add_u32_e32 v110, s24, v186
	ds_read_b128 v[50:53], v70
	ds_read_b128 v[54:57], v70 offset:1024
	ds_read_b128 v[66:69], v70 offset:2048
	ds_read_b128 v[70:73], v70 offset:3072
	ds_read_b128 v[98:101], v110
	ds_read_b128 v[102:105], v110 offset:1024
	ds_read_b128 v[106:109], v110 offset:2048
	ds_read_b128 v[110:113], v110 offset:3072
	s_add_u32 s22, s58, 0x80000
	s_addc_u32 s23, s59, 0
	s_mov_b32 m0, s33
	v_lshl_add_u64 v[250:251], s[22:23], 0, v[162:163]
	ds_read_b128 v[212:215], v205 offset:32768
	ds_read_b128 v[216:219], v205 offset:33792
	ds_read_b128 v[220:223], v205 offset:34816
	ds_read_b128 v[224:227], v205 offset:35840
	ds_read_b128 v[228:231], v205 offset:36864
	ds_read_b128 v[232:235], v205 offset:37888
	ds_read_b128 v[236:239], v205 offset:38912
	ds_read_b128 v[240:243], v205 offset:39936
	global_load_lds_dwordx4 v[250:251], off
	v_lshl_add_u64 v[250:251], s[22:23], 0, v[166:167]
	s_mov_b32 m0, s60
	s_nop 0
	global_load_lds_dwordx4 v[250:251], off
	s_waitcnt vmcnt(8)
	s_waitcnt lgkmcnt(0)
	s_barrier
	s_waitcnt lgkmcnt(0)
	v_mfma_f32_16x16x32_bf16 v[158:161], v[50:53], v[212:215], v[158:161]
	v_mfma_f32_16x16x32_bf16 v[154:157], v[66:69], v[212:215], v[154:157]
	v_mfma_f32_16x16x32_bf16 v[142:145], v[50:53], v[220:223], v[142:145]
	v_mfma_f32_16x16x32_bf16 v[138:141], v[66:69], v[220:223], v[138:141]
	v_mfma_f32_16x16x32_bf16 v[126:129], v[50:53], v[228:231], v[126:129]
	v_mfma_f32_16x16x32_bf16 v[122:125], v[66:69], v[228:231], v[122:125]
	v_mfma_f32_16x16x32_bf16 v[94:97], v[50:53], v[236:239], v[94:97]
	v_mfma_f32_16x16x32_bf16 v[90:93], v[66:69], v[236:239], v[90:93]
	v_mfma_f32_16x16x32_bf16 v[158:161], v[54:57], v[216:219], v[158:161]
	v_mfma_f32_16x16x32_bf16 v[154:157], v[70:73], v[216:219], v[154:157]
	v_mfma_f32_16x16x32_bf16 v[142:145], v[54:57], v[224:227], v[142:145]
	v_mfma_f32_16x16x32_bf16 v[138:141], v[70:73], v[224:227], v[138:141]
	v_mfma_f32_16x16x32_bf16 v[126:129], v[54:57], v[232:235], v[126:129]
	v_mfma_f32_16x16x32_bf16 v[122:125], v[70:73], v[232:235], v[122:125]
	v_mfma_f32_16x16x32_bf16 v[94:97], v[54:57], v[240:243], v[94:97]
	v_mfma_f32_16x16x32_bf16 v[90:93], v[70:73], v[240:243], v[90:93]
	v_mfma_f32_16x16x32_bf16 v[150:153], v[98:101], v[212:215], v[150:153]
	v_mfma_f32_16x16x32_bf16 v[146:149], v[106:109], v[212:215], v[146:149]
	v_mfma_f32_16x16x32_bf16 v[134:137], v[98:101], v[220:223], v[134:137]
	v_mfma_f32_16x16x32_bf16 v[130:133], v[106:109], v[220:223], v[130:133]
	v_mfma_f32_16x16x32_bf16 v[118:121], v[98:101], v[228:231], v[118:121]
	v_mfma_f32_16x16x32_bf16 v[114:117], v[106:109], v[228:231], v[114:117]
	v_mfma_f32_16x16x32_bf16 v[86:89], v[98:101], v[236:239], v[86:89]
	v_mfma_f32_16x16x32_bf16 v[82:85], v[106:109], v[236:239], v[82:85]
	v_mfma_f32_16x16x32_bf16 v[150:153], v[102:105], v[216:219], v[150:153]
	v_mfma_f32_16x16x32_bf16 v[146:149], v[110:113], v[216:219], v[146:149]
	v_mfma_f32_16x16x32_bf16 v[134:137], v[102:105], v[224:227], v[134:137]
	v_mfma_f32_16x16x32_bf16 v[130:133], v[110:113], v[224:227], v[130:133]
	v_mfma_f32_16x16x32_bf16 v[118:121], v[102:105], v[232:235], v[118:121]
	v_mfma_f32_16x16x32_bf16 v[114:117], v[110:113], v[232:235], v[114:117]
	v_mfma_f32_16x16x32_bf16 v[86:89], v[102:105], v[240:243], v[86:89]
	v_mfma_f32_16x16x32_bf16 v[82:85], v[110:113], v[240:243], v[82:85]
	s_barrier
; #define PG8_STAGE(bufoff, gbase, voff) do { _Pragma("unroll") for (int _i = 0; _i < 2; ++_i) \
;         __builtin_amdgcn_global_load_lds((const unsigned*)((const char*)(gbase) + (voff)[_i]), (LAS unsigned*)(lds + (bufoff) + ldsw + _i * 8192), 16, 0, 0); } while (0)
; #define PG8_LDA(dst, b, h) do { _Pragma("unroll") for (int m = 0; m < 4; ++m) _Pragma("unroll") for (int k = 0; k < 2; ++k) dst[m][k] = *(const LAS bf16x8*)(lds + PG8_SA(b, h) + aoff + m * 2048 + k * 1024); } while (0)
; #define PG8_MMA(ai, bj, At, Bt) do { __builtin_amdgcn_s_setprio(1); _Pragma("unroll") for (int m = 0; m < 4; ++m) _Pragma("unroll") for (int n = 0; n < 2; ++n) _Pragma("unroll") for (int k = 0; k < 2; ++k) \
;         acc[ai][bj][m][n] = __builtin_amdgcn_mfma_f32_16x16x32_bf16(Bt[n][k], At[m][k], acc[ai][bj][m][n], 0, 0, 0); __builtin_amdgcn_s_setprio(0); } while (0)
; #define PG8_WAIT_V(n) asm volatile("s_waitcnt vmcnt(" #n ")" ::: "memory")
; #define PG8_WAIT_L(n) asm volatile("s_waitcnt lgkmcnt(" #n ")" ::: "memory")
; #define PG8_BAR __builtin_amdgcn_s_barrier()
; #define PG8_SCHED __builtin_amdgcn_sched_barrier(0)
; template <class Epi, class Sched, bool ALIGN_EPI = false, bool SP2 = false>
; __device__ __forceinline__ void gemm_phase(LAS unsigned char* lds, const Gemm g, const Sched& S, const Epi& E) {
;     ...
;             PG8_LDA(At, 1, 1); PG8_STAGE(PG8_SB(1, 0), b3, voffB); PG8_STAGE(PG8_SB(1, 1), b3 + hstepB, voffB); PG8_STAGE(PG8_SA(1, 0), a3, voffA);
;             PG8_WAIT_V(8); PG8_WAIT_L(0); PG8_BAR; PG8_MMA(1, 0, At, B0); PG8_MMA(1, 1, At, B1); PG8_BAR; PG8_SCHED;
;     ...
;         if constexpr (ALIGN_EPI) { if (wr == 0) PG8_BAR; }
	s_add_i32 s21, s21, s29
	v_lshl_add_u64 v[182:183], v[182:183], 0, s[34:35]
	s_mov_b32 m0, s21
	ds_read_b128 v[212:215], v205 offset:49152
	ds_read_b128 v[216:219], v205 offset:50176
	ds_read_b128 v[220:223], v205 offset:51200
	ds_read_b128 v[224:227], v205 offset:52224
	ds_read_b128 v[228:231], v205 offset:53248
	ds_read_b128 v[232:235], v205 offset:54272
	ds_read_b128 v[236:239], v205 offset:55296
	ds_read_b128 v[240:243], v205 offset:56320
	global_load_lds_dwordx4 v[182:183], off
	s_add_i32 m0, s21, 0x2000
	s_add_u32 s22, s48, 0x20080
	v_lshl_add_u64 v[182:183], v[244:245], 0, s[34:35]
	s_addc_u32 s23, s49, 0
	s_add_i32 s21, s24, s29
	global_load_lds_dwordx4 v[182:183], off
	v_lshl_add_u64 v[182:183], s[22:23], 0, v[164:165]
	s_mov_b32 m0, s21
	s_nop 0
	global_load_lds_dwordx4 v[182:183], off
	v_lshl_add_u64 v[182:183], s[22:23], 0, v[168:169]
	s_add_i32 m0, s21, 0x2000
	s_nop 0
	global_load_lds_dwordx4 v[182:183], off
	v_lshl_add_u64 v[182:183], v[246:247], 0, s[34:35]
	s_mov_b32 m0, s65
	s_nop 0
	global_load_lds_dwordx4 v[182:183], off
	v_lshl_add_u64 v[182:183], v[248:249], 0, s[34:35]
	s_mov_b32 m0, s66
	s_nop 0
	global_load_lds_dwordx4 v[182:183], off
	s_waitcnt vmcnt(8)
	s_waitcnt lgkmcnt(0)
	s_barrier
	s_waitcnt lgkmcnt(0)
	v_mfma_f32_16x16x32_bf16 v[78:81], v[50:53], v[212:215], v[78:81]
	v_mfma_f32_16x16x32_bf16 v[74:77], v[66:69], v[212:215], v[74:77]
	v_mfma_f32_16x16x32_bf16 v[62:65], v[50:53], v[220:223], v[62:65]
	v_mfma_f32_16x16x32_bf16 v[58:61], v[66:69], v[220:223], v[58:61]
	v_mfma_f32_16x16x32_bf16 v[30:33], v[50:53], v[228:231], v[30:33]
	v_mfma_f32_16x16x32_bf16 v[26:29], v[66:69], v[228:231], v[26:29]
	v_mfma_f32_16x16x32_bf16 v[14:17], v[50:53], v[236:239], v[14:17]
	v_mfma_f32_16x16x32_bf16 v[10:13], v[66:69], v[236:239], v[10:13]
	v_mfma_f32_16x16x32_bf16 v[78:81], v[54:57], v[216:219], v[78:81]
	v_mfma_f32_16x16x32_bf16 v[74:77], v[70:73], v[216:219], v[74:77]
	v_mfma_f32_16x16x32_bf16 v[62:65], v[54:57], v[224:227], v[62:65]
	v_mfma_f32_16x16x32_bf16 v[58:61], v[70:73], v[224:227], v[58:61]
	v_mfma_f32_16x16x32_bf16 v[30:33], v[54:57], v[232:235], v[30:33]
	v_mfma_f32_16x16x32_bf16 v[26:29], v[70:73], v[232:235], v[26:29]
	v_mfma_f32_16x16x32_bf16 v[14:17], v[54:57], v[240:243], v[14:17]
	v_mfma_f32_16x16x32_bf16 v[10:13], v[70:73], v[240:243], v[10:13]
	v_mfma_f32_16x16x32_bf16 v[34:37], v[98:101], v[212:215], v[34:37]
	v_mfma_f32_16x16x32_bf16 v[70:73], v[102:105], v[216:219], v[34:37]
	v_mfma_f32_16x16x32_bf16 v[34:37], v[106:109], v[212:215], v[38:41]
	v_mfma_f32_16x16x32_bf16 v[66:69], v[110:113], v[216:219], v[34:37]
	v_mfma_f32_16x16x32_bf16 v[34:37], v[98:101], v[220:223], v[42:45]
	v_mfma_f32_16x16x32_bf16 v[54:57], v[102:105], v[224:227], v[34:37]
	v_mfma_f32_16x16x32_bf16 v[34:37], v[106:109], v[220:223], v[46:49]
	v_mfma_f32_16x16x32_bf16 v[22:25], v[98:101], v[228:231], v[22:25]
	v_mfma_f32_16x16x32_bf16 v[18:21], v[106:109], v[228:231], v[18:21]
	v_mfma_f32_16x16x32_bf16 v[6:9], v[98:101], v[236:239], v[6:9]
	v_mfma_f32_16x16x32_bf16 v[2:5], v[106:109], v[236:239], v[2:5]
	v_mfma_f32_16x16x32_bf16 v[50:53], v[110:113], v[224:227], v[34:37]
	v_mfma_f32_16x16x32_bf16 v[22:25], v[102:105], v[232:235], v[22:25]
	v_mfma_f32_16x16x32_bf16 v[18:21], v[110:113], v[232:235], v[18:21]
	v_mfma_f32_16x16x32_bf16 v[6:9], v[102:105], v[240:243], v[6:9]
	v_mfma_f32_16x16x32_bf16 v[2:5], v[110:113], v[240:243], v[2:5]
	s_barrier
	s_add_i32 s20, s20, 2
	s_add_u32 s16, s16, 0x100
	s_addc_u32 s17, s17, 0
	s_add_u32 s18, s18, 0x100
	s_addc_u32 s19, s19, 0
	s_cmp_gt_u32 s20, 29
	s_cbranch_scc0 .LBB0_535
	s_and_b64 vcc, exec, s[76:77]
	s_cbranch_vccz .LBB0_538
	s_barrier

; #define PG8_STAGE(bufoff, gbase, voff) do { _Pragma("unroll") for (int _i = 0; _i < 2; ++_i) \
;         __builtin_amdgcn_global_load_lds((const unsigned*)((const char*)(gbase) + (voff)[_i]), (LAS unsigned*)(lds + (bufoff) + ldsw + _i * 8192), 16, 0, 0); } while (0)
; #define PG8_LDA(dst, b, h) do { _Pragma("unroll") for (int m = 0; m < 4; ++m) _Pragma("unroll") for (int k = 0; k < 2; ++k) dst[m][k] = *(const LAS bf16x8*)(lds + PG8_SA(b, h) + aoff + m * 2048 + k * 1024); } while (0)
; #define PG8_LDB(dst, b, h) do { _Pragma("unroll") for (int n = 0; n < 2; ++n) _Pragma("unroll") for (int k = 0; k < 2; ++k) dst[n][k] = *(const LAS bf16x8*)(lds + PG8_SB(b, h) + boff + n * 2048 + k * 1024); } while (0)
; #define PG8_MMA(ai, bj, At, Bt) do { __builtin_amdgcn_s_setprio(1); _Pragma("unroll") for (int m = 0; m < 4; ++m) _Pragma("unroll") for (int n = 0; n < 2; ++n) _Pragma("unroll") for (int k = 0; k < 2; ++k) \
;         acc[ai][bj][m][n] = __builtin_amdgcn_mfma_f32_16x16x32_bf16(Bt[n][k], At[m][k], acc[ai][bj][m][n], 0, 0, 0); __builtin_amdgcn_s_setprio(0); } while (0)
; #define PG8_WAIT_V(n) asm volatile("s_waitcnt vmcnt(" #n ")" ::: "memory")
; #define PG8_WAIT_L(n) asm volatile("s_waitcnt lgkmcnt(" #n ")" ::: "memory")
; #define PG8_BAR __builtin_amdgcn_s_barrier()
; #define PG8_SCHED __builtin_amdgcn_sched_barrier(0)
; template <class Epi, class Sched, bool ALIGN_EPI = false, bool SP2 = false>
; __device__ __forceinline__ void gemm_phase(LAS unsigned char* lds, const Gemm g, const Sched& S, const Epi& E) {
;     ...
;         for (int t = 0; t < nt; t += 2) {
;             const bool last = (t == nt - 2);
;             const char* a1 = cA + (size_t)(t + 1) * kstep;
;             const char* a2 = last ? nA : cA + (size_t)(t + 2) * kstep; const char* b2 = last ? nB : cB + (size_t)(t + 2) * kstep;
;             const char* a3 = a2 + kstep; const char* b3 = b2 + kstep;
;             if (last && has_next) S.a_ready(nxt);
;             if constexpr (SP2) {
;             PG8_LDB(B0, 0, 0); PG8_LDB(B1, 0, 1); PG8_SCHED; PG8_LDA(At, 0, 0); PG8_STAGE(PG8_SA(1, 1), a1 + hstep, voffA);
;             PG8_WAIT_V(8); PG8_WAIT_L(0); PG8_BAR; PG8_MMA(0, 0, At, B0); PG8_MMA(0, 1, At, B1); PG8_BAR; PG8_SCHED;
;             PG8_LDA(At, 0, 1); PG8_STAGE(PG8_SB(0, 0), b2, voffB); PG8_STAGE(PG8_SB(0, 1), b2 + hstepB, voffB); PG8_STAGE(PG8_SA(0, 0), a2, voffA);
.LBB0_1225:
	ds_read_b128 v[140:143], v135
	ds_read_b128 v[144:147], v135 offset:1024
	ds_read_b128 v[148:151], v135 offset:2048
	ds_read_b128 v[152:155], v135 offset:3072
	ds_read_b128 v[156:159], v136
	ds_read_b128 v[160:163], v136 offset:1024
	ds_read_b128 v[164:167], v136 offset:2048
	ds_read_b128 v[168:171], v136 offset:3072
	s_add_i32 s16, s18, 2
	s_mov_b32 s17, s13
	s_or_b32 s12, s18, 1
	s_lshl_b64 s[20:21], s[16:17], 7
	s_cmp_lg_u32 s18, s33
	s_cselect_b32 s18, s20, 0
	s_cselect_b32 s17, s21, 0
	s_add_u32 s20, s8, s18
	s_addc_u32 s21, s9, s17
	s_add_u32 s18, s4, s18
	s_addc_u32 s19, s5, s17
	s_lshl_b64 s[44:45], s[12:13], 7
	s_add_u32 s44, s10, s44
	s_addc_u32 s45, s11, s45
	s_mov_b32 m0, s34
	v_lshl_add_u64 v[204:205], s[44:45], 0, v[132:133]
	ds_read_b128 v[172:175], v137
	ds_read_b128 v[176:179], v137 offset:1024
	ds_read_b128 v[180:183], v137 offset:2048
	ds_read_b128 v[184:187], v137 offset:3072
	ds_read_b128 v[188:191], v137 offset:4096
	ds_read_b128 v[192:195], v137 offset:5120
	ds_read_b128 v[196:199], v137 offset:6144
	ds_read_b128 v[200:203], v137 offset:7168
	global_load_lds_dwordx4 v[204:205], off
	v_lshl_add_u64 v[204:205], s[44:45], 0, v[130:131]
	s_mov_b32 m0, s35
	s_nop 0
	global_load_lds_dwordx4 v[204:205], off
	s_waitcnt vmcnt(8)
	s_waitcnt lgkmcnt(0)
	s_barrier
	s_waitcnt lgkmcnt(0)
	v_mfma_f32_16x16x32_bf16 v[126:129], v[140:143], v[172:175], v[126:129]
	v_mfma_f32_16x16x32_bf16 v[94:97], v[148:151], v[172:175], v[94:97]
	v_mfma_f32_16x16x32_bf16 v[122:125], v[140:143], v[180:183], v[122:125]
	v_mfma_f32_16x16x32_bf16 v[90:93], v[148:151], v[180:183], v[90:93]
	v_mfma_f32_16x16x32_bf16 v[118:121], v[140:143], v[188:191], v[118:121]
	v_mfma_f32_16x16x32_bf16 v[86:89], v[148:151], v[188:191], v[86:89]
	v_mfma_f32_16x16x32_bf16 v[114:117], v[140:143], v[196:199], v[114:117]
	v_mfma_f32_16x16x32_bf16 v[82:85], v[148:151], v[196:199], v[82:85]
	v_mfma_f32_16x16x32_bf16 v[126:129], v[144:147], v[176:179], v[126:129]
	v_mfma_f32_16x16x32_bf16 v[94:97], v[152:155], v[176:179], v[94:97]
	v_mfma_f32_16x16x32_bf16 v[122:125], v[144:147], v[184:187], v[122:125]
	v_mfma_f32_16x16x32_bf16 v[90:93], v[152:155], v[184:187], v[90:93]
	v_mfma_f32_16x16x32_bf16 v[118:121], v[144:147], v[192:195], v[118:121]
	v_mfma_f32_16x16x32_bf16 v[86:89], v[152:155], v[192:195], v[86:89]
	v_mfma_f32_16x16x32_bf16 v[114:117], v[144:147], v[200:203], v[114:117]
	v_mfma_f32_16x16x32_bf16 v[82:85], v[152:155], v[200:203], v[82:85]
	v_mfma_f32_16x16x32_bf16 v[70:73], v[156:159], v[172:175], v[70:73]
	v_mfma_f32_16x16x32_bf16 v[42:45], v[164:167], v[172:175], v[42:45]
	v_mfma_f32_16x16x32_bf16 v[62:65], v[156:159], v[180:183], v[62:65]
	v_mfma_f32_16x16x32_bf16 v[34:37], v[164:167], v[180:183], v[34:37]
	v_mfma_f32_16x16x32_bf16 v[54:57], v[156:159], v[188:191], v[54:57]
	v_mfma_f32_16x16x32_bf16 v[26:29], v[164:167], v[188:191], v[26:29]
	v_mfma_f32_16x16x32_bf16 v[50:53], v[156:159], v[196:199], v[50:53]
	v_mfma_f32_16x16x32_bf16 v[18:21], v[164:167], v[196:199], v[18:21]
	v_mfma_f32_16x16x32_bf16 v[70:73], v[160:163], v[176:179], v[70:73]
	v_mfma_f32_16x16x32_bf16 v[42:45], v[168:171], v[176:179], v[42:45]
	v_mfma_f32_16x16x32_bf16 v[62:65], v[160:163], v[184:187], v[62:65]
	v_mfma_f32_16x16x32_bf16 v[34:37], v[168:171], v[184:187], v[34:37]
	v_mfma_f32_16x16x32_bf16 v[54:57], v[160:163], v[192:195], v[54:57]
	v_mfma_f32_16x16x32_bf16 v[26:29], v[168:171], v[192:195], v[26:29]
	v_mfma_f32_16x16x32_bf16 v[50:53], v[160:163], v[200:203], v[50:53]
	v_mfma_f32_16x16x32_bf16 v[18:21], v[168:171], v[200:203], v[18:21]
	s_barrier
	s_mov_b32 m0, s36
	v_lshl_add_u64 v[204:205], s[18:19], 0, v[132:133]
	s_add_u32 s44, s18, 0x80000
	ds_read_b128 v[172:175], v137 offset:16384
	ds_read_b128 v[176:179], v137 offset:17408
	ds_read_b128 v[180:183], v137 offset:18432
	ds_read_b128 v[184:187], v137 offset:19456
	ds_read_b128 v[188:191], v137 offset:20480
	ds_read_b128 v[192:195], v137 offset:21504
	ds_read_b128 v[196:199], v137 offset:22528
	ds_read_b128 v[200:203], v137 offset:23552
	global_load_lds_dwordx4 v[204:205], off
	v_lshl_add_u64 v[206:207], s[18:19], 0, v[130:131]
	s_mov_b32 m0, s37
	s_addc_u32 s45, s19, 0
	global_load_lds_dwordx4 v[206:207], off
	v_lshl_add_u64 v[208:209], s[44:45], 0, v[132:133]
	s_mov_b32 m0, s38
	v_lshl_add_u64 v[210:211], s[20:21], 0, v[130:131]
	global_load_lds_dwordx4 v[208:209], off
	v_lshl_add_u64 v[208:209], s[44:45], 0, v[130:131]
	s_mov_b32 m0, s39
	s_nop 0
	global_load_lds_dwordx4 v[208:209], off
	v_lshl_add_u64 v[208:209], s[20:21], 0, v[132:133]
	s_mov_b32 m0, s3
	s_nop 0
	global_load_lds_dwordx4 v[208:209], off
	s_mov_b32 m0, s24
	s_nop 0
	global_load_lds_dwordx4 v[210:211], off
	s_waitcnt vmcnt(8)
	s_waitcnt lgkmcnt(0)
	s_barrier
; #define PG8_STAGE(bufoff, gbase, voff) do { _Pragma("unroll") for (int _i = 0; _i < 2; ++_i) \
;         __builtin_amdgcn_global_load_lds((const unsigned*)((const char*)(gbase) + (voff)[_i]), (LAS unsigned*)(lds + (bufoff) + ldsw + _i * 8192), 16, 0, 0); } while (0)
; #define PG8_LDA(dst, b, h) do { _Pragma("unroll") for (int m = 0; m < 4; ++m) _Pragma("unroll") for (int k = 0; k < 2; ++k) dst[m][k] = *(const LAS bf16x8*)(lds + PG8_SA(b, h) + aoff + m * 2048 + k * 1024); } while (0)
; #define PG8_LDB(dst, b, h) do { _Pragma("unroll") for (int n = 0; n < 2; ++n) _Pragma("unroll") for (int k = 0; k < 2; ++k) dst[n][k] = *(const LAS bf16x8*)(lds + PG8_SB(b, h) + boff + n * 2048 + k * 1024); } while (0)
; #define PG8_MMA(ai, bj, At, Bt) do { __builtin_amdgcn_s_setprio(1); _Pragma("unroll") for (int m = 0; m < 4; ++m) _Pragma("unroll") for (int n = 0; n < 2; ++n) _Pragma("unroll") for (int k = 0; k < 2; ++k) \
;         acc[ai][bj][m][n] = __builtin_amdgcn_mfma_f32_16x16x32_bf16(Bt[n][k], At[m][k], acc[ai][bj][m][n], 0, 0, 0); __builtin_amdgcn_s_setprio(0); } while (0)
; #define PG8_WAIT_V(n) asm volatile("s_waitcnt vmcnt(" #n ")" ::: "memory")
; #define PG8_WAIT_L(n) asm volatile("s_waitcnt lgkmcnt(" #n ")" ::: "memory")
; #define PG8_BAR __builtin_amdgcn_s_barrier()
; #define PG8_SCHED __builtin_amdgcn_sched_barrier(0)
; template <class Epi, class Sched, bool ALIGN_EPI = false, bool SP2 = false>
; __device__ __forceinline__ void gemm_phase(LAS unsigned char* lds, const Gemm g, const Sched& S, const Epi& E) {
;     ...
;             PG8_WAIT_V(8); PG8_WAIT_L(0); PG8_BAR; PG8_MMA(1, 0, At, B0); PG8_MMA(1, 1, At, B1); PG8_BAR; PG8_SCHED;
;             PG8_LDB(B0, 1, 0); PG8_LDB(B1, 1, 1); PG8_SCHED; PG8_LDA(At, 1, 0); PG8_STAGE(PG8_SA(0, 1), a2 + hstep, voffA);
;             PG8_WAIT_V(8); PG8_WAIT_L(0); PG8_BAR; PG8_MMA(0, 0, At, B0); PG8_MMA(0, 1, At, B1); PG8_BAR; PG8_SCHED;
	s_waitcnt lgkmcnt(0)
	v_mfma_f32_16x16x32_bf16 v[110:113], v[140:143], v[172:175], v[110:113]
	v_mfma_f32_16x16x32_bf16 v[78:81], v[148:151], v[172:175], v[78:81]
	v_mfma_f32_16x16x32_bf16 v[106:109], v[140:143], v[180:183], v[106:109]
	v_mfma_f32_16x16x32_bf16 v[74:77], v[148:151], v[180:183], v[74:77]
	v_mfma_f32_16x16x32_bf16 v[102:105], v[140:143], v[188:191], v[102:105]
	v_mfma_f32_16x16x32_bf16 v[66:69], v[148:151], v[188:191], v[66:69]
	v_mfma_f32_16x16x32_bf16 v[98:101], v[140:143], v[196:199], v[98:101]
	v_mfma_f32_16x16x32_bf16 v[58:61], v[148:151], v[196:199], v[58:61]
	v_mfma_f32_16x16x32_bf16 v[110:113], v[144:147], v[176:179], v[110:113]
	v_mfma_f32_16x16x32_bf16 v[78:81], v[152:155], v[176:179], v[78:81]
	v_mfma_f32_16x16x32_bf16 v[106:109], v[144:147], v[184:187], v[106:109]
	v_mfma_f32_16x16x32_bf16 v[74:77], v[152:155], v[184:187], v[74:77]
	v_mfma_f32_16x16x32_bf16 v[102:105], v[144:147], v[192:195], v[102:105]
	v_mfma_f32_16x16x32_bf16 v[66:69], v[152:155], v[192:195], v[66:69]
	v_mfma_f32_16x16x32_bf16 v[98:101], v[144:147], v[200:203], v[98:101]
	v_mfma_f32_16x16x32_bf16 v[58:61], v[152:155], v[200:203], v[58:61]
	v_mfma_f32_16x16x32_bf16 v[46:49], v[156:159], v[172:175], v[46:49]
	v_mfma_f32_16x16x32_bf16 v[14:17], v[164:167], v[172:175], v[14:17]
	v_mfma_f32_16x16x32_bf16 v[38:41], v[156:159], v[180:183], v[38:41]
	v_mfma_f32_16x16x32_bf16 v[10:13], v[164:167], v[180:183], v[10:13]
	v_mfma_f32_16x16x32_bf16 v[30:33], v[156:159], v[188:191], v[30:33]
	v_mfma_f32_16x16x32_bf16 v[6:9], v[164:167], v[188:191], v[6:9]
	v_mfma_f32_16x16x32_bf16 v[22:25], v[156:159], v[196:199], v[22:25]
	v_mfma_f32_16x16x32_bf16 v[2:5], v[164:167], v[196:199], v[2:5]
	v_mfma_f32_16x16x32_bf16 v[46:49], v[160:163], v[176:179], v[46:49]
	v_mfma_f32_16x16x32_bf16 v[14:17], v[168:171], v[176:179], v[14:17]
	v_mfma_f32_16x16x32_bf16 v[38:41], v[160:163], v[184:187], v[38:41]
	v_mfma_f32_16x16x32_bf16 v[10:13], v[168:171], v[184:187], v[10:13]
	v_mfma_f32_16x16x32_bf16 v[30:33], v[160:163], v[192:195], v[30:33]
	v_mfma_f32_16x16x32_bf16 v[6:9], v[168:171], v[192:195], v[6:9]
	v_mfma_f32_16x16x32_bf16 v[22:25], v[160:163], v[200:203], v[22:25]
	v_mfma_f32_16x16x32_bf16 v[2:5], v[168:171], v[200:203], v[2:5]
	s_barrier
	ds_read_b128 v[140:143], v138
	ds_read_b128 v[144:147], v138 offset:1024
	ds_read_b128 v[148:151], v138 offset:2048
	ds_read_b128 v[152:155], v138 offset:3072
	ds_read_b128 v[156:159], v139
	ds_read_b128 v[160:163], v139 offset:1024
	ds_read_b128 v[164:167], v139 offset:2048
	ds_read_b128 v[168:171], v139 offset:3072
	s_add_u32 s20, s20, 0x80000
	s_addc_u32 s21, s21, 0
	s_mov_b32 m0, s25
	v_lshl_add_u64 v[212:213], s[20:21], 0, v[132:133]
	ds_read_b128 v[172:175], v137 offset:32768
	ds_read_b128 v[176:179], v137 offset:33792
	ds_read_b128 v[180:183], v137 offset:34816
	ds_read_b128 v[184:187], v137 offset:35840
	ds_read_b128 v[188:191], v137 offset:36864
	ds_read_b128 v[192:195], v137 offset:37888
	ds_read_b128 v[196:199], v137 offset:38912
	ds_read_b128 v[200:203], v137 offset:39936
	global_load_lds_dwordx4 v[212:213], off
	v_lshl_add_u64 v[212:213], s[20:21], 0, v[130:131]
	s_mov_b32 m0, s28
	s_nop 0
	global_load_lds_dwordx4 v[212:213], off
	s_waitcnt vmcnt(8)
	s_waitcnt lgkmcnt(0)
	s_barrier
	s_waitcnt lgkmcnt(0)
	v_mfma_f32_16x16x32_bf16 v[126:129], v[140:143], v[172:175], v[126:129]
	v_mfma_f32_16x16x32_bf16 v[94:97], v[148:151], v[172:175], v[94:97]
	v_mfma_f32_16x16x32_bf16 v[122:125], v[140:143], v[180:183], v[122:125]
	v_mfma_f32_16x16x32_bf16 v[90:93], v[148:151], v[180:183], v[90:93]
	v_mfma_f32_16x16x32_bf16 v[118:121], v[140:143], v[188:191], v[118:121]
	v_mfma_f32_16x16x32_bf16 v[86:89], v[148:151], v[188:191], v[86:89]
	v_mfma_f32_16x16x32_bf16 v[114:117], v[140:143], v[196:199], v[114:117]
	v_mfma_f32_16x16x32_bf16 v[82:85], v[148:151], v[196:199], v[82:85]
	v_mfma_f32_16x16x32_bf16 v[126:129], v[144:147], v[176:179], v[126:129]
	v_mfma_f32_16x16x32_bf16 v[94:97], v[152:155], v[176:179], v[94:97]
	v_mfma_f32_16x16x32_bf16 v[122:125], v[144:147], v[184:187], v[122:125]
	v_mfma_f32_16x16x32_bf16 v[90:93], v[152:155], v[184:187], v[90:93]
	v_mfma_f32_16x16x32_bf16 v[118:121], v[144:147], v[192:195], v[118:121]
	v_mfma_f32_16x16x32_bf16 v[86:89], v[152:155], v[192:195], v[86:89]
	v_mfma_f32_16x16x32_bf16 v[114:117], v[144:147], v[200:203], v[114:117]
	v_mfma_f32_16x16x32_bf16 v[82:85], v[152:155], v[200:203], v[82:85]
	v_mfma_f32_16x16x32_bf16 v[70:73], v[156:159], v[172:175], v[70:73]
	v_mfma_f32_16x16x32_bf16 v[42:45], v[164:167], v[172:175], v[42:45]
	v_mfma_f32_16x16x32_bf16 v[62:65], v[156:159], v[180:183], v[62:65]
	v_mfma_f32_16x16x32_bf16 v[34:37], v[164:167], v[180:183], v[34:37]
	v_mfma_f32_16x16x32_bf16 v[54:57], v[156:159], v[188:191], v[54:57]
	v_mfma_f32_16x16x32_bf16 v[26:29], v[164:167], v[188:191], v[26:29]
	v_mfma_f32_16x16x32_bf16 v[50:53], v[156:159], v[196:199], v[50:53]
	v_mfma_f32_16x16x32_bf16 v[18:21], v[164:167], v[196:199], v[18:21]
	v_mfma_f32_16x16x32_bf16 v[70:73], v[160:163], v[176:179], v[70:73]
	v_mfma_f32_16x16x32_bf16 v[42:45], v[168:171], v[176:179], v[42:45]
	v_mfma_f32_16x16x32_bf16 v[62:65], v[160:163], v[184:187], v[62:65]
	v_mfma_f32_16x16x32_bf16 v[34:37], v[168:171], v[184:187], v[34:37]
	v_mfma_f32_16x16x32_bf16 v[54:57], v[160:163], v[192:195], v[54:57]
	v_mfma_f32_16x16x32_bf16 v[26:29], v[168:171], v[192:195], v[26:29]
	v_mfma_f32_16x16x32_bf16 v[50:53], v[160:163], v[200:203], v[50:53]
	v_mfma_f32_16x16x32_bf16 v[18:21], v[168:171], v[200:203], v[18:21]
	s_barrier
; #define PG8_STAGE(bufoff, gbase, voff) do { _Pragma("unroll") for (int _i = 0; _i < 2; ++_i) \
;         __builtin_amdgcn_global_load_lds((const unsigned*)((const char*)(gbase) + (voff)[_i]), (LAS unsigned*)(lds + (bufoff) + ldsw + _i * 8192), 16, 0, 0); } while (0)
; #define PG8_LDA(dst, b, h) do { _Pragma("unroll") for (int m = 0; m < 4; ++m) _Pragma("unroll") for (int k = 0; k < 2; ++k) dst[m][k] = *(const LAS bf16x8*)(lds + PG8_SA(b, h) + aoff + m * 2048 + k * 1024); } while (0)
; #define PG8_MMA(ai, bj, At, Bt) do { __builtin_amdgcn_s_setprio(1); _Pragma("unroll") for (int m = 0; m < 4; ++m) _Pragma("unroll") for (int n = 0; n < 2; ++n) _Pragma("unroll") for (int k = 0; k < 2; ++k) \
;         acc[ai][bj][m][n] = __builtin_amdgcn_mfma_f32_16x16x32_bf16(Bt[n][k], At[m][k], acc[ai][bj][m][n], 0, 0, 0); __builtin_amdgcn_s_setprio(0); } while (0)
; #define PG8_WAIT_V(n) asm volatile("s_waitcnt vmcnt(" #n ")" ::: "memory")
; #define PG8_WAIT_L(n) asm volatile("s_waitcnt lgkmcnt(" #n ")" ::: "memory")
; #define PG8_BAR __builtin_amdgcn_s_barrier()
; #define PG8_SCHED __builtin_amdgcn_sched_barrier(0)
; template <class Epi, class Sched, bool ALIGN_EPI = false, bool SP2 = false>
; __device__ __forceinline__ void gemm_phase(LAS unsigned char* lds, const Gemm g, const Sched& S, const Epi& E) {
;     ...
;             PG8_LDA(At, 1, 1); PG8_STAGE(PG8_SB(1, 0), b3, voffB); PG8_STAGE(PG8_SB(1, 1), b3 + hstepB, voffB); PG8_STAGE(PG8_SA(1, 0), a3, voffA);
;             PG8_WAIT_V(8); PG8_WAIT_L(0); PG8_BAR; PG8_MMA(1, 0, At, B0); PG8_MMA(1, 1, At, B1); PG8_BAR; PG8_SCHED;
;     ...
;         if constexpr (ALIGN_EPI) { if (wr == 0) PG8_BAR; }
;         if constexpr (!Epi::AFTER_DRAIN) { E(acc, cur, wr, wc, fr, fq); S.done(cur); }
;         if (!has_next) break;
	s_mov_b32 m0, s40
	v_lshl_add_u64 v[204:205], v[204:205], 0, s[14:15]
	s_add_u32 s18, s18, 0x80080
	ds_read_b128 v[172:175], v137 offset:49152
	ds_read_b128 v[176:179], v137 offset:50176
	ds_read_b128 v[180:183], v137 offset:51200
	ds_read_b128 v[184:187], v137 offset:52224
	ds_read_b128 v[188:191], v137 offset:53248
	ds_read_b128 v[192:195], v137 offset:54272
	ds_read_b128 v[196:199], v137 offset:55296
	ds_read_b128 v[200:203], v137 offset:56320
	global_load_lds_dwordx4 v[204:205], off
	v_lshl_add_u64 v[204:205], v[206:207], 0, s[14:15]
	s_mov_b32 m0, s41
	s_addc_u32 s19, s19, 0
	global_load_lds_dwordx4 v[204:205], off
	v_lshl_add_u64 v[204:205], s[18:19], 0, v[132:133]
	s_mov_b32 m0, s42
	s_nop 0
	global_load_lds_dwordx4 v[204:205], off
	v_lshl_add_u64 v[204:205], s[18:19], 0, v[130:131]
	s_mov_b32 m0, s43
	s_nop 0
	global_load_lds_dwordx4 v[204:205], off
	v_lshl_add_u64 v[204:205], v[208:209], 0, s[14:15]
	s_mov_b32 m0, s30
	s_nop 0
	global_load_lds_dwordx4 v[204:205], off
	v_lshl_add_u64 v[204:205], v[210:211], 0, s[14:15]
	s_mov_b32 m0, s31
	s_nop 0
	global_load_lds_dwordx4 v[204:205], off
	s_waitcnt vmcnt(8)
	s_waitcnt lgkmcnt(0)
	s_barrier
	s_waitcnt lgkmcnt(0)
	v_mfma_f32_16x16x32_bf16 v[110:113], v[140:143], v[172:175], v[110:113]
	v_mfma_f32_16x16x32_bf16 v[78:81], v[148:151], v[172:175], v[78:81]
	v_mfma_f32_16x16x32_bf16 v[106:109], v[140:143], v[180:183], v[106:109]
	v_mfma_f32_16x16x32_bf16 v[74:77], v[148:151], v[180:183], v[74:77]
	v_mfma_f32_16x16x32_bf16 v[102:105], v[140:143], v[188:191], v[102:105]
	v_mfma_f32_16x16x32_bf16 v[66:69], v[148:151], v[188:191], v[66:69]
	v_mfma_f32_16x16x32_bf16 v[98:101], v[140:143], v[196:199], v[98:101]
	v_mfma_f32_16x16x32_bf16 v[58:61], v[148:151], v[196:199], v[58:61]
	v_mfma_f32_16x16x32_bf16 v[110:113], v[144:147], v[176:179], v[110:113]
	v_mfma_f32_16x16x32_bf16 v[78:81], v[152:155], v[176:179], v[78:81]
	v_mfma_f32_16x16x32_bf16 v[106:109], v[144:147], v[184:187], v[106:109]
	v_mfma_f32_16x16x32_bf16 v[74:77], v[152:155], v[184:187], v[74:77]
	v_mfma_f32_16x16x32_bf16 v[102:105], v[144:147], v[192:195], v[102:105]
	v_mfma_f32_16x16x32_bf16 v[66:69], v[152:155], v[192:195], v[66:69]
	v_mfma_f32_16x16x32_bf16 v[98:101], v[144:147], v[200:203], v[98:101]
	v_mfma_f32_16x16x32_bf16 v[58:61], v[152:155], v[200:203], v[58:61]
	v_mfma_f32_16x16x32_bf16 v[46:49], v[156:159], v[172:175], v[46:49]
	v_mfma_f32_16x16x32_bf16 v[14:17], v[164:167], v[172:175], v[14:17]
	v_mfma_f32_16x16x32_bf16 v[38:41], v[156:159], v[180:183], v[38:41]
	v_mfma_f32_16x16x32_bf16 v[10:13], v[164:167], v[180:183], v[10:13]
	v_mfma_f32_16x16x32_bf16 v[30:33], v[156:159], v[188:191], v[30:33]
	v_mfma_f32_16x16x32_bf16 v[6:9], v[164:167], v[188:191], v[6:9]
	v_mfma_f32_16x16x32_bf16 v[22:25], v[156:159], v[196:199], v[22:25]
	v_mfma_f32_16x16x32_bf16 v[2:5], v[164:167], v[196:199], v[2:5]
	v_mfma_f32_16x16x32_bf16 v[46:49], v[160:163], v[176:179], v[46:49]
	v_mfma_f32_16x16x32_bf16 v[14:17], v[168:171], v[176:179], v[14:17]
	v_mfma_f32_16x16x32_bf16 v[38:41], v[160:163], v[184:187], v[38:41]
	v_mfma_f32_16x16x32_bf16 v[10:13], v[168:171], v[184:187], v[10:13]
	v_mfma_f32_16x16x32_bf16 v[30:33], v[160:163], v[192:195], v[30:33]
	v_mfma_f32_16x16x32_bf16 v[6:9], v[168:171], v[192:195], v[6:9]
	v_mfma_f32_16x16x32_bf16 v[22:25], v[160:163], v[200:203], v[22:25]
	v_mfma_f32_16x16x32_bf16 v[2:5], v[168:171], v[200:203], v[2:5]
	s_barrier
	s_cmp_ge_u32 s16, s29
	s_mov_b32 s18, s16
	s_cbranch_scc0 .LBB0_1225
	v_readlane_b32 s30, v252, 2
	v_readlane_b32 s34, v252, 37
	s_cmpk_lt_u32 s22, 0x100
	v_readlane_b32 s31, v252, 3
	v_readlane_b32 s35, v252, 38
	s_cbranch_scc0 .LBB0_1228
	s_barrier

;     __device__ bool next(int i, Unit& u) const { if (i != 0 || c >= 128) return false; const int t = c >> 2; u.pm = t & 3; u.pn = t >> 2; u.koff = koff_bytes; u.q = c & 3; return true; }
; #define PG8_STAGE(bufoff, gbase, voff) do { _Pragma("unroll") for (int _i = 0; _i < 2; ++_i) \
;         __builtin_amdgcn_global_load_lds((const unsigned*)((const char*)(gbase) + (voff)[_i]), (LAS unsigned*)(lds + (bufoff) + ldsw + _i * 8192), 16, 0, 0); } while (0)
; #define PG8_LDA(dst, b, h) do { _Pragma("unroll") for (int m = 0; m < 4; ++m) _Pragma("unroll") for (int k = 0; k < 2; ++k) dst[m][k] = *(const LAS bf16x8*)(lds + PG8_SA(b, h) + aoff + m * 2048 + k * 1024); } while (0)
; #define PG8_LDB(dst, b, h) do { _Pragma("unroll") for (int n = 0; n < 2; ++n) _Pragma("unroll") for (int k = 0; k < 2; ++k) dst[n][k] = *(const LAS bf16x8*)(lds + PG8_SB(b, h) + boff + n * 2048 + k * 1024); } while (0)
; #define PG8_WAIT_V(n) asm volatile("s_waitcnt vmcnt(" #n ")" ::: "memory")
; #define PG8_WAIT_L(n) asm volatile("s_waitcnt lgkmcnt(" #n ")" ::: "memory")
; #define PG8_BAR __builtin_amdgcn_s_barrier()
; template <class Epi, class Sched, bool ALIGN_EPI = false, bool SP2 = false>
; __device__ __forceinline__ void gemm_phase(LAS unsigned char* lds, const Gemm g, const Sched& S, const Epi& E) {
;     ...
;         const bool has_next = S.next(ui + 1, nxt);
;         const char* nA = has_next ? (const char*)g.A + (size_t)nxt.pm * tstep + nxt.koff : cA; const char* nB = has_next ? (const char*)g.Bt + (size_t)nxt.pn * tstep + nxt.koff : cB;
;         for (int t = 0; t < nt; t += 2) {
;             const bool last = (t == nt - 2);
;             const char* a1 = cA + (size_t)(t + 1) * kstep;
;             const char* a2 = last ? nA : cA + (size_t)(t + 2) * kstep; const char* b2 = last ? nB : cB + (size_t)(t + 2) * kstep;
;             const char* a3 = a2 + kstep; const char* b3 = b2 + kstep;
;             if (last && has_next) S.a_ready(nxt);
;             if constexpr (SP2) {
;             PG8_LDB(B0, 0, 0); PG8_LDB(B1, 0, 1); PG8_SCHED; PG8_LDA(At, 0, 0); PG8_STAGE(PG8_SA(1, 1), a1 + hstep, voffA);
;             PG8_WAIT_V(8); PG8_WAIT_L(0); PG8_BAR; PG8_MMA(0, 0, At, B0); PG8_MMA(0, 1, At, B1); PG8_BAR; PG8_SCHED;
;             PG8_LDA(At, 0, 1); PG8_STAGE(PG8_SB(0, 0), b2, voffB); PG8_STAGE(PG8_SB(0, 1), b2 + hstepB, voffB); PG8_STAGE(PG8_SA(0, 0), a2, voffA);
.LBB0_1249:
	s_ashr_i32 s19, s18, 31
	s_lshl_b64 s[20:21], s[18:19], 20
	v_readlane_b32 s0, v252, 25
	s_add_u32 s20, s0, s20
	v_readlane_b32 s0, v252, 26
	s_addc_u32 s21, s0, s21
	s_and_b64 s[22:23], s[44:45], exec
	s_cselect_b32 s0, s21, s17
	s_cselect_b32 s3, s20, s16
	s_ashr_i32 s15, s14, 31
	s_lshl_b64 s[22:23], s[14:15], 20
	s_add_u32 s22, s26, s22
	s_addc_u32 s23, s27, s23
	s_and_b64 s[24:25], s[44:45], exec
	s_cselect_b32 s15, s23, s49
	s_cselect_b32 s19, s22, s48
	s_add_u32 s16, s16, 0x80080
	s_addc_u32 s17, s17, 0
	s_add_u32 s24, s48, 0x100
	s_addc_u32 s25, s49, 0
	s_mov_b32 s47, -2
	s_waitcnt vmcnt(0)
	ds_read_b128 v[50:53], v196
	ds_read_b128 v[54:57], v196 offset:1024
	ds_read_b128 v[138:141], v196 offset:2048
	ds_read_b128 v[142:145], v196 offset:3072
	ds_read_b128 v[146:149], v197
	ds_read_b128 v[150:153], v197 offset:1024
	ds_read_b128 v[174:177], v197 offset:2048
	ds_read_b128 v[178:181], v197 offset:3072
	s_add_u32 s48, s16, 0xfff80080
	s_addc_u32 s49, s17, -1
	s_cmp_eq_u32 s47, 28
	s_cselect_b32 s51, s0, s49
	s_cselect_b32 s50, s3, s48
	s_cselect_b32 s49, s15, s25
	s_cselect_b32 s48, s19, s24
	v_lshl_add_u64 v[190:191], s[16:17], 0, v[166:167]
	s_add_i32 m0, s29, 0xc000
	ds_read_b128 v[182:185], v198
	ds_read_b128 v[186:189], v198 offset:1024
	ds_read_b128 v[202:205], v198 offset:2048
	ds_read_b128 v[206:209], v198 offset:3072
	ds_read_b128 v[210:213], v198 offset:4096
	ds_read_b128 v[214:217], v198 offset:5120
	ds_read_b128 v[218:221], v198 offset:6144
	ds_read_b128 v[222:225], v198 offset:7168
	global_load_lds_dwordx4 v[190:191], off
	v_lshl_add_u64 v[190:191], s[16:17], 0, v[168:169]
	s_add_i32 m0, s29, 0xe000
	s_nop 0
	global_load_lds_dwordx4 v[190:191], off
	s_waitcnt lgkmcnt(0)
	s_barrier
	s_waitcnt lgkmcnt(0)
	v_mfma_f32_16x16x32_bf16 v[134:137], v[50:53], v[182:185], 0
	v_mfma_f32_16x16x32_bf16 v[130:133], v[138:141], v[182:185], 0
	v_mfma_f32_16x16x32_bf16 v[118:121], v[50:53], v[202:205], 0
	v_mfma_f32_16x16x32_bf16 v[114:117], v[138:141], v[202:205], 0
	v_mfma_f32_16x16x32_bf16 v[102:105], v[50:53], v[210:213], 0
	v_mfma_f32_16x16x32_bf16 v[98:101], v[138:141], v[210:213], 0
	v_mfma_f32_16x16x32_bf16 v[86:89], v[50:53], v[218:221], 0
	v_mfma_f32_16x16x32_bf16 v[82:85], v[138:141], v[218:221], 0
	v_mfma_f32_16x16x32_bf16 v[134:137], v[54:57], v[186:189], v[134:137]
	v_mfma_f32_16x16x32_bf16 v[130:133], v[142:145], v[186:189], v[130:133]
	v_mfma_f32_16x16x32_bf16 v[118:121], v[54:57], v[206:209], v[118:121]
	v_mfma_f32_16x16x32_bf16 v[114:117], v[142:145], v[206:209], v[114:117]
	v_mfma_f32_16x16x32_bf16 v[102:105], v[54:57], v[214:217], v[102:105]
	v_mfma_f32_16x16x32_bf16 v[98:101], v[142:145], v[214:217], v[98:101]
	v_mfma_f32_16x16x32_bf16 v[86:89], v[54:57], v[222:225], v[86:89]
	v_mfma_f32_16x16x32_bf16 v[82:85], v[142:145], v[222:225], v[82:85]
	v_mfma_f32_16x16x32_bf16 v[126:129], v[146:149], v[182:185], 0
	v_mfma_f32_16x16x32_bf16 v[122:125], v[174:177], v[182:185], 0
	v_mfma_f32_16x16x32_bf16 v[110:113], v[146:149], v[202:205], 0
	v_mfma_f32_16x16x32_bf16 v[106:109], v[174:177], v[202:205], 0
	v_mfma_f32_16x16x32_bf16 v[94:97], v[146:149], v[210:213], 0
	v_mfma_f32_16x16x32_bf16 v[90:93], v[174:177], v[210:213], 0
	v_mfma_f32_16x16x32_bf16 v[78:81], v[146:149], v[218:221], 0
	v_mfma_f32_16x16x32_bf16 v[74:77], v[174:177], v[218:221], 0
	v_mfma_f32_16x16x32_bf16 v[126:129], v[150:153], v[186:189], v[126:129]
	v_mfma_f32_16x16x32_bf16 v[122:125], v[178:181], v[186:189], v[122:125]
	v_mfma_f32_16x16x32_bf16 v[110:113], v[150:153], v[206:209], v[110:113]
	v_mfma_f32_16x16x32_bf16 v[106:109], v[178:181], v[206:209], v[106:109]
	v_mfma_f32_16x16x32_bf16 v[94:97], v[150:153], v[214:217], v[94:97]
	v_mfma_f32_16x16x32_bf16 v[90:93], v[178:181], v[214:217], v[90:93]
	v_mfma_f32_16x16x32_bf16 v[78:81], v[150:153], v[222:225], v[78:81]
	v_mfma_f32_16x16x32_bf16 v[74:77], v[178:181], v[222:225], v[74:77]
	s_barrier
	s_add_i32 s58, s56, s28
	v_lshl_add_u64 v[190:191], s[48:49], 0, v[156:157]
	s_mov_b32 m0, s58
	ds_read_b128 v[182:185], v198 offset:16384
	ds_read_b128 v[186:189], v198 offset:17408
	ds_read_b128 v[202:205], v198 offset:18432
	ds_read_b128 v[206:209], v198 offset:19456
	ds_read_b128 v[210:213], v198 offset:20480
	ds_read_b128 v[214:217], v198 offset:21504
	ds_read_b128 v[218:221], v198 offset:22528
	ds_read_b128 v[222:225], v198 offset:23552
	global_load_lds_dwordx4 v[190:191], off
	s_add_i32 m0, s58, 0x2000
	s_add_u32 s58, s48, 0x20000
	v_lshl_add_u64 v[226:227], s[48:49], 0, v[160:161]
	s_addc_u32 s59, s49, 0
	s_add_i32 s60, s57, s28
	global_load_lds_dwordx4 v[226:227], off
	v_lshl_add_u64 v[228:229], s[58:59], 0, v[156:157]
	s_mov_b32 m0, s60
	v_lshl_add_u64 v[230:231], s[50:51], 0, v[158:159]
	global_load_lds_dwordx4 v[228:229], off
	v_lshl_add_u64 v[228:229], s[58:59], 0, v[160:161]
	s_add_i32 m0, s60, 0x2000
	s_nop 0
	global_load_lds_dwordx4 v[228:229], off
	v_lshl_add_u64 v[228:229], s[50:51], 0, v[154:155]
	s_mov_b32 m0, s29
	s_nop 0
	global_load_lds_dwordx4 v[228:229], off
	s_mov_b32 m0, s30
	s_nop 0
	global_load_lds_dwordx4 v[230:231], off
	s_waitcnt lgkmcnt(0)
	s_barrier
; #define PG8_STAGE(bufoff, gbase, voff) do { _Pragma("unroll") for (int _i = 0; _i < 2; ++_i) \
;         __builtin_amdgcn_global_load_lds((const unsigned*)((const char*)(gbase) + (voff)[_i]), (LAS unsigned*)(lds + (bufoff) + ldsw + _i * 8192), 16, 0, 0); } while (0)
; #define PG8_LDA(dst, b, h) do { _Pragma("unroll") for (int m = 0; m < 4; ++m) _Pragma("unroll") for (int k = 0; k < 2; ++k) dst[m][k] = *(const LAS bf16x8*)(lds + PG8_SA(b, h) + aoff + m * 2048 + k * 1024); } while (0)
; #define PG8_LDB(dst, b, h) do { _Pragma("unroll") for (int n = 0; n < 2; ++n) _Pragma("unroll") for (int k = 0; k < 2; ++k) dst[n][k] = *(const LAS bf16x8*)(lds + PG8_SB(b, h) + boff + n * 2048 + k * 1024); } while (0)
; #define PG8_MMA(ai, bj, At, Bt) do { __builtin_amdgcn_s_setprio(1); _Pragma("unroll") for (int m = 0; m < 4; ++m) _Pragma("unroll") for (int n = 0; n < 2; ++n) _Pragma("unroll") for (int k = 0; k < 2; ++k) \
;         acc[ai][bj][m][n] = __builtin_amdgcn_mfma_f32_16x16x32_bf16(Bt[n][k], At[m][k], acc[ai][bj][m][n], 0, 0, 0); __builtin_amdgcn_s_setprio(0); } while (0)
; #define PG8_WAIT_V(n) asm volatile("s_waitcnt vmcnt(" #n ")" ::: "memory")
; #define PG8_WAIT_L(n) asm volatile("s_waitcnt lgkmcnt(" #n ")" ::: "memory")
; #define PG8_BAR __builtin_amdgcn_s_barrier()
; #define PG8_SCHED __builtin_amdgcn_sched_barrier(0)
; template <class Epi, class Sched, bool ALIGN_EPI = false, bool SP2 = false>
; __device__ __forceinline__ void gemm_phase(LAS unsigned char* lds, const Gemm g, const Sched& S, const Epi& E) {
;     ...
;             PG8_WAIT_V(8); PG8_WAIT_L(0); PG8_BAR; PG8_MMA(1, 0, At, B0); PG8_MMA(1, 1, At, B1); PG8_BAR; PG8_SCHED;
;             PG8_LDB(B0, 1, 0); PG8_LDB(B1, 1, 1); PG8_SCHED; PG8_LDA(At, 1, 0); PG8_STAGE(PG8_SA(0, 1), a2 + hstep, voffA);
;             PG8_WAIT_V(8); PG8_WAIT_L(0); PG8_BAR; PG8_MMA(0, 0, At, B0); PG8_MMA(0, 1, At, B1); PG8_BAR; PG8_SCHED;
	s_waitcnt lgkmcnt(0)
	v_mfma_f32_16x16x32_bf16 v[70:73], v[50:53], v[182:185], 0
	v_mfma_f32_16x16x32_bf16 v[66:69], v[138:141], v[182:185], 0
	v_mfma_f32_16x16x32_bf16 v[46:49], v[50:53], v[202:205], 0
	v_mfma_f32_16x16x32_bf16 v[42:45], v[138:141], v[202:205], 0
	v_mfma_f32_16x16x32_bf16 v[30:33], v[50:53], v[210:213], 0
	v_mfma_f32_16x16x32_bf16 v[26:29], v[138:141], v[210:213], 0
	v_mfma_f32_16x16x32_bf16 v[14:17], v[50:53], v[218:221], 0
	v_mfma_f32_16x16x32_bf16 v[10:13], v[138:141], v[218:221], 0
	v_mfma_f32_16x16x32_bf16 v[70:73], v[54:57], v[186:189], v[70:73]
	v_mfma_f32_16x16x32_bf16 v[66:69], v[142:145], v[186:189], v[66:69]
	v_mfma_f32_16x16x32_bf16 v[46:49], v[54:57], v[206:209], v[46:49]
	v_mfma_f32_16x16x32_bf16 v[42:45], v[142:145], v[206:209], v[42:45]
	v_mfma_f32_16x16x32_bf16 v[30:33], v[54:57], v[214:217], v[30:33]
	v_mfma_f32_16x16x32_bf16 v[26:29], v[142:145], v[214:217], v[26:29]
	v_mfma_f32_16x16x32_bf16 v[14:17], v[54:57], v[222:225], v[14:17]
	v_mfma_f32_16x16x32_bf16 v[10:13], v[142:145], v[222:225], v[10:13]
	v_mfma_f32_16x16x32_bf16 v[38:41], v[146:149], v[202:205], 0
	v_mfma_f32_16x16x32_bf16 v[34:37], v[174:177], v[202:205], 0
	v_mfma_f32_16x16x32_bf16 v[22:25], v[146:149], v[210:213], 0
	v_mfma_f32_16x16x32_bf16 v[18:21], v[174:177], v[210:213], 0
	v_mfma_f32_16x16x32_bf16 v[6:9], v[146:149], v[218:221], 0
	v_mfma_f32_16x16x32_bf16 v[2:5], v[174:177], v[218:221], 0
	v_mfma_f32_16x16x32_bf16 v[50:53], v[146:149], v[182:185], 0
	v_mfma_f32_16x16x32_bf16 v[54:57], v[174:177], v[182:185], 0
	v_mfma_f32_16x16x32_bf16 v[38:41], v[150:153], v[206:209], v[38:41]
	v_mfma_f32_16x16x32_bf16 v[34:37], v[178:181], v[206:209], v[34:37]
	v_mfma_f32_16x16x32_bf16 v[22:25], v[150:153], v[214:217], v[22:25]
	v_mfma_f32_16x16x32_bf16 v[18:21], v[178:181], v[214:217], v[18:21]
	v_mfma_f32_16x16x32_bf16 v[6:9], v[150:153], v[222:225], v[6:9]
	v_mfma_f32_16x16x32_bf16 v[2:5], v[178:181], v[222:225], v[2:5]
	v_mfma_f32_16x16x32_bf16 v[50:53], v[150:153], v[186:189], v[50:53]
	v_mfma_f32_16x16x32_bf16 v[54:57], v[178:181], v[186:189], v[54:57]
	s_barrier
	s_add_i32 s58, 0, 0x18000
	s_add_i32 s59, 0, 0x1c000
	v_add_u32_e32 v142, s58, v1
	v_add_u32_e32 v162, s59, v1
	ds_read_b128 v[58:61], v142
	ds_read_b128 v[62:65], v142 offset:1024
	ds_read_b128 v[138:141], v142 offset:2048
	ds_read_b128 v[142:145], v142 offset:3072
	ds_read_b128 v[146:149], v162
	ds_read_b128 v[150:153], v162 offset:1024
	ds_read_b128 v[174:177], v162 offset:2048
	ds_read_b128 v[178:181], v162 offset:3072
	s_add_u32 s50, s50, 0x80000
	s_addc_u32 s51, s51, 0
	s_mov_b32 m0, s31
	v_lshl_add_u64 v[232:233], s[50:51], 0, v[154:155]
	ds_read_b128 v[182:185], v198 offset:32768
	ds_read_b128 v[186:189], v198 offset:33792
	ds_read_b128 v[202:205], v198 offset:34816
	ds_read_b128 v[206:209], v198 offset:35840
	ds_read_b128 v[210:213], v198 offset:36864
	ds_read_b128 v[214:217], v198 offset:37888
	ds_read_b128 v[218:221], v198 offset:38912
	ds_read_b128 v[222:225], v198 offset:39936
	global_load_lds_dwordx4 v[232:233], off
	v_lshl_add_u64 v[232:233], s[50:51], 0, v[158:159]
	s_mov_b32 m0, s33
	s_nop 0
	global_load_lds_dwordx4 v[232:233], off
	s_waitcnt vmcnt(8)
	s_waitcnt lgkmcnt(0)
	s_barrier
	s_waitcnt lgkmcnt(0)
	v_mfma_f32_16x16x32_bf16 v[134:137], v[58:61], v[182:185], v[134:137]
	v_mfma_f32_16x16x32_bf16 v[130:133], v[138:141], v[182:185], v[130:133]
	v_mfma_f32_16x16x32_bf16 v[118:121], v[58:61], v[202:205], v[118:121]
	v_mfma_f32_16x16x32_bf16 v[114:117], v[138:141], v[202:205], v[114:117]
	v_mfma_f32_16x16x32_bf16 v[102:105], v[58:61], v[210:213], v[102:105]
	v_mfma_f32_16x16x32_bf16 v[98:101], v[138:141], v[210:213], v[98:101]
	v_mfma_f32_16x16x32_bf16 v[86:89], v[58:61], v[218:221], v[86:89]
	v_mfma_f32_16x16x32_bf16 v[82:85], v[138:141], v[218:221], v[82:85]
	v_mfma_f32_16x16x32_bf16 v[134:137], v[62:65], v[186:189], v[134:137]
	v_mfma_f32_16x16x32_bf16 v[130:133], v[142:145], v[186:189], v[130:133]
	v_mfma_f32_16x16x32_bf16 v[118:121], v[62:65], v[206:209], v[118:121]
	v_mfma_f32_16x16x32_bf16 v[114:117], v[142:145], v[206:209], v[114:117]
	v_mfma_f32_16x16x32_bf16 v[102:105], v[62:65], v[214:217], v[102:105]
	v_mfma_f32_16x16x32_bf16 v[98:101], v[142:145], v[214:217], v[98:101]
	v_mfma_f32_16x16x32_bf16 v[86:89], v[62:65], v[222:225], v[86:89]
	v_mfma_f32_16x16x32_bf16 v[82:85], v[142:145], v[222:225], v[82:85]
	v_mfma_f32_16x16x32_bf16 v[126:129], v[146:149], v[182:185], v[126:129]
	v_mfma_f32_16x16x32_bf16 v[122:125], v[174:177], v[182:185], v[122:125]
	v_mfma_f32_16x16x32_bf16 v[110:113], v[146:149], v[202:205], v[110:113]
	v_mfma_f32_16x16x32_bf16 v[106:109], v[174:177], v[202:205], v[106:109]
	v_mfma_f32_16x16x32_bf16 v[94:97], v[146:149], v[210:213], v[94:97]
	v_mfma_f32_16x16x32_bf16 v[90:93], v[174:177], v[210:213], v[90:93]
	v_mfma_f32_16x16x32_bf16 v[78:81], v[146:149], v[218:221], v[78:81]
	v_mfma_f32_16x16x32_bf16 v[74:77], v[174:177], v[218:221], v[74:77]
	v_mfma_f32_16x16x32_bf16 v[126:129], v[150:153], v[186:189], v[126:129]
	v_mfma_f32_16x16x32_bf16 v[122:125], v[178:181], v[186:189], v[122:125]
	v_mfma_f32_16x16x32_bf16 v[110:113], v[150:153], v[206:209], v[110:113]
	v_mfma_f32_16x16x32_bf16 v[106:109], v[178:181], v[206:209], v[106:109]
	v_mfma_f32_16x16x32_bf16 v[94:97], v[150:153], v[214:217], v[94:97]
	v_mfma_f32_16x16x32_bf16 v[90:93], v[178:181], v[214:217], v[90:93]
	v_mfma_f32_16x16x32_bf16 v[78:81], v[150:153], v[222:225], v[78:81]
	v_mfma_f32_16x16x32_bf16 v[74:77], v[178:181], v[222:225], v[74:77]
	s_barrier
; #define PG8_STAGE(bufoff, gbase, voff) do { _Pragma("unroll") for (int _i = 0; _i < 2; ++_i) \
;         __builtin_amdgcn_global_load_lds((const unsigned*)((const char*)(gbase) + (voff)[_i]), (LAS unsigned*)(lds + (bufoff) + ldsw + _i * 8192), 16, 0, 0); } while (0)
; #define PG8_LDA(dst, b, h) do { _Pragma("unroll") for (int m = 0; m < 4; ++m) _Pragma("unroll") for (int k = 0; k < 2; ++k) dst[m][k] = *(const LAS bf16x8*)(lds + PG8_SA(b, h) + aoff + m * 2048 + k * 1024); } while (0)
; #define PG8_LDB(dst, b, h) do { _Pragma("unroll") for (int n = 0; n < 2; ++n) _Pragma("unroll") for (int k = 0; k < 2; ++k) dst[n][k] = *(const LAS bf16x8*)(lds + PG8_SB(b, h) + boff + n * 2048 + k * 1024); } while (0)
; #define PG8_MMA(ai, bj, At, Bt) do { __builtin_amdgcn_s_setprio(1); _Pragma("unroll") for (int m = 0; m < 4; ++m) _Pragma("unroll") for (int n = 0; n < 2; ++n) _Pragma("unroll") for (int k = 0; k < 2; ++k) \
;         acc[ai][bj][m][n] = __builtin_amdgcn_mfma_f32_16x16x32_bf16(Bt[n][k], At[m][k], acc[ai][bj][m][n], 0, 0, 0); __builtin_amdgcn_s_setprio(0); } while (0)
; #define PG8_WAIT_V(n) asm volatile("s_waitcnt vmcnt(" #n ")" ::: "memory")
; #define PG8_WAIT_L(n) asm volatile("s_waitcnt lgkmcnt(" #n ")" ::: "memory")
; #define PG8_BAR __builtin_amdgcn_s_barrier()
; #define PG8_SCHED __builtin_amdgcn_sched_barrier(0)
; template <class Epi, class Sched, bool ALIGN_EPI = false, bool SP2 = false>
; __device__ __forceinline__ void gemm_phase(LAS unsigned char* lds, const Gemm g, const Sched& S, const Epi& E) {
;     ...
;             PG8_LDB(B0, 0, 0); PG8_LDB(B1, 0, 1); PG8_SCHED; PG8_LDA(At, 0, 0); PG8_STAGE(PG8_SA(1, 1), a1 + hstep, voffA);
;             PG8_WAIT_V(8); PG8_WAIT_L(0); PG8_BAR; PG8_MMA(0, 0, At, B0); PG8_MMA(0, 1, At, B1); PG8_BAR; PG8_SCHED;
;     ...
;             PG8_LDA(At, 1, 1); PG8_STAGE(PG8_SB(1, 0), b3, voffB); PG8_STAGE(PG8_SB(1, 1), b3 + hstepB, voffB); PG8_STAGE(PG8_SA(1, 0), a3, voffA);
;             PG8_WAIT_V(8); PG8_WAIT_L(0); PG8_BAR; PG8_MMA(1, 0, At, B0); PG8_MMA(1, 1, At, B1); PG8_BAR; PG8_SCHED;
	s_add_i32 s50, s58, s28
	v_lshl_add_u64 v[190:191], v[190:191], 0, s[10:11]
	s_mov_b32 m0, s50
	ds_read_b128 v[182:185], v198 offset:49152
	ds_read_b128 v[186:189], v198 offset:50176
	ds_read_b128 v[202:205], v198 offset:51200
	ds_read_b128 v[206:209], v198 offset:52224
	ds_read_b128 v[210:213], v198 offset:53248
	ds_read_b128 v[214:217], v198 offset:54272
	ds_read_b128 v[218:221], v198 offset:55296
	ds_read_b128 v[222:225], v198 offset:56320
	global_load_lds_dwordx4 v[190:191], off
	s_add_i32 m0, s50, 0x2000
	s_add_u32 s48, s48, 0x20080
	v_lshl_add_u64 v[190:191], v[226:227], 0, s[10:11]
	s_addc_u32 s49, s49, 0
	s_add_i32 s50, s59, s28
	global_load_lds_dwordx4 v[190:191], off
	v_lshl_add_u64 v[190:191], s[48:49], 0, v[156:157]
	s_mov_b32 m0, s50
	s_nop 0
	global_load_lds_dwordx4 v[190:191], off
	v_lshl_add_u64 v[190:191], s[48:49], 0, v[160:161]
	s_add_i32 m0, s50, 0x2000
	s_nop 0
	global_load_lds_dwordx4 v[190:191], off
	v_lshl_add_u64 v[190:191], v[228:229], 0, s[10:11]
	s_mov_b32 m0, s53
	s_nop 0
	global_load_lds_dwordx4 v[190:191], off
	v_lshl_add_u64 v[190:191], v[230:231], 0, s[10:11]
	s_mov_b32 m0, s54
	s_nop 0
	global_load_lds_dwordx4 v[190:191], off
	s_waitcnt vmcnt(8)
	s_waitcnt lgkmcnt(0)
	s_barrier
	s_waitcnt lgkmcnt(0)
	v_mfma_f32_16x16x32_bf16 v[70:73], v[58:61], v[182:185], v[70:73]
	v_mfma_f32_16x16x32_bf16 v[66:69], v[138:141], v[182:185], v[66:69]
	v_mfma_f32_16x16x32_bf16 v[46:49], v[58:61], v[202:205], v[46:49]
	v_mfma_f32_16x16x32_bf16 v[42:45], v[138:141], v[202:205], v[42:45]
	v_mfma_f32_16x16x32_bf16 v[30:33], v[58:61], v[210:213], v[30:33]
	v_mfma_f32_16x16x32_bf16 v[26:29], v[138:141], v[210:213], v[26:29]
	v_mfma_f32_16x16x32_bf16 v[14:17], v[58:61], v[218:221], v[14:17]
	v_mfma_f32_16x16x32_bf16 v[10:13], v[138:141], v[218:221], v[10:13]
	v_mfma_f32_16x16x32_bf16 v[70:73], v[62:65], v[186:189], v[70:73]
	v_mfma_f32_16x16x32_bf16 v[66:69], v[142:145], v[186:189], v[66:69]
	v_mfma_f32_16x16x32_bf16 v[46:49], v[62:65], v[206:209], v[46:49]
	v_mfma_f32_16x16x32_bf16 v[42:45], v[142:145], v[206:209], v[42:45]
	v_mfma_f32_16x16x32_bf16 v[30:33], v[62:65], v[214:217], v[30:33]
	v_mfma_f32_16x16x32_bf16 v[26:29], v[142:145], v[214:217], v[26:29]
	v_mfma_f32_16x16x32_bf16 v[14:17], v[62:65], v[222:225], v[14:17]
	v_mfma_f32_16x16x32_bf16 v[10:13], v[142:145], v[222:225], v[10:13]
	v_mfma_f32_16x16x32_bf16 v[50:53], v[146:149], v[182:185], v[50:53]
	v_mfma_f32_16x16x32_bf16 v[62:65], v[150:153], v[186:189], v[50:53]
	v_mfma_f32_16x16x32_bf16 v[50:53], v[174:177], v[182:185], v[54:57]
	v_mfma_f32_16x16x32_bf16 v[38:41], v[146:149], v[202:205], v[38:41]
	v_mfma_f32_16x16x32_bf16 v[34:37], v[174:177], v[202:205], v[34:37]
	v_mfma_f32_16x16x32_bf16 v[22:25], v[146:149], v[210:213], v[22:25]
	v_mfma_f32_16x16x32_bf16 v[18:21], v[174:177], v[210:213], v[18:21]
	v_mfma_f32_16x16x32_bf16 v[6:9], v[146:149], v[218:221], v[6:9]
	v_mfma_f32_16x16x32_bf16 v[2:5], v[174:177], v[218:221], v[2:5]
	v_mfma_f32_16x16x32_bf16 v[58:61], v[178:181], v[186:189], v[50:53]
	v_mfma_f32_16x16x32_bf16 v[38:41], v[150:153], v[206:209], v[38:41]
	v_mfma_f32_16x16x32_bf16 v[34:37], v[178:181], v[206:209], v[34:37]
	v_mfma_f32_16x16x32_bf16 v[22:25], v[150:153], v[214:217], v[22:25]
	v_mfma_f32_16x16x32_bf16 v[18:21], v[178:181], v[214:217], v[18:21]
	v_mfma_f32_16x16x32_bf16 v[6:9], v[150:153], v[222:225], v[6:9]
	v_mfma_f32_16x16x32_bf16 v[2:5], v[178:181], v[222:225], v[2:5]
	s_barrier
	s_add_i32 s47, s47, 2
	s_add_u32 s16, s16, 0x100
	s_addc_u32 s17, s17, 0
	s_add_u32 s24, s24, 0x100
	s_addc_u32 s25, s25, 0
	s_cmp_gt_u32 s47, 29
.LBB0_1250:
	ds_read_b128 v[50:53], v196
	ds_read_b128 v[54:57], v196 offset:1024
	ds_read_b128 v[138:141], v196 offset:2048
	ds_read_b128 v[142:145], v196 offset:3072
	ds_read_b128 v[146:149], v197
	ds_read_b128 v[150:153], v197 offset:1024
	ds_read_b128 v[174:177], v197 offset:2048
	ds_read_b128 v[178:181], v197 offset:3072
	s_add_u32 s48, s16, 0xfff80080
	s_addc_u32 s49, s17, -1
	s_cmp_eq_u32 s47, 28
	s_cselect_b32 s51, s0, s49
	s_cselect_b32 s50, s3, s48
	s_cselect_b32 s49, s15, s25
	s_cselect_b32 s48, s19, s24
	v_lshl_add_u64 v[190:191], s[16:17], 0, v[166:167]
	s_add_i32 m0, s29, 0xc000
	ds_read_b128 v[182:185], v198
	ds_read_b128 v[186:189], v198 offset:1024
	ds_read_b128 v[202:205], v198 offset:2048
	ds_read_b128 v[206:209], v198 offset:3072
	ds_read_b128 v[210:213], v198 offset:4096
	ds_read_b128 v[214:217], v198 offset:5120
	ds_read_b128 v[218:221], v198 offset:6144
	ds_read_b128 v[222:225], v198 offset:7168
	global_load_lds_dwordx4 v[190:191], off
	v_lshl_add_u64 v[190:191], s[16:17], 0, v[168:169]
	s_add_i32 m0, s29, 0xe000
	s_nop 0
	global_load_lds_dwordx4 v[190:191], off
	s_waitcnt vmcnt(8)
	s_waitcnt lgkmcnt(0)
	s_barrier
; #define PG8_STAGE(bufoff, gbase, voff) do { _Pragma("unroll") for (int _i = 0; _i < 2; ++_i) \
;         __builtin_amdgcn_global_load_lds((const unsigned*)((const char*)(gbase) + (voff)[_i]), (LAS unsigned*)(lds + (bufoff) + ldsw + _i * 8192), 16, 0, 0); } while (0)
; #define PG8_LDA(dst, b, h) do { _Pragma("unroll") for (int m = 0; m < 4; ++m) _Pragma("unroll") for (int k = 0; k < 2; ++k) dst[m][k] = *(const LAS bf16x8*)(lds + PG8_SA(b, h) + aoff + m * 2048 + k * 1024); } while (0)
; #define PG8_LDB(dst, b, h) do { _Pragma("unroll") for (int n = 0; n < 2; ++n) _Pragma("unroll") for (int k = 0; k < 2; ++k) dst[n][k] = *(const LAS bf16x8*)(lds + PG8_SB(b, h) + boff + n * 2048 + k * 1024); } while (0)
; #define PG8_MMA(ai, bj, At, Bt) do { __builtin_amdgcn_s_setprio(1); _Pragma("unroll") for (int m = 0; m < 4; ++m) _Pragma("unroll") for (int n = 0; n < 2; ++n) _Pragma("unroll") for (int k = 0; k < 2; ++k) \
;         acc[ai][bj][m][n] = __builtin_amdgcn_mfma_f32_16x16x32_bf16(Bt[n][k], At[m][k], acc[ai][bj][m][n], 0, 0, 0); __builtin_amdgcn_s_setprio(0); } while (0)
; #define PG8_WAIT_V(n) asm volatile("s_waitcnt vmcnt(" #n ")" ::: "memory")
; #define PG8_WAIT_L(n) asm volatile("s_waitcnt lgkmcnt(" #n ")" ::: "memory")
; #define PG8_BAR __builtin_amdgcn_s_barrier()
; #define PG8_SCHED __builtin_amdgcn_sched_barrier(0)
; template <class Epi, class Sched, bool ALIGN_EPI = false, bool SP2 = false>
; __device__ __forceinline__ void gemm_phase(LAS unsigned char* lds, const Gemm g, const Sched& S, const Epi& E) {
;     ...
;             PG8_WAIT_V(8); PG8_WAIT_L(0); PG8_BAR; PG8_MMA(0, 0, At, B0); PG8_MMA(0, 1, At, B1); PG8_BAR; PG8_SCHED;
;             PG8_LDA(At, 0, 1); PG8_STAGE(PG8_SB(0, 0), b2, voffB); PG8_STAGE(PG8_SB(0, 1), b2 + hstepB, voffB); PG8_STAGE(PG8_SA(0, 0), a2, voffA);
;             PG8_WAIT_V(8); PG8_WAIT_L(0); PG8_BAR; PG8_MMA(1, 0, At, B0); PG8_MMA(1, 1, At, B1); PG8_BAR; PG8_SCHED;
;             PG8_LDB(B0, 1, 0); PG8_LDB(B1, 1, 1); PG8_SCHED; PG8_LDA(At, 1, 0); PG8_STAGE(PG8_SA(0, 1), a2 + hstep, voffA);
;             PG8_WAIT_V(8); PG8_WAIT_L(0); PG8_BAR; PG8_MMA(0, 0, At, B0); PG8_MMA(0, 1, At, B1); PG8_BAR; PG8_SCHED;
	s_waitcnt lgkmcnt(0)
	v_mfma_f32_16x16x32_bf16 v[134:137], v[50:53], v[182:185], v[134:137]
	v_mfma_f32_16x16x32_bf16 v[130:133], v[138:141], v[182:185], v[130:133]
	v_mfma_f32_16x16x32_bf16 v[118:121], v[50:53], v[202:205], v[118:121]
	v_mfma_f32_16x16x32_bf16 v[114:117], v[138:141], v[202:205], v[114:117]
	v_mfma_f32_16x16x32_bf16 v[102:105], v[50:53], v[210:213], v[102:105]
	v_mfma_f32_16x16x32_bf16 v[98:101], v[138:141], v[210:213], v[98:101]
	v_mfma_f32_16x16x32_bf16 v[86:89], v[50:53], v[218:221], v[86:89]
	v_mfma_f32_16x16x32_bf16 v[82:85], v[138:141], v[218:221], v[82:85]
	v_mfma_f32_16x16x32_bf16 v[134:137], v[54:57], v[186:189], v[134:137]
	v_mfma_f32_16x16x32_bf16 v[130:133], v[142:145], v[186:189], v[130:133]
	v_mfma_f32_16x16x32_bf16 v[118:121], v[54:57], v[206:209], v[118:121]
	v_mfma_f32_16x16x32_bf16 v[114:117], v[142:145], v[206:209], v[114:117]
	v_mfma_f32_16x16x32_bf16 v[102:105], v[54:57], v[214:217], v[102:105]
	v_mfma_f32_16x16x32_bf16 v[98:101], v[142:145], v[214:217], v[98:101]
	v_mfma_f32_16x16x32_bf16 v[86:89], v[54:57], v[222:225], v[86:89]
	v_mfma_f32_16x16x32_bf16 v[82:85], v[142:145], v[222:225], v[82:85]
	v_mfma_f32_16x16x32_bf16 v[126:129], v[146:149], v[182:185], v[126:129]
	v_mfma_f32_16x16x32_bf16 v[122:125], v[174:177], v[182:185], v[122:125]
	v_mfma_f32_16x16x32_bf16 v[110:113], v[146:149], v[202:205], v[110:113]
	v_mfma_f32_16x16x32_bf16 v[106:109], v[174:177], v[202:205], v[106:109]
	v_mfma_f32_16x16x32_bf16 v[94:97], v[146:149], v[210:213], v[94:97]
	v_mfma_f32_16x16x32_bf16 v[90:93], v[174:177], v[210:213], v[90:93]
	v_mfma_f32_16x16x32_bf16 v[78:81], v[146:149], v[218:221], v[78:81]
	v_mfma_f32_16x16x32_bf16 v[74:77], v[174:177], v[218:221], v[74:77]
	v_mfma_f32_16x16x32_bf16 v[126:129], v[150:153], v[186:189], v[126:129]
	v_mfma_f32_16x16x32_bf16 v[122:125], v[178:181], v[186:189], v[122:125]
	v_mfma_f32_16x16x32_bf16 v[110:113], v[150:153], v[206:209], v[110:113]
	v_mfma_f32_16x16x32_bf16 v[106:109], v[178:181], v[206:209], v[106:109]
	v_mfma_f32_16x16x32_bf16 v[94:97], v[150:153], v[214:217], v[94:97]
	v_mfma_f32_16x16x32_bf16 v[90:93], v[178:181], v[214:217], v[90:93]
	v_mfma_f32_16x16x32_bf16 v[78:81], v[150:153], v[222:225], v[78:81]
	v_mfma_f32_16x16x32_bf16 v[74:77], v[178:181], v[222:225], v[74:77]
	s_barrier
	s_add_i32 s58, s56, s28
	v_lshl_add_u64 v[190:191], s[48:49], 0, v[156:157]
	s_mov_b32 m0, s58
	ds_read_b128 v[182:185], v198 offset:16384
	ds_read_b128 v[186:189], v198 offset:17408
	ds_read_b128 v[202:205], v198 offset:18432
	ds_read_b128 v[206:209], v198 offset:19456
	ds_read_b128 v[210:213], v198 offset:20480
	ds_read_b128 v[214:217], v198 offset:21504
	ds_read_b128 v[218:221], v198 offset:22528
	ds_read_b128 v[222:225], v198 offset:23552
	global_load_lds_dwordx4 v[190:191], off
	s_add_i32 m0, s58, 0x2000
	s_add_u32 s58, s48, 0x20000
	v_lshl_add_u64 v[226:227], s[48:49], 0, v[160:161]
	s_addc_u32 s59, s49, 0
	s_add_i32 s60, s57, s28
	global_load_lds_dwordx4 v[226:227], off
	v_lshl_add_u64 v[228:229], s[58:59], 0, v[156:157]
	s_mov_b32 m0, s60
	v_lshl_add_u64 v[230:231], s[50:51], 0, v[158:159]
	global_load_lds_dwordx4 v[228:229], off
	v_lshl_add_u64 v[228:229], s[58:59], 0, v[160:161]
	s_add_i32 m0, s60, 0x2000
	s_nop 0
	global_load_lds_dwordx4 v[228:229], off
	v_lshl_add_u64 v[228:229], s[50:51], 0, v[154:155]
	s_mov_b32 m0, s29
	s_nop 0
	global_load_lds_dwordx4 v[228:229], off
	s_mov_b32 m0, s30
	s_nop 0
	global_load_lds_dwordx4 v[230:231], off
	s_waitcnt vmcnt(8)
	s_waitcnt lgkmcnt(0)
	s_barrier
	s_waitcnt lgkmcnt(0)
	v_mfma_f32_16x16x32_bf16 v[70:73], v[50:53], v[182:185], v[70:73]
	v_mfma_f32_16x16x32_bf16 v[66:69], v[138:141], v[182:185], v[66:69]
	v_mfma_f32_16x16x32_bf16 v[46:49], v[50:53], v[202:205], v[46:49]
	v_mfma_f32_16x16x32_bf16 v[42:45], v[138:141], v[202:205], v[42:45]
	v_mfma_f32_16x16x32_bf16 v[30:33], v[50:53], v[210:213], v[30:33]
	v_mfma_f32_16x16x32_bf16 v[26:29], v[138:141], v[210:213], v[26:29]
	v_mfma_f32_16x16x32_bf16 v[14:17], v[50:53], v[218:221], v[14:17]
	v_mfma_f32_16x16x32_bf16 v[10:13], v[138:141], v[218:221], v[10:13]
	v_mfma_f32_16x16x32_bf16 v[70:73], v[54:57], v[186:189], v[70:73]
	v_mfma_f32_16x16x32_bf16 v[66:69], v[142:145], v[186:189], v[66:69]
	v_mfma_f32_16x16x32_bf16 v[46:49], v[54:57], v[206:209], v[46:49]
	v_mfma_f32_16x16x32_bf16 v[42:45], v[142:145], v[206:209], v[42:45]
	v_mfma_f32_16x16x32_bf16 v[30:33], v[54:57], v[214:217], v[30:33]
	v_mfma_f32_16x16x32_bf16 v[26:29], v[142:145], v[214:217], v[26:29]
	v_mfma_f32_16x16x32_bf16 v[14:17], v[54:57], v[222:225], v[14:17]
	v_mfma_f32_16x16x32_bf16 v[10:13], v[142:145], v[222:225], v[10:13]
	v_mfma_f32_16x16x32_bf16 v[38:41], v[146:149], v[202:205], v[38:41]
	v_mfma_f32_16x16x32_bf16 v[34:37], v[174:177], v[202:205], v[34:37]
	v_mfma_f32_16x16x32_bf16 v[22:25], v[146:149], v[210:213], v[22:25]
	v_mfma_f32_16x16x32_bf16 v[18:21], v[174:177], v[210:213], v[18:21]
	v_mfma_f32_16x16x32_bf16 v[6:9], v[146:149], v[218:221], v[6:9]
	v_mfma_f32_16x16x32_bf16 v[2:5], v[174:177], v[218:221], v[2:5]
	v_mfma_f32_16x16x32_bf16 v[50:53], v[146:149], v[182:185], v[62:65]
	v_mfma_f32_16x16x32_bf16 v[54:57], v[174:177], v[182:185], v[58:61]
	v_mfma_f32_16x16x32_bf16 v[38:41], v[150:153], v[206:209], v[38:41]
	v_mfma_f32_16x16x32_bf16 v[34:37], v[178:181], v[206:209], v[34:37]
	v_mfma_f32_16x16x32_bf16 v[22:25], v[150:153], v[214:217], v[22:25]
	v_mfma_f32_16x16x32_bf16 v[18:21], v[178:181], v[214:217], v[18:21]
	v_mfma_f32_16x16x32_bf16 v[6:9], v[150:153], v[222:225], v[6:9]
	v_mfma_f32_16x16x32_bf16 v[2:5], v[178:181], v[222:225], v[2:5]
	v_mfma_f32_16x16x32_bf16 v[50:53], v[150:153], v[186:189], v[50:53]
	v_mfma_f32_16x16x32_bf16 v[54:57], v[178:181], v[186:189], v[54:57]
	s_barrier
; #define PG8_STAGE(bufoff, gbase, voff) do { _Pragma("unroll") for (int _i = 0; _i < 2; ++_i) \
;         __builtin_amdgcn_global_load_lds((const unsigned*)((const char*)(gbase) + (voff)[_i]), (LAS unsigned*)(lds + (bufoff) + ldsw + _i * 8192), 16, 0, 0); } while (0)
; #define PG8_LDA(dst, b, h) do { _Pragma("unroll") for (int m = 0; m < 4; ++m) _Pragma("unroll") for (int k = 0; k < 2; ++k) dst[m][k] = *(const LAS bf16x8*)(lds + PG8_SA(b, h) + aoff + m * 2048 + k * 1024); } while (0)
; #define PG8_LDB(dst, b, h) do { _Pragma("unroll") for (int n = 0; n < 2; ++n) _Pragma("unroll") for (int k = 0; k < 2; ++k) dst[n][k] = *(const LAS bf16x8*)(lds + PG8_SB(b, h) + boff + n * 2048 + k * 1024); } while (0)
; #define PG8_MMA(ai, bj, At, Bt) do { __builtin_amdgcn_s_setprio(1); _Pragma("unroll") for (int m = 0; m < 4; ++m) _Pragma("unroll") for (int n = 0; n < 2; ++n) _Pragma("unroll") for (int k = 0; k < 2; ++k) \
;         acc[ai][bj][m][n] = __builtin_amdgcn_mfma_f32_16x16x32_bf16(Bt[n][k], At[m][k], acc[ai][bj][m][n], 0, 0, 0); __builtin_amdgcn_s_setprio(0); } while (0)
; #define PG8_WAIT_V(n) asm volatile("s_waitcnt vmcnt(" #n ")" ::: "memory")
; #define PG8_WAIT_L(n) asm volatile("s_waitcnt lgkmcnt(" #n ")" ::: "memory")
; #define PG8_BAR __builtin_amdgcn_s_barrier()
; #define PG8_SCHED __builtin_amdgcn_sched_barrier(0)
; template <class Epi, class Sched, bool ALIGN_EPI = false, bool SP2 = false>
; __device__ __forceinline__ void gemm_phase(LAS unsigned char* lds, const Gemm g, const Sched& S, const Epi& E) {
;     ...
;             PG8_LDB(B0, 1, 0); PG8_LDB(B1, 1, 1); PG8_SCHED; PG8_LDA(At, 1, 0); PG8_STAGE(PG8_SA(0, 1), a2 + hstep, voffA);
;             PG8_WAIT_V(8); PG8_WAIT_L(0); PG8_BAR; PG8_MMA(0, 0, At, B0); PG8_MMA(0, 1, At, B1); PG8_BAR; PG8_SCHED;
	s_add_i32 s58, 0, 0x18000
	s_add_i32 s59, 0, 0x1c000
	v_add_u32_e32 v142, s58, v1
	v_add_u32_e32 v162, s59, v1
	ds_read_b128 v[58:61], v142
	ds_read_b128 v[62:65], v142 offset:1024
	ds_read_b128 v[138:141], v142 offset:2048
	ds_read_b128 v[142:145], v142 offset:3072
	ds_read_b128 v[146:149], v162
	ds_read_b128 v[150:153], v162 offset:1024
	ds_read_b128 v[174:177], v162 offset:2048
	ds_read_b128 v[178:181], v162 offset:3072
	s_add_u32 s50, s50, 0x80000
	s_addc_u32 s51, s51, 0
	s_mov_b32 m0, s31
	v_lshl_add_u64 v[232:233], s[50:51], 0, v[154:155]
	ds_read_b128 v[182:185], v198 offset:32768
	ds_read_b128 v[186:189], v198 offset:33792
	ds_read_b128 v[202:205], v198 offset:34816
	ds_read_b128 v[206:209], v198 offset:35840
	ds_read_b128 v[210:213], v198 offset:36864
	ds_read_b128 v[214:217], v198 offset:37888
	ds_read_b128 v[218:221], v198 offset:38912
	ds_read_b128 v[222:225], v198 offset:39936
	global_load_lds_dwordx4 v[232:233], off
	v_lshl_add_u64 v[232:233], s[50:51], 0, v[158:159]
	s_mov_b32 m0, s33
	s_nop 0
	global_load_lds_dwordx4 v[232:233], off
	s_waitcnt vmcnt(8)
	s_waitcnt lgkmcnt(0)
	s_barrier
	s_waitcnt lgkmcnt(0)
	v_mfma_f32_16x16x32_bf16 v[134:137], v[58:61], v[182:185], v[134:137]
	v_mfma_f32_16x16x32_bf16 v[130:133], v[138:141], v[182:185], v[130:133]
	v_mfma_f32_16x16x32_bf16 v[118:121], v[58:61], v[202:205], v[118:121]
	v_mfma_f32_16x16x32_bf16 v[114:117], v[138:141], v[202:205], v[114:117]
	v_mfma_f32_16x16x32_bf16 v[102:105], v[58:61], v[210:213], v[102:105]
	v_mfma_f32_16x16x32_bf16 v[98:101], v[138:141], v[210:213], v[98:101]
	v_mfma_f32_16x16x32_bf16 v[86:89], v[58:61], v[218:221], v[86:89]
	v_mfma_f32_16x16x32_bf16 v[82:85], v[138:141], v[218:221], v[82:85]
	v_mfma_f32_16x16x32_bf16 v[134:137], v[62:65], v[186:189], v[134:137]
	v_mfma_f32_16x16x32_bf16 v[130:133], v[142:145], v[186:189], v[130:133]
	v_mfma_f32_16x16x32_bf16 v[118:121], v[62:65], v[206:209], v[118:121]
	v_mfma_f32_16x16x32_bf16 v[114:117], v[142:145], v[206:209], v[114:117]
	v_mfma_f32_16x16x32_bf16 v[102:105], v[62:65], v[214:217], v[102:105]
	v_mfma_f32_16x16x32_bf16 v[98:101], v[142:145], v[214:217], v[98:101]
	v_mfma_f32_16x16x32_bf16 v[86:89], v[62:65], v[222:225], v[86:89]
	v_mfma_f32_16x16x32_bf16 v[82:85], v[142:145], v[222:225], v[82:85]
	v_mfma_f32_16x16x32_bf16 v[126:129], v[146:149], v[182:185], v[126:129]
	v_mfma_f32_16x16x32_bf16 v[122:125], v[174:177], v[182:185], v[122:125]
	v_mfma_f32_16x16x32_bf16 v[110:113], v[146:149], v[202:205], v[110:113]
	v_mfma_f32_16x16x32_bf16 v[106:109], v[174:177], v[202:205], v[106:109]
	v_mfma_f32_16x16x32_bf16 v[94:97], v[146:149], v[210:213], v[94:97]
	v_mfma_f32_16x16x32_bf16 v[90:93], v[174:177], v[210:213], v[90:93]
	v_mfma_f32_16x16x32_bf16 v[78:81], v[146:149], v[218:221], v[78:81]
	v_mfma_f32_16x16x32_bf16 v[74:77], v[174:177], v[218:221], v[74:77]
	v_mfma_f32_16x16x32_bf16 v[126:129], v[150:153], v[186:189], v[126:129]
	v_mfma_f32_16x16x32_bf16 v[122:125], v[178:181], v[186:189], v[122:125]
	v_mfma_f32_16x16x32_bf16 v[110:113], v[150:153], v[206:209], v[110:113]
	v_mfma_f32_16x16x32_bf16 v[106:109], v[178:181], v[206:209], v[106:109]
	v_mfma_f32_16x16x32_bf16 v[94:97], v[150:153], v[214:217], v[94:97]
	v_mfma_f32_16x16x32_bf16 v[90:93], v[178:181], v[214:217], v[90:93]
	v_mfma_f32_16x16x32_bf16 v[78:81], v[150:153], v[222:225], v[78:81]
	v_mfma_f32_16x16x32_bf16 v[74:77], v[178:181], v[222:225], v[74:77]
	s_barrier
; #define PG8_STAGE(bufoff, gbase, voff) do { _Pragma("unroll") for (int _i = 0; _i < 2; ++_i) \
;         __builtin_amdgcn_global_load_lds((const unsigned*)((const char*)(gbase) + (voff)[_i]), (LAS unsigned*)(lds + (bufoff) + ldsw + _i * 8192), 16, 0, 0); } while (0)
; #define PG8_LDA(dst, b, h) do { _Pragma("unroll") for (int m = 0; m < 4; ++m) _Pragma("unroll") for (int k = 0; k < 2; ++k) dst[m][k] = *(const LAS bf16x8*)(lds + PG8_SA(b, h) + aoff + m * 2048 + k * 1024); } while (0)
; #define PG8_MMA(ai, bj, At, Bt) do { __builtin_amdgcn_s_setprio(1); _Pragma("unroll") for (int m = 0; m < 4; ++m) _Pragma("unroll") for (int n = 0; n < 2; ++n) _Pragma("unroll") for (int k = 0; k < 2; ++k) \
;         acc[ai][bj][m][n] = __builtin_amdgcn_mfma_f32_16x16x32_bf16(Bt[n][k], At[m][k], acc[ai][bj][m][n], 0, 0, 0); __builtin_amdgcn_s_setprio(0); } while (0)
; #define PG8_WAIT_V(n) asm volatile("s_waitcnt vmcnt(" #n ")" ::: "memory")
; #define PG8_WAIT_L(n) asm volatile("s_waitcnt lgkmcnt(" #n ")" ::: "memory")
; #define PG8_BAR __builtin_amdgcn_s_barrier()
; #define PG8_SCHED __builtin_amdgcn_sched_barrier(0)
; template <class Epi, class Sched, bool ALIGN_EPI = false, bool SP2 = false>
; __device__ __forceinline__ void gemm_phase(LAS unsigned char* lds, const Gemm g, const Sched& S, const Epi& E) {
;     ...
;             PG8_LDA(At, 1, 1); PG8_STAGE(PG8_SB(1, 0), b3, voffB); PG8_STAGE(PG8_SB(1, 1), b3 + hstepB, voffB); PG8_STAGE(PG8_SA(1, 0), a3, voffA);
;             PG8_WAIT_V(8); PG8_WAIT_L(0); PG8_BAR; PG8_MMA(1, 0, At, B0); PG8_MMA(1, 1, At, B1); PG8_BAR; PG8_SCHED;
;     ...
;         if constexpr (ALIGN_EPI) { if (wr == 0) PG8_BAR; }
	s_add_i32 s50, s58, s28
	v_lshl_add_u64 v[190:191], v[190:191], 0, s[10:11]
	s_mov_b32 m0, s50
	ds_read_b128 v[182:185], v198 offset:49152
	ds_read_b128 v[186:189], v198 offset:50176
	ds_read_b128 v[202:205], v198 offset:51200
	ds_read_b128 v[206:209], v198 offset:52224
	ds_read_b128 v[210:213], v198 offset:53248
	ds_read_b128 v[214:217], v198 offset:54272
	ds_read_b128 v[218:221], v198 offset:55296
	ds_read_b128 v[222:225], v198 offset:56320
	global_load_lds_dwordx4 v[190:191], off
	s_add_i32 m0, s50, 0x2000
	s_add_u32 s48, s48, 0x20080
	v_lshl_add_u64 v[190:191], v[226:227], 0, s[10:11]
	s_addc_u32 s49, s49, 0
	s_add_i32 s50, s59, s28
	global_load_lds_dwordx4 v[190:191], off
	v_lshl_add_u64 v[190:191], s[48:49], 0, v[156:157]
	s_mov_b32 m0, s50
	s_nop 0
	global_load_lds_dwordx4 v[190:191], off
	v_lshl_add_u64 v[190:191], s[48:49], 0, v[160:161]
	s_add_i32 m0, s50, 0x2000
	s_nop 0
	global_load_lds_dwordx4 v[190:191], off
	v_lshl_add_u64 v[190:191], v[228:229], 0, s[10:11]
	s_mov_b32 m0, s53
	s_nop 0
	global_load_lds_dwordx4 v[190:191], off
	v_lshl_add_u64 v[190:191], v[230:231], 0, s[10:11]
	s_mov_b32 m0, s54
	s_nop 0
	global_load_lds_dwordx4 v[190:191], off
	s_waitcnt vmcnt(8)
	s_waitcnt lgkmcnt(0)
	s_barrier
	s_waitcnt lgkmcnt(0)
	v_mfma_f32_16x16x32_bf16 v[70:73], v[58:61], v[182:185], v[70:73]
	v_mfma_f32_16x16x32_bf16 v[66:69], v[138:141], v[182:185], v[66:69]
	v_mfma_f32_16x16x32_bf16 v[46:49], v[58:61], v[202:205], v[46:49]
	v_mfma_f32_16x16x32_bf16 v[42:45], v[138:141], v[202:205], v[42:45]
	v_mfma_f32_16x16x32_bf16 v[30:33], v[58:61], v[210:213], v[30:33]
	v_mfma_f32_16x16x32_bf16 v[26:29], v[138:141], v[210:213], v[26:29]
	v_mfma_f32_16x16x32_bf16 v[14:17], v[58:61], v[218:221], v[14:17]
	v_mfma_f32_16x16x32_bf16 v[10:13], v[138:141], v[218:221], v[10:13]
	v_mfma_f32_16x16x32_bf16 v[70:73], v[62:65], v[186:189], v[70:73]
	v_mfma_f32_16x16x32_bf16 v[66:69], v[142:145], v[186:189], v[66:69]
	v_mfma_f32_16x16x32_bf16 v[46:49], v[62:65], v[206:209], v[46:49]
	v_mfma_f32_16x16x32_bf16 v[42:45], v[142:145], v[206:209], v[42:45]
	v_mfma_f32_16x16x32_bf16 v[30:33], v[62:65], v[214:217], v[30:33]
	v_mfma_f32_16x16x32_bf16 v[26:29], v[142:145], v[214:217], v[26:29]
	v_mfma_f32_16x16x32_bf16 v[14:17], v[62:65], v[222:225], v[14:17]
	v_mfma_f32_16x16x32_bf16 v[10:13], v[142:145], v[222:225], v[10:13]
	v_mfma_f32_16x16x32_bf16 v[50:53], v[146:149], v[182:185], v[50:53]
	v_mfma_f32_16x16x32_bf16 v[62:65], v[150:153], v[186:189], v[50:53]
	v_mfma_f32_16x16x32_bf16 v[50:53], v[174:177], v[182:185], v[54:57]
	v_mfma_f32_16x16x32_bf16 v[38:41], v[146:149], v[202:205], v[38:41]
	v_mfma_f32_16x16x32_bf16 v[34:37], v[174:177], v[202:205], v[34:37]
	v_mfma_f32_16x16x32_bf16 v[22:25], v[146:149], v[210:213], v[22:25]
	v_mfma_f32_16x16x32_bf16 v[18:21], v[174:177], v[210:213], v[18:21]
	v_mfma_f32_16x16x32_bf16 v[6:9], v[146:149], v[218:221], v[6:9]
	v_mfma_f32_16x16x32_bf16 v[2:5], v[174:177], v[218:221], v[2:5]
	v_mfma_f32_16x16x32_bf16 v[58:61], v[178:181], v[186:189], v[50:53]
	v_mfma_f32_16x16x32_bf16 v[38:41], v[150:153], v[206:209], v[38:41]
	v_mfma_f32_16x16x32_bf16 v[34:37], v[178:181], v[206:209], v[34:37]
	v_mfma_f32_16x16x32_bf16 v[22:25], v[150:153], v[214:217], v[22:25]
	v_mfma_f32_16x16x32_bf16 v[18:21], v[178:181], v[214:217], v[18:21]
	v_mfma_f32_16x16x32_bf16 v[6:9], v[150:153], v[222:225], v[6:9]
	v_mfma_f32_16x16x32_bf16 v[2:5], v[178:181], v[222:225], v[2:5]
	s_barrier
	s_add_i32 s47, s47, 2
	s_add_u32 s16, s16, 0x100
	s_addc_u32 s17, s17, 0
	s_add_u32 s24, s24, 0x100
	s_addc_u32 s25, s25, 0
	s_cmp_gt_u32 s47, 29
	s_cbranch_scc0 .LBB0_1250
	s_and_b64 vcc, exec, s[12:13]
	s_cbranch_vccz .LBB0_1253
	s_barrier

; __device__ __forceinline__ float row_rstd(const float* ss, int row) { return 1.0f / sqrtf(ss[row] * (1.0f / DM) + 1e-6f); }
;     __device__ bool next(int i, Unit& u) const { if (i != 0 || c >= 128) return false; const int t = c >> 2; u.pm = t & 3; u.pn = t >> 2; u.koff = koff_bytes; u.q = c & 3; return true; }
; #define PG8_STAGE(bufoff, gbase, voff) do { _Pragma("unroll") for (int _i = 0; _i < 2; ++_i) \
;         __builtin_amdgcn_global_load_lds((const unsigned*)((const char*)(gbase) + (voff)[_i]), (LAS unsigned*)(lds + (bufoff) + ldsw + _i * 8192), 16, 0, 0); } while (0)
;     __device__ __forceinline__ void operator()(const f32x4 (&acc)[2][2][4][2], const Unit& u, int wr, int wc, int fr, int fq) const {
;     ...
;         const float* bp = bias + (size_t)s * BIAS_N + u.pn * BM + wc * 32 + 8 * fq;
;         const f32x4 ba0 = *(const f32x4*)bp, ba1 = *(const f32x4*)(bp + 4), bb0 = *(const f32x4*)(bp + HALF), bb1 = *(const f32x4*)(bp + HALF + 4);
;         const int lane = fq * 16 + fr;
;         const float rsl0 = row_rstd(ss, u.pm * BM + wr * 64 + lane), rsl1 = row_rstd(ss, u.pm * BM + HALF + wr * 64 + lane);
; template <class Epi, class Sched, bool ALIGN_EPI = false, bool SP2 = false>
; __device__ __forceinline__ void gemm_phase(LAS unsigned char* lds, const Gemm g, const Sched& S, const Epi& E) {
;     ...
;         const bool has_next = S.next(ui + 1, nxt);
;         const char* nA = has_next ? (const char*)g.A + (size_t)nxt.pm * tstep + nxt.koff : cA; const char* nB = has_next ? (const char*)g.Bt + (size_t)nxt.pn * tstep + nxt.koff : cB;
;         for (int t = 0; t < nt; t += 2) {
;             const bool last = (t == nt - 2);
;             const char* a1 = cA + (size_t)(t + 1) * kstep;
;             const char* a2 = last ? nA : cA + (size_t)(t + 2) * kstep; const char* b2 = last ? nB : cB + (size_t)(t + 2) * kstep;
;             const char* a3 = a2 + kstep; const char* b3 = b2 + kstep;
;             if (last && has_next) S.a_ready(nxt);
;             if constexpr (SP2) {
;             PG8_LDB(B0, 0, 0); PG8_LDB(B1, 0, 1); PG8_SCHED; PG8_LDA(At, 0, 0); PG8_STAGE(PG8_SA(1, 1), a1 + hstep, voffA);
;             PG8_WAIT_V(8); PG8_WAIT_L(0); PG8_BAR; PG8_MMA(0, 0, At, B0); PG8_MMA(0, 1, At, B1); PG8_BAR; PG8_SCHED;
;             PG8_LDA(At, 0, 1); PG8_STAGE(PG8_SB(0, 0), b2, voffB); PG8_STAGE(PG8_SB(0, 1), b2 + hstepB, voffB); PG8_STAGE(PG8_SA(0, 0), a2, voffA);
.Lpre_up2l0:
	s_lshl_b64 s[98:99], s[98:99], 2
	s_add_u32 s98, s43, s98
	s_addc_u32 s99, s44, s99
	s_lshl_b32 s100, s0, 8
	s_ashr_i32 s101, s100, 31
	s_lshl_b64 s[100:101], s[100:101], 2
	s_add_u32 s98, s98, s100
	s_addc_u32 s99, s99, s101
	s_add_u32 s98, s98, s50
	s_addc_u32 s99, s99, 0
	s_lshl_b32 s100, s2, 8
	s_add_i32 s100, s100, s42
	v_or_b32_e32 v162, s100, v171
	v_ashrrev_i32_e32 v163, 31, v162
	v_lshl_add_u64 v[162:163], v[162:163], 2, s[64:65]
	v_add_u32_e32 v164, s100, v172
	v_ashrrev_i32_e32 v165, 31, v164
	v_lshl_add_u64 v[164:165], v[164:165], 2, s[64:65]
	global_load_dwordx4 v[234:237], v177, s[98:99] offset:16
	global_load_dwordx4 v[238:241], v177, s[98:99]
	global_load_dwordx4 v[242:245], v177, s[98:99] offset:528
	global_load_dwordx4 v[246:249], v177, s[98:99] offset:512
	global_load_dword v250, v[162:163], off
	global_load_dword v251, v[164:165], off
	ds_read_b128 v[66:69], v174
	ds_read_b128 v[70:73], v174 offset:1024
	ds_read_b128 v[74:77], v174 offset:2048
	ds_read_b128 v[78:81], v174 offset:3072
	ds_read_b128 v[162:165], v175
	ds_read_b128 v[182:185], v175 offset:1024
	ds_read_b128 v[186:189], v175 offset:2048
	ds_read_b128 v[190:193], v175 offset:3072
	s_add_u32 s22, s16, 0xfff80080
	s_addc_u32 s23, s17, -1
	s_cmp_eq_u32 s53, 28
	s_cselect_b32 s41, s3, s23
	s_cselect_b32 s40, s15, s22
	s_cselect_b32 s23, s13, s52
	s_cselect_b32 s22, s24, s25
	v_lshl_add_u64 v[166:167], s[16:17], 0, v[154:155]
	s_add_i32 m0, s33, 0xc000
	ds_read_b128 v[194:197], v176
	ds_read_b128 v[198:201], v176 offset:1024
	ds_read_b128 v[202:205], v176 offset:2048
	ds_read_b128 v[206:209], v176 offset:3072
	ds_read_b128 v[210:213], v176 offset:4096
	ds_read_b128 v[214:217], v176 offset:5120
	ds_read_b128 v[218:221], v176 offset:6144
	ds_read_b128 v[222:225], v176 offset:7168
	global_load_lds_dwordx4 v[166:167], off
	v_lshl_add_u64 v[166:167], s[16:17], 0, v[156:157]
	s_add_i32 m0, s33, 0xe000
	s_nop 0
	global_load_lds_dwordx4 v[166:167], off
	s_waitcnt lgkmcnt(0)
	s_barrier
	s_waitcnt lgkmcnt(0)
	v_mfma_f32_16x16x32_bf16 v[142:145], v[66:69], v[194:197], 0
	v_mfma_f32_16x16x32_bf16 v[138:141], v[74:77], v[194:197], 0
	v_mfma_f32_16x16x32_bf16 v[126:129], v[66:69], v[202:205], 0
	v_mfma_f32_16x16x32_bf16 v[122:125], v[74:77], v[202:205], 0
	v_mfma_f32_16x16x32_bf16 v[110:113], v[66:69], v[210:213], 0
	v_mfma_f32_16x16x32_bf16 v[106:109], v[74:77], v[210:213], 0
	v_mfma_f32_16x16x32_bf16 v[94:97], v[66:69], v[218:221], 0
	v_mfma_f32_16x16x32_bf16 v[90:93], v[74:77], v[218:221], 0
	v_mfma_f32_16x16x32_bf16 v[142:145], v[70:73], v[198:201], v[142:145]
	v_mfma_f32_16x16x32_bf16 v[138:141], v[78:81], v[198:201], v[138:141]
	v_mfma_f32_16x16x32_bf16 v[126:129], v[70:73], v[206:209], v[126:129]
	v_mfma_f32_16x16x32_bf16 v[122:125], v[78:81], v[206:209], v[122:125]
	v_mfma_f32_16x16x32_bf16 v[110:113], v[70:73], v[214:217], v[110:113]
	v_mfma_f32_16x16x32_bf16 v[106:109], v[78:81], v[214:217], v[106:109]
	v_mfma_f32_16x16x32_bf16 v[94:97], v[70:73], v[222:225], v[94:97]
	v_mfma_f32_16x16x32_bf16 v[90:93], v[78:81], v[222:225], v[90:93]
	v_mfma_f32_16x16x32_bf16 v[134:137], v[162:165], v[194:197], 0
	v_mfma_f32_16x16x32_bf16 v[130:133], v[186:189], v[194:197], 0
	v_mfma_f32_16x16x32_bf16 v[118:121], v[162:165], v[202:205], 0
	v_mfma_f32_16x16x32_bf16 v[114:117], v[186:189], v[202:205], 0
	v_mfma_f32_16x16x32_bf16 v[102:105], v[162:165], v[210:213], 0
	v_mfma_f32_16x16x32_bf16 v[98:101], v[186:189], v[210:213], 0
	v_mfma_f32_16x16x32_bf16 v[86:89], v[162:165], v[218:221], 0
	v_mfma_f32_16x16x32_bf16 v[82:85], v[186:189], v[218:221], 0
	v_mfma_f32_16x16x32_bf16 v[134:137], v[182:185], v[198:201], v[134:137]
	v_mfma_f32_16x16x32_bf16 v[130:133], v[190:193], v[198:201], v[130:133]
	v_mfma_f32_16x16x32_bf16 v[118:121], v[182:185], v[206:209], v[118:121]
	v_mfma_f32_16x16x32_bf16 v[114:117], v[190:193], v[206:209], v[114:117]
	v_mfma_f32_16x16x32_bf16 v[102:105], v[182:185], v[214:217], v[102:105]
	v_mfma_f32_16x16x32_bf16 v[98:101], v[190:193], v[214:217], v[98:101]
	v_mfma_f32_16x16x32_bf16 v[86:89], v[182:185], v[222:225], v[86:89]
	v_mfma_f32_16x16x32_bf16 v[82:85], v[190:193], v[222:225], v[82:85]
	s_barrier
	s_add_i32 s54, s47, s29
	v_lshl_add_u64 v[166:167], s[22:23], 0, v[150:151]
	s_mov_b32 m0, s54
	ds_read_b128 v[194:197], v176 offset:16384
	ds_read_b128 v[198:201], v176 offset:17408
	ds_read_b128 v[202:205], v176 offset:18432
	ds_read_b128 v[206:209], v176 offset:19456
	ds_read_b128 v[210:213], v176 offset:20480
	ds_read_b128 v[214:217], v176 offset:21504
	ds_read_b128 v[218:221], v176 offset:22528
	ds_read_b128 v[222:225], v176 offset:23552
	global_load_lds_dwordx4 v[166:167], off
	s_add_i32 m0, s54, 0x2000
	s_add_u32 s54, s22, 0x80000
	v_lshl_add_u64 v[226:227], s[22:23], 0, v[146:147]
	s_addc_u32 s55, s23, 0
	s_add_i32 s56, s48, s29
	global_load_lds_dwordx4 v[226:227], off
	v_lshl_add_u64 v[228:229], s[54:55], 0, v[150:151]
	s_mov_b32 m0, s56
	v_lshl_add_u64 v[230:231], s[40:41], 0, v[148:149]
	global_load_lds_dwordx4 v[228:229], off
	v_lshl_add_u64 v[228:229], s[54:55], 0, v[146:147]
	s_add_i32 m0, s56, 0x2000
	s_nop 0
	global_load_lds_dwordx4 v[228:229], off
	v_lshl_add_u64 v[228:229], s[40:41], 0, v[152:153]
	s_mov_b32 m0, s33
	s_nop 0
	global_load_lds_dwordx4 v[228:229], off
	s_mov_b32 m0, s34
	s_nop 0
	global_load_lds_dwordx4 v[230:231], off
	s_waitcnt lgkmcnt(0)
	s_barrier
; #define PG8_STAGE(bufoff, gbase, voff) do { _Pragma("unroll") for (int _i = 0; _i < 2; ++_i) \
;         __builtin_amdgcn_global_load_lds((const unsigned*)((const char*)(gbase) + (voff)[_i]), (LAS unsigned*)(lds + (bufoff) + ldsw + _i * 8192), 16, 0, 0); } while (0)
; #define PG8_LDA(dst, b, h) do { _Pragma("unroll") for (int m = 0; m < 4; ++m) _Pragma("unroll") for (int k = 0; k < 2; ++k) dst[m][k] = *(const LAS bf16x8*)(lds + PG8_SA(b, h) + aoff + m * 2048 + k * 1024); } while (0)
; #define PG8_LDB(dst, b, h) do { _Pragma("unroll") for (int n = 0; n < 2; ++n) _Pragma("unroll") for (int k = 0; k < 2; ++k) dst[n][k] = *(const LAS bf16x8*)(lds + PG8_SB(b, h) + boff + n * 2048 + k * 1024); } while (0)
; #define PG8_MMA(ai, bj, At, Bt) do { __builtin_amdgcn_s_setprio(1); _Pragma("unroll") for (int m = 0; m < 4; ++m) _Pragma("unroll") for (int n = 0; n < 2; ++n) _Pragma("unroll") for (int k = 0; k < 2; ++k) \
;         acc[ai][bj][m][n] = __builtin_amdgcn_mfma_f32_16x16x32_bf16(Bt[n][k], At[m][k], acc[ai][bj][m][n], 0, 0, 0); __builtin_amdgcn_s_setprio(0); } while (0)
; #define PG8_WAIT_V(n) asm volatile("s_waitcnt vmcnt(" #n ")" ::: "memory")
; #define PG8_WAIT_L(n) asm volatile("s_waitcnt lgkmcnt(" #n ")" ::: "memory")
; #define PG8_BAR __builtin_amdgcn_s_barrier()
; #define PG8_SCHED __builtin_amdgcn_sched_barrier(0)
; template <class Epi, class Sched, bool ALIGN_EPI = false, bool SP2 = false>
; __device__ __forceinline__ void gemm_phase(LAS unsigned char* lds, const Gemm g, const Sched& S, const Epi& E) {
;     ...
;             PG8_WAIT_V(8); PG8_WAIT_L(0); PG8_BAR; PG8_MMA(1, 0, At, B0); PG8_MMA(1, 1, At, B1); PG8_BAR; PG8_SCHED;
;             PG8_LDB(B0, 1, 0); PG8_LDB(B1, 1, 1); PG8_SCHED; PG8_LDA(At, 1, 0); PG8_STAGE(PG8_SA(0, 1), a2 + hstep, voffA);
;             PG8_WAIT_V(8); PG8_WAIT_L(0); PG8_BAR; PG8_MMA(0, 0, At, B0); PG8_MMA(0, 1, At, B1); PG8_BAR; PG8_SCHED;
	s_waitcnt lgkmcnt(0)
	v_mfma_f32_16x16x32_bf16 v[62:65], v[66:69], v[194:197], 0
	v_mfma_f32_16x16x32_bf16 v[58:61], v[74:77], v[194:197], 0
	v_mfma_f32_16x16x32_bf16 v[46:49], v[66:69], v[202:205], 0
	v_mfma_f32_16x16x32_bf16 v[42:45], v[74:77], v[202:205], 0
	v_mfma_f32_16x16x32_bf16 v[30:33], v[66:69], v[210:213], 0
	v_mfma_f32_16x16x32_bf16 v[26:29], v[74:77], v[210:213], 0
	v_mfma_f32_16x16x32_bf16 v[14:17], v[66:69], v[218:221], 0
	v_mfma_f32_16x16x32_bf16 v[10:13], v[74:77], v[218:221], 0
	v_mfma_f32_16x16x32_bf16 v[62:65], v[70:73], v[198:201], v[62:65]
	v_mfma_f32_16x16x32_bf16 v[58:61], v[78:81], v[198:201], v[58:61]
	v_mfma_f32_16x16x32_bf16 v[46:49], v[70:73], v[206:209], v[46:49]
	v_mfma_f32_16x16x32_bf16 v[42:45], v[78:81], v[206:209], v[42:45]
	v_mfma_f32_16x16x32_bf16 v[30:33], v[70:73], v[214:217], v[30:33]
	v_mfma_f32_16x16x32_bf16 v[26:29], v[78:81], v[214:217], v[26:29]
	v_mfma_f32_16x16x32_bf16 v[14:17], v[70:73], v[222:225], v[14:17]
	v_mfma_f32_16x16x32_bf16 v[10:13], v[78:81], v[222:225], v[10:13]
	v_mfma_f32_16x16x32_bf16 v[54:57], v[162:165], v[194:197], 0
	v_mfma_f32_16x16x32_bf16 v[50:53], v[186:189], v[194:197], 0
	v_mfma_f32_16x16x32_bf16 v[38:41], v[162:165], v[202:205], 0
	v_mfma_f32_16x16x32_bf16 v[34:37], v[186:189], v[202:205], 0
	v_mfma_f32_16x16x32_bf16 v[22:25], v[162:165], v[210:213], 0
	v_mfma_f32_16x16x32_bf16 v[18:21], v[186:189], v[210:213], 0
	v_mfma_f32_16x16x32_bf16 v[6:9], v[162:165], v[218:221], 0
	v_mfma_f32_16x16x32_bf16 v[2:5], v[186:189], v[218:221], 0
	v_mfma_f32_16x16x32_bf16 v[54:57], v[182:185], v[198:201], v[54:57]
	v_mfma_f32_16x16x32_bf16 v[50:53], v[190:193], v[198:201], v[50:53]
	v_mfma_f32_16x16x32_bf16 v[38:41], v[182:185], v[206:209], v[38:41]
	v_mfma_f32_16x16x32_bf16 v[34:37], v[190:193], v[206:209], v[34:37]
	v_mfma_f32_16x16x32_bf16 v[22:25], v[182:185], v[214:217], v[22:25]
	v_mfma_f32_16x16x32_bf16 v[18:21], v[190:193], v[214:217], v[18:21]
	v_mfma_f32_16x16x32_bf16 v[6:9], v[182:185], v[222:225], v[6:9]
	v_mfma_f32_16x16x32_bf16 v[2:5], v[190:193], v[222:225], v[2:5]
	s_barrier
	s_add_i32 s54, 0, 0x18000
	s_add_i32 s55, 0, 0x1c000
	v_add_u32_e32 v78, s54, v170
	v_add_u32_e32 v168, s55, v170
	ds_read_b128 v[66:69], v78
	ds_read_b128 v[70:73], v78 offset:1024
	ds_read_b128 v[74:77], v78 offset:2048
	ds_read_b128 v[78:81], v78 offset:3072
	ds_read_b128 v[162:165], v168
	ds_read_b128 v[182:185], v168 offset:1024
	ds_read_b128 v[186:189], v168 offset:2048
	ds_read_b128 v[190:193], v168 offset:3072
	s_add_u32 s40, s40, 0x80000
	s_addc_u32 s41, s41, 0
	s_mov_b32 m0, s35
	v_lshl_add_u64 v[232:233], s[40:41], 0, v[152:153]
	ds_read_b128 v[194:197], v176 offset:32768
	ds_read_b128 v[198:201], v176 offset:33792
	ds_read_b128 v[202:205], v176 offset:34816
	ds_read_b128 v[206:209], v176 offset:35840
	ds_read_b128 v[210:213], v176 offset:36864
	ds_read_b128 v[214:217], v176 offset:37888
	ds_read_b128 v[218:221], v176 offset:38912
	ds_read_b128 v[222:225], v176 offset:39936
	global_load_lds_dwordx4 v[232:233], off
	v_lshl_add_u64 v[232:233], s[40:41], 0, v[148:149]
	s_mov_b32 m0, s36
	s_nop 0
	global_load_lds_dwordx4 v[232:233], off
	s_waitcnt vmcnt(8)
	s_waitcnt lgkmcnt(0)
	s_barrier
	s_waitcnt lgkmcnt(0)
	v_mfma_f32_16x16x32_bf16 v[142:145], v[66:69], v[194:197], v[142:145]
	v_mfma_f32_16x16x32_bf16 v[138:141], v[74:77], v[194:197], v[138:141]
	v_mfma_f32_16x16x32_bf16 v[126:129], v[66:69], v[202:205], v[126:129]
	v_mfma_f32_16x16x32_bf16 v[122:125], v[74:77], v[202:205], v[122:125]
	v_mfma_f32_16x16x32_bf16 v[110:113], v[66:69], v[210:213], v[110:113]
	v_mfma_f32_16x16x32_bf16 v[106:109], v[74:77], v[210:213], v[106:109]
	v_mfma_f32_16x16x32_bf16 v[94:97], v[66:69], v[218:221], v[94:97]
	v_mfma_f32_16x16x32_bf16 v[90:93], v[74:77], v[218:221], v[90:93]
	v_mfma_f32_16x16x32_bf16 v[142:145], v[70:73], v[198:201], v[142:145]
	v_mfma_f32_16x16x32_bf16 v[138:141], v[78:81], v[198:201], v[138:141]
	v_mfma_f32_16x16x32_bf16 v[126:129], v[70:73], v[206:209], v[126:129]
	v_mfma_f32_16x16x32_bf16 v[122:125], v[78:81], v[206:209], v[122:125]
	v_mfma_f32_16x16x32_bf16 v[110:113], v[70:73], v[214:217], v[110:113]
	v_mfma_f32_16x16x32_bf16 v[106:109], v[78:81], v[214:217], v[106:109]
	v_mfma_f32_16x16x32_bf16 v[94:97], v[70:73], v[222:225], v[94:97]
	v_mfma_f32_16x16x32_bf16 v[90:93], v[78:81], v[222:225], v[90:93]
	v_mfma_f32_16x16x32_bf16 v[134:137], v[162:165], v[194:197], v[134:137]
	v_mfma_f32_16x16x32_bf16 v[130:133], v[186:189], v[194:197], v[130:133]
	v_mfma_f32_16x16x32_bf16 v[118:121], v[162:165], v[202:205], v[118:121]
	v_mfma_f32_16x16x32_bf16 v[114:117], v[186:189], v[202:205], v[114:117]
	v_mfma_f32_16x16x32_bf16 v[102:105], v[162:165], v[210:213], v[102:105]
	v_mfma_f32_16x16x32_bf16 v[98:101], v[186:189], v[210:213], v[98:101]
	v_mfma_f32_16x16x32_bf16 v[86:89], v[162:165], v[218:221], v[86:89]
	v_mfma_f32_16x16x32_bf16 v[82:85], v[186:189], v[218:221], v[82:85]
	v_mfma_f32_16x16x32_bf16 v[134:137], v[182:185], v[198:201], v[134:137]
	v_mfma_f32_16x16x32_bf16 v[130:133], v[190:193], v[198:201], v[130:133]
	v_mfma_f32_16x16x32_bf16 v[118:121], v[182:185], v[206:209], v[118:121]
	v_mfma_f32_16x16x32_bf16 v[114:117], v[190:193], v[206:209], v[114:117]
	v_mfma_f32_16x16x32_bf16 v[102:105], v[182:185], v[214:217], v[102:105]
	v_mfma_f32_16x16x32_bf16 v[98:101], v[190:193], v[214:217], v[98:101]
	v_mfma_f32_16x16x32_bf16 v[86:89], v[182:185], v[222:225], v[86:89]
	v_mfma_f32_16x16x32_bf16 v[82:85], v[190:193], v[222:225], v[82:85]
	s_barrier
; #define PG8_STAGE(bufoff, gbase, voff) do { _Pragma("unroll") for (int _i = 0; _i < 2; ++_i) \
;         __builtin_amdgcn_global_load_lds((const unsigned*)((const char*)(gbase) + (voff)[_i]), (LAS unsigned*)(lds + (bufoff) + ldsw + _i * 8192), 16, 0, 0); } while (0)
; #define PG8_LDA(dst, b, h) do { _Pragma("unroll") for (int m = 0; m < 4; ++m) _Pragma("unroll") for (int k = 0; k < 2; ++k) dst[m][k] = *(const LAS bf16x8*)(lds + PG8_SA(b, h) + aoff + m * 2048 + k * 1024); } while (0)
; #define PG8_LDB(dst, b, h) do { _Pragma("unroll") for (int n = 0; n < 2; ++n) _Pragma("unroll") for (int k = 0; k < 2; ++k) dst[n][k] = *(const LAS bf16x8*)(lds + PG8_SB(b, h) + boff + n * 2048 + k * 1024); } while (0)
; #define PG8_MMA(ai, bj, At, Bt) do { __builtin_amdgcn_s_setprio(1); _Pragma("unroll") for (int m = 0; m < 4; ++m) _Pragma("unroll") for (int n = 0; n < 2; ++n) _Pragma("unroll") for (int k = 0; k < 2; ++k) \
;         acc[ai][bj][m][n] = __builtin_amdgcn_mfma_f32_16x16x32_bf16(Bt[n][k], At[m][k], acc[ai][bj][m][n], 0, 0, 0); __builtin_amdgcn_s_setprio(0); } while (0)
; #define PG8_WAIT_V(n) asm volatile("s_waitcnt vmcnt(" #n ")" ::: "memory")
; #define PG8_WAIT_L(n) asm volatile("s_waitcnt lgkmcnt(" #n ")" ::: "memory")
; #define PG8_BAR __builtin_amdgcn_s_barrier()
; #define PG8_SCHED __builtin_amdgcn_sched_barrier(0)
; template <class Epi, class Sched, bool ALIGN_EPI = false, bool SP2 = false>
; __device__ __forceinline__ void gemm_phase(LAS unsigned char* lds, const Gemm g, const Sched& S, const Epi& E) {
;     ...
;             PG8_LDB(B0, 0, 0); PG8_LDB(B1, 0, 1); PG8_SCHED; PG8_LDA(At, 0, 0); PG8_STAGE(PG8_SA(1, 1), a1 + hstep, voffA);
;             PG8_WAIT_V(8); PG8_WAIT_L(0); PG8_BAR; PG8_MMA(0, 0, At, B0); PG8_MMA(0, 1, At, B1); PG8_BAR; PG8_SCHED;
;     ...
;             PG8_LDA(At, 1, 1); PG8_STAGE(PG8_SB(1, 0), b3, voffB); PG8_STAGE(PG8_SB(1, 1), b3 + hstepB, voffB); PG8_STAGE(PG8_SA(1, 0), a3, voffA);
;             PG8_WAIT_V(8); PG8_WAIT_L(0); PG8_BAR; PG8_MMA(1, 0, At, B0); PG8_MMA(1, 1, At, B1); PG8_BAR; PG8_SCHED;
	s_add_i32 s40, s54, s29
	v_lshl_add_u64 v[166:167], v[166:167], 0, s[8:9]
	s_mov_b32 m0, s40
	ds_read_b128 v[194:197], v176 offset:49152
	ds_read_b128 v[198:201], v176 offset:50176
	ds_read_b128 v[202:205], v176 offset:51200
	ds_read_b128 v[206:209], v176 offset:52224
	ds_read_b128 v[210:213], v176 offset:53248
	ds_read_b128 v[214:217], v176 offset:54272
	ds_read_b128 v[218:221], v176 offset:55296
	ds_read_b128 v[222:225], v176 offset:56320
	global_load_lds_dwordx4 v[166:167], off
	s_add_i32 m0, s40, 0x2000
	s_add_u32 s22, s22, 0x80080
	v_lshl_add_u64 v[166:167], v[226:227], 0, s[8:9]
	s_addc_u32 s23, s23, 0
	s_add_i32 s40, s55, s29
	global_load_lds_dwordx4 v[166:167], off
	v_lshl_add_u64 v[166:167], s[22:23], 0, v[150:151]
	s_mov_b32 m0, s40
	s_nop 0
	global_load_lds_dwordx4 v[166:167], off
	v_lshl_add_u64 v[166:167], s[22:23], 0, v[146:147]
	s_add_i32 m0, s40, 0x2000
	s_nop 0
	global_load_lds_dwordx4 v[166:167], off
	v_lshl_add_u64 v[166:167], v[228:229], 0, s[8:9]
	s_mov_b32 m0, s45
	s_nop 0
	global_load_lds_dwordx4 v[166:167], off
	v_lshl_add_u64 v[166:167], v[230:231], 0, s[8:9]
	s_mov_b32 m0, s46
	s_nop 0
	global_load_lds_dwordx4 v[166:167], off
	s_waitcnt vmcnt(8)
	s_waitcnt lgkmcnt(0)
	s_barrier
	s_waitcnt lgkmcnt(0)
	v_mfma_f32_16x16x32_bf16 v[62:65], v[66:69], v[194:197], v[62:65]
	v_mfma_f32_16x16x32_bf16 v[58:61], v[74:77], v[194:197], v[58:61]
	v_mfma_f32_16x16x32_bf16 v[46:49], v[66:69], v[202:205], v[46:49]
	v_mfma_f32_16x16x32_bf16 v[42:45], v[74:77], v[202:205], v[42:45]
	v_mfma_f32_16x16x32_bf16 v[30:33], v[66:69], v[210:213], v[30:33]
	v_mfma_f32_16x16x32_bf16 v[26:29], v[74:77], v[210:213], v[26:29]
	v_mfma_f32_16x16x32_bf16 v[14:17], v[66:69], v[218:221], v[14:17]
	v_mfma_f32_16x16x32_bf16 v[10:13], v[74:77], v[218:221], v[10:13]
	v_mfma_f32_16x16x32_bf16 v[62:65], v[70:73], v[198:201], v[62:65]
	v_mfma_f32_16x16x32_bf16 v[58:61], v[78:81], v[198:201], v[58:61]
	v_mfma_f32_16x16x32_bf16 v[46:49], v[70:73], v[206:209], v[46:49]
	v_mfma_f32_16x16x32_bf16 v[42:45], v[78:81], v[206:209], v[42:45]
	v_mfma_f32_16x16x32_bf16 v[30:33], v[70:73], v[214:217], v[30:33]
	v_mfma_f32_16x16x32_bf16 v[26:29], v[78:81], v[214:217], v[26:29]
	v_mfma_f32_16x16x32_bf16 v[14:17], v[70:73], v[222:225], v[14:17]
	v_mfma_f32_16x16x32_bf16 v[10:13], v[78:81], v[222:225], v[10:13]
	v_mfma_f32_16x16x32_bf16 v[54:57], v[162:165], v[194:197], v[54:57]
	v_mfma_f32_16x16x32_bf16 v[50:53], v[186:189], v[194:197], v[50:53]
	v_mfma_f32_16x16x32_bf16 v[38:41], v[162:165], v[202:205], v[38:41]
	v_mfma_f32_16x16x32_bf16 v[34:37], v[186:189], v[202:205], v[34:37]
	v_mfma_f32_16x16x32_bf16 v[22:25], v[162:165], v[210:213], v[22:25]
	v_mfma_f32_16x16x32_bf16 v[18:21], v[186:189], v[210:213], v[18:21]
	v_mfma_f32_16x16x32_bf16 v[6:9], v[162:165], v[218:221], v[6:9]
	v_mfma_f32_16x16x32_bf16 v[2:5], v[186:189], v[218:221], v[2:5]
	v_mfma_f32_16x16x32_bf16 v[54:57], v[182:185], v[198:201], v[54:57]
	v_mfma_f32_16x16x32_bf16 v[50:53], v[190:193], v[198:201], v[50:53]
	v_mfma_f32_16x16x32_bf16 v[38:41], v[182:185], v[206:209], v[38:41]
	v_mfma_f32_16x16x32_bf16 v[34:37], v[190:193], v[206:209], v[34:37]
	v_mfma_f32_16x16x32_bf16 v[22:25], v[182:185], v[214:217], v[22:25]
	v_mfma_f32_16x16x32_bf16 v[18:21], v[190:193], v[214:217], v[18:21]
	v_mfma_f32_16x16x32_bf16 v[6:9], v[182:185], v[222:225], v[6:9]
	v_mfma_f32_16x16x32_bf16 v[2:5], v[190:193], v[222:225], v[2:5]
	s_barrier
	s_add_i32 s53, s53, 2
	s_add_u32 s16, s16, 0x100
	s_addc_u32 s17, s17, 0
	s_add_u32 s25, s25, 0x100
	s_addc_u32 s52, s52, 0
	s_cmp_gt_u32 s53, 29
.LBB0_1465:
	ds_read_b128 v[66:69], v174
	ds_read_b128 v[70:73], v174 offset:1024
	ds_read_b128 v[74:77], v174 offset:2048
	ds_read_b128 v[78:81], v174 offset:3072
	ds_read_b128 v[162:165], v175
	ds_read_b128 v[182:185], v175 offset:1024
	ds_read_b128 v[186:189], v175 offset:2048
	ds_read_b128 v[190:193], v175 offset:3072
	s_add_u32 s22, s16, 0xfff80080
	s_addc_u32 s23, s17, -1
	s_cmp_eq_u32 s53, 28
	s_cselect_b32 s41, s3, s23
	s_cselect_b32 s40, s15, s22
	s_cselect_b32 s23, s13, s52
	s_cselect_b32 s22, s24, s25
	v_lshl_add_u64 v[166:167], s[16:17], 0, v[154:155]
	s_add_i32 m0, s33, 0xc000
	ds_read_b128 v[194:197], v176
	ds_read_b128 v[198:201], v176 offset:1024
	ds_read_b128 v[202:205], v176 offset:2048
	ds_read_b128 v[206:209], v176 offset:3072
	ds_read_b128 v[210:213], v176 offset:4096
	ds_read_b128 v[214:217], v176 offset:5120
	ds_read_b128 v[218:221], v176 offset:6144
	ds_read_b128 v[222:225], v176 offset:7168
	global_load_lds_dwordx4 v[166:167], off
	v_lshl_add_u64 v[166:167], s[16:17], 0, v[156:157]
	s_add_i32 m0, s33, 0xe000
	s_nop 0
	global_load_lds_dwordx4 v[166:167], off
	s_waitcnt vmcnt(8)
	s_waitcnt lgkmcnt(0)
	s_barrier
; #define PG8_STAGE(bufoff, gbase, voff) do { _Pragma("unroll") for (int _i = 0; _i < 2; ++_i) \
;         __builtin_amdgcn_global_load_lds((const unsigned*)((const char*)(gbase) + (voff)[_i]), (LAS unsigned*)(lds + (bufoff) + ldsw + _i * 8192), 16, 0, 0); } while (0)
; #define PG8_LDA(dst, b, h) do { _Pragma("unroll") for (int m = 0; m < 4; ++m) _Pragma("unroll") for (int k = 0; k < 2; ++k) dst[m][k] = *(const LAS bf16x8*)(lds + PG8_SA(b, h) + aoff + m * 2048 + k * 1024); } while (0)
; #define PG8_LDB(dst, b, h) do { _Pragma("unroll") for (int n = 0; n < 2; ++n) _Pragma("unroll") for (int k = 0; k < 2; ++k) dst[n][k] = *(const LAS bf16x8*)(lds + PG8_SB(b, h) + boff + n * 2048 + k * 1024); } while (0)
; #define PG8_MMA(ai, bj, At, Bt) do { __builtin_amdgcn_s_setprio(1); _Pragma("unroll") for (int m = 0; m < 4; ++m) _Pragma("unroll") for (int n = 0; n < 2; ++n) _Pragma("unroll") for (int k = 0; k < 2; ++k) \
;         acc[ai][bj][m][n] = __builtin_amdgcn_mfma_f32_16x16x32_bf16(Bt[n][k], At[m][k], acc[ai][bj][m][n], 0, 0, 0); __builtin_amdgcn_s_setprio(0); } while (0)
; #define PG8_WAIT_V(n) asm volatile("s_waitcnt vmcnt(" #n ")" ::: "memory")
; #define PG8_WAIT_L(n) asm volatile("s_waitcnt lgkmcnt(" #n ")" ::: "memory")
; #define PG8_BAR __builtin_amdgcn_s_barrier()
; #define PG8_SCHED __builtin_amdgcn_sched_barrier(0)
; template <class Epi, class Sched, bool ALIGN_EPI = false, bool SP2 = false>
; __device__ __forceinline__ void gemm_phase(LAS unsigned char* lds, const Gemm g, const Sched& S, const Epi& E) {
;     ...
;             PG8_WAIT_V(8); PG8_WAIT_L(0); PG8_BAR; PG8_MMA(0, 0, At, B0); PG8_MMA(0, 1, At, B1); PG8_BAR; PG8_SCHED;
;             PG8_LDA(At, 0, 1); PG8_STAGE(PG8_SB(0, 0), b2, voffB); PG8_STAGE(PG8_SB(0, 1), b2 + hstepB, voffB); PG8_STAGE(PG8_SA(0, 0), a2, voffA);
;             PG8_WAIT_V(8); PG8_WAIT_L(0); PG8_BAR; PG8_MMA(1, 0, At, B0); PG8_MMA(1, 1, At, B1); PG8_BAR; PG8_SCHED;
;             PG8_LDB(B0, 1, 0); PG8_LDB(B1, 1, 1); PG8_SCHED; PG8_LDA(At, 1, 0); PG8_STAGE(PG8_SA(0, 1), a2 + hstep, voffA);
;             PG8_WAIT_V(8); PG8_WAIT_L(0); PG8_BAR; PG8_MMA(0, 0, At, B0); PG8_MMA(0, 1, At, B1); PG8_BAR; PG8_SCHED;
	s_waitcnt lgkmcnt(0)
	v_mfma_f32_16x16x32_bf16 v[142:145], v[66:69], v[194:197], v[142:145]
	v_mfma_f32_16x16x32_bf16 v[138:141], v[74:77], v[194:197], v[138:141]
	v_mfma_f32_16x16x32_bf16 v[126:129], v[66:69], v[202:205], v[126:129]
	v_mfma_f32_16x16x32_bf16 v[122:125], v[74:77], v[202:205], v[122:125]
	v_mfma_f32_16x16x32_bf16 v[110:113], v[66:69], v[210:213], v[110:113]
	v_mfma_f32_16x16x32_bf16 v[106:109], v[74:77], v[210:213], v[106:109]
	v_mfma_f32_16x16x32_bf16 v[94:97], v[66:69], v[218:221], v[94:97]
	v_mfma_f32_16x16x32_bf16 v[90:93], v[74:77], v[218:221], v[90:93]
	v_mfma_f32_16x16x32_bf16 v[142:145], v[70:73], v[198:201], v[142:145]
	v_mfma_f32_16x16x32_bf16 v[138:141], v[78:81], v[198:201], v[138:141]
	v_mfma_f32_16x16x32_bf16 v[126:129], v[70:73], v[206:209], v[126:129]
	v_mfma_f32_16x16x32_bf16 v[122:125], v[78:81], v[206:209], v[122:125]
	v_mfma_f32_16x16x32_bf16 v[110:113], v[70:73], v[214:217], v[110:113]
	v_mfma_f32_16x16x32_bf16 v[106:109], v[78:81], v[214:217], v[106:109]
	v_mfma_f32_16x16x32_bf16 v[94:97], v[70:73], v[222:225], v[94:97]
	v_mfma_f32_16x16x32_bf16 v[90:93], v[78:81], v[222:225], v[90:93]
	v_mfma_f32_16x16x32_bf16 v[134:137], v[162:165], v[194:197], v[134:137]
	v_mfma_f32_16x16x32_bf16 v[130:133], v[186:189], v[194:197], v[130:133]
	v_mfma_f32_16x16x32_bf16 v[118:121], v[162:165], v[202:205], v[118:121]
	v_mfma_f32_16x16x32_bf16 v[114:117], v[186:189], v[202:205], v[114:117]
	v_mfma_f32_16x16x32_bf16 v[102:105], v[162:165], v[210:213], v[102:105]
	v_mfma_f32_16x16x32_bf16 v[98:101], v[186:189], v[210:213], v[98:101]
	v_mfma_f32_16x16x32_bf16 v[86:89], v[162:165], v[218:221], v[86:89]
	v_mfma_f32_16x16x32_bf16 v[82:85], v[186:189], v[218:221], v[82:85]
	v_mfma_f32_16x16x32_bf16 v[134:137], v[182:185], v[198:201], v[134:137]
	v_mfma_f32_16x16x32_bf16 v[130:133], v[190:193], v[198:201], v[130:133]
	v_mfma_f32_16x16x32_bf16 v[118:121], v[182:185], v[206:209], v[118:121]
	v_mfma_f32_16x16x32_bf16 v[114:117], v[190:193], v[206:209], v[114:117]
	v_mfma_f32_16x16x32_bf16 v[102:105], v[182:185], v[214:217], v[102:105]
	v_mfma_f32_16x16x32_bf16 v[98:101], v[190:193], v[214:217], v[98:101]
	v_mfma_f32_16x16x32_bf16 v[86:89], v[182:185], v[222:225], v[86:89]
	v_mfma_f32_16x16x32_bf16 v[82:85], v[190:193], v[222:225], v[82:85]
	s_barrier
	s_add_i32 s54, s47, s29
	v_lshl_add_u64 v[166:167], s[22:23], 0, v[150:151]
	s_mov_b32 m0, s54
	ds_read_b128 v[194:197], v176 offset:16384
	ds_read_b128 v[198:201], v176 offset:17408
	ds_read_b128 v[202:205], v176 offset:18432
	ds_read_b128 v[206:209], v176 offset:19456
	ds_read_b128 v[210:213], v176 offset:20480
	ds_read_b128 v[214:217], v176 offset:21504
	ds_read_b128 v[218:221], v176 offset:22528
	ds_read_b128 v[222:225], v176 offset:23552
	global_load_lds_dwordx4 v[166:167], off
	s_add_i32 m0, s54, 0x2000
	s_add_u32 s54, s22, 0x80000
	v_lshl_add_u64 v[226:227], s[22:23], 0, v[146:147]
	s_addc_u32 s55, s23, 0
	s_add_i32 s56, s48, s29
	global_load_lds_dwordx4 v[226:227], off
	v_lshl_add_u64 v[228:229], s[54:55], 0, v[150:151]
	s_mov_b32 m0, s56
	v_lshl_add_u64 v[230:231], s[40:41], 0, v[148:149]
	global_load_lds_dwordx4 v[228:229], off
	v_lshl_add_u64 v[228:229], s[54:55], 0, v[146:147]
	s_add_i32 m0, s56, 0x2000
	s_nop 0
	global_load_lds_dwordx4 v[228:229], off
	v_lshl_add_u64 v[228:229], s[40:41], 0, v[152:153]
	s_mov_b32 m0, s33
	s_nop 0
	global_load_lds_dwordx4 v[228:229], off
	s_mov_b32 m0, s34
	s_nop 0
	global_load_lds_dwordx4 v[230:231], off
	s_waitcnt vmcnt(8)
	s_waitcnt lgkmcnt(0)
	s_barrier
	s_waitcnt lgkmcnt(0)
	v_mfma_f32_16x16x32_bf16 v[62:65], v[66:69], v[194:197], v[62:65]
	v_mfma_f32_16x16x32_bf16 v[58:61], v[74:77], v[194:197], v[58:61]
	v_mfma_f32_16x16x32_bf16 v[46:49], v[66:69], v[202:205], v[46:49]
	v_mfma_f32_16x16x32_bf16 v[42:45], v[74:77], v[202:205], v[42:45]
	v_mfma_f32_16x16x32_bf16 v[30:33], v[66:69], v[210:213], v[30:33]
	v_mfma_f32_16x16x32_bf16 v[26:29], v[74:77], v[210:213], v[26:29]
	v_mfma_f32_16x16x32_bf16 v[14:17], v[66:69], v[218:221], v[14:17]
	v_mfma_f32_16x16x32_bf16 v[10:13], v[74:77], v[218:221], v[10:13]
	v_mfma_f32_16x16x32_bf16 v[62:65], v[70:73], v[198:201], v[62:65]
	v_mfma_f32_16x16x32_bf16 v[58:61], v[78:81], v[198:201], v[58:61]
	v_mfma_f32_16x16x32_bf16 v[46:49], v[70:73], v[206:209], v[46:49]
	v_mfma_f32_16x16x32_bf16 v[42:45], v[78:81], v[206:209], v[42:45]
	v_mfma_f32_16x16x32_bf16 v[30:33], v[70:73], v[214:217], v[30:33]
	v_mfma_f32_16x16x32_bf16 v[26:29], v[78:81], v[214:217], v[26:29]
	v_mfma_f32_16x16x32_bf16 v[14:17], v[70:73], v[222:225], v[14:17]
	v_mfma_f32_16x16x32_bf16 v[10:13], v[78:81], v[222:225], v[10:13]
	v_mfma_f32_16x16x32_bf16 v[54:57], v[162:165], v[194:197], v[54:57]
	v_mfma_f32_16x16x32_bf16 v[50:53], v[186:189], v[194:197], v[50:53]
	v_mfma_f32_16x16x32_bf16 v[38:41], v[162:165], v[202:205], v[38:41]
	v_mfma_f32_16x16x32_bf16 v[34:37], v[186:189], v[202:205], v[34:37]
	v_mfma_f32_16x16x32_bf16 v[22:25], v[162:165], v[210:213], v[22:25]
	v_mfma_f32_16x16x32_bf16 v[18:21], v[186:189], v[210:213], v[18:21]
	v_mfma_f32_16x16x32_bf16 v[6:9], v[162:165], v[218:221], v[6:9]
	v_mfma_f32_16x16x32_bf16 v[2:5], v[186:189], v[218:221], v[2:5]
	v_mfma_f32_16x16x32_bf16 v[54:57], v[182:185], v[198:201], v[54:57]
	v_mfma_f32_16x16x32_bf16 v[50:53], v[190:193], v[198:201], v[50:53]
	v_mfma_f32_16x16x32_bf16 v[38:41], v[182:185], v[206:209], v[38:41]
	v_mfma_f32_16x16x32_bf16 v[34:37], v[190:193], v[206:209], v[34:37]
	v_mfma_f32_16x16x32_bf16 v[22:25], v[182:185], v[214:217], v[22:25]
	v_mfma_f32_16x16x32_bf16 v[18:21], v[190:193], v[214:217], v[18:21]
	v_mfma_f32_16x16x32_bf16 v[6:9], v[182:185], v[222:225], v[6:9]
	v_mfma_f32_16x16x32_bf16 v[2:5], v[190:193], v[222:225], v[2:5]
	s_barrier
; #define PG8_STAGE(bufoff, gbase, voff) do { _Pragma("unroll") for (int _i = 0; _i < 2; ++_i) \
;         __builtin_amdgcn_global_load_lds((const unsigned*)((const char*)(gbase) + (voff)[_i]), (LAS unsigned*)(lds + (bufoff) + ldsw + _i * 8192), 16, 0, 0); } while (0)
; #define PG8_LDA(dst, b, h) do { _Pragma("unroll") for (int m = 0; m < 4; ++m) _Pragma("unroll") for (int k = 0; k < 2; ++k) dst[m][k] = *(const LAS bf16x8*)(lds + PG8_SA(b, h) + aoff + m * 2048 + k * 1024); } while (0)
; #define PG8_LDB(dst, b, h) do { _Pragma("unroll") for (int n = 0; n < 2; ++n) _Pragma("unroll") for (int k = 0; k < 2; ++k) dst[n][k] = *(const LAS bf16x8*)(lds + PG8_SB(b, h) + boff + n * 2048 + k * 1024); } while (0)
; #define PG8_MMA(ai, bj, At, Bt) do { __builtin_amdgcn_s_setprio(1); _Pragma("unroll") for (int m = 0; m < 4; ++m) _Pragma("unroll") for (int n = 0; n < 2; ++n) _Pragma("unroll") for (int k = 0; k < 2; ++k) \
;         acc[ai][bj][m][n] = __builtin_amdgcn_mfma_f32_16x16x32_bf16(Bt[n][k], At[m][k], acc[ai][bj][m][n], 0, 0, 0); __builtin_amdgcn_s_setprio(0); } while (0)
; #define PG8_WAIT_V(n) asm volatile("s_waitcnt vmcnt(" #n ")" ::: "memory")
; #define PG8_WAIT_L(n) asm volatile("s_waitcnt lgkmcnt(" #n ")" ::: "memory")
; #define PG8_BAR __builtin_amdgcn_s_barrier()
; #define PG8_SCHED __builtin_amdgcn_sched_barrier(0)
; template <class Epi, class Sched, bool ALIGN_EPI = false, bool SP2 = false>
; __device__ __forceinline__ void gemm_phase(LAS unsigned char* lds, const Gemm g, const Sched& S, const Epi& E) {
;     ...
;             PG8_LDB(B0, 1, 0); PG8_LDB(B1, 1, 1); PG8_SCHED; PG8_LDA(At, 1, 0); PG8_STAGE(PG8_SA(0, 1), a2 + hstep, voffA);
;             PG8_WAIT_V(8); PG8_WAIT_L(0); PG8_BAR; PG8_MMA(0, 0, At, B0); PG8_MMA(0, 1, At, B1); PG8_BAR; PG8_SCHED;
	s_add_i32 s54, 0, 0x18000
	s_add_i32 s55, 0, 0x1c000
	v_add_u32_e32 v78, s54, v170
	v_add_u32_e32 v168, s55, v170
	ds_read_b128 v[66:69], v78
	ds_read_b128 v[70:73], v78 offset:1024
	ds_read_b128 v[74:77], v78 offset:2048
	ds_read_b128 v[78:81], v78 offset:3072
	ds_read_b128 v[162:165], v168
	ds_read_b128 v[182:185], v168 offset:1024
	ds_read_b128 v[186:189], v168 offset:2048
	ds_read_b128 v[190:193], v168 offset:3072
	s_add_u32 s40, s40, 0x80000
	s_addc_u32 s41, s41, 0
	s_mov_b32 m0, s35
	v_lshl_add_u64 v[232:233], s[40:41], 0, v[152:153]
	ds_read_b128 v[194:197], v176 offset:32768
	ds_read_b128 v[198:201], v176 offset:33792
	ds_read_b128 v[202:205], v176 offset:34816
	ds_read_b128 v[206:209], v176 offset:35840
	ds_read_b128 v[210:213], v176 offset:36864
	ds_read_b128 v[214:217], v176 offset:37888
	ds_read_b128 v[218:221], v176 offset:38912
	ds_read_b128 v[222:225], v176 offset:39936
	global_load_lds_dwordx4 v[232:233], off
	v_lshl_add_u64 v[232:233], s[40:41], 0, v[148:149]
	s_mov_b32 m0, s36
	s_nop 0
	global_load_lds_dwordx4 v[232:233], off
	s_waitcnt vmcnt(8)
	s_waitcnt lgkmcnt(0)
	s_barrier
	s_waitcnt lgkmcnt(0)
	v_mfma_f32_16x16x32_bf16 v[142:145], v[66:69], v[194:197], v[142:145]
	v_mfma_f32_16x16x32_bf16 v[138:141], v[74:77], v[194:197], v[138:141]
	v_mfma_f32_16x16x32_bf16 v[126:129], v[66:69], v[202:205], v[126:129]
	v_mfma_f32_16x16x32_bf16 v[122:125], v[74:77], v[202:205], v[122:125]
	v_mfma_f32_16x16x32_bf16 v[110:113], v[66:69], v[210:213], v[110:113]
	v_mfma_f32_16x16x32_bf16 v[106:109], v[74:77], v[210:213], v[106:109]
	v_mfma_f32_16x16x32_bf16 v[94:97], v[66:69], v[218:221], v[94:97]
	v_mfma_f32_16x16x32_bf16 v[90:93], v[74:77], v[218:221], v[90:93]
	v_mfma_f32_16x16x32_bf16 v[142:145], v[70:73], v[198:201], v[142:145]
	v_mfma_f32_16x16x32_bf16 v[138:141], v[78:81], v[198:201], v[138:141]
	v_mfma_f32_16x16x32_bf16 v[126:129], v[70:73], v[206:209], v[126:129]
	v_mfma_f32_16x16x32_bf16 v[122:125], v[78:81], v[206:209], v[122:125]
	v_mfma_f32_16x16x32_bf16 v[110:113], v[70:73], v[214:217], v[110:113]
	v_mfma_f32_16x16x32_bf16 v[106:109], v[78:81], v[214:217], v[106:109]
	v_mfma_f32_16x16x32_bf16 v[94:97], v[70:73], v[222:225], v[94:97]
	v_mfma_f32_16x16x32_bf16 v[90:93], v[78:81], v[222:225], v[90:93]
	v_mfma_f32_16x16x32_bf16 v[134:137], v[162:165], v[194:197], v[134:137]
	v_mfma_f32_16x16x32_bf16 v[130:133], v[186:189], v[194:197], v[130:133]
	v_mfma_f32_16x16x32_bf16 v[118:121], v[162:165], v[202:205], v[118:121]
	v_mfma_f32_16x16x32_bf16 v[114:117], v[186:189], v[202:205], v[114:117]
	v_mfma_f32_16x16x32_bf16 v[102:105], v[162:165], v[210:213], v[102:105]
	v_mfma_f32_16x16x32_bf16 v[98:101], v[186:189], v[210:213], v[98:101]
	v_mfma_f32_16x16x32_bf16 v[86:89], v[162:165], v[218:221], v[86:89]
	v_mfma_f32_16x16x32_bf16 v[82:85], v[186:189], v[218:221], v[82:85]
	v_mfma_f32_16x16x32_bf16 v[134:137], v[182:185], v[198:201], v[134:137]
	v_mfma_f32_16x16x32_bf16 v[130:133], v[190:193], v[198:201], v[130:133]
	v_mfma_f32_16x16x32_bf16 v[118:121], v[182:185], v[206:209], v[118:121]
	v_mfma_f32_16x16x32_bf16 v[114:117], v[190:193], v[206:209], v[114:117]
	v_mfma_f32_16x16x32_bf16 v[102:105], v[182:185], v[214:217], v[102:105]
	v_mfma_f32_16x16x32_bf16 v[98:101], v[190:193], v[214:217], v[98:101]
	v_mfma_f32_16x16x32_bf16 v[86:89], v[182:185], v[222:225], v[86:89]
	v_mfma_f32_16x16x32_bf16 v[82:85], v[190:193], v[222:225], v[82:85]
	s_barrier
; #define PG8_STAGE(bufoff, gbase, voff) do { _Pragma("unroll") for (int _i = 0; _i < 2; ++_i) \
;         __builtin_amdgcn_global_load_lds((const unsigned*)((const char*)(gbase) + (voff)[_i]), (LAS unsigned*)(lds + (bufoff) + ldsw + _i * 8192), 16, 0, 0); } while (0)
; #define PG8_LDA(dst, b, h) do { _Pragma("unroll") for (int m = 0; m < 4; ++m) _Pragma("unroll") for (int k = 0; k < 2; ++k) dst[m][k] = *(const LAS bf16x8*)(lds + PG8_SA(b, h) + aoff + m * 2048 + k * 1024); } while (0)
; #define PG8_MMA(ai, bj, At, Bt) do { __builtin_amdgcn_s_setprio(1); _Pragma("unroll") for (int m = 0; m < 4; ++m) _Pragma("unroll") for (int n = 0; n < 2; ++n) _Pragma("unroll") for (int k = 0; k < 2; ++k) \
;         acc[ai][bj][m][n] = __builtin_amdgcn_mfma_f32_16x16x32_bf16(Bt[n][k], At[m][k], acc[ai][bj][m][n], 0, 0, 0); __builtin_amdgcn_s_setprio(0); } while (0)
; #define PG8_WAIT_V(n) asm volatile("s_waitcnt vmcnt(" #n ")" ::: "memory")
; #define PG8_WAIT_L(n) asm volatile("s_waitcnt lgkmcnt(" #n ")" ::: "memory")
; #define PG8_BAR __builtin_amdgcn_s_barrier()
; #define PG8_SCHED __builtin_amdgcn_sched_barrier(0)
; template <class Epi, class Sched, bool ALIGN_EPI = false, bool SP2 = false>
; __device__ __forceinline__ void gemm_phase(LAS unsigned char* lds, const Gemm g, const Sched& S, const Epi& E) {
;     ...
;             PG8_LDA(At, 1, 1); PG8_STAGE(PG8_SB(1, 0), b3, voffB); PG8_STAGE(PG8_SB(1, 1), b3 + hstepB, voffB); PG8_STAGE(PG8_SA(1, 0), a3, voffA);
;             PG8_WAIT_V(8); PG8_WAIT_L(0); PG8_BAR; PG8_MMA(1, 0, At, B0); PG8_MMA(1, 1, At, B1); PG8_BAR; PG8_SCHED;
;     ...
;         if constexpr (ALIGN_EPI) { if (wr == 0) PG8_BAR; }
	s_add_i32 s40, s54, s29
	v_lshl_add_u64 v[166:167], v[166:167], 0, s[8:9]
	s_mov_b32 m0, s40
	ds_read_b128 v[194:197], v176 offset:49152
	ds_read_b128 v[198:201], v176 offset:50176
	ds_read_b128 v[202:205], v176 offset:51200
	ds_read_b128 v[206:209], v176 offset:52224
	ds_read_b128 v[210:213], v176 offset:53248
	ds_read_b128 v[214:217], v176 offset:54272
	ds_read_b128 v[218:221], v176 offset:55296
	ds_read_b128 v[222:225], v176 offset:56320
	global_load_lds_dwordx4 v[166:167], off
	s_add_i32 m0, s40, 0x2000
	s_add_u32 s22, s22, 0x80080
	v_lshl_add_u64 v[166:167], v[226:227], 0, s[8:9]
	s_addc_u32 s23, s23, 0
	s_add_i32 s40, s55, s29
	global_load_lds_dwordx4 v[166:167], off
	v_lshl_add_u64 v[166:167], s[22:23], 0, v[150:151]
	s_mov_b32 m0, s40
	s_nop 0
	global_load_lds_dwordx4 v[166:167], off
	v_lshl_add_u64 v[166:167], s[22:23], 0, v[146:147]
	s_add_i32 m0, s40, 0x2000
	s_nop 0
	global_load_lds_dwordx4 v[166:167], off
	v_lshl_add_u64 v[166:167], v[228:229], 0, s[8:9]
	s_mov_b32 m0, s45
	s_nop 0
	global_load_lds_dwordx4 v[166:167], off
	v_lshl_add_u64 v[166:167], v[230:231], 0, s[8:9]
	s_mov_b32 m0, s46
	s_nop 0
	global_load_lds_dwordx4 v[166:167], off
	s_waitcnt vmcnt(8)
	s_waitcnt lgkmcnt(0)
	s_barrier
	s_waitcnt lgkmcnt(0)
	v_mfma_f32_16x16x32_bf16 v[62:65], v[66:69], v[194:197], v[62:65]
	v_mfma_f32_16x16x32_bf16 v[58:61], v[74:77], v[194:197], v[58:61]
	v_mfma_f32_16x16x32_bf16 v[46:49], v[66:69], v[202:205], v[46:49]
	v_mfma_f32_16x16x32_bf16 v[42:45], v[74:77], v[202:205], v[42:45]
	v_mfma_f32_16x16x32_bf16 v[30:33], v[66:69], v[210:213], v[30:33]
	v_mfma_f32_16x16x32_bf16 v[26:29], v[74:77], v[210:213], v[26:29]
	v_mfma_f32_16x16x32_bf16 v[14:17], v[66:69], v[218:221], v[14:17]
	v_mfma_f32_16x16x32_bf16 v[10:13], v[74:77], v[218:221], v[10:13]
	v_mfma_f32_16x16x32_bf16 v[62:65], v[70:73], v[198:201], v[62:65]
	v_mfma_f32_16x16x32_bf16 v[58:61], v[78:81], v[198:201], v[58:61]
	v_mfma_f32_16x16x32_bf16 v[46:49], v[70:73], v[206:209], v[46:49]
	v_mfma_f32_16x16x32_bf16 v[42:45], v[78:81], v[206:209], v[42:45]
	v_mfma_f32_16x16x32_bf16 v[30:33], v[70:73], v[214:217], v[30:33]
	v_mfma_f32_16x16x32_bf16 v[26:29], v[78:81], v[214:217], v[26:29]
	v_mfma_f32_16x16x32_bf16 v[14:17], v[70:73], v[222:225], v[14:17]
	v_mfma_f32_16x16x32_bf16 v[10:13], v[78:81], v[222:225], v[10:13]
	v_mfma_f32_16x16x32_bf16 v[54:57], v[162:165], v[194:197], v[54:57]
	v_mfma_f32_16x16x32_bf16 v[50:53], v[186:189], v[194:197], v[50:53]
	v_mfma_f32_16x16x32_bf16 v[38:41], v[162:165], v[202:205], v[38:41]
	v_mfma_f32_16x16x32_bf16 v[34:37], v[186:189], v[202:205], v[34:37]
	v_mfma_f32_16x16x32_bf16 v[22:25], v[162:165], v[210:213], v[22:25]
	v_mfma_f32_16x16x32_bf16 v[18:21], v[186:189], v[210:213], v[18:21]
	v_mfma_f32_16x16x32_bf16 v[6:9], v[162:165], v[218:221], v[6:9]
	v_mfma_f32_16x16x32_bf16 v[2:5], v[186:189], v[218:221], v[2:5]
	v_mfma_f32_16x16x32_bf16 v[54:57], v[182:185], v[198:201], v[54:57]
	v_mfma_f32_16x16x32_bf16 v[50:53], v[190:193], v[198:201], v[50:53]
	v_mfma_f32_16x16x32_bf16 v[38:41], v[182:185], v[206:209], v[38:41]
	v_mfma_f32_16x16x32_bf16 v[34:37], v[190:193], v[206:209], v[34:37]
	v_mfma_f32_16x16x32_bf16 v[22:25], v[182:185], v[214:217], v[22:25]
	v_mfma_f32_16x16x32_bf16 v[18:21], v[190:193], v[214:217], v[18:21]
	v_mfma_f32_16x16x32_bf16 v[6:9], v[182:185], v[222:225], v[6:9]
	v_mfma_f32_16x16x32_bf16 v[2:5], v[190:193], v[222:225], v[2:5]
	s_barrier
	s_add_i32 s53, s53, 2
	s_add_u32 s16, s16, 0x100
	s_addc_u32 s17, s17, 0
	s_add_u32 s25, s25, 0x100
	s_addc_u32 s52, s52, 0
	s_cmp_gt_u32 s53, 29
	s_cbranch_scc0 .LBB0_1465
	s_and_b64 vcc, exec, s[10:11]
	s_cbranch_vccz .LBB0_1468
	s_barrier

; #define PG8_STAGE(bufoff, gbase, voff) do { _Pragma("unroll") for (int _i = 0; _i < 2; ++_i) \
;         __builtin_amdgcn_global_load_lds((const unsigned*)((const char*)(gbase) + (voff)[_i]), (LAS unsigned*)(lds + (bufoff) + ldsw + _i * 8192), 16, 0, 0); } while (0)
; #define PG8_LDA(dst, b, h) do { _Pragma("unroll") for (int m = 0; m < 4; ++m) _Pragma("unroll") for (int k = 0; k < 2; ++k) dst[m][k] = *(const LAS bf16x8*)(lds + PG8_SA(b, h) + aoff + m * 2048 + k * 1024); } while (0)
; #define PG8_LDB(dst, b, h) do { _Pragma("unroll") for (int n = 0; n < 2; ++n) _Pragma("unroll") for (int k = 0; k < 2; ++k) dst[n][k] = *(const LAS bf16x8*)(lds + PG8_SB(b, h) + boff + n * 2048 + k * 1024); } while (0)
; #define PG8_MMA(ai, bj, At, Bt) do { __builtin_amdgcn_s_setprio(1); _Pragma("unroll") for (int m = 0; m < 4; ++m) _Pragma("unroll") for (int n = 0; n < 2; ++n) _Pragma("unroll") for (int k = 0; k < 2; ++k) \
;         acc[ai][bj][m][n] = __builtin_amdgcn_mfma_f32_16x16x32_bf16(Bt[n][k], At[m][k], acc[ai][bj][m][n], 0, 0, 0); __builtin_amdgcn_s_setprio(0); } while (0)
; #define PG8_WAIT_V(n) asm volatile("s_waitcnt vmcnt(" #n ")" ::: "memory")
; #define PG8_WAIT_L(n) asm volatile("s_waitcnt lgkmcnt(" #n ")" ::: "memory")
; #define PG8_BAR __builtin_amdgcn_s_barrier()
; #define PG8_SCHED __builtin_amdgcn_sched_barrier(0)
; template <class Epi, class Sched, bool ALIGN_EPI = false, bool SP2 = false>
; __device__ __forceinline__ void gemm_phase(LAS unsigned char* lds, const Gemm g, const Sched& S, const Epi& E) {
;     ...
;         for (int t = 0; t < nt; t += 2) {
;             const bool last = (t == nt - 2);
;             const char* a1 = cA + (size_t)(t + 1) * kstep;
;             const char* a2 = last ? nA : cA + (size_t)(t + 2) * kstep; const char* b2 = last ? nB : cB + (size_t)(t + 2) * kstep;
;             const char* a3 = a2 + kstep; const char* b3 = b2 + kstep;
;             if (last && has_next) S.a_ready(nxt);
;             if constexpr (SP2) {
;             PG8_LDB(B0, 0, 0); PG8_LDB(B1, 0, 1); PG8_SCHED; PG8_LDA(At, 0, 0); PG8_STAGE(PG8_SA(1, 1), a1 + hstep, voffA);
;             PG8_WAIT_V(8); PG8_WAIT_L(0); PG8_BAR; PG8_MMA(0, 0, At, B0); PG8_MMA(0, 1, At, B1); PG8_BAR; PG8_SCHED;
;             PG8_LDA(At, 0, 1); PG8_STAGE(PG8_SB(0, 0), b2, voffB); PG8_STAGE(PG8_SB(0, 1), b2 + hstepB, voffB); PG8_STAGE(PG8_SA(0, 0), a2, voffA);
.LBB0_1565:
	ds_read_b128 v[144:147], v135
	ds_read_b128 v[148:151], v135 offset:1024
	ds_read_b128 v[152:155], v135 offset:2048
	ds_read_b128 v[156:159], v135 offset:3072
	ds_read_b128 v[160:163], v140
	ds_read_b128 v[164:167], v140 offset:1024
	ds_read_b128 v[168:171], v140 offset:2048
	ds_read_b128 v[172:175], v140 offset:3072
	s_add_i32 s46, s16, 2
	s_cmp_lg_u32 s35, s16
	s_cselect_b32 s16, s12, 0
	s_cselect_b32 s17, s13, 0
	s_add_u32 s18, s8, s16
	s_addc_u32 s19, s9, s17
	s_add_u32 s16, s2, s16
	s_addc_u32 s17, s3, s17
	v_lshl_add_u64 v[208:209], v[136:137], 0, s[12:13]
	s_mov_b32 m0, s36
	v_lshl_add_u64 v[208:209], v[208:209], 0, s[14:15]
	ds_read_b128 v[176:179], v141
	ds_read_b128 v[180:183], v141 offset:1024
	ds_read_b128 v[184:187], v141 offset:2048
	ds_read_b128 v[188:191], v141 offset:3072
	ds_read_b128 v[192:195], v141 offset:4096
	ds_read_b128 v[196:199], v141 offset:5120
	ds_read_b128 v[200:203], v141 offset:6144
	ds_read_b128 v[204:207], v141 offset:7168
	global_load_lds_dwordx4 v[208:209], off
	v_lshl_add_u64 v[208:209], v[138:139], 0, s[12:13]
	v_lshl_add_u64 v[208:209], v[208:209], 0, s[14:15]
	s_mov_b32 m0, s37
	s_nop 0
	global_load_lds_dwordx4 v[208:209], off
	s_waitcnt vmcnt(8)
	s_waitcnt lgkmcnt(0)
	s_barrier
	s_waitcnt lgkmcnt(0)
	v_mfma_f32_16x16x32_bf16 v[126:129], v[144:147], v[176:179], v[126:129]
	v_mfma_f32_16x16x32_bf16 v[94:97], v[152:155], v[176:179], v[94:97]
	v_mfma_f32_16x16x32_bf16 v[122:125], v[144:147], v[184:187], v[122:125]
	v_mfma_f32_16x16x32_bf16 v[90:93], v[152:155], v[184:187], v[90:93]
	v_mfma_f32_16x16x32_bf16 v[118:121], v[144:147], v[192:195], v[118:121]
	v_mfma_f32_16x16x32_bf16 v[86:89], v[152:155], v[192:195], v[86:89]
	v_mfma_f32_16x16x32_bf16 v[114:117], v[144:147], v[200:203], v[114:117]
	v_mfma_f32_16x16x32_bf16 v[82:85], v[152:155], v[200:203], v[82:85]
	v_mfma_f32_16x16x32_bf16 v[126:129], v[148:151], v[180:183], v[126:129]
	v_mfma_f32_16x16x32_bf16 v[94:97], v[156:159], v[180:183], v[94:97]
	v_mfma_f32_16x16x32_bf16 v[122:125], v[148:151], v[188:191], v[122:125]
	v_mfma_f32_16x16x32_bf16 v[90:93], v[156:159], v[188:191], v[90:93]
	v_mfma_f32_16x16x32_bf16 v[118:121], v[148:151], v[196:199], v[118:121]
	v_mfma_f32_16x16x32_bf16 v[86:89], v[156:159], v[196:199], v[86:89]
	v_mfma_f32_16x16x32_bf16 v[114:117], v[148:151], v[204:207], v[114:117]
	v_mfma_f32_16x16x32_bf16 v[82:85], v[156:159], v[204:207], v[82:85]
	v_mfma_f32_16x16x32_bf16 v[70:73], v[160:163], v[176:179], v[70:73]
	v_mfma_f32_16x16x32_bf16 v[42:45], v[168:171], v[176:179], v[42:45]
	v_mfma_f32_16x16x32_bf16 v[62:65], v[160:163], v[184:187], v[62:65]
	v_mfma_f32_16x16x32_bf16 v[34:37], v[168:171], v[184:187], v[34:37]
	v_mfma_f32_16x16x32_bf16 v[54:57], v[160:163], v[192:195], v[54:57]
	v_mfma_f32_16x16x32_bf16 v[26:29], v[168:171], v[192:195], v[26:29]
	v_mfma_f32_16x16x32_bf16 v[50:53], v[160:163], v[200:203], v[50:53]
	v_mfma_f32_16x16x32_bf16 v[18:21], v[168:171], v[200:203], v[18:21]
	v_mfma_f32_16x16x32_bf16 v[70:73], v[164:167], v[180:183], v[70:73]
	v_mfma_f32_16x16x32_bf16 v[42:45], v[172:175], v[180:183], v[42:45]
	v_mfma_f32_16x16x32_bf16 v[62:65], v[164:167], v[188:191], v[62:65]
	v_mfma_f32_16x16x32_bf16 v[34:37], v[172:175], v[188:191], v[34:37]
	v_mfma_f32_16x16x32_bf16 v[54:57], v[164:167], v[196:199], v[54:57]
	v_mfma_f32_16x16x32_bf16 v[26:29], v[172:175], v[196:199], v[26:29]
	v_mfma_f32_16x16x32_bf16 v[50:53], v[164:167], v[204:207], v[50:53]
	v_mfma_f32_16x16x32_bf16 v[18:21], v[172:175], v[204:207], v[18:21]
	s_barrier
	s_mov_b32 m0, s38
	v_lshl_add_u64 v[208:209], s[16:17], 0, v[132:133]
	s_add_u32 s48, s16, 0x160000
	ds_read_b128 v[176:179], v141 offset:16384
	ds_read_b128 v[180:183], v141 offset:17408
	ds_read_b128 v[184:187], v141 offset:18432
	ds_read_b128 v[188:191], v141 offset:19456
	ds_read_b128 v[192:195], v141 offset:20480
	ds_read_b128 v[196:199], v141 offset:21504
	ds_read_b128 v[200:203], v141 offset:22528
	ds_read_b128 v[204:207], v141 offset:23552
	global_load_lds_dwordx4 v[208:209], off
	v_lshl_add_u64 v[210:211], s[16:17], 0, v[130:131]
	s_mov_b32 m0, s39
	s_addc_u32 s49, s17, 0
	global_load_lds_dwordx4 v[210:211], off
	v_lshl_add_u64 v[212:213], s[48:49], 0, v[132:133]
	s_mov_b32 m0, s40
	v_lshl_add_u64 v[214:215], s[18:19], 0, v[130:131]
	global_load_lds_dwordx4 v[212:213], off
	v_lshl_add_u64 v[212:213], s[48:49], 0, v[130:131]
	s_mov_b32 m0, s41
	s_nop 0
	global_load_lds_dwordx4 v[212:213], off
	v_lshl_add_u64 v[212:213], s[18:19], 0, v[132:133]
	s_mov_b32 m0, s22
	s_nop 0
	global_load_lds_dwordx4 v[212:213], off
	s_mov_b32 m0, s24
	s_nop 0
	global_load_lds_dwordx4 v[214:215], off
	s_waitcnt vmcnt(8)
	s_waitcnt lgkmcnt(0)
	s_barrier
; #define PG8_STAGE(bufoff, gbase, voff) do { _Pragma("unroll") for (int _i = 0; _i < 2; ++_i) \
;         __builtin_amdgcn_global_load_lds((const unsigned*)((const char*)(gbase) + (voff)[_i]), (LAS unsigned*)(lds + (bufoff) + ldsw + _i * 8192), 16, 0, 0); } while (0)
; #define PG8_LDA(dst, b, h) do { _Pragma("unroll") for (int m = 0; m < 4; ++m) _Pragma("unroll") for (int k = 0; k < 2; ++k) dst[m][k] = *(const LAS bf16x8*)(lds + PG8_SA(b, h) + aoff + m * 2048 + k * 1024); } while (0)
; #define PG8_LDB(dst, b, h) do { _Pragma("unroll") for (int n = 0; n < 2; ++n) _Pragma("unroll") for (int k = 0; k < 2; ++k) dst[n][k] = *(const LAS bf16x8*)(lds + PG8_SB(b, h) + boff + n * 2048 + k * 1024); } while (0)
; #define PG8_MMA(ai, bj, At, Bt) do { __builtin_amdgcn_s_setprio(1); _Pragma("unroll") for (int m = 0; m < 4; ++m) _Pragma("unroll") for (int n = 0; n < 2; ++n) _Pragma("unroll") for (int k = 0; k < 2; ++k) \
;         acc[ai][bj][m][n] = __builtin_amdgcn_mfma_f32_16x16x32_bf16(Bt[n][k], At[m][k], acc[ai][bj][m][n], 0, 0, 0); __builtin_amdgcn_s_setprio(0); } while (0)
; #define PG8_BAR __builtin_amdgcn_s_barrier()
; template <class Epi, class Sched, bool ALIGN_EPI = false, bool SP2 = false>
; __device__ __forceinline__ void gemm_phase(LAS unsigned char* lds, const Gemm g, const Sched& S, const Epi& E) {
;     ...
;             if constexpr (SP2) {
;             PG8_LDB(B0, 0, 0); PG8_LDB(B1, 0, 1); PG8_SCHED; PG8_LDA(At, 0, 0); PG8_STAGE(PG8_SA(1, 1), a1 + hstep, voffA);
;             PG8_WAIT_V(8); PG8_WAIT_L(0); PG8_BAR; PG8_MMA(0, 0, At, B0); PG8_MMA(0, 1, At, B1); PG8_BAR; PG8_SCHED;
;             PG8_LDA(At, 0, 1); PG8_STAGE(PG8_SB(0, 0), b2, voffB); PG8_STAGE(PG8_SB(0, 1), b2 + hstepB, voffB); PG8_STAGE(PG8_SA(0, 0), a2, voffA);
;             PG8_WAIT_V(8); PG8_WAIT_L(0); PG8_BAR; PG8_MMA(1, 0, At, B0); PG8_MMA(1, 1, At, B1); PG8_BAR; PG8_SCHED;
;             PG8_LDB(B0, 1, 0); PG8_LDB(B1, 1, 1); PG8_SCHED; PG8_LDA(At, 1, 0); PG8_STAGE(PG8_SA(0, 1), a2 + hstep, voffA);
;             PG8_WAIT_V(8); PG8_WAIT_L(0); PG8_BAR; PG8_MMA(0, 0, At, B0); PG8_MMA(0, 1, At, B1); PG8_BAR; PG8_SCHED;
;             PG8_LDA(At, 1, 1); PG8_STAGE(PG8_SB(1, 0), b3, voffB); PG8_STAGE(PG8_SB(1, 1), b3 + hstepB, voffB); PG8_STAGE(PG8_SA(1, 0), a3, voffA);
;             PG8_WAIT_V(8); PG8_WAIT_L(0); PG8_BAR; PG8_MMA(1, 0, At, B0); PG8_MMA(1, 1, At, B1); PG8_BAR; PG8_SCHED;
	s_waitcnt lgkmcnt(0)
	v_mfma_f32_16x16x32_bf16 v[110:113], v[144:147], v[176:179], v[110:113]
	v_mfma_f32_16x16x32_bf16 v[78:81], v[152:155], v[176:179], v[78:81]
	v_mfma_f32_16x16x32_bf16 v[106:109], v[144:147], v[184:187], v[106:109]
	v_mfma_f32_16x16x32_bf16 v[74:77], v[152:155], v[184:187], v[74:77]
	v_mfma_f32_16x16x32_bf16 v[102:105], v[144:147], v[192:195], v[102:105]
	v_mfma_f32_16x16x32_bf16 v[66:69], v[152:155], v[192:195], v[66:69]
	v_mfma_f32_16x16x32_bf16 v[98:101], v[144:147], v[200:203], v[98:101]
	v_mfma_f32_16x16x32_bf16 v[58:61], v[152:155], v[200:203], v[58:61]
	v_mfma_f32_16x16x32_bf16 v[110:113], v[148:151], v[180:183], v[110:113]
	v_mfma_f32_16x16x32_bf16 v[78:81], v[156:159], v[180:183], v[78:81]
	v_mfma_f32_16x16x32_bf16 v[106:109], v[148:151], v[188:191], v[106:109]
	v_mfma_f32_16x16x32_bf16 v[74:77], v[156:159], v[188:191], v[74:77]
	v_mfma_f32_16x16x32_bf16 v[102:105], v[148:151], v[196:199], v[102:105]
	v_mfma_f32_16x16x32_bf16 v[66:69], v[156:159], v[196:199], v[66:69]
	v_mfma_f32_16x16x32_bf16 v[98:101], v[148:151], v[204:207], v[98:101]
	v_mfma_f32_16x16x32_bf16 v[58:61], v[156:159], v[204:207], v[58:61]
	v_mfma_f32_16x16x32_bf16 v[46:49], v[160:163], v[176:179], v[46:49]
	v_mfma_f32_16x16x32_bf16 v[14:17], v[168:171], v[176:179], v[14:17]
	v_mfma_f32_16x16x32_bf16 v[38:41], v[160:163], v[184:187], v[38:41]
	v_mfma_f32_16x16x32_bf16 v[10:13], v[168:171], v[184:187], v[10:13]
	v_mfma_f32_16x16x32_bf16 v[30:33], v[160:163], v[192:195], v[30:33]
	v_mfma_f32_16x16x32_bf16 v[6:9], v[168:171], v[192:195], v[6:9]
	v_mfma_f32_16x16x32_bf16 v[22:25], v[160:163], v[200:203], v[22:25]
	v_mfma_f32_16x16x32_bf16 v[2:5], v[168:171], v[200:203], v[2:5]
	v_mfma_f32_16x16x32_bf16 v[46:49], v[164:167], v[180:183], v[46:49]
	v_mfma_f32_16x16x32_bf16 v[14:17], v[172:175], v[180:183], v[14:17]
	v_mfma_f32_16x16x32_bf16 v[38:41], v[164:167], v[188:191], v[38:41]
	v_mfma_f32_16x16x32_bf16 v[10:13], v[172:175], v[188:191], v[10:13]
	v_mfma_f32_16x16x32_bf16 v[30:33], v[164:167], v[196:199], v[30:33]
	v_mfma_f32_16x16x32_bf16 v[6:9], v[172:175], v[196:199], v[6:9]
	v_mfma_f32_16x16x32_bf16 v[22:25], v[164:167], v[204:207], v[22:25]
	v_mfma_f32_16x16x32_bf16 v[2:5], v[172:175], v[204:207], v[2:5]
	s_barrier
	ds_read_b128 v[144:147], v142
	ds_read_b128 v[148:151], v142 offset:1024
	ds_read_b128 v[152:155], v142 offset:2048
	ds_read_b128 v[156:159], v142 offset:3072
	ds_read_b128 v[160:163], v143
	ds_read_b128 v[164:167], v143 offset:1024
	ds_read_b128 v[168:171], v143 offset:2048
	ds_read_b128 v[172:175], v143 offset:3072
	s_add_u32 s18, s18, 0x160000
	s_addc_u32 s19, s19, 0
	s_mov_b32 m0, s25
	v_lshl_add_u64 v[216:217], s[18:19], 0, v[132:133]
	ds_read_b128 v[176:179], v141 offset:32768
	ds_read_b128 v[180:183], v141 offset:33792
	ds_read_b128 v[184:187], v141 offset:34816
	ds_read_b128 v[188:191], v141 offset:35840
	ds_read_b128 v[192:195], v141 offset:36864
	ds_read_b128 v[196:199], v141 offset:37888
	ds_read_b128 v[200:203], v141 offset:38912
	ds_read_b128 v[204:207], v141 offset:39936
	global_load_lds_dwordx4 v[216:217], off
	v_lshl_add_u64 v[216:217], s[18:19], 0, v[130:131]
	s_mov_b32 m0, s30
	s_nop 0
	global_load_lds_dwordx4 v[216:217], off
	s_waitcnt vmcnt(8)
	s_waitcnt lgkmcnt(0)
	s_barrier
	s_waitcnt lgkmcnt(0)
	v_mfma_f32_16x16x32_bf16 v[126:129], v[144:147], v[176:179], v[126:129]
	v_mfma_f32_16x16x32_bf16 v[94:97], v[152:155], v[176:179], v[94:97]
	v_mfma_f32_16x16x32_bf16 v[122:125], v[144:147], v[184:187], v[122:125]
	v_mfma_f32_16x16x32_bf16 v[90:93], v[152:155], v[184:187], v[90:93]
	v_mfma_f32_16x16x32_bf16 v[118:121], v[144:147], v[192:195], v[118:121]
	v_mfma_f32_16x16x32_bf16 v[86:89], v[152:155], v[192:195], v[86:89]
	v_mfma_f32_16x16x32_bf16 v[114:117], v[144:147], v[200:203], v[114:117]
	v_mfma_f32_16x16x32_bf16 v[82:85], v[152:155], v[200:203], v[82:85]
	v_mfma_f32_16x16x32_bf16 v[126:129], v[148:151], v[180:183], v[126:129]
	v_mfma_f32_16x16x32_bf16 v[94:97], v[156:159], v[180:183], v[94:97]
	v_mfma_f32_16x16x32_bf16 v[122:125], v[148:151], v[188:191], v[122:125]
	v_mfma_f32_16x16x32_bf16 v[90:93], v[156:159], v[188:191], v[90:93]
	v_mfma_f32_16x16x32_bf16 v[118:121], v[148:151], v[196:199], v[118:121]
	v_mfma_f32_16x16x32_bf16 v[86:89], v[156:159], v[196:199], v[86:89]
	v_mfma_f32_16x16x32_bf16 v[114:117], v[148:151], v[204:207], v[114:117]
	v_mfma_f32_16x16x32_bf16 v[82:85], v[156:159], v[204:207], v[82:85]
	v_mfma_f32_16x16x32_bf16 v[70:73], v[160:163], v[176:179], v[70:73]
	v_mfma_f32_16x16x32_bf16 v[42:45], v[168:171], v[176:179], v[42:45]
	v_mfma_f32_16x16x32_bf16 v[62:65], v[160:163], v[184:187], v[62:65]
	v_mfma_f32_16x16x32_bf16 v[34:37], v[168:171], v[184:187], v[34:37]
	v_mfma_f32_16x16x32_bf16 v[54:57], v[160:163], v[192:195], v[54:57]
	v_mfma_f32_16x16x32_bf16 v[26:29], v[168:171], v[192:195], v[26:29]
	v_mfma_f32_16x16x32_bf16 v[50:53], v[160:163], v[200:203], v[50:53]
	v_mfma_f32_16x16x32_bf16 v[18:21], v[168:171], v[200:203], v[18:21]
	v_mfma_f32_16x16x32_bf16 v[70:73], v[164:167], v[180:183], v[70:73]
	v_mfma_f32_16x16x32_bf16 v[42:45], v[172:175], v[180:183], v[42:45]
	v_mfma_f32_16x16x32_bf16 v[62:65], v[164:167], v[188:191], v[62:65]
	v_mfma_f32_16x16x32_bf16 v[34:37], v[172:175], v[188:191], v[34:37]
	v_mfma_f32_16x16x32_bf16 v[54:57], v[164:167], v[196:199], v[54:57]
	v_mfma_f32_16x16x32_bf16 v[26:29], v[172:175], v[196:199], v[26:29]
	v_mfma_f32_16x16x32_bf16 v[50:53], v[164:167], v[204:207], v[50:53]
	v_mfma_f32_16x16x32_bf16 v[18:21], v[172:175], v[204:207], v[18:21]
	s_barrier
; #define PG8_STAGE(bufoff, gbase, voff) do { _Pragma("unroll") for (int _i = 0; _i < 2; ++_i) \
;         __builtin_amdgcn_global_load_lds((const unsigned*)((const char*)(gbase) + (voff)[_i]), (LAS unsigned*)(lds + (bufoff) + ldsw + _i * 8192), 16, 0, 0); } while (0)
; #define PG8_LDA(dst, b, h) do { _Pragma("unroll") for (int m = 0; m < 4; ++m) _Pragma("unroll") for (int k = 0; k < 2; ++k) dst[m][k] = *(const LAS bf16x8*)(lds + PG8_SA(b, h) + aoff + m * 2048 + k * 1024); } while (0)
; #define PG8_BAR __builtin_amdgcn_s_barrier()
; template <class Epi, class Sched, bool ALIGN_EPI = false, bool SP2 = false>
; __device__ __forceinline__ void gemm_phase(LAS unsigned char* lds, const Gemm g, const Sched& S, const Epi& E) {
;     ...
;         for (int t = 0; t < nt; t += 2) {
;             const bool last = (t == nt - 2);
;             const char* a1 = cA + (size_t)(t + 1) * kstep;
;             const char* a2 = last ? nA : cA + (size_t)(t + 2) * kstep; const char* b2 = last ? nB : cB + (size_t)(t + 2) * kstep;
;             const char* a3 = a2 + kstep; const char* b3 = b2 + kstep;
;             if (last && has_next) S.a_ready(nxt);
;             if constexpr (SP2) {
;             PG8_LDB(B0, 0, 0); PG8_LDB(B1, 0, 1); PG8_SCHED; PG8_LDA(At, 0, 0); PG8_STAGE(PG8_SA(1, 1), a1 + hstep, voffA);
;             PG8_WAIT_V(8); PG8_WAIT_L(0); PG8_BAR; PG8_MMA(0, 0, At, B0); PG8_MMA(0, 1, At, B1); PG8_BAR; PG8_SCHED;
;             PG8_LDA(At, 0, 1); PG8_STAGE(PG8_SB(0, 0), b2, voffB); PG8_STAGE(PG8_SB(0, 1), b2 + hstepB, voffB); PG8_STAGE(PG8_SA(0, 0), a2, voffA);
;             PG8_WAIT_V(8); PG8_WAIT_L(0); PG8_BAR; PG8_MMA(1, 0, At, B0); PG8_MMA(1, 1, At, B1); PG8_BAR; PG8_SCHED;
;             PG8_LDB(B0, 1, 0); PG8_LDB(B1, 1, 1); PG8_SCHED; PG8_LDA(At, 1, 0); PG8_STAGE(PG8_SA(0, 1), a2 + hstep, voffA);
;             PG8_WAIT_V(8); PG8_WAIT_L(0); PG8_BAR; PG8_MMA(0, 0, At, B0); PG8_MMA(0, 1, At, B1); PG8_BAR; PG8_SCHED;
;             PG8_LDA(At, 1, 1); PG8_STAGE(PG8_SB(1, 0), b3, voffB); PG8_STAGE(PG8_SB(1, 1), b3 + hstepB, voffB); PG8_STAGE(PG8_SA(1, 0), a3, voffA);
;             PG8_WAIT_V(8); PG8_WAIT_L(0); PG8_BAR; PG8_MMA(1, 0, At, B0); PG8_MMA(1, 1, At, B1); PG8_BAR; PG8_SCHED;
;     ...
;         if constexpr (ALIGN_EPI) { if (wr == 0) PG8_BAR; }
;         if constexpr (!Epi::AFTER_DRAIN) { E(acc, cur, wr, wc, fr, fq); S.done(cur); }
;         if (!has_next) break;
	s_mov_b32 m0, s42
	v_lshl_add_u64 v[208:209], v[208:209], 0, s[10:11]
	s_add_u32 s16, s16, 0x160080
	ds_read_b128 v[176:179], v141 offset:49152
	ds_read_b128 v[180:183], v141 offset:50176
	ds_read_b128 v[184:187], v141 offset:51200
	ds_read_b128 v[188:191], v141 offset:52224
	ds_read_b128 v[192:195], v141 offset:53248
	ds_read_b128 v[196:199], v141 offset:54272
	ds_read_b128 v[200:203], v141 offset:55296
	ds_read_b128 v[204:207], v141 offset:56320
	global_load_lds_dwordx4 v[208:209], off
	v_lshl_add_u64 v[208:209], v[210:211], 0, s[10:11]
	s_mov_b32 m0, s43
	s_addc_u32 s17, s17, 0
	global_load_lds_dwordx4 v[208:209], off
	v_lshl_add_u64 v[208:209], s[16:17], 0, v[132:133]
	s_mov_b32 m0, s44
	s_nop 0
	global_load_lds_dwordx4 v[208:209], off
	v_lshl_add_u64 v[208:209], s[16:17], 0, v[130:131]
	s_mov_b32 m0, s45
	s_nop 0
	global_load_lds_dwordx4 v[208:209], off
	v_lshl_add_u64 v[208:209], v[212:213], 0, s[10:11]
	s_mov_b32 m0, s33
	s_nop 0
	global_load_lds_dwordx4 v[208:209], off
	v_lshl_add_u64 v[208:209], v[214:215], 0, s[10:11]
	s_mov_b32 m0, s34
	s_nop 0
	global_load_lds_dwordx4 v[208:209], off
	s_waitcnt vmcnt(8)
	s_waitcnt lgkmcnt(0)
	s_barrier
	s_waitcnt lgkmcnt(0)
	v_mfma_f32_16x16x32_bf16 v[110:113], v[144:147], v[176:179], v[110:113]
	v_mfma_f32_16x16x32_bf16 v[78:81], v[152:155], v[176:179], v[78:81]
	v_mfma_f32_16x16x32_bf16 v[106:109], v[144:147], v[184:187], v[106:109]
	v_mfma_f32_16x16x32_bf16 v[74:77], v[152:155], v[184:187], v[74:77]
	v_mfma_f32_16x16x32_bf16 v[102:105], v[144:147], v[192:195], v[102:105]
	v_mfma_f32_16x16x32_bf16 v[66:69], v[152:155], v[192:195], v[66:69]
	v_mfma_f32_16x16x32_bf16 v[98:101], v[144:147], v[200:203], v[98:101]
	v_mfma_f32_16x16x32_bf16 v[58:61], v[152:155], v[200:203], v[58:61]
	v_mfma_f32_16x16x32_bf16 v[110:113], v[148:151], v[180:183], v[110:113]
	v_mfma_f32_16x16x32_bf16 v[78:81], v[156:159], v[180:183], v[78:81]
	v_mfma_f32_16x16x32_bf16 v[106:109], v[148:151], v[188:191], v[106:109]
	v_mfma_f32_16x16x32_bf16 v[74:77], v[156:159], v[188:191], v[74:77]
	v_mfma_f32_16x16x32_bf16 v[102:105], v[148:151], v[196:199], v[102:105]
	v_mfma_f32_16x16x32_bf16 v[66:69], v[156:159], v[196:199], v[66:69]
	v_mfma_f32_16x16x32_bf16 v[98:101], v[148:151], v[204:207], v[98:101]
	v_mfma_f32_16x16x32_bf16 v[58:61], v[156:159], v[204:207], v[58:61]
	v_mfma_f32_16x16x32_bf16 v[46:49], v[160:163], v[176:179], v[46:49]
	v_mfma_f32_16x16x32_bf16 v[14:17], v[168:171], v[176:179], v[14:17]
	v_mfma_f32_16x16x32_bf16 v[38:41], v[160:163], v[184:187], v[38:41]
	v_mfma_f32_16x16x32_bf16 v[10:13], v[168:171], v[184:187], v[10:13]
	v_mfma_f32_16x16x32_bf16 v[30:33], v[160:163], v[192:195], v[30:33]
	v_mfma_f32_16x16x32_bf16 v[6:9], v[168:171], v[192:195], v[6:9]
	v_mfma_f32_16x16x32_bf16 v[22:25], v[160:163], v[200:203], v[22:25]
	v_mfma_f32_16x16x32_bf16 v[2:5], v[168:171], v[200:203], v[2:5]
	v_mfma_f32_16x16x32_bf16 v[46:49], v[164:167], v[180:183], v[46:49]
	v_mfma_f32_16x16x32_bf16 v[14:17], v[172:175], v[180:183], v[14:17]
	v_mfma_f32_16x16x32_bf16 v[38:41], v[164:167], v[188:191], v[38:41]
	v_mfma_f32_16x16x32_bf16 v[10:13], v[172:175], v[188:191], v[10:13]
	v_mfma_f32_16x16x32_bf16 v[30:33], v[164:167], v[196:199], v[30:33]
	v_mfma_f32_16x16x32_bf16 v[6:9], v[172:175], v[196:199], v[6:9]
	v_mfma_f32_16x16x32_bf16 v[22:25], v[164:167], v[204:207], v[22:25]
	v_mfma_f32_16x16x32_bf16 v[2:5], v[172:175], v[204:207], v[2:5]
	s_barrier
	s_add_u32 s12, s12, 0x100
	s_addc_u32 s13, s13, 0
	s_cmp_ge_u32 s46, s31
	s_mov_b32 s16, s46
	s_cbranch_scc0 .LBB0_1565
	s_cmpk_lt_u32 s21, 0x100
	s_cbranch_scc0 .LBB0_1568
	s_barrier

;     __device__ bool next(int i, Unit& u) const { if (i != 0 || c >= 128) return false; const int t = c >> 2; u.pm = t & 3; u.pn = t >> 2; u.koff = koff_bytes; u.q = c & 3; return true; }
; #define PG8_STAGE(bufoff, gbase, voff) do { _Pragma("unroll") for (int _i = 0; _i < 2; ++_i) \
;         __builtin_amdgcn_global_load_lds((const unsigned*)((const char*)(gbase) + (voff)[_i]), (LAS unsigned*)(lds + (bufoff) + ldsw + _i * 8192), 16, 0, 0); } while (0)
; #define PG8_LDA(dst, b, h) do { _Pragma("unroll") for (int m = 0; m < 4; ++m) _Pragma("unroll") for (int k = 0; k < 2; ++k) dst[m][k] = *(const LAS bf16x8*)(lds + PG8_SA(b, h) + aoff + m * 2048 + k * 1024); } while (0)
; #define PG8_LDB(dst, b, h) do { _Pragma("unroll") for (int n = 0; n < 2; ++n) _Pragma("unroll") for (int k = 0; k < 2; ++k) dst[n][k] = *(const LAS bf16x8*)(lds + PG8_SB(b, h) + boff + n * 2048 + k * 1024); } while (0)
; #define PG8_WAIT_V(n) asm volatile("s_waitcnt vmcnt(" #n ")" ::: "memory")
; template <class Epi, class Sched, bool ALIGN_EPI = false, bool SP2 = false>
; __device__ __forceinline__ void gemm_phase(LAS unsigned char* lds, const Gemm g, const Sched& S, const Epi& E) {
;     ...
;         const bool has_next = S.next(ui + 1, nxt);
;         const char* nA = has_next ? (const char*)g.A + (size_t)nxt.pm * tstep + nxt.koff : cA; const char* nB = has_next ? (const char*)g.Bt + (size_t)nxt.pn * tstep + nxt.koff : cB;
;         for (int t = 0; t < nt; t += 2) {
;             const bool last = (t == nt - 2);
;             const char* a1 = cA + (size_t)(t + 1) * kstep;
;             const char* a2 = last ? nA : cA + (size_t)(t + 2) * kstep; const char* b2 = last ? nB : cB + (size_t)(t + 2) * kstep;
;             const char* a3 = a2 + kstep; const char* b3 = b2 + kstep;
;             if (last && has_next) S.a_ready(nxt);
;             if constexpr (SP2) {
;             PG8_LDB(B0, 0, 0); PG8_LDB(B1, 0, 1); PG8_SCHED; PG8_LDA(At, 0, 0); PG8_STAGE(PG8_SA(1, 1), a1 + hstep, voffA);
;             PG8_WAIT_V(8); PG8_WAIT_L(0); PG8_BAR; PG8_MMA(0, 0, At, B0); PG8_MMA(0, 1, At, B1); PG8_BAR; PG8_SCHED;
;             PG8_LDA(At, 0, 1); PG8_STAGE(PG8_SB(0, 0), b2, voffB); PG8_STAGE(PG8_SB(0, 1), b2 + hstepB, voffB); PG8_STAGE(PG8_SA(0, 0), a2, voffA);
;             PG8_WAIT_V(8); PG8_WAIT_L(0); PG8_BAR; PG8_MMA(1, 0, At, B0); PG8_MMA(1, 1, At, B1); PG8_BAR; PG8_SCHED;
.LBB0_1594:
	s_add_u32 s9, s20, 0x100
	s_addc_u32 s24, s21, 0
	s_mov_b32 s25, -2
	s_waitcnt vmcnt(0)
	ds_read_b128 v[130:133], v196
	ds_read_b128 v[134:137], v196 offset:1024
	ds_read_b128 v[138:141], v196 offset:2048
	ds_read_b128 v[142:145], v196 offset:3072
	ds_read_b128 v[166:169], v197
	ds_read_b128 v[170:173], v197 offset:1024
	ds_read_b128 v[174:177], v197 offset:2048
	ds_read_b128 v[178:181], v197 offset:3072
	s_add_u32 s20, s16, 0x100
	s_addc_u32 s21, s17, 0
	s_cmpk_eq_i32 s25, 0x54
	s_cselect_b32 s47, s3, s21
	s_cselect_b32 s46, s2, s20
	s_cselect_b32 s23, s19, s24
	s_cselect_b32 s22, s18, s9
	v_lshl_add_u64 v[190:191], s[16:17], 0, v[158:159]
	s_add_i32 m0, s31, 0xc000
	ds_read_b128 v[182:185], v198
	ds_read_b128 v[186:189], v198 offset:1024
	ds_read_b128 v[202:205], v198 offset:2048
	ds_read_b128 v[206:209], v198 offset:3072
	ds_read_b128 v[210:213], v198 offset:4096
	ds_read_b128 v[214:217], v198 offset:5120
	ds_read_b128 v[218:221], v198 offset:6144
	ds_read_b128 v[222:225], v198 offset:7168
	global_load_lds_dwordx4 v[190:191], off
	v_lshl_add_u64 v[190:191], s[16:17], 0, v[160:161]
	s_add_i32 m0, s31, 0xe000
	s_nop 0
	global_load_lds_dwordx4 v[190:191], off
	s_waitcnt lgkmcnt(0)
	s_barrier
	s_waitcnt lgkmcnt(0)
	v_mfma_f32_16x16x32_bf16 v[126:129], v[130:133], v[182:185], 0
	v_mfma_f32_16x16x32_bf16 v[122:125], v[138:141], v[182:185], 0
	v_mfma_f32_16x16x32_bf16 v[110:113], v[130:133], v[202:205], 0
	v_mfma_f32_16x16x32_bf16 v[106:109], v[138:141], v[202:205], 0
	v_mfma_f32_16x16x32_bf16 v[94:97], v[130:133], v[210:213], 0
	v_mfma_f32_16x16x32_bf16 v[90:93], v[138:141], v[210:213], 0
	v_mfma_f32_16x16x32_bf16 v[78:81], v[130:133], v[218:221], 0
	v_mfma_f32_16x16x32_bf16 v[74:77], v[138:141], v[218:221], 0
	v_mfma_f32_16x16x32_bf16 v[126:129], v[134:137], v[186:189], v[126:129]
	v_mfma_f32_16x16x32_bf16 v[122:125], v[142:145], v[186:189], v[122:125]
	v_mfma_f32_16x16x32_bf16 v[110:113], v[134:137], v[206:209], v[110:113]
	v_mfma_f32_16x16x32_bf16 v[106:109], v[142:145], v[206:209], v[106:109]
	v_mfma_f32_16x16x32_bf16 v[94:97], v[134:137], v[214:217], v[94:97]
	v_mfma_f32_16x16x32_bf16 v[90:93], v[142:145], v[214:217], v[90:93]
	v_mfma_f32_16x16x32_bf16 v[78:81], v[134:137], v[222:225], v[78:81]
	v_mfma_f32_16x16x32_bf16 v[74:77], v[142:145], v[222:225], v[74:77]
	v_mfma_f32_16x16x32_bf16 v[118:121], v[166:169], v[182:185], 0
	v_mfma_f32_16x16x32_bf16 v[114:117], v[174:177], v[182:185], 0
	v_mfma_f32_16x16x32_bf16 v[102:105], v[166:169], v[202:205], 0
	v_mfma_f32_16x16x32_bf16 v[98:101], v[174:177], v[202:205], 0
	v_mfma_f32_16x16x32_bf16 v[86:89], v[166:169], v[210:213], 0
	v_mfma_f32_16x16x32_bf16 v[82:85], v[174:177], v[210:213], 0
	v_mfma_f32_16x16x32_bf16 v[70:73], v[166:169], v[218:221], 0
	v_mfma_f32_16x16x32_bf16 v[66:69], v[174:177], v[218:221], 0
	v_mfma_f32_16x16x32_bf16 v[118:121], v[170:173], v[186:189], v[118:121]
	v_mfma_f32_16x16x32_bf16 v[114:117], v[178:181], v[186:189], v[114:117]
	v_mfma_f32_16x16x32_bf16 v[102:105], v[170:173], v[206:209], v[102:105]
	v_mfma_f32_16x16x32_bf16 v[98:101], v[178:181], v[206:209], v[98:101]
	v_mfma_f32_16x16x32_bf16 v[86:89], v[170:173], v[214:217], v[86:89]
	v_mfma_f32_16x16x32_bf16 v[82:85], v[178:181], v[214:217], v[82:85]
	v_mfma_f32_16x16x32_bf16 v[70:73], v[170:173], v[222:225], v[70:73]
	v_mfma_f32_16x16x32_bf16 v[66:69], v[178:181], v[222:225], v[66:69]
	s_barrier
	s_add_i32 s16, s52, s30
	v_lshl_add_u64 v[190:191], s[22:23], 0, v[148:149]
	s_mov_b32 m0, s16
	ds_read_b128 v[182:185], v198 offset:16384
	ds_read_b128 v[186:189], v198 offset:17408
	ds_read_b128 v[202:205], v198 offset:18432
	ds_read_b128 v[206:209], v198 offset:19456
	ds_read_b128 v[210:213], v198 offset:20480
	ds_read_b128 v[214:217], v198 offset:21504
	ds_read_b128 v[218:221], v198 offset:22528
	ds_read_b128 v[222:225], v198 offset:23552
	global_load_lds_dwordx4 v[190:191], off
	s_add_i32 m0, s16, 0x2000
	s_add_u32 s16, s22, 0x58000
	v_lshl_add_u64 v[226:227], s[22:23], 0, v[152:153]
	s_addc_u32 s17, s23, 0
	s_add_i32 s56, s53, s30
	global_load_lds_dwordx4 v[226:227], off
	v_lshl_add_u64 v[228:229], s[16:17], 0, v[148:149]
	s_mov_b32 m0, s56
	v_lshl_add_u64 v[230:231], s[46:47], 0, v[150:151]
	global_load_lds_dwordx4 v[228:229], off
	v_lshl_add_u64 v[228:229], s[16:17], 0, v[152:153]
	s_add_i32 m0, s56, 0x2000
	s_nop 0
	global_load_lds_dwordx4 v[228:229], off
	v_lshl_add_u64 v[228:229], s[46:47], 0, v[146:147]
	s_mov_b32 m0, s31
	s_nop 0
	global_load_lds_dwordx4 v[228:229], off
	s_mov_b32 m0, s33
	s_nop 0
	global_load_lds_dwordx4 v[230:231], off
	s_waitcnt lgkmcnt(0)
	s_barrier
; #define PG8_STAGE(bufoff, gbase, voff) do { _Pragma("unroll") for (int _i = 0; _i < 2; ++_i) \
;         __builtin_amdgcn_global_load_lds((const unsigned*)((const char*)(gbase) + (voff)[_i]), (LAS unsigned*)(lds + (bufoff) + ldsw + _i * 8192), 16, 0, 0); } while (0)
; #define PG8_LDA(dst, b, h) do { _Pragma("unroll") for (int m = 0; m < 4; ++m) _Pragma("unroll") for (int k = 0; k < 2; ++k) dst[m][k] = *(const LAS bf16x8*)(lds + PG8_SA(b, h) + aoff + m * 2048 + k * 1024); } while (0)
; #define PG8_LDB(dst, b, h) do { _Pragma("unroll") for (int n = 0; n < 2; ++n) _Pragma("unroll") for (int k = 0; k < 2; ++k) dst[n][k] = *(const LAS bf16x8*)(lds + PG8_SB(b, h) + boff + n * 2048 + k * 1024); } while (0)
; #define PG8_MMA(ai, bj, At, Bt) do { __builtin_amdgcn_s_setprio(1); _Pragma("unroll") for (int m = 0; m < 4; ++m) _Pragma("unroll") for (int n = 0; n < 2; ++n) _Pragma("unroll") for (int k = 0; k < 2; ++k) \
;         acc[ai][bj][m][n] = __builtin_amdgcn_mfma_f32_16x16x32_bf16(Bt[n][k], At[m][k], acc[ai][bj][m][n], 0, 0, 0); __builtin_amdgcn_s_setprio(0); } while (0)
; #define PG8_WAIT_V(n) asm volatile("s_waitcnt vmcnt(" #n ")" ::: "memory")
; #define PG8_WAIT_L(n) asm volatile("s_waitcnt lgkmcnt(" #n ")" ::: "memory")
; #define PG8_BAR __builtin_amdgcn_s_barrier()
; #define PG8_SCHED __builtin_amdgcn_sched_barrier(0)
; template <class Epi, class Sched, bool ALIGN_EPI = false, bool SP2 = false>
; __device__ __forceinline__ void gemm_phase(LAS unsigned char* lds, const Gemm g, const Sched& S, const Epi& E) {
;     ...
;             PG8_LDB(B0, 0, 0); PG8_LDB(B1, 0, 1); PG8_SCHED; PG8_LDA(At, 0, 0); PG8_STAGE(PG8_SA(1, 1), a1 + hstep, voffA);
;             PG8_WAIT_V(8); PG8_WAIT_L(0); PG8_BAR; PG8_MMA(0, 0, At, B0); PG8_MMA(0, 1, At, B1); PG8_BAR; PG8_SCHED;
;             PG8_LDA(At, 0, 1); PG8_STAGE(PG8_SB(0, 0), b2, voffB); PG8_STAGE(PG8_SB(0, 1), b2 + hstepB, voffB); PG8_STAGE(PG8_SA(0, 0), a2, voffA);
;             PG8_WAIT_V(8); PG8_WAIT_L(0); PG8_BAR; PG8_MMA(1, 0, At, B0); PG8_MMA(1, 1, At, B1); PG8_BAR; PG8_SCHED;
;             PG8_LDB(B0, 1, 0); PG8_LDB(B1, 1, 1); PG8_SCHED; PG8_LDA(At, 1, 0); PG8_STAGE(PG8_SA(0, 1), a2 + hstep, voffA);
;             PG8_WAIT_V(8); PG8_WAIT_L(0); PG8_BAR; PG8_MMA(0, 0, At, B0); PG8_MMA(0, 1, At, B1); PG8_BAR; PG8_SCHED;
	s_waitcnt lgkmcnt(0)
	v_mfma_f32_16x16x32_bf16 v[62:65], v[130:133], v[182:185], 0
	v_mfma_f32_16x16x32_bf16 v[58:61], v[138:141], v[182:185], 0
	v_mfma_f32_16x16x32_bf16 v[46:49], v[130:133], v[202:205], 0
	v_mfma_f32_16x16x32_bf16 v[42:45], v[138:141], v[202:205], 0
	v_mfma_f32_16x16x32_bf16 v[30:33], v[130:133], v[210:213], 0
	v_mfma_f32_16x16x32_bf16 v[26:29], v[138:141], v[210:213], 0
	v_mfma_f32_16x16x32_bf16 v[14:17], v[130:133], v[218:221], 0
	v_mfma_f32_16x16x32_bf16 v[10:13], v[138:141], v[218:221], 0
	v_mfma_f32_16x16x32_bf16 v[62:65], v[134:137], v[186:189], v[62:65]
	v_mfma_f32_16x16x32_bf16 v[58:61], v[142:145], v[186:189], v[58:61]
	v_mfma_f32_16x16x32_bf16 v[46:49], v[134:137], v[206:209], v[46:49]
	v_mfma_f32_16x16x32_bf16 v[42:45], v[142:145], v[206:209], v[42:45]
	v_mfma_f32_16x16x32_bf16 v[30:33], v[134:137], v[214:217], v[30:33]
	v_mfma_f32_16x16x32_bf16 v[26:29], v[142:145], v[214:217], v[26:29]
	v_mfma_f32_16x16x32_bf16 v[14:17], v[134:137], v[222:225], v[14:17]
	v_mfma_f32_16x16x32_bf16 v[10:13], v[142:145], v[222:225], v[10:13]
	v_mfma_f32_16x16x32_bf16 v[54:57], v[166:169], v[182:185], 0
	v_mfma_f32_16x16x32_bf16 v[50:53], v[174:177], v[182:185], 0
	v_mfma_f32_16x16x32_bf16 v[38:41], v[166:169], v[202:205], 0
	v_mfma_f32_16x16x32_bf16 v[34:37], v[174:177], v[202:205], 0
	v_mfma_f32_16x16x32_bf16 v[22:25], v[166:169], v[210:213], 0
	v_mfma_f32_16x16x32_bf16 v[18:21], v[174:177], v[210:213], 0
	v_mfma_f32_16x16x32_bf16 v[6:9], v[166:169], v[218:221], 0
	v_mfma_f32_16x16x32_bf16 v[2:5], v[174:177], v[218:221], 0
	v_mfma_f32_16x16x32_bf16 v[54:57], v[170:173], v[186:189], v[54:57]
	v_mfma_f32_16x16x32_bf16 v[50:53], v[178:181], v[186:189], v[50:53]
	v_mfma_f32_16x16x32_bf16 v[38:41], v[170:173], v[206:209], v[38:41]
	v_mfma_f32_16x16x32_bf16 v[34:37], v[178:181], v[206:209], v[34:37]
	v_mfma_f32_16x16x32_bf16 v[22:25], v[170:173], v[214:217], v[22:25]
	v_mfma_f32_16x16x32_bf16 v[18:21], v[178:181], v[214:217], v[18:21]
	v_mfma_f32_16x16x32_bf16 v[6:9], v[170:173], v[222:225], v[6:9]
	v_mfma_f32_16x16x32_bf16 v[2:5], v[178:181], v[222:225], v[2:5]
	s_barrier
	s_add_i32 s56, 0, 0x18000
	s_add_i32 s57, 0, 0x1c000
	v_add_u32_e32 v142, s56, v1
	v_add_u32_e32 v154, s57, v1
	ds_read_b128 v[130:133], v142
	ds_read_b128 v[134:137], v142 offset:1024
	ds_read_b128 v[138:141], v142 offset:2048
	ds_read_b128 v[142:145], v142 offset:3072
	ds_read_b128 v[166:169], v154
	ds_read_b128 v[170:173], v154 offset:1024
	ds_read_b128 v[174:177], v154 offset:2048
	ds_read_b128 v[178:181], v154 offset:3072
	s_add_u32 s16, s46, 0x160000
	s_addc_u32 s17, s47, 0
	s_mov_b32 m0, s34
	v_lshl_add_u64 v[232:233], s[16:17], 0, v[146:147]
	ds_read_b128 v[182:185], v198 offset:32768
	ds_read_b128 v[186:189], v198 offset:33792
	ds_read_b128 v[202:205], v198 offset:34816
	ds_read_b128 v[206:209], v198 offset:35840
	ds_read_b128 v[210:213], v198 offset:36864
	ds_read_b128 v[214:217], v198 offset:37888
	ds_read_b128 v[218:221], v198 offset:38912
	ds_read_b128 v[222:225], v198 offset:39936
	global_load_lds_dwordx4 v[232:233], off
	v_lshl_add_u64 v[232:233], s[16:17], 0, v[150:151]
	s_mov_b32 m0, s35
	s_nop 0
	global_load_lds_dwordx4 v[232:233], off
	s_waitcnt vmcnt(8)
	s_waitcnt lgkmcnt(0)
	s_barrier
	s_waitcnt lgkmcnt(0)
	v_mfma_f32_16x16x32_bf16 v[126:129], v[130:133], v[182:185], v[126:129]
	v_mfma_f32_16x16x32_bf16 v[122:125], v[138:141], v[182:185], v[122:125]
	v_mfma_f32_16x16x32_bf16 v[110:113], v[130:133], v[202:205], v[110:113]
	v_mfma_f32_16x16x32_bf16 v[106:109], v[138:141], v[202:205], v[106:109]
	v_mfma_f32_16x16x32_bf16 v[94:97], v[130:133], v[210:213], v[94:97]
	v_mfma_f32_16x16x32_bf16 v[90:93], v[138:141], v[210:213], v[90:93]
	v_mfma_f32_16x16x32_bf16 v[78:81], v[130:133], v[218:221], v[78:81]
	v_mfma_f32_16x16x32_bf16 v[74:77], v[138:141], v[218:221], v[74:77]
	v_mfma_f32_16x16x32_bf16 v[126:129], v[134:137], v[186:189], v[126:129]
	v_mfma_f32_16x16x32_bf16 v[122:125], v[142:145], v[186:189], v[122:125]
	v_mfma_f32_16x16x32_bf16 v[110:113], v[134:137], v[206:209], v[110:113]
	v_mfma_f32_16x16x32_bf16 v[106:109], v[142:145], v[206:209], v[106:109]
	v_mfma_f32_16x16x32_bf16 v[94:97], v[134:137], v[214:217], v[94:97]
	v_mfma_f32_16x16x32_bf16 v[90:93], v[142:145], v[214:217], v[90:93]
	v_mfma_f32_16x16x32_bf16 v[78:81], v[134:137], v[222:225], v[78:81]
	v_mfma_f32_16x16x32_bf16 v[74:77], v[142:145], v[222:225], v[74:77]
	v_mfma_f32_16x16x32_bf16 v[118:121], v[166:169], v[182:185], v[118:121]
	v_mfma_f32_16x16x32_bf16 v[114:117], v[174:177], v[182:185], v[114:117]
	v_mfma_f32_16x16x32_bf16 v[102:105], v[166:169], v[202:205], v[102:105]
	v_mfma_f32_16x16x32_bf16 v[98:101], v[174:177], v[202:205], v[98:101]
	v_mfma_f32_16x16x32_bf16 v[86:89], v[166:169], v[210:213], v[86:89]
	v_mfma_f32_16x16x32_bf16 v[82:85], v[174:177], v[210:213], v[82:85]
	v_mfma_f32_16x16x32_bf16 v[70:73], v[166:169], v[218:221], v[70:73]
	v_mfma_f32_16x16x32_bf16 v[66:69], v[174:177], v[218:221], v[66:69]
	v_mfma_f32_16x16x32_bf16 v[118:121], v[170:173], v[186:189], v[118:121]
	v_mfma_f32_16x16x32_bf16 v[114:117], v[178:181], v[186:189], v[114:117]
	v_mfma_f32_16x16x32_bf16 v[102:105], v[170:173], v[206:209], v[102:105]
	v_mfma_f32_16x16x32_bf16 v[98:101], v[178:181], v[206:209], v[98:101]
	v_mfma_f32_16x16x32_bf16 v[86:89], v[170:173], v[214:217], v[86:89]
	v_mfma_f32_16x16x32_bf16 v[82:85], v[178:181], v[214:217], v[82:85]
	v_mfma_f32_16x16x32_bf16 v[70:73], v[170:173], v[222:225], v[70:73]
	v_mfma_f32_16x16x32_bf16 v[66:69], v[178:181], v[222:225], v[66:69]
	s_barrier
; #define PG8_STAGE(bufoff, gbase, voff) do { _Pragma("unroll") for (int _i = 0; _i < 2; ++_i) \
;         __builtin_amdgcn_global_load_lds((const unsigned*)((const char*)(gbase) + (voff)[_i]), (LAS unsigned*)(lds + (bufoff) + ldsw + _i * 8192), 16, 0, 0); } while (0)
; #define PG8_LDA(dst, b, h) do { _Pragma("unroll") for (int m = 0; m < 4; ++m) _Pragma("unroll") for (int k = 0; k < 2; ++k) dst[m][k] = *(const LAS bf16x8*)(lds + PG8_SA(b, h) + aoff + m * 2048 + k * 1024); } while (0)
; #define PG8_LDB(dst, b, h) do { _Pragma("unroll") for (int n = 0; n < 2; ++n) _Pragma("unroll") for (int k = 0; k < 2; ++k) dst[n][k] = *(const LAS bf16x8*)(lds + PG8_SB(b, h) + boff + n * 2048 + k * 1024); } while (0)
; #define PG8_MMA(ai, bj, At, Bt) do { __builtin_amdgcn_s_setprio(1); _Pragma("unroll") for (int m = 0; m < 4; ++m) _Pragma("unroll") for (int n = 0; n < 2; ++n) _Pragma("unroll") for (int k = 0; k < 2; ++k) \
;         acc[ai][bj][m][n] = __builtin_amdgcn_mfma_f32_16x16x32_bf16(Bt[n][k], At[m][k], acc[ai][bj][m][n], 0, 0, 0); __builtin_amdgcn_s_setprio(0); } while (0)
; #define PG8_WAIT_V(n) asm volatile("s_waitcnt vmcnt(" #n ")" ::: "memory")
; #define PG8_WAIT_L(n) asm volatile("s_waitcnt lgkmcnt(" #n ")" ::: "memory")
; #define PG8_BAR __builtin_amdgcn_s_barrier()
; #define PG8_SCHED __builtin_amdgcn_sched_barrier(0)
; template <class Epi, class Sched, bool ALIGN_EPI = false, bool SP2 = false>
; __device__ __forceinline__ void gemm_phase(LAS unsigned char* lds, const Gemm g, const Sched& S, const Epi& E) {
;     ...
;             PG8_LDB(B0, 0, 0); PG8_LDB(B1, 0, 1); PG8_SCHED; PG8_LDA(At, 0, 0); PG8_STAGE(PG8_SA(1, 1), a1 + hstep, voffA);
;             PG8_WAIT_V(8); PG8_WAIT_L(0); PG8_BAR; PG8_MMA(0, 0, At, B0); PG8_MMA(0, 1, At, B1); PG8_BAR; PG8_SCHED;
;     ...
;             PG8_LDA(At, 1, 1); PG8_STAGE(PG8_SB(1, 0), b3, voffB); PG8_STAGE(PG8_SB(1, 1), b3 + hstepB, voffB); PG8_STAGE(PG8_SA(1, 0), a3, voffA);
;             PG8_WAIT_V(8); PG8_WAIT_L(0); PG8_BAR; PG8_MMA(1, 0, At, B0); PG8_MMA(1, 1, At, B1); PG8_BAR; PG8_SCHED;
	s_add_i32 s16, s56, s30
	v_lshl_add_u64 v[190:191], v[190:191], 0, s[12:13]
	s_mov_b32 m0, s16
	ds_read_b128 v[182:185], v198 offset:49152
	ds_read_b128 v[186:189], v198 offset:50176
	ds_read_b128 v[202:205], v198 offset:51200
	ds_read_b128 v[206:209], v198 offset:52224
	ds_read_b128 v[210:213], v198 offset:53248
	ds_read_b128 v[214:217], v198 offset:54272
	ds_read_b128 v[218:221], v198 offset:55296
	ds_read_b128 v[222:225], v198 offset:56320
	global_load_lds_dwordx4 v[190:191], off
	s_add_i32 m0, s16, 0x2000
	s_add_u32 s16, s22, 0x58080
	v_lshl_add_u64 v[190:191], v[226:227], 0, s[12:13]
	s_addc_u32 s17, s23, 0
	s_add_i32 s22, s57, s30
	global_load_lds_dwordx4 v[190:191], off
	v_lshl_add_u64 v[190:191], s[16:17], 0, v[148:149]
	s_mov_b32 m0, s22
	s_nop 0
	global_load_lds_dwordx4 v[190:191], off
	v_lshl_add_u64 v[190:191], s[16:17], 0, v[152:153]
	s_add_i32 m0, s22, 0x2000
	s_nop 0
	global_load_lds_dwordx4 v[190:191], off
	v_lshl_add_u64 v[190:191], v[228:229], 0, s[12:13]
	s_mov_b32 m0, s49
	s_nop 0
	global_load_lds_dwordx4 v[190:191], off
	v_lshl_add_u64 v[190:191], v[230:231], 0, s[12:13]
	s_mov_b32 m0, s50
	s_nop 0
	global_load_lds_dwordx4 v[190:191], off
	s_waitcnt vmcnt(8)
	s_waitcnt lgkmcnt(0)
	s_barrier
	s_waitcnt lgkmcnt(0)
	v_mfma_f32_16x16x32_bf16 v[62:65], v[130:133], v[182:185], v[62:65]
	v_mfma_f32_16x16x32_bf16 v[58:61], v[138:141], v[182:185], v[58:61]
	v_mfma_f32_16x16x32_bf16 v[46:49], v[130:133], v[202:205], v[46:49]
	v_mfma_f32_16x16x32_bf16 v[42:45], v[138:141], v[202:205], v[42:45]
	v_mfma_f32_16x16x32_bf16 v[30:33], v[130:133], v[210:213], v[30:33]
	v_mfma_f32_16x16x32_bf16 v[26:29], v[138:141], v[210:213], v[26:29]
	v_mfma_f32_16x16x32_bf16 v[14:17], v[130:133], v[218:221], v[14:17]
	v_mfma_f32_16x16x32_bf16 v[10:13], v[138:141], v[218:221], v[10:13]
	v_mfma_f32_16x16x32_bf16 v[62:65], v[134:137], v[186:189], v[62:65]
	v_mfma_f32_16x16x32_bf16 v[58:61], v[142:145], v[186:189], v[58:61]
	v_mfma_f32_16x16x32_bf16 v[46:49], v[134:137], v[206:209], v[46:49]
	v_mfma_f32_16x16x32_bf16 v[42:45], v[142:145], v[206:209], v[42:45]
	v_mfma_f32_16x16x32_bf16 v[30:33], v[134:137], v[214:217], v[30:33]
	v_mfma_f32_16x16x32_bf16 v[26:29], v[142:145], v[214:217], v[26:29]
	v_mfma_f32_16x16x32_bf16 v[14:17], v[134:137], v[222:225], v[14:17]
	v_mfma_f32_16x16x32_bf16 v[10:13], v[142:145], v[222:225], v[10:13]
	v_mfma_f32_16x16x32_bf16 v[54:57], v[166:169], v[182:185], v[54:57]
	v_mfma_f32_16x16x32_bf16 v[50:53], v[174:177], v[182:185], v[50:53]
	v_mfma_f32_16x16x32_bf16 v[38:41], v[166:169], v[202:205], v[38:41]
	v_mfma_f32_16x16x32_bf16 v[34:37], v[174:177], v[202:205], v[34:37]
	v_mfma_f32_16x16x32_bf16 v[22:25], v[166:169], v[210:213], v[22:25]
	v_mfma_f32_16x16x32_bf16 v[18:21], v[174:177], v[210:213], v[18:21]
	v_mfma_f32_16x16x32_bf16 v[6:9], v[166:169], v[218:221], v[6:9]
	v_mfma_f32_16x16x32_bf16 v[2:5], v[174:177], v[218:221], v[2:5]
	v_mfma_f32_16x16x32_bf16 v[54:57], v[170:173], v[186:189], v[54:57]
	v_mfma_f32_16x16x32_bf16 v[50:53], v[178:181], v[186:189], v[50:53]
	v_mfma_f32_16x16x32_bf16 v[38:41], v[170:173], v[206:209], v[38:41]
	v_mfma_f32_16x16x32_bf16 v[34:37], v[178:181], v[206:209], v[34:37]
	v_mfma_f32_16x16x32_bf16 v[22:25], v[170:173], v[214:217], v[22:25]
	v_mfma_f32_16x16x32_bf16 v[18:21], v[178:181], v[214:217], v[18:21]
	v_mfma_f32_16x16x32_bf16 v[6:9], v[170:173], v[222:225], v[6:9]
	v_mfma_f32_16x16x32_bf16 v[2:5], v[178:181], v[222:225], v[2:5]
	s_barrier
	s_add_i32 s25, s25, 2
	s_add_u32 s9, s9, 0x100
	s_addc_u32 s24, s24, 0
	s_cmpk_gt_u32 s25, 0x55
	s_mov_b64 s[16:17], s[20:21]
.LBB0_1595:
	ds_read_b128 v[130:133], v196
	ds_read_b128 v[134:137], v196 offset:1024
	ds_read_b128 v[138:141], v196 offset:2048
	ds_read_b128 v[142:145], v196 offset:3072
	ds_read_b128 v[166:169], v197
	ds_read_b128 v[170:173], v197 offset:1024
	ds_read_b128 v[174:177], v197 offset:2048
	ds_read_b128 v[178:181], v197 offset:3072
	s_add_u32 s20, s16, 0x100
	s_addc_u32 s21, s17, 0
	s_cmpk_eq_i32 s25, 0x54
	s_cselect_b32 s47, s3, s21
	s_cselect_b32 s46, s2, s20
	s_cselect_b32 s23, s19, s24
	s_cselect_b32 s22, s18, s9
	v_lshl_add_u64 v[190:191], s[16:17], 0, v[158:159]
	s_add_i32 m0, s31, 0xc000
	ds_read_b128 v[182:185], v198
	ds_read_b128 v[186:189], v198 offset:1024
	ds_read_b128 v[202:205], v198 offset:2048
	ds_read_b128 v[206:209], v198 offset:3072
	ds_read_b128 v[210:213], v198 offset:4096
	ds_read_b128 v[214:217], v198 offset:5120
	ds_read_b128 v[218:221], v198 offset:6144
	ds_read_b128 v[222:225], v198 offset:7168
	global_load_lds_dwordx4 v[190:191], off
	v_lshl_add_u64 v[190:191], s[16:17], 0, v[160:161]
	s_add_i32 m0, s31, 0xe000
	s_nop 0
	global_load_lds_dwordx4 v[190:191], off
	s_waitcnt vmcnt(8)
	s_waitcnt lgkmcnt(0)
	s_barrier
; #define PG8_STAGE(bufoff, gbase, voff) do { _Pragma("unroll") for (int _i = 0; _i < 2; ++_i) \
;         __builtin_amdgcn_global_load_lds((const unsigned*)((const char*)(gbase) + (voff)[_i]), (LAS unsigned*)(lds + (bufoff) + ldsw + _i * 8192), 16, 0, 0); } while (0)
; #define PG8_LDA(dst, b, h) do { _Pragma("unroll") for (int m = 0; m < 4; ++m) _Pragma("unroll") for (int k = 0; k < 2; ++k) dst[m][k] = *(const LAS bf16x8*)(lds + PG8_SA(b, h) + aoff + m * 2048 + k * 1024); } while (0)
; #define PG8_LDB(dst, b, h) do { _Pragma("unroll") for (int n = 0; n < 2; ++n) _Pragma("unroll") for (int k = 0; k < 2; ++k) dst[n][k] = *(const LAS bf16x8*)(lds + PG8_SB(b, h) + boff + n * 2048 + k * 1024); } while (0)
; #define PG8_MMA(ai, bj, At, Bt) do { __builtin_amdgcn_s_setprio(1); _Pragma("unroll") for (int m = 0; m < 4; ++m) _Pragma("unroll") for (int n = 0; n < 2; ++n) _Pragma("unroll") for (int k = 0; k < 2; ++k) \
;         acc[ai][bj][m][n] = __builtin_amdgcn_mfma_f32_16x16x32_bf16(Bt[n][k], At[m][k], acc[ai][bj][m][n], 0, 0, 0); __builtin_amdgcn_s_setprio(0); } while (0)
; #define PG8_WAIT_V(n) asm volatile("s_waitcnt vmcnt(" #n ")" ::: "memory")
; #define PG8_WAIT_L(n) asm volatile("s_waitcnt lgkmcnt(" #n ")" ::: "memory")
; #define PG8_BAR __builtin_amdgcn_s_barrier()
; #define PG8_SCHED __builtin_amdgcn_sched_barrier(0)
; template <class Epi, class Sched, bool ALIGN_EPI = false, bool SP2 = false>
; __device__ __forceinline__ void gemm_phase(LAS unsigned char* lds, const Gemm g, const Sched& S, const Epi& E) {
;     ...
;             PG8_LDB(B0, 0, 0); PG8_LDB(B1, 0, 1); PG8_SCHED; PG8_LDA(At, 0, 0); PG8_STAGE(PG8_SA(1, 1), a1 + hstep, voffA);
;             PG8_WAIT_V(8); PG8_WAIT_L(0); PG8_BAR; PG8_MMA(0, 0, At, B0); PG8_MMA(0, 1, At, B1); PG8_BAR; PG8_SCHED;
;             PG8_LDA(At, 0, 1); PG8_STAGE(PG8_SB(0, 0), b2, voffB); PG8_STAGE(PG8_SB(0, 1), b2 + hstepB, voffB); PG8_STAGE(PG8_SA(0, 0), a2, voffA);
;             PG8_WAIT_V(8); PG8_WAIT_L(0); PG8_BAR; PG8_MMA(1, 0, At, B0); PG8_MMA(1, 1, At, B1); PG8_BAR; PG8_SCHED;
;             PG8_LDB(B0, 1, 0); PG8_LDB(B1, 1, 1); PG8_SCHED; PG8_LDA(At, 1, 0); PG8_STAGE(PG8_SA(0, 1), a2 + hstep, voffA);
;             PG8_WAIT_V(8); PG8_WAIT_L(0); PG8_BAR; PG8_MMA(0, 0, At, B0); PG8_MMA(0, 1, At, B1); PG8_BAR; PG8_SCHED;
	s_waitcnt lgkmcnt(0)
	v_mfma_f32_16x16x32_bf16 v[126:129], v[130:133], v[182:185], v[126:129]
	v_mfma_f32_16x16x32_bf16 v[122:125], v[138:141], v[182:185], v[122:125]
	v_mfma_f32_16x16x32_bf16 v[110:113], v[130:133], v[202:205], v[110:113]
	v_mfma_f32_16x16x32_bf16 v[106:109], v[138:141], v[202:205], v[106:109]
	v_mfma_f32_16x16x32_bf16 v[94:97], v[130:133], v[210:213], v[94:97]
	v_mfma_f32_16x16x32_bf16 v[90:93], v[138:141], v[210:213], v[90:93]
	v_mfma_f32_16x16x32_bf16 v[78:81], v[130:133], v[218:221], v[78:81]
	v_mfma_f32_16x16x32_bf16 v[74:77], v[138:141], v[218:221], v[74:77]
	v_mfma_f32_16x16x32_bf16 v[126:129], v[134:137], v[186:189], v[126:129]
	v_mfma_f32_16x16x32_bf16 v[122:125], v[142:145], v[186:189], v[122:125]
	v_mfma_f32_16x16x32_bf16 v[110:113], v[134:137], v[206:209], v[110:113]
	v_mfma_f32_16x16x32_bf16 v[106:109], v[142:145], v[206:209], v[106:109]
	v_mfma_f32_16x16x32_bf16 v[94:97], v[134:137], v[214:217], v[94:97]
	v_mfma_f32_16x16x32_bf16 v[90:93], v[142:145], v[214:217], v[90:93]
	v_mfma_f32_16x16x32_bf16 v[78:81], v[134:137], v[222:225], v[78:81]
	v_mfma_f32_16x16x32_bf16 v[74:77], v[142:145], v[222:225], v[74:77]
	v_mfma_f32_16x16x32_bf16 v[118:121], v[166:169], v[182:185], v[118:121]
	v_mfma_f32_16x16x32_bf16 v[114:117], v[174:177], v[182:185], v[114:117]
	v_mfma_f32_16x16x32_bf16 v[102:105], v[166:169], v[202:205], v[102:105]
	v_mfma_f32_16x16x32_bf16 v[98:101], v[174:177], v[202:205], v[98:101]
	v_mfma_f32_16x16x32_bf16 v[86:89], v[166:169], v[210:213], v[86:89]
	v_mfma_f32_16x16x32_bf16 v[82:85], v[174:177], v[210:213], v[82:85]
	v_mfma_f32_16x16x32_bf16 v[70:73], v[166:169], v[218:221], v[70:73]
	v_mfma_f32_16x16x32_bf16 v[66:69], v[174:177], v[218:221], v[66:69]
	v_mfma_f32_16x16x32_bf16 v[118:121], v[170:173], v[186:189], v[118:121]
	v_mfma_f32_16x16x32_bf16 v[114:117], v[178:181], v[186:189], v[114:117]
	v_mfma_f32_16x16x32_bf16 v[102:105], v[170:173], v[206:209], v[102:105]
	v_mfma_f32_16x16x32_bf16 v[98:101], v[178:181], v[206:209], v[98:101]
	v_mfma_f32_16x16x32_bf16 v[86:89], v[170:173], v[214:217], v[86:89]
	v_mfma_f32_16x16x32_bf16 v[82:85], v[178:181], v[214:217], v[82:85]
	v_mfma_f32_16x16x32_bf16 v[70:73], v[170:173], v[222:225], v[70:73]
	v_mfma_f32_16x16x32_bf16 v[66:69], v[178:181], v[222:225], v[66:69]
	s_barrier
	s_add_i32 s16, s52, s30
	v_lshl_add_u64 v[190:191], s[22:23], 0, v[148:149]
	s_mov_b32 m0, s16
	ds_read_b128 v[182:185], v198 offset:16384
	ds_read_b128 v[186:189], v198 offset:17408
	ds_read_b128 v[202:205], v198 offset:18432
	ds_read_b128 v[206:209], v198 offset:19456
	ds_read_b128 v[210:213], v198 offset:20480
	ds_read_b128 v[214:217], v198 offset:21504
	ds_read_b128 v[218:221], v198 offset:22528
	ds_read_b128 v[222:225], v198 offset:23552
	global_load_lds_dwordx4 v[190:191], off
	s_add_i32 m0, s16, 0x2000
	s_add_u32 s16, s22, 0x58000
	v_lshl_add_u64 v[226:227], s[22:23], 0, v[152:153]
	s_addc_u32 s17, s23, 0
	s_add_i32 s56, s53, s30
	global_load_lds_dwordx4 v[226:227], off
	v_lshl_add_u64 v[228:229], s[16:17], 0, v[148:149]
	s_mov_b32 m0, s56
	v_lshl_add_u64 v[230:231], s[46:47], 0, v[150:151]
	global_load_lds_dwordx4 v[228:229], off
	v_lshl_add_u64 v[228:229], s[16:17], 0, v[152:153]
	s_add_i32 m0, s56, 0x2000
	s_nop 0
	global_load_lds_dwordx4 v[228:229], off
	v_lshl_add_u64 v[228:229], s[46:47], 0, v[146:147]
	s_mov_b32 m0, s31
	s_nop 0
	global_load_lds_dwordx4 v[228:229], off
	s_mov_b32 m0, s33
	s_nop 0
	global_load_lds_dwordx4 v[230:231], off
	s_waitcnt vmcnt(8)
	s_waitcnt lgkmcnt(0)
	s_barrier
	s_waitcnt lgkmcnt(0)
	v_mfma_f32_16x16x32_bf16 v[62:65], v[130:133], v[182:185], v[62:65]
	v_mfma_f32_16x16x32_bf16 v[58:61], v[138:141], v[182:185], v[58:61]
	v_mfma_f32_16x16x32_bf16 v[46:49], v[130:133], v[202:205], v[46:49]
	v_mfma_f32_16x16x32_bf16 v[42:45], v[138:141], v[202:205], v[42:45]
	v_mfma_f32_16x16x32_bf16 v[30:33], v[130:133], v[210:213], v[30:33]
	v_mfma_f32_16x16x32_bf16 v[26:29], v[138:141], v[210:213], v[26:29]
	v_mfma_f32_16x16x32_bf16 v[14:17], v[130:133], v[218:221], v[14:17]
	v_mfma_f32_16x16x32_bf16 v[10:13], v[138:141], v[218:221], v[10:13]
	v_mfma_f32_16x16x32_bf16 v[62:65], v[134:137], v[186:189], v[62:65]
	v_mfma_f32_16x16x32_bf16 v[58:61], v[142:145], v[186:189], v[58:61]
	v_mfma_f32_16x16x32_bf16 v[46:49], v[134:137], v[206:209], v[46:49]
	v_mfma_f32_16x16x32_bf16 v[42:45], v[142:145], v[206:209], v[42:45]
	v_mfma_f32_16x16x32_bf16 v[30:33], v[134:137], v[214:217], v[30:33]
	v_mfma_f32_16x16x32_bf16 v[26:29], v[142:145], v[214:217], v[26:29]
	v_mfma_f32_16x16x32_bf16 v[14:17], v[134:137], v[222:225], v[14:17]
	v_mfma_f32_16x16x32_bf16 v[10:13], v[142:145], v[222:225], v[10:13]
	v_mfma_f32_16x16x32_bf16 v[54:57], v[166:169], v[182:185], v[54:57]
	v_mfma_f32_16x16x32_bf16 v[50:53], v[174:177], v[182:185], v[50:53]
	v_mfma_f32_16x16x32_bf16 v[38:41], v[166:169], v[202:205], v[38:41]
	v_mfma_f32_16x16x32_bf16 v[34:37], v[174:177], v[202:205], v[34:37]
	v_mfma_f32_16x16x32_bf16 v[22:25], v[166:169], v[210:213], v[22:25]
	v_mfma_f32_16x16x32_bf16 v[18:21], v[174:177], v[210:213], v[18:21]
	v_mfma_f32_16x16x32_bf16 v[6:9], v[166:169], v[218:221], v[6:9]
	v_mfma_f32_16x16x32_bf16 v[2:5], v[174:177], v[218:221], v[2:5]
	v_mfma_f32_16x16x32_bf16 v[54:57], v[170:173], v[186:189], v[54:57]
	v_mfma_f32_16x16x32_bf16 v[50:53], v[178:181], v[186:189], v[50:53]
	v_mfma_f32_16x16x32_bf16 v[38:41], v[170:173], v[206:209], v[38:41]
	v_mfma_f32_16x16x32_bf16 v[34:37], v[178:181], v[206:209], v[34:37]
	v_mfma_f32_16x16x32_bf16 v[22:25], v[170:173], v[214:217], v[22:25]
	v_mfma_f32_16x16x32_bf16 v[18:21], v[178:181], v[214:217], v[18:21]
	v_mfma_f32_16x16x32_bf16 v[6:9], v[170:173], v[222:225], v[6:9]
	v_mfma_f32_16x16x32_bf16 v[2:5], v[178:181], v[222:225], v[2:5]
	s_barrier
; #define PG8_STAGE(bufoff, gbase, voff) do { _Pragma("unroll") for (int _i = 0; _i < 2; ++_i) \
;         __builtin_amdgcn_global_load_lds((const unsigned*)((const char*)(gbase) + (voff)[_i]), (LAS unsigned*)(lds + (bufoff) + ldsw + _i * 8192), 16, 0, 0); } while (0)
; #define PG8_LDA(dst, b, h) do { _Pragma("unroll") for (int m = 0; m < 4; ++m) _Pragma("unroll") for (int k = 0; k < 2; ++k) dst[m][k] = *(const LAS bf16x8*)(lds + PG8_SA(b, h) + aoff + m * 2048 + k * 1024); } while (0)
; #define PG8_LDB(dst, b, h) do { _Pragma("unroll") for (int n = 0; n < 2; ++n) _Pragma("unroll") for (int k = 0; k < 2; ++k) dst[n][k] = *(const LAS bf16x8*)(lds + PG8_SB(b, h) + boff + n * 2048 + k * 1024); } while (0)
; #define PG8_MMA(ai, bj, At, Bt) do { __builtin_amdgcn_s_setprio(1); _Pragma("unroll") for (int m = 0; m < 4; ++m) _Pragma("unroll") for (int n = 0; n < 2; ++n) _Pragma("unroll") for (int k = 0; k < 2; ++k) \
;         acc[ai][bj][m][n] = __builtin_amdgcn_mfma_f32_16x16x32_bf16(Bt[n][k], At[m][k], acc[ai][bj][m][n], 0, 0, 0); __builtin_amdgcn_s_setprio(0); } while (0)
; #define PG8_WAIT_V(n) asm volatile("s_waitcnt vmcnt(" #n ")" ::: "memory")
; #define PG8_WAIT_L(n) asm volatile("s_waitcnt lgkmcnt(" #n ")" ::: "memory")
; #define PG8_BAR __builtin_amdgcn_s_barrier()
; #define PG8_SCHED __builtin_amdgcn_sched_barrier(0)
; template <class Epi, class Sched, bool ALIGN_EPI = false, bool SP2 = false>
; __device__ __forceinline__ void gemm_phase(LAS unsigned char* lds, const Gemm g, const Sched& S, const Epi& E) {
;     ...
;             PG8_LDB(B0, 1, 0); PG8_LDB(B1, 1, 1); PG8_SCHED; PG8_LDA(At, 1, 0); PG8_STAGE(PG8_SA(0, 1), a2 + hstep, voffA);
;             PG8_WAIT_V(8); PG8_WAIT_L(0); PG8_BAR; PG8_MMA(0, 0, At, B0); PG8_MMA(0, 1, At, B1); PG8_BAR; PG8_SCHED;
	s_add_i32 s56, 0, 0x18000
	s_add_i32 s57, 0, 0x1c000
	v_add_u32_e32 v142, s56, v1
	v_add_u32_e32 v154, s57, v1
	ds_read_b128 v[130:133], v142
	ds_read_b128 v[134:137], v142 offset:1024
	ds_read_b128 v[138:141], v142 offset:2048
	ds_read_b128 v[142:145], v142 offset:3072
	ds_read_b128 v[166:169], v154
	ds_read_b128 v[170:173], v154 offset:1024
	ds_read_b128 v[174:177], v154 offset:2048
	ds_read_b128 v[178:181], v154 offset:3072
	s_add_u32 s16, s46, 0x160000
	s_addc_u32 s17, s47, 0
	s_mov_b32 m0, s34
	v_lshl_add_u64 v[232:233], s[16:17], 0, v[146:147]
	ds_read_b128 v[182:185], v198 offset:32768
	ds_read_b128 v[186:189], v198 offset:33792
	ds_read_b128 v[202:205], v198 offset:34816
	ds_read_b128 v[206:209], v198 offset:35840
	ds_read_b128 v[210:213], v198 offset:36864
	ds_read_b128 v[214:217], v198 offset:37888
	ds_read_b128 v[218:221], v198 offset:38912
	ds_read_b128 v[222:225], v198 offset:39936
	global_load_lds_dwordx4 v[232:233], off
	v_lshl_add_u64 v[232:233], s[16:17], 0, v[150:151]
	s_mov_b32 m0, s35
	s_nop 0
	global_load_lds_dwordx4 v[232:233], off
	s_waitcnt vmcnt(8)
	s_waitcnt lgkmcnt(0)
	s_barrier
	s_waitcnt lgkmcnt(0)
	v_mfma_f32_16x16x32_bf16 v[126:129], v[130:133], v[182:185], v[126:129]
	v_mfma_f32_16x16x32_bf16 v[122:125], v[138:141], v[182:185], v[122:125]
	v_mfma_f32_16x16x32_bf16 v[110:113], v[130:133], v[202:205], v[110:113]
	v_mfma_f32_16x16x32_bf16 v[106:109], v[138:141], v[202:205], v[106:109]
	v_mfma_f32_16x16x32_bf16 v[94:97], v[130:133], v[210:213], v[94:97]
	v_mfma_f32_16x16x32_bf16 v[90:93], v[138:141], v[210:213], v[90:93]
	v_mfma_f32_16x16x32_bf16 v[78:81], v[130:133], v[218:221], v[78:81]
	v_mfma_f32_16x16x32_bf16 v[74:77], v[138:141], v[218:221], v[74:77]
	v_mfma_f32_16x16x32_bf16 v[126:129], v[134:137], v[186:189], v[126:129]
	v_mfma_f32_16x16x32_bf16 v[122:125], v[142:145], v[186:189], v[122:125]
	v_mfma_f32_16x16x32_bf16 v[110:113], v[134:137], v[206:209], v[110:113]
	v_mfma_f32_16x16x32_bf16 v[106:109], v[142:145], v[206:209], v[106:109]
	v_mfma_f32_16x16x32_bf16 v[94:97], v[134:137], v[214:217], v[94:97]
	v_mfma_f32_16x16x32_bf16 v[90:93], v[142:145], v[214:217], v[90:93]
	v_mfma_f32_16x16x32_bf16 v[78:81], v[134:137], v[222:225], v[78:81]
	v_mfma_f32_16x16x32_bf16 v[74:77], v[142:145], v[222:225], v[74:77]
	v_mfma_f32_16x16x32_bf16 v[118:121], v[166:169], v[182:185], v[118:121]
	v_mfma_f32_16x16x32_bf16 v[114:117], v[174:177], v[182:185], v[114:117]
	v_mfma_f32_16x16x32_bf16 v[102:105], v[166:169], v[202:205], v[102:105]
	v_mfma_f32_16x16x32_bf16 v[98:101], v[174:177], v[202:205], v[98:101]
	v_mfma_f32_16x16x32_bf16 v[86:89], v[166:169], v[210:213], v[86:89]
	v_mfma_f32_16x16x32_bf16 v[82:85], v[174:177], v[210:213], v[82:85]
	v_mfma_f32_16x16x32_bf16 v[70:73], v[166:169], v[218:221], v[70:73]
	v_mfma_f32_16x16x32_bf16 v[66:69], v[174:177], v[218:221], v[66:69]
	v_mfma_f32_16x16x32_bf16 v[118:121], v[170:173], v[186:189], v[118:121]
	v_mfma_f32_16x16x32_bf16 v[114:117], v[178:181], v[186:189], v[114:117]
	v_mfma_f32_16x16x32_bf16 v[102:105], v[170:173], v[206:209], v[102:105]
	v_mfma_f32_16x16x32_bf16 v[98:101], v[178:181], v[206:209], v[98:101]
	v_mfma_f32_16x16x32_bf16 v[86:89], v[170:173], v[214:217], v[86:89]
	v_mfma_f32_16x16x32_bf16 v[82:85], v[178:181], v[214:217], v[82:85]
	v_mfma_f32_16x16x32_bf16 v[70:73], v[170:173], v[222:225], v[70:73]
	v_mfma_f32_16x16x32_bf16 v[66:69], v[178:181], v[222:225], v[66:69]
	s_barrier
; #define PG8_STAGE(bufoff, gbase, voff) do { _Pragma("unroll") for (int _i = 0; _i < 2; ++_i) \
;         __builtin_amdgcn_global_load_lds((const unsigned*)((const char*)(gbase) + (voff)[_i]), (LAS unsigned*)(lds + (bufoff) + ldsw + _i * 8192), 16, 0, 0); } while (0)
; #define PG8_LDA(dst, b, h) do { _Pragma("unroll") for (int m = 0; m < 4; ++m) _Pragma("unroll") for (int k = 0; k < 2; ++k) dst[m][k] = *(const LAS bf16x8*)(lds + PG8_SA(b, h) + aoff + m * 2048 + k * 1024); } while (0)
; #define PG8_MMA(ai, bj, At, Bt) do { __builtin_amdgcn_s_setprio(1); _Pragma("unroll") for (int m = 0; m < 4; ++m) _Pragma("unroll") for (int n = 0; n < 2; ++n) _Pragma("unroll") for (int k = 0; k < 2; ++k) \
;         acc[ai][bj][m][n] = __builtin_amdgcn_mfma_f32_16x16x32_bf16(Bt[n][k], At[m][k], acc[ai][bj][m][n], 0, 0, 0); __builtin_amdgcn_s_setprio(0); } while (0)
; #define PG8_WAIT_V(n) asm volatile("s_waitcnt vmcnt(" #n ")" ::: "memory")
; #define PG8_WAIT_L(n) asm volatile("s_waitcnt lgkmcnt(" #n ")" ::: "memory")
; #define PG8_BAR __builtin_amdgcn_s_barrier()
; #define PG8_SCHED __builtin_amdgcn_sched_barrier(0)
; template <class Epi, class Sched, bool ALIGN_EPI = false, bool SP2 = false>
; __device__ __forceinline__ void gemm_phase(LAS unsigned char* lds, const Gemm g, const Sched& S, const Epi& E) {
;     ...
;         for (int t = 0; t < nt; t += 2) {
;     ...
;             PG8_LDA(At, 1, 1); PG8_STAGE(PG8_SB(1, 0), b3, voffB); PG8_STAGE(PG8_SB(1, 1), b3 + hstepB, voffB); PG8_STAGE(PG8_SA(1, 0), a3, voffA);
;             PG8_WAIT_V(8); PG8_WAIT_L(0); PG8_BAR; PG8_MMA(1, 0, At, B0); PG8_MMA(1, 1, At, B1); PG8_BAR; PG8_SCHED;
	s_add_i32 s16, s56, s30
	v_lshl_add_u64 v[190:191], v[190:191], 0, s[12:13]
	s_mov_b32 m0, s16
	ds_read_b128 v[182:185], v198 offset:49152
	ds_read_b128 v[186:189], v198 offset:50176
	ds_read_b128 v[202:205], v198 offset:51200
	ds_read_b128 v[206:209], v198 offset:52224
	ds_read_b128 v[210:213], v198 offset:53248
	ds_read_b128 v[214:217], v198 offset:54272
	ds_read_b128 v[218:221], v198 offset:55296
	ds_read_b128 v[222:225], v198 offset:56320
	global_load_lds_dwordx4 v[190:191], off
	s_add_i32 m0, s16, 0x2000
	s_add_u32 s16, s22, 0x58080
	v_lshl_add_u64 v[190:191], v[226:227], 0, s[12:13]
	s_addc_u32 s17, s23, 0
	s_add_i32 s22, s57, s30
	global_load_lds_dwordx4 v[190:191], off
	v_lshl_add_u64 v[190:191], s[16:17], 0, v[148:149]
	s_mov_b32 m0, s22
	s_nop 0
	global_load_lds_dwordx4 v[190:191], off
	v_lshl_add_u64 v[190:191], s[16:17], 0, v[152:153]
	s_add_i32 m0, s22, 0x2000
	s_nop 0
	global_load_lds_dwordx4 v[190:191], off
	v_lshl_add_u64 v[190:191], v[228:229], 0, s[12:13]
	s_mov_b32 m0, s49
	s_nop 0
	global_load_lds_dwordx4 v[190:191], off
	v_lshl_add_u64 v[190:191], v[230:231], 0, s[12:13]
	s_mov_b32 m0, s50
	s_nop 0
	global_load_lds_dwordx4 v[190:191], off
	s_waitcnt vmcnt(8)
	s_waitcnt lgkmcnt(0)
	s_barrier
	s_waitcnt lgkmcnt(0)
	v_mfma_f32_16x16x32_bf16 v[62:65], v[130:133], v[182:185], v[62:65]
	v_mfma_f32_16x16x32_bf16 v[58:61], v[138:141], v[182:185], v[58:61]
	v_mfma_f32_16x16x32_bf16 v[46:49], v[130:133], v[202:205], v[46:49]
	v_mfma_f32_16x16x32_bf16 v[42:45], v[138:141], v[202:205], v[42:45]
	v_mfma_f32_16x16x32_bf16 v[30:33], v[130:133], v[210:213], v[30:33]
	v_mfma_f32_16x16x32_bf16 v[26:29], v[138:141], v[210:213], v[26:29]
	v_mfma_f32_16x16x32_bf16 v[14:17], v[130:133], v[218:221], v[14:17]
	v_mfma_f32_16x16x32_bf16 v[10:13], v[138:141], v[218:221], v[10:13]
	v_mfma_f32_16x16x32_bf16 v[62:65], v[134:137], v[186:189], v[62:65]
	v_mfma_f32_16x16x32_bf16 v[58:61], v[142:145], v[186:189], v[58:61]
	v_mfma_f32_16x16x32_bf16 v[46:49], v[134:137], v[206:209], v[46:49]
	v_mfma_f32_16x16x32_bf16 v[42:45], v[142:145], v[206:209], v[42:45]
	v_mfma_f32_16x16x32_bf16 v[30:33], v[134:137], v[214:217], v[30:33]
	v_mfma_f32_16x16x32_bf16 v[26:29], v[142:145], v[214:217], v[26:29]
	v_mfma_f32_16x16x32_bf16 v[14:17], v[134:137], v[222:225], v[14:17]
	v_mfma_f32_16x16x32_bf16 v[10:13], v[142:145], v[222:225], v[10:13]
	v_mfma_f32_16x16x32_bf16 v[54:57], v[166:169], v[182:185], v[54:57]
	v_mfma_f32_16x16x32_bf16 v[50:53], v[174:177], v[182:185], v[50:53]
	v_mfma_f32_16x16x32_bf16 v[38:41], v[166:169], v[202:205], v[38:41]
	v_mfma_f32_16x16x32_bf16 v[34:37], v[174:177], v[202:205], v[34:37]
	v_mfma_f32_16x16x32_bf16 v[22:25], v[166:169], v[210:213], v[22:25]
	v_mfma_f32_16x16x32_bf16 v[18:21], v[174:177], v[210:213], v[18:21]
	v_mfma_f32_16x16x32_bf16 v[6:9], v[166:169], v[218:221], v[6:9]
	v_mfma_f32_16x16x32_bf16 v[2:5], v[174:177], v[218:221], v[2:5]
	v_mfma_f32_16x16x32_bf16 v[54:57], v[170:173], v[186:189], v[54:57]
	v_mfma_f32_16x16x32_bf16 v[50:53], v[178:181], v[186:189], v[50:53]
	v_mfma_f32_16x16x32_bf16 v[38:41], v[170:173], v[206:209], v[38:41]
	v_mfma_f32_16x16x32_bf16 v[34:37], v[178:181], v[206:209], v[34:37]
	v_mfma_f32_16x16x32_bf16 v[22:25], v[170:173], v[214:217], v[22:25]
	v_mfma_f32_16x16x32_bf16 v[18:21], v[178:181], v[214:217], v[18:21]
	v_mfma_f32_16x16x32_bf16 v[6:9], v[170:173], v[222:225], v[6:9]
	v_mfma_f32_16x16x32_bf16 v[2:5], v[178:181], v[222:225], v[2:5]
	s_barrier
	s_add_i32 s25, s25, 2
	s_add_u32 s9, s9, 0x100
	s_addc_u32 s24, s24, 0
	s_cmpk_gt_u32 s25, 0x55
	s_mov_b64 s[16:17], s[20:21]
	s_cbranch_scc0 .LBB0_1595
	s_and_b64 vcc, exec, s[14:15]
	s_cbranch_vccz .LBB0_1598
	s_barrier

; __device__ __forceinline__ float row_rstd(const float* ss, int row) { return 1.0f / sqrtf(ss[row] * (1.0f / DM) + 1e-6f); }
;     __device__ bool next(int i, Unit& u) const { if (i != 0 || c >= 128) return false; const int t = c >> 2; u.pm = t & 3; u.pn = t >> 2; u.koff = koff_bytes; u.q = c & 3; return true; }
;     __device__ __forceinline__ void operator()(const f32x4 (&acc)[2][2][4][2], const Unit& u, int wr, int wc, int fr, int fq) const {
;         const int row0 = u.pm * BM + wr * 64 + fr, col0 = u.pn * HALF + wc * 32 + 8 * fq;
;         const int s = (u.pm < ML / BM) ? (u.pm >> 5) : 4;
;         const float* bp = bias + (size_t)s * BIAS_N + u.pn * BM + wc * 32 + 8 * fq;
;         const f32x4 ba0 = *(const f32x4*)bp, ba1 = *(const f32x4*)(bp + 4), bb0 = *(const f32x4*)(bp + HALF), bb1 = *(const f32x4*)(bp + HALF + 4);
;         const int lane = fq * 16 + fr;
;         const float rsl0 = row_rstd(ss, u.pm * BM + wr * 64 + lane), rsl1 = row_rstd(ss, u.pm * BM + HALF + wr * 64 + lane);
; template <class Epi, class Sched, bool ALIGN_EPI = false, bool SP2 = false>
; __device__ __forceinline__ void gemm_phase(LAS unsigned char* lds, const Gemm g, const Sched& S, const Epi& E) {
;     ...
;         const bool has_next = S.next(ui + 1, nxt);
;         const char* nA = has_next ? (const char*)g.A + (size_t)nxt.pm * tstep + nxt.koff : cA; const char* nB = has_next ? (const char*)g.Bt + (size_t)nxt.pn * tstep + nxt.koff : cB;
;         for (int t = 0; t < nt; t += 2) {
;             const bool last = (t == nt - 2);
;             const char* a1 = cA + (size_t)(t + 1) * kstep;
;             const char* a2 = last ? nA : cA + (size_t)(t + 2) * kstep; const char* b2 = last ? nB : cB + (size_t)(t + 2) * kstep;
;             const char* a3 = a2 + kstep; const char* b3 = b2 + kstep;
;             if (last && has_next) S.a_ready(nxt);
;             if constexpr (SP2) {
;             PG8_LDB(B0, 0, 0); PG8_LDB(B1, 0, 1); PG8_SCHED; PG8_LDA(At, 0, 0); PG8_STAGE(PG8_SA(1, 1), a1 + hstep, voffA);
;             PG8_WAIT_V(8); PG8_WAIT_L(0); PG8_BAR; PG8_MMA(0, 0, At, B0); PG8_MMA(0, 1, At, B1); PG8_BAR; PG8_SCHED;
;             PG8_LDA(At, 0, 1); PG8_STAGE(PG8_SB(0, 0), b2, voffB); PG8_STAGE(PG8_SB(0, 1), b2 + hstepB, voffB); PG8_STAGE(PG8_SA(0, 0), a2, voffA);
;             PG8_WAIT_V(8); PG8_WAIT_L(0); PG8_BAR; PG8_MMA(1, 0, At, B0); PG8_MMA(1, 1, At, B1); PG8_BAR; PG8_SCHED;
.Lpre_up1l1:
	s_lshl_b64 s[98:99], s[98:99], 2
	s_add_u32 s98, s36, s98
	s_addc_u32 s99, s37, s99
	s_lshl_b32 s100, s0, 8
	s_ashr_i32 s101, s100, 31
	s_lshl_b64 s[100:101], s[100:101], 2
	s_add_u32 s98, s98, s100
	s_addc_u32 s99, s99, s101
	s_add_u32 s98, s98, s47
	s_addc_u32 s99, s99, 0
	s_lshl_b32 s100, s2, 8
	s_add_i32 s100, s100, s35
	v_or_b32_e32 v162, s100, v170
	v_ashrrev_i32_e32 v163, 31, v162
	v_lshl_add_u64 v[162:163], v[162:163], 2, s[6:7]
	v_add_u32_e32 v164, s100, v171
	v_ashrrev_i32_e32 v165, 31, v164
	v_lshl_add_u64 v[164:165], v[164:165], 2, s[6:7]
	global_load_dwordx4 v[234:237], v176, s[98:99] offset:16
	global_load_dwordx4 v[238:241], v176, s[98:99]
	global_load_dwordx4 v[242:245], v176, s[98:99] offset:528
	global_load_dwordx4 v[246:249], v176, s[98:99] offset:512
	global_load_dword v250, v[162:163], off
	global_load_dword v251, v[164:165], off
	ds_read_b128 v[66:69], v173
	ds_read_b128 v[70:73], v173 offset:1024
	ds_read_b128 v[74:77], v173 offset:2048
	ds_read_b128 v[78:81], v173 offset:3072
	ds_read_b128 v[162:165], v174
	ds_read_b128 v[180:183], v174 offset:1024
	ds_read_b128 v[184:187], v174 offset:2048
	ds_read_b128 v[188:191], v174 offset:3072
	s_add_u32 s22, s16, 0xfff80080
	s_addc_u32 s23, s17, -1
	s_cmp_eq_u32 s50, 28
	s_cselect_b32 s41, s3, s23
	s_cselect_b32 s40, s15, s22
	s_cselect_b32 s23, s13, s49
	s_cselect_b32 s22, s24, s25
	v_lshl_add_u64 v[166:167], s[16:17], 0, v[156:157]
	s_add_i32 m0, s29, 0xc000
	ds_read_b128 v[192:195], v175
	ds_read_b128 v[196:199], v175 offset:1024
	ds_read_b128 v[200:203], v175 offset:2048
	ds_read_b128 v[204:207], v175 offset:3072
	ds_read_b128 v[208:211], v175 offset:4096
	ds_read_b128 v[212:215], v175 offset:5120
	ds_read_b128 v[216:219], v175 offset:6144
	ds_read_b128 v[220:223], v175 offset:7168
	global_load_lds_dwordx4 v[166:167], off
	v_lshl_add_u64 v[166:167], s[16:17], 0, v[154:155]
	s_add_i32 m0, s29, 0xe000
	s_nop 0
	global_load_lds_dwordx4 v[166:167], off
	s_waitcnt lgkmcnt(0)
	s_barrier
	s_waitcnt lgkmcnt(0)
	v_mfma_f32_16x16x32_bf16 v[142:145], v[66:69], v[192:195], 0
	v_mfma_f32_16x16x32_bf16 v[138:141], v[74:77], v[192:195], 0
	v_mfma_f32_16x16x32_bf16 v[126:129], v[66:69], v[200:203], 0
	v_mfma_f32_16x16x32_bf16 v[122:125], v[74:77], v[200:203], 0
	v_mfma_f32_16x16x32_bf16 v[110:113], v[66:69], v[208:211], 0
	v_mfma_f32_16x16x32_bf16 v[106:109], v[74:77], v[208:211], 0
	v_mfma_f32_16x16x32_bf16 v[94:97], v[66:69], v[216:219], 0
	v_mfma_f32_16x16x32_bf16 v[90:93], v[74:77], v[216:219], 0
	v_mfma_f32_16x16x32_bf16 v[142:145], v[70:73], v[196:199], v[142:145]
	v_mfma_f32_16x16x32_bf16 v[138:141], v[78:81], v[196:199], v[138:141]
	v_mfma_f32_16x16x32_bf16 v[126:129], v[70:73], v[204:207], v[126:129]
	v_mfma_f32_16x16x32_bf16 v[122:125], v[78:81], v[204:207], v[122:125]
	v_mfma_f32_16x16x32_bf16 v[110:113], v[70:73], v[212:215], v[110:113]
	v_mfma_f32_16x16x32_bf16 v[106:109], v[78:81], v[212:215], v[106:109]
	v_mfma_f32_16x16x32_bf16 v[94:97], v[70:73], v[220:223], v[94:97]
	v_mfma_f32_16x16x32_bf16 v[90:93], v[78:81], v[220:223], v[90:93]
	v_mfma_f32_16x16x32_bf16 v[134:137], v[162:165], v[192:195], 0
	v_mfma_f32_16x16x32_bf16 v[130:133], v[184:187], v[192:195], 0
	v_mfma_f32_16x16x32_bf16 v[118:121], v[162:165], v[200:203], 0
	v_mfma_f32_16x16x32_bf16 v[114:117], v[184:187], v[200:203], 0
	v_mfma_f32_16x16x32_bf16 v[102:105], v[162:165], v[208:211], 0
	v_mfma_f32_16x16x32_bf16 v[98:101], v[184:187], v[208:211], 0
	v_mfma_f32_16x16x32_bf16 v[86:89], v[162:165], v[216:219], 0
	v_mfma_f32_16x16x32_bf16 v[82:85], v[184:187], v[216:219], 0
	v_mfma_f32_16x16x32_bf16 v[134:137], v[180:183], v[196:199], v[134:137]
	v_mfma_f32_16x16x32_bf16 v[130:133], v[188:191], v[196:199], v[130:133]
	v_mfma_f32_16x16x32_bf16 v[118:121], v[180:183], v[204:207], v[118:121]
	v_mfma_f32_16x16x32_bf16 v[114:117], v[188:191], v[204:207], v[114:117]
	v_mfma_f32_16x16x32_bf16 v[102:105], v[180:183], v[212:215], v[102:105]
	v_mfma_f32_16x16x32_bf16 v[98:101], v[188:191], v[212:215], v[98:101]
	v_mfma_f32_16x16x32_bf16 v[86:89], v[180:183], v[220:223], v[86:89]
	v_mfma_f32_16x16x32_bf16 v[82:85], v[188:191], v[220:223], v[82:85]
	s_barrier
	s_add_i32 s51, s44, s26
	v_lshl_add_u64 v[166:167], s[22:23], 0, v[150:151]
	s_mov_b32 m0, s51
	ds_read_b128 v[192:195], v175 offset:16384
	ds_read_b128 v[196:199], v175 offset:17408
	ds_read_b128 v[200:203], v175 offset:18432
	ds_read_b128 v[204:207], v175 offset:19456
	ds_read_b128 v[208:211], v175 offset:20480
	ds_read_b128 v[212:215], v175 offset:21504
	ds_read_b128 v[216:219], v175 offset:22528
	ds_read_b128 v[220:223], v175 offset:23552
	global_load_lds_dwordx4 v[166:167], off
	s_add_i32 m0, s51, 0x2000
	s_add_u32 s52, s22, 0x80000
	v_lshl_add_u64 v[224:225], s[22:23], 0, v[146:147]
	s_addc_u32 s53, s23, 0
	s_add_i32 s51, s45, s26
	global_load_lds_dwordx4 v[224:225], off
	v_lshl_add_u64 v[226:227], s[52:53], 0, v[150:151]
	s_mov_b32 m0, s51
	v_lshl_add_u64 v[228:229], s[40:41], 0, v[148:149]
	global_load_lds_dwordx4 v[226:227], off
	v_lshl_add_u64 v[226:227], s[52:53], 0, v[146:147]
	s_add_i32 m0, s51, 0x2000
	s_nop 0
	global_load_lds_dwordx4 v[226:227], off
	v_lshl_add_u64 v[226:227], s[40:41], 0, v[152:153]
	s_mov_b32 m0, s29
	s_nop 0
	global_load_lds_dwordx4 v[226:227], off
	s_mov_b32 m0, s30
	s_nop 0
	global_load_lds_dwordx4 v[228:229], off
	s_waitcnt lgkmcnt(0)
	s_barrier
; #define PG8_STAGE(bufoff, gbase, voff) do { _Pragma("unroll") for (int _i = 0; _i < 2; ++_i) \
;         __builtin_amdgcn_global_load_lds((const unsigned*)((const char*)(gbase) + (voff)[_i]), (LAS unsigned*)(lds + (bufoff) + ldsw + _i * 8192), 16, 0, 0); } while (0)
; #define PG8_LDA(dst, b, h) do { _Pragma("unroll") for (int m = 0; m < 4; ++m) _Pragma("unroll") for (int k = 0; k < 2; ++k) dst[m][k] = *(const LAS bf16x8*)(lds + PG8_SA(b, h) + aoff + m * 2048 + k * 1024); } while (0)
; #define PG8_LDB(dst, b, h) do { _Pragma("unroll") for (int n = 0; n < 2; ++n) _Pragma("unroll") for (int k = 0; k < 2; ++k) dst[n][k] = *(const LAS bf16x8*)(lds + PG8_SB(b, h) + boff + n * 2048 + k * 1024); } while (0)
; #define PG8_MMA(ai, bj, At, Bt) do { __builtin_amdgcn_s_setprio(1); _Pragma("unroll") for (int m = 0; m < 4; ++m) _Pragma("unroll") for (int n = 0; n < 2; ++n) _Pragma("unroll") for (int k = 0; k < 2; ++k) \
;         acc[ai][bj][m][n] = __builtin_amdgcn_mfma_f32_16x16x32_bf16(Bt[n][k], At[m][k], acc[ai][bj][m][n], 0, 0, 0); __builtin_amdgcn_s_setprio(0); } while (0)
; #define PG8_WAIT_V(n) asm volatile("s_waitcnt vmcnt(" #n ")" ::: "memory")
; #define PG8_WAIT_L(n) asm volatile("s_waitcnt lgkmcnt(" #n ")" ::: "memory")
; #define PG8_BAR __builtin_amdgcn_s_barrier()
; #define PG8_SCHED __builtin_amdgcn_sched_barrier(0)
; template <class Epi, class Sched, bool ALIGN_EPI = false, bool SP2 = false>
; __device__ __forceinline__ void gemm_phase(LAS unsigned char* lds, const Gemm g, const Sched& S, const Epi& E) {
;     ...
;             PG8_LDB(B0, 0, 0); PG8_LDB(B1, 0, 1); PG8_SCHED; PG8_LDA(At, 0, 0); PG8_STAGE(PG8_SA(1, 1), a1 + hstep, voffA);
;             PG8_WAIT_V(8); PG8_WAIT_L(0); PG8_BAR; PG8_MMA(0, 0, At, B0); PG8_MMA(0, 1, At, B1); PG8_BAR; PG8_SCHED;
;             PG8_LDA(At, 0, 1); PG8_STAGE(PG8_SB(0, 0), b2, voffB); PG8_STAGE(PG8_SB(0, 1), b2 + hstepB, voffB); PG8_STAGE(PG8_SA(0, 0), a2, voffA);
;             PG8_WAIT_V(8); PG8_WAIT_L(0); PG8_BAR; PG8_MMA(1, 0, At, B0); PG8_MMA(1, 1, At, B1); PG8_BAR; PG8_SCHED;
;             PG8_LDB(B0, 1, 0); PG8_LDB(B1, 1, 1); PG8_SCHED; PG8_LDA(At, 1, 0); PG8_STAGE(PG8_SA(0, 1), a2 + hstep, voffA);
;             PG8_WAIT_V(8); PG8_WAIT_L(0); PG8_BAR; PG8_MMA(0, 0, At, B0); PG8_MMA(0, 1, At, B1); PG8_BAR; PG8_SCHED;
	s_waitcnt lgkmcnt(0)
	v_mfma_f32_16x16x32_bf16 v[62:65], v[66:69], v[192:195], 0
	v_mfma_f32_16x16x32_bf16 v[58:61], v[74:77], v[192:195], 0
	v_mfma_f32_16x16x32_bf16 v[46:49], v[66:69], v[200:203], 0
	v_mfma_f32_16x16x32_bf16 v[42:45], v[74:77], v[200:203], 0
	v_mfma_f32_16x16x32_bf16 v[30:33], v[66:69], v[208:211], 0
	v_mfma_f32_16x16x32_bf16 v[26:29], v[74:77], v[208:211], 0
	v_mfma_f32_16x16x32_bf16 v[14:17], v[66:69], v[216:219], 0
	v_mfma_f32_16x16x32_bf16 v[10:13], v[74:77], v[216:219], 0
	v_mfma_f32_16x16x32_bf16 v[62:65], v[70:73], v[196:199], v[62:65]
	v_mfma_f32_16x16x32_bf16 v[58:61], v[78:81], v[196:199], v[58:61]
	v_mfma_f32_16x16x32_bf16 v[46:49], v[70:73], v[204:207], v[46:49]
	v_mfma_f32_16x16x32_bf16 v[42:45], v[78:81], v[204:207], v[42:45]
	v_mfma_f32_16x16x32_bf16 v[30:33], v[70:73], v[212:215], v[30:33]
	v_mfma_f32_16x16x32_bf16 v[26:29], v[78:81], v[212:215], v[26:29]
	v_mfma_f32_16x16x32_bf16 v[14:17], v[70:73], v[220:223], v[14:17]
	v_mfma_f32_16x16x32_bf16 v[10:13], v[78:81], v[220:223], v[10:13]
	v_mfma_f32_16x16x32_bf16 v[54:57], v[162:165], v[192:195], 0
	v_mfma_f32_16x16x32_bf16 v[50:53], v[184:187], v[192:195], 0
	v_mfma_f32_16x16x32_bf16 v[38:41], v[162:165], v[200:203], 0
	v_mfma_f32_16x16x32_bf16 v[34:37], v[184:187], v[200:203], 0
	v_mfma_f32_16x16x32_bf16 v[22:25], v[162:165], v[208:211], 0
	v_mfma_f32_16x16x32_bf16 v[18:21], v[184:187], v[208:211], 0
	v_mfma_f32_16x16x32_bf16 v[6:9], v[162:165], v[216:219], 0
	v_mfma_f32_16x16x32_bf16 v[2:5], v[184:187], v[216:219], 0
	v_mfma_f32_16x16x32_bf16 v[54:57], v[180:183], v[196:199], v[54:57]
	v_mfma_f32_16x16x32_bf16 v[50:53], v[188:191], v[196:199], v[50:53]
	v_mfma_f32_16x16x32_bf16 v[38:41], v[180:183], v[204:207], v[38:41]
	v_mfma_f32_16x16x32_bf16 v[34:37], v[188:191], v[204:207], v[34:37]
	v_mfma_f32_16x16x32_bf16 v[22:25], v[180:183], v[212:215], v[22:25]
	v_mfma_f32_16x16x32_bf16 v[18:21], v[188:191], v[212:215], v[18:21]
	v_mfma_f32_16x16x32_bf16 v[6:9], v[180:183], v[220:223], v[6:9]
	v_mfma_f32_16x16x32_bf16 v[2:5], v[188:191], v[220:223], v[2:5]
	s_barrier
	s_add_i32 s51, 0, 0x18000
	s_add_i32 s52, 0, 0x1c000
	v_add_u32_e32 v78, s51, v169
	v_add_u32_e32 v168, s52, v169
	ds_read_b128 v[66:69], v78
	ds_read_b128 v[70:73], v78 offset:1024
	ds_read_b128 v[74:77], v78 offset:2048
	ds_read_b128 v[78:81], v78 offset:3072
	ds_read_b128 v[162:165], v168
	ds_read_b128 v[180:183], v168 offset:1024
	ds_read_b128 v[184:187], v168 offset:2048
	ds_read_b128 v[188:191], v168 offset:3072
	s_add_u32 s40, s40, 0x80000
	s_addc_u32 s41, s41, 0
	s_mov_b32 m0, s31
	v_lshl_add_u64 v[230:231], s[40:41], 0, v[152:153]
	ds_read_b128 v[192:195], v175 offset:32768
	ds_read_b128 v[196:199], v175 offset:33792
	ds_read_b128 v[200:203], v175 offset:34816
	ds_read_b128 v[204:207], v175 offset:35840
	ds_read_b128 v[208:211], v175 offset:36864
	ds_read_b128 v[212:215], v175 offset:37888
	ds_read_b128 v[216:219], v175 offset:38912
	ds_read_b128 v[220:223], v175 offset:39936
	global_load_lds_dwordx4 v[230:231], off
	v_lshl_add_u64 v[230:231], s[40:41], 0, v[148:149]
	s_mov_b32 m0, s33
	s_nop 0
	global_load_lds_dwordx4 v[230:231], off
	s_waitcnt vmcnt(8)
	s_waitcnt lgkmcnt(0)
	s_barrier
	s_waitcnt lgkmcnt(0)
	v_mfma_f32_16x16x32_bf16 v[142:145], v[66:69], v[192:195], v[142:145]
	v_mfma_f32_16x16x32_bf16 v[138:141], v[74:77], v[192:195], v[138:141]
	v_mfma_f32_16x16x32_bf16 v[126:129], v[66:69], v[200:203], v[126:129]
	v_mfma_f32_16x16x32_bf16 v[122:125], v[74:77], v[200:203], v[122:125]
	v_mfma_f32_16x16x32_bf16 v[110:113], v[66:69], v[208:211], v[110:113]
	v_mfma_f32_16x16x32_bf16 v[106:109], v[74:77], v[208:211], v[106:109]
	v_mfma_f32_16x16x32_bf16 v[94:97], v[66:69], v[216:219], v[94:97]
	v_mfma_f32_16x16x32_bf16 v[90:93], v[74:77], v[216:219], v[90:93]
	v_mfma_f32_16x16x32_bf16 v[142:145], v[70:73], v[196:199], v[142:145]
	v_mfma_f32_16x16x32_bf16 v[138:141], v[78:81], v[196:199], v[138:141]
	v_mfma_f32_16x16x32_bf16 v[126:129], v[70:73], v[204:207], v[126:129]
	v_mfma_f32_16x16x32_bf16 v[122:125], v[78:81], v[204:207], v[122:125]
	v_mfma_f32_16x16x32_bf16 v[110:113], v[70:73], v[212:215], v[110:113]
	v_mfma_f32_16x16x32_bf16 v[106:109], v[78:81], v[212:215], v[106:109]
	v_mfma_f32_16x16x32_bf16 v[94:97], v[70:73], v[220:223], v[94:97]
	v_mfma_f32_16x16x32_bf16 v[90:93], v[78:81], v[220:223], v[90:93]
	v_mfma_f32_16x16x32_bf16 v[134:137], v[162:165], v[192:195], v[134:137]
	v_mfma_f32_16x16x32_bf16 v[130:133], v[184:187], v[192:195], v[130:133]
	v_mfma_f32_16x16x32_bf16 v[118:121], v[162:165], v[200:203], v[118:121]
	v_mfma_f32_16x16x32_bf16 v[114:117], v[184:187], v[200:203], v[114:117]
	v_mfma_f32_16x16x32_bf16 v[102:105], v[162:165], v[208:211], v[102:105]
	v_mfma_f32_16x16x32_bf16 v[98:101], v[184:187], v[208:211], v[98:101]
	v_mfma_f32_16x16x32_bf16 v[86:89], v[162:165], v[216:219], v[86:89]
	v_mfma_f32_16x16x32_bf16 v[82:85], v[184:187], v[216:219], v[82:85]
	v_mfma_f32_16x16x32_bf16 v[134:137], v[180:183], v[196:199], v[134:137]
	v_mfma_f32_16x16x32_bf16 v[130:133], v[188:191], v[196:199], v[130:133]
	v_mfma_f32_16x16x32_bf16 v[118:121], v[180:183], v[204:207], v[118:121]
	v_mfma_f32_16x16x32_bf16 v[114:117], v[188:191], v[204:207], v[114:117]
	v_mfma_f32_16x16x32_bf16 v[102:105], v[180:183], v[212:215], v[102:105]
	v_mfma_f32_16x16x32_bf16 v[98:101], v[188:191], v[212:215], v[98:101]
	v_mfma_f32_16x16x32_bf16 v[86:89], v[180:183], v[220:223], v[86:89]
	v_mfma_f32_16x16x32_bf16 v[82:85], v[188:191], v[220:223], v[82:85]
	s_barrier
; #define PG8_STAGE(bufoff, gbase, voff) do { _Pragma("unroll") for (int _i = 0; _i < 2; ++_i) \
;         __builtin_amdgcn_global_load_lds((const unsigned*)((const char*)(gbase) + (voff)[_i]), (LAS unsigned*)(lds + (bufoff) + ldsw + _i * 8192), 16, 0, 0); } while (0)
; #define PG8_LDA(dst, b, h) do { _Pragma("unroll") for (int m = 0; m < 4; ++m) _Pragma("unroll") for (int k = 0; k < 2; ++k) dst[m][k] = *(const LAS bf16x8*)(lds + PG8_SA(b, h) + aoff + m * 2048 + k * 1024); } while (0)
; #define PG8_LDB(dst, b, h) do { _Pragma("unroll") for (int n = 0; n < 2; ++n) _Pragma("unroll") for (int k = 0; k < 2; ++k) dst[n][k] = *(const LAS bf16x8*)(lds + PG8_SB(b, h) + boff + n * 2048 + k * 1024); } while (0)
; #define PG8_MMA(ai, bj, At, Bt) do { __builtin_amdgcn_s_setprio(1); _Pragma("unroll") for (int m = 0; m < 4; ++m) _Pragma("unroll") for (int n = 0; n < 2; ++n) _Pragma("unroll") for (int k = 0; k < 2; ++k) \
;         acc[ai][bj][m][n] = __builtin_amdgcn_mfma_f32_16x16x32_bf16(Bt[n][k], At[m][k], acc[ai][bj][m][n], 0, 0, 0); __builtin_amdgcn_s_setprio(0); } while (0)
; #define PG8_WAIT_V(n) asm volatile("s_waitcnt vmcnt(" #n ")" ::: "memory")
; #define PG8_WAIT_L(n) asm volatile("s_waitcnt lgkmcnt(" #n ")" ::: "memory")
; #define PG8_BAR __builtin_amdgcn_s_barrier()
; #define PG8_SCHED __builtin_amdgcn_sched_barrier(0)
; template <class Epi, class Sched, bool ALIGN_EPI = false, bool SP2 = false>
; __device__ __forceinline__ void gemm_phase(LAS unsigned char* lds, const Gemm g, const Sched& S, const Epi& E) {
;     ...
;             PG8_LDB(B0, 0, 0); PG8_LDB(B1, 0, 1); PG8_SCHED; PG8_LDA(At, 0, 0); PG8_STAGE(PG8_SA(1, 1), a1 + hstep, voffA);
;             PG8_WAIT_V(8); PG8_WAIT_L(0); PG8_BAR; PG8_MMA(0, 0, At, B0); PG8_MMA(0, 1, At, B1); PG8_BAR; PG8_SCHED;
;     ...
;             PG8_LDA(At, 1, 1); PG8_STAGE(PG8_SB(1, 0), b3, voffB); PG8_STAGE(PG8_SB(1, 1), b3 + hstepB, voffB); PG8_STAGE(PG8_SA(1, 0), a3, voffA);
;             PG8_WAIT_V(8); PG8_WAIT_L(0); PG8_BAR; PG8_MMA(1, 0, At, B0); PG8_MMA(1, 1, At, B1); PG8_BAR; PG8_SCHED;
	s_add_i32 s40, s51, s26
	v_lshl_add_u64 v[166:167], v[166:167], 0, s[8:9]
	s_mov_b32 m0, s40
	ds_read_b128 v[192:195], v175 offset:49152
	ds_read_b128 v[196:199], v175 offset:50176
	ds_read_b128 v[200:203], v175 offset:51200
	ds_read_b128 v[204:207], v175 offset:52224
	ds_read_b128 v[208:211], v175 offset:53248
	ds_read_b128 v[212:215], v175 offset:54272
	ds_read_b128 v[216:219], v175 offset:55296
	ds_read_b128 v[220:223], v175 offset:56320
	global_load_lds_dwordx4 v[166:167], off
	s_add_i32 m0, s40, 0x2000
	s_add_u32 s22, s22, 0x80080
	v_lshl_add_u64 v[166:167], v[224:225], 0, s[8:9]
	s_addc_u32 s23, s23, 0
	s_add_i32 s40, s52, s26
	global_load_lds_dwordx4 v[166:167], off
	v_lshl_add_u64 v[166:167], s[22:23], 0, v[150:151]
	s_mov_b32 m0, s40
	s_nop 0
	global_load_lds_dwordx4 v[166:167], off
	v_lshl_add_u64 v[166:167], s[22:23], 0, v[146:147]
	s_add_i32 m0, s40, 0x2000
	s_nop 0
	global_load_lds_dwordx4 v[166:167], off
	v_lshl_add_u64 v[166:167], v[226:227], 0, s[8:9]
	s_mov_b32 m0, s42
	s_nop 0
	global_load_lds_dwordx4 v[166:167], off
	v_lshl_add_u64 v[166:167], v[228:229], 0, s[8:9]
	s_mov_b32 m0, s43
	s_nop 0
	global_load_lds_dwordx4 v[166:167], off
	s_waitcnt vmcnt(8)
	s_waitcnt lgkmcnt(0)
	s_barrier
	s_waitcnt lgkmcnt(0)
	v_mfma_f32_16x16x32_bf16 v[62:65], v[66:69], v[192:195], v[62:65]
	v_mfma_f32_16x16x32_bf16 v[58:61], v[74:77], v[192:195], v[58:61]
	v_mfma_f32_16x16x32_bf16 v[46:49], v[66:69], v[200:203], v[46:49]
	v_mfma_f32_16x16x32_bf16 v[42:45], v[74:77], v[200:203], v[42:45]
	v_mfma_f32_16x16x32_bf16 v[30:33], v[66:69], v[208:211], v[30:33]
	v_mfma_f32_16x16x32_bf16 v[26:29], v[74:77], v[208:211], v[26:29]
	v_mfma_f32_16x16x32_bf16 v[14:17], v[66:69], v[216:219], v[14:17]
	v_mfma_f32_16x16x32_bf16 v[10:13], v[74:77], v[216:219], v[10:13]
	v_mfma_f32_16x16x32_bf16 v[62:65], v[70:73], v[196:199], v[62:65]
	v_mfma_f32_16x16x32_bf16 v[58:61], v[78:81], v[196:199], v[58:61]
	v_mfma_f32_16x16x32_bf16 v[46:49], v[70:73], v[204:207], v[46:49]
	v_mfma_f32_16x16x32_bf16 v[42:45], v[78:81], v[204:207], v[42:45]
	v_mfma_f32_16x16x32_bf16 v[30:33], v[70:73], v[212:215], v[30:33]
	v_mfma_f32_16x16x32_bf16 v[26:29], v[78:81], v[212:215], v[26:29]
	v_mfma_f32_16x16x32_bf16 v[14:17], v[70:73], v[220:223], v[14:17]
	v_mfma_f32_16x16x32_bf16 v[10:13], v[78:81], v[220:223], v[10:13]
	v_mfma_f32_16x16x32_bf16 v[54:57], v[162:165], v[192:195], v[54:57]
	v_mfma_f32_16x16x32_bf16 v[50:53], v[184:187], v[192:195], v[50:53]
	v_mfma_f32_16x16x32_bf16 v[38:41], v[162:165], v[200:203], v[38:41]
	v_mfma_f32_16x16x32_bf16 v[34:37], v[184:187], v[200:203], v[34:37]
	v_mfma_f32_16x16x32_bf16 v[22:25], v[162:165], v[208:211], v[22:25]
	v_mfma_f32_16x16x32_bf16 v[18:21], v[184:187], v[208:211], v[18:21]
	v_mfma_f32_16x16x32_bf16 v[6:9], v[162:165], v[216:219], v[6:9]
	v_mfma_f32_16x16x32_bf16 v[2:5], v[184:187], v[216:219], v[2:5]
	v_mfma_f32_16x16x32_bf16 v[54:57], v[180:183], v[196:199], v[54:57]
	v_mfma_f32_16x16x32_bf16 v[50:53], v[188:191], v[196:199], v[50:53]
	v_mfma_f32_16x16x32_bf16 v[38:41], v[180:183], v[204:207], v[38:41]
	v_mfma_f32_16x16x32_bf16 v[34:37], v[188:191], v[204:207], v[34:37]
	v_mfma_f32_16x16x32_bf16 v[22:25], v[180:183], v[212:215], v[22:25]
	v_mfma_f32_16x16x32_bf16 v[18:21], v[188:191], v[212:215], v[18:21]
	v_mfma_f32_16x16x32_bf16 v[6:9], v[180:183], v[220:223], v[6:9]
	v_mfma_f32_16x16x32_bf16 v[2:5], v[188:191], v[220:223], v[2:5]
	s_barrier
	s_add_i32 s50, s50, 2
	s_add_u32 s25, s25, 0x100
	s_addc_u32 s49, s49, 0
	s_add_u32 s16, s16, 0x100
	s_addc_u32 s17, s17, 0
	s_cmp_lt_u32 s50, 30
.LBB0_1822:
	ds_read_b128 v[66:69], v173
	ds_read_b128 v[70:73], v173 offset:1024
	ds_read_b128 v[74:77], v173 offset:2048
	ds_read_b128 v[78:81], v173 offset:3072
	ds_read_b128 v[162:165], v174
	ds_read_b128 v[180:183], v174 offset:1024
	ds_read_b128 v[184:187], v174 offset:2048
	ds_read_b128 v[188:191], v174 offset:3072
	s_add_u32 s22, s16, 0xfff80080
	s_addc_u32 s23, s17, -1
	s_cmp_eq_u32 s50, 28
	s_cselect_b32 s41, s3, s23
	s_cselect_b32 s40, s15, s22
	s_cselect_b32 s23, s13, s49
	s_cselect_b32 s22, s24, s25
	v_lshl_add_u64 v[166:167], s[16:17], 0, v[156:157]
	s_add_i32 m0, s29, 0xc000
	ds_read_b128 v[192:195], v175
	ds_read_b128 v[196:199], v175 offset:1024
	ds_read_b128 v[200:203], v175 offset:2048
	ds_read_b128 v[204:207], v175 offset:3072
	ds_read_b128 v[208:211], v175 offset:4096
	ds_read_b128 v[212:215], v175 offset:5120
	ds_read_b128 v[216:219], v175 offset:6144
	ds_read_b128 v[220:223], v175 offset:7168
	global_load_lds_dwordx4 v[166:167], off
	v_lshl_add_u64 v[166:167], s[16:17], 0, v[154:155]
	s_add_i32 m0, s29, 0xe000
	s_nop 0
	global_load_lds_dwordx4 v[166:167], off
	s_waitcnt vmcnt(8)
	s_waitcnt lgkmcnt(0)
	s_barrier
; #define PG8_STAGE(bufoff, gbase, voff) do { _Pragma("unroll") for (int _i = 0; _i < 2; ++_i) \
;         __builtin_amdgcn_global_load_lds((const unsigned*)((const char*)(gbase) + (voff)[_i]), (LAS unsigned*)(lds + (bufoff) + ldsw + _i * 8192), 16, 0, 0); } while (0)
; #define PG8_LDA(dst, b, h) do { _Pragma("unroll") for (int m = 0; m < 4; ++m) _Pragma("unroll") for (int k = 0; k < 2; ++k) dst[m][k] = *(const LAS bf16x8*)(lds + PG8_SA(b, h) + aoff + m * 2048 + k * 1024); } while (0)
; #define PG8_LDB(dst, b, h) do { _Pragma("unroll") for (int n = 0; n < 2; ++n) _Pragma("unroll") for (int k = 0; k < 2; ++k) dst[n][k] = *(const LAS bf16x8*)(lds + PG8_SB(b, h) + boff + n * 2048 + k * 1024); } while (0)
; #define PG8_MMA(ai, bj, At, Bt) do { __builtin_amdgcn_s_setprio(1); _Pragma("unroll") for (int m = 0; m < 4; ++m) _Pragma("unroll") for (int n = 0; n < 2; ++n) _Pragma("unroll") for (int k = 0; k < 2; ++k) \
;         acc[ai][bj][m][n] = __builtin_amdgcn_mfma_f32_16x16x32_bf16(Bt[n][k], At[m][k], acc[ai][bj][m][n], 0, 0, 0); __builtin_amdgcn_s_setprio(0); } while (0)
; #define PG8_WAIT_V(n) asm volatile("s_waitcnt vmcnt(" #n ")" ::: "memory")
; #define PG8_WAIT_L(n) asm volatile("s_waitcnt lgkmcnt(" #n ")" ::: "memory")
; #define PG8_BAR __builtin_amdgcn_s_barrier()
; #define PG8_SCHED __builtin_amdgcn_sched_barrier(0)
; template <class Epi, class Sched, bool ALIGN_EPI = false, bool SP2 = false>
; __device__ __forceinline__ void gemm_phase(LAS unsigned char* lds, const Gemm g, const Sched& S, const Epi& E) {
;     ...
;             PG8_LDB(B0, 0, 0); PG8_LDB(B1, 0, 1); PG8_SCHED; PG8_LDA(At, 0, 0); PG8_STAGE(PG8_SA(1, 1), a1 + hstep, voffA);
;             PG8_WAIT_V(8); PG8_WAIT_L(0); PG8_BAR; PG8_MMA(0, 0, At, B0); PG8_MMA(0, 1, At, B1); PG8_BAR; PG8_SCHED;
;             PG8_LDA(At, 0, 1); PG8_STAGE(PG8_SB(0, 0), b2, voffB); PG8_STAGE(PG8_SB(0, 1), b2 + hstepB, voffB); PG8_STAGE(PG8_SA(0, 0), a2, voffA);
;             PG8_WAIT_V(8); PG8_WAIT_L(0); PG8_BAR; PG8_MMA(1, 0, At, B0); PG8_MMA(1, 1, At, B1); PG8_BAR; PG8_SCHED;
;             PG8_LDB(B0, 1, 0); PG8_LDB(B1, 1, 1); PG8_SCHED; PG8_LDA(At, 1, 0); PG8_STAGE(PG8_SA(0, 1), a2 + hstep, voffA);
;             PG8_WAIT_V(8); PG8_WAIT_L(0); PG8_BAR; PG8_MMA(0, 0, At, B0); PG8_MMA(0, 1, At, B1); PG8_BAR; PG8_SCHED;
	s_waitcnt lgkmcnt(0)
	v_mfma_f32_16x16x32_bf16 v[142:145], v[66:69], v[192:195], v[142:145]
	v_mfma_f32_16x16x32_bf16 v[138:141], v[74:77], v[192:195], v[138:141]
	v_mfma_f32_16x16x32_bf16 v[126:129], v[66:69], v[200:203], v[126:129]
	v_mfma_f32_16x16x32_bf16 v[122:125], v[74:77], v[200:203], v[122:125]
	v_mfma_f32_16x16x32_bf16 v[110:113], v[66:69], v[208:211], v[110:113]
	v_mfma_f32_16x16x32_bf16 v[106:109], v[74:77], v[208:211], v[106:109]
	v_mfma_f32_16x16x32_bf16 v[94:97], v[66:69], v[216:219], v[94:97]
	v_mfma_f32_16x16x32_bf16 v[90:93], v[74:77], v[216:219], v[90:93]
	v_mfma_f32_16x16x32_bf16 v[142:145], v[70:73], v[196:199], v[142:145]
	v_mfma_f32_16x16x32_bf16 v[138:141], v[78:81], v[196:199], v[138:141]
	v_mfma_f32_16x16x32_bf16 v[126:129], v[70:73], v[204:207], v[126:129]
	v_mfma_f32_16x16x32_bf16 v[122:125], v[78:81], v[204:207], v[122:125]
	v_mfma_f32_16x16x32_bf16 v[110:113], v[70:73], v[212:215], v[110:113]
	v_mfma_f32_16x16x32_bf16 v[106:109], v[78:81], v[212:215], v[106:109]
	v_mfma_f32_16x16x32_bf16 v[94:97], v[70:73], v[220:223], v[94:97]
	v_mfma_f32_16x16x32_bf16 v[90:93], v[78:81], v[220:223], v[90:93]
	v_mfma_f32_16x16x32_bf16 v[134:137], v[162:165], v[192:195], v[134:137]
	v_mfma_f32_16x16x32_bf16 v[130:133], v[184:187], v[192:195], v[130:133]
	v_mfma_f32_16x16x32_bf16 v[118:121], v[162:165], v[200:203], v[118:121]
	v_mfma_f32_16x16x32_bf16 v[114:117], v[184:187], v[200:203], v[114:117]
	v_mfma_f32_16x16x32_bf16 v[102:105], v[162:165], v[208:211], v[102:105]
	v_mfma_f32_16x16x32_bf16 v[98:101], v[184:187], v[208:211], v[98:101]
	v_mfma_f32_16x16x32_bf16 v[86:89], v[162:165], v[216:219], v[86:89]
	v_mfma_f32_16x16x32_bf16 v[82:85], v[184:187], v[216:219], v[82:85]
	v_mfma_f32_16x16x32_bf16 v[134:137], v[180:183], v[196:199], v[134:137]
	v_mfma_f32_16x16x32_bf16 v[130:133], v[188:191], v[196:199], v[130:133]
	v_mfma_f32_16x16x32_bf16 v[118:121], v[180:183], v[204:207], v[118:121]
	v_mfma_f32_16x16x32_bf16 v[114:117], v[188:191], v[204:207], v[114:117]
	v_mfma_f32_16x16x32_bf16 v[102:105], v[180:183], v[212:215], v[102:105]
	v_mfma_f32_16x16x32_bf16 v[98:101], v[188:191], v[212:215], v[98:101]
	v_mfma_f32_16x16x32_bf16 v[86:89], v[180:183], v[220:223], v[86:89]
	v_mfma_f32_16x16x32_bf16 v[82:85], v[188:191], v[220:223], v[82:85]
	s_barrier
	s_add_i32 s51, s44, s26
	v_lshl_add_u64 v[166:167], s[22:23], 0, v[150:151]
	s_mov_b32 m0, s51
	ds_read_b128 v[192:195], v175 offset:16384
	ds_read_b128 v[196:199], v175 offset:17408
	ds_read_b128 v[200:203], v175 offset:18432
	ds_read_b128 v[204:207], v175 offset:19456
	ds_read_b128 v[208:211], v175 offset:20480
	ds_read_b128 v[212:215], v175 offset:21504
	ds_read_b128 v[216:219], v175 offset:22528
	ds_read_b128 v[220:223], v175 offset:23552
	global_load_lds_dwordx4 v[166:167], off
	s_add_i32 m0, s51, 0x2000
	s_add_u32 s52, s22, 0x80000
	v_lshl_add_u64 v[224:225], s[22:23], 0, v[146:147]
	s_addc_u32 s53, s23, 0
	s_add_i32 s51, s45, s26
	global_load_lds_dwordx4 v[224:225], off
	v_lshl_add_u64 v[226:227], s[52:53], 0, v[150:151]
	s_mov_b32 m0, s51
	v_lshl_add_u64 v[228:229], s[40:41], 0, v[148:149]
	global_load_lds_dwordx4 v[226:227], off
	v_lshl_add_u64 v[226:227], s[52:53], 0, v[146:147]
	s_add_i32 m0, s51, 0x2000
	s_nop 0
	global_load_lds_dwordx4 v[226:227], off
	v_lshl_add_u64 v[226:227], s[40:41], 0, v[152:153]
	s_mov_b32 m0, s29
	s_nop 0
	global_load_lds_dwordx4 v[226:227], off
	s_mov_b32 m0, s30
	s_nop 0
	global_load_lds_dwordx4 v[228:229], off
	s_waitcnt vmcnt(8)
	s_waitcnt lgkmcnt(0)
	s_barrier
	s_waitcnt lgkmcnt(0)
	v_mfma_f32_16x16x32_bf16 v[62:65], v[66:69], v[192:195], v[62:65]
	v_mfma_f32_16x16x32_bf16 v[58:61], v[74:77], v[192:195], v[58:61]
	v_mfma_f32_16x16x32_bf16 v[46:49], v[66:69], v[200:203], v[46:49]
	v_mfma_f32_16x16x32_bf16 v[42:45], v[74:77], v[200:203], v[42:45]
	v_mfma_f32_16x16x32_bf16 v[30:33], v[66:69], v[208:211], v[30:33]
	v_mfma_f32_16x16x32_bf16 v[26:29], v[74:77], v[208:211], v[26:29]
	v_mfma_f32_16x16x32_bf16 v[14:17], v[66:69], v[216:219], v[14:17]
	v_mfma_f32_16x16x32_bf16 v[10:13], v[74:77], v[216:219], v[10:13]
	v_mfma_f32_16x16x32_bf16 v[62:65], v[70:73], v[196:199], v[62:65]
	v_mfma_f32_16x16x32_bf16 v[58:61], v[78:81], v[196:199], v[58:61]
	v_mfma_f32_16x16x32_bf16 v[46:49], v[70:73], v[204:207], v[46:49]
	v_mfma_f32_16x16x32_bf16 v[42:45], v[78:81], v[204:207], v[42:45]
	v_mfma_f32_16x16x32_bf16 v[30:33], v[70:73], v[212:215], v[30:33]
	v_mfma_f32_16x16x32_bf16 v[26:29], v[78:81], v[212:215], v[26:29]
	v_mfma_f32_16x16x32_bf16 v[14:17], v[70:73], v[220:223], v[14:17]
	v_mfma_f32_16x16x32_bf16 v[10:13], v[78:81], v[220:223], v[10:13]
	v_mfma_f32_16x16x32_bf16 v[54:57], v[162:165], v[192:195], v[54:57]
	v_mfma_f32_16x16x32_bf16 v[50:53], v[184:187], v[192:195], v[50:53]
	v_mfma_f32_16x16x32_bf16 v[38:41], v[162:165], v[200:203], v[38:41]
	v_mfma_f32_16x16x32_bf16 v[34:37], v[184:187], v[200:203], v[34:37]
	v_mfma_f32_16x16x32_bf16 v[22:25], v[162:165], v[208:211], v[22:25]
	v_mfma_f32_16x16x32_bf16 v[18:21], v[184:187], v[208:211], v[18:21]
	v_mfma_f32_16x16x32_bf16 v[6:9], v[162:165], v[216:219], v[6:9]
	v_mfma_f32_16x16x32_bf16 v[2:5], v[184:187], v[216:219], v[2:5]
	v_mfma_f32_16x16x32_bf16 v[54:57], v[180:183], v[196:199], v[54:57]
	v_mfma_f32_16x16x32_bf16 v[50:53], v[188:191], v[196:199], v[50:53]
	v_mfma_f32_16x16x32_bf16 v[38:41], v[180:183], v[204:207], v[38:41]
	v_mfma_f32_16x16x32_bf16 v[34:37], v[188:191], v[204:207], v[34:37]
	v_mfma_f32_16x16x32_bf16 v[22:25], v[180:183], v[212:215], v[22:25]
	v_mfma_f32_16x16x32_bf16 v[18:21], v[188:191], v[212:215], v[18:21]
	v_mfma_f32_16x16x32_bf16 v[6:9], v[180:183], v[220:223], v[6:9]
	v_mfma_f32_16x16x32_bf16 v[2:5], v[188:191], v[220:223], v[2:5]
	s_barrier
; #define PG8_STAGE(bufoff, gbase, voff) do { _Pragma("unroll") for (int _i = 0; _i < 2; ++_i) \
;         __builtin_amdgcn_global_load_lds((const unsigned*)((const char*)(gbase) + (voff)[_i]), (LAS unsigned*)(lds + (bufoff) + ldsw + _i * 8192), 16, 0, 0); } while (0)
; #define PG8_LDA(dst, b, h) do { _Pragma("unroll") for (int m = 0; m < 4; ++m) _Pragma("unroll") for (int k = 0; k < 2; ++k) dst[m][k] = *(const LAS bf16x8*)(lds + PG8_SA(b, h) + aoff + m * 2048 + k * 1024); } while (0)
; #define PG8_LDB(dst, b, h) do { _Pragma("unroll") for (int n = 0; n < 2; ++n) _Pragma("unroll") for (int k = 0; k < 2; ++k) dst[n][k] = *(const LAS bf16x8*)(lds + PG8_SB(b, h) + boff + n * 2048 + k * 1024); } while (0)
; #define PG8_MMA(ai, bj, At, Bt) do { __builtin_amdgcn_s_setprio(1); _Pragma("unroll") for (int m = 0; m < 4; ++m) _Pragma("unroll") for (int n = 0; n < 2; ++n) _Pragma("unroll") for (int k = 0; k < 2; ++k) \
;         acc[ai][bj][m][n] = __builtin_amdgcn_mfma_f32_16x16x32_bf16(Bt[n][k], At[m][k], acc[ai][bj][m][n], 0, 0, 0); __builtin_amdgcn_s_setprio(0); } while (0)
; #define PG8_WAIT_V(n) asm volatile("s_waitcnt vmcnt(" #n ")" ::: "memory")
; #define PG8_WAIT_L(n) asm volatile("s_waitcnt lgkmcnt(" #n ")" ::: "memory")
; #define PG8_BAR __builtin_amdgcn_s_barrier()
; #define PG8_SCHED __builtin_amdgcn_sched_barrier(0)
; template <class Epi, class Sched, bool ALIGN_EPI = false, bool SP2 = false>
; __device__ __forceinline__ void gemm_phase(LAS unsigned char* lds, const Gemm g, const Sched& S, const Epi& E) {
;     ...
;             PG8_LDB(B0, 1, 0); PG8_LDB(B1, 1, 1); PG8_SCHED; PG8_LDA(At, 1, 0); PG8_STAGE(PG8_SA(0, 1), a2 + hstep, voffA);
;             PG8_WAIT_V(8); PG8_WAIT_L(0); PG8_BAR; PG8_MMA(0, 0, At, B0); PG8_MMA(0, 1, At, B1); PG8_BAR; PG8_SCHED;
	s_add_i32 s51, 0, 0x18000
	s_add_i32 s52, 0, 0x1c000
	v_add_u32_e32 v78, s51, v169
	v_add_u32_e32 v168, s52, v169
	ds_read_b128 v[66:69], v78
	ds_read_b128 v[70:73], v78 offset:1024
	ds_read_b128 v[74:77], v78 offset:2048
	ds_read_b128 v[78:81], v78 offset:3072
	ds_read_b128 v[162:165], v168
	ds_read_b128 v[180:183], v168 offset:1024
	ds_read_b128 v[184:187], v168 offset:2048
	ds_read_b128 v[188:191], v168 offset:3072
	s_add_u32 s40, s40, 0x80000
	s_addc_u32 s41, s41, 0
	s_mov_b32 m0, s31
	v_lshl_add_u64 v[230:231], s[40:41], 0, v[152:153]
	ds_read_b128 v[192:195], v175 offset:32768
	ds_read_b128 v[196:199], v175 offset:33792
	ds_read_b128 v[200:203], v175 offset:34816
	ds_read_b128 v[204:207], v175 offset:35840
	ds_read_b128 v[208:211], v175 offset:36864
	ds_read_b128 v[212:215], v175 offset:37888
	ds_read_b128 v[216:219], v175 offset:38912
	ds_read_b128 v[220:223], v175 offset:39936
	global_load_lds_dwordx4 v[230:231], off
	v_lshl_add_u64 v[230:231], s[40:41], 0, v[148:149]
	s_mov_b32 m0, s33
	s_nop 0
	global_load_lds_dwordx4 v[230:231], off
	s_waitcnt vmcnt(8)
	s_waitcnt lgkmcnt(0)
	s_barrier
	s_waitcnt lgkmcnt(0)
	v_mfma_f32_16x16x32_bf16 v[142:145], v[66:69], v[192:195], v[142:145]
	v_mfma_f32_16x16x32_bf16 v[138:141], v[74:77], v[192:195], v[138:141]
	v_mfma_f32_16x16x32_bf16 v[126:129], v[66:69], v[200:203], v[126:129]
	v_mfma_f32_16x16x32_bf16 v[122:125], v[74:77], v[200:203], v[122:125]
	v_mfma_f32_16x16x32_bf16 v[110:113], v[66:69], v[208:211], v[110:113]
	v_mfma_f32_16x16x32_bf16 v[106:109], v[74:77], v[208:211], v[106:109]
	v_mfma_f32_16x16x32_bf16 v[94:97], v[66:69], v[216:219], v[94:97]
	v_mfma_f32_16x16x32_bf16 v[90:93], v[74:77], v[216:219], v[90:93]
	v_mfma_f32_16x16x32_bf16 v[142:145], v[70:73], v[196:199], v[142:145]
	v_mfma_f32_16x16x32_bf16 v[138:141], v[78:81], v[196:199], v[138:141]
	v_mfma_f32_16x16x32_bf16 v[126:129], v[70:73], v[204:207], v[126:129]
	v_mfma_f32_16x16x32_bf16 v[122:125], v[78:81], v[204:207], v[122:125]
	v_mfma_f32_16x16x32_bf16 v[110:113], v[70:73], v[212:215], v[110:113]
	v_mfma_f32_16x16x32_bf16 v[106:109], v[78:81], v[212:215], v[106:109]
	v_mfma_f32_16x16x32_bf16 v[94:97], v[70:73], v[220:223], v[94:97]
	v_mfma_f32_16x16x32_bf16 v[90:93], v[78:81], v[220:223], v[90:93]
	v_mfma_f32_16x16x32_bf16 v[134:137], v[162:165], v[192:195], v[134:137]
	v_mfma_f32_16x16x32_bf16 v[130:133], v[184:187], v[192:195], v[130:133]
	v_mfma_f32_16x16x32_bf16 v[118:121], v[162:165], v[200:203], v[118:121]
	v_mfma_f32_16x16x32_bf16 v[114:117], v[184:187], v[200:203], v[114:117]
	v_mfma_f32_16x16x32_bf16 v[102:105], v[162:165], v[208:211], v[102:105]
	v_mfma_f32_16x16x32_bf16 v[98:101], v[184:187], v[208:211], v[98:101]
	v_mfma_f32_16x16x32_bf16 v[86:89], v[162:165], v[216:219], v[86:89]
	v_mfma_f32_16x16x32_bf16 v[82:85], v[184:187], v[216:219], v[82:85]
	v_mfma_f32_16x16x32_bf16 v[134:137], v[180:183], v[196:199], v[134:137]
	v_mfma_f32_16x16x32_bf16 v[130:133], v[188:191], v[196:199], v[130:133]
	v_mfma_f32_16x16x32_bf16 v[118:121], v[180:183], v[204:207], v[118:121]
	v_mfma_f32_16x16x32_bf16 v[114:117], v[188:191], v[204:207], v[114:117]
	v_mfma_f32_16x16x32_bf16 v[102:105], v[180:183], v[212:215], v[102:105]
	v_mfma_f32_16x16x32_bf16 v[98:101], v[188:191], v[212:215], v[98:101]
	v_mfma_f32_16x16x32_bf16 v[86:89], v[180:183], v[220:223], v[86:89]
	v_mfma_f32_16x16x32_bf16 v[82:85], v[188:191], v[220:223], v[82:85]
	s_barrier
; #define PG8_STAGE(bufoff, gbase, voff) do { _Pragma("unroll") for (int _i = 0; _i < 2; ++_i) \
;         __builtin_amdgcn_global_load_lds((const unsigned*)((const char*)(gbase) + (voff)[_i]), (LAS unsigned*)(lds + (bufoff) + ldsw + _i * 8192), 16, 0, 0); } while (0)
; #define PG8_LDA(dst, b, h) do { _Pragma("unroll") for (int m = 0; m < 4; ++m) _Pragma("unroll") for (int k = 0; k < 2; ++k) dst[m][k] = *(const LAS bf16x8*)(lds + PG8_SA(b, h) + aoff + m * 2048 + k * 1024); } while (0)
; #define PG8_MMA(ai, bj, At, Bt) do { __builtin_amdgcn_s_setprio(1); _Pragma("unroll") for (int m = 0; m < 4; ++m) _Pragma("unroll") for (int n = 0; n < 2; ++n) _Pragma("unroll") for (int k = 0; k < 2; ++k) \
;         acc[ai][bj][m][n] = __builtin_amdgcn_mfma_f32_16x16x32_bf16(Bt[n][k], At[m][k], acc[ai][bj][m][n], 0, 0, 0); __builtin_amdgcn_s_setprio(0); } while (0)
; #define PG8_WAIT_V(n) asm volatile("s_waitcnt vmcnt(" #n ")" ::: "memory")
; #define PG8_WAIT_L(n) asm volatile("s_waitcnt lgkmcnt(" #n ")" ::: "memory")
; #define PG8_BAR __builtin_amdgcn_s_barrier()
; #define PG8_SCHED __builtin_amdgcn_sched_barrier(0)
; template <class Epi, class Sched, bool ALIGN_EPI = false, bool SP2 = false>
; __device__ __forceinline__ void gemm_phase(LAS unsigned char* lds, const Gemm g, const Sched& S, const Epi& E) {
;     ...
;         for (int t = 0; t < nt; t += 2) {
;     ...
;             PG8_LDA(At, 1, 1); PG8_STAGE(PG8_SB(1, 0), b3, voffB); PG8_STAGE(PG8_SB(1, 1), b3 + hstepB, voffB); PG8_STAGE(PG8_SA(1, 0), a3, voffA);
;             PG8_WAIT_V(8); PG8_WAIT_L(0); PG8_BAR; PG8_MMA(1, 0, At, B0); PG8_MMA(1, 1, At, B1); PG8_BAR; PG8_SCHED;
	s_add_i32 s40, s51, s26
	v_lshl_add_u64 v[166:167], v[166:167], 0, s[8:9]
	s_mov_b32 m0, s40
	ds_read_b128 v[192:195], v175 offset:49152
	ds_read_b128 v[196:199], v175 offset:50176
	ds_read_b128 v[200:203], v175 offset:51200
	ds_read_b128 v[204:207], v175 offset:52224
	ds_read_b128 v[208:211], v175 offset:53248
	ds_read_b128 v[212:215], v175 offset:54272
	ds_read_b128 v[216:219], v175 offset:55296
	ds_read_b128 v[220:223], v175 offset:56320
	global_load_lds_dwordx4 v[166:167], off
	s_add_i32 m0, s40, 0x2000
	s_add_u32 s22, s22, 0x80080
	v_lshl_add_u64 v[166:167], v[224:225], 0, s[8:9]
	s_addc_u32 s23, s23, 0
	s_add_i32 s40, s52, s26
	global_load_lds_dwordx4 v[166:167], off
	v_lshl_add_u64 v[166:167], s[22:23], 0, v[150:151]
	s_mov_b32 m0, s40
	s_nop 0
	global_load_lds_dwordx4 v[166:167], off
	v_lshl_add_u64 v[166:167], s[22:23], 0, v[146:147]
	s_add_i32 m0, s40, 0x2000
	s_nop 0
	global_load_lds_dwordx4 v[166:167], off
	v_lshl_add_u64 v[166:167], v[226:227], 0, s[8:9]
	s_mov_b32 m0, s42
	s_nop 0
	global_load_lds_dwordx4 v[166:167], off
	v_lshl_add_u64 v[166:167], v[228:229], 0, s[8:9]
	s_mov_b32 m0, s43
	s_nop 0
	global_load_lds_dwordx4 v[166:167], off
	s_waitcnt vmcnt(8)
	s_waitcnt lgkmcnt(0)
	s_barrier
	s_waitcnt lgkmcnt(0)
	v_mfma_f32_16x16x32_bf16 v[62:65], v[66:69], v[192:195], v[62:65]
	v_mfma_f32_16x16x32_bf16 v[58:61], v[74:77], v[192:195], v[58:61]
	v_mfma_f32_16x16x32_bf16 v[46:49], v[66:69], v[200:203], v[46:49]
	v_mfma_f32_16x16x32_bf16 v[42:45], v[74:77], v[200:203], v[42:45]
	v_mfma_f32_16x16x32_bf16 v[30:33], v[66:69], v[208:211], v[30:33]
	v_mfma_f32_16x16x32_bf16 v[26:29], v[74:77], v[208:211], v[26:29]
	v_mfma_f32_16x16x32_bf16 v[14:17], v[66:69], v[216:219], v[14:17]
	v_mfma_f32_16x16x32_bf16 v[10:13], v[74:77], v[216:219], v[10:13]
	v_mfma_f32_16x16x32_bf16 v[62:65], v[70:73], v[196:199], v[62:65]
	v_mfma_f32_16x16x32_bf16 v[58:61], v[78:81], v[196:199], v[58:61]
	v_mfma_f32_16x16x32_bf16 v[46:49], v[70:73], v[204:207], v[46:49]
	v_mfma_f32_16x16x32_bf16 v[42:45], v[78:81], v[204:207], v[42:45]
	v_mfma_f32_16x16x32_bf16 v[30:33], v[70:73], v[212:215], v[30:33]
	v_mfma_f32_16x16x32_bf16 v[26:29], v[78:81], v[212:215], v[26:29]
	v_mfma_f32_16x16x32_bf16 v[14:17], v[70:73], v[220:223], v[14:17]
	v_mfma_f32_16x16x32_bf16 v[10:13], v[78:81], v[220:223], v[10:13]
	v_mfma_f32_16x16x32_bf16 v[54:57], v[162:165], v[192:195], v[54:57]
	v_mfma_f32_16x16x32_bf16 v[50:53], v[184:187], v[192:195], v[50:53]
	v_mfma_f32_16x16x32_bf16 v[38:41], v[162:165], v[200:203], v[38:41]
	v_mfma_f32_16x16x32_bf16 v[34:37], v[184:187], v[200:203], v[34:37]
	v_mfma_f32_16x16x32_bf16 v[22:25], v[162:165], v[208:211], v[22:25]
	v_mfma_f32_16x16x32_bf16 v[18:21], v[184:187], v[208:211], v[18:21]
	v_mfma_f32_16x16x32_bf16 v[6:9], v[162:165], v[216:219], v[6:9]
	v_mfma_f32_16x16x32_bf16 v[2:5], v[184:187], v[216:219], v[2:5]
	v_mfma_f32_16x16x32_bf16 v[54:57], v[180:183], v[196:199], v[54:57]
	v_mfma_f32_16x16x32_bf16 v[50:53], v[188:191], v[196:199], v[50:53]
	v_mfma_f32_16x16x32_bf16 v[38:41], v[180:183], v[204:207], v[38:41]
	v_mfma_f32_16x16x32_bf16 v[34:37], v[188:191], v[204:207], v[34:37]
	v_mfma_f32_16x16x32_bf16 v[22:25], v[180:183], v[212:215], v[22:25]
	v_mfma_f32_16x16x32_bf16 v[18:21], v[188:191], v[212:215], v[18:21]
	v_mfma_f32_16x16x32_bf16 v[6:9], v[180:183], v[220:223], v[6:9]
	v_mfma_f32_16x16x32_bf16 v[2:5], v[188:191], v[220:223], v[2:5]
	s_barrier
	s_add_i32 s50, s50, 2
	s_add_u32 s25, s25, 0x100
	s_addc_u32 s49, s49, 0
	s_add_u32 s16, s16, 0x100
	s_addc_u32 s17, s17, 0
	s_cmp_lt_u32 s50, 30
	s_cbranch_scc1 .LBB0_1822
	s_andn2_b64 vcc, exec, s[10:11]
	s_cbranch_vccnz .LBB0_1825
	s_barrier

;     __device__ bool next(int i, Unit& u) const { if (i != 0 || c >= 128) return false; const int t = c >> 2; u.pm = t & 3; u.pn = t >> 2; u.koff = koff_bytes; u.q = c & 3; return true; }
; #define PG8_STAGE(bufoff, gbase, voff) do { _Pragma("unroll") for (int _i = 0; _i < 2; ++_i) \
;         __builtin_amdgcn_global_load_lds((const unsigned*)((const char*)(gbase) + (voff)[_i]), (LAS unsigned*)(lds + (bufoff) + ldsw + _i * 8192), 16, 0, 0); } while (0)
; #define PG8_LDA(dst, b, h) do { _Pragma("unroll") for (int m = 0; m < 4; ++m) _Pragma("unroll") for (int k = 0; k < 2; ++k) dst[m][k] = *(const LAS bf16x8*)(lds + PG8_SA(b, h) + aoff + m * 2048 + k * 1024); } while (0)
; #define PG8_LDB(dst, b, h) do { _Pragma("unroll") for (int n = 0; n < 2; ++n) _Pragma("unroll") for (int k = 0; k < 2; ++k) dst[n][k] = *(const LAS bf16x8*)(lds + PG8_SB(b, h) + boff + n * 2048 + k * 1024); } while (0)
; #define PG8_WAIT_V(n) asm volatile("s_waitcnt vmcnt(" #n ")" ::: "memory")
; template <class Epi, class Sched, bool ALIGN_EPI = false, bool SP2 = false>
; __device__ __forceinline__ void gemm_phase(LAS unsigned char* lds, const Gemm g, const Sched& S, const Epi& E) {
;     ...
;         const bool has_next = S.next(ui + 1, nxt);
;         const char* nA = has_next ? (const char*)g.A + (size_t)nxt.pm * tstep + nxt.koff : cA; const char* nB = has_next ? (const char*)g.Bt + (size_t)nxt.pn * tstep + nxt.koff : cB;
;         for (int t = 0; t < nt; t += 2) {
;             const bool last = (t == nt - 2);
;             const char* a1 = cA + (size_t)(t + 1) * kstep;
;             const char* a2 = last ? nA : cA + (size_t)(t + 2) * kstep; const char* b2 = last ? nB : cB + (size_t)(t + 2) * kstep;
;             const char* a3 = a2 + kstep; const char* b3 = b2 + kstep;
;             if (last && has_next) S.a_ready(nxt);
;             if constexpr (SP2) {
;             PG8_LDB(B0, 0, 0); PG8_LDB(B1, 0, 1); PG8_SCHED; PG8_LDA(At, 0, 0); PG8_STAGE(PG8_SA(1, 1), a1 + hstep, voffA);
;             PG8_WAIT_V(8); PG8_WAIT_L(0); PG8_BAR; PG8_MMA(0, 0, At, B0); PG8_MMA(0, 1, At, B1); PG8_BAR; PG8_SCHED;
;             PG8_LDA(At, 0, 1); PG8_STAGE(PG8_SB(0, 0), b2, voffB); PG8_STAGE(PG8_SB(0, 1), b2 + hstepB, voffB); PG8_STAGE(PG8_SA(0, 0), a2, voffA);
;             PG8_WAIT_V(8); PG8_WAIT_L(0); PG8_BAR; PG8_MMA(1, 0, At, B0); PG8_MMA(1, 1, At, B1); PG8_BAR; PG8_SCHED;
.LBB0_1896:
	ds_read_b128 v[144:147], v135
	ds_read_b128 v[148:151], v135 offset:1024
	ds_read_b128 v[152:155], v135 offset:2048
	ds_read_b128 v[156:159], v135 offset:3072
	ds_read_b128 v[160:163], v140
	ds_read_b128 v[164:167], v140 offset:1024
	ds_read_b128 v[168:171], v140 offset:2048
	ds_read_b128 v[172:175], v140 offset:3072
	s_add_i32 s40, s14, 2
	s_cmp_lg_u32 s28, s14
	s_cselect_b32 s14, s10, 0
	s_cselect_b32 s15, s11, 0
	s_add_u32 s16, s4, s14
	s_addc_u32 s17, s5, s15
	s_add_u32 s14, s2, s14
	s_addc_u32 s15, s3, s15
	v_lshl_add_u64 v[208:209], v[138:139], 0, s[10:11]
	s_mov_b32 m0, s29
	v_lshl_add_u64 v[208:209], v[208:209], 0, s[12:13]
	ds_read_b128 v[176:179], v141
	ds_read_b128 v[180:183], v141 offset:1024
	ds_read_b128 v[184:187], v141 offset:2048
	ds_read_b128 v[188:191], v141 offset:3072
	ds_read_b128 v[192:195], v141 offset:4096
	ds_read_b128 v[196:199], v141 offset:5120
	ds_read_b128 v[200:203], v141 offset:6144
	ds_read_b128 v[204:207], v141 offset:7168
	global_load_lds_dwordx4 v[208:209], off
	v_lshl_add_u64 v[208:209], v[136:137], 0, s[10:11]
	v_lshl_add_u64 v[208:209], v[208:209], 0, s[12:13]
	s_mov_b32 m0, s30
	s_nop 0
	global_load_lds_dwordx4 v[208:209], off
	s_waitcnt vmcnt(8)
	s_waitcnt lgkmcnt(0)
	s_barrier
	s_waitcnt lgkmcnt(0)
	v_mfma_f32_16x16x32_bf16 v[126:129], v[144:147], v[176:179], v[126:129]
	v_mfma_f32_16x16x32_bf16 v[94:97], v[152:155], v[176:179], v[94:97]
	v_mfma_f32_16x16x32_bf16 v[122:125], v[144:147], v[184:187], v[122:125]
	v_mfma_f32_16x16x32_bf16 v[90:93], v[152:155], v[184:187], v[90:93]
	v_mfma_f32_16x16x32_bf16 v[118:121], v[144:147], v[192:195], v[118:121]
	v_mfma_f32_16x16x32_bf16 v[86:89], v[152:155], v[192:195], v[86:89]
	v_mfma_f32_16x16x32_bf16 v[114:117], v[144:147], v[200:203], v[114:117]
	v_mfma_f32_16x16x32_bf16 v[82:85], v[152:155], v[200:203], v[82:85]
	v_mfma_f32_16x16x32_bf16 v[126:129], v[148:151], v[180:183], v[126:129]
	v_mfma_f32_16x16x32_bf16 v[94:97], v[156:159], v[180:183], v[94:97]
	v_mfma_f32_16x16x32_bf16 v[122:125], v[148:151], v[188:191], v[122:125]
	v_mfma_f32_16x16x32_bf16 v[90:93], v[156:159], v[188:191], v[90:93]
	v_mfma_f32_16x16x32_bf16 v[118:121], v[148:151], v[196:199], v[118:121]
	v_mfma_f32_16x16x32_bf16 v[86:89], v[156:159], v[196:199], v[86:89]
	v_mfma_f32_16x16x32_bf16 v[114:117], v[148:151], v[204:207], v[114:117]
	v_mfma_f32_16x16x32_bf16 v[82:85], v[156:159], v[204:207], v[82:85]
	v_mfma_f32_16x16x32_bf16 v[70:73], v[160:163], v[176:179], v[70:73]
	v_mfma_f32_16x16x32_bf16 v[42:45], v[168:171], v[176:179], v[42:45]
	v_mfma_f32_16x16x32_bf16 v[62:65], v[160:163], v[184:187], v[62:65]
	v_mfma_f32_16x16x32_bf16 v[34:37], v[168:171], v[184:187], v[34:37]
	v_mfma_f32_16x16x32_bf16 v[54:57], v[160:163], v[192:195], v[54:57]
	v_mfma_f32_16x16x32_bf16 v[26:29], v[168:171], v[192:195], v[26:29]
	v_mfma_f32_16x16x32_bf16 v[50:53], v[160:163], v[200:203], v[50:53]
	v_mfma_f32_16x16x32_bf16 v[18:21], v[168:171], v[200:203], v[18:21]
	v_mfma_f32_16x16x32_bf16 v[70:73], v[164:167], v[180:183], v[70:73]
	v_mfma_f32_16x16x32_bf16 v[42:45], v[172:175], v[180:183], v[42:45]
	v_mfma_f32_16x16x32_bf16 v[62:65], v[164:167], v[188:191], v[62:65]
	v_mfma_f32_16x16x32_bf16 v[34:37], v[172:175], v[188:191], v[34:37]
	v_mfma_f32_16x16x32_bf16 v[54:57], v[164:167], v[196:199], v[54:57]
	v_mfma_f32_16x16x32_bf16 v[26:29], v[172:175], v[196:199], v[26:29]
	v_mfma_f32_16x16x32_bf16 v[50:53], v[164:167], v[204:207], v[50:53]
	v_mfma_f32_16x16x32_bf16 v[18:21], v[172:175], v[204:207], v[18:21]
	s_barrier
	s_mov_b32 m0, s31
	v_lshl_add_u64 v[208:209], s[14:15], 0, v[132:133]
	s_add_u32 s42, s14, 0x160000
	ds_read_b128 v[176:179], v141 offset:16384
	ds_read_b128 v[180:183], v141 offset:17408
	ds_read_b128 v[184:187], v141 offset:18432
	ds_read_b128 v[188:191], v141 offset:19456
	ds_read_b128 v[192:195], v141 offset:20480
	ds_read_b128 v[196:199], v141 offset:21504
	ds_read_b128 v[200:203], v141 offset:22528
	ds_read_b128 v[204:207], v141 offset:23552
	global_load_lds_dwordx4 v[208:209], off
	v_lshl_add_u64 v[210:211], s[14:15], 0, v[130:131]
	s_mov_b32 m0, s33
	s_addc_u32 s43, s15, 0
	global_load_lds_dwordx4 v[210:211], off
	v_lshl_add_u64 v[212:213], s[42:43], 0, v[132:133]
	s_mov_b32 m0, s34
	v_lshl_add_u64 v[214:215], s[16:17], 0, v[130:131]
	global_load_lds_dwordx4 v[212:213], off
	v_lshl_add_u64 v[212:213], s[42:43], 0, v[130:131]
	s_mov_b32 m0, s35
	s_nop 0
	global_load_lds_dwordx4 v[212:213], off
	v_lshl_add_u64 v[212:213], s[16:17], 0, v[132:133]
	s_mov_b32 m0, s20
	s_nop 0
	global_load_lds_dwordx4 v[212:213], off
	s_mov_b32 m0, s22
	s_nop 0
	global_load_lds_dwordx4 v[214:215], off
	s_waitcnt vmcnt(8)
	s_waitcnt lgkmcnt(0)
	s_barrier
; #define PG8_STAGE(bufoff, gbase, voff) do { _Pragma("unroll") for (int _i = 0; _i < 2; ++_i) \
;         __builtin_amdgcn_global_load_lds((const unsigned*)((const char*)(gbase) + (voff)[_i]), (LAS unsigned*)(lds + (bufoff) + ldsw + _i * 8192), 16, 0, 0); } while (0)
; #define PG8_LDA(dst, b, h) do { _Pragma("unroll") for (int m = 0; m < 4; ++m) _Pragma("unroll") for (int k = 0; k < 2; ++k) dst[m][k] = *(const LAS bf16x8*)(lds + PG8_SA(b, h) + aoff + m * 2048 + k * 1024); } while (0)
; #define PG8_LDB(dst, b, h) do { _Pragma("unroll") for (int n = 0; n < 2; ++n) _Pragma("unroll") for (int k = 0; k < 2; ++k) dst[n][k] = *(const LAS bf16x8*)(lds + PG8_SB(b, h) + boff + n * 2048 + k * 1024); } while (0)
; #define PG8_MMA(ai, bj, At, Bt) do { __builtin_amdgcn_s_setprio(1); _Pragma("unroll") for (int m = 0; m < 4; ++m) _Pragma("unroll") for (int n = 0; n < 2; ++n) _Pragma("unroll") for (int k = 0; k < 2; ++k) \
;         acc[ai][bj][m][n] = __builtin_amdgcn_mfma_f32_16x16x32_bf16(Bt[n][k], At[m][k], acc[ai][bj][m][n], 0, 0, 0); __builtin_amdgcn_s_setprio(0); } while (0)
; #define PG8_WAIT_V(n) asm volatile("s_waitcnt vmcnt(" #n ")" ::: "memory")
; #define PG8_WAIT_L(n) asm volatile("s_waitcnt lgkmcnt(" #n ")" ::: "memory")
; #define PG8_BAR __builtin_amdgcn_s_barrier()
; #define PG8_SCHED __builtin_amdgcn_sched_barrier(0)
; template <class Epi, class Sched, bool ALIGN_EPI = false, bool SP2 = false>
; __device__ __forceinline__ void gemm_phase(LAS unsigned char* lds, const Gemm g, const Sched& S, const Epi& E) {
;     ...
;             PG8_LDA(At, 0, 1); PG8_STAGE(PG8_SB(0, 0), b2, voffB); PG8_STAGE(PG8_SB(0, 1), b2 + hstepB, voffB); PG8_STAGE(PG8_SA(0, 0), a2, voffA);
;             PG8_WAIT_V(8); PG8_WAIT_L(0); PG8_BAR; PG8_MMA(1, 0, At, B0); PG8_MMA(1, 1, At, B1); PG8_BAR; PG8_SCHED;
;             PG8_LDB(B0, 1, 0); PG8_LDB(B1, 1, 1); PG8_SCHED; PG8_LDA(At, 1, 0); PG8_STAGE(PG8_SA(0, 1), a2 + hstep, voffA);
;             PG8_WAIT_V(8); PG8_WAIT_L(0); PG8_BAR; PG8_MMA(0, 0, At, B0); PG8_MMA(0, 1, At, B1); PG8_BAR; PG8_SCHED;
	s_waitcnt lgkmcnt(0)
	v_mfma_f32_16x16x32_bf16 v[110:113], v[144:147], v[176:179], v[110:113]
	v_mfma_f32_16x16x32_bf16 v[78:81], v[152:155], v[176:179], v[78:81]
	v_mfma_f32_16x16x32_bf16 v[106:109], v[144:147], v[184:187], v[106:109]
	v_mfma_f32_16x16x32_bf16 v[74:77], v[152:155], v[184:187], v[74:77]
	v_mfma_f32_16x16x32_bf16 v[102:105], v[144:147], v[192:195], v[102:105]
	v_mfma_f32_16x16x32_bf16 v[66:69], v[152:155], v[192:195], v[66:69]
	v_mfma_f32_16x16x32_bf16 v[98:101], v[144:147], v[200:203], v[98:101]
	v_mfma_f32_16x16x32_bf16 v[58:61], v[152:155], v[200:203], v[58:61]
	v_mfma_f32_16x16x32_bf16 v[110:113], v[148:151], v[180:183], v[110:113]
	v_mfma_f32_16x16x32_bf16 v[78:81], v[156:159], v[180:183], v[78:81]
	v_mfma_f32_16x16x32_bf16 v[106:109], v[148:151], v[188:191], v[106:109]
	v_mfma_f32_16x16x32_bf16 v[74:77], v[156:159], v[188:191], v[74:77]
	v_mfma_f32_16x16x32_bf16 v[102:105], v[148:151], v[196:199], v[102:105]
	v_mfma_f32_16x16x32_bf16 v[66:69], v[156:159], v[196:199], v[66:69]
	v_mfma_f32_16x16x32_bf16 v[98:101], v[148:151], v[204:207], v[98:101]
	v_mfma_f32_16x16x32_bf16 v[58:61], v[156:159], v[204:207], v[58:61]
	v_mfma_f32_16x16x32_bf16 v[46:49], v[160:163], v[176:179], v[46:49]
	v_mfma_f32_16x16x32_bf16 v[14:17], v[168:171], v[176:179], v[14:17]
	v_mfma_f32_16x16x32_bf16 v[38:41], v[160:163], v[184:187], v[38:41]
	v_mfma_f32_16x16x32_bf16 v[10:13], v[168:171], v[184:187], v[10:13]
	v_mfma_f32_16x16x32_bf16 v[30:33], v[160:163], v[192:195], v[30:33]
	v_mfma_f32_16x16x32_bf16 v[6:9], v[168:171], v[192:195], v[6:9]
	v_mfma_f32_16x16x32_bf16 v[22:25], v[160:163], v[200:203], v[22:25]
	v_mfma_f32_16x16x32_bf16 v[2:5], v[168:171], v[200:203], v[2:5]
	v_mfma_f32_16x16x32_bf16 v[46:49], v[164:167], v[180:183], v[46:49]
	v_mfma_f32_16x16x32_bf16 v[14:17], v[172:175], v[180:183], v[14:17]
	v_mfma_f32_16x16x32_bf16 v[38:41], v[164:167], v[188:191], v[38:41]
	v_mfma_f32_16x16x32_bf16 v[10:13], v[172:175], v[188:191], v[10:13]
	v_mfma_f32_16x16x32_bf16 v[30:33], v[164:167], v[196:199], v[30:33]
	v_mfma_f32_16x16x32_bf16 v[6:9], v[172:175], v[196:199], v[6:9]
	v_mfma_f32_16x16x32_bf16 v[22:25], v[164:167], v[204:207], v[22:25]
	v_mfma_f32_16x16x32_bf16 v[2:5], v[172:175], v[204:207], v[2:5]
	s_barrier
	ds_read_b128 v[144:147], v142
	ds_read_b128 v[148:151], v142 offset:1024
	ds_read_b128 v[152:155], v142 offset:2048
	ds_read_b128 v[156:159], v142 offset:3072
	ds_read_b128 v[160:163], v143
	ds_read_b128 v[164:167], v143 offset:1024
	ds_read_b128 v[168:171], v143 offset:2048
	ds_read_b128 v[172:175], v143 offset:3072
	s_add_u32 s16, s16, 0x160000
	s_addc_u32 s17, s17, 0
	s_mov_b32 m0, s23
	v_lshl_add_u64 v[216:217], s[16:17], 0, v[132:133]
	ds_read_b128 v[176:179], v141 offset:32768
	ds_read_b128 v[180:183], v141 offset:33792
	ds_read_b128 v[184:187], v141 offset:34816
	ds_read_b128 v[188:191], v141 offset:35840
	ds_read_b128 v[192:195], v141 offset:36864
	ds_read_b128 v[196:199], v141 offset:37888
	ds_read_b128 v[200:203], v141 offset:38912
	ds_read_b128 v[204:207], v141 offset:39936
	global_load_lds_dwordx4 v[216:217], off
	v_lshl_add_u64 v[216:217], s[16:17], 0, v[130:131]
	s_mov_b32 m0, s24
	s_nop 0
	global_load_lds_dwordx4 v[216:217], off
	s_waitcnt vmcnt(8)
	s_waitcnt lgkmcnt(0)
	s_barrier
	s_waitcnt lgkmcnt(0)
	v_mfma_f32_16x16x32_bf16 v[126:129], v[144:147], v[176:179], v[126:129]
	v_mfma_f32_16x16x32_bf16 v[94:97], v[152:155], v[176:179], v[94:97]
	v_mfma_f32_16x16x32_bf16 v[122:125], v[144:147], v[184:187], v[122:125]
	v_mfma_f32_16x16x32_bf16 v[90:93], v[152:155], v[184:187], v[90:93]
	v_mfma_f32_16x16x32_bf16 v[118:121], v[144:147], v[192:195], v[118:121]
	v_mfma_f32_16x16x32_bf16 v[86:89], v[152:155], v[192:195], v[86:89]
	v_mfma_f32_16x16x32_bf16 v[114:117], v[144:147], v[200:203], v[114:117]
	v_mfma_f32_16x16x32_bf16 v[82:85], v[152:155], v[200:203], v[82:85]
	v_mfma_f32_16x16x32_bf16 v[126:129], v[148:151], v[180:183], v[126:129]
	v_mfma_f32_16x16x32_bf16 v[94:97], v[156:159], v[180:183], v[94:97]
	v_mfma_f32_16x16x32_bf16 v[122:125], v[148:151], v[188:191], v[122:125]
	v_mfma_f32_16x16x32_bf16 v[90:93], v[156:159], v[188:191], v[90:93]
	v_mfma_f32_16x16x32_bf16 v[118:121], v[148:151], v[196:199], v[118:121]
	v_mfma_f32_16x16x32_bf16 v[86:89], v[156:159], v[196:199], v[86:89]
	v_mfma_f32_16x16x32_bf16 v[114:117], v[148:151], v[204:207], v[114:117]
	v_mfma_f32_16x16x32_bf16 v[82:85], v[156:159], v[204:207], v[82:85]
	v_mfma_f32_16x16x32_bf16 v[70:73], v[160:163], v[176:179], v[70:73]
	v_mfma_f32_16x16x32_bf16 v[42:45], v[168:171], v[176:179], v[42:45]
	v_mfma_f32_16x16x32_bf16 v[62:65], v[160:163], v[184:187], v[62:65]
	v_mfma_f32_16x16x32_bf16 v[34:37], v[168:171], v[184:187], v[34:37]
	v_mfma_f32_16x16x32_bf16 v[54:57], v[160:163], v[192:195], v[54:57]
	v_mfma_f32_16x16x32_bf16 v[26:29], v[168:171], v[192:195], v[26:29]
	v_mfma_f32_16x16x32_bf16 v[50:53], v[160:163], v[200:203], v[50:53]
	v_mfma_f32_16x16x32_bf16 v[18:21], v[168:171], v[200:203], v[18:21]
	v_mfma_f32_16x16x32_bf16 v[70:73], v[164:167], v[180:183], v[70:73]
	v_mfma_f32_16x16x32_bf16 v[42:45], v[172:175], v[180:183], v[42:45]
	v_mfma_f32_16x16x32_bf16 v[62:65], v[164:167], v[188:191], v[62:65]
	v_mfma_f32_16x16x32_bf16 v[34:37], v[172:175], v[188:191], v[34:37]
	v_mfma_f32_16x16x32_bf16 v[54:57], v[164:167], v[196:199], v[54:57]
	v_mfma_f32_16x16x32_bf16 v[26:29], v[172:175], v[196:199], v[26:29]
	v_mfma_f32_16x16x32_bf16 v[50:53], v[164:167], v[204:207], v[50:53]
	v_mfma_f32_16x16x32_bf16 v[18:21], v[172:175], v[204:207], v[18:21]
	s_barrier
; #define PG8_STAGE(bufoff, gbase, voff) do { _Pragma("unroll") for (int _i = 0; _i < 2; ++_i) \
;         __builtin_amdgcn_global_load_lds((const unsigned*)((const char*)(gbase) + (voff)[_i]), (LAS unsigned*)(lds + (bufoff) + ldsw + _i * 8192), 16, 0, 0); } while (0)
; #define PG8_LDA(dst, b, h) do { _Pragma("unroll") for (int m = 0; m < 4; ++m) _Pragma("unroll") for (int k = 0; k < 2; ++k) dst[m][k] = *(const LAS bf16x8*)(lds + PG8_SA(b, h) + aoff + m * 2048 + k * 1024); } while (0)
; #define PG8_MMA(ai, bj, At, Bt) do { __builtin_amdgcn_s_setprio(1); _Pragma("unroll") for (int m = 0; m < 4; ++m) _Pragma("unroll") for (int n = 0; n < 2; ++n) _Pragma("unroll") for (int k = 0; k < 2; ++k) \
;         acc[ai][bj][m][n] = __builtin_amdgcn_mfma_f32_16x16x32_bf16(Bt[n][k], At[m][k], acc[ai][bj][m][n], 0, 0, 0); __builtin_amdgcn_s_setprio(0); } while (0)
; #define PG8_WAIT_V(n) asm volatile("s_waitcnt vmcnt(" #n ")" ::: "memory")
; #define PG8_WAIT_L(n) asm volatile("s_waitcnt lgkmcnt(" #n ")" ::: "memory")
; #define PG8_BAR __builtin_amdgcn_s_barrier()
; #define PG8_SCHED __builtin_amdgcn_sched_barrier(0)
; template <class Epi, class Sched, bool ALIGN_EPI = false, bool SP2 = false>
; __device__ __forceinline__ void gemm_phase(LAS unsigned char* lds, const Gemm g, const Sched& S, const Epi& E) {
;     ...
;         for (int t = 0; t < nt; t += 2) {
;     ...
;             PG8_LDA(At, 1, 1); PG8_STAGE(PG8_SB(1, 0), b3, voffB); PG8_STAGE(PG8_SB(1, 1), b3 + hstepB, voffB); PG8_STAGE(PG8_SA(1, 0), a3, voffA);
;             PG8_WAIT_V(8); PG8_WAIT_L(0); PG8_BAR; PG8_MMA(1, 0, At, B0); PG8_MMA(1, 1, At, B1); PG8_BAR; PG8_SCHED;
	s_mov_b32 m0, s36
	v_lshl_add_u64 v[208:209], v[208:209], 0, s[8:9]
	s_add_u32 s14, s14, 0x160080
	ds_read_b128 v[176:179], v141 offset:49152
	ds_read_b128 v[180:183], v141 offset:50176
	ds_read_b128 v[184:187], v141 offset:51200
	ds_read_b128 v[188:191], v141 offset:52224
	ds_read_b128 v[192:195], v141 offset:53248
	ds_read_b128 v[196:199], v141 offset:54272
	ds_read_b128 v[200:203], v141 offset:55296
	ds_read_b128 v[204:207], v141 offset:56320
	global_load_lds_dwordx4 v[208:209], off
	v_lshl_add_u64 v[208:209], v[210:211], 0, s[8:9]
	s_mov_b32 m0, s37
	s_addc_u32 s15, s15, 0
	global_load_lds_dwordx4 v[208:209], off
	v_lshl_add_u64 v[208:209], s[14:15], 0, v[132:133]
	s_mov_b32 m0, s38
	s_nop 0
	global_load_lds_dwordx4 v[208:209], off
	v_lshl_add_u64 v[208:209], s[14:15], 0, v[130:131]
	s_mov_b32 m0, s39
	s_nop 0
	global_load_lds_dwordx4 v[208:209], off
	v_lshl_add_u64 v[208:209], v[212:213], 0, s[8:9]
	s_mov_b32 m0, s26
	s_nop 0
	global_load_lds_dwordx4 v[208:209], off
	v_lshl_add_u64 v[208:209], v[214:215], 0, s[8:9]
	s_mov_b32 m0, s27
	s_nop 0
	global_load_lds_dwordx4 v[208:209], off
	s_waitcnt vmcnt(8)
	s_waitcnt lgkmcnt(0)
	s_barrier
	s_waitcnt lgkmcnt(0)
	v_mfma_f32_16x16x32_bf16 v[110:113], v[144:147], v[176:179], v[110:113]
	v_mfma_f32_16x16x32_bf16 v[78:81], v[152:155], v[176:179], v[78:81]
	v_mfma_f32_16x16x32_bf16 v[106:109], v[144:147], v[184:187], v[106:109]
	v_mfma_f32_16x16x32_bf16 v[74:77], v[152:155], v[184:187], v[74:77]
	v_mfma_f32_16x16x32_bf16 v[102:105], v[144:147], v[192:195], v[102:105]
	v_mfma_f32_16x16x32_bf16 v[66:69], v[152:155], v[192:195], v[66:69]
	v_mfma_f32_16x16x32_bf16 v[98:101], v[144:147], v[200:203], v[98:101]
	v_mfma_f32_16x16x32_bf16 v[58:61], v[152:155], v[200:203], v[58:61]
	v_mfma_f32_16x16x32_bf16 v[110:113], v[148:151], v[180:183], v[110:113]
	v_mfma_f32_16x16x32_bf16 v[78:81], v[156:159], v[180:183], v[78:81]
	v_mfma_f32_16x16x32_bf16 v[106:109], v[148:151], v[188:191], v[106:109]
	v_mfma_f32_16x16x32_bf16 v[74:77], v[156:159], v[188:191], v[74:77]
	v_mfma_f32_16x16x32_bf16 v[102:105], v[148:151], v[196:199], v[102:105]
	v_mfma_f32_16x16x32_bf16 v[66:69], v[156:159], v[196:199], v[66:69]
	v_mfma_f32_16x16x32_bf16 v[98:101], v[148:151], v[204:207], v[98:101]
	v_mfma_f32_16x16x32_bf16 v[58:61], v[156:159], v[204:207], v[58:61]
	v_mfma_f32_16x16x32_bf16 v[46:49], v[160:163], v[176:179], v[46:49]
	v_mfma_f32_16x16x32_bf16 v[14:17], v[168:171], v[176:179], v[14:17]
	v_mfma_f32_16x16x32_bf16 v[38:41], v[160:163], v[184:187], v[38:41]
	v_mfma_f32_16x16x32_bf16 v[10:13], v[168:171], v[184:187], v[10:13]
	v_mfma_f32_16x16x32_bf16 v[30:33], v[160:163], v[192:195], v[30:33]
	v_mfma_f32_16x16x32_bf16 v[6:9], v[168:171], v[192:195], v[6:9]
	v_mfma_f32_16x16x32_bf16 v[22:25], v[160:163], v[200:203], v[22:25]
	v_mfma_f32_16x16x32_bf16 v[2:5], v[168:171], v[200:203], v[2:5]
	v_mfma_f32_16x16x32_bf16 v[46:49], v[164:167], v[180:183], v[46:49]
	v_mfma_f32_16x16x32_bf16 v[14:17], v[172:175], v[180:183], v[14:17]
	v_mfma_f32_16x16x32_bf16 v[38:41], v[164:167], v[188:191], v[38:41]
	v_mfma_f32_16x16x32_bf16 v[10:13], v[172:175], v[188:191], v[10:13]
	v_mfma_f32_16x16x32_bf16 v[30:33], v[164:167], v[196:199], v[30:33]
	v_mfma_f32_16x16x32_bf16 v[6:9], v[172:175], v[196:199], v[6:9]
	v_mfma_f32_16x16x32_bf16 v[22:25], v[164:167], v[204:207], v[22:25]
	v_mfma_f32_16x16x32_bf16 v[2:5], v[172:175], v[204:207], v[2:5]
	s_barrier
	s_add_u32 s10, s10, 0x100
	s_addc_u32 s11, s11, 0
	s_cmp_lt_u32 s40, s25
	s_mov_b32 s14, s40
	s_cbranch_scc1 .LBB0_1896
	v_readlane_b32 s30, v252, 2
	v_readlane_b32 s34, v252, 37
	s_cmpk_gt_u32 s19, 0xff
	v_readlane_b32 s31, v252, 3
	v_readlane_b32 s35, v252, 38
	s_cbranch_scc1 .LBB0_1899
	s_barrier

;     __device__ bool next(int i, Unit& u) const { if (i != 0 || c >= 128) return false; const int t = c >> 2; u.pm = t & 3; u.pn = t >> 2; u.koff = koff_bytes; u.q = c & 3; return true; }
; #define PG8_STAGE(bufoff, gbase, voff) do { _Pragma("unroll") for (int _i = 0; _i < 2; ++_i) \
;         __builtin_amdgcn_global_load_lds((const unsigned*)((const char*)(gbase) + (voff)[_i]), (LAS unsigned*)(lds + (bufoff) + ldsw + _i * 8192), 16, 0, 0); } while (0)
; #define PG8_LDA(dst, b, h) do { _Pragma("unroll") for (int m = 0; m < 4; ++m) _Pragma("unroll") for (int k = 0; k < 2; ++k) dst[m][k] = *(const LAS bf16x8*)(lds + PG8_SA(b, h) + aoff + m * 2048 + k * 1024); } while (0)
; #define PG8_LDB(dst, b, h) do { _Pragma("unroll") for (int n = 0; n < 2; ++n) _Pragma("unroll") for (int k = 0; k < 2; ++k) dst[n][k] = *(const LAS bf16x8*)(lds + PG8_SB(b, h) + boff + n * 2048 + k * 1024); } while (0)
; #define PG8_WAIT_V(n) asm volatile("s_waitcnt vmcnt(" #n ")" ::: "memory")
; template <class Epi, class Sched, bool ALIGN_EPI = false, bool SP2 = false>
; __device__ __forceinline__ void gemm_phase(LAS unsigned char* lds, const Gemm g, const Sched& S, const Epi& E) {
;     ...
;         const bool has_next = S.next(ui + 1, nxt);
;         const char* nA = has_next ? (const char*)g.A + (size_t)nxt.pm * tstep + nxt.koff : cA; const char* nB = has_next ? (const char*)g.Bt + (size_t)nxt.pn * tstep + nxt.koff : cB;
;         for (int t = 0; t < nt; t += 2) {
;             const bool last = (t == nt - 2);
;             const char* a1 = cA + (size_t)(t + 1) * kstep;
;             const char* a2 = last ? nA : cA + (size_t)(t + 2) * kstep; const char* b2 = last ? nB : cB + (size_t)(t + 2) * kstep;
;             const char* a3 = a2 + kstep; const char* b3 = b2 + kstep;
;             if (last && has_next) S.a_ready(nxt);
;             if constexpr (SP2) {
;             PG8_LDB(B0, 0, 0); PG8_LDB(B1, 0, 1); PG8_SCHED; PG8_LDA(At, 0, 0); PG8_STAGE(PG8_SA(1, 1), a1 + hstep, voffA);
;             PG8_WAIT_V(8); PG8_WAIT_L(0); PG8_BAR; PG8_MMA(0, 0, At, B0); PG8_MMA(0, 1, At, B1); PG8_BAR; PG8_SCHED;
;             PG8_LDA(At, 0, 1); PG8_STAGE(PG8_SB(0, 0), b2, voffB); PG8_STAGE(PG8_SB(0, 1), b2 + hstepB, voffB); PG8_STAGE(PG8_SA(0, 0), a2, voffA);
;             PG8_WAIT_V(8); PG8_WAIT_L(0); PG8_BAR; PG8_MMA(1, 0, At, B0); PG8_MMA(1, 1, At, B1); PG8_BAR; PG8_SCHED;
.LBB0_1925:
	s_add_u32 s5, s20, 0x100
	s_addc_u32 s24, s21, 0
	s_mov_b32 s25, -2
	s_waitcnt vmcnt(0)
	ds_read_b128 v[130:133], v196
	ds_read_b128 v[134:137], v196 offset:1024
	ds_read_b128 v[138:141], v196 offset:2048
	ds_read_b128 v[142:145], v196 offset:3072
	ds_read_b128 v[166:169], v197
	ds_read_b128 v[170:173], v197 offset:1024
	ds_read_b128 v[174:177], v197 offset:2048
	ds_read_b128 v[178:181], v197 offset:3072
	s_add_u32 s20, s18, 0x100
	s_addc_u32 s21, s19, 0
	s_cmpk_eq_i32 s25, 0x54
	s_cselect_b32 s47, s17, s21
	s_cselect_b32 s46, s16, s20
	s_cselect_b32 s23, s3, s24
	s_cselect_b32 s22, s2, s5
	v_lshl_add_u64 v[190:191], s[18:19], 0, v[160:161]
	s_add_i32 m0, s27, 0xc000
	ds_read_b128 v[182:185], v198
	ds_read_b128 v[186:189], v198 offset:1024
	ds_read_b128 v[202:205], v198 offset:2048
	ds_read_b128 v[206:209], v198 offset:3072
	ds_read_b128 v[210:213], v198 offset:4096
	ds_read_b128 v[214:217], v198 offset:5120
	ds_read_b128 v[218:221], v198 offset:6144
	ds_read_b128 v[222:225], v198 offset:7168
	global_load_lds_dwordx4 v[190:191], off
	v_lshl_add_u64 v[190:191], s[18:19], 0, v[158:159]
	s_add_i32 m0, s27, 0xe000
	s_nop 0
	global_load_lds_dwordx4 v[190:191], off
	s_waitcnt lgkmcnt(0)
	s_barrier
	s_waitcnt lgkmcnt(0)
	v_mfma_f32_16x16x32_bf16 v[126:129], v[130:133], v[182:185], 0
	v_mfma_f32_16x16x32_bf16 v[122:125], v[138:141], v[182:185], 0
	v_mfma_f32_16x16x32_bf16 v[110:113], v[130:133], v[202:205], 0
	v_mfma_f32_16x16x32_bf16 v[106:109], v[138:141], v[202:205], 0
	v_mfma_f32_16x16x32_bf16 v[94:97], v[130:133], v[210:213], 0
	v_mfma_f32_16x16x32_bf16 v[90:93], v[138:141], v[210:213], 0
	v_mfma_f32_16x16x32_bf16 v[78:81], v[130:133], v[218:221], 0
	v_mfma_f32_16x16x32_bf16 v[74:77], v[138:141], v[218:221], 0
	v_mfma_f32_16x16x32_bf16 v[126:129], v[134:137], v[186:189], v[126:129]
	v_mfma_f32_16x16x32_bf16 v[122:125], v[142:145], v[186:189], v[122:125]
	v_mfma_f32_16x16x32_bf16 v[110:113], v[134:137], v[206:209], v[110:113]
	v_mfma_f32_16x16x32_bf16 v[106:109], v[142:145], v[206:209], v[106:109]
	v_mfma_f32_16x16x32_bf16 v[94:97], v[134:137], v[214:217], v[94:97]
	v_mfma_f32_16x16x32_bf16 v[90:93], v[142:145], v[214:217], v[90:93]
	v_mfma_f32_16x16x32_bf16 v[78:81], v[134:137], v[222:225], v[78:81]
	v_mfma_f32_16x16x32_bf16 v[74:77], v[142:145], v[222:225], v[74:77]
	v_mfma_f32_16x16x32_bf16 v[118:121], v[166:169], v[182:185], 0
	v_mfma_f32_16x16x32_bf16 v[114:117], v[174:177], v[182:185], 0
	v_mfma_f32_16x16x32_bf16 v[102:105], v[166:169], v[202:205], 0
	v_mfma_f32_16x16x32_bf16 v[98:101], v[174:177], v[202:205], 0
	v_mfma_f32_16x16x32_bf16 v[86:89], v[166:169], v[210:213], 0
	v_mfma_f32_16x16x32_bf16 v[82:85], v[174:177], v[210:213], 0
	v_mfma_f32_16x16x32_bf16 v[70:73], v[166:169], v[218:221], 0
	v_mfma_f32_16x16x32_bf16 v[66:69], v[174:177], v[218:221], 0
	v_mfma_f32_16x16x32_bf16 v[118:121], v[170:173], v[186:189], v[118:121]
	v_mfma_f32_16x16x32_bf16 v[114:117], v[178:181], v[186:189], v[114:117]
	v_mfma_f32_16x16x32_bf16 v[102:105], v[170:173], v[206:209], v[102:105]
	v_mfma_f32_16x16x32_bf16 v[98:101], v[178:181], v[206:209], v[98:101]
	v_mfma_f32_16x16x32_bf16 v[86:89], v[170:173], v[214:217], v[86:89]
	v_mfma_f32_16x16x32_bf16 v[82:85], v[178:181], v[214:217], v[82:85]
	v_mfma_f32_16x16x32_bf16 v[70:73], v[170:173], v[222:225], v[70:73]
	v_mfma_f32_16x16x32_bf16 v[66:69], v[178:181], v[222:225], v[66:69]
	s_barrier
	s_add_i32 s18, s50, s26
	v_lshl_add_u64 v[190:191], s[22:23], 0, v[148:149]
	s_mov_b32 m0, s18
	ds_read_b128 v[182:185], v198 offset:16384
	ds_read_b128 v[186:189], v198 offset:17408
	ds_read_b128 v[202:205], v198 offset:18432
	ds_read_b128 v[206:209], v198 offset:19456
	ds_read_b128 v[210:213], v198 offset:20480
	ds_read_b128 v[214:217], v198 offset:21504
	ds_read_b128 v[218:221], v198 offset:22528
	ds_read_b128 v[222:225], v198 offset:23552
	global_load_lds_dwordx4 v[190:191], off
	s_add_i32 m0, s18, 0x2000
	s_add_u32 s18, s22, 0x58000
	v_lshl_add_u64 v[226:227], s[22:23], 0, v[152:153]
	s_addc_u32 s19, s23, 0
	s_add_i32 s54, s51, s26
	global_load_lds_dwordx4 v[226:227], off
	v_lshl_add_u64 v[228:229], s[18:19], 0, v[148:149]
	s_mov_b32 m0, s54
	v_lshl_add_u64 v[230:231], s[46:47], 0, v[150:151]
	global_load_lds_dwordx4 v[228:229], off
	v_lshl_add_u64 v[228:229], s[18:19], 0, v[152:153]
	s_add_i32 m0, s54, 0x2000
	s_nop 0
	global_load_lds_dwordx4 v[228:229], off
	v_lshl_add_u64 v[228:229], s[46:47], 0, v[146:147]
	s_mov_b32 m0, s27
	s_nop 0
	global_load_lds_dwordx4 v[228:229], off
	s_mov_b32 m0, s28
	s_nop 0
	global_load_lds_dwordx4 v[230:231], off
	s_waitcnt lgkmcnt(0)
	s_barrier
; #define PG8_STAGE(bufoff, gbase, voff) do { _Pragma("unroll") for (int _i = 0; _i < 2; ++_i) \
;         __builtin_amdgcn_global_load_lds((const unsigned*)((const char*)(gbase) + (voff)[_i]), (LAS unsigned*)(lds + (bufoff) + ldsw + _i * 8192), 16, 0, 0); } while (0)
; #define PG8_LDA(dst, b, h) do { _Pragma("unroll") for (int m = 0; m < 4; ++m) _Pragma("unroll") for (int k = 0; k < 2; ++k) dst[m][k] = *(const LAS bf16x8*)(lds + PG8_SA(b, h) + aoff + m * 2048 + k * 1024); } while (0)
; #define PG8_LDB(dst, b, h) do { _Pragma("unroll") for (int n = 0; n < 2; ++n) _Pragma("unroll") for (int k = 0; k < 2; ++k) dst[n][k] = *(const LAS bf16x8*)(lds + PG8_SB(b, h) + boff + n * 2048 + k * 1024); } while (0)
; #define PG8_MMA(ai, bj, At, Bt) do { __builtin_amdgcn_s_setprio(1); _Pragma("unroll") for (int m = 0; m < 4; ++m) _Pragma("unroll") for (int n = 0; n < 2; ++n) _Pragma("unroll") for (int k = 0; k < 2; ++k) \
;         acc[ai][bj][m][n] = __builtin_amdgcn_mfma_f32_16x16x32_bf16(Bt[n][k], At[m][k], acc[ai][bj][m][n], 0, 0, 0); __builtin_amdgcn_s_setprio(0); } while (0)
; #define PG8_WAIT_V(n) asm volatile("s_waitcnt vmcnt(" #n ")" ::: "memory")
; #define PG8_WAIT_L(n) asm volatile("s_waitcnt lgkmcnt(" #n ")" ::: "memory")
; #define PG8_BAR __builtin_amdgcn_s_barrier()
; #define PG8_SCHED __builtin_amdgcn_sched_barrier(0)
; template <class Epi, class Sched, bool ALIGN_EPI = false, bool SP2 = false>
; __device__ __forceinline__ void gemm_phase(LAS unsigned char* lds, const Gemm g, const Sched& S, const Epi& E) {
;     ...
;             PG8_LDB(B0, 0, 0); PG8_LDB(B1, 0, 1); PG8_SCHED; PG8_LDA(At, 0, 0); PG8_STAGE(PG8_SA(1, 1), a1 + hstep, voffA);
;             PG8_WAIT_V(8); PG8_WAIT_L(0); PG8_BAR; PG8_MMA(0, 0, At, B0); PG8_MMA(0, 1, At, B1); PG8_BAR; PG8_SCHED;
;             PG8_LDA(At, 0, 1); PG8_STAGE(PG8_SB(0, 0), b2, voffB); PG8_STAGE(PG8_SB(0, 1), b2 + hstepB, voffB); PG8_STAGE(PG8_SA(0, 0), a2, voffA);
;             PG8_WAIT_V(8); PG8_WAIT_L(0); PG8_BAR; PG8_MMA(1, 0, At, B0); PG8_MMA(1, 1, At, B1); PG8_BAR; PG8_SCHED;
;             PG8_LDB(B0, 1, 0); PG8_LDB(B1, 1, 1); PG8_SCHED; PG8_LDA(At, 1, 0); PG8_STAGE(PG8_SA(0, 1), a2 + hstep, voffA);
;             PG8_WAIT_V(8); PG8_WAIT_L(0); PG8_BAR; PG8_MMA(0, 0, At, B0); PG8_MMA(0, 1, At, B1); PG8_BAR; PG8_SCHED;
	s_waitcnt lgkmcnt(0)
	v_mfma_f32_16x16x32_bf16 v[62:65], v[130:133], v[182:185], 0
	v_mfma_f32_16x16x32_bf16 v[58:61], v[138:141], v[182:185], 0
	v_mfma_f32_16x16x32_bf16 v[46:49], v[130:133], v[202:205], 0
	v_mfma_f32_16x16x32_bf16 v[42:45], v[138:141], v[202:205], 0
	v_mfma_f32_16x16x32_bf16 v[30:33], v[130:133], v[210:213], 0
	v_mfma_f32_16x16x32_bf16 v[26:29], v[138:141], v[210:213], 0
	v_mfma_f32_16x16x32_bf16 v[14:17], v[130:133], v[218:221], 0
	v_mfma_f32_16x16x32_bf16 v[10:13], v[138:141], v[218:221], 0
	v_mfma_f32_16x16x32_bf16 v[62:65], v[134:137], v[186:189], v[62:65]
	v_mfma_f32_16x16x32_bf16 v[58:61], v[142:145], v[186:189], v[58:61]
	v_mfma_f32_16x16x32_bf16 v[46:49], v[134:137], v[206:209], v[46:49]
	v_mfma_f32_16x16x32_bf16 v[42:45], v[142:145], v[206:209], v[42:45]
	v_mfma_f32_16x16x32_bf16 v[30:33], v[134:137], v[214:217], v[30:33]
	v_mfma_f32_16x16x32_bf16 v[26:29], v[142:145], v[214:217], v[26:29]
	v_mfma_f32_16x16x32_bf16 v[14:17], v[134:137], v[222:225], v[14:17]
	v_mfma_f32_16x16x32_bf16 v[10:13], v[142:145], v[222:225], v[10:13]
	v_mfma_f32_16x16x32_bf16 v[54:57], v[166:169], v[182:185], 0
	v_mfma_f32_16x16x32_bf16 v[50:53], v[174:177], v[182:185], 0
	v_mfma_f32_16x16x32_bf16 v[38:41], v[166:169], v[202:205], 0
	v_mfma_f32_16x16x32_bf16 v[34:37], v[174:177], v[202:205], 0
	v_mfma_f32_16x16x32_bf16 v[22:25], v[166:169], v[210:213], 0
	v_mfma_f32_16x16x32_bf16 v[18:21], v[174:177], v[210:213], 0
	v_mfma_f32_16x16x32_bf16 v[6:9], v[166:169], v[218:221], 0
	v_mfma_f32_16x16x32_bf16 v[2:5], v[174:177], v[218:221], 0
	v_mfma_f32_16x16x32_bf16 v[54:57], v[170:173], v[186:189], v[54:57]
	v_mfma_f32_16x16x32_bf16 v[50:53], v[178:181], v[186:189], v[50:53]
	v_mfma_f32_16x16x32_bf16 v[38:41], v[170:173], v[206:209], v[38:41]
	v_mfma_f32_16x16x32_bf16 v[34:37], v[178:181], v[206:209], v[34:37]
	v_mfma_f32_16x16x32_bf16 v[22:25], v[170:173], v[214:217], v[22:25]
	v_mfma_f32_16x16x32_bf16 v[18:21], v[178:181], v[214:217], v[18:21]
	v_mfma_f32_16x16x32_bf16 v[6:9], v[170:173], v[222:225], v[6:9]
	v_mfma_f32_16x16x32_bf16 v[2:5], v[178:181], v[222:225], v[2:5]
	s_barrier
	s_add_i32 s54, 0, 0x18000
	s_add_i32 s55, 0, 0x1c000
	v_add_u32_e32 v142, s54, v1
	v_add_u32_e32 v154, s55, v1
	ds_read_b128 v[130:133], v142
	ds_read_b128 v[134:137], v142 offset:1024
	ds_read_b128 v[138:141], v142 offset:2048
	ds_read_b128 v[142:145], v142 offset:3072
	ds_read_b128 v[166:169], v154
	ds_read_b128 v[170:173], v154 offset:1024
	ds_read_b128 v[174:177], v154 offset:2048
	ds_read_b128 v[178:181], v154 offset:3072
	s_add_u32 s18, s46, 0x160000
	s_addc_u32 s19, s47, 0
	s_mov_b32 m0, s29
	v_lshl_add_u64 v[232:233], s[18:19], 0, v[146:147]
	ds_read_b128 v[182:185], v198 offset:32768
	ds_read_b128 v[186:189], v198 offset:33792
	ds_read_b128 v[202:205], v198 offset:34816
	ds_read_b128 v[206:209], v198 offset:35840
	ds_read_b128 v[210:213], v198 offset:36864
	ds_read_b128 v[214:217], v198 offset:37888
	ds_read_b128 v[218:221], v198 offset:38912
	ds_read_b128 v[222:225], v198 offset:39936
	global_load_lds_dwordx4 v[232:233], off
	v_lshl_add_u64 v[232:233], s[18:19], 0, v[150:151]
	s_mov_b32 m0, s30
	s_nop 0
	global_load_lds_dwordx4 v[232:233], off
	s_waitcnt vmcnt(8)
	s_waitcnt lgkmcnt(0)
	s_barrier
	s_waitcnt lgkmcnt(0)
	v_mfma_f32_16x16x32_bf16 v[126:129], v[130:133], v[182:185], v[126:129]
	v_mfma_f32_16x16x32_bf16 v[122:125], v[138:141], v[182:185], v[122:125]
	v_mfma_f32_16x16x32_bf16 v[110:113], v[130:133], v[202:205], v[110:113]
	v_mfma_f32_16x16x32_bf16 v[106:109], v[138:141], v[202:205], v[106:109]
	v_mfma_f32_16x16x32_bf16 v[94:97], v[130:133], v[210:213], v[94:97]
	v_mfma_f32_16x16x32_bf16 v[90:93], v[138:141], v[210:213], v[90:93]
	v_mfma_f32_16x16x32_bf16 v[78:81], v[130:133], v[218:221], v[78:81]
	v_mfma_f32_16x16x32_bf16 v[74:77], v[138:141], v[218:221], v[74:77]
	v_mfma_f32_16x16x32_bf16 v[126:129], v[134:137], v[186:189], v[126:129]
	v_mfma_f32_16x16x32_bf16 v[122:125], v[142:145], v[186:189], v[122:125]
	v_mfma_f32_16x16x32_bf16 v[110:113], v[134:137], v[206:209], v[110:113]
	v_mfma_f32_16x16x32_bf16 v[106:109], v[142:145], v[206:209], v[106:109]
	v_mfma_f32_16x16x32_bf16 v[94:97], v[134:137], v[214:217], v[94:97]
	v_mfma_f32_16x16x32_bf16 v[90:93], v[142:145], v[214:217], v[90:93]
	v_mfma_f32_16x16x32_bf16 v[78:81], v[134:137], v[222:225], v[78:81]
	v_mfma_f32_16x16x32_bf16 v[74:77], v[142:145], v[222:225], v[74:77]
	v_mfma_f32_16x16x32_bf16 v[118:121], v[166:169], v[182:185], v[118:121]
	v_mfma_f32_16x16x32_bf16 v[114:117], v[174:177], v[182:185], v[114:117]
	v_mfma_f32_16x16x32_bf16 v[102:105], v[166:169], v[202:205], v[102:105]
	v_mfma_f32_16x16x32_bf16 v[98:101], v[174:177], v[202:205], v[98:101]
	v_mfma_f32_16x16x32_bf16 v[86:89], v[166:169], v[210:213], v[86:89]
	v_mfma_f32_16x16x32_bf16 v[82:85], v[174:177], v[210:213], v[82:85]
	v_mfma_f32_16x16x32_bf16 v[70:73], v[166:169], v[218:221], v[70:73]
	v_mfma_f32_16x16x32_bf16 v[66:69], v[174:177], v[218:221], v[66:69]
	v_mfma_f32_16x16x32_bf16 v[118:121], v[170:173], v[186:189], v[118:121]
	v_mfma_f32_16x16x32_bf16 v[114:117], v[178:181], v[186:189], v[114:117]
	v_mfma_f32_16x16x32_bf16 v[102:105], v[170:173], v[206:209], v[102:105]
	v_mfma_f32_16x16x32_bf16 v[98:101], v[178:181], v[206:209], v[98:101]
	v_mfma_f32_16x16x32_bf16 v[86:89], v[170:173], v[214:217], v[86:89]
	v_mfma_f32_16x16x32_bf16 v[82:85], v[178:181], v[214:217], v[82:85]
	v_mfma_f32_16x16x32_bf16 v[70:73], v[170:173], v[222:225], v[70:73]
	v_mfma_f32_16x16x32_bf16 v[66:69], v[178:181], v[222:225], v[66:69]
	s_barrier
; #define PG8_STAGE(bufoff, gbase, voff) do { _Pragma("unroll") for (int _i = 0; _i < 2; ++_i) \
;         __builtin_amdgcn_global_load_lds((const unsigned*)((const char*)(gbase) + (voff)[_i]), (LAS unsigned*)(lds + (bufoff) + ldsw + _i * 8192), 16, 0, 0); } while (0)
; #define PG8_LDA(dst, b, h) do { _Pragma("unroll") for (int m = 0; m < 4; ++m) _Pragma("unroll") for (int k = 0; k < 2; ++k) dst[m][k] = *(const LAS bf16x8*)(lds + PG8_SA(b, h) + aoff + m * 2048 + k * 1024); } while (0)
; #define PG8_LDB(dst, b, h) do { _Pragma("unroll") for (int n = 0; n < 2; ++n) _Pragma("unroll") for (int k = 0; k < 2; ++k) dst[n][k] = *(const LAS bf16x8*)(lds + PG8_SB(b, h) + boff + n * 2048 + k * 1024); } while (0)
; #define PG8_MMA(ai, bj, At, Bt) do { __builtin_amdgcn_s_setprio(1); _Pragma("unroll") for (int m = 0; m < 4; ++m) _Pragma("unroll") for (int n = 0; n < 2; ++n) _Pragma("unroll") for (int k = 0; k < 2; ++k) \
;         acc[ai][bj][m][n] = __builtin_amdgcn_mfma_f32_16x16x32_bf16(Bt[n][k], At[m][k], acc[ai][bj][m][n], 0, 0, 0); __builtin_amdgcn_s_setprio(0); } while (0)
; #define PG8_WAIT_V(n) asm volatile("s_waitcnt vmcnt(" #n ")" ::: "memory")
; #define PG8_WAIT_L(n) asm volatile("s_waitcnt lgkmcnt(" #n ")" ::: "memory")
; #define PG8_BAR __builtin_amdgcn_s_barrier()
; #define PG8_SCHED __builtin_amdgcn_sched_barrier(0)
; template <class Epi, class Sched, bool ALIGN_EPI = false, bool SP2 = false>
; __device__ __forceinline__ void gemm_phase(LAS unsigned char* lds, const Gemm g, const Sched& S, const Epi& E) {
;     ...
;             PG8_LDB(B0, 0, 0); PG8_LDB(B1, 0, 1); PG8_SCHED; PG8_LDA(At, 0, 0); PG8_STAGE(PG8_SA(1, 1), a1 + hstep, voffA);
;             PG8_WAIT_V(8); PG8_WAIT_L(0); PG8_BAR; PG8_MMA(0, 0, At, B0); PG8_MMA(0, 1, At, B1); PG8_BAR; PG8_SCHED;
;     ...
;             PG8_LDA(At, 1, 1); PG8_STAGE(PG8_SB(1, 0), b3, voffB); PG8_STAGE(PG8_SB(1, 1), b3 + hstepB, voffB); PG8_STAGE(PG8_SA(1, 0), a3, voffA);
;             PG8_WAIT_V(8); PG8_WAIT_L(0); PG8_BAR; PG8_MMA(1, 0, At, B0); PG8_MMA(1, 1, At, B1); PG8_BAR; PG8_SCHED;
	s_add_i32 s18, s54, s26
	v_lshl_add_u64 v[190:191], v[190:191], 0, s[12:13]
	s_mov_b32 m0, s18
	ds_read_b128 v[182:185], v198 offset:49152
	ds_read_b128 v[186:189], v198 offset:50176
	ds_read_b128 v[202:205], v198 offset:51200
	ds_read_b128 v[206:209], v198 offset:52224
	ds_read_b128 v[210:213], v198 offset:53248
	ds_read_b128 v[214:217], v198 offset:54272
	ds_read_b128 v[218:221], v198 offset:55296
	ds_read_b128 v[222:225], v198 offset:56320
	global_load_lds_dwordx4 v[190:191], off
	s_add_i32 m0, s18, 0x2000
	s_add_u32 s18, s22, 0x58080
	v_lshl_add_u64 v[190:191], v[226:227], 0, s[12:13]
	s_addc_u32 s19, s23, 0
	s_add_i32 s22, s55, s26
	global_load_lds_dwordx4 v[190:191], off
	v_lshl_add_u64 v[190:191], s[18:19], 0, v[148:149]
	s_mov_b32 m0, s22
	s_nop 0
	global_load_lds_dwordx4 v[190:191], off
	v_lshl_add_u64 v[190:191], s[18:19], 0, v[152:153]
	s_add_i32 m0, s22, 0x2000
	s_nop 0
	global_load_lds_dwordx4 v[190:191], off
	v_lshl_add_u64 v[190:191], v[228:229], 0, s[12:13]
	s_mov_b32 m0, s37
	s_nop 0
	global_load_lds_dwordx4 v[190:191], off
	v_lshl_add_u64 v[190:191], v[230:231], 0, s[12:13]
	s_mov_b32 m0, s48
	s_nop 0
	global_load_lds_dwordx4 v[190:191], off
	s_waitcnt vmcnt(8)
	s_waitcnt lgkmcnt(0)
	s_barrier
	s_waitcnt lgkmcnt(0)
	v_mfma_f32_16x16x32_bf16 v[62:65], v[130:133], v[182:185], v[62:65]
	v_mfma_f32_16x16x32_bf16 v[58:61], v[138:141], v[182:185], v[58:61]
	v_mfma_f32_16x16x32_bf16 v[46:49], v[130:133], v[202:205], v[46:49]
	v_mfma_f32_16x16x32_bf16 v[42:45], v[138:141], v[202:205], v[42:45]
	v_mfma_f32_16x16x32_bf16 v[30:33], v[130:133], v[210:213], v[30:33]
	v_mfma_f32_16x16x32_bf16 v[26:29], v[138:141], v[210:213], v[26:29]
	v_mfma_f32_16x16x32_bf16 v[14:17], v[130:133], v[218:221], v[14:17]
	v_mfma_f32_16x16x32_bf16 v[10:13], v[138:141], v[218:221], v[10:13]
	v_mfma_f32_16x16x32_bf16 v[62:65], v[134:137], v[186:189], v[62:65]
	v_mfma_f32_16x16x32_bf16 v[58:61], v[142:145], v[186:189], v[58:61]
	v_mfma_f32_16x16x32_bf16 v[46:49], v[134:137], v[206:209], v[46:49]
	v_mfma_f32_16x16x32_bf16 v[42:45], v[142:145], v[206:209], v[42:45]
	v_mfma_f32_16x16x32_bf16 v[30:33], v[134:137], v[214:217], v[30:33]
	v_mfma_f32_16x16x32_bf16 v[26:29], v[142:145], v[214:217], v[26:29]
	v_mfma_f32_16x16x32_bf16 v[14:17], v[134:137], v[222:225], v[14:17]
	v_mfma_f32_16x16x32_bf16 v[10:13], v[142:145], v[222:225], v[10:13]
	v_mfma_f32_16x16x32_bf16 v[54:57], v[166:169], v[182:185], v[54:57]
	v_mfma_f32_16x16x32_bf16 v[50:53], v[174:177], v[182:185], v[50:53]
	v_mfma_f32_16x16x32_bf16 v[38:41], v[166:169], v[202:205], v[38:41]
	v_mfma_f32_16x16x32_bf16 v[34:37], v[174:177], v[202:205], v[34:37]
	v_mfma_f32_16x16x32_bf16 v[22:25], v[166:169], v[210:213], v[22:25]
	v_mfma_f32_16x16x32_bf16 v[18:21], v[174:177], v[210:213], v[18:21]
	v_mfma_f32_16x16x32_bf16 v[6:9], v[166:169], v[218:221], v[6:9]
	v_mfma_f32_16x16x32_bf16 v[2:5], v[174:177], v[218:221], v[2:5]
	v_mfma_f32_16x16x32_bf16 v[54:57], v[170:173], v[186:189], v[54:57]
	v_mfma_f32_16x16x32_bf16 v[50:53], v[178:181], v[186:189], v[50:53]
	v_mfma_f32_16x16x32_bf16 v[38:41], v[170:173], v[206:209], v[38:41]
	v_mfma_f32_16x16x32_bf16 v[34:37], v[178:181], v[206:209], v[34:37]
	v_mfma_f32_16x16x32_bf16 v[22:25], v[170:173], v[214:217], v[22:25]
	v_mfma_f32_16x16x32_bf16 v[18:21], v[178:181], v[214:217], v[18:21]
	v_mfma_f32_16x16x32_bf16 v[6:9], v[170:173], v[222:225], v[6:9]
	v_mfma_f32_16x16x32_bf16 v[2:5], v[178:181], v[222:225], v[2:5]
	s_barrier
	s_add_i32 s25, s25, 2
	s_add_u32 s5, s5, 0x100
	s_addc_u32 s24, s24, 0
	s_cmpk_lt_u32 s25, 0x56
	s_mov_b64 s[18:19], s[20:21]
.LBB0_1926:
	ds_read_b128 v[130:133], v196
	ds_read_b128 v[134:137], v196 offset:1024
	ds_read_b128 v[138:141], v196 offset:2048
	ds_read_b128 v[142:145], v196 offset:3072
	ds_read_b128 v[166:169], v197
	ds_read_b128 v[170:173], v197 offset:1024
	ds_read_b128 v[174:177], v197 offset:2048
	ds_read_b128 v[178:181], v197 offset:3072
	s_add_u32 s20, s18, 0x100
	s_addc_u32 s21, s19, 0
	s_cmpk_eq_i32 s25, 0x54
	s_cselect_b32 s47, s17, s21
	s_cselect_b32 s46, s16, s20
	s_cselect_b32 s23, s3, s24
	s_cselect_b32 s22, s2, s5
	v_lshl_add_u64 v[190:191], s[18:19], 0, v[160:161]
	s_add_i32 m0, s27, 0xc000
	ds_read_b128 v[182:185], v198
	ds_read_b128 v[186:189], v198 offset:1024
	ds_read_b128 v[202:205], v198 offset:2048
	ds_read_b128 v[206:209], v198 offset:3072
	ds_read_b128 v[210:213], v198 offset:4096
	ds_read_b128 v[214:217], v198 offset:5120
	ds_read_b128 v[218:221], v198 offset:6144
	ds_read_b128 v[222:225], v198 offset:7168
	global_load_lds_dwordx4 v[190:191], off
	v_lshl_add_u64 v[190:191], s[18:19], 0, v[158:159]
	s_add_i32 m0, s27, 0xe000
	s_nop 0
	global_load_lds_dwordx4 v[190:191], off
	s_waitcnt vmcnt(8)
	s_waitcnt lgkmcnt(0)
	s_barrier
; #define PG8_STAGE(bufoff, gbase, voff) do { _Pragma("unroll") for (int _i = 0; _i < 2; ++_i) \
;         __builtin_amdgcn_global_load_lds((const unsigned*)((const char*)(gbase) + (voff)[_i]), (LAS unsigned*)(lds + (bufoff) + ldsw + _i * 8192), 16, 0, 0); } while (0)
; #define PG8_LDA(dst, b, h) do { _Pragma("unroll") for (int m = 0; m < 4; ++m) _Pragma("unroll") for (int k = 0; k < 2; ++k) dst[m][k] = *(const LAS bf16x8*)(lds + PG8_SA(b, h) + aoff + m * 2048 + k * 1024); } while (0)
; #define PG8_LDB(dst, b, h) do { _Pragma("unroll") for (int n = 0; n < 2; ++n) _Pragma("unroll") for (int k = 0; k < 2; ++k) dst[n][k] = *(const LAS bf16x8*)(lds + PG8_SB(b, h) + boff + n * 2048 + k * 1024); } while (0)
; #define PG8_MMA(ai, bj, At, Bt) do { __builtin_amdgcn_s_setprio(1); _Pragma("unroll") for (int m = 0; m < 4; ++m) _Pragma("unroll") for (int n = 0; n < 2; ++n) _Pragma("unroll") for (int k = 0; k < 2; ++k) \
;         acc[ai][bj][m][n] = __builtin_amdgcn_mfma_f32_16x16x32_bf16(Bt[n][k], At[m][k], acc[ai][bj][m][n], 0, 0, 0); __builtin_amdgcn_s_setprio(0); } while (0)
; #define PG8_WAIT_V(n) asm volatile("s_waitcnt vmcnt(" #n ")" ::: "memory")
; #define PG8_WAIT_L(n) asm volatile("s_waitcnt lgkmcnt(" #n ")" ::: "memory")
; #define PG8_BAR __builtin_amdgcn_s_barrier()
; #define PG8_SCHED __builtin_amdgcn_sched_barrier(0)
; template <class Epi, class Sched, bool ALIGN_EPI = false, bool SP2 = false>
; __device__ __forceinline__ void gemm_phase(LAS unsigned char* lds, const Gemm g, const Sched& S, const Epi& E) {
;     ...
;             PG8_LDB(B0, 0, 0); PG8_LDB(B1, 0, 1); PG8_SCHED; PG8_LDA(At, 0, 0); PG8_STAGE(PG8_SA(1, 1), a1 + hstep, voffA);
;             PG8_WAIT_V(8); PG8_WAIT_L(0); PG8_BAR; PG8_MMA(0, 0, At, B0); PG8_MMA(0, 1, At, B1); PG8_BAR; PG8_SCHED;
;             PG8_LDA(At, 0, 1); PG8_STAGE(PG8_SB(0, 0), b2, voffB); PG8_STAGE(PG8_SB(0, 1), b2 + hstepB, voffB); PG8_STAGE(PG8_SA(0, 0), a2, voffA);
;             PG8_WAIT_V(8); PG8_WAIT_L(0); PG8_BAR; PG8_MMA(1, 0, At, B0); PG8_MMA(1, 1, At, B1); PG8_BAR; PG8_SCHED;
;             PG8_LDB(B0, 1, 0); PG8_LDB(B1, 1, 1); PG8_SCHED; PG8_LDA(At, 1, 0); PG8_STAGE(PG8_SA(0, 1), a2 + hstep, voffA);
;             PG8_WAIT_V(8); PG8_WAIT_L(0); PG8_BAR; PG8_MMA(0, 0, At, B0); PG8_MMA(0, 1, At, B1); PG8_BAR; PG8_SCHED;
	s_waitcnt lgkmcnt(0)
	v_mfma_f32_16x16x32_bf16 v[126:129], v[130:133], v[182:185], v[126:129]
	v_mfma_f32_16x16x32_bf16 v[122:125], v[138:141], v[182:185], v[122:125]
	v_mfma_f32_16x16x32_bf16 v[110:113], v[130:133], v[202:205], v[110:113]
	v_mfma_f32_16x16x32_bf16 v[106:109], v[138:141], v[202:205], v[106:109]
	v_mfma_f32_16x16x32_bf16 v[94:97], v[130:133], v[210:213], v[94:97]
	v_mfma_f32_16x16x32_bf16 v[90:93], v[138:141], v[210:213], v[90:93]
	v_mfma_f32_16x16x32_bf16 v[78:81], v[130:133], v[218:221], v[78:81]
	v_mfma_f32_16x16x32_bf16 v[74:77], v[138:141], v[218:221], v[74:77]
	v_mfma_f32_16x16x32_bf16 v[126:129], v[134:137], v[186:189], v[126:129]
	v_mfma_f32_16x16x32_bf16 v[122:125], v[142:145], v[186:189], v[122:125]
	v_mfma_f32_16x16x32_bf16 v[110:113], v[134:137], v[206:209], v[110:113]
	v_mfma_f32_16x16x32_bf16 v[106:109], v[142:145], v[206:209], v[106:109]
	v_mfma_f32_16x16x32_bf16 v[94:97], v[134:137], v[214:217], v[94:97]
	v_mfma_f32_16x16x32_bf16 v[90:93], v[142:145], v[214:217], v[90:93]
	v_mfma_f32_16x16x32_bf16 v[78:81], v[134:137], v[222:225], v[78:81]
	v_mfma_f32_16x16x32_bf16 v[74:77], v[142:145], v[222:225], v[74:77]
	v_mfma_f32_16x16x32_bf16 v[118:121], v[166:169], v[182:185], v[118:121]
	v_mfma_f32_16x16x32_bf16 v[114:117], v[174:177], v[182:185], v[114:117]
	v_mfma_f32_16x16x32_bf16 v[102:105], v[166:169], v[202:205], v[102:105]
	v_mfma_f32_16x16x32_bf16 v[98:101], v[174:177], v[202:205], v[98:101]
	v_mfma_f32_16x16x32_bf16 v[86:89], v[166:169], v[210:213], v[86:89]
	v_mfma_f32_16x16x32_bf16 v[82:85], v[174:177], v[210:213], v[82:85]
	v_mfma_f32_16x16x32_bf16 v[70:73], v[166:169], v[218:221], v[70:73]
	v_mfma_f32_16x16x32_bf16 v[66:69], v[174:177], v[218:221], v[66:69]
	v_mfma_f32_16x16x32_bf16 v[118:121], v[170:173], v[186:189], v[118:121]
	v_mfma_f32_16x16x32_bf16 v[114:117], v[178:181], v[186:189], v[114:117]
	v_mfma_f32_16x16x32_bf16 v[102:105], v[170:173], v[206:209], v[102:105]
	v_mfma_f32_16x16x32_bf16 v[98:101], v[178:181], v[206:209], v[98:101]
	v_mfma_f32_16x16x32_bf16 v[86:89], v[170:173], v[214:217], v[86:89]
	v_mfma_f32_16x16x32_bf16 v[82:85], v[178:181], v[214:217], v[82:85]
	v_mfma_f32_16x16x32_bf16 v[70:73], v[170:173], v[222:225], v[70:73]
	v_mfma_f32_16x16x32_bf16 v[66:69], v[178:181], v[222:225], v[66:69]
	s_barrier
	s_add_i32 s18, s50, s26
	v_lshl_add_u64 v[190:191], s[22:23], 0, v[148:149]
	s_mov_b32 m0, s18
	ds_read_b128 v[182:185], v198 offset:16384
	ds_read_b128 v[186:189], v198 offset:17408
	ds_read_b128 v[202:205], v198 offset:18432
	ds_read_b128 v[206:209], v198 offset:19456
	ds_read_b128 v[210:213], v198 offset:20480
	ds_read_b128 v[214:217], v198 offset:21504
	ds_read_b128 v[218:221], v198 offset:22528
	ds_read_b128 v[222:225], v198 offset:23552
	global_load_lds_dwordx4 v[190:191], off
	s_add_i32 m0, s18, 0x2000
	s_add_u32 s18, s22, 0x58000
	v_lshl_add_u64 v[226:227], s[22:23], 0, v[152:153]
	s_addc_u32 s19, s23, 0
	s_add_i32 s54, s51, s26
	global_load_lds_dwordx4 v[226:227], off
	v_lshl_add_u64 v[228:229], s[18:19], 0, v[148:149]
	s_mov_b32 m0, s54
	v_lshl_add_u64 v[230:231], s[46:47], 0, v[150:151]
	global_load_lds_dwordx4 v[228:229], off
	v_lshl_add_u64 v[228:229], s[18:19], 0, v[152:153]
	s_add_i32 m0, s54, 0x2000
	s_nop 0
	global_load_lds_dwordx4 v[228:229], off
	v_lshl_add_u64 v[228:229], s[46:47], 0, v[146:147]
	s_mov_b32 m0, s27
	s_nop 0
	global_load_lds_dwordx4 v[228:229], off
	s_mov_b32 m0, s28
	s_nop 0
	global_load_lds_dwordx4 v[230:231], off
	s_waitcnt vmcnt(8)
	s_waitcnt lgkmcnt(0)
	s_barrier
	s_waitcnt lgkmcnt(0)
	v_mfma_f32_16x16x32_bf16 v[62:65], v[130:133], v[182:185], v[62:65]
	v_mfma_f32_16x16x32_bf16 v[58:61], v[138:141], v[182:185], v[58:61]
	v_mfma_f32_16x16x32_bf16 v[46:49], v[130:133], v[202:205], v[46:49]
	v_mfma_f32_16x16x32_bf16 v[42:45], v[138:141], v[202:205], v[42:45]
	v_mfma_f32_16x16x32_bf16 v[30:33], v[130:133], v[210:213], v[30:33]
	v_mfma_f32_16x16x32_bf16 v[26:29], v[138:141], v[210:213], v[26:29]
	v_mfma_f32_16x16x32_bf16 v[14:17], v[130:133], v[218:221], v[14:17]
	v_mfma_f32_16x16x32_bf16 v[10:13], v[138:141], v[218:221], v[10:13]
	v_mfma_f32_16x16x32_bf16 v[62:65], v[134:137], v[186:189], v[62:65]
	v_mfma_f32_16x16x32_bf16 v[58:61], v[142:145], v[186:189], v[58:61]
	v_mfma_f32_16x16x32_bf16 v[46:49], v[134:137], v[206:209], v[46:49]
	v_mfma_f32_16x16x32_bf16 v[42:45], v[142:145], v[206:209], v[42:45]
	v_mfma_f32_16x16x32_bf16 v[30:33], v[134:137], v[214:217], v[30:33]
	v_mfma_f32_16x16x32_bf16 v[26:29], v[142:145], v[214:217], v[26:29]
	v_mfma_f32_16x16x32_bf16 v[14:17], v[134:137], v[222:225], v[14:17]
	v_mfma_f32_16x16x32_bf16 v[10:13], v[142:145], v[222:225], v[10:13]
	v_mfma_f32_16x16x32_bf16 v[54:57], v[166:169], v[182:185], v[54:57]
	v_mfma_f32_16x16x32_bf16 v[50:53], v[174:177], v[182:185], v[50:53]
	v_mfma_f32_16x16x32_bf16 v[38:41], v[166:169], v[202:205], v[38:41]
	v_mfma_f32_16x16x32_bf16 v[34:37], v[174:177], v[202:205], v[34:37]
	v_mfma_f32_16x16x32_bf16 v[22:25], v[166:169], v[210:213], v[22:25]
	v_mfma_f32_16x16x32_bf16 v[18:21], v[174:177], v[210:213], v[18:21]
	v_mfma_f32_16x16x32_bf16 v[6:9], v[166:169], v[218:221], v[6:9]
	v_mfma_f32_16x16x32_bf16 v[2:5], v[174:177], v[218:221], v[2:5]
	v_mfma_f32_16x16x32_bf16 v[54:57], v[170:173], v[186:189], v[54:57]
	v_mfma_f32_16x16x32_bf16 v[50:53], v[178:181], v[186:189], v[50:53]
	v_mfma_f32_16x16x32_bf16 v[38:41], v[170:173], v[206:209], v[38:41]
	v_mfma_f32_16x16x32_bf16 v[34:37], v[178:181], v[206:209], v[34:37]
	v_mfma_f32_16x16x32_bf16 v[22:25], v[170:173], v[214:217], v[22:25]
	v_mfma_f32_16x16x32_bf16 v[18:21], v[178:181], v[214:217], v[18:21]
	v_mfma_f32_16x16x32_bf16 v[6:9], v[170:173], v[222:225], v[6:9]
	v_mfma_f32_16x16x32_bf16 v[2:5], v[178:181], v[222:225], v[2:5]
	s_barrier
; #define PG8_STAGE(bufoff, gbase, voff) do { _Pragma("unroll") for (int _i = 0; _i < 2; ++_i) \
;         __builtin_amdgcn_global_load_lds((const unsigned*)((const char*)(gbase) + (voff)[_i]), (LAS unsigned*)(lds + (bufoff) + ldsw + _i * 8192), 16, 0, 0); } while (0)
; #define PG8_LDA(dst, b, h) do { _Pragma("unroll") for (int m = 0; m < 4; ++m) _Pragma("unroll") for (int k = 0; k < 2; ++k) dst[m][k] = *(const LAS bf16x8*)(lds + PG8_SA(b, h) + aoff + m * 2048 + k * 1024); } while (0)
; #define PG8_LDB(dst, b, h) do { _Pragma("unroll") for (int n = 0; n < 2; ++n) _Pragma("unroll") for (int k = 0; k < 2; ++k) dst[n][k] = *(const LAS bf16x8*)(lds + PG8_SB(b, h) + boff + n * 2048 + k * 1024); } while (0)
; #define PG8_MMA(ai, bj, At, Bt) do { __builtin_amdgcn_s_setprio(1); _Pragma("unroll") for (int m = 0; m < 4; ++m) _Pragma("unroll") for (int n = 0; n < 2; ++n) _Pragma("unroll") for (int k = 0; k < 2; ++k) \
;         acc[ai][bj][m][n] = __builtin_amdgcn_mfma_f32_16x16x32_bf16(Bt[n][k], At[m][k], acc[ai][bj][m][n], 0, 0, 0); __builtin_amdgcn_s_setprio(0); } while (0)
; #define PG8_WAIT_V(n) asm volatile("s_waitcnt vmcnt(" #n ")" ::: "memory")
; #define PG8_WAIT_L(n) asm volatile("s_waitcnt lgkmcnt(" #n ")" ::: "memory")
; #define PG8_BAR __builtin_amdgcn_s_barrier()
; #define PG8_SCHED __builtin_amdgcn_sched_barrier(0)
; template <class Epi, class Sched, bool ALIGN_EPI = false, bool SP2 = false>
; __device__ __forceinline__ void gemm_phase(LAS unsigned char* lds, const Gemm g, const Sched& S, const Epi& E) {
;     ...
;             PG8_LDB(B0, 1, 0); PG8_LDB(B1, 1, 1); PG8_SCHED; PG8_LDA(At, 1, 0); PG8_STAGE(PG8_SA(0, 1), a2 + hstep, voffA);
;             PG8_WAIT_V(8); PG8_WAIT_L(0); PG8_BAR; PG8_MMA(0, 0, At, B0); PG8_MMA(0, 1, At, B1); PG8_BAR; PG8_SCHED;
	s_add_i32 s54, 0, 0x18000
	s_add_i32 s55, 0, 0x1c000
	v_add_u32_e32 v142, s54, v1
	v_add_u32_e32 v154, s55, v1
	ds_read_b128 v[130:133], v142
	ds_read_b128 v[134:137], v142 offset:1024
	ds_read_b128 v[138:141], v142 offset:2048
	ds_read_b128 v[142:145], v142 offset:3072
	ds_read_b128 v[166:169], v154
	ds_read_b128 v[170:173], v154 offset:1024
	ds_read_b128 v[174:177], v154 offset:2048
	ds_read_b128 v[178:181], v154 offset:3072
	s_add_u32 s18, s46, 0x160000
	s_addc_u32 s19, s47, 0
	s_mov_b32 m0, s29
	v_lshl_add_u64 v[232:233], s[18:19], 0, v[146:147]
	ds_read_b128 v[182:185], v198 offset:32768
	ds_read_b128 v[186:189], v198 offset:33792
	ds_read_b128 v[202:205], v198 offset:34816
	ds_read_b128 v[206:209], v198 offset:35840
	ds_read_b128 v[210:213], v198 offset:36864
	ds_read_b128 v[214:217], v198 offset:37888
	ds_read_b128 v[218:221], v198 offset:38912
	ds_read_b128 v[222:225], v198 offset:39936
	global_load_lds_dwordx4 v[232:233], off
	v_lshl_add_u64 v[232:233], s[18:19], 0, v[150:151]
	s_mov_b32 m0, s30
	s_nop 0
	global_load_lds_dwordx4 v[232:233], off
	s_waitcnt vmcnt(8)
	s_waitcnt lgkmcnt(0)
	s_barrier
	s_waitcnt lgkmcnt(0)
	v_mfma_f32_16x16x32_bf16 v[126:129], v[130:133], v[182:185], v[126:129]
	v_mfma_f32_16x16x32_bf16 v[122:125], v[138:141], v[182:185], v[122:125]
	v_mfma_f32_16x16x32_bf16 v[110:113], v[130:133], v[202:205], v[110:113]
	v_mfma_f32_16x16x32_bf16 v[106:109], v[138:141], v[202:205], v[106:109]
	v_mfma_f32_16x16x32_bf16 v[94:97], v[130:133], v[210:213], v[94:97]
	v_mfma_f32_16x16x32_bf16 v[90:93], v[138:141], v[210:213], v[90:93]
	v_mfma_f32_16x16x32_bf16 v[78:81], v[130:133], v[218:221], v[78:81]
	v_mfma_f32_16x16x32_bf16 v[74:77], v[138:141], v[218:221], v[74:77]
	v_mfma_f32_16x16x32_bf16 v[126:129], v[134:137], v[186:189], v[126:129]
	v_mfma_f32_16x16x32_bf16 v[122:125], v[142:145], v[186:189], v[122:125]
	v_mfma_f32_16x16x32_bf16 v[110:113], v[134:137], v[206:209], v[110:113]
	v_mfma_f32_16x16x32_bf16 v[106:109], v[142:145], v[206:209], v[106:109]
	v_mfma_f32_16x16x32_bf16 v[94:97], v[134:137], v[214:217], v[94:97]
	v_mfma_f32_16x16x32_bf16 v[90:93], v[142:145], v[214:217], v[90:93]
	v_mfma_f32_16x16x32_bf16 v[78:81], v[134:137], v[222:225], v[78:81]
	v_mfma_f32_16x16x32_bf16 v[74:77], v[142:145], v[222:225], v[74:77]
	v_mfma_f32_16x16x32_bf16 v[118:121], v[166:169], v[182:185], v[118:121]
	v_mfma_f32_16x16x32_bf16 v[114:117], v[174:177], v[182:185], v[114:117]
	v_mfma_f32_16x16x32_bf16 v[102:105], v[166:169], v[202:205], v[102:105]
	v_mfma_f32_16x16x32_bf16 v[98:101], v[174:177], v[202:205], v[98:101]
	v_mfma_f32_16x16x32_bf16 v[86:89], v[166:169], v[210:213], v[86:89]
	v_mfma_f32_16x16x32_bf16 v[82:85], v[174:177], v[210:213], v[82:85]
	v_mfma_f32_16x16x32_bf16 v[70:73], v[166:169], v[218:221], v[70:73]
	v_mfma_f32_16x16x32_bf16 v[66:69], v[174:177], v[218:221], v[66:69]
	v_mfma_f32_16x16x32_bf16 v[118:121], v[170:173], v[186:189], v[118:121]
	v_mfma_f32_16x16x32_bf16 v[114:117], v[178:181], v[186:189], v[114:117]
	v_mfma_f32_16x16x32_bf16 v[102:105], v[170:173], v[206:209], v[102:105]
	v_mfma_f32_16x16x32_bf16 v[98:101], v[178:181], v[206:209], v[98:101]
	v_mfma_f32_16x16x32_bf16 v[86:89], v[170:173], v[214:217], v[86:89]
	v_mfma_f32_16x16x32_bf16 v[82:85], v[178:181], v[214:217], v[82:85]
	v_mfma_f32_16x16x32_bf16 v[70:73], v[170:173], v[222:225], v[70:73]
	v_mfma_f32_16x16x32_bf16 v[66:69], v[178:181], v[222:225], v[66:69]
	s_barrier
; #define PG8_STAGE(bufoff, gbase, voff) do { _Pragma("unroll") for (int _i = 0; _i < 2; ++_i) \
;         __builtin_amdgcn_global_load_lds((const unsigned*)((const char*)(gbase) + (voff)[_i]), (LAS unsigned*)(lds + (bufoff) + ldsw + _i * 8192), 16, 0, 0); } while (0)
; #define PG8_LDA(dst, b, h) do { _Pragma("unroll") for (int m = 0; m < 4; ++m) _Pragma("unroll") for (int k = 0; k < 2; ++k) dst[m][k] = *(const LAS bf16x8*)(lds + PG8_SA(b, h) + aoff + m * 2048 + k * 1024); } while (0)
; #define PG8_MMA(ai, bj, At, Bt) do { __builtin_amdgcn_s_setprio(1); _Pragma("unroll") for (int m = 0; m < 4; ++m) _Pragma("unroll") for (int n = 0; n < 2; ++n) _Pragma("unroll") for (int k = 0; k < 2; ++k) \
;         acc[ai][bj][m][n] = __builtin_amdgcn_mfma_f32_16x16x32_bf16(Bt[n][k], At[m][k], acc[ai][bj][m][n], 0, 0, 0); __builtin_amdgcn_s_setprio(0); } while (0)
; #define PG8_WAIT_V(n) asm volatile("s_waitcnt vmcnt(" #n ")" ::: "memory")
; #define PG8_WAIT_L(n) asm volatile("s_waitcnt lgkmcnt(" #n ")" ::: "memory")
; #define PG8_BAR __builtin_amdgcn_s_barrier()
; #define PG8_SCHED __builtin_amdgcn_sched_barrier(0)
; template <class Epi, class Sched, bool ALIGN_EPI = false, bool SP2 = false>
; __device__ __forceinline__ void gemm_phase(LAS unsigned char* lds, const Gemm g, const Sched& S, const Epi& E) {
;     ...
;         for (int t = 0; t < nt; t += 2) {
;     ...
;             PG8_LDA(At, 1, 1); PG8_STAGE(PG8_SB(1, 0), b3, voffB); PG8_STAGE(PG8_SB(1, 1), b3 + hstepB, voffB); PG8_STAGE(PG8_SA(1, 0), a3, voffA);
;             PG8_WAIT_V(8); PG8_WAIT_L(0); PG8_BAR; PG8_MMA(1, 0, At, B0); PG8_MMA(1, 1, At, B1); PG8_BAR; PG8_SCHED;
	s_add_i32 s18, s54, s26
	v_lshl_add_u64 v[190:191], v[190:191], 0, s[12:13]
	s_mov_b32 m0, s18
	ds_read_b128 v[182:185], v198 offset:49152
	ds_read_b128 v[186:189], v198 offset:50176
	ds_read_b128 v[202:205], v198 offset:51200
	ds_read_b128 v[206:209], v198 offset:52224
	ds_read_b128 v[210:213], v198 offset:53248
	ds_read_b128 v[214:217], v198 offset:54272
	ds_read_b128 v[218:221], v198 offset:55296
	ds_read_b128 v[222:225], v198 offset:56320
	global_load_lds_dwordx4 v[190:191], off
	s_add_i32 m0, s18, 0x2000
	s_add_u32 s18, s22, 0x58080
	v_lshl_add_u64 v[190:191], v[226:227], 0, s[12:13]
	s_addc_u32 s19, s23, 0
	s_add_i32 s22, s55, s26
	global_load_lds_dwordx4 v[190:191], off
	v_lshl_add_u64 v[190:191], s[18:19], 0, v[148:149]
	s_mov_b32 m0, s22
	s_nop 0
	global_load_lds_dwordx4 v[190:191], off
	v_lshl_add_u64 v[190:191], s[18:19], 0, v[152:153]
	s_add_i32 m0, s22, 0x2000
	s_nop 0
	global_load_lds_dwordx4 v[190:191], off
	v_lshl_add_u64 v[190:191], v[228:229], 0, s[12:13]
	s_mov_b32 m0, s37
	s_nop 0
	global_load_lds_dwordx4 v[190:191], off
	v_lshl_add_u64 v[190:191], v[230:231], 0, s[12:13]
	s_mov_b32 m0, s48
	s_nop 0
	global_load_lds_dwordx4 v[190:191], off
	s_waitcnt vmcnt(8)
	s_waitcnt lgkmcnt(0)
	s_barrier
	s_waitcnt lgkmcnt(0)
	v_mfma_f32_16x16x32_bf16 v[62:65], v[130:133], v[182:185], v[62:65]
	v_mfma_f32_16x16x32_bf16 v[58:61], v[138:141], v[182:185], v[58:61]
	v_mfma_f32_16x16x32_bf16 v[46:49], v[130:133], v[202:205], v[46:49]
	v_mfma_f32_16x16x32_bf16 v[42:45], v[138:141], v[202:205], v[42:45]
	v_mfma_f32_16x16x32_bf16 v[30:33], v[130:133], v[210:213], v[30:33]
	v_mfma_f32_16x16x32_bf16 v[26:29], v[138:141], v[210:213], v[26:29]
	v_mfma_f32_16x16x32_bf16 v[14:17], v[130:133], v[218:221], v[14:17]
	v_mfma_f32_16x16x32_bf16 v[10:13], v[138:141], v[218:221], v[10:13]
	v_mfma_f32_16x16x32_bf16 v[62:65], v[134:137], v[186:189], v[62:65]
	v_mfma_f32_16x16x32_bf16 v[58:61], v[142:145], v[186:189], v[58:61]
	v_mfma_f32_16x16x32_bf16 v[46:49], v[134:137], v[206:209], v[46:49]
	v_mfma_f32_16x16x32_bf16 v[42:45], v[142:145], v[206:209], v[42:45]
	v_mfma_f32_16x16x32_bf16 v[30:33], v[134:137], v[214:217], v[30:33]
	v_mfma_f32_16x16x32_bf16 v[26:29], v[142:145], v[214:217], v[26:29]
	v_mfma_f32_16x16x32_bf16 v[14:17], v[134:137], v[222:225], v[14:17]
	v_mfma_f32_16x16x32_bf16 v[10:13], v[142:145], v[222:225], v[10:13]
	v_mfma_f32_16x16x32_bf16 v[54:57], v[166:169], v[182:185], v[54:57]
	v_mfma_f32_16x16x32_bf16 v[50:53], v[174:177], v[182:185], v[50:53]
	v_mfma_f32_16x16x32_bf16 v[38:41], v[166:169], v[202:205], v[38:41]
	v_mfma_f32_16x16x32_bf16 v[34:37], v[174:177], v[202:205], v[34:37]
	v_mfma_f32_16x16x32_bf16 v[22:25], v[166:169], v[210:213], v[22:25]
	v_mfma_f32_16x16x32_bf16 v[18:21], v[174:177], v[210:213], v[18:21]
	v_mfma_f32_16x16x32_bf16 v[6:9], v[166:169], v[218:221], v[6:9]
	v_mfma_f32_16x16x32_bf16 v[2:5], v[174:177], v[218:221], v[2:5]
	v_mfma_f32_16x16x32_bf16 v[54:57], v[170:173], v[186:189], v[54:57]
	v_mfma_f32_16x16x32_bf16 v[50:53], v[178:181], v[186:189], v[50:53]
	v_mfma_f32_16x16x32_bf16 v[38:41], v[170:173], v[206:209], v[38:41]
	v_mfma_f32_16x16x32_bf16 v[34:37], v[178:181], v[206:209], v[34:37]
	v_mfma_f32_16x16x32_bf16 v[22:25], v[170:173], v[214:217], v[22:25]
	v_mfma_f32_16x16x32_bf16 v[18:21], v[178:181], v[214:217], v[18:21]
	v_mfma_f32_16x16x32_bf16 v[6:9], v[170:173], v[222:225], v[6:9]
	v_mfma_f32_16x16x32_bf16 v[2:5], v[178:181], v[222:225], v[2:5]
	s_barrier
	s_add_i32 s25, s25, 2
	s_add_u32 s5, s5, 0x100
	s_addc_u32 s24, s24, 0
	s_cmpk_lt_u32 s25, 0x56
	s_mov_b64 s[18:19], s[20:21]
	s_cbranch_scc1 .LBB0_1926
	s_andn2_b64 vcc, exec, s[14:15]
	s_cbranch_vccnz .LBB0_1929
	s_barrier

;     __device__ bool next(int i, Unit& u) const { if (i != 0 || c >= 128) return false; const int t = c >> 2; u.pm = t & 3; u.pn = t >> 2; u.koff = koff_bytes; u.q = c & 3; return true; }
; #define PG8_STAGE(bufoff, gbase, voff) do { _Pragma("unroll") for (int _i = 0; _i < 2; ++_i) \
;         __builtin_amdgcn_global_load_lds((const unsigned*)((const char*)(gbase) + (voff)[_i]), (LAS unsigned*)(lds + (bufoff) + ldsw + _i * 8192), 16, 0, 0); } while (0)
; #define PG8_LDA(dst, b, h) do { _Pragma("unroll") for (int m = 0; m < 4; ++m) _Pragma("unroll") for (int k = 0; k < 2; ++k) dst[m][k] = *(const LAS bf16x8*)(lds + PG8_SA(b, h) + aoff + m * 2048 + k * 1024); } while (0)
; #define PG8_LDB(dst, b, h) do { _Pragma("unroll") for (int n = 0; n < 2; ++n) _Pragma("unroll") for (int k = 0; k < 2; ++k) dst[n][k] = *(const LAS bf16x8*)(lds + PG8_SB(b, h) + boff + n * 2048 + k * 1024); } while (0)
; #define PG8_WAIT_V(n) asm volatile("s_waitcnt vmcnt(" #n ")" ::: "memory")
; template <class Epi, class Sched, bool ALIGN_EPI = false, bool SP2 = false>
; __device__ __forceinline__ void gemm_phase(LAS unsigned char* lds, const Gemm g, const Sched& S, const Epi& E) {
;     ...
;         const bool has_next = S.next(ui + 1, nxt);
;         const char* nA = has_next ? (const char*)g.A + (size_t)nxt.pm * tstep + nxt.koff : cA; const char* nB = has_next ? (const char*)g.Bt + (size_t)nxt.pn * tstep + nxt.koff : cB;
;         for (int t = 0; t < nt; t += 2) {
;             const bool last = (t == nt - 2);
;             const char* a1 = cA + (size_t)(t + 1) * kstep;
;             const char* a2 = last ? nA : cA + (size_t)(t + 2) * kstep; const char* b2 = last ? nB : cB + (size_t)(t + 2) * kstep;
;             const char* a3 = a2 + kstep; const char* b3 = b2 + kstep;
;             if (last && has_next) S.a_ready(nxt);
;             if constexpr (SP2) {
;             PG8_LDB(B0, 0, 0); PG8_LDB(B1, 0, 1); PG8_SCHED; PG8_LDA(At, 0, 0); PG8_STAGE(PG8_SA(1, 1), a1 + hstep, voffA);
;             PG8_WAIT_V(8); PG8_WAIT_L(0); PG8_BAR; PG8_MMA(0, 0, At, B0); PG8_MMA(0, 1, At, B1); PG8_BAR; PG8_SCHED;
;             PG8_LDA(At, 0, 1); PG8_STAGE(PG8_SB(0, 0), b2, voffB); PG8_STAGE(PG8_SB(0, 1), b2 + hstepB, voffB); PG8_STAGE(PG8_SA(0, 0), a2, voffA);
;             PG8_WAIT_V(8); PG8_WAIT_L(0); PG8_BAR; PG8_MMA(1, 0, At, B0); PG8_MMA(1, 1, At, B1); PG8_BAR; PG8_SCHED;
.LBB0_2142:
	s_ashr_i32 s13, s12, 31
	v_cmp_lt_i64_e64 s[44:45], s[14:15], v[176:177]
	s_lshl_b64 s[14:15], s[12:13], 20
	s_add_u32 s14, s93, s14
	s_addc_u32 s15, s92, s15
	s_and_b64 s[16:17], s[44:45], exec
	s_cselect_b32 s3, s15, s23
	s_cselect_b32 s13, s14, s22
	s_ashr_i32 s11, s10, 31
	s_lshl_b64 s[16:17], s[10:11], 20
	v_readlane_b32 s24, v254, 58
	v_readlane_b32 s25, v254, 59
	s_add_u32 s16, s24, s16
	s_addc_u32 s17, s25, s17
	s_and_b64 s[24:25], s[44:45], exec
	s_cselect_b32 s11, s17, s21
	s_cselect_b32 s19, s16, s20
	s_add_u32 s24, s20, 0x100
	s_addc_u32 s25, s21, 0
	s_add_u32 s20, s22, 0x80080
	s_addc_u32 s21, s23, 0
	s_mov_b32 s34, -2
	s_waitcnt vmcnt(0)
	ds_read_b128 v[34:37], v202
	ds_read_b128 v[38:41], v202 offset:1024
	ds_read_b128 v[42:45], v202 offset:2048
	ds_read_b128 v[46:49], v202 offset:3072
	ds_read_b128 v[98:101], v203
	ds_read_b128 v[102:105], v203 offset:1024
	ds_read_b128 v[106:109], v203 offset:2048
	ds_read_b128 v[110:113], v203 offset:3072
	s_add_u32 s22, s20, 0xfff80080
	s_addc_u32 s23, s21, -1
	s_cmp_eq_u32 s34, 28
	s_cselect_b32 s37, s3, s23
	s_cselect_b32 s36, s13, s22
	s_cselect_b32 s23, s11, s25
	s_cselect_b32 s22, s19, s24
	v_lshl_add_u64 v[182:183], s[20:21], 0, v[174:175]
	s_add_i32 m0, s28, 0xc000
	ds_read_b128 v[210:213], v204
	ds_read_b128 v[214:217], v204 offset:1024
	ds_read_b128 v[218:221], v204 offset:2048
	ds_read_b128 v[222:225], v204 offset:3072
	ds_read_b128 v[226:229], v204 offset:4096
	ds_read_b128 v[230:233], v204 offset:5120
	ds_read_b128 v[234:237], v204 offset:6144
	ds_read_b128 v[238:241], v204 offset:7168
	global_load_lds_dwordx4 v[182:183], off
	v_lshl_add_u64 v[182:183], s[20:21], 0, v[172:173]
	s_add_i32 m0, s28, 0xe000
	s_nop 0
	global_load_lds_dwordx4 v[182:183], off
	s_waitcnt lgkmcnt(0)
	s_barrier
	s_waitcnt lgkmcnt(0)
	v_mfma_f32_16x16x32_bf16 v[158:161], v[34:37], v[210:213], 0
	v_mfma_f32_16x16x32_bf16 v[154:157], v[42:45], v[210:213], 0
	v_mfma_f32_16x16x32_bf16 v[142:145], v[34:37], v[218:221], 0
	v_mfma_f32_16x16x32_bf16 v[138:141], v[42:45], v[218:221], 0
	v_mfma_f32_16x16x32_bf16 v[126:129], v[34:37], v[226:229], 0
	v_mfma_f32_16x16x32_bf16 v[122:125], v[42:45], v[226:229], 0
	v_mfma_f32_16x16x32_bf16 v[94:97], v[34:37], v[234:237], 0
	v_mfma_f32_16x16x32_bf16 v[90:93], v[42:45], v[234:237], 0
	v_mfma_f32_16x16x32_bf16 v[158:161], v[38:41], v[214:217], v[158:161]
	v_mfma_f32_16x16x32_bf16 v[154:157], v[46:49], v[214:217], v[154:157]
	v_mfma_f32_16x16x32_bf16 v[142:145], v[38:41], v[222:225], v[142:145]
	v_mfma_f32_16x16x32_bf16 v[138:141], v[46:49], v[222:225], v[138:141]
	v_mfma_f32_16x16x32_bf16 v[126:129], v[38:41], v[230:233], v[126:129]
	v_mfma_f32_16x16x32_bf16 v[122:125], v[46:49], v[230:233], v[122:125]
	v_mfma_f32_16x16x32_bf16 v[94:97], v[38:41], v[238:241], v[94:97]
	v_mfma_f32_16x16x32_bf16 v[90:93], v[46:49], v[238:241], v[90:93]
	v_mfma_f32_16x16x32_bf16 v[150:153], v[98:101], v[210:213], 0
	v_mfma_f32_16x16x32_bf16 v[146:149], v[106:109], v[210:213], 0
	v_mfma_f32_16x16x32_bf16 v[134:137], v[98:101], v[218:221], 0
	v_mfma_f32_16x16x32_bf16 v[130:133], v[106:109], v[218:221], 0
	v_mfma_f32_16x16x32_bf16 v[118:121], v[98:101], v[226:229], 0
	v_mfma_f32_16x16x32_bf16 v[114:117], v[106:109], v[226:229], 0
	v_mfma_f32_16x16x32_bf16 v[86:89], v[98:101], v[234:237], 0
	v_mfma_f32_16x16x32_bf16 v[82:85], v[106:109], v[234:237], 0
	v_mfma_f32_16x16x32_bf16 v[150:153], v[102:105], v[214:217], v[150:153]
	v_mfma_f32_16x16x32_bf16 v[146:149], v[110:113], v[214:217], v[146:149]
	v_mfma_f32_16x16x32_bf16 v[134:137], v[102:105], v[222:225], v[134:137]
	v_mfma_f32_16x16x32_bf16 v[130:133], v[110:113], v[222:225], v[130:133]
	v_mfma_f32_16x16x32_bf16 v[118:121], v[102:105], v[230:233], v[118:121]
	v_mfma_f32_16x16x32_bf16 v[114:117], v[110:113], v[230:233], v[114:117]
	v_mfma_f32_16x16x32_bf16 v[86:89], v[102:105], v[238:241], v[86:89]
	v_mfma_f32_16x16x32_bf16 v[82:85], v[110:113], v[238:241], v[82:85]
	s_barrier
	s_add_i32 s35, s56, s27
	v_lshl_add_u64 v[182:183], s[22:23], 0, v[164:165]
	s_mov_b32 m0, s35
	ds_read_b128 v[210:213], v204 offset:16384
	ds_read_b128 v[214:217], v204 offset:17408
	ds_read_b128 v[218:221], v204 offset:18432
	ds_read_b128 v[222:225], v204 offset:19456
	ds_read_b128 v[226:229], v204 offset:20480
	ds_read_b128 v[230:233], v204 offset:21504
	ds_read_b128 v[234:237], v204 offset:22528
	ds_read_b128 v[238:241], v204 offset:23552
	global_load_lds_dwordx4 v[182:183], off
	s_add_i32 m0, s35, 0x2000
	s_add_u32 s46, s22, 0x20000
	v_lshl_add_u64 v[242:243], s[22:23], 0, v[168:169]
	s_addc_u32 s47, s23, 0
	s_add_i32 s35, s57, s27
	global_load_lds_dwordx4 v[242:243], off
	v_lshl_add_u64 v[244:245], s[46:47], 0, v[164:165]
	s_mov_b32 m0, s35
	v_lshl_add_u64 v[246:247], s[36:37], 0, v[166:167]
	global_load_lds_dwordx4 v[244:245], off
	v_lshl_add_u64 v[244:245], s[46:47], 0, v[168:169]
	s_add_i32 m0, s35, 0x2000
	s_nop 0
	global_load_lds_dwordx4 v[244:245], off
	v_lshl_add_u64 v[244:245], s[36:37], 0, v[162:163]
	s_mov_b32 m0, s28
	s_nop 0
	global_load_lds_dwordx4 v[244:245], off
	s_mov_b32 m0, s29
	s_nop 0
	global_load_lds_dwordx4 v[246:247], off
	s_waitcnt lgkmcnt(0)
	s_barrier
; #define PG8_STAGE(bufoff, gbase, voff) do { _Pragma("unroll") for (int _i = 0; _i < 2; ++_i) \
;         __builtin_amdgcn_global_load_lds((const unsigned*)((const char*)(gbase) + (voff)[_i]), (LAS unsigned*)(lds + (bufoff) + ldsw + _i * 8192), 16, 0, 0); } while (0)
; #define PG8_LDA(dst, b, h) do { _Pragma("unroll") for (int m = 0; m < 4; ++m) _Pragma("unroll") for (int k = 0; k < 2; ++k) dst[m][k] = *(const LAS bf16x8*)(lds + PG8_SA(b, h) + aoff + m * 2048 + k * 1024); } while (0)
; #define PG8_LDB(dst, b, h) do { _Pragma("unroll") for (int n = 0; n < 2; ++n) _Pragma("unroll") for (int k = 0; k < 2; ++k) dst[n][k] = *(const LAS bf16x8*)(lds + PG8_SB(b, h) + boff + n * 2048 + k * 1024); } while (0)
; #define PG8_MMA(ai, bj, At, Bt) do { __builtin_amdgcn_s_setprio(1); _Pragma("unroll") for (int m = 0; m < 4; ++m) _Pragma("unroll") for (int n = 0; n < 2; ++n) _Pragma("unroll") for (int k = 0; k < 2; ++k) \
;         acc[ai][bj][m][n] = __builtin_amdgcn_mfma_f32_16x16x32_bf16(Bt[n][k], At[m][k], acc[ai][bj][m][n], 0, 0, 0); __builtin_amdgcn_s_setprio(0); } while (0)
; #define PG8_WAIT_V(n) asm volatile("s_waitcnt vmcnt(" #n ")" ::: "memory")
; #define PG8_WAIT_L(n) asm volatile("s_waitcnt lgkmcnt(" #n ")" ::: "memory")
; #define PG8_BAR __builtin_amdgcn_s_barrier()
; #define PG8_SCHED __builtin_amdgcn_sched_barrier(0)
; template <class Epi, class Sched, bool ALIGN_EPI = false, bool SP2 = false>
; __device__ __forceinline__ void gemm_phase(LAS unsigned char* lds, const Gemm g, const Sched& S, const Epi& E) {
;     ...
;             PG8_LDB(B0, 0, 0); PG8_LDB(B1, 0, 1); PG8_SCHED; PG8_LDA(At, 0, 0); PG8_STAGE(PG8_SA(1, 1), a1 + hstep, voffA);
;             PG8_WAIT_V(8); PG8_WAIT_L(0); PG8_BAR; PG8_MMA(0, 0, At, B0); PG8_MMA(0, 1, At, B1); PG8_BAR; PG8_SCHED;
;             PG8_LDA(At, 0, 1); PG8_STAGE(PG8_SB(0, 0), b2, voffB); PG8_STAGE(PG8_SB(0, 1), b2 + hstepB, voffB); PG8_STAGE(PG8_SA(0, 0), a2, voffA);
;             PG8_WAIT_V(8); PG8_WAIT_L(0); PG8_BAR; PG8_MMA(1, 0, At, B0); PG8_MMA(1, 1, At, B1); PG8_BAR; PG8_SCHED;
;             PG8_LDB(B0, 1, 0); PG8_LDB(B1, 1, 1); PG8_SCHED; PG8_LDA(At, 1, 0); PG8_STAGE(PG8_SA(0, 1), a2 + hstep, voffA);
;             PG8_WAIT_V(8); PG8_WAIT_L(0); PG8_BAR; PG8_MMA(0, 0, At, B0); PG8_MMA(0, 1, At, B1); PG8_BAR; PG8_SCHED;
	s_waitcnt lgkmcnt(0)
	v_mfma_f32_16x16x32_bf16 v[78:81], v[34:37], v[210:213], 0
	v_mfma_f32_16x16x32_bf16 v[74:77], v[42:45], v[210:213], 0
	v_mfma_f32_16x16x32_bf16 v[62:65], v[34:37], v[218:221], 0
	v_mfma_f32_16x16x32_bf16 v[58:61], v[42:45], v[218:221], 0
	v_mfma_f32_16x16x32_bf16 v[30:33], v[34:37], v[226:229], 0
	v_mfma_f32_16x16x32_bf16 v[26:29], v[42:45], v[226:229], 0
	v_mfma_f32_16x16x32_bf16 v[14:17], v[34:37], v[234:237], 0
	v_mfma_f32_16x16x32_bf16 v[10:13], v[42:45], v[234:237], 0
	v_mfma_f32_16x16x32_bf16 v[78:81], v[38:41], v[214:217], v[78:81]
	v_mfma_f32_16x16x32_bf16 v[74:77], v[46:49], v[214:217], v[74:77]
	v_mfma_f32_16x16x32_bf16 v[62:65], v[38:41], v[222:225], v[62:65]
	v_mfma_f32_16x16x32_bf16 v[58:61], v[46:49], v[222:225], v[58:61]
	v_mfma_f32_16x16x32_bf16 v[30:33], v[38:41], v[230:233], v[30:33]
	v_mfma_f32_16x16x32_bf16 v[26:29], v[46:49], v[230:233], v[26:29]
	v_mfma_f32_16x16x32_bf16 v[14:17], v[38:41], v[238:241], v[14:17]
	v_mfma_f32_16x16x32_bf16 v[10:13], v[46:49], v[238:241], v[10:13]
	v_mfma_f32_16x16x32_bf16 v[22:25], v[98:101], v[226:229], 0
	v_mfma_f32_16x16x32_bf16 v[18:21], v[106:109], v[226:229], 0
	v_mfma_f32_16x16x32_bf16 v[6:9], v[98:101], v[234:237], 0
	v_mfma_f32_16x16x32_bf16 v[2:5], v[106:109], v[234:237], 0
	v_mfma_f32_16x16x32_bf16 v[34:37], v[98:101], v[210:213], 0
	v_mfma_f32_16x16x32_bf16 v[38:41], v[106:109], v[210:213], 0
	v_mfma_f32_16x16x32_bf16 v[42:45], v[98:101], v[218:221], 0
	v_mfma_f32_16x16x32_bf16 v[46:49], v[106:109], v[218:221], 0
	v_mfma_f32_16x16x32_bf16 v[22:25], v[102:105], v[230:233], v[22:25]
	v_mfma_f32_16x16x32_bf16 v[18:21], v[110:113], v[230:233], v[18:21]
	v_mfma_f32_16x16x32_bf16 v[6:9], v[102:105], v[238:241], v[6:9]
	v_mfma_f32_16x16x32_bf16 v[2:5], v[110:113], v[238:241], v[2:5]
	v_mfma_f32_16x16x32_bf16 v[34:37], v[102:105], v[214:217], v[34:37]
	v_mfma_f32_16x16x32_bf16 v[38:41], v[110:113], v[214:217], v[38:41]
	v_mfma_f32_16x16x32_bf16 v[42:45], v[102:105], v[222:225], v[42:45]
	v_mfma_f32_16x16x32_bf16 v[46:49], v[110:113], v[222:225], v[46:49]
	s_barrier
	s_add_i32 s35, 0, 0x18000
	s_add_i32 s46, 0, 0x1c000
	v_add_u32_e32 v70, s35, v185
	v_add_u32_e32 v110, s46, v185
	ds_read_b128 v[50:53], v70
	ds_read_b128 v[54:57], v70 offset:1024
	ds_read_b128 v[66:69], v70 offset:2048
	ds_read_b128 v[70:73], v70 offset:3072
	ds_read_b128 v[98:101], v110
	ds_read_b128 v[102:105], v110 offset:1024
	ds_read_b128 v[106:109], v110 offset:2048
	ds_read_b128 v[110:113], v110 offset:3072
	s_add_u32 s36, s36, 0x80000
	s_addc_u32 s37, s37, 0
	s_mov_b32 m0, s30
	v_lshl_add_u64 v[248:249], s[36:37], 0, v[162:163]
	ds_read_b128 v[210:213], v204 offset:32768
	ds_read_b128 v[214:217], v204 offset:33792
	ds_read_b128 v[218:221], v204 offset:34816
	ds_read_b128 v[222:225], v204 offset:35840
	ds_read_b128 v[226:229], v204 offset:36864
	ds_read_b128 v[230:233], v204 offset:37888
	ds_read_b128 v[234:237], v204 offset:38912
	ds_read_b128 v[238:241], v204 offset:39936
	global_load_lds_dwordx4 v[248:249], off
	v_lshl_add_u64 v[248:249], s[36:37], 0, v[166:167]
	s_mov_b32 m0, s31
	s_nop 0
	global_load_lds_dwordx4 v[248:249], off
	s_waitcnt vmcnt(8)
	s_waitcnt lgkmcnt(0)
	s_barrier
	s_waitcnt lgkmcnt(0)
	v_mfma_f32_16x16x32_bf16 v[158:161], v[50:53], v[210:213], v[158:161]
	v_mfma_f32_16x16x32_bf16 v[154:157], v[66:69], v[210:213], v[154:157]
	v_mfma_f32_16x16x32_bf16 v[142:145], v[50:53], v[218:221], v[142:145]
	v_mfma_f32_16x16x32_bf16 v[138:141], v[66:69], v[218:221], v[138:141]
	v_mfma_f32_16x16x32_bf16 v[126:129], v[50:53], v[226:229], v[126:129]
	v_mfma_f32_16x16x32_bf16 v[122:125], v[66:69], v[226:229], v[122:125]
	v_mfma_f32_16x16x32_bf16 v[94:97], v[50:53], v[234:237], v[94:97]
	v_mfma_f32_16x16x32_bf16 v[90:93], v[66:69], v[234:237], v[90:93]
	v_mfma_f32_16x16x32_bf16 v[158:161], v[54:57], v[214:217], v[158:161]
	v_mfma_f32_16x16x32_bf16 v[154:157], v[70:73], v[214:217], v[154:157]
	v_mfma_f32_16x16x32_bf16 v[142:145], v[54:57], v[222:225], v[142:145]
	v_mfma_f32_16x16x32_bf16 v[138:141], v[70:73], v[222:225], v[138:141]
	v_mfma_f32_16x16x32_bf16 v[126:129], v[54:57], v[230:233], v[126:129]
	v_mfma_f32_16x16x32_bf16 v[122:125], v[70:73], v[230:233], v[122:125]
	v_mfma_f32_16x16x32_bf16 v[94:97], v[54:57], v[238:241], v[94:97]
	v_mfma_f32_16x16x32_bf16 v[90:93], v[70:73], v[238:241], v[90:93]
	v_mfma_f32_16x16x32_bf16 v[150:153], v[98:101], v[210:213], v[150:153]
	v_mfma_f32_16x16x32_bf16 v[146:149], v[106:109], v[210:213], v[146:149]
	v_mfma_f32_16x16x32_bf16 v[134:137], v[98:101], v[218:221], v[134:137]
	v_mfma_f32_16x16x32_bf16 v[130:133], v[106:109], v[218:221], v[130:133]
	v_mfma_f32_16x16x32_bf16 v[118:121], v[98:101], v[226:229], v[118:121]
	v_mfma_f32_16x16x32_bf16 v[114:117], v[106:109], v[226:229], v[114:117]
	v_mfma_f32_16x16x32_bf16 v[86:89], v[98:101], v[234:237], v[86:89]
	v_mfma_f32_16x16x32_bf16 v[82:85], v[106:109], v[234:237], v[82:85]
	v_mfma_f32_16x16x32_bf16 v[150:153], v[102:105], v[214:217], v[150:153]
	v_mfma_f32_16x16x32_bf16 v[146:149], v[110:113], v[214:217], v[146:149]
	v_mfma_f32_16x16x32_bf16 v[134:137], v[102:105], v[222:225], v[134:137]
	v_mfma_f32_16x16x32_bf16 v[130:133], v[110:113], v[222:225], v[130:133]
	v_mfma_f32_16x16x32_bf16 v[118:121], v[102:105], v[230:233], v[118:121]
	v_mfma_f32_16x16x32_bf16 v[114:117], v[110:113], v[230:233], v[114:117]
	v_mfma_f32_16x16x32_bf16 v[86:89], v[102:105], v[238:241], v[86:89]
	v_mfma_f32_16x16x32_bf16 v[82:85], v[110:113], v[238:241], v[82:85]
	s_barrier
; #define PG8_STAGE(bufoff, gbase, voff) do { _Pragma("unroll") for (int _i = 0; _i < 2; ++_i) \
;         __builtin_amdgcn_global_load_lds((const unsigned*)((const char*)(gbase) + (voff)[_i]), (LAS unsigned*)(lds + (bufoff) + ldsw + _i * 8192), 16, 0, 0); } while (0)
; #define PG8_LDA(dst, b, h) do { _Pragma("unroll") for (int m = 0; m < 4; ++m) _Pragma("unroll") for (int k = 0; k < 2; ++k) dst[m][k] = *(const LAS bf16x8*)(lds + PG8_SA(b, h) + aoff + m * 2048 + k * 1024); } while (0)
; #define PG8_LDB(dst, b, h) do { _Pragma("unroll") for (int n = 0; n < 2; ++n) _Pragma("unroll") for (int k = 0; k < 2; ++k) dst[n][k] = *(const LAS bf16x8*)(lds + PG8_SB(b, h) + boff + n * 2048 + k * 1024); } while (0)
; #define PG8_MMA(ai, bj, At, Bt) do { __builtin_amdgcn_s_setprio(1); _Pragma("unroll") for (int m = 0; m < 4; ++m) _Pragma("unroll") for (int n = 0; n < 2; ++n) _Pragma("unroll") for (int k = 0; k < 2; ++k) \
;         acc[ai][bj][m][n] = __builtin_amdgcn_mfma_f32_16x16x32_bf16(Bt[n][k], At[m][k], acc[ai][bj][m][n], 0, 0, 0); __builtin_amdgcn_s_setprio(0); } while (0)
; #define PG8_WAIT_V(n) asm volatile("s_waitcnt vmcnt(" #n ")" ::: "memory")
; #define PG8_WAIT_L(n) asm volatile("s_waitcnt lgkmcnt(" #n ")" ::: "memory")
; #define PG8_BAR __builtin_amdgcn_s_barrier()
; #define PG8_SCHED __builtin_amdgcn_sched_barrier(0)
; template <class Epi, class Sched, bool ALIGN_EPI = false, bool SP2 = false>
; __device__ __forceinline__ void gemm_phase(LAS unsigned char* lds, const Gemm g, const Sched& S, const Epi& E) {
;     ...
;             PG8_LDB(B0, 0, 0); PG8_LDB(B1, 0, 1); PG8_SCHED; PG8_LDA(At, 0, 0); PG8_STAGE(PG8_SA(1, 1), a1 + hstep, voffA);
;             PG8_WAIT_V(8); PG8_WAIT_L(0); PG8_BAR; PG8_MMA(0, 0, At, B0); PG8_MMA(0, 1, At, B1); PG8_BAR; PG8_SCHED;
;     ...
;             PG8_LDA(At, 1, 1); PG8_STAGE(PG8_SB(1, 0), b3, voffB); PG8_STAGE(PG8_SB(1, 1), b3 + hstepB, voffB); PG8_STAGE(PG8_SA(1, 0), a3, voffA);
;             PG8_WAIT_V(8); PG8_WAIT_L(0); PG8_BAR; PG8_MMA(1, 0, At, B0); PG8_MMA(1, 1, At, B1); PG8_BAR; PG8_SCHED;
	s_add_i32 s35, s35, s27
	v_lshl_add_u64 v[182:183], v[182:183], 0, s[4:5]
	s_mov_b32 m0, s35
	ds_read_b128 v[210:213], v204 offset:49152
	ds_read_b128 v[214:217], v204 offset:50176
	ds_read_b128 v[218:221], v204 offset:51200
	ds_read_b128 v[222:225], v204 offset:52224
	ds_read_b128 v[226:229], v204 offset:53248
	ds_read_b128 v[230:233], v204 offset:54272
	ds_read_b128 v[234:237], v204 offset:55296
	ds_read_b128 v[238:241], v204 offset:56320
	global_load_lds_dwordx4 v[182:183], off
	s_add_i32 m0, s35, 0x2000
	s_add_u32 s22, s22, 0x20080
	v_lshl_add_u64 v[182:183], v[242:243], 0, s[4:5]
	s_addc_u32 s23, s23, 0
	s_add_i32 s35, s46, s27
	global_load_lds_dwordx4 v[182:183], off
	v_lshl_add_u64 v[182:183], s[22:23], 0, v[164:165]
	s_mov_b32 m0, s35
	s_nop 0
	global_load_lds_dwordx4 v[182:183], off
	v_lshl_add_u64 v[182:183], s[22:23], 0, v[168:169]
	s_add_i32 m0, s35, 0x2000
	s_nop 0
	global_load_lds_dwordx4 v[182:183], off
	v_lshl_add_u64 v[182:183], v[244:245], 0, s[4:5]
	s_mov_b32 m0, s53
	s_nop 0
	global_load_lds_dwordx4 v[182:183], off
	v_lshl_add_u64 v[182:183], v[246:247], 0, s[4:5]
	s_mov_b32 m0, s54
	s_nop 0
	global_load_lds_dwordx4 v[182:183], off
	s_waitcnt vmcnt(8)
	s_waitcnt lgkmcnt(0)
	s_barrier
	s_waitcnt lgkmcnt(0)
	v_mfma_f32_16x16x32_bf16 v[78:81], v[50:53], v[210:213], v[78:81]
	v_mfma_f32_16x16x32_bf16 v[74:77], v[66:69], v[210:213], v[74:77]
	v_mfma_f32_16x16x32_bf16 v[62:65], v[50:53], v[218:221], v[62:65]
	v_mfma_f32_16x16x32_bf16 v[58:61], v[66:69], v[218:221], v[58:61]
	v_mfma_f32_16x16x32_bf16 v[30:33], v[50:53], v[226:229], v[30:33]
	v_mfma_f32_16x16x32_bf16 v[26:29], v[66:69], v[226:229], v[26:29]
	v_mfma_f32_16x16x32_bf16 v[14:17], v[50:53], v[234:237], v[14:17]
	v_mfma_f32_16x16x32_bf16 v[10:13], v[66:69], v[234:237], v[10:13]
	v_mfma_f32_16x16x32_bf16 v[78:81], v[54:57], v[214:217], v[78:81]
	v_mfma_f32_16x16x32_bf16 v[74:77], v[70:73], v[214:217], v[74:77]
	v_mfma_f32_16x16x32_bf16 v[62:65], v[54:57], v[222:225], v[62:65]
	v_mfma_f32_16x16x32_bf16 v[58:61], v[70:73], v[222:225], v[58:61]
	v_mfma_f32_16x16x32_bf16 v[30:33], v[54:57], v[230:233], v[30:33]
	v_mfma_f32_16x16x32_bf16 v[26:29], v[70:73], v[230:233], v[26:29]
	v_mfma_f32_16x16x32_bf16 v[14:17], v[54:57], v[238:241], v[14:17]
	v_mfma_f32_16x16x32_bf16 v[10:13], v[70:73], v[238:241], v[10:13]
	v_mfma_f32_16x16x32_bf16 v[34:37], v[98:101], v[210:213], v[34:37]
	v_mfma_f32_16x16x32_bf16 v[70:73], v[102:105], v[214:217], v[34:37]
	v_mfma_f32_16x16x32_bf16 v[34:37], v[106:109], v[210:213], v[38:41]
	v_mfma_f32_16x16x32_bf16 v[66:69], v[110:113], v[214:217], v[34:37]
	v_mfma_f32_16x16x32_bf16 v[34:37], v[98:101], v[218:221], v[42:45]
	v_mfma_f32_16x16x32_bf16 v[54:57], v[102:105], v[222:225], v[34:37]
	v_mfma_f32_16x16x32_bf16 v[34:37], v[106:109], v[218:221], v[46:49]
	v_mfma_f32_16x16x32_bf16 v[22:25], v[98:101], v[226:229], v[22:25]
	v_mfma_f32_16x16x32_bf16 v[18:21], v[106:109], v[226:229], v[18:21]
	v_mfma_f32_16x16x32_bf16 v[6:9], v[98:101], v[234:237], v[6:9]
	v_mfma_f32_16x16x32_bf16 v[2:5], v[106:109], v[234:237], v[2:5]
	v_mfma_f32_16x16x32_bf16 v[50:53], v[110:113], v[222:225], v[34:37]
	v_mfma_f32_16x16x32_bf16 v[22:25], v[102:105], v[230:233], v[22:25]
	v_mfma_f32_16x16x32_bf16 v[18:21], v[110:113], v[230:233], v[18:21]
	v_mfma_f32_16x16x32_bf16 v[6:9], v[102:105], v[238:241], v[6:9]
	v_mfma_f32_16x16x32_bf16 v[2:5], v[110:113], v[238:241], v[2:5]
	s_barrier
	s_add_i32 s34, s34, 2
	s_add_u32 s24, s24, 0x100
	s_addc_u32 s25, s25, 0
	s_add_u32 s20, s20, 0x100
	s_addc_u32 s21, s21, 0
	s_cmp_lt_u32 s34, 30
.LBB0_2143:
	ds_read_b128 v[34:37], v202
	ds_read_b128 v[38:41], v202 offset:1024
	ds_read_b128 v[42:45], v202 offset:2048
	ds_read_b128 v[46:49], v202 offset:3072
	ds_read_b128 v[98:101], v203
	ds_read_b128 v[102:105], v203 offset:1024
	ds_read_b128 v[106:109], v203 offset:2048
	ds_read_b128 v[110:113], v203 offset:3072
	s_add_u32 s22, s20, 0xfff80080
	s_addc_u32 s23, s21, -1
	s_cmp_eq_u32 s34, 28
	s_cselect_b32 s37, s3, s23
	s_cselect_b32 s36, s13, s22
	s_cselect_b32 s23, s11, s25
	s_cselect_b32 s22, s19, s24
	v_lshl_add_u64 v[182:183], s[20:21], 0, v[174:175]
	s_add_i32 m0, s28, 0xc000
	ds_read_b128 v[210:213], v204
	ds_read_b128 v[214:217], v204 offset:1024
	ds_read_b128 v[218:221], v204 offset:2048
	ds_read_b128 v[222:225], v204 offset:3072
	ds_read_b128 v[226:229], v204 offset:4096
	ds_read_b128 v[230:233], v204 offset:5120
	ds_read_b128 v[234:237], v204 offset:6144
	ds_read_b128 v[238:241], v204 offset:7168
	global_load_lds_dwordx4 v[182:183], off
	v_lshl_add_u64 v[182:183], s[20:21], 0, v[172:173]
	s_add_i32 m0, s28, 0xe000
	s_nop 0
	global_load_lds_dwordx4 v[182:183], off
	s_waitcnt vmcnt(8)
	s_waitcnt lgkmcnt(0)
	s_barrier
; #define PG8_STAGE(bufoff, gbase, voff) do { _Pragma("unroll") for (int _i = 0; _i < 2; ++_i) \
;         __builtin_amdgcn_global_load_lds((const unsigned*)((const char*)(gbase) + (voff)[_i]), (LAS unsigned*)(lds + (bufoff) + ldsw + _i * 8192), 16, 0, 0); } while (0)
; #define PG8_LDA(dst, b, h) do { _Pragma("unroll") for (int m = 0; m < 4; ++m) _Pragma("unroll") for (int k = 0; k < 2; ++k) dst[m][k] = *(const LAS bf16x8*)(lds + PG8_SA(b, h) + aoff + m * 2048 + k * 1024); } while (0)
; #define PG8_LDB(dst, b, h) do { _Pragma("unroll") for (int n = 0; n < 2; ++n) _Pragma("unroll") for (int k = 0; k < 2; ++k) dst[n][k] = *(const LAS bf16x8*)(lds + PG8_SB(b, h) + boff + n * 2048 + k * 1024); } while (0)
; #define PG8_MMA(ai, bj, At, Bt) do { __builtin_amdgcn_s_setprio(1); _Pragma("unroll") for (int m = 0; m < 4; ++m) _Pragma("unroll") for (int n = 0; n < 2; ++n) _Pragma("unroll") for (int k = 0; k < 2; ++k) \
;         acc[ai][bj][m][n] = __builtin_amdgcn_mfma_f32_16x16x32_bf16(Bt[n][k], At[m][k], acc[ai][bj][m][n], 0, 0, 0); __builtin_amdgcn_s_setprio(0); } while (0)
; #define PG8_BAR __builtin_amdgcn_s_barrier()
; template <class Epi, class Sched, bool ALIGN_EPI = false, bool SP2 = false>
; __device__ __forceinline__ void gemm_phase(LAS unsigned char* lds, const Gemm g, const Sched& S, const Epi& E) {
;     ...
;             if constexpr (SP2) {
;             PG8_LDB(B0, 0, 0); PG8_LDB(B1, 0, 1); PG8_SCHED; PG8_LDA(At, 0, 0); PG8_STAGE(PG8_SA(1, 1), a1 + hstep, voffA);
;             PG8_WAIT_V(8); PG8_WAIT_L(0); PG8_BAR; PG8_MMA(0, 0, At, B0); PG8_MMA(0, 1, At, B1); PG8_BAR; PG8_SCHED;
;             PG8_LDA(At, 0, 1); PG8_STAGE(PG8_SB(0, 0), b2, voffB); PG8_STAGE(PG8_SB(0, 1), b2 + hstepB, voffB); PG8_STAGE(PG8_SA(0, 0), a2, voffA);
;             PG8_WAIT_V(8); PG8_WAIT_L(0); PG8_BAR; PG8_MMA(1, 0, At, B0); PG8_MMA(1, 1, At, B1); PG8_BAR; PG8_SCHED;
;             PG8_LDB(B0, 1, 0); PG8_LDB(B1, 1, 1); PG8_SCHED; PG8_LDA(At, 1, 0); PG8_STAGE(PG8_SA(0, 1), a2 + hstep, voffA);
;             PG8_WAIT_V(8); PG8_WAIT_L(0); PG8_BAR; PG8_MMA(0, 0, At, B0); PG8_MMA(0, 1, At, B1); PG8_BAR; PG8_SCHED;
;             PG8_LDA(At, 1, 1); PG8_STAGE(PG8_SB(1, 0), b3, voffB); PG8_STAGE(PG8_SB(1, 1), b3 + hstepB, voffB); PG8_STAGE(PG8_SA(1, 0), a3, voffA);
;             PG8_WAIT_V(8); PG8_WAIT_L(0); PG8_BAR; PG8_MMA(1, 0, At, B0); PG8_MMA(1, 1, At, B1); PG8_BAR; PG8_SCHED;
	s_waitcnt lgkmcnt(0)
	v_mfma_f32_16x16x32_bf16 v[158:161], v[34:37], v[210:213], v[158:161]
	v_mfma_f32_16x16x32_bf16 v[154:157], v[42:45], v[210:213], v[154:157]
	v_mfma_f32_16x16x32_bf16 v[142:145], v[34:37], v[218:221], v[142:145]
	v_mfma_f32_16x16x32_bf16 v[138:141], v[42:45], v[218:221], v[138:141]
	v_mfma_f32_16x16x32_bf16 v[126:129], v[34:37], v[226:229], v[126:129]
	v_mfma_f32_16x16x32_bf16 v[122:125], v[42:45], v[226:229], v[122:125]
	v_mfma_f32_16x16x32_bf16 v[94:97], v[34:37], v[234:237], v[94:97]
	v_mfma_f32_16x16x32_bf16 v[90:93], v[42:45], v[234:237], v[90:93]
	v_mfma_f32_16x16x32_bf16 v[158:161], v[38:41], v[214:217], v[158:161]
	v_mfma_f32_16x16x32_bf16 v[154:157], v[46:49], v[214:217], v[154:157]
	v_mfma_f32_16x16x32_bf16 v[142:145], v[38:41], v[222:225], v[142:145]
	v_mfma_f32_16x16x32_bf16 v[138:141], v[46:49], v[222:225], v[138:141]
	v_mfma_f32_16x16x32_bf16 v[126:129], v[38:41], v[230:233], v[126:129]
	v_mfma_f32_16x16x32_bf16 v[122:125], v[46:49], v[230:233], v[122:125]
	v_mfma_f32_16x16x32_bf16 v[94:97], v[38:41], v[238:241], v[94:97]
	v_mfma_f32_16x16x32_bf16 v[90:93], v[46:49], v[238:241], v[90:93]
	v_mfma_f32_16x16x32_bf16 v[150:153], v[98:101], v[210:213], v[150:153]
	v_mfma_f32_16x16x32_bf16 v[146:149], v[106:109], v[210:213], v[146:149]
	v_mfma_f32_16x16x32_bf16 v[134:137], v[98:101], v[218:221], v[134:137]
	v_mfma_f32_16x16x32_bf16 v[130:133], v[106:109], v[218:221], v[130:133]
	v_mfma_f32_16x16x32_bf16 v[118:121], v[98:101], v[226:229], v[118:121]
	v_mfma_f32_16x16x32_bf16 v[114:117], v[106:109], v[226:229], v[114:117]
	v_mfma_f32_16x16x32_bf16 v[86:89], v[98:101], v[234:237], v[86:89]
	v_mfma_f32_16x16x32_bf16 v[82:85], v[106:109], v[234:237], v[82:85]
	v_mfma_f32_16x16x32_bf16 v[150:153], v[102:105], v[214:217], v[150:153]
	v_mfma_f32_16x16x32_bf16 v[146:149], v[110:113], v[214:217], v[146:149]
	v_mfma_f32_16x16x32_bf16 v[134:137], v[102:105], v[222:225], v[134:137]
	v_mfma_f32_16x16x32_bf16 v[130:133], v[110:113], v[222:225], v[130:133]
	v_mfma_f32_16x16x32_bf16 v[118:121], v[102:105], v[230:233], v[118:121]
	v_mfma_f32_16x16x32_bf16 v[114:117], v[110:113], v[230:233], v[114:117]
	v_mfma_f32_16x16x32_bf16 v[86:89], v[102:105], v[238:241], v[86:89]
	v_mfma_f32_16x16x32_bf16 v[82:85], v[110:113], v[238:241], v[82:85]
	s_barrier
	s_add_i32 s35, s56, s27
	v_lshl_add_u64 v[182:183], s[22:23], 0, v[164:165]
	s_mov_b32 m0, s35
	ds_read_b128 v[210:213], v204 offset:16384
	ds_read_b128 v[214:217], v204 offset:17408
	ds_read_b128 v[218:221], v204 offset:18432
	ds_read_b128 v[222:225], v204 offset:19456
	ds_read_b128 v[226:229], v204 offset:20480
	ds_read_b128 v[230:233], v204 offset:21504
	ds_read_b128 v[234:237], v204 offset:22528
	ds_read_b128 v[238:241], v204 offset:23552
	global_load_lds_dwordx4 v[182:183], off
	s_add_i32 m0, s35, 0x2000
	s_add_u32 s46, s22, 0x20000
	v_lshl_add_u64 v[242:243], s[22:23], 0, v[168:169]
	s_addc_u32 s47, s23, 0
	s_add_i32 s35, s57, s27
	global_load_lds_dwordx4 v[242:243], off
	v_lshl_add_u64 v[244:245], s[46:47], 0, v[164:165]
	s_mov_b32 m0, s35
	v_lshl_add_u64 v[246:247], s[36:37], 0, v[166:167]
	global_load_lds_dwordx4 v[244:245], off
	v_lshl_add_u64 v[244:245], s[46:47], 0, v[168:169]
	s_add_i32 m0, s35, 0x2000
	s_nop 0
	global_load_lds_dwordx4 v[244:245], off
	v_lshl_add_u64 v[244:245], s[36:37], 0, v[162:163]
	s_mov_b32 m0, s28
	s_nop 0
	global_load_lds_dwordx4 v[244:245], off
	s_mov_b32 m0, s29
	s_nop 0
	global_load_lds_dwordx4 v[246:247], off
	s_waitcnt vmcnt(8)
	s_waitcnt lgkmcnt(0)
	s_barrier
	s_waitcnt lgkmcnt(0)
	v_mfma_f32_16x16x32_bf16 v[78:81], v[34:37], v[210:213], v[78:81]
	v_mfma_f32_16x16x32_bf16 v[74:77], v[42:45], v[210:213], v[74:77]
	v_mfma_f32_16x16x32_bf16 v[62:65], v[34:37], v[218:221], v[62:65]
	v_mfma_f32_16x16x32_bf16 v[58:61], v[42:45], v[218:221], v[58:61]
	v_mfma_f32_16x16x32_bf16 v[30:33], v[34:37], v[226:229], v[30:33]
	v_mfma_f32_16x16x32_bf16 v[26:29], v[42:45], v[226:229], v[26:29]
	v_mfma_f32_16x16x32_bf16 v[14:17], v[34:37], v[234:237], v[14:17]
	v_mfma_f32_16x16x32_bf16 v[10:13], v[42:45], v[234:237], v[10:13]
	v_mfma_f32_16x16x32_bf16 v[78:81], v[38:41], v[214:217], v[78:81]
	v_mfma_f32_16x16x32_bf16 v[74:77], v[46:49], v[214:217], v[74:77]
	v_mfma_f32_16x16x32_bf16 v[62:65], v[38:41], v[222:225], v[62:65]
	v_mfma_f32_16x16x32_bf16 v[58:61], v[46:49], v[222:225], v[58:61]
	v_mfma_f32_16x16x32_bf16 v[30:33], v[38:41], v[230:233], v[30:33]
	v_mfma_f32_16x16x32_bf16 v[26:29], v[46:49], v[230:233], v[26:29]
	v_mfma_f32_16x16x32_bf16 v[14:17], v[38:41], v[238:241], v[14:17]
	v_mfma_f32_16x16x32_bf16 v[10:13], v[46:49], v[238:241], v[10:13]
	v_mfma_f32_16x16x32_bf16 v[22:25], v[98:101], v[226:229], v[22:25]
	v_mfma_f32_16x16x32_bf16 v[18:21], v[106:109], v[226:229], v[18:21]
	v_mfma_f32_16x16x32_bf16 v[6:9], v[98:101], v[234:237], v[6:9]
	v_mfma_f32_16x16x32_bf16 v[2:5], v[106:109], v[234:237], v[2:5]
	v_mfma_f32_16x16x32_bf16 v[34:37], v[98:101], v[210:213], v[70:73]
	v_mfma_f32_16x16x32_bf16 v[38:41], v[106:109], v[210:213], v[66:69]
	v_mfma_f32_16x16x32_bf16 v[42:45], v[98:101], v[218:221], v[54:57]
	v_mfma_f32_16x16x32_bf16 v[46:49], v[106:109], v[218:221], v[50:53]
	v_mfma_f32_16x16x32_bf16 v[22:25], v[102:105], v[230:233], v[22:25]
	v_mfma_f32_16x16x32_bf16 v[18:21], v[110:113], v[230:233], v[18:21]
	v_mfma_f32_16x16x32_bf16 v[6:9], v[102:105], v[238:241], v[6:9]
	v_mfma_f32_16x16x32_bf16 v[2:5], v[110:113], v[238:241], v[2:5]
	v_mfma_f32_16x16x32_bf16 v[34:37], v[102:105], v[214:217], v[34:37]
	v_mfma_f32_16x16x32_bf16 v[38:41], v[110:113], v[214:217], v[38:41]
	v_mfma_f32_16x16x32_bf16 v[42:45], v[102:105], v[222:225], v[42:45]
	v_mfma_f32_16x16x32_bf16 v[46:49], v[110:113], v[222:225], v[46:49]
	s_barrier
; #define PG8_STAGE(bufoff, gbase, voff) do { _Pragma("unroll") for (int _i = 0; _i < 2; ++_i) \
;         __builtin_amdgcn_global_load_lds((const unsigned*)((const char*)(gbase) + (voff)[_i]), (LAS unsigned*)(lds + (bufoff) + ldsw + _i * 8192), 16, 0, 0); } while (0)
; #define PG8_LDA(dst, b, h) do { _Pragma("unroll") for (int m = 0; m < 4; ++m) _Pragma("unroll") for (int k = 0; k < 2; ++k) dst[m][k] = *(const LAS bf16x8*)(lds + PG8_SA(b, h) + aoff + m * 2048 + k * 1024); } while (0)
; #define PG8_LDB(dst, b, h) do { _Pragma("unroll") for (int n = 0; n < 2; ++n) _Pragma("unroll") for (int k = 0; k < 2; ++k) dst[n][k] = *(const LAS bf16x8*)(lds + PG8_SB(b, h) + boff + n * 2048 + k * 1024); } while (0)
; #define PG8_MMA(ai, bj, At, Bt) do { __builtin_amdgcn_s_setprio(1); _Pragma("unroll") for (int m = 0; m < 4; ++m) _Pragma("unroll") for (int n = 0; n < 2; ++n) _Pragma("unroll") for (int k = 0; k < 2; ++k) \
;         acc[ai][bj][m][n] = __builtin_amdgcn_mfma_f32_16x16x32_bf16(Bt[n][k], At[m][k], acc[ai][bj][m][n], 0, 0, 0); __builtin_amdgcn_s_setprio(0); } while (0)
; #define PG8_WAIT_V(n) asm volatile("s_waitcnt vmcnt(" #n ")" ::: "memory")
; #define PG8_WAIT_L(n) asm volatile("s_waitcnt lgkmcnt(" #n ")" ::: "memory")
; #define PG8_BAR __builtin_amdgcn_s_barrier()
; #define PG8_SCHED __builtin_amdgcn_sched_barrier(0)
; template <class Epi, class Sched, bool ALIGN_EPI = false, bool SP2 = false>
; __device__ __forceinline__ void gemm_phase(LAS unsigned char* lds, const Gemm g, const Sched& S, const Epi& E) {
;     ...
;             PG8_LDB(B0, 1, 0); PG8_LDB(B1, 1, 1); PG8_SCHED; PG8_LDA(At, 1, 0); PG8_STAGE(PG8_SA(0, 1), a2 + hstep, voffA);
;             PG8_WAIT_V(8); PG8_WAIT_L(0); PG8_BAR; PG8_MMA(0, 0, At, B0); PG8_MMA(0, 1, At, B1); PG8_BAR; PG8_SCHED;
	s_add_i32 s35, 0, 0x18000
	s_add_i32 s46, 0, 0x1c000
	v_add_u32_e32 v70, s35, v185
	v_add_u32_e32 v110, s46, v185
	ds_read_b128 v[50:53], v70
	ds_read_b128 v[54:57], v70 offset:1024
	ds_read_b128 v[66:69], v70 offset:2048
	ds_read_b128 v[70:73], v70 offset:3072
	ds_read_b128 v[98:101], v110
	ds_read_b128 v[102:105], v110 offset:1024
	ds_read_b128 v[106:109], v110 offset:2048
	ds_read_b128 v[110:113], v110 offset:3072
	s_add_u32 s36, s36, 0x80000
	s_addc_u32 s37, s37, 0
	s_mov_b32 m0, s30
	v_lshl_add_u64 v[248:249], s[36:37], 0, v[162:163]
	ds_read_b128 v[210:213], v204 offset:32768
	ds_read_b128 v[214:217], v204 offset:33792
	ds_read_b128 v[218:221], v204 offset:34816
	ds_read_b128 v[222:225], v204 offset:35840
	ds_read_b128 v[226:229], v204 offset:36864
	ds_read_b128 v[230:233], v204 offset:37888
	ds_read_b128 v[234:237], v204 offset:38912
	ds_read_b128 v[238:241], v204 offset:39936
	global_load_lds_dwordx4 v[248:249], off
	v_lshl_add_u64 v[248:249], s[36:37], 0, v[166:167]
	s_mov_b32 m0, s31
	s_nop 0
	global_load_lds_dwordx4 v[248:249], off
	s_waitcnt vmcnt(8)
	s_waitcnt lgkmcnt(0)
	s_barrier
	s_waitcnt lgkmcnt(0)
	v_mfma_f32_16x16x32_bf16 v[158:161], v[50:53], v[210:213], v[158:161]
	v_mfma_f32_16x16x32_bf16 v[154:157], v[66:69], v[210:213], v[154:157]
	v_mfma_f32_16x16x32_bf16 v[142:145], v[50:53], v[218:221], v[142:145]
	v_mfma_f32_16x16x32_bf16 v[138:141], v[66:69], v[218:221], v[138:141]
	v_mfma_f32_16x16x32_bf16 v[126:129], v[50:53], v[226:229], v[126:129]
	v_mfma_f32_16x16x32_bf16 v[122:125], v[66:69], v[226:229], v[122:125]
	v_mfma_f32_16x16x32_bf16 v[94:97], v[50:53], v[234:237], v[94:97]
	v_mfma_f32_16x16x32_bf16 v[90:93], v[66:69], v[234:237], v[90:93]
	v_mfma_f32_16x16x32_bf16 v[158:161], v[54:57], v[214:217], v[158:161]
	v_mfma_f32_16x16x32_bf16 v[154:157], v[70:73], v[214:217], v[154:157]
	v_mfma_f32_16x16x32_bf16 v[142:145], v[54:57], v[222:225], v[142:145]
	v_mfma_f32_16x16x32_bf16 v[138:141], v[70:73], v[222:225], v[138:141]
	v_mfma_f32_16x16x32_bf16 v[126:129], v[54:57], v[230:233], v[126:129]
	v_mfma_f32_16x16x32_bf16 v[122:125], v[70:73], v[230:233], v[122:125]
	v_mfma_f32_16x16x32_bf16 v[94:97], v[54:57], v[238:241], v[94:97]
	v_mfma_f32_16x16x32_bf16 v[90:93], v[70:73], v[238:241], v[90:93]
	v_mfma_f32_16x16x32_bf16 v[150:153], v[98:101], v[210:213], v[150:153]
	v_mfma_f32_16x16x32_bf16 v[146:149], v[106:109], v[210:213], v[146:149]
	v_mfma_f32_16x16x32_bf16 v[134:137], v[98:101], v[218:221], v[134:137]
	v_mfma_f32_16x16x32_bf16 v[130:133], v[106:109], v[218:221], v[130:133]
	v_mfma_f32_16x16x32_bf16 v[118:121], v[98:101], v[226:229], v[118:121]
	v_mfma_f32_16x16x32_bf16 v[114:117], v[106:109], v[226:229], v[114:117]
	v_mfma_f32_16x16x32_bf16 v[86:89], v[98:101], v[234:237], v[86:89]
	v_mfma_f32_16x16x32_bf16 v[82:85], v[106:109], v[234:237], v[82:85]
	v_mfma_f32_16x16x32_bf16 v[150:153], v[102:105], v[214:217], v[150:153]
	v_mfma_f32_16x16x32_bf16 v[146:149], v[110:113], v[214:217], v[146:149]
	v_mfma_f32_16x16x32_bf16 v[134:137], v[102:105], v[222:225], v[134:137]
	v_mfma_f32_16x16x32_bf16 v[130:133], v[110:113], v[222:225], v[130:133]
	v_mfma_f32_16x16x32_bf16 v[118:121], v[102:105], v[230:233], v[118:121]
	v_mfma_f32_16x16x32_bf16 v[114:117], v[110:113], v[230:233], v[114:117]
	v_mfma_f32_16x16x32_bf16 v[86:89], v[102:105], v[238:241], v[86:89]
	v_mfma_f32_16x16x32_bf16 v[82:85], v[110:113], v[238:241], v[82:85]
	s_barrier
; #define PG8_STAGE(bufoff, gbase, voff) do { _Pragma("unroll") for (int _i = 0; _i < 2; ++_i) \
;         __builtin_amdgcn_global_load_lds((const unsigned*)((const char*)(gbase) + (voff)[_i]), (LAS unsigned*)(lds + (bufoff) + ldsw + _i * 8192), 16, 0, 0); } while (0)
; #define PG8_LDA(dst, b, h) do { _Pragma("unroll") for (int m = 0; m < 4; ++m) _Pragma("unroll") for (int k = 0; k < 2; ++k) dst[m][k] = *(const LAS bf16x8*)(lds + PG8_SA(b, h) + aoff + m * 2048 + k * 1024); } while (0)
; #define PG8_MMA(ai, bj, At, Bt) do { __builtin_amdgcn_s_setprio(1); _Pragma("unroll") for (int m = 0; m < 4; ++m) _Pragma("unroll") for (int n = 0; n < 2; ++n) _Pragma("unroll") for (int k = 0; k < 2; ++k) \
;         acc[ai][bj][m][n] = __builtin_amdgcn_mfma_f32_16x16x32_bf16(Bt[n][k], At[m][k], acc[ai][bj][m][n], 0, 0, 0); __builtin_amdgcn_s_setprio(0); } while (0)
; #define PG8_WAIT_V(n) asm volatile("s_waitcnt vmcnt(" #n ")" ::: "memory")
; #define PG8_WAIT_L(n) asm volatile("s_waitcnt lgkmcnt(" #n ")" ::: "memory")
; #define PG8_BAR __builtin_amdgcn_s_barrier()
; #define PG8_SCHED __builtin_amdgcn_sched_barrier(0)
; template <class Epi, class Sched, bool ALIGN_EPI = false, bool SP2 = false>
; __device__ __forceinline__ void gemm_phase(LAS unsigned char* lds, const Gemm g, const Sched& S, const Epi& E) {
;     ...
;         for (int t = 0; t < nt; t += 2) {
;     ...
;             PG8_LDA(At, 1, 1); PG8_STAGE(PG8_SB(1, 0), b3, voffB); PG8_STAGE(PG8_SB(1, 1), b3 + hstepB, voffB); PG8_STAGE(PG8_SA(1, 0), a3, voffA);
;             PG8_WAIT_V(8); PG8_WAIT_L(0); PG8_BAR; PG8_MMA(1, 0, At, B0); PG8_MMA(1, 1, At, B1); PG8_BAR; PG8_SCHED;
	s_add_i32 s35, s35, s27
	v_lshl_add_u64 v[182:183], v[182:183], 0, s[4:5]
	s_mov_b32 m0, s35
	ds_read_b128 v[210:213], v204 offset:49152
	ds_read_b128 v[214:217], v204 offset:50176
	ds_read_b128 v[218:221], v204 offset:51200
	ds_read_b128 v[222:225], v204 offset:52224
	ds_read_b128 v[226:229], v204 offset:53248
	ds_read_b128 v[230:233], v204 offset:54272
	ds_read_b128 v[234:237], v204 offset:55296
	ds_read_b128 v[238:241], v204 offset:56320
	global_load_lds_dwordx4 v[182:183], off
	s_add_i32 m0, s35, 0x2000
	s_add_u32 s22, s22, 0x20080
	v_lshl_add_u64 v[182:183], v[242:243], 0, s[4:5]
	s_addc_u32 s23, s23, 0
	s_add_i32 s35, s46, s27
	global_load_lds_dwordx4 v[182:183], off
	v_lshl_add_u64 v[182:183], s[22:23], 0, v[164:165]
	s_mov_b32 m0, s35
	s_nop 0
	global_load_lds_dwordx4 v[182:183], off
	v_lshl_add_u64 v[182:183], s[22:23], 0, v[168:169]
	s_add_i32 m0, s35, 0x2000
	s_nop 0
	global_load_lds_dwordx4 v[182:183], off
	v_lshl_add_u64 v[182:183], v[244:245], 0, s[4:5]
	s_mov_b32 m0, s53
	s_nop 0
	global_load_lds_dwordx4 v[182:183], off
	v_lshl_add_u64 v[182:183], v[246:247], 0, s[4:5]
	s_mov_b32 m0, s54
	s_nop 0
	global_load_lds_dwordx4 v[182:183], off
	s_waitcnt vmcnt(8)
	s_waitcnt lgkmcnt(0)
	s_barrier
	s_waitcnt lgkmcnt(0)
	v_mfma_f32_16x16x32_bf16 v[78:81], v[50:53], v[210:213], v[78:81]
	v_mfma_f32_16x16x32_bf16 v[74:77], v[66:69], v[210:213], v[74:77]
	v_mfma_f32_16x16x32_bf16 v[62:65], v[50:53], v[218:221], v[62:65]
	v_mfma_f32_16x16x32_bf16 v[58:61], v[66:69], v[218:221], v[58:61]
	v_mfma_f32_16x16x32_bf16 v[30:33], v[50:53], v[226:229], v[30:33]
	v_mfma_f32_16x16x32_bf16 v[26:29], v[66:69], v[226:229], v[26:29]
	v_mfma_f32_16x16x32_bf16 v[14:17], v[50:53], v[234:237], v[14:17]
	v_mfma_f32_16x16x32_bf16 v[10:13], v[66:69], v[234:237], v[10:13]
	v_mfma_f32_16x16x32_bf16 v[78:81], v[54:57], v[214:217], v[78:81]
	v_mfma_f32_16x16x32_bf16 v[74:77], v[70:73], v[214:217], v[74:77]
	v_mfma_f32_16x16x32_bf16 v[62:65], v[54:57], v[222:225], v[62:65]
	v_mfma_f32_16x16x32_bf16 v[58:61], v[70:73], v[222:225], v[58:61]
	v_mfma_f32_16x16x32_bf16 v[30:33], v[54:57], v[230:233], v[30:33]
	v_mfma_f32_16x16x32_bf16 v[26:29], v[70:73], v[230:233], v[26:29]
	v_mfma_f32_16x16x32_bf16 v[14:17], v[54:57], v[238:241], v[14:17]
	v_mfma_f32_16x16x32_bf16 v[10:13], v[70:73], v[238:241], v[10:13]
	v_mfma_f32_16x16x32_bf16 v[34:37], v[98:101], v[210:213], v[34:37]
	v_mfma_f32_16x16x32_bf16 v[70:73], v[102:105], v[214:217], v[34:37]
	v_mfma_f32_16x16x32_bf16 v[34:37], v[106:109], v[210:213], v[38:41]
	v_mfma_f32_16x16x32_bf16 v[66:69], v[110:113], v[214:217], v[34:37]
	v_mfma_f32_16x16x32_bf16 v[34:37], v[98:101], v[218:221], v[42:45]
	v_mfma_f32_16x16x32_bf16 v[54:57], v[102:105], v[222:225], v[34:37]
	v_mfma_f32_16x16x32_bf16 v[34:37], v[106:109], v[218:221], v[46:49]
	v_mfma_f32_16x16x32_bf16 v[22:25], v[98:101], v[226:229], v[22:25]
	v_mfma_f32_16x16x32_bf16 v[18:21], v[106:109], v[226:229], v[18:21]
	v_mfma_f32_16x16x32_bf16 v[6:9], v[98:101], v[234:237], v[6:9]
	v_mfma_f32_16x16x32_bf16 v[2:5], v[106:109], v[234:237], v[2:5]
	v_mfma_f32_16x16x32_bf16 v[50:53], v[110:113], v[222:225], v[34:37]
	v_mfma_f32_16x16x32_bf16 v[22:25], v[102:105], v[230:233], v[22:25]
	v_mfma_f32_16x16x32_bf16 v[18:21], v[110:113], v[230:233], v[18:21]
	v_mfma_f32_16x16x32_bf16 v[6:9], v[102:105], v[238:241], v[6:9]
	v_mfma_f32_16x16x32_bf16 v[2:5], v[110:113], v[238:241], v[2:5]
	s_barrier
	s_add_i32 s34, s34, 2
	s_add_u32 s24, s24, 0x100
	s_addc_u32 s25, s25, 0
	s_add_u32 s20, s20, 0x100
	s_addc_u32 s21, s21, 0
	s_cmp_lt_u32 s34, 30
	s_cbranch_scc1 .LBB0_2143
	s_andn2_b64 vcc, exec, s[8:9]
	s_cbranch_vccnz .LBB0_2146
	s_barrier

;     __device__ bool next(int i, Unit& u) const { if (i != 0 || c >= 128) return false; const int t = c >> 2; u.pm = t & 3; u.pn = t >> 2; u.koff = koff_bytes; u.q = c & 3; return true; }
; #define PG8_STAGE(bufoff, gbase, voff) do { _Pragma("unroll") for (int _i = 0; _i < 2; ++_i) \
;         __builtin_amdgcn_global_load_lds((const unsigned*)((const char*)(gbase) + (voff)[_i]), (LAS unsigned*)(lds + (bufoff) + ldsw + _i * 8192), 16, 0, 0); } while (0)
; #define PG8_LDA(dst, b, h) do { _Pragma("unroll") for (int m = 0; m < 4; ++m) _Pragma("unroll") for (int k = 0; k < 2; ++k) dst[m][k] = *(const LAS bf16x8*)(lds + PG8_SA(b, h) + aoff + m * 2048 + k * 1024); } while (0)
; #define PG8_LDB(dst, b, h) do { _Pragma("unroll") for (int n = 0; n < 2; ++n) _Pragma("unroll") for (int k = 0; k < 2; ++k) dst[n][k] = *(const LAS bf16x8*)(lds + PG8_SB(b, h) + boff + n * 2048 + k * 1024); } while (0)
; #define PG8_WAIT_V(n) asm volatile("s_waitcnt vmcnt(" #n ")" ::: "memory")
; template <class Epi, class Sched, bool ALIGN_EPI = false, bool SP2 = false>
; __device__ __forceinline__ void gemm_phase(LAS unsigned char* lds, const Gemm g, const Sched& S, const Epi& E) {
;     ...
;         const bool has_next = S.next(ui + 1, nxt);
;         const char* nA = has_next ? (const char*)g.A + (size_t)nxt.pm * tstep + nxt.koff : cA; const char* nB = has_next ? (const char*)g.Bt + (size_t)nxt.pn * tstep + nxt.koff : cB;
;         for (int t = 0; t < nt; t += 2) {
;             const bool last = (t == nt - 2);
;             const char* a1 = cA + (size_t)(t + 1) * kstep;
;             const char* a2 = last ? nA : cA + (size_t)(t + 2) * kstep; const char* b2 = last ? nB : cB + (size_t)(t + 2) * kstep;
;             const char* a3 = a2 + kstep; const char* b3 = b2 + kstep;
;             if (last && has_next) S.a_ready(nxt);
;             if constexpr (SP2) {
;             PG8_LDB(B0, 0, 0); PG8_LDB(B1, 0, 1); PG8_SCHED; PG8_LDA(At, 0, 0); PG8_STAGE(PG8_SA(1, 1), a1 + hstep, voffA);
;             PG8_WAIT_V(8); PG8_WAIT_L(0); PG8_BAR; PG8_MMA(0, 0, At, B0); PG8_MMA(0, 1, At, B1); PG8_BAR; PG8_SCHED;
;             PG8_LDA(At, 0, 1); PG8_STAGE(PG8_SB(0, 0), b2, voffB); PG8_STAGE(PG8_SB(0, 1), b2 + hstepB, voffB); PG8_STAGE(PG8_SA(0, 0), a2, voffA);
;             PG8_WAIT_V(8); PG8_WAIT_L(0); PG8_BAR; PG8_MMA(1, 0, At, B0); PG8_MMA(1, 1, At, B1); PG8_BAR; PG8_SCHED;
.LBB0_2765:
	s_ashr_i32 s15, s14, 31
	v_cmp_lt_i64_e64 s[42:43], s[16:17], v[170:171]
	s_lshl_b64 s[16:17], s[14:15], 20
	v_readlane_b32 s3, v252, 25
	s_add_u32 s16, s3, s16
	v_readlane_b32 s3, v252, 26
	s_addc_u32 s17, s3, s17
	s_and_b64 s[18:19], s[42:43], exec
	s_cselect_b32 s3, s17, s35
	s_cselect_b32 s15, s16, s34
	s_ashr_i32 s13, s12, 31
	s_lshl_b64 s[18:19], s[12:13], 20
	v_readlane_b32 s4, v254, 56
	v_readlane_b32 s5, v254, 57
	s_add_u32 s18, s4, s18
	s_addc_u32 s19, s5, s19
	s_and_b64 s[24:25], s[42:43], exec
	s_cselect_b32 s13, s19, s23
	s_cselect_b32 s21, s18, s22
	s_add_u32 s53, s22, 0x100
	s_addc_u32 s54, s23, 0
	s_add_u32 s22, s34, 0x80080
	s_mov_b64 s[70:71], s[58:59]
	s_addc_u32 s23, s35, 0
	s_mov_b32 s55, -2
	s_waitcnt vmcnt(0)
	ds_read_b128 v[50:53], v196
	ds_read_b128 v[54:57], v196 offset:1024
	ds_read_b128 v[138:141], v196 offset:2048
	ds_read_b128 v[142:145], v196 offset:3072
	ds_read_b128 v[146:149], v197
	ds_read_b128 v[150:153], v197 offset:1024
	ds_read_b128 v[174:177], v197 offset:2048
	ds_read_b128 v[178:181], v197 offset:3072
	s_add_u32 s24, s22, 0xfff80080
	s_addc_u32 s25, s23, -1
	s_cmp_eq_u32 s55, 28
	s_cselect_b32 s35, s3, s25
	s_cselect_b32 s34, s15, s24
	s_cselect_b32 s25, s13, s54
	s_cselect_b32 s24, s21, s53
	v_lshl_add_u64 v[190:191], s[22:23], 0, v[168:169]
	s_add_i32 m0, s28, 0xc000
	ds_read_b128 v[182:185], v198
	ds_read_b128 v[186:189], v198 offset:1024
	ds_read_b128 v[202:205], v198 offset:2048
	ds_read_b128 v[206:209], v198 offset:3072
	ds_read_b128 v[210:213], v198 offset:4096
	ds_read_b128 v[214:217], v198 offset:5120
	ds_read_b128 v[218:221], v198 offset:6144
	ds_read_b128 v[222:225], v198 offset:7168
	global_load_lds_dwordx4 v[190:191], off
	v_lshl_add_u64 v[190:191], s[22:23], 0, v[166:167]
	s_add_i32 m0, s28, 0xe000
	s_nop 0
	global_load_lds_dwordx4 v[190:191], off
	s_waitcnt lgkmcnt(0)
	s_barrier
	s_waitcnt lgkmcnt(0)
	v_mfma_f32_16x16x32_bf16 v[134:137], v[50:53], v[182:185], 0
	v_mfma_f32_16x16x32_bf16 v[130:133], v[138:141], v[182:185], 0
	v_mfma_f32_16x16x32_bf16 v[118:121], v[50:53], v[202:205], 0
	v_mfma_f32_16x16x32_bf16 v[114:117], v[138:141], v[202:205], 0
	v_mfma_f32_16x16x32_bf16 v[102:105], v[50:53], v[210:213], 0
	v_mfma_f32_16x16x32_bf16 v[98:101], v[138:141], v[210:213], 0
	v_mfma_f32_16x16x32_bf16 v[86:89], v[50:53], v[218:221], 0
	v_mfma_f32_16x16x32_bf16 v[82:85], v[138:141], v[218:221], 0
	v_mfma_f32_16x16x32_bf16 v[134:137], v[54:57], v[186:189], v[134:137]
	v_mfma_f32_16x16x32_bf16 v[130:133], v[142:145], v[186:189], v[130:133]
	v_mfma_f32_16x16x32_bf16 v[118:121], v[54:57], v[206:209], v[118:121]
	v_mfma_f32_16x16x32_bf16 v[114:117], v[142:145], v[206:209], v[114:117]
	v_mfma_f32_16x16x32_bf16 v[102:105], v[54:57], v[214:217], v[102:105]
	v_mfma_f32_16x16x32_bf16 v[98:101], v[142:145], v[214:217], v[98:101]
	v_mfma_f32_16x16x32_bf16 v[86:89], v[54:57], v[222:225], v[86:89]
	v_mfma_f32_16x16x32_bf16 v[82:85], v[142:145], v[222:225], v[82:85]
	v_mfma_f32_16x16x32_bf16 v[126:129], v[146:149], v[182:185], 0
	v_mfma_f32_16x16x32_bf16 v[122:125], v[174:177], v[182:185], 0
	v_mfma_f32_16x16x32_bf16 v[110:113], v[146:149], v[202:205], 0
	v_mfma_f32_16x16x32_bf16 v[106:109], v[174:177], v[202:205], 0
	v_mfma_f32_16x16x32_bf16 v[94:97], v[146:149], v[210:213], 0
	v_mfma_f32_16x16x32_bf16 v[90:93], v[174:177], v[210:213], 0
	v_mfma_f32_16x16x32_bf16 v[78:81], v[146:149], v[218:221], 0
	v_mfma_f32_16x16x32_bf16 v[74:77], v[174:177], v[218:221], 0
	v_mfma_f32_16x16x32_bf16 v[126:129], v[150:153], v[186:189], v[126:129]
	v_mfma_f32_16x16x32_bf16 v[122:125], v[178:181], v[186:189], v[122:125]
	v_mfma_f32_16x16x32_bf16 v[110:113], v[150:153], v[206:209], v[110:113]
	v_mfma_f32_16x16x32_bf16 v[106:109], v[178:181], v[206:209], v[106:109]
	v_mfma_f32_16x16x32_bf16 v[94:97], v[150:153], v[214:217], v[94:97]
	v_mfma_f32_16x16x32_bf16 v[90:93], v[178:181], v[214:217], v[90:93]
	v_mfma_f32_16x16x32_bf16 v[78:81], v[150:153], v[222:225], v[78:81]
	v_mfma_f32_16x16x32_bf16 v[74:77], v[178:181], v[222:225], v[74:77]
	s_barrier
	s_add_i32 s56, s51, s27
	v_lshl_add_u64 v[190:191], s[24:25], 0, v[156:157]
	s_mov_b32 m0, s56
	ds_read_b128 v[182:185], v198 offset:16384
	ds_read_b128 v[186:189], v198 offset:17408
	ds_read_b128 v[202:205], v198 offset:18432
	ds_read_b128 v[206:209], v198 offset:19456
	ds_read_b128 v[210:213], v198 offset:20480
	ds_read_b128 v[214:217], v198 offset:21504
	ds_read_b128 v[218:221], v198 offset:22528
	ds_read_b128 v[222:225], v198 offset:23552
	global_load_lds_dwordx4 v[190:191], off
	s_add_i32 m0, s56, 0x2000
	s_add_u32 s56, s24, 0x20000
	v_lshl_add_u64 v[226:227], s[24:25], 0, v[160:161]
	s_addc_u32 s57, s25, 0
	s_add_i32 s58, s52, s27
	global_load_lds_dwordx4 v[226:227], off
	v_lshl_add_u64 v[228:229], s[56:57], 0, v[156:157]
	s_mov_b32 m0, s58
	v_lshl_add_u64 v[230:231], s[34:35], 0, v[158:159]
	global_load_lds_dwordx4 v[228:229], off
	v_lshl_add_u64 v[228:229], s[56:57], 0, v[160:161]
	s_add_i32 m0, s58, 0x2000
	s_nop 0
	global_load_lds_dwordx4 v[228:229], off
	v_lshl_add_u64 v[228:229], s[34:35], 0, v[154:155]
	s_mov_b32 m0, s28
	s_nop 0
	global_load_lds_dwordx4 v[228:229], off
	s_mov_b32 m0, s29
	s_nop 0
	global_load_lds_dwordx4 v[230:231], off
	s_waitcnt lgkmcnt(0)
	s_barrier
; #define PG8_STAGE(bufoff, gbase, voff) do { _Pragma("unroll") for (int _i = 0; _i < 2; ++_i) \
;         __builtin_amdgcn_global_load_lds((const unsigned*)((const char*)(gbase) + (voff)[_i]), (LAS unsigned*)(lds + (bufoff) + ldsw + _i * 8192), 16, 0, 0); } while (0)
; #define PG8_LDA(dst, b, h) do { _Pragma("unroll") for (int m = 0; m < 4; ++m) _Pragma("unroll") for (int k = 0; k < 2; ++k) dst[m][k] = *(const LAS bf16x8*)(lds + PG8_SA(b, h) + aoff + m * 2048 + k * 1024); } while (0)
; #define PG8_LDB(dst, b, h) do { _Pragma("unroll") for (int n = 0; n < 2; ++n) _Pragma("unroll") for (int k = 0; k < 2; ++k) dst[n][k] = *(const LAS bf16x8*)(lds + PG8_SB(b, h) + boff + n * 2048 + k * 1024); } while (0)
; #define PG8_MMA(ai, bj, At, Bt) do { __builtin_amdgcn_s_setprio(1); _Pragma("unroll") for (int m = 0; m < 4; ++m) _Pragma("unroll") for (int n = 0; n < 2; ++n) _Pragma("unroll") for (int k = 0; k < 2; ++k) \
;         acc[ai][bj][m][n] = __builtin_amdgcn_mfma_f32_16x16x32_bf16(Bt[n][k], At[m][k], acc[ai][bj][m][n], 0, 0, 0); __builtin_amdgcn_s_setprio(0); } while (0)
; #define PG8_WAIT_V(n) asm volatile("s_waitcnt vmcnt(" #n ")" ::: "memory")
; #define PG8_WAIT_L(n) asm volatile("s_waitcnt lgkmcnt(" #n ")" ::: "memory")
; #define PG8_BAR __builtin_amdgcn_s_barrier()
; #define PG8_SCHED __builtin_amdgcn_sched_barrier(0)
; template <class Epi, class Sched, bool ALIGN_EPI = false, bool SP2 = false>
; __device__ __forceinline__ void gemm_phase(LAS unsigned char* lds, const Gemm g, const Sched& S, const Epi& E) {
;     ...
;             PG8_WAIT_V(8); PG8_WAIT_L(0); PG8_BAR; PG8_MMA(1, 0, At, B0); PG8_MMA(1, 1, At, B1); PG8_BAR; PG8_SCHED;
;             PG8_LDB(B0, 1, 0); PG8_LDB(B1, 1, 1); PG8_SCHED; PG8_LDA(At, 1, 0); PG8_STAGE(PG8_SA(0, 1), a2 + hstep, voffA);
;             PG8_WAIT_V(8); PG8_WAIT_L(0); PG8_BAR; PG8_MMA(0, 0, At, B0); PG8_MMA(0, 1, At, B1); PG8_BAR; PG8_SCHED;
	s_waitcnt lgkmcnt(0)
	v_mfma_f32_16x16x32_bf16 v[70:73], v[50:53], v[182:185], 0
	v_mfma_f32_16x16x32_bf16 v[66:69], v[138:141], v[182:185], 0
	v_mfma_f32_16x16x32_bf16 v[46:49], v[50:53], v[202:205], 0
	v_mfma_f32_16x16x32_bf16 v[42:45], v[138:141], v[202:205], 0
	v_mfma_f32_16x16x32_bf16 v[30:33], v[50:53], v[210:213], 0
	v_mfma_f32_16x16x32_bf16 v[26:29], v[138:141], v[210:213], 0
	v_mfma_f32_16x16x32_bf16 v[14:17], v[50:53], v[218:221], 0
	v_mfma_f32_16x16x32_bf16 v[10:13], v[138:141], v[218:221], 0
	v_mfma_f32_16x16x32_bf16 v[70:73], v[54:57], v[186:189], v[70:73]
	v_mfma_f32_16x16x32_bf16 v[66:69], v[142:145], v[186:189], v[66:69]
	v_mfma_f32_16x16x32_bf16 v[46:49], v[54:57], v[206:209], v[46:49]
	v_mfma_f32_16x16x32_bf16 v[42:45], v[142:145], v[206:209], v[42:45]
	v_mfma_f32_16x16x32_bf16 v[30:33], v[54:57], v[214:217], v[30:33]
	v_mfma_f32_16x16x32_bf16 v[26:29], v[142:145], v[214:217], v[26:29]
	v_mfma_f32_16x16x32_bf16 v[14:17], v[54:57], v[222:225], v[14:17]
	v_mfma_f32_16x16x32_bf16 v[10:13], v[142:145], v[222:225], v[10:13]
	v_mfma_f32_16x16x32_bf16 v[38:41], v[146:149], v[202:205], 0
	v_mfma_f32_16x16x32_bf16 v[34:37], v[174:177], v[202:205], 0
	v_mfma_f32_16x16x32_bf16 v[22:25], v[146:149], v[210:213], 0
	v_mfma_f32_16x16x32_bf16 v[18:21], v[174:177], v[210:213], 0
	v_mfma_f32_16x16x32_bf16 v[6:9], v[146:149], v[218:221], 0
	v_mfma_f32_16x16x32_bf16 v[2:5], v[174:177], v[218:221], 0
	v_mfma_f32_16x16x32_bf16 v[50:53], v[146:149], v[182:185], 0
	v_mfma_f32_16x16x32_bf16 v[54:57], v[174:177], v[182:185], 0
	v_mfma_f32_16x16x32_bf16 v[38:41], v[150:153], v[206:209], v[38:41]
	v_mfma_f32_16x16x32_bf16 v[34:37], v[178:181], v[206:209], v[34:37]
	v_mfma_f32_16x16x32_bf16 v[22:25], v[150:153], v[214:217], v[22:25]
	v_mfma_f32_16x16x32_bf16 v[18:21], v[178:181], v[214:217], v[18:21]
	v_mfma_f32_16x16x32_bf16 v[6:9], v[150:153], v[222:225], v[6:9]
	v_mfma_f32_16x16x32_bf16 v[2:5], v[178:181], v[222:225], v[2:5]
	v_mfma_f32_16x16x32_bf16 v[50:53], v[150:153], v[186:189], v[50:53]
	v_mfma_f32_16x16x32_bf16 v[54:57], v[178:181], v[186:189], v[54:57]
	s_barrier
	s_add_i32 s56, 0, 0x18000
	s_add_i32 s57, 0, 0x1c000
	v_add_u32_e32 v142, s56, v1
	v_add_u32_e32 v162, s57, v1
	ds_read_b128 v[58:61], v142
	ds_read_b128 v[62:65], v142 offset:1024
	ds_read_b128 v[138:141], v142 offset:2048
	ds_read_b128 v[142:145], v142 offset:3072
	ds_read_b128 v[146:149], v162
	ds_read_b128 v[150:153], v162 offset:1024
	ds_read_b128 v[174:177], v162 offset:2048
	ds_read_b128 v[178:181], v162 offset:3072
	s_add_u32 s34, s34, 0x80000
	s_addc_u32 s35, s35, 0
	s_mov_b32 m0, s30
	v_lshl_add_u64 v[232:233], s[34:35], 0, v[154:155]
	ds_read_b128 v[182:185], v198 offset:32768
	ds_read_b128 v[186:189], v198 offset:33792
	ds_read_b128 v[202:205], v198 offset:34816
	ds_read_b128 v[206:209], v198 offset:35840
	ds_read_b128 v[210:213], v198 offset:36864
	ds_read_b128 v[214:217], v198 offset:37888
	ds_read_b128 v[218:221], v198 offset:38912
	ds_read_b128 v[222:225], v198 offset:39936
	global_load_lds_dwordx4 v[232:233], off
	v_lshl_add_u64 v[232:233], s[34:35], 0, v[158:159]
	s_mov_b32 m0, s31
	s_nop 0
	global_load_lds_dwordx4 v[232:233], off
	s_waitcnt vmcnt(8)
	s_waitcnt lgkmcnt(0)
	s_barrier
	s_waitcnt lgkmcnt(0)
	v_mfma_f32_16x16x32_bf16 v[134:137], v[58:61], v[182:185], v[134:137]
	v_mfma_f32_16x16x32_bf16 v[130:133], v[138:141], v[182:185], v[130:133]
	v_mfma_f32_16x16x32_bf16 v[118:121], v[58:61], v[202:205], v[118:121]
	v_mfma_f32_16x16x32_bf16 v[114:117], v[138:141], v[202:205], v[114:117]
	v_mfma_f32_16x16x32_bf16 v[102:105], v[58:61], v[210:213], v[102:105]
	v_mfma_f32_16x16x32_bf16 v[98:101], v[138:141], v[210:213], v[98:101]
	v_mfma_f32_16x16x32_bf16 v[86:89], v[58:61], v[218:221], v[86:89]
	v_mfma_f32_16x16x32_bf16 v[82:85], v[138:141], v[218:221], v[82:85]
	v_mfma_f32_16x16x32_bf16 v[134:137], v[62:65], v[186:189], v[134:137]
	v_mfma_f32_16x16x32_bf16 v[130:133], v[142:145], v[186:189], v[130:133]
	v_mfma_f32_16x16x32_bf16 v[118:121], v[62:65], v[206:209], v[118:121]
	v_mfma_f32_16x16x32_bf16 v[114:117], v[142:145], v[206:209], v[114:117]
	v_mfma_f32_16x16x32_bf16 v[102:105], v[62:65], v[214:217], v[102:105]
	v_mfma_f32_16x16x32_bf16 v[98:101], v[142:145], v[214:217], v[98:101]
	v_mfma_f32_16x16x32_bf16 v[86:89], v[62:65], v[222:225], v[86:89]
	v_mfma_f32_16x16x32_bf16 v[82:85], v[142:145], v[222:225], v[82:85]
	v_mfma_f32_16x16x32_bf16 v[126:129], v[146:149], v[182:185], v[126:129]
	v_mfma_f32_16x16x32_bf16 v[122:125], v[174:177], v[182:185], v[122:125]
	v_mfma_f32_16x16x32_bf16 v[110:113], v[146:149], v[202:205], v[110:113]
	v_mfma_f32_16x16x32_bf16 v[106:109], v[174:177], v[202:205], v[106:109]
	v_mfma_f32_16x16x32_bf16 v[94:97], v[146:149], v[210:213], v[94:97]
	v_mfma_f32_16x16x32_bf16 v[90:93], v[174:177], v[210:213], v[90:93]
	v_mfma_f32_16x16x32_bf16 v[78:81], v[146:149], v[218:221], v[78:81]
	v_mfma_f32_16x16x32_bf16 v[74:77], v[174:177], v[218:221], v[74:77]
	v_mfma_f32_16x16x32_bf16 v[126:129], v[150:153], v[186:189], v[126:129]
	v_mfma_f32_16x16x32_bf16 v[122:125], v[178:181], v[186:189], v[122:125]
	v_mfma_f32_16x16x32_bf16 v[110:113], v[150:153], v[206:209], v[110:113]
	v_mfma_f32_16x16x32_bf16 v[106:109], v[178:181], v[206:209], v[106:109]
	v_mfma_f32_16x16x32_bf16 v[94:97], v[150:153], v[214:217], v[94:97]
	v_mfma_f32_16x16x32_bf16 v[90:93], v[178:181], v[214:217], v[90:93]
	v_mfma_f32_16x16x32_bf16 v[78:81], v[150:153], v[222:225], v[78:81]
	v_mfma_f32_16x16x32_bf16 v[74:77], v[178:181], v[222:225], v[74:77]
	s_barrier
; #define PG8_STAGE(bufoff, gbase, voff) do { _Pragma("unroll") for (int _i = 0; _i < 2; ++_i) \
;         __builtin_amdgcn_global_load_lds((const unsigned*)((const char*)(gbase) + (voff)[_i]), (LAS unsigned*)(lds + (bufoff) + ldsw + _i * 8192), 16, 0, 0); } while (0)
; #define PG8_LDA(dst, b, h) do { _Pragma("unroll") for (int m = 0; m < 4; ++m) _Pragma("unroll") for (int k = 0; k < 2; ++k) dst[m][k] = *(const LAS bf16x8*)(lds + PG8_SA(b, h) + aoff + m * 2048 + k * 1024); } while (0)
; #define PG8_LDB(dst, b, h) do { _Pragma("unroll") for (int n = 0; n < 2; ++n) _Pragma("unroll") for (int k = 0; k < 2; ++k) dst[n][k] = *(const LAS bf16x8*)(lds + PG8_SB(b, h) + boff + n * 2048 + k * 1024); } while (0)
; #define PG8_MMA(ai, bj, At, Bt) do { __builtin_amdgcn_s_setprio(1); _Pragma("unroll") for (int m = 0; m < 4; ++m) _Pragma("unroll") for (int n = 0; n < 2; ++n) _Pragma("unroll") for (int k = 0; k < 2; ++k) \
;         acc[ai][bj][m][n] = __builtin_amdgcn_mfma_f32_16x16x32_bf16(Bt[n][k], At[m][k], acc[ai][bj][m][n], 0, 0, 0); __builtin_amdgcn_s_setprio(0); } while (0)
; #define PG8_WAIT_V(n) asm volatile("s_waitcnt vmcnt(" #n ")" ::: "memory")
; #define PG8_WAIT_L(n) asm volatile("s_waitcnt lgkmcnt(" #n ")" ::: "memory")
; #define PG8_BAR __builtin_amdgcn_s_barrier()
; #define PG8_SCHED __builtin_amdgcn_sched_barrier(0)
; template <class Epi, class Sched, bool ALIGN_EPI = false, bool SP2 = false>
; __device__ __forceinline__ void gemm_phase(LAS unsigned char* lds, const Gemm g, const Sched& S, const Epi& E) {
;     ...
;             PG8_LDB(B0, 0, 0); PG8_LDB(B1, 0, 1); PG8_SCHED; PG8_LDA(At, 0, 0); PG8_STAGE(PG8_SA(1, 1), a1 + hstep, voffA);
;             PG8_WAIT_V(8); PG8_WAIT_L(0); PG8_BAR; PG8_MMA(0, 0, At, B0); PG8_MMA(0, 1, At, B1); PG8_BAR; PG8_SCHED;
;     ...
;             PG8_LDA(At, 1, 1); PG8_STAGE(PG8_SB(1, 0), b3, voffB); PG8_STAGE(PG8_SB(1, 1), b3 + hstepB, voffB); PG8_STAGE(PG8_SA(1, 0), a3, voffA);
;             PG8_WAIT_V(8); PG8_WAIT_L(0); PG8_BAR; PG8_MMA(1, 0, At, B0); PG8_MMA(1, 1, At, B1); PG8_BAR; PG8_SCHED;
	s_add_i32 s34, s56, s27
	v_lshl_add_u64 v[190:191], v[190:191], 0, s[8:9]
	s_mov_b32 m0, s34
	ds_read_b128 v[182:185], v198 offset:49152
	ds_read_b128 v[186:189], v198 offset:50176
	ds_read_b128 v[202:205], v198 offset:51200
	ds_read_b128 v[206:209], v198 offset:52224
	ds_read_b128 v[210:213], v198 offset:53248
	ds_read_b128 v[214:217], v198 offset:54272
	ds_read_b128 v[218:221], v198 offset:55296
	ds_read_b128 v[222:225], v198 offset:56320
	global_load_lds_dwordx4 v[190:191], off
	s_add_i32 m0, s34, 0x2000
	s_add_u32 s24, s24, 0x20080
	v_lshl_add_u64 v[190:191], v[226:227], 0, s[8:9]
	s_addc_u32 s25, s25, 0
	s_add_i32 s34, s57, s27
	global_load_lds_dwordx4 v[190:191], off
	v_lshl_add_u64 v[190:191], s[24:25], 0, v[156:157]
	s_mov_b32 m0, s34
	s_nop 0
	global_load_lds_dwordx4 v[190:191], off
	v_lshl_add_u64 v[190:191], s[24:25], 0, v[160:161]
	s_add_i32 m0, s34, 0x2000
	s_nop 0
	global_load_lds_dwordx4 v[190:191], off
	v_lshl_add_u64 v[190:191], v[228:229], 0, s[8:9]
	s_mov_b32 m0, s48
	s_nop 0
	global_load_lds_dwordx4 v[190:191], off
	v_lshl_add_u64 v[190:191], v[230:231], 0, s[8:9]
	s_mov_b32 m0, s49
	s_nop 0
	global_load_lds_dwordx4 v[190:191], off
	s_waitcnt vmcnt(8)
	s_waitcnt lgkmcnt(0)
	s_barrier
	s_waitcnt lgkmcnt(0)
	v_mfma_f32_16x16x32_bf16 v[70:73], v[58:61], v[182:185], v[70:73]
	v_mfma_f32_16x16x32_bf16 v[66:69], v[138:141], v[182:185], v[66:69]
	v_mfma_f32_16x16x32_bf16 v[46:49], v[58:61], v[202:205], v[46:49]
	v_mfma_f32_16x16x32_bf16 v[42:45], v[138:141], v[202:205], v[42:45]
	v_mfma_f32_16x16x32_bf16 v[30:33], v[58:61], v[210:213], v[30:33]
	v_mfma_f32_16x16x32_bf16 v[26:29], v[138:141], v[210:213], v[26:29]
	v_mfma_f32_16x16x32_bf16 v[14:17], v[58:61], v[218:221], v[14:17]
	v_mfma_f32_16x16x32_bf16 v[10:13], v[138:141], v[218:221], v[10:13]
	v_mfma_f32_16x16x32_bf16 v[70:73], v[62:65], v[186:189], v[70:73]
	v_mfma_f32_16x16x32_bf16 v[66:69], v[142:145], v[186:189], v[66:69]
	v_mfma_f32_16x16x32_bf16 v[46:49], v[62:65], v[206:209], v[46:49]
	v_mfma_f32_16x16x32_bf16 v[42:45], v[142:145], v[206:209], v[42:45]
	v_mfma_f32_16x16x32_bf16 v[30:33], v[62:65], v[214:217], v[30:33]
	v_mfma_f32_16x16x32_bf16 v[26:29], v[142:145], v[214:217], v[26:29]
	v_mfma_f32_16x16x32_bf16 v[14:17], v[62:65], v[222:225], v[14:17]
	v_mfma_f32_16x16x32_bf16 v[10:13], v[142:145], v[222:225], v[10:13]
	v_mfma_f32_16x16x32_bf16 v[50:53], v[146:149], v[182:185], v[50:53]
	v_mfma_f32_16x16x32_bf16 v[62:65], v[150:153], v[186:189], v[50:53]
	v_mfma_f32_16x16x32_bf16 v[50:53], v[174:177], v[182:185], v[54:57]
	v_mfma_f32_16x16x32_bf16 v[38:41], v[146:149], v[202:205], v[38:41]
	v_mfma_f32_16x16x32_bf16 v[34:37], v[174:177], v[202:205], v[34:37]
	v_mfma_f32_16x16x32_bf16 v[22:25], v[146:149], v[210:213], v[22:25]
	v_mfma_f32_16x16x32_bf16 v[18:21], v[174:177], v[210:213], v[18:21]
	v_mfma_f32_16x16x32_bf16 v[6:9], v[146:149], v[218:221], v[6:9]
	v_mfma_f32_16x16x32_bf16 v[2:5], v[174:177], v[218:221], v[2:5]
	v_mfma_f32_16x16x32_bf16 v[58:61], v[178:181], v[186:189], v[50:53]
	v_mfma_f32_16x16x32_bf16 v[38:41], v[150:153], v[206:209], v[38:41]
	v_mfma_f32_16x16x32_bf16 v[34:37], v[178:181], v[206:209], v[34:37]
	v_mfma_f32_16x16x32_bf16 v[22:25], v[150:153], v[214:217], v[22:25]
	v_mfma_f32_16x16x32_bf16 v[18:21], v[178:181], v[214:217], v[18:21]
	v_mfma_f32_16x16x32_bf16 v[6:9], v[150:153], v[222:225], v[6:9]
	v_mfma_f32_16x16x32_bf16 v[2:5], v[178:181], v[222:225], v[2:5]
	s_barrier
	s_add_i32 s55, s55, 2
	s_add_u32 s53, s53, 0x100
	s_addc_u32 s54, s54, 0
	s_add_u32 s22, s22, 0x100
	s_addc_u32 s23, s23, 0
	s_cmp_lt_u32 s55, 30
.LBB0_2766:
	ds_read_b128 v[50:53], v196
	ds_read_b128 v[54:57], v196 offset:1024
	ds_read_b128 v[138:141], v196 offset:2048
	ds_read_b128 v[142:145], v196 offset:3072
	ds_read_b128 v[146:149], v197
	ds_read_b128 v[150:153], v197 offset:1024
	ds_read_b128 v[174:177], v197 offset:2048
	ds_read_b128 v[178:181], v197 offset:3072
	s_add_u32 s24, s22, 0xfff80080
	s_addc_u32 s25, s23, -1
	s_cmp_eq_u32 s55, 28
	s_cselect_b32 s35, s3, s25
	s_cselect_b32 s34, s15, s24
	s_cselect_b32 s25, s13, s54
	s_cselect_b32 s24, s21, s53
	v_lshl_add_u64 v[190:191], s[22:23], 0, v[168:169]
	s_add_i32 m0, s28, 0xc000
	ds_read_b128 v[182:185], v198
	ds_read_b128 v[186:189], v198 offset:1024
	ds_read_b128 v[202:205], v198 offset:2048
	ds_read_b128 v[206:209], v198 offset:3072
	ds_read_b128 v[210:213], v198 offset:4096
	ds_read_b128 v[214:217], v198 offset:5120
	ds_read_b128 v[218:221], v198 offset:6144
	ds_read_b128 v[222:225], v198 offset:7168
	global_load_lds_dwordx4 v[190:191], off
	v_lshl_add_u64 v[190:191], s[22:23], 0, v[166:167]
	s_add_i32 m0, s28, 0xe000
	s_nop 0
	global_load_lds_dwordx4 v[190:191], off
	s_waitcnt vmcnt(8)
	s_waitcnt lgkmcnt(0)
	s_barrier
; #define PG8_STAGE(bufoff, gbase, voff) do { _Pragma("unroll") for (int _i = 0; _i < 2; ++_i) \
;         __builtin_amdgcn_global_load_lds((const unsigned*)((const char*)(gbase) + (voff)[_i]), (LAS unsigned*)(lds + (bufoff) + ldsw + _i * 8192), 16, 0, 0); } while (0)
; #define PG8_LDA(dst, b, h) do { _Pragma("unroll") for (int m = 0; m < 4; ++m) _Pragma("unroll") for (int k = 0; k < 2; ++k) dst[m][k] = *(const LAS bf16x8*)(lds + PG8_SA(b, h) + aoff + m * 2048 + k * 1024); } while (0)
; #define PG8_LDB(dst, b, h) do { _Pragma("unroll") for (int n = 0; n < 2; ++n) _Pragma("unroll") for (int k = 0; k < 2; ++k) dst[n][k] = *(const LAS bf16x8*)(lds + PG8_SB(b, h) + boff + n * 2048 + k * 1024); } while (0)
; #define PG8_MMA(ai, bj, At, Bt) do { __builtin_amdgcn_s_setprio(1); _Pragma("unroll") for (int m = 0; m < 4; ++m) _Pragma("unroll") for (int n = 0; n < 2; ++n) _Pragma("unroll") for (int k = 0; k < 2; ++k) \
;         acc[ai][bj][m][n] = __builtin_amdgcn_mfma_f32_16x16x32_bf16(Bt[n][k], At[m][k], acc[ai][bj][m][n], 0, 0, 0); __builtin_amdgcn_s_setprio(0); } while (0)
; #define PG8_WAIT_V(n) asm volatile("s_waitcnt vmcnt(" #n ")" ::: "memory")
; #define PG8_WAIT_L(n) asm volatile("s_waitcnt lgkmcnt(" #n ")" ::: "memory")
; #define PG8_BAR __builtin_amdgcn_s_barrier()
; #define PG8_SCHED __builtin_amdgcn_sched_barrier(0)
; template <class Epi, class Sched, bool ALIGN_EPI = false, bool SP2 = false>
; __device__ __forceinline__ void gemm_phase(LAS unsigned char* lds, const Gemm g, const Sched& S, const Epi& E) {
;     ...
;             PG8_WAIT_V(8); PG8_WAIT_L(0); PG8_BAR; PG8_MMA(0, 0, At, B0); PG8_MMA(0, 1, At, B1); PG8_BAR; PG8_SCHED;
;             PG8_LDA(At, 0, 1); PG8_STAGE(PG8_SB(0, 0), b2, voffB); PG8_STAGE(PG8_SB(0, 1), b2 + hstepB, voffB); PG8_STAGE(PG8_SA(0, 0), a2, voffA);
;             PG8_WAIT_V(8); PG8_WAIT_L(0); PG8_BAR; PG8_MMA(1, 0, At, B0); PG8_MMA(1, 1, At, B1); PG8_BAR; PG8_SCHED;
;             PG8_LDB(B0, 1, 0); PG8_LDB(B1, 1, 1); PG8_SCHED; PG8_LDA(At, 1, 0); PG8_STAGE(PG8_SA(0, 1), a2 + hstep, voffA);
;             PG8_WAIT_V(8); PG8_WAIT_L(0); PG8_BAR; PG8_MMA(0, 0, At, B0); PG8_MMA(0, 1, At, B1); PG8_BAR; PG8_SCHED;
	s_waitcnt lgkmcnt(0)
	v_mfma_f32_16x16x32_bf16 v[134:137], v[50:53], v[182:185], v[134:137]
	v_mfma_f32_16x16x32_bf16 v[130:133], v[138:141], v[182:185], v[130:133]
	v_mfma_f32_16x16x32_bf16 v[118:121], v[50:53], v[202:205], v[118:121]
	v_mfma_f32_16x16x32_bf16 v[114:117], v[138:141], v[202:205], v[114:117]
	v_mfma_f32_16x16x32_bf16 v[102:105], v[50:53], v[210:213], v[102:105]
	v_mfma_f32_16x16x32_bf16 v[98:101], v[138:141], v[210:213], v[98:101]
	v_mfma_f32_16x16x32_bf16 v[86:89], v[50:53], v[218:221], v[86:89]
	v_mfma_f32_16x16x32_bf16 v[82:85], v[138:141], v[218:221], v[82:85]
	v_mfma_f32_16x16x32_bf16 v[134:137], v[54:57], v[186:189], v[134:137]
	v_mfma_f32_16x16x32_bf16 v[130:133], v[142:145], v[186:189], v[130:133]
	v_mfma_f32_16x16x32_bf16 v[118:121], v[54:57], v[206:209], v[118:121]
	v_mfma_f32_16x16x32_bf16 v[114:117], v[142:145], v[206:209], v[114:117]
	v_mfma_f32_16x16x32_bf16 v[102:105], v[54:57], v[214:217], v[102:105]
	v_mfma_f32_16x16x32_bf16 v[98:101], v[142:145], v[214:217], v[98:101]
	v_mfma_f32_16x16x32_bf16 v[86:89], v[54:57], v[222:225], v[86:89]
	v_mfma_f32_16x16x32_bf16 v[82:85], v[142:145], v[222:225], v[82:85]
	v_mfma_f32_16x16x32_bf16 v[126:129], v[146:149], v[182:185], v[126:129]
	v_mfma_f32_16x16x32_bf16 v[122:125], v[174:177], v[182:185], v[122:125]
	v_mfma_f32_16x16x32_bf16 v[110:113], v[146:149], v[202:205], v[110:113]
	v_mfma_f32_16x16x32_bf16 v[106:109], v[174:177], v[202:205], v[106:109]
	v_mfma_f32_16x16x32_bf16 v[94:97], v[146:149], v[210:213], v[94:97]
	v_mfma_f32_16x16x32_bf16 v[90:93], v[174:177], v[210:213], v[90:93]
	v_mfma_f32_16x16x32_bf16 v[78:81], v[146:149], v[218:221], v[78:81]
	v_mfma_f32_16x16x32_bf16 v[74:77], v[174:177], v[218:221], v[74:77]
	v_mfma_f32_16x16x32_bf16 v[126:129], v[150:153], v[186:189], v[126:129]
	v_mfma_f32_16x16x32_bf16 v[122:125], v[178:181], v[186:189], v[122:125]
	v_mfma_f32_16x16x32_bf16 v[110:113], v[150:153], v[206:209], v[110:113]
	v_mfma_f32_16x16x32_bf16 v[106:109], v[178:181], v[206:209], v[106:109]
	v_mfma_f32_16x16x32_bf16 v[94:97], v[150:153], v[214:217], v[94:97]
	v_mfma_f32_16x16x32_bf16 v[90:93], v[178:181], v[214:217], v[90:93]
	v_mfma_f32_16x16x32_bf16 v[78:81], v[150:153], v[222:225], v[78:81]
	v_mfma_f32_16x16x32_bf16 v[74:77], v[178:181], v[222:225], v[74:77]
	s_barrier
	s_add_i32 s56, s51, s27
	v_lshl_add_u64 v[190:191], s[24:25], 0, v[156:157]
	s_mov_b32 m0, s56
	ds_read_b128 v[182:185], v198 offset:16384
	ds_read_b128 v[186:189], v198 offset:17408
	ds_read_b128 v[202:205], v198 offset:18432
	ds_read_b128 v[206:209], v198 offset:19456
	ds_read_b128 v[210:213], v198 offset:20480
	ds_read_b128 v[214:217], v198 offset:21504
	ds_read_b128 v[218:221], v198 offset:22528
	ds_read_b128 v[222:225], v198 offset:23552
	global_load_lds_dwordx4 v[190:191], off
	s_add_i32 m0, s56, 0x2000
	s_add_u32 s56, s24, 0x20000
	v_lshl_add_u64 v[226:227], s[24:25], 0, v[160:161]
	s_addc_u32 s57, s25, 0
	s_add_i32 s58, s52, s27
	global_load_lds_dwordx4 v[226:227], off
	v_lshl_add_u64 v[228:229], s[56:57], 0, v[156:157]
	s_mov_b32 m0, s58
	v_lshl_add_u64 v[230:231], s[34:35], 0, v[158:159]
	global_load_lds_dwordx4 v[228:229], off
	v_lshl_add_u64 v[228:229], s[56:57], 0, v[160:161]
	s_add_i32 m0, s58, 0x2000
	s_nop 0
	global_load_lds_dwordx4 v[228:229], off
	v_lshl_add_u64 v[228:229], s[34:35], 0, v[154:155]
	s_mov_b32 m0, s28
	s_nop 0
	global_load_lds_dwordx4 v[228:229], off
	s_mov_b32 m0, s29
	s_nop 0
	global_load_lds_dwordx4 v[230:231], off
	s_waitcnt vmcnt(8)
	s_waitcnt lgkmcnt(0)
	s_barrier
	s_waitcnt lgkmcnt(0)
	v_mfma_f32_16x16x32_bf16 v[70:73], v[50:53], v[182:185], v[70:73]
	v_mfma_f32_16x16x32_bf16 v[66:69], v[138:141], v[182:185], v[66:69]
	v_mfma_f32_16x16x32_bf16 v[46:49], v[50:53], v[202:205], v[46:49]
	v_mfma_f32_16x16x32_bf16 v[42:45], v[138:141], v[202:205], v[42:45]
	v_mfma_f32_16x16x32_bf16 v[30:33], v[50:53], v[210:213], v[30:33]
	v_mfma_f32_16x16x32_bf16 v[26:29], v[138:141], v[210:213], v[26:29]
	v_mfma_f32_16x16x32_bf16 v[14:17], v[50:53], v[218:221], v[14:17]
	v_mfma_f32_16x16x32_bf16 v[10:13], v[138:141], v[218:221], v[10:13]
	v_mfma_f32_16x16x32_bf16 v[70:73], v[54:57], v[186:189], v[70:73]
	v_mfma_f32_16x16x32_bf16 v[66:69], v[142:145], v[186:189], v[66:69]
	v_mfma_f32_16x16x32_bf16 v[46:49], v[54:57], v[206:209], v[46:49]
	v_mfma_f32_16x16x32_bf16 v[42:45], v[142:145], v[206:209], v[42:45]
	v_mfma_f32_16x16x32_bf16 v[30:33], v[54:57], v[214:217], v[30:33]
	v_mfma_f32_16x16x32_bf16 v[26:29], v[142:145], v[214:217], v[26:29]
	v_mfma_f32_16x16x32_bf16 v[14:17], v[54:57], v[222:225], v[14:17]
	v_mfma_f32_16x16x32_bf16 v[10:13], v[142:145], v[222:225], v[10:13]
	v_mfma_f32_16x16x32_bf16 v[38:41], v[146:149], v[202:205], v[38:41]
	v_mfma_f32_16x16x32_bf16 v[34:37], v[174:177], v[202:205], v[34:37]
	v_mfma_f32_16x16x32_bf16 v[22:25], v[146:149], v[210:213], v[22:25]
	v_mfma_f32_16x16x32_bf16 v[18:21], v[174:177], v[210:213], v[18:21]
	v_mfma_f32_16x16x32_bf16 v[6:9], v[146:149], v[218:221], v[6:9]
	v_mfma_f32_16x16x32_bf16 v[2:5], v[174:177], v[218:221], v[2:5]
	v_mfma_f32_16x16x32_bf16 v[50:53], v[146:149], v[182:185], v[62:65]
	v_mfma_f32_16x16x32_bf16 v[54:57], v[174:177], v[182:185], v[58:61]
	v_mfma_f32_16x16x32_bf16 v[38:41], v[150:153], v[206:209], v[38:41]
	v_mfma_f32_16x16x32_bf16 v[34:37], v[178:181], v[206:209], v[34:37]
	v_mfma_f32_16x16x32_bf16 v[22:25], v[150:153], v[214:217], v[22:25]
	v_mfma_f32_16x16x32_bf16 v[18:21], v[178:181], v[214:217], v[18:21]
	v_mfma_f32_16x16x32_bf16 v[6:9], v[150:153], v[222:225], v[6:9]
	v_mfma_f32_16x16x32_bf16 v[2:5], v[178:181], v[222:225], v[2:5]
	v_mfma_f32_16x16x32_bf16 v[50:53], v[150:153], v[186:189], v[50:53]
	v_mfma_f32_16x16x32_bf16 v[54:57], v[178:181], v[186:189], v[54:57]
	s_barrier
; #define PG8_STAGE(bufoff, gbase, voff) do { _Pragma("unroll") for (int _i = 0; _i < 2; ++_i) \
;         __builtin_amdgcn_global_load_lds((const unsigned*)((const char*)(gbase) + (voff)[_i]), (LAS unsigned*)(lds + (bufoff) + ldsw + _i * 8192), 16, 0, 0); } while (0)
; #define PG8_LDA(dst, b, h) do { _Pragma("unroll") for (int m = 0; m < 4; ++m) _Pragma("unroll") for (int k = 0; k < 2; ++k) dst[m][k] = *(const LAS bf16x8*)(lds + PG8_SA(b, h) + aoff + m * 2048 + k * 1024); } while (0)
; #define PG8_LDB(dst, b, h) do { _Pragma("unroll") for (int n = 0; n < 2; ++n) _Pragma("unroll") for (int k = 0; k < 2; ++k) dst[n][k] = *(const LAS bf16x8*)(lds + PG8_SB(b, h) + boff + n * 2048 + k * 1024); } while (0)
; #define PG8_MMA(ai, bj, At, Bt) do { __builtin_amdgcn_s_setprio(1); _Pragma("unroll") for (int m = 0; m < 4; ++m) _Pragma("unroll") for (int n = 0; n < 2; ++n) _Pragma("unroll") for (int k = 0; k < 2; ++k) \
;         acc[ai][bj][m][n] = __builtin_amdgcn_mfma_f32_16x16x32_bf16(Bt[n][k], At[m][k], acc[ai][bj][m][n], 0, 0, 0); __builtin_amdgcn_s_setprio(0); } while (0)
; #define PG8_WAIT_V(n) asm volatile("s_waitcnt vmcnt(" #n ")" ::: "memory")
; #define PG8_WAIT_L(n) asm volatile("s_waitcnt lgkmcnt(" #n ")" ::: "memory")
; #define PG8_BAR __builtin_amdgcn_s_barrier()
; #define PG8_SCHED __builtin_amdgcn_sched_barrier(0)
; template <class Epi, class Sched, bool ALIGN_EPI = false, bool SP2 = false>
; __device__ __forceinline__ void gemm_phase(LAS unsigned char* lds, const Gemm g, const Sched& S, const Epi& E) {
;     ...
;             PG8_LDB(B0, 1, 0); PG8_LDB(B1, 1, 1); PG8_SCHED; PG8_LDA(At, 1, 0); PG8_STAGE(PG8_SA(0, 1), a2 + hstep, voffA);
;             PG8_WAIT_V(8); PG8_WAIT_L(0); PG8_BAR; PG8_MMA(0, 0, At, B0); PG8_MMA(0, 1, At, B1); PG8_BAR; PG8_SCHED;
	s_add_i32 s56, 0, 0x18000
	s_add_i32 s57, 0, 0x1c000
	v_add_u32_e32 v142, s56, v1
	v_add_u32_e32 v162, s57, v1
	ds_read_b128 v[58:61], v142
	ds_read_b128 v[62:65], v142 offset:1024
	ds_read_b128 v[138:141], v142 offset:2048
	ds_read_b128 v[142:145], v142 offset:3072
	ds_read_b128 v[146:149], v162
	ds_read_b128 v[150:153], v162 offset:1024
	ds_read_b128 v[174:177], v162 offset:2048
	ds_read_b128 v[178:181], v162 offset:3072
	s_add_u32 s34, s34, 0x80000
	s_addc_u32 s35, s35, 0
	s_mov_b32 m0, s30
	v_lshl_add_u64 v[232:233], s[34:35], 0, v[154:155]
	ds_read_b128 v[182:185], v198 offset:32768
	ds_read_b128 v[186:189], v198 offset:33792
	ds_read_b128 v[202:205], v198 offset:34816
	ds_read_b128 v[206:209], v198 offset:35840
	ds_read_b128 v[210:213], v198 offset:36864
	ds_read_b128 v[214:217], v198 offset:37888
	ds_read_b128 v[218:221], v198 offset:38912
	ds_read_b128 v[222:225], v198 offset:39936
	global_load_lds_dwordx4 v[232:233], off
	v_lshl_add_u64 v[232:233], s[34:35], 0, v[158:159]
	s_mov_b32 m0, s31
	s_nop 0
	global_load_lds_dwordx4 v[232:233], off
	s_waitcnt vmcnt(8)
	s_waitcnt lgkmcnt(0)
	s_barrier
	s_waitcnt lgkmcnt(0)
	v_mfma_f32_16x16x32_bf16 v[134:137], v[58:61], v[182:185], v[134:137]
	v_mfma_f32_16x16x32_bf16 v[130:133], v[138:141], v[182:185], v[130:133]
	v_mfma_f32_16x16x32_bf16 v[118:121], v[58:61], v[202:205], v[118:121]
	v_mfma_f32_16x16x32_bf16 v[114:117], v[138:141], v[202:205], v[114:117]
	v_mfma_f32_16x16x32_bf16 v[102:105], v[58:61], v[210:213], v[102:105]
	v_mfma_f32_16x16x32_bf16 v[98:101], v[138:141], v[210:213], v[98:101]
	v_mfma_f32_16x16x32_bf16 v[86:89], v[58:61], v[218:221], v[86:89]
	v_mfma_f32_16x16x32_bf16 v[82:85], v[138:141], v[218:221], v[82:85]
	v_mfma_f32_16x16x32_bf16 v[134:137], v[62:65], v[186:189], v[134:137]
	v_mfma_f32_16x16x32_bf16 v[130:133], v[142:145], v[186:189], v[130:133]
	v_mfma_f32_16x16x32_bf16 v[118:121], v[62:65], v[206:209], v[118:121]
	v_mfma_f32_16x16x32_bf16 v[114:117], v[142:145], v[206:209], v[114:117]
	v_mfma_f32_16x16x32_bf16 v[102:105], v[62:65], v[214:217], v[102:105]
	v_mfma_f32_16x16x32_bf16 v[98:101], v[142:145], v[214:217], v[98:101]
	v_mfma_f32_16x16x32_bf16 v[86:89], v[62:65], v[222:225], v[86:89]
	v_mfma_f32_16x16x32_bf16 v[82:85], v[142:145], v[222:225], v[82:85]
	v_mfma_f32_16x16x32_bf16 v[126:129], v[146:149], v[182:185], v[126:129]
	v_mfma_f32_16x16x32_bf16 v[122:125], v[174:177], v[182:185], v[122:125]
	v_mfma_f32_16x16x32_bf16 v[110:113], v[146:149], v[202:205], v[110:113]
	v_mfma_f32_16x16x32_bf16 v[106:109], v[174:177], v[202:205], v[106:109]
	v_mfma_f32_16x16x32_bf16 v[94:97], v[146:149], v[210:213], v[94:97]
	v_mfma_f32_16x16x32_bf16 v[90:93], v[174:177], v[210:213], v[90:93]
	v_mfma_f32_16x16x32_bf16 v[78:81], v[146:149], v[218:221], v[78:81]
	v_mfma_f32_16x16x32_bf16 v[74:77], v[174:177], v[218:221], v[74:77]
	v_mfma_f32_16x16x32_bf16 v[126:129], v[150:153], v[186:189], v[126:129]
	v_mfma_f32_16x16x32_bf16 v[122:125], v[178:181], v[186:189], v[122:125]
	v_mfma_f32_16x16x32_bf16 v[110:113], v[150:153], v[206:209], v[110:113]
	v_mfma_f32_16x16x32_bf16 v[106:109], v[178:181], v[206:209], v[106:109]
	v_mfma_f32_16x16x32_bf16 v[94:97], v[150:153], v[214:217], v[94:97]
	v_mfma_f32_16x16x32_bf16 v[90:93], v[178:181], v[214:217], v[90:93]
	v_mfma_f32_16x16x32_bf16 v[78:81], v[150:153], v[222:225], v[78:81]
	v_mfma_f32_16x16x32_bf16 v[74:77], v[178:181], v[222:225], v[74:77]
	s_barrier
; #define PG8_STAGE(bufoff, gbase, voff) do { _Pragma("unroll") for (int _i = 0; _i < 2; ++_i) \
;         __builtin_amdgcn_global_load_lds((const unsigned*)((const char*)(gbase) + (voff)[_i]), (LAS unsigned*)(lds + (bufoff) + ldsw + _i * 8192), 16, 0, 0); } while (0)
; #define PG8_LDA(dst, b, h) do { _Pragma("unroll") for (int m = 0; m < 4; ++m) _Pragma("unroll") for (int k = 0; k < 2; ++k) dst[m][k] = *(const LAS bf16x8*)(lds + PG8_SA(b, h) + aoff + m * 2048 + k * 1024); } while (0)
; #define PG8_MMA(ai, bj, At, Bt) do { __builtin_amdgcn_s_setprio(1); _Pragma("unroll") for (int m = 0; m < 4; ++m) _Pragma("unroll") for (int n = 0; n < 2; ++n) _Pragma("unroll") for (int k = 0; k < 2; ++k) \
;         acc[ai][bj][m][n] = __builtin_amdgcn_mfma_f32_16x16x32_bf16(Bt[n][k], At[m][k], acc[ai][bj][m][n], 0, 0, 0); __builtin_amdgcn_s_setprio(0); } while (0)
; #define PG8_WAIT_V(n) asm volatile("s_waitcnt vmcnt(" #n ")" ::: "memory")
; #define PG8_WAIT_L(n) asm volatile("s_waitcnt lgkmcnt(" #n ")" ::: "memory")
; #define PG8_BAR __builtin_amdgcn_s_barrier()
; #define PG8_SCHED __builtin_amdgcn_sched_barrier(0)
; template <class Epi, class Sched, bool ALIGN_EPI = false, bool SP2 = false>
; __device__ __forceinline__ void gemm_phase(LAS unsigned char* lds, const Gemm g, const Sched& S, const Epi& E) {
;     ...
;         for (int t = 0; t < nt; t += 2) {
;     ...
;             PG8_LDA(At, 1, 1); PG8_STAGE(PG8_SB(1, 0), b3, voffB); PG8_STAGE(PG8_SB(1, 1), b3 + hstepB, voffB); PG8_STAGE(PG8_SA(1, 0), a3, voffA);
;             PG8_WAIT_V(8); PG8_WAIT_L(0); PG8_BAR; PG8_MMA(1, 0, At, B0); PG8_MMA(1, 1, At, B1); PG8_BAR; PG8_SCHED;
	s_add_i32 s34, s56, s27
	v_lshl_add_u64 v[190:191], v[190:191], 0, s[8:9]
	s_mov_b32 m0, s34
	ds_read_b128 v[182:185], v198 offset:49152
	ds_read_b128 v[186:189], v198 offset:50176
	ds_read_b128 v[202:205], v198 offset:51200
	ds_read_b128 v[206:209], v198 offset:52224
	ds_read_b128 v[210:213], v198 offset:53248
	ds_read_b128 v[214:217], v198 offset:54272
	ds_read_b128 v[218:221], v198 offset:55296
	ds_read_b128 v[222:225], v198 offset:56320
	global_load_lds_dwordx4 v[190:191], off
	s_add_i32 m0, s34, 0x2000
	s_add_u32 s24, s24, 0x20080
	v_lshl_add_u64 v[190:191], v[226:227], 0, s[8:9]
	s_addc_u32 s25, s25, 0
	s_add_i32 s34, s57, s27
	global_load_lds_dwordx4 v[190:191], off
	v_lshl_add_u64 v[190:191], s[24:25], 0, v[156:157]
	s_mov_b32 m0, s34
	s_nop 0
	global_load_lds_dwordx4 v[190:191], off
	v_lshl_add_u64 v[190:191], s[24:25], 0, v[160:161]
	s_add_i32 m0, s34, 0x2000
	s_nop 0
	global_load_lds_dwordx4 v[190:191], off
	v_lshl_add_u64 v[190:191], v[228:229], 0, s[8:9]
	s_mov_b32 m0, s48
	s_nop 0
	global_load_lds_dwordx4 v[190:191], off
	v_lshl_add_u64 v[190:191], v[230:231], 0, s[8:9]
	s_mov_b32 m0, s49
	s_nop 0
	global_load_lds_dwordx4 v[190:191], off
	s_waitcnt vmcnt(8)
	s_waitcnt lgkmcnt(0)
	s_barrier
	s_waitcnt lgkmcnt(0)
	v_mfma_f32_16x16x32_bf16 v[70:73], v[58:61], v[182:185], v[70:73]
	v_mfma_f32_16x16x32_bf16 v[66:69], v[138:141], v[182:185], v[66:69]
	v_mfma_f32_16x16x32_bf16 v[46:49], v[58:61], v[202:205], v[46:49]
	v_mfma_f32_16x16x32_bf16 v[42:45], v[138:141], v[202:205], v[42:45]
	v_mfma_f32_16x16x32_bf16 v[30:33], v[58:61], v[210:213], v[30:33]
	v_mfma_f32_16x16x32_bf16 v[26:29], v[138:141], v[210:213], v[26:29]
	v_mfma_f32_16x16x32_bf16 v[14:17], v[58:61], v[218:221], v[14:17]
	v_mfma_f32_16x16x32_bf16 v[10:13], v[138:141], v[218:221], v[10:13]
	v_mfma_f32_16x16x32_bf16 v[70:73], v[62:65], v[186:189], v[70:73]
	v_mfma_f32_16x16x32_bf16 v[66:69], v[142:145], v[186:189], v[66:69]
	v_mfma_f32_16x16x32_bf16 v[46:49], v[62:65], v[206:209], v[46:49]
	v_mfma_f32_16x16x32_bf16 v[42:45], v[142:145], v[206:209], v[42:45]
	v_mfma_f32_16x16x32_bf16 v[30:33], v[62:65], v[214:217], v[30:33]
	v_mfma_f32_16x16x32_bf16 v[26:29], v[142:145], v[214:217], v[26:29]
	v_mfma_f32_16x16x32_bf16 v[14:17], v[62:65], v[222:225], v[14:17]
	v_mfma_f32_16x16x32_bf16 v[10:13], v[142:145], v[222:225], v[10:13]
	v_mfma_f32_16x16x32_bf16 v[50:53], v[146:149], v[182:185], v[50:53]
	v_mfma_f32_16x16x32_bf16 v[62:65], v[150:153], v[186:189], v[50:53]
	v_mfma_f32_16x16x32_bf16 v[50:53], v[174:177], v[182:185], v[54:57]
	v_mfma_f32_16x16x32_bf16 v[38:41], v[146:149], v[202:205], v[38:41]
	v_mfma_f32_16x16x32_bf16 v[34:37], v[174:177], v[202:205], v[34:37]
	v_mfma_f32_16x16x32_bf16 v[22:25], v[146:149], v[210:213], v[22:25]
	v_mfma_f32_16x16x32_bf16 v[18:21], v[174:177], v[210:213], v[18:21]
	v_mfma_f32_16x16x32_bf16 v[6:9], v[146:149], v[218:221], v[6:9]
	v_mfma_f32_16x16x32_bf16 v[2:5], v[174:177], v[218:221], v[2:5]
	v_mfma_f32_16x16x32_bf16 v[58:61], v[178:181], v[186:189], v[50:53]
	v_mfma_f32_16x16x32_bf16 v[38:41], v[150:153], v[206:209], v[38:41]
	v_mfma_f32_16x16x32_bf16 v[34:37], v[178:181], v[206:209], v[34:37]
	v_mfma_f32_16x16x32_bf16 v[22:25], v[150:153], v[214:217], v[22:25]
	v_mfma_f32_16x16x32_bf16 v[18:21], v[178:181], v[214:217], v[18:21]
	v_mfma_f32_16x16x32_bf16 v[6:9], v[150:153], v[222:225], v[6:9]
	v_mfma_f32_16x16x32_bf16 v[2:5], v[178:181], v[222:225], v[2:5]
	s_barrier
	s_add_i32 s55, s55, 2
	s_add_u32 s53, s53, 0x100
	s_addc_u32 s54, s54, 0
	s_add_u32 s22, s22, 0x100
	s_addc_u32 s23, s23, 0
	s_cmp_lt_u32 s55, 30
	s_cbranch_scc1 .LBB0_2766
	s_andn2_b64 vcc, exec, s[10:11]
	s_cbranch_vccnz .LBB0_2769
	s_barrier

; __device__ __forceinline__ float row_rstd(const float* ss, int row) { return 1.0f / sqrtf(ss[row] * (1.0f / DM) + 1e-6f); }
; #define PG8_STAGE(bufoff, gbase, voff) do { _Pragma("unroll") for (int _i = 0; _i < 2; ++_i) \
;         __builtin_amdgcn_global_load_lds((const unsigned*)((const char*)(gbase) + (voff)[_i]), (LAS unsigned*)(lds + (bufoff) + ldsw + _i * 8192), 16, 0, 0); } while (0)
; #define PG8_LDA(dst, b, h) do { _Pragma("unroll") for (int m = 0; m < 4; ++m) _Pragma("unroll") for (int k = 0; k < 2; ++k) dst[m][k] = *(const LAS bf16x8*)(lds + PG8_SA(b, h) + aoff + m * 2048 + k * 1024); } while (0)
; #define PG8_LDB(dst, b, h) do { _Pragma("unroll") for (int n = 0; n < 2; ++n) _Pragma("unroll") for (int k = 0; k < 2; ++k) dst[n][k] = *(const LAS bf16x8*)(lds + PG8_SB(b, h) + boff + n * 2048 + k * 1024); } while (0)
; #define PG8_WAIT_V(n) asm volatile("s_waitcnt vmcnt(" #n ")" ::: "memory")
; #define PG8_WAIT_L(n) asm volatile("s_waitcnt lgkmcnt(" #n ")" ::: "memory")
; #define PG8_BAR __builtin_amdgcn_s_barrier()
; #define PG8_SCHED __builtin_amdgcn_sched_barrier(0)
;     __device__ __forceinline__ void operator()(const f32x4 (&acc)[2][2][4][2], const Unit& u, int wr, int wc, int fr, int fq) const {
;     ...
;         const float* bp = bias + (size_t)s * BIAS_N + u.pn * BM + wc * 32 + 8 * fq;
;         const f32x4 ba0 = *(const f32x4*)bp, ba1 = *(const f32x4*)(bp + 4), bb0 = *(const f32x4*)(bp + HALF), bb1 = *(const f32x4*)(bp + HALF + 4);
;         const int lane = fq * 16 + fr;
;         const float rsl0 = row_rstd(ss, u.pm * BM + wr * 64 + lane), rsl1 = row_rstd(ss, u.pm * BM + HALF + wr * 64 + lane);
; template <class Epi, class Sched, bool ALIGN_EPI = false, bool SP2 = false>
; __device__ __forceinline__ void gemm_phase(LAS unsigned char* lds, const Gemm g, const Sched& S, const Epi& E) {
;     ...
;             PG8_LDB(B0, 0, 0); PG8_LDB(B1, 0, 1); PG8_SCHED; PG8_LDA(At, 0, 0); PG8_STAGE(PG8_SA(1, 1), a1 + hstep, voffA);
;             PG8_WAIT_V(8); PG8_WAIT_L(0); PG8_BAR; PG8_MMA(0, 0, At, B0); PG8_MMA(0, 1, At, B1); PG8_BAR; PG8_SCHED;
;             PG8_LDA(At, 0, 1); PG8_STAGE(PG8_SB(0, 0), b2, voffB); PG8_STAGE(PG8_SB(0, 1), b2 + hstepB, voffB); PG8_STAGE(PG8_SA(0, 0), a2, voffA);
;             PG8_WAIT_V(8); PG8_WAIT_L(0); PG8_BAR; PG8_MMA(1, 0, At, B0); PG8_MMA(1, 1, At, B1); PG8_BAR; PG8_SCHED;
.Lpre_up2l1:
	s_lshl_b64 s[98:99], s[98:99], 2
	s_add_u32 s98, s35, s98
	s_addc_u32 s99, s38, s99
	s_lshl_b32 s100, s3, 8
	s_ashr_i32 s101, s100, 31
	s_lshl_b64 s[100:101], s[100:101], 2
	s_add_u32 s98, s98, s100
	s_addc_u32 s99, s99, s101
	s_add_u32 s98, s98, s44
	s_addc_u32 s99, s99, 0
	s_lshl_b32 s100, s2, 8
	s_add_i32 s100, s100, s34
	v_or_b32_e32 v162, s100, v170
	v_ashrrev_i32_e32 v163, 31, v162
	v_lshl_add_u64 v[162:163], v[162:163], 2, s[0:1]
	v_add_u32_e32 v164, s100, v171
	v_ashrrev_i32_e32 v165, 31, v164
	v_lshl_add_u64 v[164:165], v[164:165], 2, s[0:1]
	global_load_dwordx4 v[234:237], v176, s[98:99] offset:16
	global_load_dwordx4 v[238:241], v176, s[98:99]
	global_load_dwordx4 v[242:245], v176, s[98:99] offset:528
	global_load_dwordx4 v[246:249], v176, s[98:99] offset:512
	global_load_dword v250, v[162:163], off
	global_load_dword v251, v[164:165], off
	ds_read_b128 v[66:69], v173
	ds_read_b128 v[70:73], v173 offset:1024
	ds_read_b128 v[74:77], v173 offset:2048
	ds_read_b128 v[78:81], v173 offset:3072
	ds_read_b128 v[162:165], v174
	ds_read_b128 v[180:183], v174 offset:1024
	ds_read_b128 v[184:187], v174 offset:2048
	ds_read_b128 v[188:191], v174 offset:3072
	s_add_u32 s20, s18, 0xfff80080
	s_addc_u32 s21, s19, -1
	s_cmp_eq_u32 s50, 28
	s_cselect_b32 s23, s13, s21
	s_cselect_b32 s22, s46, s20
	s_cselect_b32 s21, s11, s49
	s_cselect_b32 s20, s47, s48
	v_lshl_add_u64 v[166:167], s[18:19], 0, v[156:157]
	s_add_i32 m0, s28, 0xc000
	ds_read_b128 v[192:195], v175
	ds_read_b128 v[196:199], v175 offset:1024
	ds_read_b128 v[200:203], v175 offset:2048
	ds_read_b128 v[204:207], v175 offset:3072
	ds_read_b128 v[208:211], v175 offset:4096
	ds_read_b128 v[212:215], v175 offset:5120
	ds_read_b128 v[216:219], v175 offset:6144
	ds_read_b128 v[220:223], v175 offset:7168
	global_load_lds_dwordx4 v[166:167], off
	v_lshl_add_u64 v[166:167], s[18:19], 0, v[154:155]
	s_add_i32 m0, s28, 0xe000
	s_nop 0
	global_load_lds_dwordx4 v[166:167], off
	s_waitcnt lgkmcnt(0)
	s_barrier
	s_waitcnt lgkmcnt(0)
	v_mfma_f32_16x16x32_bf16 v[142:145], v[66:69], v[192:195], 0
	v_mfma_f32_16x16x32_bf16 v[138:141], v[74:77], v[192:195], 0
	v_mfma_f32_16x16x32_bf16 v[126:129], v[66:69], v[200:203], 0
	v_mfma_f32_16x16x32_bf16 v[122:125], v[74:77], v[200:203], 0
	v_mfma_f32_16x16x32_bf16 v[110:113], v[66:69], v[208:211], 0
	v_mfma_f32_16x16x32_bf16 v[106:109], v[74:77], v[208:211], 0
	v_mfma_f32_16x16x32_bf16 v[94:97], v[66:69], v[216:219], 0
	v_mfma_f32_16x16x32_bf16 v[90:93], v[74:77], v[216:219], 0
	v_mfma_f32_16x16x32_bf16 v[142:145], v[70:73], v[196:199], v[142:145]
	v_mfma_f32_16x16x32_bf16 v[138:141], v[78:81], v[196:199], v[138:141]
	v_mfma_f32_16x16x32_bf16 v[126:129], v[70:73], v[204:207], v[126:129]
	v_mfma_f32_16x16x32_bf16 v[122:125], v[78:81], v[204:207], v[122:125]
	v_mfma_f32_16x16x32_bf16 v[110:113], v[70:73], v[212:215], v[110:113]
	v_mfma_f32_16x16x32_bf16 v[106:109], v[78:81], v[212:215], v[106:109]
	v_mfma_f32_16x16x32_bf16 v[94:97], v[70:73], v[220:223], v[94:97]
	v_mfma_f32_16x16x32_bf16 v[90:93], v[78:81], v[220:223], v[90:93]
	v_mfma_f32_16x16x32_bf16 v[134:137], v[162:165], v[192:195], 0
	v_mfma_f32_16x16x32_bf16 v[130:133], v[184:187], v[192:195], 0
	v_mfma_f32_16x16x32_bf16 v[118:121], v[162:165], v[200:203], 0
	v_mfma_f32_16x16x32_bf16 v[114:117], v[184:187], v[200:203], 0
	v_mfma_f32_16x16x32_bf16 v[102:105], v[162:165], v[208:211], 0
	v_mfma_f32_16x16x32_bf16 v[98:101], v[184:187], v[208:211], 0
	v_mfma_f32_16x16x32_bf16 v[86:89], v[162:165], v[216:219], 0
	v_mfma_f32_16x16x32_bf16 v[82:85], v[184:187], v[216:219], 0
	v_mfma_f32_16x16x32_bf16 v[134:137], v[180:183], v[196:199], v[134:137]
	v_mfma_f32_16x16x32_bf16 v[130:133], v[188:191], v[196:199], v[130:133]
	v_mfma_f32_16x16x32_bf16 v[118:121], v[180:183], v[204:207], v[118:121]
	v_mfma_f32_16x16x32_bf16 v[114:117], v[188:191], v[204:207], v[114:117]
	v_mfma_f32_16x16x32_bf16 v[102:105], v[180:183], v[212:215], v[102:105]
	v_mfma_f32_16x16x32_bf16 v[98:101], v[188:191], v[212:215], v[98:101]
	v_mfma_f32_16x16x32_bf16 v[86:89], v[180:183], v[220:223], v[86:89]
	v_mfma_f32_16x16x32_bf16 v[82:85], v[188:191], v[220:223], v[82:85]
	s_barrier
	s_add_i32 s51, s41, s25
	v_lshl_add_u64 v[166:167], s[20:21], 0, v[150:151]
	s_mov_b32 m0, s51
	ds_read_b128 v[192:195], v175 offset:16384
	ds_read_b128 v[196:199], v175 offset:17408
	ds_read_b128 v[200:203], v175 offset:18432
	ds_read_b128 v[204:207], v175 offset:19456
	ds_read_b128 v[208:211], v175 offset:20480
	ds_read_b128 v[212:215], v175 offset:21504
	ds_read_b128 v[216:219], v175 offset:22528
	ds_read_b128 v[220:223], v175 offset:23552
	global_load_lds_dwordx4 v[166:167], off
	s_add_i32 m0, s51, 0x2000
	s_add_u32 s52, s20, 0x80000
	v_lshl_add_u64 v[224:225], s[20:21], 0, v[146:147]
	s_addc_u32 s53, s21, 0
	s_add_i32 s51, s42, s25
	global_load_lds_dwordx4 v[224:225], off
	v_lshl_add_u64 v[226:227], s[52:53], 0, v[150:151]
	s_mov_b32 m0, s51
	v_lshl_add_u64 v[228:229], s[22:23], 0, v[148:149]
	global_load_lds_dwordx4 v[226:227], off
	v_lshl_add_u64 v[226:227], s[52:53], 0, v[146:147]
	s_add_i32 m0, s51, 0x2000
	s_nop 0
	global_load_lds_dwordx4 v[226:227], off
	v_lshl_add_u64 v[226:227], s[22:23], 0, v[152:153]
	s_mov_b32 m0, s28
	s_nop 0
	global_load_lds_dwordx4 v[226:227], off
	s_mov_b32 m0, s29
	s_nop 0
	global_load_lds_dwordx4 v[228:229], off
	s_waitcnt lgkmcnt(0)
	s_barrier
; #define PG8_STAGE(bufoff, gbase, voff) do { _Pragma("unroll") for (int _i = 0; _i < 2; ++_i) \
;         __builtin_amdgcn_global_load_lds((const unsigned*)((const char*)(gbase) + (voff)[_i]), (LAS unsigned*)(lds + (bufoff) + ldsw + _i * 8192), 16, 0, 0); } while (0)
; #define PG8_LDA(dst, b, h) do { _Pragma("unroll") for (int m = 0; m < 4; ++m) _Pragma("unroll") for (int k = 0; k < 2; ++k) dst[m][k] = *(const LAS bf16x8*)(lds + PG8_SA(b, h) + aoff + m * 2048 + k * 1024); } while (0)
; #define PG8_LDB(dst, b, h) do { _Pragma("unroll") for (int n = 0; n < 2; ++n) _Pragma("unroll") for (int k = 0; k < 2; ++k) dst[n][k] = *(const LAS bf16x8*)(lds + PG8_SB(b, h) + boff + n * 2048 + k * 1024); } while (0)
; #define PG8_MMA(ai, bj, At, Bt) do { __builtin_amdgcn_s_setprio(1); _Pragma("unroll") for (int m = 0; m < 4; ++m) _Pragma("unroll") for (int n = 0; n < 2; ++n) _Pragma("unroll") for (int k = 0; k < 2; ++k) \
;         acc[ai][bj][m][n] = __builtin_amdgcn_mfma_f32_16x16x32_bf16(Bt[n][k], At[m][k], acc[ai][bj][m][n], 0, 0, 0); __builtin_amdgcn_s_setprio(0); } while (0)
; #define PG8_WAIT_V(n) asm volatile("s_waitcnt vmcnt(" #n ")" ::: "memory")
; #define PG8_WAIT_L(n) asm volatile("s_waitcnt lgkmcnt(" #n ")" ::: "memory")
; #define PG8_BAR __builtin_amdgcn_s_barrier()
; #define PG8_SCHED __builtin_amdgcn_sched_barrier(0)
; template <class Epi, class Sched, bool ALIGN_EPI = false, bool SP2 = false>
; __device__ __forceinline__ void gemm_phase(LAS unsigned char* lds, const Gemm g, const Sched& S, const Epi& E) {
;     ...
;             PG8_WAIT_V(8); PG8_WAIT_L(0); PG8_BAR; PG8_MMA(1, 0, At, B0); PG8_MMA(1, 1, At, B1); PG8_BAR; PG8_SCHED;
;             PG8_LDB(B0, 1, 0); PG8_LDB(B1, 1, 1); PG8_SCHED; PG8_LDA(At, 1, 0); PG8_STAGE(PG8_SA(0, 1), a2 + hstep, voffA);
;             PG8_WAIT_V(8); PG8_WAIT_L(0); PG8_BAR; PG8_MMA(0, 0, At, B0); PG8_MMA(0, 1, At, B1); PG8_BAR; PG8_SCHED;
	s_waitcnt lgkmcnt(0)
	v_mfma_f32_16x16x32_bf16 v[62:65], v[66:69], v[192:195], 0
	v_mfma_f32_16x16x32_bf16 v[58:61], v[74:77], v[192:195], 0
	v_mfma_f32_16x16x32_bf16 v[46:49], v[66:69], v[200:203], 0
	v_mfma_f32_16x16x32_bf16 v[42:45], v[74:77], v[200:203], 0
	v_mfma_f32_16x16x32_bf16 v[30:33], v[66:69], v[208:211], 0
	v_mfma_f32_16x16x32_bf16 v[26:29], v[74:77], v[208:211], 0
	v_mfma_f32_16x16x32_bf16 v[14:17], v[66:69], v[216:219], 0
	v_mfma_f32_16x16x32_bf16 v[10:13], v[74:77], v[216:219], 0
	v_mfma_f32_16x16x32_bf16 v[62:65], v[70:73], v[196:199], v[62:65]
	v_mfma_f32_16x16x32_bf16 v[58:61], v[78:81], v[196:199], v[58:61]
	v_mfma_f32_16x16x32_bf16 v[46:49], v[70:73], v[204:207], v[46:49]
	v_mfma_f32_16x16x32_bf16 v[42:45], v[78:81], v[204:207], v[42:45]
	v_mfma_f32_16x16x32_bf16 v[30:33], v[70:73], v[212:215], v[30:33]
	v_mfma_f32_16x16x32_bf16 v[26:29], v[78:81], v[212:215], v[26:29]
	v_mfma_f32_16x16x32_bf16 v[14:17], v[70:73], v[220:223], v[14:17]
	v_mfma_f32_16x16x32_bf16 v[10:13], v[78:81], v[220:223], v[10:13]
	v_mfma_f32_16x16x32_bf16 v[54:57], v[162:165], v[192:195], 0
	v_mfma_f32_16x16x32_bf16 v[50:53], v[184:187], v[192:195], 0
	v_mfma_f32_16x16x32_bf16 v[38:41], v[162:165], v[200:203], 0
	v_mfma_f32_16x16x32_bf16 v[34:37], v[184:187], v[200:203], 0
	v_mfma_f32_16x16x32_bf16 v[22:25], v[162:165], v[208:211], 0
	v_mfma_f32_16x16x32_bf16 v[18:21], v[184:187], v[208:211], 0
	v_mfma_f32_16x16x32_bf16 v[6:9], v[162:165], v[216:219], 0
	v_mfma_f32_16x16x32_bf16 v[2:5], v[184:187], v[216:219], 0
	v_mfma_f32_16x16x32_bf16 v[54:57], v[180:183], v[196:199], v[54:57]
	v_mfma_f32_16x16x32_bf16 v[50:53], v[188:191], v[196:199], v[50:53]
	v_mfma_f32_16x16x32_bf16 v[38:41], v[180:183], v[204:207], v[38:41]
	v_mfma_f32_16x16x32_bf16 v[34:37], v[188:191], v[204:207], v[34:37]
	v_mfma_f32_16x16x32_bf16 v[22:25], v[180:183], v[212:215], v[22:25]
	v_mfma_f32_16x16x32_bf16 v[18:21], v[188:191], v[212:215], v[18:21]
	v_mfma_f32_16x16x32_bf16 v[6:9], v[180:183], v[220:223], v[6:9]
	v_mfma_f32_16x16x32_bf16 v[2:5], v[188:191], v[220:223], v[2:5]
	s_barrier
	s_add_i32 s51, 0, 0x18000
	s_add_i32 s52, 0, 0x1c000
	v_add_u32_e32 v78, s51, v169
	v_add_u32_e32 v168, s52, v169
	ds_read_b128 v[66:69], v78
	ds_read_b128 v[70:73], v78 offset:1024
	ds_read_b128 v[74:77], v78 offset:2048
	ds_read_b128 v[78:81], v78 offset:3072
	ds_read_b128 v[162:165], v168
	ds_read_b128 v[180:183], v168 offset:1024
	ds_read_b128 v[184:187], v168 offset:2048
	ds_read_b128 v[188:191], v168 offset:3072
	s_add_u32 s22, s22, 0x80000
	s_addc_u32 s23, s23, 0
	s_mov_b32 m0, s30
	v_lshl_add_u64 v[230:231], s[22:23], 0, v[152:153]
	ds_read_b128 v[192:195], v175 offset:32768
	ds_read_b128 v[196:199], v175 offset:33792
	ds_read_b128 v[200:203], v175 offset:34816
	ds_read_b128 v[204:207], v175 offset:35840
	ds_read_b128 v[208:211], v175 offset:36864
	ds_read_b128 v[212:215], v175 offset:37888
	ds_read_b128 v[216:219], v175 offset:38912
	ds_read_b128 v[220:223], v175 offset:39936
	global_load_lds_dwordx4 v[230:231], off
	v_lshl_add_u64 v[230:231], s[22:23], 0, v[148:149]
	s_mov_b32 m0, s31
	s_nop 0
	global_load_lds_dwordx4 v[230:231], off
	s_waitcnt vmcnt(8)
	s_waitcnt lgkmcnt(0)
	s_barrier
	s_waitcnt lgkmcnt(0)
	v_mfma_f32_16x16x32_bf16 v[142:145], v[66:69], v[192:195], v[142:145]
	v_mfma_f32_16x16x32_bf16 v[138:141], v[74:77], v[192:195], v[138:141]
	v_mfma_f32_16x16x32_bf16 v[126:129], v[66:69], v[200:203], v[126:129]
	v_mfma_f32_16x16x32_bf16 v[122:125], v[74:77], v[200:203], v[122:125]
	v_mfma_f32_16x16x32_bf16 v[110:113], v[66:69], v[208:211], v[110:113]
	v_mfma_f32_16x16x32_bf16 v[106:109], v[74:77], v[208:211], v[106:109]
	v_mfma_f32_16x16x32_bf16 v[94:97], v[66:69], v[216:219], v[94:97]
	v_mfma_f32_16x16x32_bf16 v[90:93], v[74:77], v[216:219], v[90:93]
	v_mfma_f32_16x16x32_bf16 v[142:145], v[70:73], v[196:199], v[142:145]
	v_mfma_f32_16x16x32_bf16 v[138:141], v[78:81], v[196:199], v[138:141]
	v_mfma_f32_16x16x32_bf16 v[126:129], v[70:73], v[204:207], v[126:129]
	v_mfma_f32_16x16x32_bf16 v[122:125], v[78:81], v[204:207], v[122:125]
	v_mfma_f32_16x16x32_bf16 v[110:113], v[70:73], v[212:215], v[110:113]
	v_mfma_f32_16x16x32_bf16 v[106:109], v[78:81], v[212:215], v[106:109]
	v_mfma_f32_16x16x32_bf16 v[94:97], v[70:73], v[220:223], v[94:97]
	v_mfma_f32_16x16x32_bf16 v[90:93], v[78:81], v[220:223], v[90:93]
	v_mfma_f32_16x16x32_bf16 v[134:137], v[162:165], v[192:195], v[134:137]
	v_mfma_f32_16x16x32_bf16 v[130:133], v[184:187], v[192:195], v[130:133]
	v_mfma_f32_16x16x32_bf16 v[118:121], v[162:165], v[200:203], v[118:121]
	v_mfma_f32_16x16x32_bf16 v[114:117], v[184:187], v[200:203], v[114:117]
	v_mfma_f32_16x16x32_bf16 v[102:105], v[162:165], v[208:211], v[102:105]
	v_mfma_f32_16x16x32_bf16 v[98:101], v[184:187], v[208:211], v[98:101]
	v_mfma_f32_16x16x32_bf16 v[86:89], v[162:165], v[216:219], v[86:89]
	v_mfma_f32_16x16x32_bf16 v[82:85], v[184:187], v[216:219], v[82:85]
	v_mfma_f32_16x16x32_bf16 v[134:137], v[180:183], v[196:199], v[134:137]
	v_mfma_f32_16x16x32_bf16 v[130:133], v[188:191], v[196:199], v[130:133]
	v_mfma_f32_16x16x32_bf16 v[118:121], v[180:183], v[204:207], v[118:121]
	v_mfma_f32_16x16x32_bf16 v[114:117], v[188:191], v[204:207], v[114:117]
	v_mfma_f32_16x16x32_bf16 v[102:105], v[180:183], v[212:215], v[102:105]
	v_mfma_f32_16x16x32_bf16 v[98:101], v[188:191], v[212:215], v[98:101]
	v_mfma_f32_16x16x32_bf16 v[86:89], v[180:183], v[220:223], v[86:89]
	v_mfma_f32_16x16x32_bf16 v[82:85], v[188:191], v[220:223], v[82:85]
	s_barrier
; #define PG8_STAGE(bufoff, gbase, voff) do { _Pragma("unroll") for (int _i = 0; _i < 2; ++_i) \
;         __builtin_amdgcn_global_load_lds((const unsigned*)((const char*)(gbase) + (voff)[_i]), (LAS unsigned*)(lds + (bufoff) + ldsw + _i * 8192), 16, 0, 0); } while (0)
; #define PG8_LDA(dst, b, h) do { _Pragma("unroll") for (int m = 0; m < 4; ++m) _Pragma("unroll") for (int k = 0; k < 2; ++k) dst[m][k] = *(const LAS bf16x8*)(lds + PG8_SA(b, h) + aoff + m * 2048 + k * 1024); } while (0)
; #define PG8_LDB(dst, b, h) do { _Pragma("unroll") for (int n = 0; n < 2; ++n) _Pragma("unroll") for (int k = 0; k < 2; ++k) dst[n][k] = *(const LAS bf16x8*)(lds + PG8_SB(b, h) + boff + n * 2048 + k * 1024); } while (0)
; #define PG8_MMA(ai, bj, At, Bt) do { __builtin_amdgcn_s_setprio(1); _Pragma("unroll") for (int m = 0; m < 4; ++m) _Pragma("unroll") for (int n = 0; n < 2; ++n) _Pragma("unroll") for (int k = 0; k < 2; ++k) \
;         acc[ai][bj][m][n] = __builtin_amdgcn_mfma_f32_16x16x32_bf16(Bt[n][k], At[m][k], acc[ai][bj][m][n], 0, 0, 0); __builtin_amdgcn_s_setprio(0); } while (0)
; #define PG8_WAIT_V(n) asm volatile("s_waitcnt vmcnt(" #n ")" ::: "memory")
; #define PG8_WAIT_L(n) asm volatile("s_waitcnt lgkmcnt(" #n ")" ::: "memory")
; #define PG8_BAR __builtin_amdgcn_s_barrier()
; #define PG8_SCHED __builtin_amdgcn_sched_barrier(0)
; template <class Epi, class Sched, bool ALIGN_EPI = false, bool SP2 = false>
; __device__ __forceinline__ void gemm_phase(LAS unsigned char* lds, const Gemm g, const Sched& S, const Epi& E) {
;     ...
;             PG8_LDB(B0, 0, 0); PG8_LDB(B1, 0, 1); PG8_SCHED; PG8_LDA(At, 0, 0); PG8_STAGE(PG8_SA(1, 1), a1 + hstep, voffA);
;             PG8_WAIT_V(8); PG8_WAIT_L(0); PG8_BAR; PG8_MMA(0, 0, At, B0); PG8_MMA(0, 1, At, B1); PG8_BAR; PG8_SCHED;
;     ...
;             PG8_LDA(At, 1, 1); PG8_STAGE(PG8_SB(1, 0), b3, voffB); PG8_STAGE(PG8_SB(1, 1), b3 + hstepB, voffB); PG8_STAGE(PG8_SA(1, 0), a3, voffA);
;             PG8_WAIT_V(8); PG8_WAIT_L(0); PG8_BAR; PG8_MMA(1, 0, At, B0); PG8_MMA(1, 1, At, B1); PG8_BAR; PG8_SCHED;
	s_add_i32 s22, s51, s25
	v_lshl_add_u64 v[166:167], v[166:167], 0, s[6:7]
	s_mov_b32 m0, s22
	ds_read_b128 v[192:195], v175 offset:49152
	ds_read_b128 v[196:199], v175 offset:50176
	ds_read_b128 v[200:203], v175 offset:51200
	ds_read_b128 v[204:207], v175 offset:52224
	ds_read_b128 v[208:211], v175 offset:53248
	ds_read_b128 v[212:215], v175 offset:54272
	ds_read_b128 v[216:219], v175 offset:55296
	ds_read_b128 v[220:223], v175 offset:56320
	global_load_lds_dwordx4 v[166:167], off
	s_add_i32 m0, s22, 0x2000
	s_add_u32 s20, s20, 0x80080
	v_lshl_add_u64 v[166:167], v[224:225], 0, s[6:7]
	s_addc_u32 s21, s21, 0
	s_add_i32 s22, s52, s25
	global_load_lds_dwordx4 v[166:167], off
	v_lshl_add_u64 v[166:167], s[20:21], 0, v[150:151]
	s_mov_b32 m0, s22
	s_nop 0
	global_load_lds_dwordx4 v[166:167], off
	v_lshl_add_u64 v[166:167], s[20:21], 0, v[146:147]
	s_add_i32 m0, s22, 0x2000
	s_nop 0
	global_load_lds_dwordx4 v[166:167], off
	v_lshl_add_u64 v[166:167], v[226:227], 0, s[6:7]
	s_mov_b32 m0, s39
	s_nop 0
	global_load_lds_dwordx4 v[166:167], off
	v_lshl_add_u64 v[166:167], v[228:229], 0, s[6:7]
	s_mov_b32 m0, s40
	s_nop 0
	global_load_lds_dwordx4 v[166:167], off
	s_waitcnt vmcnt(8)
	s_waitcnt lgkmcnt(0)
	s_barrier
	s_waitcnt lgkmcnt(0)
	v_mfma_f32_16x16x32_bf16 v[62:65], v[66:69], v[192:195], v[62:65]
	v_mfma_f32_16x16x32_bf16 v[58:61], v[74:77], v[192:195], v[58:61]
	v_mfma_f32_16x16x32_bf16 v[46:49], v[66:69], v[200:203], v[46:49]
	v_mfma_f32_16x16x32_bf16 v[42:45], v[74:77], v[200:203], v[42:45]
	v_mfma_f32_16x16x32_bf16 v[30:33], v[66:69], v[208:211], v[30:33]
	v_mfma_f32_16x16x32_bf16 v[26:29], v[74:77], v[208:211], v[26:29]
	v_mfma_f32_16x16x32_bf16 v[14:17], v[66:69], v[216:219], v[14:17]
	v_mfma_f32_16x16x32_bf16 v[10:13], v[74:77], v[216:219], v[10:13]
	v_mfma_f32_16x16x32_bf16 v[62:65], v[70:73], v[196:199], v[62:65]
	v_mfma_f32_16x16x32_bf16 v[58:61], v[78:81], v[196:199], v[58:61]
	v_mfma_f32_16x16x32_bf16 v[46:49], v[70:73], v[204:207], v[46:49]
	v_mfma_f32_16x16x32_bf16 v[42:45], v[78:81], v[204:207], v[42:45]
	v_mfma_f32_16x16x32_bf16 v[30:33], v[70:73], v[212:215], v[30:33]
	v_mfma_f32_16x16x32_bf16 v[26:29], v[78:81], v[212:215], v[26:29]
	v_mfma_f32_16x16x32_bf16 v[14:17], v[70:73], v[220:223], v[14:17]
	v_mfma_f32_16x16x32_bf16 v[10:13], v[78:81], v[220:223], v[10:13]
	v_mfma_f32_16x16x32_bf16 v[54:57], v[162:165], v[192:195], v[54:57]
	v_mfma_f32_16x16x32_bf16 v[50:53], v[184:187], v[192:195], v[50:53]
	v_mfma_f32_16x16x32_bf16 v[38:41], v[162:165], v[200:203], v[38:41]
	v_mfma_f32_16x16x32_bf16 v[34:37], v[184:187], v[200:203], v[34:37]
	v_mfma_f32_16x16x32_bf16 v[22:25], v[162:165], v[208:211], v[22:25]
	v_mfma_f32_16x16x32_bf16 v[18:21], v[184:187], v[208:211], v[18:21]
	v_mfma_f32_16x16x32_bf16 v[6:9], v[162:165], v[216:219], v[6:9]
	v_mfma_f32_16x16x32_bf16 v[2:5], v[184:187], v[216:219], v[2:5]
	v_mfma_f32_16x16x32_bf16 v[54:57], v[180:183], v[196:199], v[54:57]
	v_mfma_f32_16x16x32_bf16 v[50:53], v[188:191], v[196:199], v[50:53]
	v_mfma_f32_16x16x32_bf16 v[38:41], v[180:183], v[204:207], v[38:41]
	v_mfma_f32_16x16x32_bf16 v[34:37], v[188:191], v[204:207], v[34:37]
	v_mfma_f32_16x16x32_bf16 v[22:25], v[180:183], v[212:215], v[22:25]
	v_mfma_f32_16x16x32_bf16 v[18:21], v[188:191], v[212:215], v[18:21]
	v_mfma_f32_16x16x32_bf16 v[6:9], v[180:183], v[220:223], v[6:9]
	v_mfma_f32_16x16x32_bf16 v[2:5], v[188:191], v[220:223], v[2:5]
	s_barrier
	s_add_i32 s50, s50, 2
	s_add_u32 s48, s48, 0x100
	s_addc_u32 s49, s49, 0
	s_add_u32 s18, s18, 0x100
	s_addc_u32 s19, s19, 0
	s_cmp_lt_u32 s50, 30
.LBB0_2916:
	ds_read_b128 v[66:69], v173
	ds_read_b128 v[70:73], v173 offset:1024
	ds_read_b128 v[74:77], v173 offset:2048
	ds_read_b128 v[78:81], v173 offset:3072
	ds_read_b128 v[162:165], v174
	ds_read_b128 v[180:183], v174 offset:1024
	ds_read_b128 v[184:187], v174 offset:2048
	ds_read_b128 v[188:191], v174 offset:3072
	s_add_u32 s20, s18, 0xfff80080
	s_addc_u32 s21, s19, -1
	s_cmp_eq_u32 s50, 28
	s_cselect_b32 s23, s13, s21
	s_cselect_b32 s22, s46, s20
	s_cselect_b32 s21, s11, s49
	s_cselect_b32 s20, s47, s48
	v_lshl_add_u64 v[166:167], s[18:19], 0, v[156:157]
	s_add_i32 m0, s28, 0xc000
	ds_read_b128 v[192:195], v175
	ds_read_b128 v[196:199], v175 offset:1024
	ds_read_b128 v[200:203], v175 offset:2048
	ds_read_b128 v[204:207], v175 offset:3072
	ds_read_b128 v[208:211], v175 offset:4096
	ds_read_b128 v[212:215], v175 offset:5120
	ds_read_b128 v[216:219], v175 offset:6144
	ds_read_b128 v[220:223], v175 offset:7168
	global_load_lds_dwordx4 v[166:167], off
	v_lshl_add_u64 v[166:167], s[18:19], 0, v[154:155]
	s_add_i32 m0, s28, 0xe000
	s_nop 0
	global_load_lds_dwordx4 v[166:167], off
	s_waitcnt vmcnt(8)
	s_waitcnt lgkmcnt(0)
	s_barrier
; #define PG8_STAGE(bufoff, gbase, voff) do { _Pragma("unroll") for (int _i = 0; _i < 2; ++_i) \
;         __builtin_amdgcn_global_load_lds((const unsigned*)((const char*)(gbase) + (voff)[_i]), (LAS unsigned*)(lds + (bufoff) + ldsw + _i * 8192), 16, 0, 0); } while (0)
; #define PG8_LDA(dst, b, h) do { _Pragma("unroll") for (int m = 0; m < 4; ++m) _Pragma("unroll") for (int k = 0; k < 2; ++k) dst[m][k] = *(const LAS bf16x8*)(lds + PG8_SA(b, h) + aoff + m * 2048 + k * 1024); } while (0)
; #define PG8_MMA(ai, bj, At, Bt) do { __builtin_amdgcn_s_setprio(1); _Pragma("unroll") for (int m = 0; m < 4; ++m) _Pragma("unroll") for (int n = 0; n < 2; ++n) _Pragma("unroll") for (int k = 0; k < 2; ++k) \
;         acc[ai][bj][m][n] = __builtin_amdgcn_mfma_f32_16x16x32_bf16(Bt[n][k], At[m][k], acc[ai][bj][m][n], 0, 0, 0); __builtin_amdgcn_s_setprio(0); } while (0)
; #define PG8_WAIT_V(n) asm volatile("s_waitcnt vmcnt(" #n ")" ::: "memory")
; #define PG8_WAIT_L(n) asm volatile("s_waitcnt lgkmcnt(" #n ")" ::: "memory")
; #define PG8_BAR __builtin_amdgcn_s_barrier()
; #define PG8_SCHED __builtin_amdgcn_sched_barrier(0)
; template <class Epi, class Sched, bool ALIGN_EPI = false, bool SP2 = false>
; __device__ __forceinline__ void gemm_phase(LAS unsigned char* lds, const Gemm g, const Sched& S, const Epi& E) {
;     ...
;             PG8_WAIT_V(8); PG8_WAIT_L(0); PG8_BAR; PG8_MMA(0, 0, At, B0); PG8_MMA(0, 1, At, B1); PG8_BAR; PG8_SCHED;
;             PG8_LDA(At, 0, 1); PG8_STAGE(PG8_SB(0, 0), b2, voffB); PG8_STAGE(PG8_SB(0, 1), b2 + hstepB, voffB); PG8_STAGE(PG8_SA(0, 0), a2, voffA);
;             PG8_WAIT_V(8); PG8_WAIT_L(0); PG8_BAR; PG8_MMA(1, 0, At, B0); PG8_MMA(1, 1, At, B1); PG8_BAR; PG8_SCHED;
	s_waitcnt lgkmcnt(0)
	v_mfma_f32_16x16x32_bf16 v[142:145], v[66:69], v[192:195], v[142:145]
	v_mfma_f32_16x16x32_bf16 v[138:141], v[74:77], v[192:195], v[138:141]
	v_mfma_f32_16x16x32_bf16 v[126:129], v[66:69], v[200:203], v[126:129]
	v_mfma_f32_16x16x32_bf16 v[122:125], v[74:77], v[200:203], v[122:125]
	v_mfma_f32_16x16x32_bf16 v[110:113], v[66:69], v[208:211], v[110:113]
	v_mfma_f32_16x16x32_bf16 v[106:109], v[74:77], v[208:211], v[106:109]
	v_mfma_f32_16x16x32_bf16 v[94:97], v[66:69], v[216:219], v[94:97]
	v_mfma_f32_16x16x32_bf16 v[90:93], v[74:77], v[216:219], v[90:93]
	v_mfma_f32_16x16x32_bf16 v[142:145], v[70:73], v[196:199], v[142:145]
	v_mfma_f32_16x16x32_bf16 v[138:141], v[78:81], v[196:199], v[138:141]
	v_mfma_f32_16x16x32_bf16 v[126:129], v[70:73], v[204:207], v[126:129]
	v_mfma_f32_16x16x32_bf16 v[122:125], v[78:81], v[204:207], v[122:125]
	v_mfma_f32_16x16x32_bf16 v[110:113], v[70:73], v[212:215], v[110:113]
	v_mfma_f32_16x16x32_bf16 v[106:109], v[78:81], v[212:215], v[106:109]
	v_mfma_f32_16x16x32_bf16 v[94:97], v[70:73], v[220:223], v[94:97]
	v_mfma_f32_16x16x32_bf16 v[90:93], v[78:81], v[220:223], v[90:93]
	v_mfma_f32_16x16x32_bf16 v[134:137], v[162:165], v[192:195], v[134:137]
	v_mfma_f32_16x16x32_bf16 v[130:133], v[184:187], v[192:195], v[130:133]
	v_mfma_f32_16x16x32_bf16 v[118:121], v[162:165], v[200:203], v[118:121]
	v_mfma_f32_16x16x32_bf16 v[114:117], v[184:187], v[200:203], v[114:117]
	v_mfma_f32_16x16x32_bf16 v[102:105], v[162:165], v[208:211], v[102:105]
	v_mfma_f32_16x16x32_bf16 v[98:101], v[184:187], v[208:211], v[98:101]
	v_mfma_f32_16x16x32_bf16 v[86:89], v[162:165], v[216:219], v[86:89]
	v_mfma_f32_16x16x32_bf16 v[82:85], v[184:187], v[216:219], v[82:85]
	v_mfma_f32_16x16x32_bf16 v[134:137], v[180:183], v[196:199], v[134:137]
	v_mfma_f32_16x16x32_bf16 v[130:133], v[188:191], v[196:199], v[130:133]
	v_mfma_f32_16x16x32_bf16 v[118:121], v[180:183], v[204:207], v[118:121]
	v_mfma_f32_16x16x32_bf16 v[114:117], v[188:191], v[204:207], v[114:117]
	v_mfma_f32_16x16x32_bf16 v[102:105], v[180:183], v[212:215], v[102:105]
	v_mfma_f32_16x16x32_bf16 v[98:101], v[188:191], v[212:215], v[98:101]
	v_mfma_f32_16x16x32_bf16 v[86:89], v[180:183], v[220:223], v[86:89]
	v_mfma_f32_16x16x32_bf16 v[82:85], v[188:191], v[220:223], v[82:85]
	s_barrier
	s_add_i32 s51, s41, s25
	v_lshl_add_u64 v[166:167], s[20:21], 0, v[150:151]
	s_mov_b32 m0, s51
	ds_read_b128 v[192:195], v175 offset:16384
	ds_read_b128 v[196:199], v175 offset:17408
	ds_read_b128 v[200:203], v175 offset:18432
	ds_read_b128 v[204:207], v175 offset:19456
	ds_read_b128 v[208:211], v175 offset:20480
	ds_read_b128 v[212:215], v175 offset:21504
	ds_read_b128 v[216:219], v175 offset:22528
	ds_read_b128 v[220:223], v175 offset:23552
	global_load_lds_dwordx4 v[166:167], off
	s_add_i32 m0, s51, 0x2000
	s_add_u32 s52, s20, 0x80000
	v_lshl_add_u64 v[224:225], s[20:21], 0, v[146:147]
	s_addc_u32 s53, s21, 0
	s_add_i32 s51, s42, s25
	global_load_lds_dwordx4 v[224:225], off
	v_lshl_add_u64 v[226:227], s[52:53], 0, v[150:151]
	s_mov_b32 m0, s51
	v_lshl_add_u64 v[228:229], s[22:23], 0, v[148:149]
	global_load_lds_dwordx4 v[226:227], off
	v_lshl_add_u64 v[226:227], s[52:53], 0, v[146:147]
	s_add_i32 m0, s51, 0x2000
	s_nop 0
	global_load_lds_dwordx4 v[226:227], off
	v_lshl_add_u64 v[226:227], s[22:23], 0, v[152:153]
	s_mov_b32 m0, s28
	s_nop 0
	global_load_lds_dwordx4 v[226:227], off
	s_mov_b32 m0, s29
	s_nop 0
	global_load_lds_dwordx4 v[228:229], off
	s_waitcnt vmcnt(8)
	s_waitcnt lgkmcnt(0)
	s_barrier
	s_waitcnt lgkmcnt(0)
	v_mfma_f32_16x16x32_bf16 v[62:65], v[66:69], v[192:195], v[62:65]
	v_mfma_f32_16x16x32_bf16 v[58:61], v[74:77], v[192:195], v[58:61]
	v_mfma_f32_16x16x32_bf16 v[46:49], v[66:69], v[200:203], v[46:49]
	v_mfma_f32_16x16x32_bf16 v[42:45], v[74:77], v[200:203], v[42:45]
	v_mfma_f32_16x16x32_bf16 v[30:33], v[66:69], v[208:211], v[30:33]
	v_mfma_f32_16x16x32_bf16 v[26:29], v[74:77], v[208:211], v[26:29]
	v_mfma_f32_16x16x32_bf16 v[14:17], v[66:69], v[216:219], v[14:17]
	v_mfma_f32_16x16x32_bf16 v[10:13], v[74:77], v[216:219], v[10:13]
	v_mfma_f32_16x16x32_bf16 v[62:65], v[70:73], v[196:199], v[62:65]
	v_mfma_f32_16x16x32_bf16 v[58:61], v[78:81], v[196:199], v[58:61]
	v_mfma_f32_16x16x32_bf16 v[46:49], v[70:73], v[204:207], v[46:49]
	v_mfma_f32_16x16x32_bf16 v[42:45], v[78:81], v[204:207], v[42:45]
	v_mfma_f32_16x16x32_bf16 v[30:33], v[70:73], v[212:215], v[30:33]
	v_mfma_f32_16x16x32_bf16 v[26:29], v[78:81], v[212:215], v[26:29]
	v_mfma_f32_16x16x32_bf16 v[14:17], v[70:73], v[220:223], v[14:17]
	v_mfma_f32_16x16x32_bf16 v[10:13], v[78:81], v[220:223], v[10:13]
	v_mfma_f32_16x16x32_bf16 v[54:57], v[162:165], v[192:195], v[54:57]
	v_mfma_f32_16x16x32_bf16 v[50:53], v[184:187], v[192:195], v[50:53]
	v_mfma_f32_16x16x32_bf16 v[38:41], v[162:165], v[200:203], v[38:41]
	v_mfma_f32_16x16x32_bf16 v[34:37], v[184:187], v[200:203], v[34:37]
	v_mfma_f32_16x16x32_bf16 v[22:25], v[162:165], v[208:211], v[22:25]
	v_mfma_f32_16x16x32_bf16 v[18:21], v[184:187], v[208:211], v[18:21]
	v_mfma_f32_16x16x32_bf16 v[6:9], v[162:165], v[216:219], v[6:9]
	v_mfma_f32_16x16x32_bf16 v[2:5], v[184:187], v[216:219], v[2:5]
	v_mfma_f32_16x16x32_bf16 v[54:57], v[180:183], v[196:199], v[54:57]
	v_mfma_f32_16x16x32_bf16 v[50:53], v[188:191], v[196:199], v[50:53]
	v_mfma_f32_16x16x32_bf16 v[38:41], v[180:183], v[204:207], v[38:41]
	v_mfma_f32_16x16x32_bf16 v[34:37], v[188:191], v[204:207], v[34:37]
	v_mfma_f32_16x16x32_bf16 v[22:25], v[180:183], v[212:215], v[22:25]
	v_mfma_f32_16x16x32_bf16 v[18:21], v[188:191], v[212:215], v[18:21]
	v_mfma_f32_16x16x32_bf16 v[6:9], v[180:183], v[220:223], v[6:9]
	v_mfma_f32_16x16x32_bf16 v[2:5], v[188:191], v[220:223], v[2:5]
	s_barrier
; #define PG8_STAGE(bufoff, gbase, voff) do { _Pragma("unroll") for (int _i = 0; _i < 2; ++_i) \
;         __builtin_amdgcn_global_load_lds((const unsigned*)((const char*)(gbase) + (voff)[_i]), (LAS unsigned*)(lds + (bufoff) + ldsw + _i * 8192), 16, 0, 0); } while (0)
; #define PG8_LDA(dst, b, h) do { _Pragma("unroll") for (int m = 0; m < 4; ++m) _Pragma("unroll") for (int k = 0; k < 2; ++k) dst[m][k] = *(const LAS bf16x8*)(lds + PG8_SA(b, h) + aoff + m * 2048 + k * 1024); } while (0)
; #define PG8_LDB(dst, b, h) do { _Pragma("unroll") for (int n = 0; n < 2; ++n) _Pragma("unroll") for (int k = 0; k < 2; ++k) dst[n][k] = *(const LAS bf16x8*)(lds + PG8_SB(b, h) + boff + n * 2048 + k * 1024); } while (0)
; #define PG8_MMA(ai, bj, At, Bt) do { __builtin_amdgcn_s_setprio(1); _Pragma("unroll") for (int m = 0; m < 4; ++m) _Pragma("unroll") for (int n = 0; n < 2; ++n) _Pragma("unroll") for (int k = 0; k < 2; ++k) \
;         acc[ai][bj][m][n] = __builtin_amdgcn_mfma_f32_16x16x32_bf16(Bt[n][k], At[m][k], acc[ai][bj][m][n], 0, 0, 0); __builtin_amdgcn_s_setprio(0); } while (0)
; #define PG8_WAIT_V(n) asm volatile("s_waitcnt vmcnt(" #n ")" ::: "memory")
; #define PG8_WAIT_L(n) asm volatile("s_waitcnt lgkmcnt(" #n ")" ::: "memory")
; #define PG8_BAR __builtin_amdgcn_s_barrier()
; #define PG8_SCHED __builtin_amdgcn_sched_barrier(0)
; template <class Epi, class Sched, bool ALIGN_EPI = false, bool SP2 = false>
; __device__ __forceinline__ void gemm_phase(LAS unsigned char* lds, const Gemm g, const Sched& S, const Epi& E) {
;     ...
;             PG8_LDB(B0, 1, 0); PG8_LDB(B1, 1, 1); PG8_SCHED; PG8_LDA(At, 1, 0); PG8_STAGE(PG8_SA(0, 1), a2 + hstep, voffA);
;             PG8_WAIT_V(8); PG8_WAIT_L(0); PG8_BAR; PG8_MMA(0, 0, At, B0); PG8_MMA(0, 1, At, B1); PG8_BAR; PG8_SCHED;
	s_add_i32 s51, 0, 0x18000
	s_add_i32 s52, 0, 0x1c000
	v_add_u32_e32 v78, s51, v169
	v_add_u32_e32 v168, s52, v169
	ds_read_b128 v[66:69], v78
	ds_read_b128 v[70:73], v78 offset:1024
	ds_read_b128 v[74:77], v78 offset:2048
	ds_read_b128 v[78:81], v78 offset:3072
	ds_read_b128 v[162:165], v168
	ds_read_b128 v[180:183], v168 offset:1024
	ds_read_b128 v[184:187], v168 offset:2048
	ds_read_b128 v[188:191], v168 offset:3072
	s_add_u32 s22, s22, 0x80000
	s_addc_u32 s23, s23, 0
	s_mov_b32 m0, s30
	v_lshl_add_u64 v[230:231], s[22:23], 0, v[152:153]
	ds_read_b128 v[192:195], v175 offset:32768
	ds_read_b128 v[196:199], v175 offset:33792
	ds_read_b128 v[200:203], v175 offset:34816
	ds_read_b128 v[204:207], v175 offset:35840
	ds_read_b128 v[208:211], v175 offset:36864
	ds_read_b128 v[212:215], v175 offset:37888
	ds_read_b128 v[216:219], v175 offset:38912
	ds_read_b128 v[220:223], v175 offset:39936
	global_load_lds_dwordx4 v[230:231], off
	v_lshl_add_u64 v[230:231], s[22:23], 0, v[148:149]
	s_mov_b32 m0, s31
	s_nop 0
	global_load_lds_dwordx4 v[230:231], off
	s_waitcnt vmcnt(8)
	s_waitcnt lgkmcnt(0)
	s_barrier
	s_waitcnt lgkmcnt(0)
	v_mfma_f32_16x16x32_bf16 v[142:145], v[66:69], v[192:195], v[142:145]
	v_mfma_f32_16x16x32_bf16 v[138:141], v[74:77], v[192:195], v[138:141]
	v_mfma_f32_16x16x32_bf16 v[126:129], v[66:69], v[200:203], v[126:129]
	v_mfma_f32_16x16x32_bf16 v[122:125], v[74:77], v[200:203], v[122:125]
	v_mfma_f32_16x16x32_bf16 v[110:113], v[66:69], v[208:211], v[110:113]
	v_mfma_f32_16x16x32_bf16 v[106:109], v[74:77], v[208:211], v[106:109]
	v_mfma_f32_16x16x32_bf16 v[94:97], v[66:69], v[216:219], v[94:97]
	v_mfma_f32_16x16x32_bf16 v[90:93], v[74:77], v[216:219], v[90:93]
	v_mfma_f32_16x16x32_bf16 v[142:145], v[70:73], v[196:199], v[142:145]
	v_mfma_f32_16x16x32_bf16 v[138:141], v[78:81], v[196:199], v[138:141]
	v_mfma_f32_16x16x32_bf16 v[126:129], v[70:73], v[204:207], v[126:129]
	v_mfma_f32_16x16x32_bf16 v[122:125], v[78:81], v[204:207], v[122:125]
	v_mfma_f32_16x16x32_bf16 v[110:113], v[70:73], v[212:215], v[110:113]
	v_mfma_f32_16x16x32_bf16 v[106:109], v[78:81], v[212:215], v[106:109]
	v_mfma_f32_16x16x32_bf16 v[94:97], v[70:73], v[220:223], v[94:97]
	v_mfma_f32_16x16x32_bf16 v[90:93], v[78:81], v[220:223], v[90:93]
	v_mfma_f32_16x16x32_bf16 v[134:137], v[162:165], v[192:195], v[134:137]
	v_mfma_f32_16x16x32_bf16 v[130:133], v[184:187], v[192:195], v[130:133]
	v_mfma_f32_16x16x32_bf16 v[118:121], v[162:165], v[200:203], v[118:121]
	v_mfma_f32_16x16x32_bf16 v[114:117], v[184:187], v[200:203], v[114:117]
	v_mfma_f32_16x16x32_bf16 v[102:105], v[162:165], v[208:211], v[102:105]
	v_mfma_f32_16x16x32_bf16 v[98:101], v[184:187], v[208:211], v[98:101]
	v_mfma_f32_16x16x32_bf16 v[86:89], v[162:165], v[216:219], v[86:89]
	v_mfma_f32_16x16x32_bf16 v[82:85], v[184:187], v[216:219], v[82:85]
	v_mfma_f32_16x16x32_bf16 v[134:137], v[180:183], v[196:199], v[134:137]
	v_mfma_f32_16x16x32_bf16 v[130:133], v[188:191], v[196:199], v[130:133]
	v_mfma_f32_16x16x32_bf16 v[118:121], v[180:183], v[204:207], v[118:121]
	v_mfma_f32_16x16x32_bf16 v[114:117], v[188:191], v[204:207], v[114:117]
	v_mfma_f32_16x16x32_bf16 v[102:105], v[180:183], v[212:215], v[102:105]
	v_mfma_f32_16x16x32_bf16 v[98:101], v[188:191], v[212:215], v[98:101]
	v_mfma_f32_16x16x32_bf16 v[86:89], v[180:183], v[220:223], v[86:89]
	v_mfma_f32_16x16x32_bf16 v[82:85], v[188:191], v[220:223], v[82:85]
	s_barrier
; #define PG8_STAGE(bufoff, gbase, voff) do { _Pragma("unroll") for (int _i = 0; _i < 2; ++_i) \
;         __builtin_amdgcn_global_load_lds((const unsigned*)((const char*)(gbase) + (voff)[_i]), (LAS unsigned*)(lds + (bufoff) + ldsw + _i * 8192), 16, 0, 0); } while (0)
; #define PG8_LDA(dst, b, h) do { _Pragma("unroll") for (int m = 0; m < 4; ++m) _Pragma("unroll") for (int k = 0; k < 2; ++k) dst[m][k] = *(const LAS bf16x8*)(lds + PG8_SA(b, h) + aoff + m * 2048 + k * 1024); } while (0)
; #define PG8_MMA(ai, bj, At, Bt) do { __builtin_amdgcn_s_setprio(1); _Pragma("unroll") for (int m = 0; m < 4; ++m) _Pragma("unroll") for (int n = 0; n < 2; ++n) _Pragma("unroll") for (int k = 0; k < 2; ++k) \
;         acc[ai][bj][m][n] = __builtin_amdgcn_mfma_f32_16x16x32_bf16(Bt[n][k], At[m][k], acc[ai][bj][m][n], 0, 0, 0); __builtin_amdgcn_s_setprio(0); } while (0)
; #define PG8_WAIT_V(n) asm volatile("s_waitcnt vmcnt(" #n ")" ::: "memory")
; #define PG8_WAIT_L(n) asm volatile("s_waitcnt lgkmcnt(" #n ")" ::: "memory")
; #define PG8_BAR __builtin_amdgcn_s_barrier()
; #define PG8_SCHED __builtin_amdgcn_sched_barrier(0)
; template <class Epi, class Sched, bool ALIGN_EPI = false, bool SP2 = false>
; __device__ __forceinline__ void gemm_phase(LAS unsigned char* lds, const Gemm g, const Sched& S, const Epi& E) {
;     ...
;         for (int t = 0; t < nt; t += 2) {
;     ...
;             PG8_LDA(At, 1, 1); PG8_STAGE(PG8_SB(1, 0), b3, voffB); PG8_STAGE(PG8_SB(1, 1), b3 + hstepB, voffB); PG8_STAGE(PG8_SA(1, 0), a3, voffA);
;             PG8_WAIT_V(8); PG8_WAIT_L(0); PG8_BAR; PG8_MMA(1, 0, At, B0); PG8_MMA(1, 1, At, B1); PG8_BAR; PG8_SCHED;
	s_add_i32 s22, s51, s25
	v_lshl_add_u64 v[166:167], v[166:167], 0, s[6:7]
	s_mov_b32 m0, s22
	ds_read_b128 v[192:195], v175 offset:49152
	ds_read_b128 v[196:199], v175 offset:50176
	ds_read_b128 v[200:203], v175 offset:51200
	ds_read_b128 v[204:207], v175 offset:52224
	ds_read_b128 v[208:211], v175 offset:53248
	ds_read_b128 v[212:215], v175 offset:54272
	ds_read_b128 v[216:219], v175 offset:55296
	ds_read_b128 v[220:223], v175 offset:56320
	global_load_lds_dwordx4 v[166:167], off
	s_add_i32 m0, s22, 0x2000
	s_add_u32 s20, s20, 0x80080
	v_lshl_add_u64 v[166:167], v[224:225], 0, s[6:7]
	s_addc_u32 s21, s21, 0
	s_add_i32 s22, s52, s25
	global_load_lds_dwordx4 v[166:167], off
	v_lshl_add_u64 v[166:167], s[20:21], 0, v[150:151]
	s_mov_b32 m0, s22
	s_nop 0
	global_load_lds_dwordx4 v[166:167], off
	v_lshl_add_u64 v[166:167], s[20:21], 0, v[146:147]
	s_add_i32 m0, s22, 0x2000
	s_nop 0
	global_load_lds_dwordx4 v[166:167], off
	v_lshl_add_u64 v[166:167], v[226:227], 0, s[6:7]
	s_mov_b32 m0, s39
	s_nop 0
	global_load_lds_dwordx4 v[166:167], off
	v_lshl_add_u64 v[166:167], v[228:229], 0, s[6:7]
	s_mov_b32 m0, s40
	s_nop 0
	global_load_lds_dwordx4 v[166:167], off
	s_waitcnt vmcnt(8)
	s_waitcnt lgkmcnt(0)
	s_barrier
	s_waitcnt lgkmcnt(0)
	v_mfma_f32_16x16x32_bf16 v[62:65], v[66:69], v[192:195], v[62:65]
	v_mfma_f32_16x16x32_bf16 v[58:61], v[74:77], v[192:195], v[58:61]
	v_mfma_f32_16x16x32_bf16 v[46:49], v[66:69], v[200:203], v[46:49]
	v_mfma_f32_16x16x32_bf16 v[42:45], v[74:77], v[200:203], v[42:45]
	v_mfma_f32_16x16x32_bf16 v[30:33], v[66:69], v[208:211], v[30:33]
	v_mfma_f32_16x16x32_bf16 v[26:29], v[74:77], v[208:211], v[26:29]
	v_mfma_f32_16x16x32_bf16 v[14:17], v[66:69], v[216:219], v[14:17]
	v_mfma_f32_16x16x32_bf16 v[10:13], v[74:77], v[216:219], v[10:13]
	v_mfma_f32_16x16x32_bf16 v[62:65], v[70:73], v[196:199], v[62:65]
	v_mfma_f32_16x16x32_bf16 v[58:61], v[78:81], v[196:199], v[58:61]
	v_mfma_f32_16x16x32_bf16 v[46:49], v[70:73], v[204:207], v[46:49]
	v_mfma_f32_16x16x32_bf16 v[42:45], v[78:81], v[204:207], v[42:45]
	v_mfma_f32_16x16x32_bf16 v[30:33], v[70:73], v[212:215], v[30:33]
	v_mfma_f32_16x16x32_bf16 v[26:29], v[78:81], v[212:215], v[26:29]
	v_mfma_f32_16x16x32_bf16 v[14:17], v[70:73], v[220:223], v[14:17]
	v_mfma_f32_16x16x32_bf16 v[10:13], v[78:81], v[220:223], v[10:13]
	v_mfma_f32_16x16x32_bf16 v[54:57], v[162:165], v[192:195], v[54:57]
	v_mfma_f32_16x16x32_bf16 v[50:53], v[184:187], v[192:195], v[50:53]
	v_mfma_f32_16x16x32_bf16 v[38:41], v[162:165], v[200:203], v[38:41]
	v_mfma_f32_16x16x32_bf16 v[34:37], v[184:187], v[200:203], v[34:37]
	v_mfma_f32_16x16x32_bf16 v[22:25], v[162:165], v[208:211], v[22:25]
	v_mfma_f32_16x16x32_bf16 v[18:21], v[184:187], v[208:211], v[18:21]
	v_mfma_f32_16x16x32_bf16 v[6:9], v[162:165], v[216:219], v[6:9]
	v_mfma_f32_16x16x32_bf16 v[2:5], v[184:187], v[216:219], v[2:5]
	v_mfma_f32_16x16x32_bf16 v[54:57], v[180:183], v[196:199], v[54:57]
	v_mfma_f32_16x16x32_bf16 v[50:53], v[188:191], v[196:199], v[50:53]
	v_mfma_f32_16x16x32_bf16 v[38:41], v[180:183], v[204:207], v[38:41]
	v_mfma_f32_16x16x32_bf16 v[34:37], v[188:191], v[204:207], v[34:37]
	v_mfma_f32_16x16x32_bf16 v[22:25], v[180:183], v[212:215], v[22:25]
	v_mfma_f32_16x16x32_bf16 v[18:21], v[188:191], v[212:215], v[18:21]
	v_mfma_f32_16x16x32_bf16 v[6:9], v[180:183], v[220:223], v[6:9]
	v_mfma_f32_16x16x32_bf16 v[2:5], v[188:191], v[220:223], v[2:5]
	s_barrier
	s_add_i32 s50, s50, 2
	s_add_u32 s48, s48, 0x100
	s_addc_u32 s49, s49, 0
	s_add_u32 s18, s18, 0x100
	s_addc_u32 s19, s19, 0
	s_cmp_lt_u32 s50, 30
	s_cbranch_scc1 .LBB0_2916
	s_andn2_b64 vcc, exec, s[8:9]
	s_cbranch_vccnz .LBB0_2919
	s_barrier

;     __device__ bool next(int i, Unit& u) const { if (i != 0 || c >= 128) return false; const int t = c >> 2; u.pm = t & 3; u.pn = t >> 2; u.koff = koff_bytes; u.q = c & 3; return true; }
; #define PG8_STAGE(bufoff, gbase, voff) do { _Pragma("unroll") for (int _i = 0; _i < 2; ++_i) \
;         __builtin_amdgcn_global_load_lds((const unsigned*)((const char*)(gbase) + (voff)[_i]), (LAS unsigned*)(lds + (bufoff) + ldsw + _i * 8192), 16, 0, 0); } while (0)
; #define PG8_LDA(dst, b, h) do { _Pragma("unroll") for (int m = 0; m < 4; ++m) _Pragma("unroll") for (int k = 0; k < 2; ++k) dst[m][k] = *(const LAS bf16x8*)(lds + PG8_SA(b, h) + aoff + m * 2048 + k * 1024); } while (0)
; #define PG8_LDB(dst, b, h) do { _Pragma("unroll") for (int n = 0; n < 2; ++n) _Pragma("unroll") for (int k = 0; k < 2; ++k) dst[n][k] = *(const LAS bf16x8*)(lds + PG8_SB(b, h) + boff + n * 2048 + k * 1024); } while (0)
; #define PG8_WAIT_V(n) asm volatile("s_waitcnt vmcnt(" #n ")" ::: "memory")
; template <class Epi, class Sched, bool ALIGN_EPI = false, bool SP2 = false>
; __device__ __forceinline__ void gemm_phase(LAS unsigned char* lds, const Gemm g, const Sched& S, const Epi& E) {
;     ...
;         const bool has_next = S.next(ui + 1, nxt);
;         const char* nA = has_next ? (const char*)g.A + (size_t)nxt.pm * tstep + nxt.koff : cA; const char* nB = has_next ? (const char*)g.Bt + (size_t)nxt.pn * tstep + nxt.koff : cB;
;         for (int t = 0; t < nt; t += 2) {
;             const bool last = (t == nt - 2);
;             const char* a1 = cA + (size_t)(t + 1) * kstep;
;             const char* a2 = last ? nA : cA + (size_t)(t + 2) * kstep; const char* b2 = last ? nB : cB + (size_t)(t + 2) * kstep;
;             const char* a3 = a2 + kstep; const char* b3 = b2 + kstep;
;             if (last && has_next) S.a_ready(nxt);
;             if constexpr (SP2) {
;             PG8_LDB(B0, 0, 0); PG8_LDB(B1, 0, 1); PG8_SCHED; PG8_LDA(At, 0, 0); PG8_STAGE(PG8_SA(1, 1), a1 + hstep, voffA);
;             PG8_WAIT_V(8); PG8_WAIT_L(0); PG8_BAR; PG8_MMA(0, 0, At, B0); PG8_MMA(0, 1, At, B1); PG8_BAR; PG8_SCHED;
;             PG8_LDA(At, 0, 1); PG8_STAGE(PG8_SB(0, 0), b2, voffB); PG8_STAGE(PG8_SB(0, 1), b2 + hstepB, voffB); PG8_STAGE(PG8_SA(0, 0), a2, voffA);
;             PG8_WAIT_V(8); PG8_WAIT_L(0); PG8_BAR; PG8_MMA(1, 0, At, B0); PG8_MMA(1, 1, At, B1); PG8_BAR; PG8_SCHED;
.LBB0_3001:
	s_add_u32 s13, s16, 0x100
	s_addc_u32 s39, s17, 0
	s_mov_b32 s40, -2
	s_waitcnt vmcnt(0)
	ds_read_b128 v[152:155], v147
	ds_read_b128 v[156:159], v147 offset:1024
	ds_read_b128 v[160:163], v147 offset:2048
	ds_read_b128 v[164:167], v147 offset:3072
	ds_read_b128 v[168:171], v148
	ds_read_b128 v[172:175], v148 offset:1024
	ds_read_b128 v[176:179], v148 offset:2048
	ds_read_b128 v[180:183], v148 offset:3072
	s_add_u32 s16, s14, 0x100
	s_addc_u32 s17, s15, 0
	s_cmpk_eq_i32 s40, 0x54
	s_cselect_b32 s21, s11, s17
	s_cselect_b32 s20, s10, s16
	s_cselect_b32 s19, s3, s39
	s_cselect_b32 s18, s2, s13
	v_lshl_add_u64 v[216:217], s[14:15], 0, v[138:139]
	s_add_i32 m0, s24, 0xc000
	ds_read_b128 v[184:187], v149
	ds_read_b128 v[188:191], v149 offset:1024
	ds_read_b128 v[192:195], v149 offset:2048
	ds_read_b128 v[196:199], v149 offset:3072
	ds_read_b128 v[200:203], v149 offset:4096
	ds_read_b128 v[204:207], v149 offset:5120
	ds_read_b128 v[208:211], v149 offset:6144
	ds_read_b128 v[212:215], v149 offset:7168
	global_load_lds_dwordx4 v[216:217], off
	v_lshl_add_u64 v[216:217], s[14:15], 0, v[136:137]
	s_add_i32 m0, s24, 0xe000
	s_nop 0
	global_load_lds_dwordx4 v[216:217], off
	s_waitcnt lgkmcnt(0)
	s_barrier
	s_waitcnt lgkmcnt(0)
	v_mfma_f32_16x16x32_bf16 v[124:127], v[152:155], v[184:187], 0
	v_mfma_f32_16x16x32_bf16 v[120:123], v[160:163], v[184:187], 0
	v_mfma_f32_16x16x32_bf16 v[112:115], v[152:155], v[192:195], 0
	v_mfma_f32_16x16x32_bf16 v[104:107], v[160:163], v[192:195], 0
	v_mfma_f32_16x16x32_bf16 v[92:95], v[152:155], v[200:203], 0
	v_mfma_f32_16x16x32_bf16 v[88:91], v[160:163], v[200:203], 0
	v_mfma_f32_16x16x32_bf16 v[76:79], v[152:155], v[208:211], 0
	v_mfma_f32_16x16x32_bf16 v[72:75], v[160:163], v[208:211], 0
	v_mfma_f32_16x16x32_bf16 v[124:127], v[156:159], v[188:191], v[124:127]
	v_mfma_f32_16x16x32_bf16 v[120:123], v[164:167], v[188:191], v[120:123]
	v_mfma_f32_16x16x32_bf16 v[112:115], v[156:159], v[196:199], v[112:115]
	v_mfma_f32_16x16x32_bf16 v[104:107], v[164:167], v[196:199], v[104:107]
	v_mfma_f32_16x16x32_bf16 v[92:95], v[156:159], v[204:207], v[92:95]
	v_mfma_f32_16x16x32_bf16 v[88:91], v[164:167], v[204:207], v[88:91]
	v_mfma_f32_16x16x32_bf16 v[76:79], v[156:159], v[212:215], v[76:79]
	v_mfma_f32_16x16x32_bf16 v[72:75], v[164:167], v[212:215], v[72:75]
	v_mfma_f32_16x16x32_bf16 v[116:119], v[168:171], v[184:187], 0
	v_mfma_f32_16x16x32_bf16 v[108:111], v[176:179], v[184:187], 0
	v_mfma_f32_16x16x32_bf16 v[100:103], v[168:171], v[192:195], 0
	v_mfma_f32_16x16x32_bf16 v[96:99], v[176:179], v[192:195], 0
	v_mfma_f32_16x16x32_bf16 v[84:87], v[168:171], v[200:203], 0
	v_mfma_f32_16x16x32_bf16 v[80:83], v[176:179], v[200:203], 0
	v_mfma_f32_16x16x32_bf16 v[68:71], v[168:171], v[208:211], 0
	v_mfma_f32_16x16x32_bf16 v[64:67], v[176:179], v[208:211], 0
	v_mfma_f32_16x16x32_bf16 v[116:119], v[172:175], v[188:191], v[116:119]
	v_mfma_f32_16x16x32_bf16 v[108:111], v[180:183], v[188:191], v[108:111]
	v_mfma_f32_16x16x32_bf16 v[100:103], v[172:175], v[196:199], v[100:103]
	v_mfma_f32_16x16x32_bf16 v[96:99], v[180:183], v[196:199], v[96:99]
	v_mfma_f32_16x16x32_bf16 v[84:87], v[172:175], v[204:207], v[84:87]
	v_mfma_f32_16x16x32_bf16 v[80:83], v[180:183], v[204:207], v[80:83]
	v_mfma_f32_16x16x32_bf16 v[68:71], v[172:175], v[212:215], v[68:71]
	v_mfma_f32_16x16x32_bf16 v[64:67], v[180:183], v[212:215], v[64:67]
	s_barrier
	s_add_i32 s14, s34, s23
	v_lshl_add_u64 v[216:217], s[18:19], 0, v[130:131]
	s_mov_b32 m0, s14
	ds_read_b128 v[184:187], v149 offset:16384
	ds_read_b128 v[188:191], v149 offset:17408
	ds_read_b128 v[192:195], v149 offset:18432
	ds_read_b128 v[196:199], v149 offset:19456
	ds_read_b128 v[200:203], v149 offset:20480
	ds_read_b128 v[204:207], v149 offset:21504
	ds_read_b128 v[208:211], v149 offset:22528
	ds_read_b128 v[212:215], v149 offset:23552
	global_load_lds_dwordx4 v[216:217], off
	s_add_i32 m0, s14, 0x2000
	s_add_u32 s14, s18, 0x58000
	v_lshl_add_u64 v[218:219], s[18:19], 0, v[134:135]
	s_addc_u32 s15, s19, 0
	s_add_i32 s41, s35, s23
	global_load_lds_dwordx4 v[218:219], off
	v_lshl_add_u64 v[220:221], s[14:15], 0, v[130:131]
	s_mov_b32 m0, s41
	v_lshl_add_u64 v[222:223], s[20:21], 0, v[132:133]
	global_load_lds_dwordx4 v[220:221], off
	v_lshl_add_u64 v[220:221], s[14:15], 0, v[134:135]
	s_add_i32 m0, s41, 0x2000
	s_nop 0
	global_load_lds_dwordx4 v[220:221], off
	v_lshl_add_u64 v[220:221], s[20:21], 0, v[128:129]
	s_mov_b32 m0, s24
	s_nop 0
	global_load_lds_dwordx4 v[220:221], off
	s_mov_b32 m0, s25
	s_nop 0
	global_load_lds_dwordx4 v[222:223], off
	s_waitcnt lgkmcnt(0)
	s_barrier
; #define PG8_STAGE(bufoff, gbase, voff) do { _Pragma("unroll") for (int _i = 0; _i < 2; ++_i) \
;         __builtin_amdgcn_global_load_lds((const unsigned*)((const char*)(gbase) + (voff)[_i]), (LAS unsigned*)(lds + (bufoff) + ldsw + _i * 8192), 16, 0, 0); } while (0)
; #define PG8_LDA(dst, b, h) do { _Pragma("unroll") for (int m = 0; m < 4; ++m) _Pragma("unroll") for (int k = 0; k < 2; ++k) dst[m][k] = *(const LAS bf16x8*)(lds + PG8_SA(b, h) + aoff + m * 2048 + k * 1024); } while (0)
; #define PG8_LDB(dst, b, h) do { _Pragma("unroll") for (int n = 0; n < 2; ++n) _Pragma("unroll") for (int k = 0; k < 2; ++k) dst[n][k] = *(const LAS bf16x8*)(lds + PG8_SB(b, h) + boff + n * 2048 + k * 1024); } while (0)
; #define PG8_MMA(ai, bj, At, Bt) do { __builtin_amdgcn_s_setprio(1); _Pragma("unroll") for (int m = 0; m < 4; ++m) _Pragma("unroll") for (int n = 0; n < 2; ++n) _Pragma("unroll") for (int k = 0; k < 2; ++k) \
;         acc[ai][bj][m][n] = __builtin_amdgcn_mfma_f32_16x16x32_bf16(Bt[n][k], At[m][k], acc[ai][bj][m][n], 0, 0, 0); __builtin_amdgcn_s_setprio(0); } while (0)
; #define PG8_WAIT_V(n) asm volatile("s_waitcnt vmcnt(" #n ")" ::: "memory")
; #define PG8_WAIT_L(n) asm volatile("s_waitcnt lgkmcnt(" #n ")" ::: "memory")
; #define PG8_BAR __builtin_amdgcn_s_barrier()
; #define PG8_SCHED __builtin_amdgcn_sched_barrier(0)
; template <class Epi, class Sched, bool ALIGN_EPI = false, bool SP2 = false>
; __device__ __forceinline__ void gemm_phase(LAS unsigned char* lds, const Gemm g, const Sched& S, const Epi& E) {
;     ...
;             PG8_WAIT_V(8); PG8_WAIT_L(0); PG8_BAR; PG8_MMA(1, 0, At, B0); PG8_MMA(1, 1, At, B1); PG8_BAR; PG8_SCHED;
;             PG8_LDB(B0, 1, 0); PG8_LDB(B1, 1, 1); PG8_SCHED; PG8_LDA(At, 1, 0); PG8_STAGE(PG8_SA(0, 1), a2 + hstep, voffA);
;             PG8_WAIT_V(8); PG8_WAIT_L(0); PG8_BAR; PG8_MMA(0, 0, At, B0); PG8_MMA(0, 1, At, B1); PG8_BAR; PG8_SCHED;
	s_waitcnt lgkmcnt(0)
	v_mfma_f32_16x16x32_bf16 v[60:63], v[152:155], v[184:187], 0
	v_mfma_f32_16x16x32_bf16 v[56:59], v[160:163], v[184:187], 0
	v_mfma_f32_16x16x32_bf16 v[44:47], v[152:155], v[192:195], 0
	v_mfma_f32_16x16x32_bf16 v[40:43], v[160:163], v[192:195], 0
	v_mfma_f32_16x16x32_bf16 v[28:31], v[152:155], v[200:203], 0
	v_mfma_f32_16x16x32_bf16 v[24:27], v[160:163], v[200:203], 0
	v_mfma_f32_16x16x32_bf16 v[12:15], v[152:155], v[208:211], 0
	v_mfma_f32_16x16x32_bf16 v[8:11], v[160:163], v[208:211], 0
	v_mfma_f32_16x16x32_bf16 v[60:63], v[156:159], v[188:191], v[60:63]
	v_mfma_f32_16x16x32_bf16 v[56:59], v[164:167], v[188:191], v[56:59]
	v_mfma_f32_16x16x32_bf16 v[44:47], v[156:159], v[196:199], v[44:47]
	v_mfma_f32_16x16x32_bf16 v[40:43], v[164:167], v[196:199], v[40:43]
	v_mfma_f32_16x16x32_bf16 v[28:31], v[156:159], v[204:207], v[28:31]
	v_mfma_f32_16x16x32_bf16 v[24:27], v[164:167], v[204:207], v[24:27]
	v_mfma_f32_16x16x32_bf16 v[12:15], v[156:159], v[212:215], v[12:15]
	v_mfma_f32_16x16x32_bf16 v[8:11], v[164:167], v[212:215], v[8:11]
	v_mfma_f32_16x16x32_bf16 v[52:55], v[168:171], v[184:187], 0
	v_mfma_f32_16x16x32_bf16 v[48:51], v[176:179], v[184:187], 0
	v_mfma_f32_16x16x32_bf16 v[36:39], v[168:171], v[192:195], 0
	v_mfma_f32_16x16x32_bf16 v[32:35], v[176:179], v[192:195], 0
	v_mfma_f32_16x16x32_bf16 v[20:23], v[168:171], v[200:203], 0
	v_mfma_f32_16x16x32_bf16 v[16:19], v[176:179], v[200:203], 0
	v_mfma_f32_16x16x32_bf16 v[4:7], v[168:171], v[208:211], 0
	v_mfma_f32_16x16x32_bf16 v[0:3], v[176:179], v[208:211], 0
	v_mfma_f32_16x16x32_bf16 v[52:55], v[172:175], v[188:191], v[52:55]
	v_mfma_f32_16x16x32_bf16 v[48:51], v[180:183], v[188:191], v[48:51]
	v_mfma_f32_16x16x32_bf16 v[36:39], v[172:175], v[196:199], v[36:39]
	v_mfma_f32_16x16x32_bf16 v[32:35], v[180:183], v[196:199], v[32:35]
	v_mfma_f32_16x16x32_bf16 v[20:23], v[172:175], v[204:207], v[20:23]
	v_mfma_f32_16x16x32_bf16 v[16:19], v[180:183], v[204:207], v[16:19]
	v_mfma_f32_16x16x32_bf16 v[4:7], v[172:175], v[212:215], v[4:7]
	v_mfma_f32_16x16x32_bf16 v[0:3], v[180:183], v[212:215], v[0:3]
	s_barrier
	s_add_i32 s41, 0, 0x18000
	s_add_i32 s42, 0, 0x1c000
	v_add_u32_e32 v164, s41, v144
	v_add_u32_e32 v180, s42, v144
	ds_read_b128 v[152:155], v164
	ds_read_b128 v[156:159], v164 offset:1024
	ds_read_b128 v[160:163], v164 offset:2048
	ds_read_b128 v[164:167], v164 offset:3072
	ds_read_b128 v[168:171], v180
	ds_read_b128 v[172:175], v180 offset:1024
	ds_read_b128 v[176:179], v180 offset:2048
	ds_read_b128 v[180:183], v180 offset:3072
	s_add_u32 s14, s20, 0x160000
	s_addc_u32 s15, s21, 0
	s_mov_b32 m0, s26
	v_lshl_add_u64 v[224:225], s[14:15], 0, v[128:129]
	ds_read_b128 v[184:187], v149 offset:32768
	ds_read_b128 v[188:191], v149 offset:33792
	ds_read_b128 v[192:195], v149 offset:34816
	ds_read_b128 v[196:199], v149 offset:35840
	ds_read_b128 v[200:203], v149 offset:36864
	ds_read_b128 v[204:207], v149 offset:37888
	ds_read_b128 v[208:211], v149 offset:38912
	ds_read_b128 v[212:215], v149 offset:39936
	global_load_lds_dwordx4 v[224:225], off
	v_lshl_add_u64 v[224:225], s[14:15], 0, v[132:133]
	s_mov_b32 m0, s27
	s_nop 0
	global_load_lds_dwordx4 v[224:225], off
	s_waitcnt vmcnt(8)
	s_waitcnt lgkmcnt(0)
	s_barrier
	s_waitcnt lgkmcnt(0)
	v_mfma_f32_16x16x32_bf16 v[124:127], v[152:155], v[184:187], v[124:127]
	v_mfma_f32_16x16x32_bf16 v[120:123], v[160:163], v[184:187], v[120:123]
	v_mfma_f32_16x16x32_bf16 v[112:115], v[152:155], v[192:195], v[112:115]
	v_mfma_f32_16x16x32_bf16 v[104:107], v[160:163], v[192:195], v[104:107]
	v_mfma_f32_16x16x32_bf16 v[92:95], v[152:155], v[200:203], v[92:95]
	v_mfma_f32_16x16x32_bf16 v[88:91], v[160:163], v[200:203], v[88:91]
	v_mfma_f32_16x16x32_bf16 v[76:79], v[152:155], v[208:211], v[76:79]
	v_mfma_f32_16x16x32_bf16 v[72:75], v[160:163], v[208:211], v[72:75]
	v_mfma_f32_16x16x32_bf16 v[124:127], v[156:159], v[188:191], v[124:127]
	v_mfma_f32_16x16x32_bf16 v[120:123], v[164:167], v[188:191], v[120:123]
	v_mfma_f32_16x16x32_bf16 v[112:115], v[156:159], v[196:199], v[112:115]
	v_mfma_f32_16x16x32_bf16 v[104:107], v[164:167], v[196:199], v[104:107]
	v_mfma_f32_16x16x32_bf16 v[92:95], v[156:159], v[204:207], v[92:95]
	v_mfma_f32_16x16x32_bf16 v[88:91], v[164:167], v[204:207], v[88:91]
	v_mfma_f32_16x16x32_bf16 v[76:79], v[156:159], v[212:215], v[76:79]
	v_mfma_f32_16x16x32_bf16 v[72:75], v[164:167], v[212:215], v[72:75]
	v_mfma_f32_16x16x32_bf16 v[116:119], v[168:171], v[184:187], v[116:119]
	v_mfma_f32_16x16x32_bf16 v[108:111], v[176:179], v[184:187], v[108:111]
	v_mfma_f32_16x16x32_bf16 v[100:103], v[168:171], v[192:195], v[100:103]
	v_mfma_f32_16x16x32_bf16 v[96:99], v[176:179], v[192:195], v[96:99]
	v_mfma_f32_16x16x32_bf16 v[84:87], v[168:171], v[200:203], v[84:87]
	v_mfma_f32_16x16x32_bf16 v[80:83], v[176:179], v[200:203], v[80:83]
	v_mfma_f32_16x16x32_bf16 v[68:71], v[168:171], v[208:211], v[68:71]
	v_mfma_f32_16x16x32_bf16 v[64:67], v[176:179], v[208:211], v[64:67]
	v_mfma_f32_16x16x32_bf16 v[116:119], v[172:175], v[188:191], v[116:119]
	v_mfma_f32_16x16x32_bf16 v[108:111], v[180:183], v[188:191], v[108:111]
	v_mfma_f32_16x16x32_bf16 v[100:103], v[172:175], v[196:199], v[100:103]
	v_mfma_f32_16x16x32_bf16 v[96:99], v[180:183], v[196:199], v[96:99]
	v_mfma_f32_16x16x32_bf16 v[84:87], v[172:175], v[204:207], v[84:87]
	v_mfma_f32_16x16x32_bf16 v[80:83], v[180:183], v[204:207], v[80:83]
	v_mfma_f32_16x16x32_bf16 v[68:71], v[172:175], v[212:215], v[68:71]
	v_mfma_f32_16x16x32_bf16 v[64:67], v[180:183], v[212:215], v[64:67]
	s_barrier
; #define PG8_STAGE(bufoff, gbase, voff) do { _Pragma("unroll") for (int _i = 0; _i < 2; ++_i) \
;         __builtin_amdgcn_global_load_lds((const unsigned*)((const char*)(gbase) + (voff)[_i]), (LAS unsigned*)(lds + (bufoff) + ldsw + _i * 8192), 16, 0, 0); } while (0)
; #define PG8_LDA(dst, b, h) do { _Pragma("unroll") for (int m = 0; m < 4; ++m) _Pragma("unroll") for (int k = 0; k < 2; ++k) dst[m][k] = *(const LAS bf16x8*)(lds + PG8_SA(b, h) + aoff + m * 2048 + k * 1024); } while (0)
; #define PG8_LDB(dst, b, h) do { _Pragma("unroll") for (int n = 0; n < 2; ++n) _Pragma("unroll") for (int k = 0; k < 2; ++k) dst[n][k] = *(const LAS bf16x8*)(lds + PG8_SB(b, h) + boff + n * 2048 + k * 1024); } while (0)
; #define PG8_MMA(ai, bj, At, Bt) do { __builtin_amdgcn_s_setprio(1); _Pragma("unroll") for (int m = 0; m < 4; ++m) _Pragma("unroll") for (int n = 0; n < 2; ++n) _Pragma("unroll") for (int k = 0; k < 2; ++k) \
;         acc[ai][bj][m][n] = __builtin_amdgcn_mfma_f32_16x16x32_bf16(Bt[n][k], At[m][k], acc[ai][bj][m][n], 0, 0, 0); __builtin_amdgcn_s_setprio(0); } while (0)
; #define PG8_WAIT_V(n) asm volatile("s_waitcnt vmcnt(" #n ")" ::: "memory")
; #define PG8_WAIT_L(n) asm volatile("s_waitcnt lgkmcnt(" #n ")" ::: "memory")
; #define PG8_BAR __builtin_amdgcn_s_barrier()
; #define PG8_SCHED __builtin_amdgcn_sched_barrier(0)
; template <class Epi, class Sched, bool ALIGN_EPI = false, bool SP2 = false>
; __device__ __forceinline__ void gemm_phase(LAS unsigned char* lds, const Gemm g, const Sched& S, const Epi& E) {
;     ...
;             PG8_LDB(B0, 0, 0); PG8_LDB(B1, 0, 1); PG8_SCHED; PG8_LDA(At, 0, 0); PG8_STAGE(PG8_SA(1, 1), a1 + hstep, voffA);
;             PG8_WAIT_V(8); PG8_WAIT_L(0); PG8_BAR; PG8_MMA(0, 0, At, B0); PG8_MMA(0, 1, At, B1); PG8_BAR; PG8_SCHED;
;     ...
;             PG8_LDA(At, 1, 1); PG8_STAGE(PG8_SB(1, 0), b3, voffB); PG8_STAGE(PG8_SB(1, 1), b3 + hstepB, voffB); PG8_STAGE(PG8_SA(1, 0), a3, voffA);
;             PG8_WAIT_V(8); PG8_WAIT_L(0); PG8_BAR; PG8_MMA(1, 0, At, B0); PG8_MMA(1, 1, At, B1); PG8_BAR; PG8_SCHED;
	s_add_i32 s14, s41, s23
	v_lshl_add_u64 v[216:217], v[216:217], 0, s[6:7]
	s_mov_b32 m0, s14
	ds_read_b128 v[184:187], v149 offset:49152
	ds_read_b128 v[188:191], v149 offset:50176
	ds_read_b128 v[192:195], v149 offset:51200
	ds_read_b128 v[196:199], v149 offset:52224
	ds_read_b128 v[200:203], v149 offset:53248
	ds_read_b128 v[204:207], v149 offset:54272
	ds_read_b128 v[208:211], v149 offset:55296
	ds_read_b128 v[212:215], v149 offset:56320
	global_load_lds_dwordx4 v[216:217], off
	s_add_i32 m0, s14, 0x2000
	s_add_u32 s14, s18, 0x58080
	v_lshl_add_u64 v[216:217], v[218:219], 0, s[6:7]
	s_addc_u32 s15, s19, 0
	s_add_i32 s18, s42, s23
	global_load_lds_dwordx4 v[216:217], off
	v_lshl_add_u64 v[216:217], s[14:15], 0, v[130:131]
	s_mov_b32 m0, s18
	s_nop 0
	global_load_lds_dwordx4 v[216:217], off
	v_lshl_add_u64 v[216:217], s[14:15], 0, v[134:135]
	s_add_i32 m0, s18, 0x2000
	s_nop 0
	global_load_lds_dwordx4 v[216:217], off
	v_lshl_add_u64 v[216:217], v[220:221], 0, s[6:7]
	s_mov_b32 m0, s31
	s_nop 0
	global_load_lds_dwordx4 v[216:217], off
	v_lshl_add_u64 v[216:217], v[222:223], 0, s[6:7]
	s_mov_b32 m0, s33
	s_nop 0
	global_load_lds_dwordx4 v[216:217], off
	s_waitcnt vmcnt(8)
	s_waitcnt lgkmcnt(0)
	s_barrier
	s_waitcnt lgkmcnt(0)
	v_mfma_f32_16x16x32_bf16 v[60:63], v[152:155], v[184:187], v[60:63]
	v_mfma_f32_16x16x32_bf16 v[56:59], v[160:163], v[184:187], v[56:59]
	v_mfma_f32_16x16x32_bf16 v[44:47], v[152:155], v[192:195], v[44:47]
	v_mfma_f32_16x16x32_bf16 v[40:43], v[160:163], v[192:195], v[40:43]
	v_mfma_f32_16x16x32_bf16 v[28:31], v[152:155], v[200:203], v[28:31]
	v_mfma_f32_16x16x32_bf16 v[24:27], v[160:163], v[200:203], v[24:27]
	v_mfma_f32_16x16x32_bf16 v[12:15], v[152:155], v[208:211], v[12:15]
	v_mfma_f32_16x16x32_bf16 v[8:11], v[160:163], v[208:211], v[8:11]
	v_mfma_f32_16x16x32_bf16 v[60:63], v[156:159], v[188:191], v[60:63]
	v_mfma_f32_16x16x32_bf16 v[56:59], v[164:167], v[188:191], v[56:59]
	v_mfma_f32_16x16x32_bf16 v[44:47], v[156:159], v[196:199], v[44:47]
	v_mfma_f32_16x16x32_bf16 v[40:43], v[164:167], v[196:199], v[40:43]
	v_mfma_f32_16x16x32_bf16 v[28:31], v[156:159], v[204:207], v[28:31]
	v_mfma_f32_16x16x32_bf16 v[24:27], v[164:167], v[204:207], v[24:27]
	v_mfma_f32_16x16x32_bf16 v[12:15], v[156:159], v[212:215], v[12:15]
	v_mfma_f32_16x16x32_bf16 v[8:11], v[164:167], v[212:215], v[8:11]
	v_mfma_f32_16x16x32_bf16 v[52:55], v[168:171], v[184:187], v[52:55]
	v_mfma_f32_16x16x32_bf16 v[48:51], v[176:179], v[184:187], v[48:51]
	v_mfma_f32_16x16x32_bf16 v[36:39], v[168:171], v[192:195], v[36:39]
	v_mfma_f32_16x16x32_bf16 v[32:35], v[176:179], v[192:195], v[32:35]
	v_mfma_f32_16x16x32_bf16 v[20:23], v[168:171], v[200:203], v[20:23]
	v_mfma_f32_16x16x32_bf16 v[16:19], v[176:179], v[200:203], v[16:19]
	v_mfma_f32_16x16x32_bf16 v[4:7], v[168:171], v[208:211], v[4:7]
	v_mfma_f32_16x16x32_bf16 v[0:3], v[176:179], v[208:211], v[0:3]
	v_mfma_f32_16x16x32_bf16 v[52:55], v[172:175], v[188:191], v[52:55]
	v_mfma_f32_16x16x32_bf16 v[48:51], v[180:183], v[188:191], v[48:51]
	v_mfma_f32_16x16x32_bf16 v[36:39], v[172:175], v[196:199], v[36:39]
	v_mfma_f32_16x16x32_bf16 v[32:35], v[180:183], v[196:199], v[32:35]
	v_mfma_f32_16x16x32_bf16 v[20:23], v[172:175], v[204:207], v[20:23]
	v_mfma_f32_16x16x32_bf16 v[16:19], v[180:183], v[204:207], v[16:19]
	v_mfma_f32_16x16x32_bf16 v[4:7], v[172:175], v[212:215], v[4:7]
	v_mfma_f32_16x16x32_bf16 v[0:3], v[180:183], v[212:215], v[0:3]
	s_barrier
	s_add_i32 s40, s40, 2
	s_add_u32 s13, s13, 0x100
	s_addc_u32 s39, s39, 0
	s_cmpk_lt_u32 s40, 0x56
	s_mov_b64 s[14:15], s[16:17]
.LBB0_3002:
	ds_read_b128 v[152:155], v147
	ds_read_b128 v[156:159], v147 offset:1024
	ds_read_b128 v[160:163], v147 offset:2048
	ds_read_b128 v[164:167], v147 offset:3072
	ds_read_b128 v[168:171], v148
	ds_read_b128 v[172:175], v148 offset:1024
	ds_read_b128 v[176:179], v148 offset:2048
	ds_read_b128 v[180:183], v148 offset:3072
	s_add_u32 s16, s14, 0x100
	s_addc_u32 s17, s15, 0
	s_cmpk_eq_i32 s40, 0x54
	s_cselect_b32 s21, s11, s17
	s_cselect_b32 s20, s10, s16
	s_cselect_b32 s19, s3, s39
	s_cselect_b32 s18, s2, s13
	v_lshl_add_u64 v[216:217], s[14:15], 0, v[138:139]
	s_add_i32 m0, s24, 0xc000
	ds_read_b128 v[184:187], v149
	ds_read_b128 v[188:191], v149 offset:1024
	ds_read_b128 v[192:195], v149 offset:2048
	ds_read_b128 v[196:199], v149 offset:3072
	ds_read_b128 v[200:203], v149 offset:4096
	ds_read_b128 v[204:207], v149 offset:5120
	ds_read_b128 v[208:211], v149 offset:6144
	ds_read_b128 v[212:215], v149 offset:7168
	global_load_lds_dwordx4 v[216:217], off
	v_lshl_add_u64 v[216:217], s[14:15], 0, v[136:137]
	s_add_i32 m0, s24, 0xe000
	s_nop 0
	global_load_lds_dwordx4 v[216:217], off
	s_waitcnt vmcnt(8)
	s_waitcnt lgkmcnt(0)
	s_barrier
; #define PG8_STAGE(bufoff, gbase, voff) do { _Pragma("unroll") for (int _i = 0; _i < 2; ++_i) \
;         __builtin_amdgcn_global_load_lds((const unsigned*)((const char*)(gbase) + (voff)[_i]), (LAS unsigned*)(lds + (bufoff) + ldsw + _i * 8192), 16, 0, 0); } while (0)
; #define PG8_LDA(dst, b, h) do { _Pragma("unroll") for (int m = 0; m < 4; ++m) _Pragma("unroll") for (int k = 0; k < 2; ++k) dst[m][k] = *(const LAS bf16x8*)(lds + PG8_SA(b, h) + aoff + m * 2048 + k * 1024); } while (0)
; #define PG8_MMA(ai, bj, At, Bt) do { __builtin_amdgcn_s_setprio(1); _Pragma("unroll") for (int m = 0; m < 4; ++m) _Pragma("unroll") for (int n = 0; n < 2; ++n) _Pragma("unroll") for (int k = 0; k < 2; ++k) \
;         acc[ai][bj][m][n] = __builtin_amdgcn_mfma_f32_16x16x32_bf16(Bt[n][k], At[m][k], acc[ai][bj][m][n], 0, 0, 0); __builtin_amdgcn_s_setprio(0); } while (0)
; #define PG8_WAIT_V(n) asm volatile("s_waitcnt vmcnt(" #n ")" ::: "memory")
; #define PG8_WAIT_L(n) asm volatile("s_waitcnt lgkmcnt(" #n ")" ::: "memory")
; #define PG8_BAR __builtin_amdgcn_s_barrier()
; #define PG8_SCHED __builtin_amdgcn_sched_barrier(0)
; template <class Epi, class Sched, bool ALIGN_EPI = false, bool SP2 = false>
; __device__ __forceinline__ void gemm_phase(LAS unsigned char* lds, const Gemm g, const Sched& S, const Epi& E) {
;     ...
;             PG8_WAIT_V(8); PG8_WAIT_L(0); PG8_BAR; PG8_MMA(0, 0, At, B0); PG8_MMA(0, 1, At, B1); PG8_BAR; PG8_SCHED;
;             PG8_LDA(At, 0, 1); PG8_STAGE(PG8_SB(0, 0), b2, voffB); PG8_STAGE(PG8_SB(0, 1), b2 + hstepB, voffB); PG8_STAGE(PG8_SA(0, 0), a2, voffA);
;             PG8_WAIT_V(8); PG8_WAIT_L(0); PG8_BAR; PG8_MMA(1, 0, At, B0); PG8_MMA(1, 1, At, B1); PG8_BAR; PG8_SCHED;
	s_waitcnt lgkmcnt(0)
	v_mfma_f32_16x16x32_bf16 v[124:127], v[152:155], v[184:187], v[124:127]
	v_mfma_f32_16x16x32_bf16 v[120:123], v[160:163], v[184:187], v[120:123]
	v_mfma_f32_16x16x32_bf16 v[112:115], v[152:155], v[192:195], v[112:115]
	v_mfma_f32_16x16x32_bf16 v[104:107], v[160:163], v[192:195], v[104:107]
	v_mfma_f32_16x16x32_bf16 v[92:95], v[152:155], v[200:203], v[92:95]
	v_mfma_f32_16x16x32_bf16 v[88:91], v[160:163], v[200:203], v[88:91]
	v_mfma_f32_16x16x32_bf16 v[76:79], v[152:155], v[208:211], v[76:79]
	v_mfma_f32_16x16x32_bf16 v[72:75], v[160:163], v[208:211], v[72:75]
	v_mfma_f32_16x16x32_bf16 v[124:127], v[156:159], v[188:191], v[124:127]
	v_mfma_f32_16x16x32_bf16 v[120:123], v[164:167], v[188:191], v[120:123]
	v_mfma_f32_16x16x32_bf16 v[112:115], v[156:159], v[196:199], v[112:115]
	v_mfma_f32_16x16x32_bf16 v[104:107], v[164:167], v[196:199], v[104:107]
	v_mfma_f32_16x16x32_bf16 v[92:95], v[156:159], v[204:207], v[92:95]
	v_mfma_f32_16x16x32_bf16 v[88:91], v[164:167], v[204:207], v[88:91]
	v_mfma_f32_16x16x32_bf16 v[76:79], v[156:159], v[212:215], v[76:79]
	v_mfma_f32_16x16x32_bf16 v[72:75], v[164:167], v[212:215], v[72:75]
	v_mfma_f32_16x16x32_bf16 v[116:119], v[168:171], v[184:187], v[116:119]
	v_mfma_f32_16x16x32_bf16 v[108:111], v[176:179], v[184:187], v[108:111]
	v_mfma_f32_16x16x32_bf16 v[100:103], v[168:171], v[192:195], v[100:103]
	v_mfma_f32_16x16x32_bf16 v[96:99], v[176:179], v[192:195], v[96:99]
	v_mfma_f32_16x16x32_bf16 v[84:87], v[168:171], v[200:203], v[84:87]
	v_mfma_f32_16x16x32_bf16 v[80:83], v[176:179], v[200:203], v[80:83]
	v_mfma_f32_16x16x32_bf16 v[68:71], v[168:171], v[208:211], v[68:71]
	v_mfma_f32_16x16x32_bf16 v[64:67], v[176:179], v[208:211], v[64:67]
	v_mfma_f32_16x16x32_bf16 v[116:119], v[172:175], v[188:191], v[116:119]
	v_mfma_f32_16x16x32_bf16 v[108:111], v[180:183], v[188:191], v[108:111]
	v_mfma_f32_16x16x32_bf16 v[100:103], v[172:175], v[196:199], v[100:103]
	v_mfma_f32_16x16x32_bf16 v[96:99], v[180:183], v[196:199], v[96:99]
	v_mfma_f32_16x16x32_bf16 v[84:87], v[172:175], v[204:207], v[84:87]
	v_mfma_f32_16x16x32_bf16 v[80:83], v[180:183], v[204:207], v[80:83]
	v_mfma_f32_16x16x32_bf16 v[68:71], v[172:175], v[212:215], v[68:71]
	v_mfma_f32_16x16x32_bf16 v[64:67], v[180:183], v[212:215], v[64:67]
	s_barrier
	s_add_i32 s14, s34, s23
	v_lshl_add_u64 v[216:217], s[18:19], 0, v[130:131]
	s_mov_b32 m0, s14
	ds_read_b128 v[184:187], v149 offset:16384
	ds_read_b128 v[188:191], v149 offset:17408
	ds_read_b128 v[192:195], v149 offset:18432
	ds_read_b128 v[196:199], v149 offset:19456
	ds_read_b128 v[200:203], v149 offset:20480
	ds_read_b128 v[204:207], v149 offset:21504
	ds_read_b128 v[208:211], v149 offset:22528
	ds_read_b128 v[212:215], v149 offset:23552
	global_load_lds_dwordx4 v[216:217], off
	s_add_i32 m0, s14, 0x2000
	s_add_u32 s14, s18, 0x58000
	v_lshl_add_u64 v[218:219], s[18:19], 0, v[134:135]
	s_addc_u32 s15, s19, 0
	s_add_i32 s41, s35, s23
	global_load_lds_dwordx4 v[218:219], off
	v_lshl_add_u64 v[220:221], s[14:15], 0, v[130:131]
	s_mov_b32 m0, s41
	v_lshl_add_u64 v[222:223], s[20:21], 0, v[132:133]
	global_load_lds_dwordx4 v[220:221], off
	v_lshl_add_u64 v[220:221], s[14:15], 0, v[134:135]
	s_add_i32 m0, s41, 0x2000
	s_nop 0
	global_load_lds_dwordx4 v[220:221], off
	v_lshl_add_u64 v[220:221], s[20:21], 0, v[128:129]
	s_mov_b32 m0, s24
	s_nop 0
	global_load_lds_dwordx4 v[220:221], off
	s_mov_b32 m0, s25
	s_nop 0
	global_load_lds_dwordx4 v[222:223], off
	s_waitcnt vmcnt(8)
	s_waitcnt lgkmcnt(0)
	s_barrier
	s_waitcnt lgkmcnt(0)
	v_mfma_f32_16x16x32_bf16 v[60:63], v[152:155], v[184:187], v[60:63]
	v_mfma_f32_16x16x32_bf16 v[56:59], v[160:163], v[184:187], v[56:59]
	v_mfma_f32_16x16x32_bf16 v[44:47], v[152:155], v[192:195], v[44:47]
	v_mfma_f32_16x16x32_bf16 v[40:43], v[160:163], v[192:195], v[40:43]
	v_mfma_f32_16x16x32_bf16 v[28:31], v[152:155], v[200:203], v[28:31]
	v_mfma_f32_16x16x32_bf16 v[24:27], v[160:163], v[200:203], v[24:27]
	v_mfma_f32_16x16x32_bf16 v[12:15], v[152:155], v[208:211], v[12:15]
	v_mfma_f32_16x16x32_bf16 v[8:11], v[160:163], v[208:211], v[8:11]
	v_mfma_f32_16x16x32_bf16 v[60:63], v[156:159], v[188:191], v[60:63]
	v_mfma_f32_16x16x32_bf16 v[56:59], v[164:167], v[188:191], v[56:59]
	v_mfma_f32_16x16x32_bf16 v[44:47], v[156:159], v[196:199], v[44:47]
	v_mfma_f32_16x16x32_bf16 v[40:43], v[164:167], v[196:199], v[40:43]
	v_mfma_f32_16x16x32_bf16 v[28:31], v[156:159], v[204:207], v[28:31]
	v_mfma_f32_16x16x32_bf16 v[24:27], v[164:167], v[204:207], v[24:27]
	v_mfma_f32_16x16x32_bf16 v[12:15], v[156:159], v[212:215], v[12:15]
	v_mfma_f32_16x16x32_bf16 v[8:11], v[164:167], v[212:215], v[8:11]
	v_mfma_f32_16x16x32_bf16 v[52:55], v[168:171], v[184:187], v[52:55]
	v_mfma_f32_16x16x32_bf16 v[48:51], v[176:179], v[184:187], v[48:51]
	v_mfma_f32_16x16x32_bf16 v[36:39], v[168:171], v[192:195], v[36:39]
	v_mfma_f32_16x16x32_bf16 v[32:35], v[176:179], v[192:195], v[32:35]
	v_mfma_f32_16x16x32_bf16 v[20:23], v[168:171], v[200:203], v[20:23]
	v_mfma_f32_16x16x32_bf16 v[16:19], v[176:179], v[200:203], v[16:19]
	v_mfma_f32_16x16x32_bf16 v[4:7], v[168:171], v[208:211], v[4:7]
	v_mfma_f32_16x16x32_bf16 v[0:3], v[176:179], v[208:211], v[0:3]
	v_mfma_f32_16x16x32_bf16 v[52:55], v[172:175], v[188:191], v[52:55]
	v_mfma_f32_16x16x32_bf16 v[48:51], v[180:183], v[188:191], v[48:51]
	v_mfma_f32_16x16x32_bf16 v[36:39], v[172:175], v[196:199], v[36:39]
	v_mfma_f32_16x16x32_bf16 v[32:35], v[180:183], v[196:199], v[32:35]
	v_mfma_f32_16x16x32_bf16 v[20:23], v[172:175], v[204:207], v[20:23]
	v_mfma_f32_16x16x32_bf16 v[16:19], v[180:183], v[204:207], v[16:19]
	v_mfma_f32_16x16x32_bf16 v[4:7], v[172:175], v[212:215], v[4:7]
	v_mfma_f32_16x16x32_bf16 v[0:3], v[180:183], v[212:215], v[0:3]
	s_barrier
; #define PG8_STAGE(bufoff, gbase, voff) do { _Pragma("unroll") for (int _i = 0; _i < 2; ++_i) \
;         __builtin_amdgcn_global_load_lds((const unsigned*)((const char*)(gbase) + (voff)[_i]), (LAS unsigned*)(lds + (bufoff) + ldsw + _i * 8192), 16, 0, 0); } while (0)
; #define PG8_LDA(dst, b, h) do { _Pragma("unroll") for (int m = 0; m < 4; ++m) _Pragma("unroll") for (int k = 0; k < 2; ++k) dst[m][k] = *(const LAS bf16x8*)(lds + PG8_SA(b, h) + aoff + m * 2048 + k * 1024); } while (0)
; #define PG8_LDB(dst, b, h) do { _Pragma("unroll") for (int n = 0; n < 2; ++n) _Pragma("unroll") for (int k = 0; k < 2; ++k) dst[n][k] = *(const LAS bf16x8*)(lds + PG8_SB(b, h) + boff + n * 2048 + k * 1024); } while (0)
; #define PG8_MMA(ai, bj, At, Bt) do { __builtin_amdgcn_s_setprio(1); _Pragma("unroll") for (int m = 0; m < 4; ++m) _Pragma("unroll") for (int n = 0; n < 2; ++n) _Pragma("unroll") for (int k = 0; k < 2; ++k) \
;         acc[ai][bj][m][n] = __builtin_amdgcn_mfma_f32_16x16x32_bf16(Bt[n][k], At[m][k], acc[ai][bj][m][n], 0, 0, 0); __builtin_amdgcn_s_setprio(0); } while (0)
; #define PG8_WAIT_V(n) asm volatile("s_waitcnt vmcnt(" #n ")" ::: "memory")
; #define PG8_WAIT_L(n) asm volatile("s_waitcnt lgkmcnt(" #n ")" ::: "memory")
; #define PG8_BAR __builtin_amdgcn_s_barrier()
; #define PG8_SCHED __builtin_amdgcn_sched_barrier(0)
; template <class Epi, class Sched, bool ALIGN_EPI = false, bool SP2 = false>
; __device__ __forceinline__ void gemm_phase(LAS unsigned char* lds, const Gemm g, const Sched& S, const Epi& E) {
;     ...
;             PG8_LDB(B0, 1, 0); PG8_LDB(B1, 1, 1); PG8_SCHED; PG8_LDA(At, 1, 0); PG8_STAGE(PG8_SA(0, 1), a2 + hstep, voffA);
;             PG8_WAIT_V(8); PG8_WAIT_L(0); PG8_BAR; PG8_MMA(0, 0, At, B0); PG8_MMA(0, 1, At, B1); PG8_BAR; PG8_SCHED;
	s_add_i32 s41, 0, 0x18000
	s_add_i32 s42, 0, 0x1c000
	v_add_u32_e32 v164, s41, v144
	v_add_u32_e32 v180, s42, v144
	ds_read_b128 v[152:155], v164
	ds_read_b128 v[156:159], v164 offset:1024
	ds_read_b128 v[160:163], v164 offset:2048
	ds_read_b128 v[164:167], v164 offset:3072
	ds_read_b128 v[168:171], v180
	ds_read_b128 v[172:175], v180 offset:1024
	ds_read_b128 v[176:179], v180 offset:2048
	ds_read_b128 v[180:183], v180 offset:3072
	s_add_u32 s14, s20, 0x160000
	s_addc_u32 s15, s21, 0
	s_mov_b32 m0, s26
	v_lshl_add_u64 v[224:225], s[14:15], 0, v[128:129]
	ds_read_b128 v[184:187], v149 offset:32768
	ds_read_b128 v[188:191], v149 offset:33792
	ds_read_b128 v[192:195], v149 offset:34816
	ds_read_b128 v[196:199], v149 offset:35840
	ds_read_b128 v[200:203], v149 offset:36864
	ds_read_b128 v[204:207], v149 offset:37888
	ds_read_b128 v[208:211], v149 offset:38912
	ds_read_b128 v[212:215], v149 offset:39936
	global_load_lds_dwordx4 v[224:225], off
	v_lshl_add_u64 v[224:225], s[14:15], 0, v[132:133]
	s_mov_b32 m0, s27
	s_nop 0
	global_load_lds_dwordx4 v[224:225], off
	s_waitcnt vmcnt(8)
	s_waitcnt lgkmcnt(0)
	s_barrier
	s_waitcnt lgkmcnt(0)
	v_mfma_f32_16x16x32_bf16 v[124:127], v[152:155], v[184:187], v[124:127]
	v_mfma_f32_16x16x32_bf16 v[120:123], v[160:163], v[184:187], v[120:123]
	v_mfma_f32_16x16x32_bf16 v[112:115], v[152:155], v[192:195], v[112:115]
	v_mfma_f32_16x16x32_bf16 v[104:107], v[160:163], v[192:195], v[104:107]
	v_mfma_f32_16x16x32_bf16 v[92:95], v[152:155], v[200:203], v[92:95]
	v_mfma_f32_16x16x32_bf16 v[88:91], v[160:163], v[200:203], v[88:91]
	v_mfma_f32_16x16x32_bf16 v[76:79], v[152:155], v[208:211], v[76:79]
	v_mfma_f32_16x16x32_bf16 v[72:75], v[160:163], v[208:211], v[72:75]
	v_mfma_f32_16x16x32_bf16 v[124:127], v[156:159], v[188:191], v[124:127]
	v_mfma_f32_16x16x32_bf16 v[120:123], v[164:167], v[188:191], v[120:123]
	v_mfma_f32_16x16x32_bf16 v[112:115], v[156:159], v[196:199], v[112:115]
	v_mfma_f32_16x16x32_bf16 v[104:107], v[164:167], v[196:199], v[104:107]
	v_mfma_f32_16x16x32_bf16 v[92:95], v[156:159], v[204:207], v[92:95]
	v_mfma_f32_16x16x32_bf16 v[88:91], v[164:167], v[204:207], v[88:91]
	v_mfma_f32_16x16x32_bf16 v[76:79], v[156:159], v[212:215], v[76:79]
	v_mfma_f32_16x16x32_bf16 v[72:75], v[164:167], v[212:215], v[72:75]
	v_mfma_f32_16x16x32_bf16 v[116:119], v[168:171], v[184:187], v[116:119]
	v_mfma_f32_16x16x32_bf16 v[108:111], v[176:179], v[184:187], v[108:111]
	v_mfma_f32_16x16x32_bf16 v[100:103], v[168:171], v[192:195], v[100:103]
	v_mfma_f32_16x16x32_bf16 v[96:99], v[176:179], v[192:195], v[96:99]
	v_mfma_f32_16x16x32_bf16 v[84:87], v[168:171], v[200:203], v[84:87]
	v_mfma_f32_16x16x32_bf16 v[80:83], v[176:179], v[200:203], v[80:83]
	v_mfma_f32_16x16x32_bf16 v[68:71], v[168:171], v[208:211], v[68:71]
	v_mfma_f32_16x16x32_bf16 v[64:67], v[176:179], v[208:211], v[64:67]
	v_mfma_f32_16x16x32_bf16 v[116:119], v[172:175], v[188:191], v[116:119]
	v_mfma_f32_16x16x32_bf16 v[108:111], v[180:183], v[188:191], v[108:111]
	v_mfma_f32_16x16x32_bf16 v[100:103], v[172:175], v[196:199], v[100:103]
	v_mfma_f32_16x16x32_bf16 v[96:99], v[180:183], v[196:199], v[96:99]
	v_mfma_f32_16x16x32_bf16 v[84:87], v[172:175], v[204:207], v[84:87]
	v_mfma_f32_16x16x32_bf16 v[80:83], v[180:183], v[204:207], v[80:83]
	v_mfma_f32_16x16x32_bf16 v[68:71], v[172:175], v[212:215], v[68:71]
	v_mfma_f32_16x16x32_bf16 v[64:67], v[180:183], v[212:215], v[64:67]
	s_barrier
; #define PG8_STAGE(bufoff, gbase, voff) do { _Pragma("unroll") for (int _i = 0; _i < 2; ++_i) \
;         __builtin_amdgcn_global_load_lds((const unsigned*)((const char*)(gbase) + (voff)[_i]), (LAS unsigned*)(lds + (bufoff) + ldsw + _i * 8192), 16, 0, 0); } while (0)
; #define PG8_LDA(dst, b, h) do { _Pragma("unroll") for (int m = 0; m < 4; ++m) _Pragma("unroll") for (int k = 0; k < 2; ++k) dst[m][k] = *(const LAS bf16x8*)(lds + PG8_SA(b, h) + aoff + m * 2048 + k * 1024); } while (0)
; #define PG8_MMA(ai, bj, At, Bt) do { __builtin_amdgcn_s_setprio(1); _Pragma("unroll") for (int m = 0; m < 4; ++m) _Pragma("unroll") for (int n = 0; n < 2; ++n) _Pragma("unroll") for (int k = 0; k < 2; ++k) \
;         acc[ai][bj][m][n] = __builtin_amdgcn_mfma_f32_16x16x32_bf16(Bt[n][k], At[m][k], acc[ai][bj][m][n], 0, 0, 0); __builtin_amdgcn_s_setprio(0); } while (0)
; #define PG8_WAIT_V(n) asm volatile("s_waitcnt vmcnt(" #n ")" ::: "memory")
; #define PG8_WAIT_L(n) asm volatile("s_waitcnt lgkmcnt(" #n ")" ::: "memory")
; #define PG8_BAR __builtin_amdgcn_s_barrier()
; #define PG8_SCHED __builtin_amdgcn_sched_barrier(0)
; template <class Epi, class Sched, bool ALIGN_EPI = false, bool SP2 = false>
; __device__ __forceinline__ void gemm_phase(LAS unsigned char* lds, const Gemm g, const Sched& S, const Epi& E) {
;     ...
;         for (int t = 0; t < nt; t += 2) {
;     ...
;             PG8_LDA(At, 1, 1); PG8_STAGE(PG8_SB(1, 0), b3, voffB); PG8_STAGE(PG8_SB(1, 1), b3 + hstepB, voffB); PG8_STAGE(PG8_SA(1, 0), a3, voffA);
;             PG8_WAIT_V(8); PG8_WAIT_L(0); PG8_BAR; PG8_MMA(1, 0, At, B0); PG8_MMA(1, 1, At, B1); PG8_BAR; PG8_SCHED;
	s_add_i32 s14, s41, s23
	v_lshl_add_u64 v[216:217], v[216:217], 0, s[6:7]
	s_mov_b32 m0, s14
	ds_read_b128 v[184:187], v149 offset:49152
	ds_read_b128 v[188:191], v149 offset:50176
	ds_read_b128 v[192:195], v149 offset:51200
	ds_read_b128 v[196:199], v149 offset:52224
	ds_read_b128 v[200:203], v149 offset:53248
	ds_read_b128 v[204:207], v149 offset:54272
	ds_read_b128 v[208:211], v149 offset:55296
	ds_read_b128 v[212:215], v149 offset:56320
	global_load_lds_dwordx4 v[216:217], off
	s_add_i32 m0, s14, 0x2000
	s_add_u32 s14, s18, 0x58080
	v_lshl_add_u64 v[216:217], v[218:219], 0, s[6:7]
	s_addc_u32 s15, s19, 0
	s_add_i32 s18, s42, s23
	global_load_lds_dwordx4 v[216:217], off
	v_lshl_add_u64 v[216:217], s[14:15], 0, v[130:131]
	s_mov_b32 m0, s18
	s_nop 0
	global_load_lds_dwordx4 v[216:217], off
	v_lshl_add_u64 v[216:217], s[14:15], 0, v[134:135]
	s_add_i32 m0, s18, 0x2000
	s_nop 0
	global_load_lds_dwordx4 v[216:217], off
	v_lshl_add_u64 v[216:217], v[220:221], 0, s[6:7]
	s_mov_b32 m0, s31
	s_nop 0
	global_load_lds_dwordx4 v[216:217], off
	v_lshl_add_u64 v[216:217], v[222:223], 0, s[6:7]
	s_mov_b32 m0, s33
	s_nop 0
	global_load_lds_dwordx4 v[216:217], off
	s_waitcnt vmcnt(8)
	s_waitcnt lgkmcnt(0)
	s_barrier
	s_waitcnt lgkmcnt(0)
	v_mfma_f32_16x16x32_bf16 v[60:63], v[152:155], v[184:187], v[60:63]
	v_mfma_f32_16x16x32_bf16 v[56:59], v[160:163], v[184:187], v[56:59]
	v_mfma_f32_16x16x32_bf16 v[44:47], v[152:155], v[192:195], v[44:47]
	v_mfma_f32_16x16x32_bf16 v[40:43], v[160:163], v[192:195], v[40:43]
	v_mfma_f32_16x16x32_bf16 v[28:31], v[152:155], v[200:203], v[28:31]
	v_mfma_f32_16x16x32_bf16 v[24:27], v[160:163], v[200:203], v[24:27]
	v_mfma_f32_16x16x32_bf16 v[12:15], v[152:155], v[208:211], v[12:15]
	v_mfma_f32_16x16x32_bf16 v[8:11], v[160:163], v[208:211], v[8:11]
	v_mfma_f32_16x16x32_bf16 v[60:63], v[156:159], v[188:191], v[60:63]
	v_mfma_f32_16x16x32_bf16 v[56:59], v[164:167], v[188:191], v[56:59]
	v_mfma_f32_16x16x32_bf16 v[44:47], v[156:159], v[196:199], v[44:47]
	v_mfma_f32_16x16x32_bf16 v[40:43], v[164:167], v[196:199], v[40:43]
	v_mfma_f32_16x16x32_bf16 v[28:31], v[156:159], v[204:207], v[28:31]
	v_mfma_f32_16x16x32_bf16 v[24:27], v[164:167], v[204:207], v[24:27]
	v_mfma_f32_16x16x32_bf16 v[12:15], v[156:159], v[212:215], v[12:15]
	v_mfma_f32_16x16x32_bf16 v[8:11], v[164:167], v[212:215], v[8:11]
	v_mfma_f32_16x16x32_bf16 v[52:55], v[168:171], v[184:187], v[52:55]
	v_mfma_f32_16x16x32_bf16 v[48:51], v[176:179], v[184:187], v[48:51]
	v_mfma_f32_16x16x32_bf16 v[36:39], v[168:171], v[192:195], v[36:39]
	v_mfma_f32_16x16x32_bf16 v[32:35], v[176:179], v[192:195], v[32:35]
	v_mfma_f32_16x16x32_bf16 v[20:23], v[168:171], v[200:203], v[20:23]
	v_mfma_f32_16x16x32_bf16 v[16:19], v[176:179], v[200:203], v[16:19]
	v_mfma_f32_16x16x32_bf16 v[4:7], v[168:171], v[208:211], v[4:7]
	v_mfma_f32_16x16x32_bf16 v[0:3], v[176:179], v[208:211], v[0:3]
	v_mfma_f32_16x16x32_bf16 v[52:55], v[172:175], v[188:191], v[52:55]
	v_mfma_f32_16x16x32_bf16 v[48:51], v[180:183], v[188:191], v[48:51]
	v_mfma_f32_16x16x32_bf16 v[36:39], v[172:175], v[196:199], v[36:39]
	v_mfma_f32_16x16x32_bf16 v[32:35], v[180:183], v[196:199], v[32:35]
	v_mfma_f32_16x16x32_bf16 v[20:23], v[172:175], v[204:207], v[20:23]
	v_mfma_f32_16x16x32_bf16 v[16:19], v[180:183], v[204:207], v[16:19]
	v_mfma_f32_16x16x32_bf16 v[4:7], v[172:175], v[212:215], v[4:7]
	v_mfma_f32_16x16x32_bf16 v[0:3], v[180:183], v[212:215], v[0:3]
	s_barrier
	s_add_i32 s40, s40, 2
	s_add_u32 s13, s13, 0x100
	s_addc_u32 s39, s39, 0
	s_cmpk_lt_u32 s40, 0x56
	s_mov_b64 s[14:15], s[16:17]
	s_cbranch_scc1 .LBB0_3002
	s_andn2_b64 vcc, exec, s[8:9]
	s_cbranch_vccnz .LBB0_3005
	s_barrier
